# all 16-byte global stores write-through (sc1) so the grid barriers' L2 writeback finds little dirty data; on top of deferred-PV + 16-granule K swizzle
# speedup vs baseline: 1.0060x; 1.0060x over previous
; __device__ __forceinline__ unsigned pk2(float lo, float hi) { unsigned r; asm volatile("v_cvt_pk_bf16_f32 %0, %1, %2" : "=v"(r) : "v"(lo), "v"(hi)); return r; }
; __device__ __forceinline__ void p0_transpose_item(const float* W, int K, int N, bf16* WT, int kb, int src_col0, int dst_row0, float* scr, int lane, const float* kgain = nullptr) {
;     ...
;     for (int j = 0; j < 4; ++j) { const int n = (lane >> 3) + 8 * j; const float* s = scr + (8 * c) * 33 + n;
;         v4u o;
;         if (src_col0 >= 0) { o.x = pk2(s[0 * 33] * g0.x, s[1 * 33] * g0.y); o.y = pk2(s[2 * 33] * g0.z, s[3 * 33] * g0.w); o.z = pk2(s[4 * 33] * g1.x, s[5 * 33] * g1.y); o.w = pk2(s[6 * 33] * g1.z, s[7 * 33] * g1.w); }
;         else { o.x = 0u; o.y = 0u; o.z = 0u; o.w = 0u; }
;         *(v4u*)(WT + (size_t)(dst_row0 + n) * K + k0 + 8 * c) = o; }
; template <class CM>
; __device__ __forceinline__ void p0_transpose_matrix(Frame& F, const float* W, int K, int N, bf16* WT, int nblk, CM colmap, int& it0, const float* kgain = nullptr) {
;     ...
;     for (int r = first; r < nitems; r += F.ngw) {
;         const int kb = r / nblk, nb = r % nblk;
;         p0_transpose_item(W, K, N, WT, kb, colmap(nb), nb * 32, scr, F.lane, kgain);
;     }
.LBB0_12:
	v_add_u32_e32 v6, 24, v28
	v_ashrrev_i32_e32 v7, 31, v6
	v_lshlrev_b64 v[6:7], 13, v[6:7]
	v_lshl_add_u64 v[6:7], v[26:27], 0, v[6:7]
	global_store_dwordx4 v[6:7], v[14:17], off sc1
	s_waitcnt lgkmcnt(0)
	s_add_i32 s20, s20, s76
	s_add_i32 s21, s21, s22
	s_cmpk_lt_i32 s20, 0x5a00
	s_cbranch_scc0 .LBB0_33

; __device__ __forceinline__ unsigned pk2(float lo, float hi) { unsigned r; asm volatile("v_cvt_pk_bf16_f32 %0, %1, %2" : "=v"(r) : "v"(lo), "v"(hi)); return r; }
; __device__ __forceinline__ void p0_transpose_item(const float* W, int K, int N, bf16* WT, int kb, int src_col0, int dst_row0, float* scr, int lane, const float* kgain = nullptr) {
;     ...
;     for (int j = 0; j < 4; ++j) { const int n = (lane >> 3) + 8 * j; const float* s = scr + (8 * c) * 33 + n;
;         v4u o;
;         if (src_col0 >= 0) { o.x = pk2(s[0 * 33] * g0.x, s[1 * 33] * g0.y); o.y = pk2(s[2 * 33] * g0.z, s[3 * 33] * g0.w); o.z = pk2(s[4 * 33] * g1.x, s[5 * 33] * g1.y); o.w = pk2(s[6 * 33] * g1.z, s[7 * 33] * g1.w); }
;         else { o.x = 0u; o.y = 0u; o.z = 0u; o.w = 0u; }
;         *(v4u*)(WT + (size_t)(dst_row0 + n) * K + k0 + 8 * c) = o; }
.LBB0_24:
	s_waitcnt lgkmcnt(0)
	s_ashr_i32 s15, s14, 31
	v_lshl_add_u64 v[26:27], s[14:15], 1, v[24:25]
	s_mov_b64 s[14:15], -1
	s_and_b64 vcc, exec, s[12:13]
	s_cbranch_vccz .LBB0_26
	s_add_i32 s10, s21, s24
	v_add_u32_e32 v28, s10, v36
	v_ashrrev_i32_e32 v29, 31, v28
	v_lshlrev_b64 v[14:15], 13, v[28:29]
	v_lshl_add_u64 v[14:15], v[26:27], 0, v[14:15]
	global_store_dwordx4 v[14:15], v[2:5], off sc1
	s_mov_b64 s[14:15], 0
.LBB0_26:
	v_mov_b32_e32 v14, 0
	s_andn2_b64 vcc, exec, s[14:15]
	v_mov_b32_e32 v15, 0
	v_mov_b32_e32 v16, 0
	v_mov_b32_e32 v17, 0
	s_cbranch_vccnz .LBB0_28
	ds_read2_b32 v[14:15], v37 offset1:33
	s_add_i32 s10, s21, s24
	v_add_u32_e32 v28, s10, v36
	s_waitcnt lgkmcnt(0)
	v_mul_f32_e32 v14, v10, v14
	v_mul_f32_e32 v15, v11, v15
	v_cvt_pk_bf16_f32 v14, v14, v15
	ds_read2_b32 v[16:17], v37 offset0:66 offset1:99
	s_waitcnt lgkmcnt(0)
	v_mul_f32_e32 v15, v12, v16
	v_mul_f32_e32 v16, v13, v17
	v_cvt_pk_bf16_f32 v15, v15, v16
	ds_read2_b32 v[16:17], v37 offset0:132 offset1:165
	s_waitcnt lgkmcnt(0)
	v_mul_f32_e32 v16, v6, v16
	v_mul_f32_e32 v17, v7, v17
	v_cvt_pk_bf16_f32 v16, v16, v17
	ds_read2_b32 v[30:31], v37 offset0:198 offset1:231
	s_waitcnt lgkmcnt(0)
	v_mul_f32_e32 v17, v8, v30
	v_mul_f32_e32 v29, v9, v31
	v_cvt_pk_bf16_f32 v17, v17, v29
	ds_read2_b32 v[30:31], v37 offset0:8 offset1:41
	v_ashrrev_i32_e32 v29, 31, v28
	v_lshlrev_b64 v[46:47], 13, v[28:29]
	v_lshl_add_u64 v[46:47], v[26:27], 0, v[46:47]
	global_store_dwordx4 v[46:47], v[14:17], off sc1
	s_waitcnt lgkmcnt(0)
	s_nop 0
	v_mul_f32_e32 v14, v10, v30
	v_mul_f32_e32 v15, v11, v31
	v_cvt_pk_bf16_f32 v14, v14, v15
	ds_read2_b32 v[16:17], v37 offset0:74 offset1:107
	s_waitcnt lgkmcnt(0)
	v_mul_f32_e32 v15, v12, v16
	v_mul_f32_e32 v16, v13, v17
	v_cvt_pk_bf16_f32 v15, v15, v16
	ds_read2_b32 v[16:17], v37 offset0:140 offset1:173
	s_waitcnt lgkmcnt(0)
	v_mul_f32_e32 v16, v6, v16
	v_mul_f32_e32 v17, v7, v17
	v_cvt_pk_bf16_f32 v16, v16, v17
	ds_read2_b32 v[30:31], v37 offset0:206 offset1:239
	s_waitcnt lgkmcnt(0)
	v_mul_f32_e32 v17, v8, v30
	v_mul_f32_e32 v29, v9, v31
	v_cvt_pk_bf16_f32 v17, v17, v29
.LBB0_28:
	v_add_u32_e32 v30, 8, v28
	v_ashrrev_i32_e32 v31, 31, v30
	v_lshlrev_b64 v[30:31], 13, v[30:31]
	v_lshl_add_u64 v[30:31], v[26:27], 0, v[30:31]
	global_store_dwordx4 v[30:31], v[14:17], off sc1
	v_add_u32_e32 v30, 16, v28
	s_mov_b64 s[14:15], -1
	s_and_b64 vcc, exec, s[12:13]
	v_ashrrev_i32_e32 v31, 31, v30
	s_cbranch_vccz .LBB0_30
	v_lshlrev_b64 v[14:15], 13, v[30:31]
	v_lshl_add_u64 v[14:15], v[26:27], 0, v[14:15]
	global_store_dwordx4 v[14:15], v[2:5], off sc1
	s_mov_b64 s[14:15], 0
.LBB0_30:
	v_mov_b32_e32 v14, 0
	s_andn2_b64 vcc, exec, s[14:15]
	v_mov_b32_e32 v15, 0
	v_mov_b32_e32 v16, 0
	v_mov_b32_e32 v17, 0
	s_cbranch_vccnz .LBB0_12
	ds_read2_b32 v[14:15], v37 offset0:16 offset1:49
	v_lshlrev_b64 v[30:31], 13, v[30:31]
	v_lshl_add_u64 v[30:31], v[26:27], 0, v[30:31]
	s_waitcnt lgkmcnt(0)
	v_mul_f32_e32 v14, v10, v14
	v_mul_f32_e32 v15, v11, v15
	v_cvt_pk_bf16_f32 v14, v14, v15
	ds_read2_b32 v[16:17], v37 offset0:82 offset1:115
	s_waitcnt lgkmcnt(0)
	v_mul_f32_e32 v15, v12, v16
	v_mul_f32_e32 v16, v13, v17
	v_cvt_pk_bf16_f32 v15, v15, v16
	ds_read2_b32 v[16:17], v37 offset0:148 offset1:181
	s_waitcnt lgkmcnt(0)
	v_mul_f32_e32 v16, v6, v16
	v_mul_f32_e32 v17, v7, v17
	v_cvt_pk_bf16_f32 v16, v16, v17
	ds_read2_b32 v[46:47], v37 offset0:214 offset1:247
	s_waitcnt lgkmcnt(0)
	v_mul_f32_e32 v17, v8, v46
	v_mul_f32_e32 v29, v9, v47
	v_cvt_pk_bf16_f32 v17, v17, v29
	ds_read2_b32 v[46:47], v37 offset0:24 offset1:57
	global_store_dwordx4 v[30:31], v[14:17], off sc1
	s_waitcnt lgkmcnt(0)
	v_mul_f32_e32 v10, v10, v46
	v_mul_f32_e32 v11, v11, v47
	v_cvt_pk_bf16_f32 v14, v10, v11
	ds_read2_b32 v[10:11], v37 offset0:90 offset1:123
	s_waitcnt lgkmcnt(0)
	v_mul_f32_e32 v10, v12, v10
	v_mul_f32_e32 v11, v13, v11
	v_cvt_pk_bf16_f32 v15, v10, v11
	ds_read2_b32 v[10:11], v37 offset0:156 offset1:189
	s_waitcnt lgkmcnt(0)
	v_mul_f32_e32 v6, v6, v10
	v_mul_f32_e32 v7, v7, v11
	v_cvt_pk_bf16_f32 v16, v6, v7
	ds_read2_b32 v[6:7], v37 offset0:222 offset1:255
	s_waitcnt lgkmcnt(0)
	v_mul_f32_e32 v6, v8, v6
	v_mul_f32_e32 v7, v9, v7
	v_cvt_pk_bf16_f32 v17, v6, v7
	s_branch .LBB0_12

; __device__ __forceinline__ unsigned pk2(float lo, float hi) { unsigned r; asm volatile("v_cvt_pk_bf16_f32 %0, %1, %2" : "=v"(r) : "v"(lo), "v"(hi)); return r; }
; __device__ __forceinline__ void p0_transpose_item(const float* W, int K, int N, bf16* WT, int kb, int src_col0, int dst_row0, float* scr, int lane, const float* kgain = nullptr) {
;     ...
;     for (int j = 0; j < 4; ++j) { const int n = (lane >> 3) + 8 * j; const float* s = scr + (8 * c) * 33 + n;
;         v4u o;
;         if (src_col0 >= 0) { o.x = pk2(s[0 * 33] * g0.x, s[1 * 33] * g0.y); o.y = pk2(s[2 * 33] * g0.z, s[3 * 33] * g0.w); o.z = pk2(s[4 * 33] * g1.x, s[5 * 33] * g1.y); o.w = pk2(s[6 * 33] * g1.z, s[7 * 33] * g1.w); }
;         else { o.x = 0u; o.y = 0u; o.z = 0u; o.w = 0u; }
;         *(v4u*)(WT + (size_t)(dst_row0 + n) * K + k0 + 8 * c) = o; }
; template <class CM>
; __device__ __forceinline__ void p0_transpose_matrix(Frame& F, const float* W, int K, int N, bf16* WT, int nblk, CM colmap, int& it0, const float* kgain = nullptr) {
;     ...
;     for (int r = first; r < nitems; r += F.ngw) {
;         const int kb = r / nblk, nb = r % nblk;
;         p0_transpose_item(W, K, N, WT, kb, colmap(nb), nb * 32, scr, F.lane, kgain);
;     }
.LBB0_35:
	v_add_u32_e32 v14, 24, v6
	v_ashrrev_i32_e32 v15, 31, v14
	v_lshlrev_b64 v[14:15], 13, v[14:15]
	v_lshl_add_u64 v[12:13], v[12:13], 0, v[14:15]
	global_store_dwordx4 v[12:13], v[2:5], off sc1
	s_waitcnt lgkmcnt(0)
	s_add_i32 s14, s14, s76
	s_add_i32 s15, s15, s20
	s_cmpk_lt_i32 s14, 0x2000
	s_cbranch_scc0 .LBB0_46

; __device__ __forceinline__ unsigned pk2(float lo, float hi) { unsigned r; asm volatile("v_cvt_pk_bf16_f32 %0, %1, %2" : "=v"(r) : "v"(lo), "v"(hi)); return r; }
; __device__ __forceinline__ void p0_transpose_item(const float* W, int K, int N, bf16* WT, int kb, int src_col0, int dst_row0, float* scr, int lane, const float* kgain = nullptr) {
;     ...
;     for (int j = 0; j < 4; ++j) { const int n = (lane >> 3) + 8 * j; const float* s = scr + (8 * c) * 33 + n;
;         v4u o;
;         if (src_col0 >= 0) { o.x = pk2(s[0 * 33] * g0.x, s[1 * 33] * g0.y); o.y = pk2(s[2 * 33] * g0.z, s[3 * 33] * g0.w); o.z = pk2(s[4 * 33] * g1.x, s[5 * 33] * g1.y); o.w = pk2(s[6 * 33] * g1.z, s[7 * 33] * g1.w); }
;         else { o.x = 0u; o.y = 0u; o.z = 0u; o.w = 0u; }
;         *(v4u*)(WT + (size_t)(dst_row0 + n) * K + k0 + 8 * c) = o; }
.LBB0_38:
	s_waitcnt lgkmcnt(0)
	s_ashr_i32 s13, s12, 31
	v_lshl_add_u64 v[12:13], s[12:13], 1, v[10:11]
	s_mov_b64 s[12:13], -1
	s_and_b64 vcc, exec, s[10:11]
	s_cbranch_vccz .LBB0_40
	s_add_i32 s2, s21, s15
	v_add_u32_e32 v2, s2, v20
	v_ashrrev_i32_e32 v3, 31, v2
	v_lshlrev_b64 v[4:5], 13, v[2:3]
	v_lshl_add_u64 v[4:5], v[12:13], 0, v[4:5]
	global_store_dwordx4 v[4:5], v[34:37], off sc1
	s_mov_b64 s[12:13], 0
	v_mov_b32_e32 v6, v2
.LBB0_40:
	v_mov_b32_e32 v2, 0
	s_andn2_b64 vcc, exec, s[12:13]
	v_mov_b32_e32 v3, 0
	v_mov_b32_e32 v4, 0
	v_mov_b32_e32 v5, 0
	s_cbranch_vccnz .LBB0_42
	ds_read2_b32 v[2:3], v21 offset1:33
	s_add_i32 s21, s21, s15
	s_waitcnt lgkmcnt(0)
	v_cvt_pk_bf16_f32 v2, v2, v3
	ds_read2_b32 v[4:5], v21 offset0:66 offset1:99
	v_add_u32_e32 v6, s21, v20
	s_waitcnt lgkmcnt(0)
	v_cvt_pk_bf16_f32 v3, v4, v5
	ds_read2_b32 v[4:5], v21 offset0:132 offset1:165
	v_lshlrev_b64 v[30:31], 13, v[6:7]
	s_waitcnt lgkmcnt(0)
	v_cvt_pk_bf16_f32 v4, v4, v5
	ds_read2_b32 v[14:15], v21 offset0:198 offset1:231
	s_waitcnt lgkmcnt(0)
	v_cvt_pk_bf16_f32 v5, v14, v15
	v_lshl_add_u64 v[30:31], v[12:13], 0, v[30:31]
	ds_read2_b32 v[14:15], v21 offset0:8 offset1:41
	global_store_dwordx4 v[30:31], v[2:5], off sc1
	s_waitcnt lgkmcnt(0)
	s_nop 0
	v_cvt_pk_bf16_f32 v2, v14, v15
	ds_read2_b32 v[4:5], v21 offset0:74 offset1:107
	s_waitcnt lgkmcnt(0)
	v_cvt_pk_bf16_f32 v3, v4, v5
	ds_read2_b32 v[4:5], v21 offset0:140 offset1:173
	s_waitcnt lgkmcnt(0)
	v_cvt_pk_bf16_f32 v4, v4, v5
	ds_read2_b32 v[14:15], v21 offset0:206 offset1:239
	s_waitcnt lgkmcnt(0)
	v_cvt_pk_bf16_f32 v5, v14, v15
.LBB0_42:
	v_add_u32_e32 v14, 8, v6
	v_ashrrev_i32_e32 v15, 31, v14
	v_lshlrev_b64 v[14:15], 13, v[14:15]
	v_lshl_add_u64 v[14:15], v[12:13], 0, v[14:15]
	global_store_dwordx4 v[14:15], v[2:5], off sc1
	s_mov_b64 s[12:13], -1
	s_and_b64 vcc, exec, s[10:11]
	v_add_u32_e32 v14, 16, v6
	s_cbranch_vccz .LBB0_44
	v_ashrrev_i32_e32 v15, 31, v14
	v_lshlrev_b64 v[2:3], 13, v[14:15]
	v_lshl_add_u64 v[2:3], v[12:13], 0, v[2:3]
	global_store_dwordx4 v[2:3], v[34:37], off sc1
	s_mov_b64 s[12:13], 0
.LBB0_44:
	v_mov_b32_e32 v2, 0
	s_andn2_b64 vcc, exec, s[12:13]
	v_mov_b32_e32 v3, 0
	v_mov_b32_e32 v4, 0
	v_mov_b32_e32 v5, 0
	s_cbranch_vccnz .LBB0_35
	ds_read2_b32 v[2:3], v21 offset0:16 offset1:49
	s_waitcnt lgkmcnt(0)
	v_cvt_pk_bf16_f32 v2, v2, v3
	ds_read2_b32 v[4:5], v21 offset0:82 offset1:115
	v_mov_b32_e32 v15, v7
	s_waitcnt lgkmcnt(0)
	v_cvt_pk_bf16_f32 v3, v4, v5
	ds_read2_b32 v[4:5], v21 offset0:148 offset1:181
	v_lshlrev_b64 v[14:15], 13, v[14:15]
	s_waitcnt lgkmcnt(0)
	v_cvt_pk_bf16_f32 v4, v4, v5
	ds_read2_b32 v[30:31], v21 offset0:214 offset1:247
	s_waitcnt lgkmcnt(0)
	v_cvt_pk_bf16_f32 v5, v30, v31
	v_lshl_add_u64 v[14:15], v[12:13], 0, v[14:15]
	ds_read2_b32 v[30:31], v21 offset0:24 offset1:57
	global_store_dwordx4 v[14:15], v[2:5], off sc1
	s_waitcnt lgkmcnt(0)
	s_nop 0
	v_cvt_pk_bf16_f32 v2, v30, v31
	ds_read2_b32 v[4:5], v21 offset0:90 offset1:123
	s_waitcnt lgkmcnt(0)
	v_cvt_pk_bf16_f32 v3, v4, v5
	ds_read2_b32 v[4:5], v21 offset0:156 offset1:189
	s_waitcnt lgkmcnt(0)
	v_cvt_pk_bf16_f32 v4, v4, v5
	ds_read2_b32 v[14:15], v21 offset0:222 offset1:255
	s_waitcnt lgkmcnt(0)
	v_cvt_pk_bf16_f32 v5, v14, v15
	s_branch .LBB0_35

; __device__ __forceinline__ unsigned pk2(float lo, float hi) { unsigned r; asm volatile("v_cvt_pk_bf16_f32 %0, %1, %2" : "=v"(r) : "v"(lo), "v"(hi)); return r; }
; __device__ __forceinline__ void p0_transpose_item(const float* W, int K, int N, bf16* WT, int kb, int src_col0, int dst_row0, float* scr, int lane, const float* kgain = nullptr) {
;     ...
;     for (int j = 0; j < 4; ++j) { const int n = (lane >> 3) + 8 * j; const float* s = scr + (8 * c) * 33 + n;
;         v4u o;
;         if (src_col0 >= 0) { o.x = pk2(s[0 * 33] * g0.x, s[1 * 33] * g0.y); o.y = pk2(s[2 * 33] * g0.z, s[3 * 33] * g0.w); o.z = pk2(s[4 * 33] * g1.x, s[5 * 33] * g1.y); o.w = pk2(s[6 * 33] * g1.z, s[7 * 33] * g1.w); }
;         else { o.x = 0u; o.y = 0u; o.z = 0u; o.w = 0u; }
;         *(v4u*)(WT + (size_t)(dst_row0 + n) * K + k0 + 8 * c) = o; }
; template <class CM>
; __device__ __forceinline__ void p0_transpose_matrix(Frame& F, const float* W, int K, int N, bf16* WT, int nblk, CM colmap, int& it0, const float* kgain = nullptr) {
;     ...
;     for (int r = first; r < nitems; r += F.ngw) {
;         const int kb = r / nblk, nb = r % nblk;
;         p0_transpose_item(W, K, N, WT, kb, colmap(nb), nb * 32, scr, F.lane, kgain);
;     }
.LBB0_49:
	s_waitcnt vmcnt(2)
	v_add_u32_e32 v2, 24, v14
	v_ashrrev_i32_e32 v3, 31, v2
	v_lshlrev_b64 v[2:3], 13, v[2:3]
	v_lshl_add_u64 v[2:3], v[24:25], 0, v[2:3]
	global_store_dwordx4 v[2:3], v[10:13], off sc1
	s_waitcnt lgkmcnt(0)
	s_add_i32 s14, s14, s76
	s_add_i32 s15, s15, s20
	s_cmpk_lt_i32 s14, 0x4000
	s_cbranch_scc0 .LBB0_61

; __device__ __forceinline__ unsigned pk2(float lo, float hi) { unsigned r; asm volatile("v_cvt_pk_bf16_f32 %0, %1, %2" : "=v"(r) : "v"(lo), "v"(hi)); return r; }
; __device__ __forceinline__ void p0_transpose_item(const float* W, int K, int N, bf16* WT, int kb, int src_col0, int dst_row0, float* scr, int lane, const float* kgain = nullptr) {
;     ...
;     for (int j = 0; j < 4; ++j) { const int n = (lane >> 3) + 8 * j; const float* s = scr + (8 * c) * 33 + n;
;         v4u o;
;         if (src_col0 >= 0) { o.x = pk2(s[0 * 33] * g0.x, s[1 * 33] * g0.y); o.y = pk2(s[2 * 33] * g0.z, s[3 * 33] * g0.w); o.z = pk2(s[4 * 33] * g1.x, s[5 * 33] * g1.y); o.w = pk2(s[6 * 33] * g1.z, s[7 * 33] * g1.w); }
;         else { o.x = 0u; o.y = 0u; o.z = 0u; o.w = 0u; }
;         *(v4u*)(WT + (size_t)(dst_row0 + n) * K + k0 + 8 * c) = o; }
.LBB0_53:
	s_waitcnt lgkmcnt(0)
	v_lshl_add_u64 v[24:25], s[12:13], 1, v[22:23]
	s_mov_b64 s[12:13], -1
	s_and_b64 vcc, exec, s[10:11]
	s_cbranch_vccz .LBB0_55
	s_add_i32 s2, s21, s15
	v_add_u32_e32 v10, s2, v30
	v_ashrrev_i32_e32 v11, 31, v10
	v_lshlrev_b64 v[12:13], 13, v[10:11]
	v_lshl_add_u64 v[12:13], v[24:25], 0, v[12:13]
	global_store_dwordx4 v[12:13], v[42:45], off sc1
	s_mov_b64 s[12:13], 0
	v_mov_b32_e32 v14, v10
.LBB0_55:
	v_mov_b32_e32 v10, 0
	s_andn2_b64 vcc, exec, s[12:13]
	v_mov_b32_e32 v11, 0
	v_mov_b32_e32 v12, 0
	v_mov_b32_e32 v13, 0
	s_cbranch_vccnz .LBB0_57
	ds_read2_b32 v[10:11], v31 offset1:33
	s_add_i32 s21, s21, s15
	s_waitcnt vmcnt(0) lgkmcnt(0)
	v_mul_f32_e32 v10, v6, v10
	v_mul_f32_e32 v11, v7, v11
	v_cvt_pk_bf16_f32 v10, v10, v11
	ds_read2_b32 v[12:13], v31 offset0:66 offset1:99
	s_waitcnt lgkmcnt(0)
	v_mul_f32_e32 v11, v8, v12
	v_mul_f32_e32 v12, v9, v13
	v_cvt_pk_bf16_f32 v11, v11, v12
	ds_read2_b32 v[12:13], v31 offset0:132 offset1:165
	s_waitcnt lgkmcnt(0)
	v_mul_f32_e32 v12, v2, v12
	v_mul_f32_e32 v13, v3, v13
	v_cvt_pk_bf16_f32 v12, v12, v13
	ds_read2_b32 v[26:27], v31 offset0:198 offset1:231
	s_waitcnt lgkmcnt(0)
	v_mul_f32_e32 v13, v4, v26
	v_mul_f32_e32 v14, v5, v27
	v_cvt_pk_bf16_f32 v13, v13, v14
	ds_read2_b32 v[26:27], v31 offset0:8 offset1:41
	v_add_u32_e32 v14, s21, v30
	v_lshlrev_b64 v[46:47], 13, v[14:15]
	v_lshl_add_u64 v[46:47], v[24:25], 0, v[46:47]
	global_store_dwordx4 v[46:47], v[10:13], off sc1
	s_waitcnt lgkmcnt(0)
	s_nop 0
	v_mul_f32_e32 v10, v6, v26
	v_mul_f32_e32 v11, v7, v27
	v_cvt_pk_bf16_f32 v10, v10, v11
	ds_read2_b32 v[12:13], v31 offset0:74 offset1:107
	s_waitcnt lgkmcnt(0)
	v_mul_f32_e32 v11, v8, v12
	v_mul_f32_e32 v12, v9, v13
	v_cvt_pk_bf16_f32 v11, v11, v12
	ds_read2_b32 v[12:13], v31 offset0:140 offset1:173
	s_waitcnt lgkmcnt(0)
	v_mul_f32_e32 v12, v2, v12
	v_mul_f32_e32 v13, v3, v13
	v_cvt_pk_bf16_f32 v12, v12, v13
	ds_read2_b32 v[26:27], v31 offset0:206 offset1:239
	s_waitcnt lgkmcnt(0)
	v_mul_f32_e32 v13, v4, v26
	v_mul_f32_e32 v26, v5, v27
	v_cvt_pk_bf16_f32 v13, v13, v26
.LBB0_57:
	v_add_u32_e32 v26, 8, v14
	v_ashrrev_i32_e32 v27, 31, v26
	v_lshlrev_b64 v[26:27], 13, v[26:27]
	v_lshl_add_u64 v[26:27], v[24:25], 0, v[26:27]
	global_store_dwordx4 v[26:27], v[10:13], off sc1
	s_mov_b64 s[12:13], -1
	s_and_b64 vcc, exec, s[10:11]
	v_add_u32_e32 v26, 16, v14
	s_cbranch_vccz .LBB0_59
	v_ashrrev_i32_e32 v27, 31, v26
	v_lshlrev_b64 v[10:11], 13, v[26:27]
	v_lshl_add_u64 v[10:11], v[24:25], 0, v[10:11]
	global_store_dwordx4 v[10:11], v[42:45], off sc1
	s_mov_b64 s[12:13], 0
.LBB0_59:
	v_mov_b32_e32 v10, 0
	s_andn2_b64 vcc, exec, s[12:13]
	v_mov_b32_e32 v11, 0
	v_mov_b32_e32 v12, 0
	v_mov_b32_e32 v13, 0
	s_cbranch_vccnz .LBB0_49
	ds_read2_b32 v[10:11], v31 offset0:16 offset1:49
	s_waitcnt vmcnt(1) lgkmcnt(0)
	v_mul_f32_e32 v10, v6, v10
	v_mul_f32_e32 v11, v7, v11
	v_cvt_pk_bf16_f32 v10, v10, v11
	ds_read2_b32 v[12:13], v31 offset0:82 offset1:115
	s_waitcnt lgkmcnt(0)
	v_mul_f32_e32 v11, v8, v12
	v_mul_f32_e32 v12, v9, v13
	v_cvt_pk_bf16_f32 v11, v11, v12
	ds_read2_b32 v[12:13], v31 offset0:148 offset1:181
	s_waitcnt lgkmcnt(0)
	v_mul_f32_e32 v12, v2, v12
	v_mul_f32_e32 v13, v3, v13
	v_cvt_pk_bf16_f32 v12, v12, v13
	ds_read2_b32 v[46:47], v31 offset0:214 offset1:247
	s_waitcnt lgkmcnt(0)
	v_mul_f32_e32 v13, v4, v46
	v_mul_f32_e32 v27, v5, v47
	v_cvt_pk_bf16_f32 v13, v13, v27
	ds_read2_b32 v[46:47], v31 offset0:24 offset1:57
	v_mov_b32_e32 v27, v15
	v_lshlrev_b64 v[26:27], 13, v[26:27]
	v_lshl_add_u64 v[26:27], v[24:25], 0, v[26:27]
	global_store_dwordx4 v[26:27], v[10:13], off sc1
	s_waitcnt lgkmcnt(0)
	v_mul_f32_e32 v6, v6, v46
	v_mul_f32_e32 v7, v7, v47
	v_cvt_pk_bf16_f32 v10, v6, v7
	ds_read2_b32 v[6:7], v31 offset0:90 offset1:123
	s_waitcnt lgkmcnt(0)
	v_mul_f32_e32 v6, v8, v6
	v_mul_f32_e32 v7, v9, v7
	v_cvt_pk_bf16_f32 v11, v6, v7
	ds_read2_b32 v[6:7], v31 offset0:156 offset1:189
	s_waitcnt lgkmcnt(0)
	v_mul_f32_e32 v2, v2, v6
	v_mul_f32_e32 v3, v3, v7
	v_cvt_pk_bf16_f32 v12, v2, v3
	ds_read2_b32 v[2:3], v31 offset0:222 offset1:255
	s_waitcnt lgkmcnt(0)
	v_mul_f32_e32 v2, v4, v2
	v_mul_f32_e32 v3, v5, v3
	v_cvt_pk_bf16_f32 v13, v2, v3
	s_branch .LBB0_49

; __device__ __forceinline__ unsigned pk2(float lo, float hi) { unsigned r; asm volatile("v_cvt_pk_bf16_f32 %0, %1, %2" : "=v"(r) : "v"(lo), "v"(hi)); return r; }
; __device__ __forceinline__ void p0_transpose_item(const float* W, int K, int N, bf16* WT, int kb, int src_col0, int dst_row0, float* scr, int lane, const float* kgain = nullptr) {
;     ...
;     for (int j = 0; j < 4; ++j) { const int n = (lane >> 3) + 8 * j; const float* s = scr + (8 * c) * 33 + n;
;         v4u o;
;         if (src_col0 >= 0) { o.x = pk2(s[0 * 33] * g0.x, s[1 * 33] * g0.y); o.y = pk2(s[2 * 33] * g0.z, s[3 * 33] * g0.w); o.z = pk2(s[4 * 33] * g1.x, s[5 * 33] * g1.y); o.w = pk2(s[6 * 33] * g1.z, s[7 * 33] * g1.w); }
;         else { o.x = 0u; o.y = 0u; o.z = 0u; o.w = 0u; }
;         *(v4u*)(WT + (size_t)(dst_row0 + n) * K + k0 + 8 * c) = o; }
; template <class CM>
; __device__ __forceinline__ void p0_transpose_matrix(Frame& F, const float* W, int K, int N, bf16* WT, int nblk, CM colmap, int& it0, const float* kgain = nullptr) {
;     ...
;     for (int r = first; r < nitems; r += F.ngw) {
;         const int kb = r / nblk, nb = r % nblk;
;         p0_transpose_item(W, K, N, WT, kb, colmap(nb), nb * 32, scr, F.lane, kgain);
;     }
.LBB0_64:
	v_add_u32_e32 v14, 24, v6
	v_ashrrev_i32_e32 v15, 31, v14
	v_lshlrev_b64 v[14:15], 13, v[14:15]
	v_lshl_add_u64 v[12:13], v[12:13], 0, v[14:15]
	global_store_dwordx4 v[12:13], v[2:5], off sc1
	s_waitcnt lgkmcnt(0)
	s_add_i32 s15, s15, s76
	s_add_i32 s20, s20, s21
	s_cmpk_lt_i32 s15, 0x2000
	s_cbranch_scc0 .LBB0_75

; __device__ __forceinline__ unsigned pk2(float lo, float hi) { unsigned r; asm volatile("v_cvt_pk_bf16_f32 %0, %1, %2" : "=v"(r) : "v"(lo), "v"(hi)); return r; }
; __device__ __forceinline__ void p0_transpose_item(const float* W, int K, int N, bf16* WT, int kb, int src_col0, int dst_row0, float* scr, int lane, const float* kgain = nullptr) {
;     ...
;     for (int j = 0; j < 4; ++j) { const int n = (lane >> 3) + 8 * j; const float* s = scr + (8 * c) * 33 + n;
;         v4u o;
;         if (src_col0 >= 0) { o.x = pk2(s[0 * 33] * g0.x, s[1 * 33] * g0.y); o.y = pk2(s[2 * 33] * g0.z, s[3 * 33] * g0.w); o.z = pk2(s[4 * 33] * g1.x, s[5 * 33] * g1.y); o.w = pk2(s[6 * 33] * g1.z, s[7 * 33] * g1.w); }
;         else { o.x = 0u; o.y = 0u; o.z = 0u; o.w = 0u; }
;         *(v4u*)(WT + (size_t)(dst_row0 + n) * K + k0 + 8 * c) = o; }
.LBB0_67:
	s_waitcnt lgkmcnt(0)
	s_ashr_i32 s13, s12, 31
	v_lshl_add_u64 v[12:13], s[12:13], 1, v[10:11]
	s_mov_b64 s[12:13], -1
	s_and_b64 vcc, exec, s[10:11]
	s_cbranch_vccz .LBB0_69
	s_add_i32 s2, s22, s20
	v_add_u32_e32 v2, s2, v20
	v_ashrrev_i32_e32 v3, 31, v2
	v_lshlrev_b64 v[4:5], 13, v[2:3]
	v_lshl_add_u64 v[4:5], v[12:13], 0, v[4:5]
	global_store_dwordx4 v[4:5], v[34:37], off sc1
	s_mov_b64 s[12:13], 0
	v_mov_b32_e32 v6, v2
.LBB0_69:
	v_mov_b32_e32 v2, 0
	s_andn2_b64 vcc, exec, s[12:13]
	v_mov_b32_e32 v3, 0
	v_mov_b32_e32 v4, 0
	v_mov_b32_e32 v5, 0
	s_cbranch_vccnz .LBB0_71
	ds_read2_b32 v[2:3], v21 offset1:33
	s_add_i32 s22, s22, s20
	s_waitcnt lgkmcnt(0)
	v_cvt_pk_bf16_f32 v2, v2, v3
	ds_read2_b32 v[4:5], v21 offset0:66 offset1:99
	v_add_u32_e32 v6, s22, v20
	s_waitcnt lgkmcnt(0)
	v_cvt_pk_bf16_f32 v3, v4, v5
	ds_read2_b32 v[4:5], v21 offset0:132 offset1:165
	v_lshlrev_b64 v[30:31], 13, v[6:7]
	s_waitcnt lgkmcnt(0)
	v_cvt_pk_bf16_f32 v4, v4, v5
	ds_read2_b32 v[14:15], v21 offset0:198 offset1:231
	s_waitcnt lgkmcnt(0)
	v_cvt_pk_bf16_f32 v5, v14, v15
	v_lshl_add_u64 v[30:31], v[12:13], 0, v[30:31]
	ds_read2_b32 v[14:15], v21 offset0:8 offset1:41
	global_store_dwordx4 v[30:31], v[2:5], off sc1
	s_waitcnt lgkmcnt(0)
	s_nop 0
	v_cvt_pk_bf16_f32 v2, v14, v15
	ds_read2_b32 v[4:5], v21 offset0:74 offset1:107
	s_waitcnt lgkmcnt(0)
	v_cvt_pk_bf16_f32 v3, v4, v5
	ds_read2_b32 v[4:5], v21 offset0:140 offset1:173
	s_waitcnt lgkmcnt(0)
	v_cvt_pk_bf16_f32 v4, v4, v5
	ds_read2_b32 v[14:15], v21 offset0:206 offset1:239
	s_waitcnt lgkmcnt(0)
	v_cvt_pk_bf16_f32 v5, v14, v15

; __device__ __forceinline__ unsigned pk2(float lo, float hi) { unsigned r; asm volatile("v_cvt_pk_bf16_f32 %0, %1, %2" : "=v"(r) : "v"(lo), "v"(hi)); return r; }
; __device__ __forceinline__ void p0_transpose_item(const float* W, int K, int N, bf16* WT, int kb, int src_col0, int dst_row0, float* scr, int lane, const float* kgain = nullptr) {
;     ...
;     for (int j = 0; j < 4; ++j) { const int n = (lane >> 3) + 8 * j; const float* s = scr + (8 * c) * 33 + n;
;         v4u o;
;         if (src_col0 >= 0) { o.x = pk2(s[0 * 33] * g0.x, s[1 * 33] * g0.y); o.y = pk2(s[2 * 33] * g0.z, s[3 * 33] * g0.w); o.z = pk2(s[4 * 33] * g1.x, s[5 * 33] * g1.y); o.w = pk2(s[6 * 33] * g1.z, s[7 * 33] * g1.w); }
;         else { o.x = 0u; o.y = 0u; o.z = 0u; o.w = 0u; }
;         *(v4u*)(WT + (size_t)(dst_row0 + n) * K + k0 + 8 * c) = o; }
; template <class CM>
; __device__ __forceinline__ void p0_transpose_matrix(Frame& F, const float* W, int K, int N, bf16* WT, int nblk, CM colmap, int& it0, const float* kgain = nullptr) {
;     ...
;     for (int r = first; r < nitems; r += F.ngw) {
;         const int kb = r / nblk, nb = r % nblk;
;         p0_transpose_item(W, K, N, WT, kb, colmap(nb), nb * 32, scr, F.lane, kgain);
;     }
.LBB0_79:
	s_waitcnt vmcnt(2)
	v_add_u32_e32 v2, 24, v20
	v_ashrrev_i32_e32 v3, 31, v2
	v_lshlrev_b64 v[2:3], 13, v[2:3]
	v_lshl_add_u64 v[2:3], v[28:29], 0, v[2:3]
	global_store_dwordx4 v[2:3], v[10:13], off sc1
	s_waitcnt lgkmcnt(0)
	s_add_i32 s12, s12, s76
	s_add_i32 s13, s13, s15
	s_cmp_lt_i32 s12, 0x8000
	s_cbranch_scc0 .LBB0_91

; __device__ __forceinline__ unsigned pk2(float lo, float hi) { unsigned r; asm volatile("v_cvt_pk_bf16_f32 %0, %1, %2" : "=v"(r) : "v"(lo), "v"(hi)); return r; }
; __device__ __forceinline__ void p0_transpose_item(const float* W, int K, int N, bf16* WT, int kb, int src_col0, int dst_row0, float* scr, int lane, const float* kgain = nullptr) {
;     ...
;     for (int j = 0; j < 4; ++j) { const int n = (lane >> 3) + 8 * j; const float* s = scr + (8 * c) * 33 + n;
;         v4u o;
;         if (src_col0 >= 0) { o.x = pk2(s[0 * 33] * g0.x, s[1 * 33] * g0.y); o.y = pk2(s[2 * 33] * g0.z, s[3 * 33] * g0.w); o.z = pk2(s[4 * 33] * g1.x, s[5 * 33] * g1.y); o.w = pk2(s[6 * 33] * g1.z, s[7 * 33] * g1.w); }
;         else { o.x = 0u; o.y = 0u; o.z = 0u; o.w = 0u; }
;         *(v4u*)(WT + (size_t)(dst_row0 + n) * K + k0 + 8 * c) = o; }
.LBB0_83:
	s_waitcnt lgkmcnt(0)
	v_lshl_add_u64 v[28:29], s[10:11], 1, v[26:27]
	s_mov_b64 s[10:11], -1
	s_and_b64 vcc, exec, s[4:5]
	s_cbranch_vccz .LBB0_85
	s_add_i32 s2, s20, s13
	v_add_u32_e32 v10, s2, v1
	v_ashrrev_i32_e32 v11, 31, v10
	v_lshlrev_b64 v[12:13], 13, v[10:11]
	v_lshl_add_u64 v[12:13], v[28:29], 0, v[12:13]
	global_store_dwordx4 v[12:13], v[46:49], off sc1
	s_mov_b64 s[10:11], 0
	v_mov_b32_e32 v20, v10
.LBB0_85:
	v_mov_b32_e32 v10, 0
	s_andn2_b64 vcc, exec, s[10:11]
	v_mov_b32_e32 v11, 0
	v_mov_b32_e32 v12, 0
	v_mov_b32_e32 v13, 0
	s_cbranch_vccnz .LBB0_87
	ds_read2_b32 v[10:11], v39 offset1:33
	s_add_i32 s20, s20, s13
	s_waitcnt vmcnt(0) lgkmcnt(0)
	v_mul_f32_e32 v10, v6, v10
	v_mul_f32_e32 v11, v7, v11
	v_cvt_pk_bf16_f32 v10, v10, v11
	ds_read2_b32 v[12:13], v39 offset0:66 offset1:99
	s_waitcnt lgkmcnt(0)
	v_mul_f32_e32 v11, v8, v12
	v_mul_f32_e32 v12, v9, v13
	v_cvt_pk_bf16_f32 v11, v11, v12
	ds_read2_b32 v[12:13], v39 offset0:132 offset1:165
	s_waitcnt lgkmcnt(0)
	v_mul_f32_e32 v12, v2, v12
	v_mul_f32_e32 v13, v3, v13
	v_cvt_pk_bf16_f32 v12, v12, v13
	ds_read2_b32 v[30:31], v39 offset0:198 offset1:231
	s_waitcnt lgkmcnt(0)
	v_mul_f32_e32 v13, v4, v30
	v_mul_f32_e32 v20, v5, v31
	v_cvt_pk_bf16_f32 v13, v13, v20
	ds_read2_b32 v[30:31], v39 offset0:8 offset1:41
	v_add_u32_e32 v20, s20, v1
	v_lshlrev_b64 v[50:51], 13, v[20:21]
	v_lshl_add_u64 v[50:51], v[28:29], 0, v[50:51]
	global_store_dwordx4 v[50:51], v[10:13], off sc1
	s_waitcnt lgkmcnt(0)
	s_nop 0
	v_mul_f32_e32 v10, v6, v30
	v_mul_f32_e32 v11, v7, v31
	v_cvt_pk_bf16_f32 v10, v10, v11
	ds_read2_b32 v[12:13], v39 offset0:74 offset1:107
	s_waitcnt lgkmcnt(0)
	v_mul_f32_e32 v11, v8, v12
	v_mul_f32_e32 v12, v9, v13
	v_cvt_pk_bf16_f32 v11, v11, v12
	ds_read2_b32 v[12:13], v39 offset0:140 offset1:173
	s_waitcnt lgkmcnt(0)
	v_mul_f32_e32 v12, v2, v12
	v_mul_f32_e32 v13, v3, v13
	v_cvt_pk_bf16_f32 v12, v12, v13
	ds_read2_b32 v[30:31], v39 offset0:206 offset1:239
	s_waitcnt lgkmcnt(0)
	v_mul_f32_e32 v13, v4, v30
	v_mul_f32_e32 v30, v5, v31
	v_cvt_pk_bf16_f32 v13, v13, v30
.LBB0_87:
	v_add_u32_e32 v30, 8, v20
	v_ashrrev_i32_e32 v31, 31, v30
	v_lshlrev_b64 v[30:31], 13, v[30:31]
	v_lshl_add_u64 v[30:31], v[28:29], 0, v[30:31]
	global_store_dwordx4 v[30:31], v[10:13], off sc1
	s_mov_b64 s[10:11], -1
	s_and_b64 vcc, exec, s[4:5]
	v_add_u32_e32 v30, 16, v20
	s_cbranch_vccz .LBB0_89
	v_ashrrev_i32_e32 v31, 31, v30
	v_lshlrev_b64 v[10:11], 13, v[30:31]
	v_lshl_add_u64 v[10:11], v[28:29], 0, v[10:11]
	global_store_dwordx4 v[10:11], v[46:49], off sc1
	s_mov_b64 s[10:11], 0
.LBB0_89:
	v_mov_b32_e32 v10, 0
	s_andn2_b64 vcc, exec, s[10:11]
	v_mov_b32_e32 v11, 0
	v_mov_b32_e32 v12, 0
	v_mov_b32_e32 v13, 0
	s_cbranch_vccnz .LBB0_79
	ds_read2_b32 v[10:11], v39 offset0:16 offset1:49
	s_waitcnt vmcnt(1) lgkmcnt(0)
	v_mul_f32_e32 v10, v6, v10
	v_mul_f32_e32 v11, v7, v11
	v_cvt_pk_bf16_f32 v10, v10, v11
	ds_read2_b32 v[12:13], v39 offset0:82 offset1:115
	s_waitcnt lgkmcnt(0)
	v_mul_f32_e32 v11, v8, v12
	v_mul_f32_e32 v12, v9, v13
	v_cvt_pk_bf16_f32 v11, v11, v12
	ds_read2_b32 v[12:13], v39 offset0:148 offset1:181
	s_waitcnt lgkmcnt(0)
	v_mul_f32_e32 v12, v2, v12
	v_mul_f32_e32 v13, v3, v13
	v_cvt_pk_bf16_f32 v12, v12, v13
	ds_read2_b32 v[50:51], v39 offset0:214 offset1:247
	s_waitcnt lgkmcnt(0)
	v_mul_f32_e32 v13, v4, v50
	v_mul_f32_e32 v31, v5, v51
	v_cvt_pk_bf16_f32 v13, v13, v31
	ds_read2_b32 v[50:51], v39 offset0:24 offset1:57
	v_mov_b32_e32 v31, v21
	v_lshlrev_b64 v[30:31], 13, v[30:31]
	v_lshl_add_u64 v[30:31], v[28:29], 0, v[30:31]
	global_store_dwordx4 v[30:31], v[10:13], off sc1
	s_waitcnt lgkmcnt(0)
	v_mul_f32_e32 v6, v6, v50
	v_mul_f32_e32 v7, v7, v51
	v_cvt_pk_bf16_f32 v10, v6, v7
	ds_read2_b32 v[6:7], v39 offset0:90 offset1:123
	s_waitcnt lgkmcnt(0)
	v_mul_f32_e32 v6, v8, v6
	v_mul_f32_e32 v7, v9, v7
	v_cvt_pk_bf16_f32 v11, v6, v7
	ds_read2_b32 v[6:7], v39 offset0:156 offset1:189
	s_waitcnt lgkmcnt(0)
	v_mul_f32_e32 v2, v2, v6
	v_mul_f32_e32 v3, v3, v7
	v_cvt_pk_bf16_f32 v12, v2, v3
	ds_read2_b32 v[2:3], v39 offset0:222 offset1:255
	s_waitcnt lgkmcnt(0)
	v_mul_f32_e32 v2, v4, v2
	v_mul_f32_e32 v3, v5, v3
	v_cvt_pk_bf16_f32 v13, v2, v3
	s_branch .LBB0_79

; __device__ __forceinline__ unsigned pk2(float lo, float hi) { unsigned r; asm volatile("v_cvt_pk_bf16_f32 %0, %1, %2" : "=v"(r) : "v"(lo), "v"(hi)); return r; }
; __device__ __forceinline__ void p0_transpose_item(const float* W, int K, int N, bf16* WT, int kb, int src_col0, int dst_row0, float* scr, int lane, const float* kgain = nullptr) {
;     ...
;     for (int j = 0; j < 4; ++j) { const int n = (lane >> 3) + 8 * j; const float* s = scr + (8 * c) * 33 + n;
;         v4u o;
;         if (src_col0 >= 0) { o.x = pk2(s[0 * 33] * g0.x, s[1 * 33] * g0.y); o.y = pk2(s[2 * 33] * g0.z, s[3 * 33] * g0.w); o.z = pk2(s[4 * 33] * g1.x, s[5 * 33] * g1.y); o.w = pk2(s[6 * 33] * g1.z, s[7 * 33] * g1.w); }
;         else { o.x = 0u; o.y = 0u; o.z = 0u; o.w = 0u; }
;         *(v4u*)(WT + (size_t)(dst_row0 + n) * K + k0 + 8 * c) = o; }
; template <class CM, class RM>
; __device__ __forceinline__ void p0_transpose_matrix2(Frame& F, const float* W, int K, int N, bf16* WT, int nblk, CM colmap, RM rowmap, int& it0, const float* kgain = nullptr) {
;     ...
;     for (int r = first; r < nitems; r += F.ngw) {
;         const int kb = r / nblk, nb = r % nblk;
;         p0_transpose_item(W, K, N, WT, kb, colmap(nb), rowmap(nb), scr, F.lane, kgain);
;     }
.LBB0_96:
	v_or_b32_e32 v42, s2, v35
	v_ashrrev_i32_e32 v43, 31, v42
	v_lshlrev_b64 v[42:43], 9, v[42:43]
	v_lshl_add_u64 v[20:21], v[20:21], 0, v[42:43]
	global_store_dwordx4 v[20:21], v[2:5], off sc1
	s_waitcnt lgkmcnt(0)
	s_add_i32 s19, s19, s76
	s_add_i32 s21, s21, s15
	s_add_i32 s22, s22, s12
	s_cmp_lt_i32 s19, 32
	s_cbranch_scc0 .LBB0_93

; __device__ __forceinline__ unsigned pk2(float lo, float hi) { unsigned r; asm volatile("v_cvt_pk_bf16_f32 %0, %1, %2" : "=v"(r) : "v"(lo), "v"(hi)); return r; }
; __device__ __forceinline__ void p0_transpose_item(const float* W, int K, int N, bf16* WT, int kb, int src_col0, int dst_row0, float* scr, int lane, const float* kgain = nullptr) {
;     ...
;     for (int j = 0; j < 4; ++j) { const int n = (lane >> 3) + 8 * j; const float* s = scr + (8 * c) * 33 + n;
;         v4u o;
;         if (src_col0 >= 0) { o.x = pk2(s[0 * 33] * g0.x, s[1 * 33] * g0.y); o.y = pk2(s[2 * 33] * g0.z, s[3 * 33] * g0.w); o.z = pk2(s[4 * 33] * g1.x, s[5 * 33] * g1.y); o.w = pk2(s[6 * 33] * g1.z, s[7 * 33] * g1.w); }
;         else { o.x = 0u; o.y = 0u; o.z = 0u; o.w = 0u; }
;         *(v4u*)(WT + (size_t)(dst_row0 + n) * K + k0 + 8 * c) = o; }
; __device__ __forceinline__ void p0_prologue(Frame& F, bool split = false) {
;     ...
;         p0_transpose_matrix2(F, FIN(F, 11) + (size_t)kn * 256 * 256, 256, 256, (bf16*)FW(F, WS_MISC + MISC_GATE), 8, [](int nb) { return nb * 32; },
;             [=](int nb) { const int e0 = nb * 32; return (2 * n + (e0 >> 7)) * 256 + (e0 & 127) + 128 * k; }, it0); }
.LBB0_99:
	s_lshl_b32 s11, s11, 9
	s_sub_i32 s11, s22, s11
	s_and_b32 s11, s11, 0xffffff00
	s_and_b32 s2, s2, 0x60
	s_add_i32 s11, s20, s11
	s_waitcnt lgkmcnt(0)
	s_or_b32 s2, s11, s2
	s_ashr_i32 s11, s10, 31
	v_lshl_add_u64 v[20:21], s[10:11], 1, v[8:9]
	s_mov_b64 s[10:11], -1
	s_and_b64 vcc, exec, s[4:5]
	v_or_b32_e32 v12, s2, v25
	s_cbranch_vccz .LBB0_101
	v_ashrrev_i32_e32 v3, 31, v12
	v_mov_b32_e32 v2, v12
	v_lshlrev_b64 v[2:3], 9, v[2:3]
	v_lshl_add_u64 v[2:3], v[20:21], 0, v[2:3]
	global_store_dwordx4 v[2:3], v[38:41], off sc1
	s_mov_b64 s[10:11], 0
.LBB0_101:
	v_mov_b32_e32 v2, 0
	s_andn2_b64 vcc, exec, s[10:11]
	v_mov_b32_e32 v3, 0
	v_mov_b32_e32 v4, 0
	v_mov_b32_e32 v5, 0
	s_cbranch_vccnz .LBB0_103
	ds_read2_b32 v[2:3], v19 offset1:33
	s_waitcnt lgkmcnt(0)
	v_cvt_pk_bf16_f32 v2, v2, v3
	ds_read2_b32 v[4:5], v19 offset0:66 offset1:99
	s_waitcnt lgkmcnt(0)
	v_cvt_pk_bf16_f32 v3, v4, v5
	ds_read2_b32 v[4:5], v19 offset0:132 offset1:165
	v_lshlrev_b64 v[44:45], 9, v[12:13]
	s_waitcnt lgkmcnt(0)
	v_cvt_pk_bf16_f32 v4, v4, v5
	ds_read2_b32 v[42:43], v19 offset0:198 offset1:231
	s_waitcnt lgkmcnt(0)
	v_cvt_pk_bf16_f32 v5, v42, v43
	v_lshl_add_u64 v[44:45], v[20:21], 0, v[44:45]
	ds_read2_b32 v[42:43], v26 offset1:33
	global_store_dwordx4 v[44:45], v[2:5], off sc1
	s_waitcnt lgkmcnt(0)
	s_nop 0
	v_cvt_pk_bf16_f32 v2, v42, v43
	ds_read2_b32 v[4:5], v26 offset0:66 offset1:99
	s_waitcnt lgkmcnt(0)
	v_cvt_pk_bf16_f32 v3, v4, v5
	ds_read2_b32 v[4:5], v26 offset0:132 offset1:165
	s_waitcnt lgkmcnt(0)
	v_cvt_pk_bf16_f32 v4, v4, v5
	ds_read2_b32 v[42:43], v26 offset0:198 offset1:231
	s_waitcnt lgkmcnt(0)
	v_cvt_pk_bf16_f32 v5, v42, v43
.LBB0_103:
	v_or_b32_e32 v42, s2, v33
	v_ashrrev_i32_e32 v43, 31, v42
	v_lshlrev_b64 v[42:43], 9, v[42:43]
	v_lshl_add_u64 v[42:43], v[20:21], 0, v[42:43]
	s_mov_b64 s[10:11], -1
	s_and_b64 vcc, exec, s[4:5]
	v_or_b32_e32 v12, s2, v34
	global_store_dwordx4 v[42:43], v[2:5], off sc1
	s_cbranch_vccz .LBB0_105
	s_nop 0
	v_ashrrev_i32_e32 v3, 31, v12
	v_mov_b32_e32 v2, v12
	v_lshlrev_b64 v[2:3], 9, v[2:3]
	v_lshl_add_u64 v[2:3], v[20:21], 0, v[2:3]
	global_store_dwordx4 v[2:3], v[38:41], off sc1
	s_mov_b64 s[10:11], 0
.LBB0_105:
	s_nop 0
	v_mov_b32_e32 v2, 0
	s_andn2_b64 vcc, exec, s[10:11]
	v_mov_b32_e32 v3, 0
	v_mov_b32_e32 v4, 0
	v_mov_b32_e32 v5, 0
	s_cbranch_vccnz .LBB0_96
	ds_read2_b32 v[2:3], v27 offset1:33
	s_waitcnt lgkmcnt(0)
	v_cvt_pk_bf16_f32 v2, v2, v3
	ds_read2_b32 v[4:5], v27 offset0:66 offset1:99
	s_waitcnt lgkmcnt(0)
	v_cvt_pk_bf16_f32 v3, v4, v5
	ds_read2_b32 v[4:5], v27 offset0:132 offset1:165
	v_lshlrev_b64 v[44:45], 9, v[12:13]
	s_waitcnt lgkmcnt(0)
	v_cvt_pk_bf16_f32 v4, v4, v5
	ds_read2_b32 v[42:43], v27 offset0:198 offset1:231
	s_waitcnt lgkmcnt(0)
	v_cvt_pk_bf16_f32 v5, v42, v43
	v_lshl_add_u64 v[44:45], v[20:21], 0, v[44:45]
	ds_read2_b32 v[42:43], v28 offset1:33
	global_store_dwordx4 v[44:45], v[2:5], off sc1
	s_waitcnt lgkmcnt(0)
	s_nop 0
	v_cvt_pk_bf16_f32 v2, v42, v43
	ds_read2_b32 v[4:5], v28 offset0:66 offset1:99
	s_waitcnt lgkmcnt(0)
	v_cvt_pk_bf16_f32 v3, v4, v5
	ds_read2_b32 v[4:5], v28 offset0:132 offset1:165
	s_waitcnt lgkmcnt(0)
	v_cvt_pk_bf16_f32 v4, v4, v5
	ds_read2_b32 v[42:43], v28 offset0:198 offset1:231
	s_waitcnt lgkmcnt(0)
	v_cvt_pk_bf16_f32 v5, v42, v43
	s_branch .LBB0_96

; __device__ __forceinline__ unsigned pk2(float lo, float hi) { unsigned r; asm volatile("v_cvt_pk_bf16_f32 %0, %1, %2" : "=v"(r) : "v"(lo), "v"(hi)); return r; }
; __device__ __forceinline__ void p0_transpose_item(const float* W, int K, int N, bf16* WT, int kb, int src_col0, int dst_row0, float* scr, int lane, const float* kgain = nullptr) {
;     ...
;     for (int j = 0; j < 4; ++j) { const int n = (lane >> 3) + 8 * j; const float* s = scr + (8 * c) * 33 + n;
;         v4u o;
;         if (src_col0 >= 0) { o.x = pk2(s[0 * 33] * g0.x, s[1 * 33] * g0.y); o.y = pk2(s[2 * 33] * g0.z, s[3 * 33] * g0.w); o.z = pk2(s[4 * 33] * g1.x, s[5 * 33] * g1.y); o.w = pk2(s[6 * 33] * g1.z, s[7 * 33] * g1.w); }
;         else { o.x = 0u; o.y = 0u; o.z = 0u; o.w = 0u; }
;         *(v4u*)(WT + (size_t)(dst_row0 + n) * K + k0 + 8 * c) = o; }
; template <class CM>
; __device__ __forceinline__ void p0_transpose_matrix(Frame& F, const float* W, int K, int N, bf16* WT, int nblk, CM colmap, int& it0, const float* kgain = nullptr) {
;     ...
;     for (int r = first; r < nitems; r += F.ngw) {
;         const int kb = r / nblk, nb = r % nblk;
;         p0_transpose_item(W, K, N, WT, kb, colmap(nb), nb * 32, scr, F.lane, kgain);
;     }
.LBB0_111:
	v_add_u32_e32 v44, s21, v35
	v_ashrrev_i32_e32 v45, 31, v44
	v_lshlrev_b64 v[44:45], 13, v[44:45]
	v_lshl_add_u64 v[22:23], v[22:23], 0, v[44:45]
	global_store_dwordx4 v[22:23], v[2:5], off sc1
	s_waitcnt lgkmcnt(0)
	s_add_i32 s19, s19, s76
	s_add_i32 s20, s20, s15
	s_cmpk_lt_i32 s19, 0x100
	s_cbranch_scc0 .LBB0_122

; __device__ __forceinline__ unsigned pk2(float lo, float hi) { unsigned r; asm volatile("v_cvt_pk_bf16_f32 %0, %1, %2" : "=v"(r) : "v"(lo), "v"(hi)); return r; }
; __device__ __forceinline__ void p0_transpose_item(const float* W, int K, int N, bf16* WT, int kb, int src_col0, int dst_row0, float* scr, int lane, const float* kgain = nullptr) {
;     ...
;     for (int j = 0; j < 4; ++j) { const int n = (lane >> 3) + 8 * j; const float* s = scr + (8 * c) * 33 + n;
;         v4u o;
;         if (src_col0 >= 0) { o.x = pk2(s[0 * 33] * g0.x, s[1 * 33] * g0.y); o.y = pk2(s[2 * 33] * g0.z, s[3 * 33] * g0.w); o.z = pk2(s[4 * 33] * g1.x, s[5 * 33] * g1.y); o.w = pk2(s[6 * 33] * g1.z, s[7 * 33] * g1.w); }
;         else { o.x = 0u; o.y = 0u; o.z = 0u; o.w = 0u; }
;         *(v4u*)(WT + (size_t)(dst_row0 + n) * K + k0 + 8 * c) = o; }
.LBB0_114:
	s_waitcnt lgkmcnt(0)
	s_ashr_i32 s13, s12, 31
	v_lshl_add_u64 v[22:23], s[12:13], 1, v[20:21]
	s_mov_b64 s[12:13], -1
	s_and_b64 vcc, exec, s[10:11]
	s_cbranch_vccz .LBB0_116
	s_add_i32 s2, s21, s20
	v_add_u32_e32 v2, s2, v25
	v_ashrrev_i32_e32 v3, 31, v2
	v_lshlrev_b64 v[2:3], 13, v[2:3]
	v_lshl_add_u64 v[2:3], v[22:23], 0, v[2:3]
	global_store_dwordx4 v[2:3], v[40:43], off sc1
	s_mov_b64 s[12:13], 0
.LBB0_116:
	v_mov_b32_e32 v2, 0
	s_andn2_b64 vcc, exec, s[12:13]
	v_mov_b32_e32 v3, 0
	v_mov_b32_e32 v4, 0
	v_mov_b32_e32 v5, 0
	s_cbranch_vccnz .LBB0_118
	ds_read2_b32 v[2:3], v19 offset1:33
	s_add_i32 s2, s21, s20
	s_waitcnt lgkmcnt(0)
	v_cvt_pk_bf16_f32 v2, v2, v3
	ds_read2_b32 v[4:5], v19 offset0:66 offset1:99
	v_add_u32_e32 v12, s2, v25
	s_waitcnt lgkmcnt(0)
	v_cvt_pk_bf16_f32 v3, v4, v5
	ds_read2_b32 v[4:5], v19 offset0:132 offset1:165
	v_lshlrev_b64 v[46:47], 13, v[12:13]
	s_waitcnt lgkmcnt(0)
	v_cvt_pk_bf16_f32 v4, v4, v5
	ds_read2_b32 v[44:45], v19 offset0:198 offset1:231
	s_waitcnt lgkmcnt(0)
	v_cvt_pk_bf16_f32 v5, v44, v45
	v_lshl_add_u64 v[46:47], v[22:23], 0, v[46:47]
	ds_read2_b32 v[44:45], v26 offset1:33
	global_store_dwordx4 v[46:47], v[2:5], off sc1
	s_waitcnt lgkmcnt(0)
	s_nop 0
	v_cvt_pk_bf16_f32 v2, v44, v45
	ds_read2_b32 v[4:5], v26 offset0:66 offset1:99
	s_waitcnt lgkmcnt(0)
	v_cvt_pk_bf16_f32 v3, v4, v5
	ds_read2_b32 v[4:5], v26 offset0:132 offset1:165
	s_waitcnt lgkmcnt(0)
	v_cvt_pk_bf16_f32 v4, v4, v5
	ds_read2_b32 v[44:45], v26 offset0:198 offset1:231
	s_waitcnt lgkmcnt(0)
	v_cvt_pk_bf16_f32 v5, v44, v45
.LBB0_118:
	s_add_i32 s21, s21, s20
	v_add_u32_e32 v44, s21, v33
	v_ashrrev_i32_e32 v45, 31, v44
	v_lshlrev_b64 v[44:45], 13, v[44:45]
	v_lshl_add_u64 v[44:45], v[22:23], 0, v[44:45]
	s_mov_b64 s[12:13], -1
	s_and_b64 vcc, exec, s[10:11]
	v_add_u32_e32 v12, s21, v34
	global_store_dwordx4 v[44:45], v[2:5], off sc1
	s_cbranch_vccz .LBB0_120
	s_nop 0
	v_ashrrev_i32_e32 v3, 31, v12
	v_mov_b32_e32 v2, v12
	v_lshlrev_b64 v[2:3], 13, v[2:3]
	v_lshl_add_u64 v[2:3], v[22:23], 0, v[2:3]
	global_store_dwordx4 v[2:3], v[40:43], off sc1
	s_mov_b64 s[12:13], 0
.LBB0_120:
	s_nop 0
	v_mov_b32_e32 v2, 0
	s_andn2_b64 vcc, exec, s[12:13]
	v_mov_b32_e32 v3, 0
	v_mov_b32_e32 v4, 0
	v_mov_b32_e32 v5, 0
	s_cbranch_vccnz .LBB0_111
	ds_read2_b32 v[2:3], v27 offset1:33
	s_waitcnt lgkmcnt(0)
	v_cvt_pk_bf16_f32 v2, v2, v3
	ds_read2_b32 v[4:5], v27 offset0:66 offset1:99
	s_waitcnt lgkmcnt(0)
	v_cvt_pk_bf16_f32 v3, v4, v5
	ds_read2_b32 v[4:5], v27 offset0:132 offset1:165
	v_lshlrev_b64 v[46:47], 13, v[12:13]
	s_waitcnt lgkmcnt(0)
	v_cvt_pk_bf16_f32 v4, v4, v5
	ds_read2_b32 v[44:45], v27 offset0:198 offset1:231
	s_waitcnt lgkmcnt(0)
	v_cvt_pk_bf16_f32 v5, v44, v45
	v_lshl_add_u64 v[46:47], v[22:23], 0, v[46:47]
	ds_read2_b32 v[44:45], v28 offset1:33
	global_store_dwordx4 v[46:47], v[2:5], off sc1
	s_waitcnt lgkmcnt(0)
	s_nop 0
	v_cvt_pk_bf16_f32 v2, v44, v45
	ds_read2_b32 v[4:5], v28 offset0:66 offset1:99
	s_waitcnt lgkmcnt(0)
	v_cvt_pk_bf16_f32 v3, v4, v5
	ds_read2_b32 v[4:5], v28 offset0:132 offset1:165
	s_waitcnt lgkmcnt(0)
	v_cvt_pk_bf16_f32 v4, v4, v5
	ds_read2_b32 v[44:45], v28 offset0:198 offset1:231
	s_waitcnt lgkmcnt(0)
	v_cvt_pk_bf16_f32 v5, v44, v45
	s_branch .LBB0_111

; __device__ __forceinline__ unsigned pk2(float lo, float hi) { unsigned r; asm volatile("v_cvt_pk_bf16_f32 %0, %1, %2" : "=v"(r) : "v"(lo), "v"(hi)); return r; }
; __device__ __forceinline__ void p0_transpose_item(const float* W, int K, int N, bf16* WT, int kb, int src_col0, int dst_row0, float* scr, int lane, const float* kgain = nullptr) {
;     ...
;     for (int j = 0; j < 4; ++j) { const int n = (lane >> 3) + 8 * j; const float* s = scr + (8 * c) * 33 + n;
;         v4u o;
;         if (src_col0 >= 0) { o.x = pk2(s[0 * 33] * g0.x, s[1 * 33] * g0.y); o.y = pk2(s[2 * 33] * g0.z, s[3 * 33] * g0.w); o.z = pk2(s[4 * 33] * g1.x, s[5 * 33] * g1.y); o.w = pk2(s[6 * 33] * g1.z, s[7 * 33] * g1.w); }
;         else { o.x = 0u; o.y = 0u; o.z = 0u; o.w = 0u; }
;         *(v4u*)(WT + (size_t)(dst_row0 + n) * K + k0 + 8 * c) = o; }
; template <class CM>
; __device__ __forceinline__ void p0_transpose_matrix(Frame& F, const float* W, int K, int N, bf16* WT, int nblk, CM colmap, int& it0, const float* kgain = nullptr) {
;     ...
;     for (int r = first; r < nitems; r += F.ngw) {
;         const int kb = r / nblk, nb = r % nblk;
;         p0_transpose_item(W, K, N, WT, kb, colmap(nb), nb * 32, scr, F.lane, kgain);
;     }
.LBB0_124:
	v_add_u32_e32 v44, s20, v35
	v_ashrrev_i32_e32 v45, 31, v44
	v_lshlrev_b64 v[44:45], 8, v[44:45]
	v_lshl_add_u64 v[22:23], v[22:23], 0, v[44:45]
	global_store_dwordx4 v[22:23], v[2:5], off sc1
	s_waitcnt lgkmcnt(0)
	s_add_i32 s19, s19, s76
	s_add_i32 s5, s5, s15
	s_cmp_lt_i32 s19, 8
	s_cbranch_scc0 .LBB0_108

; __device__ __forceinline__ unsigned pk2(float lo, float hi) { unsigned r; asm volatile("v_cvt_pk_bf16_f32 %0, %1, %2" : "=v"(r) : "v"(lo), "v"(hi)); return r; }
; __device__ __forceinline__ void p0_transpose_item(const float* W, int K, int N, bf16* WT, int kb, int src_col0, int dst_row0, float* scr, int lane, const float* kgain = nullptr) {
;     ...
;     for (int j = 0; j < 4; ++j) { const int n = (lane >> 3) + 8 * j; const float* s = scr + (8 * c) * 33 + n;
;         v4u o;
;         if (src_col0 >= 0) { o.x = pk2(s[0 * 33] * g0.x, s[1 * 33] * g0.y); o.y = pk2(s[2 * 33] * g0.z, s[3 * 33] * g0.w); o.z = pk2(s[4 * 33] * g1.x, s[5 * 33] * g1.y); o.w = pk2(s[6 * 33] * g1.z, s[7 * 33] * g1.w); }
;         else { o.x = 0u; o.y = 0u; o.z = 0u; o.w = 0u; }
;         *(v4u*)(WT + (size_t)(dst_row0 + n) * K + k0 + 8 * c) = o; }
.LBB0_127:
	s_waitcnt lgkmcnt(0)
	s_ashr_i32 s13, s12, 31
	v_lshl_add_u64 v[22:23], s[12:13], 1, v[20:21]
	s_mov_b64 s[12:13], -1
	s_and_b64 vcc, exec, s[10:11]
	s_cbranch_vccz .LBB0_129
	s_add_i32 s2, s20, s5
	v_add_u32_e32 v2, s2, v25
	v_ashrrev_i32_e32 v3, 31, v2
	v_lshlrev_b64 v[2:3], 8, v[2:3]
	v_lshl_add_u64 v[2:3], v[22:23], 0, v[2:3]
	global_store_dwordx4 v[2:3], v[40:43], off sc1
	s_mov_b64 s[12:13], 0
.LBB0_129:
	v_mov_b32_e32 v2, 0
	s_andn2_b64 vcc, exec, s[12:13]
	v_mov_b32_e32 v3, 0
	v_mov_b32_e32 v4, 0
	v_mov_b32_e32 v5, 0
	s_cbranch_vccnz .LBB0_131
	ds_read2_b32 v[2:3], v19 offset1:33
	s_add_i32 s2, s20, s5
	s_waitcnt lgkmcnt(0)
	v_cvt_pk_bf16_f32 v2, v2, v3
	ds_read2_b32 v[4:5], v19 offset0:66 offset1:99
	v_add_u32_e32 v12, s2, v25
	s_waitcnt lgkmcnt(0)
	v_cvt_pk_bf16_f32 v3, v4, v5
	ds_read2_b32 v[4:5], v19 offset0:132 offset1:165
	v_lshlrev_b64 v[46:47], 8, v[12:13]
	s_waitcnt lgkmcnt(0)
	v_cvt_pk_bf16_f32 v4, v4, v5
	ds_read2_b32 v[44:45], v19 offset0:198 offset1:231
	s_waitcnt lgkmcnt(0)
	v_cvt_pk_bf16_f32 v5, v44, v45
	v_lshl_add_u64 v[46:47], v[22:23], 0, v[46:47]
	ds_read2_b32 v[44:45], v26 offset1:33
	global_store_dwordx4 v[46:47], v[2:5], off sc1
	s_waitcnt lgkmcnt(0)
	s_nop 0
	v_cvt_pk_bf16_f32 v2, v44, v45
	ds_read2_b32 v[4:5], v26 offset0:66 offset1:99
	s_waitcnt lgkmcnt(0)
	v_cvt_pk_bf16_f32 v3, v4, v5
	ds_read2_b32 v[4:5], v26 offset0:132 offset1:165
	s_waitcnt lgkmcnt(0)
	v_cvt_pk_bf16_f32 v4, v4, v5
	ds_read2_b32 v[44:45], v26 offset0:198 offset1:231
	s_waitcnt lgkmcnt(0)
	v_cvt_pk_bf16_f32 v5, v44, v45
.LBB0_131:
	s_add_i32 s20, s20, s5
	v_add_u32_e32 v44, s20, v33
	v_ashrrev_i32_e32 v45, 31, v44
	v_lshlrev_b64 v[44:45], 8, v[44:45]
	v_lshl_add_u64 v[44:45], v[22:23], 0, v[44:45]
	s_mov_b64 s[12:13], -1
	s_and_b64 vcc, exec, s[10:11]
	v_add_u32_e32 v12, s20, v34
	global_store_dwordx4 v[44:45], v[2:5], off sc1
	s_cbranch_vccz .LBB0_133
	s_nop 0
	v_ashrrev_i32_e32 v3, 31, v12
	v_mov_b32_e32 v2, v12
	v_lshlrev_b64 v[2:3], 8, v[2:3]
	v_lshl_add_u64 v[2:3], v[22:23], 0, v[2:3]
	global_store_dwordx4 v[2:3], v[40:43], off sc1
	s_mov_b64 s[12:13], 0
.LBB0_133:
	s_nop 0
	v_mov_b32_e32 v2, 0
	s_andn2_b64 vcc, exec, s[12:13]
	v_mov_b32_e32 v3, 0
	v_mov_b32_e32 v4, 0
	v_mov_b32_e32 v5, 0
	s_cbranch_vccnz .LBB0_124
	ds_read2_b32 v[2:3], v27 offset1:33
	s_waitcnt lgkmcnt(0)
	v_cvt_pk_bf16_f32 v2, v2, v3
	ds_read2_b32 v[4:5], v27 offset0:66 offset1:99
	s_waitcnt lgkmcnt(0)
	v_cvt_pk_bf16_f32 v3, v4, v5
	ds_read2_b32 v[4:5], v27 offset0:132 offset1:165
	v_lshlrev_b64 v[46:47], 8, v[12:13]
	s_waitcnt lgkmcnt(0)
	v_cvt_pk_bf16_f32 v4, v4, v5
	ds_read2_b32 v[44:45], v27 offset0:198 offset1:231
	s_waitcnt lgkmcnt(0)
	v_cvt_pk_bf16_f32 v5, v44, v45
	v_lshl_add_u64 v[46:47], v[22:23], 0, v[46:47]
	ds_read2_b32 v[44:45], v28 offset1:33
	global_store_dwordx4 v[46:47], v[2:5], off sc1
	s_waitcnt lgkmcnt(0)
	s_nop 0
	v_cvt_pk_bf16_f32 v2, v44, v45
	ds_read2_b32 v[4:5], v28 offset0:66 offset1:99
	s_waitcnt lgkmcnt(0)
	v_cvt_pk_bf16_f32 v3, v4, v5
	ds_read2_b32 v[4:5], v28 offset0:132 offset1:165
	s_waitcnt lgkmcnt(0)
	v_cvt_pk_bf16_f32 v4, v4, v5
	ds_read2_b32 v[44:45], v28 offset0:198 offset1:231
	s_waitcnt lgkmcnt(0)
	v_cvt_pk_bf16_f32 v5, v44, v45
	s_branch .LBB0_124

; __device__ __forceinline__ unsigned cvt_pk_bf16(float lo, float hi) { unsigned r; asm volatile("v_cvt_pk_bf16_f32 %0, %1, %2" : "=v"(r) : "v"(lo), "v"(hi)); return r; }
;     __device__ __forceinline__ void operator()(const f32x4 (&acc)[2][2][4][2], const Unit& u, int wr, int wc, int fr, int fq) const {
;         const int row0 = u.pm * BM + wr * 64 + fr, col0 = u.pn * BM + wc * 32 + 8 * fq;
;         float scv[2][4];
; #pragma unroll
;         for (int ai = 0; ai < 2; ++ai)
; #pragma unroll
;             for (int m = 0; m < 4; ++m) scv[ai][m] = rs[row0 + ai * HALF + m * 16];
; #pragma unroll
;         for (int ai = 0; ai < 2; ++ai)
; #pragma unroll
;             for (int m = 0; m < 4; ++m) { const int row = row0 + ai * HALF + m * 16; const float sc = scv[ai][m]; bf16_t* rowp = O + (size_t)row * ldc + col0;
; #pragma unroll
;                 for (int bj = 0; bj < 2; ++bj) { const f32x4 v0 = acc[ai][bj][m][0] * sc, v1 = acc[ai][bj][m][1] * sc;
;                     u32x4 w; w.x = cvt_pk_bf16(v0[0], v0[1]); w.y = cvt_pk_bf16(v0[2], v0[3]); w.z = cvt_pk_bf16(v1[0], v1[1]); w.w = cvt_pk_bf16(v1[2], v1[3]);
;                     *(u32x4*)(rowp + bj * HALF) = w; } }
.LBB0_213:
	v_lshl_add_u32 v148, s22, 8, v1
	v_or_b32_e32 v162, 16, v148
	v_ashrrev_i32_e32 v149, 31, v148
	v_ashrrev_i32_e32 v163, 31, v162
	v_or_b32_e32 v166, 32, v148
	v_lshl_add_u64 v[158:159], v[148:149], 2, s[8:9]
	v_lshl_add_u64 v[146:147], v[162:163], 2, s[8:9]
	v_ashrrev_i32_e32 v167, 31, v166
	global_load_dword v160, v[158:159], off
	global_load_dword v164, v[146:147], off
	v_lshl_add_u64 v[146:147], v[166:167], 2, s[8:9]
	global_load_dword v168, v[146:147], off
	v_or_b32_e32 v170, 48, v148
	v_ashrrev_i32_e32 v171, 31, v170
	v_lshl_add_u64 v[146:147], v[170:171], 2, s[8:9]
	global_load_dword v154, v[146:147], off
	v_lshl_or_b32 v172, s48, 8, v153
	v_mov_b64_e32 v[146:147], s[4:5]
	v_ashrrev_i32_e32 v173, 31, v172
	v_add_u32_e32 v165, 0x80, v148
	v_add_u32_e32 v169, 0x90, v148
	v_add_u32_e32 v171, 0xa0, v148
	v_add_u32_e32 v177, 0xb0, v148
	v_mad_i64_i32 v[174:175], s[24:25], v148, s47, v[146:147]
	v_lshlrev_b64 v[148:149], 1, v[172:173]
	v_lshl_add_u64 v[172:173], v[174:175], 0, v[148:149]
	global_load_dword v174, v[158:159], off offset:512
	global_load_dword v176, v[158:159], off offset:576
	global_load_dword v152, v[158:159], off offset:640
	global_load_dword v150, v[158:159], off offset:704
	v_mad_i64_i32 v[162:163], s[24:25], v162, s47, v[146:147]
	v_lshl_add_u64 v[162:163], v[162:163], 0, v[148:149]
	v_mad_i64_i32 v[166:167], s[24:25], v166, s47, v[146:147]
	v_lshl_add_u64 v[166:167], v[166:167], 0, v[148:149]
	s_andn2_b64 vcc, exec, s[2:3]
	s_mov_b64 s[2:3], -1
	s_waitcnt vmcnt(0)
	v_pk_mul_f32 v[124:125], v[124:125], v[160:161] op_sel_hi:[1,0]
	v_pk_mul_f32 v[128:129], v[128:129], v[160:161] op_sel_hi:[1,0]
	v_pk_mul_f32 v[126:127], v[126:127], v[160:161] op_sel_hi:[1,0]
	v_pk_mul_f32 v[122:123], v[122:123], v[160:161] op_sel_hi:[1,0]
	v_pk_mul_f32 v[112:113], v[112:113], v[160:161] op_sel_hi:[1,0]
	v_pk_mul_f32 v[110:111], v[110:111], v[160:161] op_sel_hi:[1,0]
	v_pk_mul_f32 v[158:159], v[104:105], v[160:161] op_sel_hi:[1,0]
	v_pk_mul_f32 v[160:161], v[102:103], v[160:161] op_sel_hi:[1,0]
	v_cvt_pk_bf16_f32 v102, v126, v127
	v_cvt_pk_bf16_f32 v103, v128, v129
	v_cvt_pk_bf16_f32 v104, v122, v123
	v_cvt_pk_bf16_f32 v105, v124, v125
	v_pk_mul_f32 v[124:125], v[82:83], v[168:169] op_sel_hi:[1,0]
	global_store_dwordx4 v[172:173], v[102:105], off sc1
	v_cvt_pk_bf16_f32 v82, v110, v111
	v_cvt_pk_bf16_f32 v83, v112, v113
	v_pk_mul_f32 v[120:121], v[120:121], v[164:165] op_sel_hi:[1,0]
	v_pk_mul_f32 v[118:119], v[118:119], v[164:165] op_sel_hi:[1,0]
	v_pk_mul_f32 v[122:123], v[84:85], v[168:169] op_sel_hi:[1,0]
	v_cvt_pk_bf16_f32 v84, v160, v161
	v_cvt_pk_bf16_f32 v85, v158, v159
	global_store_dwordx4 v[172:173], v[82:85], off offset:256 sc1
	v_pk_mul_f32 v[116:117], v[116:117], v[164:165] op_sel_hi:[1,0]
	v_pk_mul_f32 v[114:115], v[114:115], v[164:165] op_sel_hi:[1,0]
	v_cvt_pk_bf16_f32 v82, v118, v119
	v_cvt_pk_bf16_f32 v83, v120, v121
	v_pk_mul_f32 v[96:97], v[96:97], v[164:165] op_sel_hi:[1,0]
	v_pk_mul_f32 v[94:95], v[94:95], v[164:165] op_sel_hi:[1,0]
	v_cvt_pk_bf16_f32 v84, v114, v115
	v_cvt_pk_bf16_f32 v85, v116, v117
	global_store_dwordx4 v[162:163], v[82:85], off sc1
	v_pk_mul_f32 v[92:93], v[92:93], v[164:165] op_sel_hi:[1,0]
	v_pk_mul_f32 v[90:91], v[90:91], v[164:165] op_sel_hi:[1,0]
	v_cvt_pk_bf16_f32 v82, v94, v95
	v_cvt_pk_bf16_f32 v83, v96, v97
	v_pk_mul_f32 v[108:109], v[108:109], v[168:169] op_sel_hi:[1,0]
	v_pk_mul_f32 v[106:107], v[106:107], v[168:169] op_sel_hi:[1,0]
	v_cvt_pk_bf16_f32 v84, v90, v91
	v_cvt_pk_bf16_f32 v85, v92, v93
	global_store_dwordx4 v[162:163], v[82:85], off offset:256 sc1
	v_pk_mul_f32 v[100:101], v[100:101], v[168:169] op_sel_hi:[1,0]
	v_pk_mul_f32 v[98:99], v[98:99], v[168:169] op_sel_hi:[1,0]
	v_cvt_pk_bf16_f32 v82, v106, v107
	v_cvt_pk_bf16_f32 v83, v108, v109
	v_pk_mul_f32 v[88:89], v[88:89], v[168:169] op_sel_hi:[1,0]
	v_pk_mul_f32 v[86:87], v[86:87], v[168:169] op_sel_hi:[1,0]
	v_cvt_pk_bf16_f32 v84, v98, v99
	v_cvt_pk_bf16_f32 v85, v100, v101
	global_store_dwordx4 v[166:167], v[82:85], off sc1
	v_pk_mul_f32 v[80:81], v[80:81], v[154:155] op_sel_hi:[1,0]
	v_pk_mul_f32 v[78:79], v[78:79], v[154:155] op_sel_hi:[1,0]
	v_cvt_pk_bf16_f32 v82, v86, v87
	v_cvt_pk_bf16_f32 v83, v88, v89
	v_cvt_pk_bf16_f32 v84, v124, v125
	v_cvt_pk_bf16_f32 v85, v122, v123
	global_store_dwordx4 v[166:167], v[82:85], off offset:256 sc1
	v_pk_mul_f32 v[72:73], v[72:73], v[154:155] op_sel_hi:[1,0]
	v_pk_mul_f32 v[70:71], v[70:71], v[154:155] op_sel_hi:[1,0]
	v_mad_i64_i32 v[82:83], s[24:25], v170, s47, v[146:147]
	v_lshl_add_u64 v[82:83], v[82:83], 0, v[148:149]
	v_pk_mul_f32 v[84:85], v[76:77], v[154:155] op_sel_hi:[1,0]
; __device__ __forceinline__ unsigned cvt_pk_bf16(float lo, float hi) { unsigned r; asm volatile("v_cvt_pk_bf16_f32 %0, %1, %2" : "=v"(r) : "v"(lo), "v"(hi)); return r; }
;     __device__ __forceinline__ void operator()(const f32x4 (&acc)[2][2][4][2], const Unit& u, int wr, int wc, int fr, int fq) const {
;     ...
; #pragma unroll
;         for (int ai = 0; ai < 2; ++ai)
; #pragma unroll
;             for (int m = 0; m < 4; ++m) { const int row = row0 + ai * HALF + m * 16; const float sc = scv[ai][m]; bf16_t* rowp = O + (size_t)row * ldc + col0;
; #pragma unroll
;                 for (int bj = 0; bj < 2; ++bj) { const f32x4 v0 = acc[ai][bj][m][0] * sc, v1 = acc[ai][bj][m][1] * sc;
;                     u32x4 w; w.x = cvt_pk_bf16(v0[0], v0[1]); w.y = cvt_pk_bf16(v0[2], v0[3]); w.z = cvt_pk_bf16(v1[0], v1[1]); w.w = cvt_pk_bf16(v1[2], v1[3]);
;                     *(u32x4*)(rowp + bj * HALF) = w; } }
	v_pk_mul_f32 v[76:77], v[74:75], v[154:155] op_sel_hi:[1,0]
	v_cvt_pk_bf16_f32 v74, v78, v79
	v_cvt_pk_bf16_f32 v75, v80, v81
	v_pk_mul_f32 v[64:65], v[64:65], v[174:175] op_sel_hi:[1,0]
	v_cvt_pk_bf16_f32 v76, v76, v77
	v_cvt_pk_bf16_f32 v77, v84, v85
	global_store_dwordx4 v[82:83], v[74:77], off sc1
	v_pk_mul_f32 v[62:63], v[62:63], v[174:175] op_sel_hi:[1,0]
	v_pk_mul_f32 v[56:57], v[56:57], v[174:175] op_sel_hi:[1,0]
	v_pk_mul_f32 v[74:75], v[68:69], v[154:155] op_sel_hi:[1,0]
	v_pk_mul_f32 v[68:69], v[66:67], v[154:155] op_sel_hi:[1,0]
	v_cvt_pk_bf16_f32 v66, v70, v71
	v_cvt_pk_bf16_f32 v67, v72, v73
	v_pk_mul_f32 v[54:55], v[54:55], v[174:175] op_sel_hi:[1,0]
	v_cvt_pk_bf16_f32 v68, v68, v69
	v_cvt_pk_bf16_f32 v69, v74, v75
	global_store_dwordx4 v[82:83], v[66:69], off offset:256 sc1
	v_pk_mul_f32 v[50:51], v[50:51], v[176:177] op_sel_hi:[1,0]
	v_pk_mul_f32 v[40:41], v[40:41], v[176:177] op_sel_hi:[1,0]
	v_mad_i64_i32 v[66:67], s[24:25], v165, s47, v[146:147]
	v_lshl_add_u64 v[66:67], v[66:67], 0, v[148:149]
	v_pk_mul_f32 v[68:69], v[60:61], v[174:175] op_sel_hi:[1,0]
	v_pk_mul_f32 v[60:61], v[58:59], v[174:175] op_sel_hi:[1,0]
	v_cvt_pk_bf16_f32 v58, v62, v63
	v_cvt_pk_bf16_f32 v59, v64, v65
	v_pk_mul_f32 v[38:39], v[38:39], v[176:177] op_sel_hi:[1,0]
	v_cvt_pk_bf16_f32 v60, v60, v61
	v_cvt_pk_bf16_f32 v61, v68, v69
	global_store_dwordx4 v[66:67], v[58:61], off sc1
	v_pk_mul_f32 v[34:35], v[34:35], v[152:153] op_sel_hi:[1,0]
	v_pk_mul_f32 v[24:25], v[24:25], v[152:153] op_sel_hi:[1,0]
	v_pk_mul_f32 v[58:59], v[48:49], v[174:175] op_sel_hi:[1,0]
	v_pk_mul_f32 v[48:49], v[46:47], v[174:175] op_sel_hi:[1,0]
	v_cvt_pk_bf16_f32 v46, v54, v55
	v_cvt_pk_bf16_f32 v47, v56, v57
	v_pk_mul_f32 v[22:23], v[22:23], v[152:153] op_sel_hi:[1,0]
	v_cvt_pk_bf16_f32 v48, v48, v49
	v_cvt_pk_bf16_f32 v49, v58, v59
	global_store_dwordx4 v[66:67], v[46:49], off offset:256 sc1
	v_pk_mul_f32 v[18:19], v[18:19], v[150:151] op_sel_hi:[1,0]
	v_pk_mul_f32 v[8:9], v[8:9], v[150:151] op_sel_hi:[1,0]
	v_mad_i64_i32 v[46:47], s[24:25], v169, s47, v[146:147]
	v_lshl_add_u64 v[46:47], v[46:47], 0, v[148:149]
	v_pk_mul_f32 v[48:49], v[52:53], v[176:177] op_sel_hi:[1,0]
	v_pk_mul_f32 v[52:53], v[44:45], v[176:177] op_sel_hi:[1,0]
	v_pk_mul_f32 v[44:45], v[42:43], v[176:177] op_sel_hi:[1,0]
	v_cvt_pk_bf16_f32 v42, v50, v51
	v_cvt_pk_bf16_f32 v43, v48, v49
	v_pk_mul_f32 v[6:7], v[6:7], v[150:151] op_sel_hi:[1,0]
	v_cvt_pk_bf16_f32 v44, v44, v45
	v_cvt_pk_bf16_f32 v45, v52, v53
	global_store_dwordx4 v[46:47], v[42:45], off sc1
	s_nop 1
	v_pk_mul_f32 v[42:43], v[32:33], v[176:177] op_sel_hi:[1,0]
	v_pk_mul_f32 v[32:33], v[30:31], v[176:177] op_sel_hi:[1,0]
	v_cvt_pk_bf16_f32 v30, v38, v39
	v_cvt_pk_bf16_f32 v31, v40, v41
	s_nop 0
	v_cvt_pk_bf16_f32 v32, v32, v33
	v_cvt_pk_bf16_f32 v33, v42, v43
	global_store_dwordx4 v[46:47], v[30:33], off offset:256 sc1
	s_nop 1
	v_mad_i64_i32 v[30:31], s[24:25], v171, s47, v[146:147]
	v_lshl_add_u64 v[30:31], v[30:31], 0, v[148:149]
	v_pk_mul_f32 v[32:33], v[36:37], v[152:153] op_sel_hi:[1,0]
	v_pk_mul_f32 v[36:37], v[28:29], v[152:153] op_sel_hi:[1,0]
	v_pk_mul_f32 v[28:29], v[26:27], v[152:153] op_sel_hi:[1,0]
	v_cvt_pk_bf16_f32 v26, v34, v35
	v_cvt_pk_bf16_f32 v27, v32, v33
	s_nop 0
	v_cvt_pk_bf16_f32 v28, v28, v29
	v_cvt_pk_bf16_f32 v29, v36, v37
	global_store_dwordx4 v[30:31], v[26:29], off sc1
	s_nop 1
	v_pk_mul_f32 v[26:27], v[16:17], v[152:153] op_sel_hi:[1,0]
	v_pk_mul_f32 v[16:17], v[14:15], v[152:153] op_sel_hi:[1,0]
	v_cvt_pk_bf16_f32 v14, v22, v23
	v_cvt_pk_bf16_f32 v15, v24, v25
	s_nop 0
	v_cvt_pk_bf16_f32 v16, v16, v17
	v_cvt_pk_bf16_f32 v17, v26, v27
	global_store_dwordx4 v[30:31], v[14:17], off offset:256 sc1
	s_nop 1
	v_mad_i64_i32 v[14:15], s[24:25], v177, s47, v[146:147]
	v_lshl_add_u64 v[14:15], v[14:15], 0, v[148:149]
	v_pk_mul_f32 v[16:17], v[20:21], v[150:151] op_sel_hi:[1,0]
	v_pk_mul_f32 v[20:21], v[12:13], v[150:151] op_sel_hi:[1,0]
	v_pk_mul_f32 v[12:13], v[10:11], v[150:151] op_sel_hi:[1,0]
	v_cvt_pk_bf16_f32 v10, v18, v19
	v_cvt_pk_bf16_f32 v11, v16, v17
	s_nop 0
	v_cvt_pk_bf16_f32 v12, v12, v13
	v_cvt_pk_bf16_f32 v13, v20, v21
	global_store_dwordx4 v[14:15], v[10:13], off sc1
	s_nop 1
	v_pk_mul_f32 v[10:11], v[4:5], v[150:151] op_sel_hi:[1,0]
	v_pk_mul_f32 v[4:5], v[2:3], v[150:151] op_sel_hi:[1,0]
	v_cvt_pk_bf16_f32 v2, v6, v7
	v_cvt_pk_bf16_f32 v3, v8, v9
	s_nop 0
	v_cvt_pk_bf16_f32 v4, v4, v5
	v_cvt_pk_bf16_f32 v5, v10, v11
	global_store_dwordx4 v[14:15], v[2:5], off offset:256 sc1
	s_cbranch_vccnz .LBB0_206
	s_andn2_b64 vcc, exec, s[0:1]
	s_cbranch_vccnz .LBB0_205
	s_barrier
	s_branch .LBB0_205

; __device__ __forceinline__ unsigned cvt_pk_bf16(float lo, float hi) { unsigned r; asm volatile("v_cvt_pk_bf16_f32 %0, %1, %2" : "=v"(r) : "v"(lo), "v"(hi)); return r; }
;     __device__ __forceinline__ void operator()(const f32x4 (&acc)[2][2][4][2], const Unit& u, int wr, int wc, int fr, int fq) const {
;         const int row0 = u.pm * BM + wr * 64 + fr, col0 = u.pn * BM + wc * 32 + 8 * fq;
;         float scv[2][4];
; #pragma unroll
;         for (int ai = 0; ai < 2; ++ai)
; #pragma unroll
;             for (int m = 0; m < 4; ++m) scv[ai][m] = rs[row0 + ai * HALF + m * 16];
; #pragma unroll
;         for (int ai = 0; ai < 2; ++ai)
; #pragma unroll
;             for (int m = 0; m < 4; ++m) { const int row = row0 + ai * HALF + m * 16; const float sc = scv[ai][m]; bf16_t* rowp = O + (size_t)row * ldc + col0;
; #pragma unroll
;                 for (int bj = 0; bj < 2; ++bj) { const f32x4 v0 = acc[ai][bj][m][0] * sc, v1 = acc[ai][bj][m][1] * sc;
;                     u32x4 w; w.x = cvt_pk_bf16(v0[0], v0[1]); w.y = cvt_pk_bf16(v0[2], v0[3]); w.z = cvt_pk_bf16(v1[0], v1[1]); w.w = cvt_pk_bf16(v1[2], v1[3]);
;                     *(u32x4*)(rowp + bj * HALF) = w; } }
.LBB0_257:
	global_load_dword v182, v[138:139], off
	global_load_dword v184, v[140:141], off
	global_load_dword v186, v[142:143], off
	global_load_dword v188, v[144:145], off
	global_load_dword v178, v[146:147], off
	global_load_dword v176, v[148:149], off
	global_load_dword v174, v[150:151], off
	global_load_dword v172, v[152:153], off
	v_lshl_or_b32 v170, s49, 9, v177
	v_lshl_add_u64 v[180:181], v[154:155], 0, v[170:171]
	v_lshl_add_u64 v[190:191], v[156:157], 0, v[170:171]
	v_lshl_add_u64 v[192:193], v[158:159], 0, v[170:171]
	v_lshl_add_u64 v[194:195], v[160:161], 0, v[170:171]
	v_lshl_add_u64 v[196:197], v[162:163], 0, v[170:171]
	s_andn2_b64 vcc, exec, s[14:15]
	s_mov_b64 s[14:15], -1
	s_waitcnt vmcnt(0)
	v_pk_mul_f32 v[128:129], v[128:129], v[182:183] op_sel_hi:[1,0]
	v_pk_mul_f32 v[126:127], v[126:127], v[182:183] op_sel_hi:[1,0]
	v_pk_mul_f32 v[120:121], v[120:121], v[184:185] op_sel_hi:[1,0]
	v_pk_mul_f32 v[118:119], v[118:119], v[184:185] op_sel_hi:[1,0]
	v_pk_mul_f32 v[116:117], v[116:117], v[184:185] op_sel_hi:[1,0]
	v_pk_mul_f32 v[114:115], v[114:115], v[184:185] op_sel_hi:[1,0]
	v_pk_mul_f32 v[92:93], v[92:93], v[184:185] op_sel_hi:[1,0]
	v_pk_mul_f32 v[90:91], v[90:91], v[184:185] op_sel_hi:[1,0]
	v_pk_mul_f32 v[84:85], v[84:85], v[184:185] op_sel_hi:[1,0]
	v_pk_mul_f32 v[82:83], v[82:83], v[184:185] op_sel_hi:[1,0]
	v_pk_mul_f32 v[184:185], v[58:59], v[178:179] op_sel_hi:[1,0]
	v_cvt_pk_bf16_f32 v58, v126, v127
	v_cvt_pk_bf16_f32 v59, v128, v129
	v_pk_mul_f32 v[124:125], v[124:125], v[182:183] op_sel_hi:[1,0]
	v_pk_mul_f32 v[122:123], v[122:123], v[182:183] op_sel_hi:[1,0]
	v_pk_mul_f32 v[108:109], v[108:109], v[182:183] op_sel_hi:[1,0]
	v_pk_mul_f32 v[106:107], v[106:107], v[182:183] op_sel_hi:[1,0]
	v_pk_mul_f32 v[100:101], v[100:101], v[182:183] op_sel_hi:[1,0]
	v_pk_mul_f32 v[98:99], v[98:99], v[182:183] op_sel_hi:[1,0]
	v_pk_mul_f32 v[182:183], v[60:61], v[178:179] op_sel_hi:[1,0]
	v_cvt_pk_bf16_f32 v60, v122, v123
	v_cvt_pk_bf16_f32 v61, v124, v125
	global_store_dwordx4 v[180:181], v[58:61], off sc1
	v_pk_mul_f32 v[112:113], v[112:113], v[186:187] op_sel_hi:[1,0]
	v_pk_mul_f32 v[110:111], v[110:111], v[186:187] op_sel_hi:[1,0]
	v_cvt_pk_bf16_f32 v58, v106, v107
	v_cvt_pk_bf16_f32 v59, v108, v109
	v_cvt_pk_bf16_f32 v60, v98, v99
	v_cvt_pk_bf16_f32 v61, v100, v101
	global_store_dwordx4 v[180:181], v[58:61], off offset:256 sc1
	v_pk_mul_f32 v[104:105], v[104:105], v[186:187] op_sel_hi:[1,0]
	v_pk_mul_f32 v[102:103], v[102:103], v[186:187] op_sel_hi:[1,0]
	v_cvt_pk_bf16_f32 v58, v118, v119
	v_cvt_pk_bf16_f32 v59, v120, v121
	v_cvt_pk_bf16_f32 v60, v114, v115
	v_cvt_pk_bf16_f32 v61, v116, v117
	global_store_dwordx4 v[190:191], v[58:61], off sc1
	v_pk_mul_f32 v[80:81], v[80:81], v[186:187] op_sel_hi:[1,0]
	v_pk_mul_f32 v[78:79], v[78:79], v[186:187] op_sel_hi:[1,0]
	v_cvt_pk_bf16_f32 v58, v90, v91
	v_cvt_pk_bf16_f32 v59, v92, v93
	v_cvt_pk_bf16_f32 v60, v82, v83
	v_cvt_pk_bf16_f32 v61, v84, v85
	global_store_dwordx4 v[190:191], v[58:61], off offset:256 sc1
	v_pk_mul_f32 v[76:77], v[76:77], v[186:187] op_sel_hi:[1,0]
	v_pk_mul_f32 v[74:75], v[74:75], v[186:187] op_sel_hi:[1,0]
	v_cvt_pk_bf16_f32 v58, v110, v111
	v_cvt_pk_bf16_f32 v59, v112, v113
	v_cvt_pk_bf16_f32 v60, v102, v103
	v_cvt_pk_bf16_f32 v61, v104, v105
	global_store_dwordx4 v[192:193], v[58:61], off sc1
	v_pk_mul_f32 v[96:97], v[96:97], v[188:189] op_sel_hi:[1,0]
	v_pk_mul_f32 v[94:95], v[94:95], v[188:189] op_sel_hi:[1,0]
	v_cvt_pk_bf16_f32 v58, v78, v79
	v_cvt_pk_bf16_f32 v59, v80, v81
	v_cvt_pk_bf16_f32 v60, v74, v75
	v_cvt_pk_bf16_f32 v61, v76, v77
	global_store_dwordx4 v[192:193], v[58:61], off offset:256 sc1
	v_pk_mul_f32 v[88:89], v[88:89], v[188:189] op_sel_hi:[1,0]
	v_pk_mul_f32 v[86:87], v[86:87], v[188:189] op_sel_hi:[1,0]
	v_cvt_pk_bf16_f32 v58, v94, v95
	v_cvt_pk_bf16_f32 v59, v96, v97
	v_pk_mul_f32 v[72:73], v[72:73], v[188:189] op_sel_hi:[1,0]
	v_pk_mul_f32 v[70:71], v[70:71], v[188:189] op_sel_hi:[1,0]
	v_cvt_pk_bf16_f32 v60, v86, v87
	v_cvt_pk_bf16_f32 v61, v88, v89
; __device__ __forceinline__ unsigned cvt_pk_bf16(float lo, float hi) { unsigned r; asm volatile("v_cvt_pk_bf16_f32 %0, %1, %2" : "=v"(r) : "v"(lo), "v"(hi)); return r; }
;     __device__ __forceinline__ void operator()(const f32x4 (&acc)[2][2][4][2], const Unit& u, int wr, int wc, int fr, int fq) const {
;     ...
; #pragma unroll
;         for (int ai = 0; ai < 2; ++ai)
; #pragma unroll
;             for (int m = 0; m < 4; ++m) { const int row = row0 + ai * HALF + m * 16; const float sc = scv[ai][m]; bf16_t* rowp = O + (size_t)row * ldc + col0;
; #pragma unroll
;                 for (int bj = 0; bj < 2; ++bj) { const f32x4 v0 = acc[ai][bj][m][0] * sc, v1 = acc[ai][bj][m][1] * sc;
;                     u32x4 w; w.x = cvt_pk_bf16(v0[0], v0[1]); w.y = cvt_pk_bf16(v0[2], v0[3]); w.z = cvt_pk_bf16(v1[0], v1[1]); w.w = cvt_pk_bf16(v1[2], v1[3]);
;                     *(u32x4*)(rowp + bj * HALF) = w; } }
	global_store_dwordx4 v[194:195], v[58:61], off sc1
	v_pk_mul_f32 v[68:69], v[68:69], v[188:189] op_sel_hi:[1,0]
	v_pk_mul_f32 v[66:67], v[66:67], v[188:189] op_sel_hi:[1,0]
	v_cvt_pk_bf16_f32 v58, v70, v71
	v_cvt_pk_bf16_f32 v59, v72, v73
	v_pk_mul_f32 v[64:65], v[64:65], v[178:179] op_sel_hi:[1,0]
	v_pk_mul_f32 v[62:63], v[62:63], v[178:179] op_sel_hi:[1,0]
	v_cvt_pk_bf16_f32 v60, v66, v67
	v_cvt_pk_bf16_f32 v61, v68, v69
	global_store_dwordx4 v[194:195], v[58:61], off offset:256 sc1
	v_pk_mul_f32 v[56:57], v[56:57], v[178:179] op_sel_hi:[1,0]
	v_pk_mul_f32 v[54:55], v[54:55], v[178:179] op_sel_hi:[1,0]
	v_cvt_pk_bf16_f32 v58, v62, v63
	v_cvt_pk_bf16_f32 v59, v64, v65
	v_cvt_pk_bf16_f32 v60, v184, v185
	v_cvt_pk_bf16_f32 v61, v182, v183
	global_store_dwordx4 v[196:197], v[58:61], off sc1
	v_pk_mul_f32 v[50:51], v[50:51], v[176:177] op_sel_hi:[1,0]
	v_pk_mul_f32 v[40:41], v[40:41], v[176:177] op_sel_hi:[1,0]
	v_pk_mul_f32 v[58:59], v[48:49], v[178:179] op_sel_hi:[1,0]
	v_pk_mul_f32 v[48:49], v[46:47], v[178:179] op_sel_hi:[1,0]
	v_cvt_pk_bf16_f32 v46, v54, v55
	v_cvt_pk_bf16_f32 v47, v56, v57
	v_pk_mul_f32 v[38:39], v[38:39], v[176:177] op_sel_hi:[1,0]
	v_cvt_pk_bf16_f32 v48, v48, v49
	v_cvt_pk_bf16_f32 v49, v58, v59
	global_store_dwordx4 v[196:197], v[46:49], off offset:256 sc1
	v_pk_mul_f32 v[34:35], v[34:35], v[174:175] op_sel_hi:[1,0]
	v_pk_mul_f32 v[24:25], v[24:25], v[174:175] op_sel_hi:[1,0]
	v_lshl_add_u64 v[46:47], v[164:165], 0, v[170:171]
	v_pk_mul_f32 v[48:49], v[52:53], v[176:177] op_sel_hi:[1,0]
	v_pk_mul_f32 v[52:53], v[44:45], v[176:177] op_sel_hi:[1,0]
	v_pk_mul_f32 v[44:45], v[42:43], v[176:177] op_sel_hi:[1,0]
	v_cvt_pk_bf16_f32 v42, v50, v51
	v_cvt_pk_bf16_f32 v43, v48, v49
	v_pk_mul_f32 v[22:23], v[22:23], v[174:175] op_sel_hi:[1,0]
	v_cvt_pk_bf16_f32 v44, v44, v45
	v_cvt_pk_bf16_f32 v45, v52, v53
	global_store_dwordx4 v[46:47], v[42:45], off sc1
	v_pk_mul_f32 v[18:19], v[18:19], v[172:173] op_sel_hi:[1,0]
	v_pk_mul_f32 v[8:9], v[8:9], v[172:173] op_sel_hi:[1,0]
	v_pk_mul_f32 v[42:43], v[32:33], v[176:177] op_sel_hi:[1,0]
	v_pk_mul_f32 v[32:33], v[30:31], v[176:177] op_sel_hi:[1,0]
	v_cvt_pk_bf16_f32 v30, v38, v39
	v_cvt_pk_bf16_f32 v31, v40, v41
	v_pk_mul_f32 v[6:7], v[6:7], v[172:173] op_sel_hi:[1,0]
	v_cvt_pk_bf16_f32 v32, v32, v33
	v_cvt_pk_bf16_f32 v33, v42, v43
	global_store_dwordx4 v[46:47], v[30:33], off offset:256 sc1
	s_nop 1
	v_lshl_add_u64 v[30:31], v[166:167], 0, v[170:171]
	v_pk_mul_f32 v[32:33], v[36:37], v[174:175] op_sel_hi:[1,0]
	v_pk_mul_f32 v[36:37], v[28:29], v[174:175] op_sel_hi:[1,0]
	v_pk_mul_f32 v[28:29], v[26:27], v[174:175] op_sel_hi:[1,0]
	v_cvt_pk_bf16_f32 v26, v34, v35
	v_cvt_pk_bf16_f32 v27, v32, v33
	s_nop 0
	v_cvt_pk_bf16_f32 v28, v28, v29
	v_cvt_pk_bf16_f32 v29, v36, v37
	global_store_dwordx4 v[30:31], v[26:29], off sc1
	s_nop 1
	v_pk_mul_f32 v[26:27], v[16:17], v[174:175] op_sel_hi:[1,0]
	v_pk_mul_f32 v[16:17], v[14:15], v[174:175] op_sel_hi:[1,0]
	v_cvt_pk_bf16_f32 v14, v22, v23
	v_cvt_pk_bf16_f32 v15, v24, v25
	s_nop 0
	v_cvt_pk_bf16_f32 v16, v16, v17
	v_cvt_pk_bf16_f32 v17, v26, v27
	global_store_dwordx4 v[30:31], v[14:17], off offset:256 sc1
	s_nop 1
	v_lshl_add_u64 v[14:15], v[168:169], 0, v[170:171]
	v_pk_mul_f32 v[16:17], v[20:21], v[172:173] op_sel_hi:[1,0]
	v_pk_mul_f32 v[20:21], v[12:13], v[172:173] op_sel_hi:[1,0]
	v_pk_mul_f32 v[12:13], v[10:11], v[172:173] op_sel_hi:[1,0]
	v_cvt_pk_bf16_f32 v10, v18, v19
	v_cvt_pk_bf16_f32 v11, v16, v17
	s_nop 0
	v_cvt_pk_bf16_f32 v12, v12, v13
	v_cvt_pk_bf16_f32 v13, v20, v21
	global_store_dwordx4 v[14:15], v[10:13], off sc1
	s_nop 1
	v_pk_mul_f32 v[10:11], v[4:5], v[172:173] op_sel_hi:[1,0]
	v_pk_mul_f32 v[4:5], v[2:3], v[172:173] op_sel_hi:[1,0]
	v_cvt_pk_bf16_f32 v2, v6, v7
	v_cvt_pk_bf16_f32 v3, v8, v9
	s_nop 0
	v_cvt_pk_bf16_f32 v4, v4, v5
	v_cvt_pk_bf16_f32 v5, v10, v11
	global_store_dwordx4 v[14:15], v[2:5], off offset:256 sc1
	s_cbranch_vccnz .LBB0_237
	s_andn2_b64 vcc, exec, s[8:9]
	s_cbranch_vccnz .LBB0_236
	s_barrier
	s_branch .LBB0_236

; __device__ __forceinline__ void p0_transpose_item(const float* W, int K, int N, bf16* WT, int kb, int src_col0, int dst_row0, float* scr, int lane, const float* kgain = nullptr) {
;     ...
;     if (src_col0 >= 0) {
;         float wv[32];
;         if (kgain) { g0 = *(const v4f*)(kgain + k0 + 8 * c); g1 = *(const v4f*)(kgain + k0 + 8 * c + 4); }
; #pragma unroll
;         for (int i = 0; i < 32; ++i) { const int kk = 2 * i + (lane >> 5); wv[i] = __builtin_nontemporal_load(&W[(size_t)(k0 + kk) * N + src_col0 + (lane & 31)]); }
; #pragma unroll
;         for (int i = 0; i < 32; ++i) { const int kk = 2 * i + (lane >> 5); scr[kk * 33 + (lane & 31)] = wv[i]; }
.LBB0_261:
	s_ashr_i32 s0, s4, 31
	s_lshr_b32 s0, s0, 24
	s_add_i32 s0, s4, s0
	s_ashr_i32 s0, s0, 8
	s_lshl_b32 s2, s0, 6
	v_or_b32_e32 v28, s2, v1
	s_add_i32 s3, s5, s8
	s_lshl_b32 s9, s0, 13
	v_or_b32_e32 v30, 2, v28
	v_or_b32_e32 v42, 14, v28
	v_or_b32_e32 v44, 16, v28
	v_or_b32_e32 v46, 18, v28
	v_or_b32_e32 v48, 20, v28
	v_or_b32_e32 v50, 22, v28
	v_or_b32_e32 v52, 24, v28
	v_or_b32_e32 v54, 26, v28
	v_or_b32_e32 v56, 28, v28
	v_or_b32_e32 v58, 30, v28
	s_sub_i32 s0, s3, s9
	v_ashrrev_i32_e32 v29, 31, v28
	v_or_b32_e32 v32, 4, v28
	v_or_b32_e32 v34, 6, v28
	v_or_b32_e32 v36, 8, v28
	v_or_b32_e32 v38, 10, v28
	v_or_b32_e32 v40, 12, v28
	v_or_b32_e32 v60, 32, v28
	v_or_b32_e32 v62, 34, v28
	v_or_b32_e32 v64, 36, v28
	v_or_b32_e32 v66, 38, v28
	v_or_b32_e32 v68, 40, v28
	v_or_b32_e32 v70, 42, v28
	v_or_b32_e32 v72, 44, v28
	v_or_b32_e32 v74, 46, v28
	v_or_b32_e32 v76, 48, v28
	v_or_b32_e32 v78, 50, v28
	v_or_b32_e32 v80, 52, v28
	v_or_b32_e32 v82, 54, v28
	v_or_b32_e32 v84, 56, v28
	v_or_b32_e32 v86, 58, v28
	v_or_b32_e32 v88, 60, v28
	v_or_b32_e32 v90, 62, v28
	v_ashrrev_i32_e32 v31, 31, v30
	v_ashrrev_i32_e32 v43, 31, v42
	v_ashrrev_i32_e32 v45, 31, v44
	v_ashrrev_i32_e32 v47, 31, v46
	v_ashrrev_i32_e32 v49, 31, v48
	v_ashrrev_i32_e32 v51, 31, v50
	v_ashrrev_i32_e32 v53, 31, v52
	v_ashrrev_i32_e32 v55, 31, v54
	v_ashrrev_i32_e32 v57, 31, v56
	v_ashrrev_i32_e32 v59, 31, v58
	s_ashr_i32 s3, s2, 31
	v_lshl_add_u64 v[16:17], s[0:1], 2, v[10:11]
	v_lshlrev_b64 v[28:29], 16, v[28:29]
	v_ashrrev_i32_e32 v33, 31, v32
	v_ashrrev_i32_e32 v35, 31, v34
	v_ashrrev_i32_e32 v37, 31, v36
	v_ashrrev_i32_e32 v39, 31, v38
	v_ashrrev_i32_e32 v41, 31, v40
	v_ashrrev_i32_e32 v61, 31, v60
	v_ashrrev_i32_e32 v63, 31, v62
	v_ashrrev_i32_e32 v65, 31, v64
	v_ashrrev_i32_e32 v67, 31, v66
	v_ashrrev_i32_e32 v69, 31, v68
	v_ashrrev_i32_e32 v71, 31, v70
	v_ashrrev_i32_e32 v73, 31, v72
	v_ashrrev_i32_e32 v75, 31, v74
	v_ashrrev_i32_e32 v77, 31, v76
	v_ashrrev_i32_e32 v79, 31, v78
	v_ashrrev_i32_e32 v81, 31, v80
	v_ashrrev_i32_e32 v83, 31, v82
	v_ashrrev_i32_e32 v85, 31, v84
	v_ashrrev_i32_e32 v87, 31, v86
	v_ashrrev_i32_e32 v89, 31, v88
	v_ashrrev_i32_e32 v91, 31, v90
	v_lshlrev_b64 v[30:31], 16, v[30:31]
	v_lshlrev_b64 v[42:43], 16, v[42:43]
	v_lshlrev_b64 v[44:45], 16, v[44:45]
	v_lshlrev_b64 v[46:47], 16, v[46:47]
	v_lshlrev_b64 v[48:49], 16, v[48:49]
	v_lshlrev_b64 v[50:51], 16, v[50:51]
	v_lshlrev_b64 v[52:53], 16, v[52:53]
	v_lshlrev_b64 v[54:55], 16, v[54:55]
	v_lshlrev_b64 v[56:57], 16, v[56:57]
	v_lshlrev_b64 v[58:59], 16, v[58:59]
	v_lshl_add_u64 v[14:15], s[2:3], 2, v[8:9]
	v_lshl_add_u64 v[28:29], v[16:17], 0, v[28:29]
	v_lshlrev_b64 v[32:33], 16, v[32:33]
	v_lshlrev_b64 v[34:35], 16, v[34:35]
	v_lshlrev_b64 v[36:37], 16, v[36:37]
	v_lshlrev_b64 v[38:39], 16, v[38:39]
	v_lshlrev_b64 v[40:41], 16, v[40:41]
	v_lshlrev_b64 v[60:61], 16, v[60:61]
	v_lshlrev_b64 v[62:63], 16, v[62:63]
	v_lshlrev_b64 v[64:65], 16, v[64:65]
	v_lshlrev_b64 v[66:67], 16, v[66:67]
	v_lshlrev_b64 v[68:69], 16, v[68:69]
	v_lshlrev_b64 v[70:71], 16, v[70:71]
	v_lshlrev_b64 v[72:73], 16, v[72:73]
	v_lshlrev_b64 v[74:75], 16, v[74:75]
	v_lshlrev_b64 v[76:77], 16, v[76:77]
	v_lshlrev_b64 v[78:79], 16, v[78:79]
	v_lshlrev_b64 v[80:81], 16, v[80:81]
	v_lshlrev_b64 v[82:83], 16, v[82:83]
	v_lshlrev_b64 v[84:85], 16, v[84:85]
	v_lshlrev_b64 v[86:87], 16, v[86:87]
	v_lshlrev_b64 v[88:89], 16, v[88:89]
	v_lshlrev_b64 v[90:91], 16, v[90:91]
	v_lshl_add_u64 v[30:31], v[16:17], 0, v[30:31]
	v_lshl_add_u64 v[42:43], v[16:17], 0, v[42:43]
	v_lshl_add_u64 v[44:45], v[16:17], 0, v[44:45]
	v_lshl_add_u64 v[46:47], v[16:17], 0, v[46:47]
	v_lshl_add_u64 v[48:49], v[16:17], 0, v[48:49]
	v_lshl_add_u64 v[50:51], v[16:17], 0, v[50:51]
	v_lshl_add_u64 v[52:53], v[16:17], 0, v[52:53]
	v_lshl_add_u64 v[54:55], v[16:17], 0, v[54:55]
	v_lshl_add_u64 v[56:57], v[16:17], 0, v[56:57]
	v_lshl_add_u64 v[58:59], v[16:17], 0, v[58:59]
	global_load_dwordx4 v[2:5], v[14:15], off
	v_lshl_add_u64 v[32:33], v[16:17], 0, v[32:33]
	v_lshl_add_u64 v[34:35], v[16:17], 0, v[34:35]
	v_lshl_add_u64 v[36:37], v[16:17], 0, v[36:37]
	v_lshl_add_u64 v[38:39], v[16:17], 0, v[38:39]
	v_lshl_add_u64 v[40:41], v[16:17], 0, v[40:41]
	v_lshl_add_u64 v[60:61], v[16:17], 0, v[60:61]
	v_lshl_add_u64 v[62:63], v[16:17], 0, v[62:63]
	v_lshl_add_u64 v[64:65], v[16:17], 0, v[64:65]
	v_lshl_add_u64 v[66:67], v[16:17], 0, v[66:67]
	v_lshl_add_u64 v[68:69], v[16:17], 0, v[68:69]
	v_lshl_add_u64 v[70:71], v[16:17], 0, v[70:71]
	v_lshl_add_u64 v[72:73], v[16:17], 0, v[72:73]
	v_lshl_add_u64 v[74:75], v[16:17], 0, v[74:75]
	v_lshl_add_u64 v[76:77], v[16:17], 0, v[76:77]
	v_lshl_add_u64 v[78:79], v[16:17], 0, v[78:79]
	v_lshl_add_u64 v[80:81], v[16:17], 0, v[80:81]
	v_lshl_add_u64 v[82:83], v[16:17], 0, v[82:83]
	v_lshl_add_u64 v[84:85], v[16:17], 0, v[84:85]
	v_lshl_add_u64 v[86:87], v[16:17], 0, v[86:87]
	v_lshl_add_u64 v[88:89], v[16:17], 0, v[88:89]
	v_lshl_add_u64 v[16:17], v[16:17], 0, v[90:91]
	global_load_dword v90, v[28:29], off nt
	global_load_dword v91, v[30:31], off nt
	global_load_dword v92, v[32:33], off nt
	global_load_dword v93, v[34:35], off nt
	global_load_dword v94, v[36:37], off nt
	global_load_dword v95, v[38:39], off nt
	global_load_dword v96, v[40:41], off nt
	global_load_dword v97, v[42:43], off nt
	global_load_dword v98, v[44:45], off nt
	global_load_dword v99, v[46:47], off nt
	global_load_dword v100, v[48:49], off nt
	global_load_dword v101, v[50:51], off nt
	global_load_dword v102, v[52:53], off nt
	global_load_dword v103, v[54:55], off nt
	global_load_dword v104, v[56:57], off nt
	global_load_dword v42, v[58:59], off nt
	global_load_dword v43, v[60:61], off nt
	global_load_dword v44, v[62:63], off nt
	global_load_dword v45, v[64:65], off nt
	global_load_dword v46, v[66:67], off nt
	global_load_dword v47, v[68:69], off nt
	global_load_dword v48, v[70:71], off nt
	global_load_dword v49, v[72:73], off nt
	global_load_dword v50, v[74:75], off nt
	global_load_dword v51, v[76:77], off nt
	global_load_dword v52, v[78:79], off nt
	global_load_dword v53, v[80:81], off nt
	global_load_dword v54, v[82:83], off nt
	global_load_dword v55, v[84:85], off nt
	global_load_dword v56, v[86:87], off nt
	global_load_dword v57, v[88:89], off nt
	global_load_dword v58, v[16:17], off nt
	global_load_dwordx4 v[28:31], v[14:15], off offset:16
	s_sub_i32 s9, s5, s9
	v_add_u32_e32 v16, s9, v19
	v_add_u32_e32 v6, 0x2000, v16
	v_lshl_add_u64 v[32:33], s[2:3], 1, v[12:13]
	v_lshlrev_b64 v[14:15], 13, v[6:7]
	v_add_u32_e32 v6, 0x2008, v16
	v_lshl_add_u64 v[34:35], v[32:33], 0, v[14:15]
	v_lshlrev_b64 v[14:15], 13, v[6:7]
	v_add_u32_e32 v6, 0x2010, v16
	v_lshl_add_u64 v[36:37], v[32:33], 0, v[14:15]
	v_lshlrev_b64 v[14:15], 13, v[6:7]
	s_waitcnt vmcnt(31)
; __device__ __forceinline__ unsigned pk2(float lo, float hi) { unsigned r; asm volatile("v_cvt_pk_bf16_f32 %0, %1, %2" : "=v"(r) : "v"(lo), "v"(hi)); return r; }
; __device__ __forceinline__ void p0_transpose_item(const float* W, int K, int N, bf16* WT, int kb, int src_col0, int dst_row0, float* scr, int lane, const float* kgain = nullptr) {
;     ...
;         for (int i = 0; i < 32; ++i) { const int kk = 2 * i + (lane >> 5); scr[kk * 33 + (lane & 31)] = wv[i]; }
;     }
;     __builtin_amdgcn_s_waitcnt(0xC07F); asm volatile("" ::: "memory");
; #pragma unroll
;     for (int j = 0; j < 4; ++j) { const int n = (lane >> 3) + 8 * j; const float* s = scr + (8 * c) * 33 + n;
;         v4u o;
;         if (src_col0 >= 0) { o.x = pk2(s[0 * 33] * g0.x, s[1 * 33] * g0.y); o.y = pk2(s[2 * 33] * g0.z, s[3 * 33] * g0.w); o.z = pk2(s[4 * 33] * g1.x, s[5 * 33] * g1.y); o.w = pk2(s[6 * 33] * g1.z, s[7 * 33] * g1.w); }
;         else { o.x = 0u; o.y = 0u; o.z = 0u; o.w = 0u; }
;         *(v4u*)(WT + (size_t)(dst_row0 + n) * K + k0 + 8 * c) = o; }
;     __builtin_amdgcn_s_waitcnt(0xC07F); asm volatile("" ::: "memory");
	ds_write2_b32 v18, v90, v91 offset1:66
	s_waitcnt vmcnt(29)
	ds_write2_b32 v18, v92, v93 offset0:132 offset1:198
	s_waitcnt vmcnt(27)
	ds_write2_b32 v21, v94, v95 offset0:8 offset1:74
	s_waitcnt vmcnt(25)
	ds_write2_b32 v21, v96, v97 offset0:140 offset1:206
	s_waitcnt vmcnt(23)
	ds_write2_b32 v22, v98, v99 offset0:16 offset1:82
	s_waitcnt vmcnt(21)
	ds_write2_b32 v22, v100, v101 offset0:148 offset1:214
	s_waitcnt vmcnt(19)
	ds_write2_b32 v23, v102, v103 offset0:24 offset1:90
	s_waitcnt vmcnt(17)
	ds_write2_b32 v23, v104, v42 offset0:156 offset1:222
	s_waitcnt vmcnt(15)
	ds_write2_b32 v24, v43, v44 offset0:32 offset1:98
	s_waitcnt vmcnt(13)
	ds_write2_b32 v24, v45, v46 offset0:164 offset1:230
	s_waitcnt vmcnt(11)
	ds_write2_b32 v25, v47, v48 offset0:40 offset1:106
	s_waitcnt vmcnt(9)
	ds_write2_b32 v25, v49, v50 offset0:172 offset1:238
	s_waitcnt vmcnt(7)
	ds_write2_b32 v26, v51, v52 offset0:48 offset1:114
	s_waitcnt vmcnt(5)
	ds_write2_b32 v26, v53, v54 offset0:180 offset1:246
	s_waitcnt vmcnt(3)
	ds_write2_b32 v27, v55, v56 offset0:56 offset1:122
	s_waitcnt vmcnt(1)
	ds_write2_b32 v27, v57, v58 offset0:188 offset1:254
	s_waitcnt lgkmcnt(0)
	v_lshl_add_u64 v[38:39], v[32:33], 0, v[14:15]
	ds_read2_b32 v[14:15], v20 offset1:33
	v_add_u32_e32 v6, 0x2018, v16
	v_lshlrev_b64 v[40:41], 13, v[6:7]
	s_add_i32 s0, s4, 0x400
	s_add_i32 s8, s8, 0x8000
	s_waitcnt lgkmcnt(0)
	v_mul_f32_e32 v6, v2, v14
	v_mul_f32_e32 v14, v3, v15
	v_cvt_pk_bf16_f32 v14, v6, v14
	ds_read2_b32 v[16:17], v20 offset0:66 offset1:99
	v_add_u32_e32 v19, 0x8000, v19
	s_cmpk_lt_i32 s4, 0x3c00
	s_mov_b32 s4, s0
	s_waitcnt lgkmcnt(0)
	v_mul_f32_e32 v15, v5, v17
	v_mul_f32_e32 v6, v4, v16
	v_cvt_pk_bf16_f32 v15, v6, v15
	ds_read2_b32 v[16:17], v20 offset0:132 offset1:165
	s_waitcnt vmcnt(0) lgkmcnt(0)
	v_mul_f32_e32 v6, v28, v16
	v_mul_f32_e32 v16, v29, v17
	v_cvt_pk_bf16_f32 v16, v6, v16
	ds_read2_b32 v[42:43], v20 offset0:198 offset1:231
	s_waitcnt lgkmcnt(0)
	v_mul_f32_e32 v17, v31, v43
	v_mul_f32_e32 v6, v30, v42
	v_cvt_pk_bf16_f32 v17, v6, v17
	ds_read2_b32 v[42:43], v20 offset0:8 offset1:41
	global_store_dwordx4 v[34:35], v[14:17], off sc1
	s_waitcnt lgkmcnt(0)
	v_mul_f32_e32 v6, v2, v42
	v_mul_f32_e32 v14, v3, v43
	v_cvt_pk_bf16_f32 v14, v6, v14
	ds_read2_b32 v[16:17], v20 offset0:74 offset1:107
	s_waitcnt lgkmcnt(0)
	v_mul_f32_e32 v15, v5, v17
	v_mul_f32_e32 v6, v4, v16
	v_cvt_pk_bf16_f32 v15, v6, v15
	ds_read2_b32 v[16:17], v20 offset0:140 offset1:173
	s_waitcnt lgkmcnt(0)
	v_mul_f32_e32 v6, v28, v16
	v_mul_f32_e32 v16, v29, v17
	v_cvt_pk_bf16_f32 v16, v6, v16
	ds_read2_b32 v[34:35], v20 offset0:206 offset1:239
	s_waitcnt lgkmcnt(0)
	v_mul_f32_e32 v17, v31, v35
	v_mul_f32_e32 v6, v30, v34
	v_cvt_pk_bf16_f32 v17, v6, v17
	ds_read2_b32 v[34:35], v20 offset0:16 offset1:49
	global_store_dwordx4 v[36:37], v[14:17], off sc1
	s_waitcnt lgkmcnt(0)
	v_mul_f32_e32 v6, v2, v34
	v_mul_f32_e32 v14, v3, v35
	v_cvt_pk_bf16_f32 v14, v6, v14
	ds_read2_b32 v[16:17], v20 offset0:82 offset1:115
	s_waitcnt lgkmcnt(0)
	v_mul_f32_e32 v15, v5, v17
	v_mul_f32_e32 v6, v4, v16
	v_cvt_pk_bf16_f32 v15, v6, v15
	ds_read2_b32 v[16:17], v20 offset0:148 offset1:181
	s_waitcnt lgkmcnt(0)
	v_mul_f32_e32 v6, v28, v16
	v_mul_f32_e32 v16, v29, v17
	v_cvt_pk_bf16_f32 v16, v6, v16
	ds_read2_b32 v[34:35], v20 offset0:214 offset1:247
	s_waitcnt lgkmcnt(0)
	v_mul_f32_e32 v17, v31, v35
	v_mul_f32_e32 v6, v30, v34
	v_cvt_pk_bf16_f32 v17, v6, v17
	ds_read2_b32 v[34:35], v20 offset0:24 offset1:57
	global_store_dwordx4 v[38:39], v[14:17], off sc1
	s_waitcnt lgkmcnt(0)
	v_mul_f32_e32 v2, v2, v34
	v_mul_f32_e32 v3, v3, v35
	v_cvt_pk_bf16_f32 v2, v2, v3
	ds_read2_b32 v[14:15], v20 offset0:90 offset1:123
	v_lshl_add_u64 v[16:17], v[32:33], 0, v[40:41]
	s_waitcnt lgkmcnt(0)
	v_mul_f32_e32 v3, v4, v14
	v_mul_f32_e32 v4, v5, v15
	v_cvt_pk_bf16_f32 v3, v3, v4
	ds_read2_b32 v[4:5], v20 offset0:156 offset1:189
	s_waitcnt lgkmcnt(0)
	v_mul_f32_e32 v4, v28, v4
	v_mul_f32_e32 v5, v29, v5
	v_cvt_pk_bf16_f32 v4, v4, v5
	ds_read2_b32 v[14:15], v20 offset0:222 offset1:255
	s_waitcnt lgkmcnt(0)
	v_mul_f32_e32 v5, v30, v14
	v_mul_f32_e32 v6, v31, v15
	v_cvt_pk_bf16_f32 v5, v5, v6
	global_store_dwordx4 v[16:17], v[2:5], off sc1
	s_waitcnt lgkmcnt(0)
	s_cbranch_scc1 .LBB0_261
	s_mov_b64 s[0:1], 0

; __device__ __forceinline__ unsigned pk2(float lo, float hi) { unsigned r; asm volatile("v_cvt_pk_bf16_f32 %0, %1, %2" : "=v"(r) : "v"(lo), "v"(hi)); return r; }
; __device__ __forceinline__ void p0_transpose_item(const float* W, int K, int N, bf16* WT, int kb, int src_col0, int dst_row0, float* scr, int lane, const float* kgain = nullptr) {
;     ...
;     for (int j = 0; j < 4; ++j) { const int n = (lane >> 3) + 8 * j; const float* s = scr + (8 * c) * 33 + n;
;         v4u o;
;         if (src_col0 >= 0) { o.x = pk2(s[0 * 33] * g0.x, s[1 * 33] * g0.y); o.y = pk2(s[2 * 33] * g0.z, s[3 * 33] * g0.w); o.z = pk2(s[4 * 33] * g1.x, s[5 * 33] * g1.y); o.w = pk2(s[6 * 33] * g1.z, s[7 * 33] * g1.w); }
;         else { o.x = 0u; o.y = 0u; o.z = 0u; o.w = 0u; }
;         *(v4u*)(WT + (size_t)(dst_row0 + n) * K + k0 + 8 * c) = o; }
.LBB0_267:
	v_add_u32_e32 v6, 24, v30
	v_ashrrev_i32_e32 v7, 31, v6
	v_lshlrev_b64 v[6:7], 13, v[6:7]
	v_lshl_add_u64 v[6:7], v[28:29], 0, v[6:7]
	global_store_dwordx4 v[6:7], v[14:17], off sc1
	s_waitcnt lgkmcnt(0)
	s_add_i32 s8, s23, 0x400
	s_add_i32 s13, s13, 0x8000
	s_cmpk_lt_i32 s23, 0x400
	s_mov_b32 s23, s8
	s_cbranch_scc0 .LBB0_282

; __device__ __forceinline__ unsigned pk2(float lo, float hi) { unsigned r; asm volatile("v_cvt_pk_bf16_f32 %0, %1, %2" : "=v"(r) : "v"(lo), "v"(hi)); return r; }
; __device__ __forceinline__ void p0_transpose_item(const float* W, int K, int N, bf16* WT, int kb, int src_col0, int dst_row0, float* scr, int lane, const float* kgain = nullptr) {
;     ...
;     for (int j = 0; j < 4; ++j) { const int n = (lane >> 3) + 8 * j; const float* s = scr + (8 * c) * 33 + n;
;         v4u o;
;         if (src_col0 >= 0) { o.x = pk2(s[0 * 33] * g0.x, s[1 * 33] * g0.y); o.y = pk2(s[2 * 33] * g0.z, s[3 * 33] * g0.w); o.z = pk2(s[4 * 33] * g1.x, s[5 * 33] * g1.y); o.w = pk2(s[6 * 33] * g1.z, s[7 * 33] * g1.w); }
;         else { o.x = 0u; o.y = 0u; o.z = 0u; o.w = 0u; }
;         *(v4u*)(WT + (size_t)(dst_row0 + n) * K + k0 + 8 * c) = o; }
;     __builtin_amdgcn_s_waitcnt(0xC07F); asm volatile("" ::: "memory");
.LBB0_274:
	s_waitcnt lgkmcnt(0)
	s_ashr_i32 s17, s16, 31
	s_sub_i32 s8, 0, s24
	v_lshl_add_u64 v[28:29], s[16:17], 1, v[26:27]
	s_mov_b64 s[16:17], -1
	s_and_b64 vcc, exec, s[14:15]
	s_cbranch_vccz .LBB0_276
	s_add_i32 s16, s8, s13
	v_add_u32_e32 v30, s16, v35
	v_ashrrev_i32_e32 v31, 31, v30
	v_lshlrev_b64 v[14:15], 13, v[30:31]
	v_lshl_add_u64 v[14:15], v[28:29], 0, v[14:15]
	global_store_dwordx4 v[14:15], v[2:5], off sc1
	s_mov_b64 s[16:17], 0
.LBB0_276:
	v_mov_b32_e32 v14, 0
	s_andn2_b64 vcc, exec, s[16:17]
	v_mov_b32_e32 v15, 0
	v_mov_b32_e32 v16, 0
	v_mov_b32_e32 v17, 0
	s_cbranch_vccnz .LBB0_278
	ds_read2_b32 v[14:15], v36 offset1:33
	s_add_i32 s8, s8, s13
	v_add_u32_e32 v30, s8, v35
	s_waitcnt lgkmcnt(0)
	v_mul_f32_e32 v14, v10, v14
	v_mul_f32_e32 v15, v11, v15
	v_cvt_pk_bf16_f32 v14, v14, v15
	ds_read2_b32 v[16:17], v36 offset0:66 offset1:99
	s_waitcnt lgkmcnt(0)
	v_mul_f32_e32 v15, v12, v16
	v_mul_f32_e32 v16, v13, v17
	v_cvt_pk_bf16_f32 v15, v15, v16
	ds_read2_b32 v[16:17], v36 offset0:132 offset1:165
	s_waitcnt lgkmcnt(0)
	v_mul_f32_e32 v16, v6, v16
	v_mul_f32_e32 v17, v7, v17
	v_cvt_pk_bf16_f32 v16, v16, v17
	ds_read2_b32 v[32:33], v36 offset0:198 offset1:231
	s_waitcnt lgkmcnt(0)
	v_mul_f32_e32 v17, v8, v32
	v_mul_f32_e32 v31, v9, v33
	v_cvt_pk_bf16_f32 v17, v17, v31
	ds_read2_b32 v[32:33], v36 offset0:8 offset1:41
	v_ashrrev_i32_e32 v31, 31, v30
	v_lshlrev_b64 v[42:43], 13, v[30:31]
	v_lshl_add_u64 v[42:43], v[28:29], 0, v[42:43]
	global_store_dwordx4 v[42:43], v[14:17], off sc1
	s_waitcnt lgkmcnt(0)
	s_nop 0
	v_mul_f32_e32 v14, v10, v32
	v_mul_f32_e32 v15, v11, v33
	v_cvt_pk_bf16_f32 v14, v14, v15
	ds_read2_b32 v[16:17], v36 offset0:74 offset1:107
	s_waitcnt lgkmcnt(0)
	v_mul_f32_e32 v15, v12, v16
	v_mul_f32_e32 v16, v13, v17
	v_cvt_pk_bf16_f32 v15, v15, v16
	ds_read2_b32 v[16:17], v36 offset0:140 offset1:173
	s_waitcnt lgkmcnt(0)
	v_mul_f32_e32 v16, v6, v16
	v_mul_f32_e32 v17, v7, v17
	v_cvt_pk_bf16_f32 v16, v16, v17
	ds_read2_b32 v[32:33], v36 offset0:206 offset1:239
	s_waitcnt lgkmcnt(0)
	v_mul_f32_e32 v17, v8, v32
	v_mul_f32_e32 v31, v9, v33
	v_cvt_pk_bf16_f32 v17, v17, v31
.LBB0_278:
	v_add_u32_e32 v32, 8, v30
	v_ashrrev_i32_e32 v33, 31, v32
	v_lshlrev_b64 v[32:33], 13, v[32:33]
	v_lshl_add_u64 v[32:33], v[28:29], 0, v[32:33]
	global_store_dwordx4 v[32:33], v[14:17], off sc1
	v_add_u32_e32 v32, 16, v30
	s_mov_b64 s[16:17], -1
	s_and_b64 vcc, exec, s[14:15]
	v_ashrrev_i32_e32 v33, 31, v32
	s_cbranch_vccz .LBB0_280
	v_lshlrev_b64 v[14:15], 13, v[32:33]
	v_lshl_add_u64 v[14:15], v[28:29], 0, v[14:15]
	global_store_dwordx4 v[14:15], v[2:5], off sc1
	s_mov_b64 s[16:17], 0
.LBB0_280:
	v_mov_b32_e32 v14, 0
	s_andn2_b64 vcc, exec, s[16:17]
	v_mov_b32_e32 v15, 0
	v_mov_b32_e32 v16, 0
	v_mov_b32_e32 v17, 0
	s_cbranch_vccnz .LBB0_267
	ds_read2_b32 v[14:15], v36 offset0:16 offset1:49
	v_lshlrev_b64 v[32:33], 13, v[32:33]
	v_lshl_add_u64 v[32:33], v[28:29], 0, v[32:33]
	s_waitcnt lgkmcnt(0)
	v_mul_f32_e32 v14, v10, v14
	v_mul_f32_e32 v15, v11, v15
	v_cvt_pk_bf16_f32 v14, v14, v15
	ds_read2_b32 v[16:17], v36 offset0:82 offset1:115
	s_waitcnt lgkmcnt(0)
	v_mul_f32_e32 v15, v12, v16
	v_mul_f32_e32 v16, v13, v17
	v_cvt_pk_bf16_f32 v15, v15, v16
	ds_read2_b32 v[16:17], v36 offset0:148 offset1:181
	s_waitcnt lgkmcnt(0)
	v_mul_f32_e32 v16, v6, v16
	v_mul_f32_e32 v17, v7, v17
	v_cvt_pk_bf16_f32 v16, v16, v17
	ds_read2_b32 v[42:43], v36 offset0:214 offset1:247
	s_waitcnt lgkmcnt(0)
	v_mul_f32_e32 v17, v8, v42
	v_mul_f32_e32 v31, v9, v43
	v_cvt_pk_bf16_f32 v17, v17, v31
	ds_read2_b32 v[42:43], v36 offset0:24 offset1:57
	global_store_dwordx4 v[32:33], v[14:17], off sc1
	s_waitcnt lgkmcnt(0)
	v_mul_f32_e32 v10, v10, v42
	v_mul_f32_e32 v11, v11, v43
	v_cvt_pk_bf16_f32 v14, v10, v11
	ds_read2_b32 v[10:11], v36 offset0:90 offset1:123
	s_waitcnt lgkmcnt(0)
	v_mul_f32_e32 v10, v12, v10
	v_mul_f32_e32 v11, v13, v11
	v_cvt_pk_bf16_f32 v15, v10, v11
	ds_read2_b32 v[10:11], v36 offset0:156 offset1:189
	s_waitcnt lgkmcnt(0)
	v_mul_f32_e32 v6, v6, v10
	v_mul_f32_e32 v7, v7, v11
	v_cvt_pk_bf16_f32 v16, v6, v7
	ds_read2_b32 v[6:7], v36 offset0:222 offset1:255
	s_waitcnt lgkmcnt(0)
	v_mul_f32_e32 v6, v8, v6
	v_mul_f32_e32 v7, v9, v7
	v_cvt_pk_bf16_f32 v17, v6, v7
	s_branch .LBB0_267

; __device__ __forceinline__ unsigned pk2(float lo, float hi) { unsigned r; asm volatile("v_cvt_pk_bf16_f32 %0, %1, %2" : "=v"(r) : "v"(lo), "v"(hi)); return r; }
; __device__ __forceinline__ void p0_transpose_item(const float* W, int K, int N, bf16* WT, int kb, int src_col0, int dst_row0, float* scr, int lane, const float* kgain = nullptr) {
;     ...
;     for (int j = 0; j < 4; ++j) { const int n = (lane >> 3) + 8 * j; const float* s = scr + (8 * c) * 33 + n;
;         v4u o;
;         if (src_col0 >= 0) { o.x = pk2(s[0 * 33] * g0.x, s[1 * 33] * g0.y); o.y = pk2(s[2 * 33] * g0.z, s[3 * 33] * g0.w); o.z = pk2(s[4 * 33] * g1.x, s[5 * 33] * g1.y); o.w = pk2(s[6 * 33] * g1.z, s[7 * 33] * g1.w); }
;         else { o.x = 0u; o.y = 0u; o.z = 0u; o.w = 0u; }
;         *(v4u*)(WT + (size_t)(dst_row0 + n) * K + k0 + 8 * c) = o; }
.LBB0_286:
	v_add_u32_e32 v6, 24, v30
	v_ashrrev_i32_e32 v7, 31, v6
	v_lshlrev_b64 v[6:7], 13, v[6:7]
	v_lshl_add_u64 v[6:7], v[28:29], 0, v[6:7]
	global_store_dwordx4 v[6:7], v[14:17], off sc1
	s_waitcnt lgkmcnt(0)
	s_add_i32 s4, s20, 0x400
	s_add_i32 s12, s12, 0x8000
	s_cmpk_lt_i32 s20, 0x4600
	s_mov_b32 s20, s4
	s_cbranch_scc0 .LBB0_306

; __device__ __forceinline__ unsigned pk2(float lo, float hi) { unsigned r; asm volatile("v_cvt_pk_bf16_f32 %0, %1, %2" : "=v"(r) : "v"(lo), "v"(hi)); return r; }
; __device__ __forceinline__ void p0_transpose_item(const float* W, int K, int N, bf16* WT, int kb, int src_col0, int dst_row0, float* scr, int lane, const float* kgain = nullptr) {
;     ...
;     for (int j = 0; j < 4; ++j) { const int n = (lane >> 3) + 8 * j; const float* s = scr + (8 * c) * 33 + n;
;         v4u o;
;         if (src_col0 >= 0) { o.x = pk2(s[0 * 33] * g0.x, s[1 * 33] * g0.y); o.y = pk2(s[2 * 33] * g0.z, s[3 * 33] * g0.w); o.z = pk2(s[4 * 33] * g1.x, s[5 * 33] * g1.y); o.w = pk2(s[6 * 33] * g1.z, s[7 * 33] * g1.w); }
;         else { o.x = 0u; o.y = 0u; o.z = 0u; o.w = 0u; }
;         *(v4u*)(WT + (size_t)(dst_row0 + n) * K + k0 + 8 * c) = o; }
;     __builtin_amdgcn_s_waitcnt(0xC07F); asm volatile("" ::: "memory");
.LBB0_298:
	s_waitcnt lgkmcnt(0)
	s_ashr_i32 s11, s10, 31
	v_lshl_add_u64 v[28:29], s[10:11], 1, v[26:27]
	s_mov_b64 s[10:11], -1
	s_and_b64 vcc, exec, s[8:9]
	s_cbranch_vccz .LBB0_300
	s_add_i32 s4, s12, s14
	v_add_u32_e32 v30, s4, v35
	v_ashrrev_i32_e32 v31, 31, v30
	v_lshlrev_b64 v[14:15], 13, v[30:31]
	v_lshl_add_u64 v[14:15], v[28:29], 0, v[14:15]
	global_store_dwordx4 v[14:15], v[2:5], off sc1
	s_mov_b64 s[10:11], 0
.LBB0_300:
	v_mov_b32_e32 v14, 0
	s_andn2_b64 vcc, exec, s[10:11]
	v_mov_b32_e32 v15, 0
	v_mov_b32_e32 v16, 0
	v_mov_b32_e32 v17, 0
	s_cbranch_vccnz .LBB0_302
	ds_read2_b32 v[14:15], v36 offset1:33
	s_add_i32 s4, s12, s14
	v_add_u32_e32 v30, s4, v35
	s_waitcnt lgkmcnt(0)
	v_mul_f32_e32 v14, v10, v14
	v_mul_f32_e32 v15, v11, v15
	v_cvt_pk_bf16_f32 v14, v14, v15
	ds_read2_b32 v[16:17], v36 offset0:66 offset1:99
	s_waitcnt lgkmcnt(0)
	v_mul_f32_e32 v15, v12, v16
	v_mul_f32_e32 v16, v13, v17
	v_cvt_pk_bf16_f32 v15, v15, v16
	ds_read2_b32 v[16:17], v36 offset0:132 offset1:165
	s_waitcnt lgkmcnt(0)
	v_mul_f32_e32 v16, v6, v16
	v_mul_f32_e32 v17, v7, v17
	v_cvt_pk_bf16_f32 v16, v16, v17
	ds_read2_b32 v[32:33], v36 offset0:198 offset1:231
	s_waitcnt lgkmcnt(0)
	v_mul_f32_e32 v17, v8, v32
	v_mul_f32_e32 v31, v9, v33
	v_cvt_pk_bf16_f32 v17, v17, v31
	ds_read2_b32 v[32:33], v36 offset0:8 offset1:41
	v_ashrrev_i32_e32 v31, 31, v30
	v_lshlrev_b64 v[42:43], 13, v[30:31]
	v_lshl_add_u64 v[42:43], v[28:29], 0, v[42:43]
	global_store_dwordx4 v[42:43], v[14:17], off sc1
	s_waitcnt lgkmcnt(0)
	s_nop 0
	v_mul_f32_e32 v14, v10, v32
	v_mul_f32_e32 v15, v11, v33
	v_cvt_pk_bf16_f32 v14, v14, v15
	ds_read2_b32 v[16:17], v36 offset0:74 offset1:107
	s_waitcnt lgkmcnt(0)
	v_mul_f32_e32 v15, v12, v16
	v_mul_f32_e32 v16, v13, v17
	v_cvt_pk_bf16_f32 v15, v15, v16
	ds_read2_b32 v[16:17], v36 offset0:140 offset1:173
	s_waitcnt lgkmcnt(0)
	v_mul_f32_e32 v16, v6, v16
	v_mul_f32_e32 v17, v7, v17
	v_cvt_pk_bf16_f32 v16, v16, v17
	ds_read2_b32 v[32:33], v36 offset0:206 offset1:239
	s_waitcnt lgkmcnt(0)
	v_mul_f32_e32 v17, v8, v32
	v_mul_f32_e32 v31, v9, v33
	v_cvt_pk_bf16_f32 v17, v17, v31
.LBB0_302:
	v_add_u32_e32 v32, 8, v30
	v_ashrrev_i32_e32 v33, 31, v32
	v_lshlrev_b64 v[32:33], 13, v[32:33]
	v_lshl_add_u64 v[32:33], v[28:29], 0, v[32:33]
	global_store_dwordx4 v[32:33], v[14:17], off sc1
	v_add_u32_e32 v32, 16, v30
	s_mov_b64 s[10:11], -1
	s_and_b64 vcc, exec, s[8:9]
	v_ashrrev_i32_e32 v33, 31, v32
	s_cbranch_vccz .LBB0_304
	v_lshlrev_b64 v[14:15], 13, v[32:33]
	v_lshl_add_u64 v[14:15], v[28:29], 0, v[14:15]
	global_store_dwordx4 v[14:15], v[2:5], off sc1
	s_mov_b64 s[10:11], 0
.LBB0_304:
	v_mov_b32_e32 v14, 0
	s_andn2_b64 vcc, exec, s[10:11]
	v_mov_b32_e32 v15, 0
	v_mov_b32_e32 v16, 0
	v_mov_b32_e32 v17, 0
	s_cbranch_vccnz .LBB0_286
	ds_read2_b32 v[14:15], v36 offset0:16 offset1:49
	v_lshlrev_b64 v[32:33], 13, v[32:33]
	v_lshl_add_u64 v[32:33], v[28:29], 0, v[32:33]
	s_waitcnt lgkmcnt(0)
	v_mul_f32_e32 v14, v10, v14
	v_mul_f32_e32 v15, v11, v15
	v_cvt_pk_bf16_f32 v14, v14, v15
	ds_read2_b32 v[16:17], v36 offset0:82 offset1:115
	s_waitcnt lgkmcnt(0)
	v_mul_f32_e32 v15, v12, v16
	v_mul_f32_e32 v16, v13, v17
	v_cvt_pk_bf16_f32 v15, v15, v16
	ds_read2_b32 v[16:17], v36 offset0:148 offset1:181
	s_waitcnt lgkmcnt(0)
	v_mul_f32_e32 v16, v6, v16
	v_mul_f32_e32 v17, v7, v17
	v_cvt_pk_bf16_f32 v16, v16, v17
	ds_read2_b32 v[42:43], v36 offset0:214 offset1:247
	s_waitcnt lgkmcnt(0)
	v_mul_f32_e32 v17, v8, v42
	v_mul_f32_e32 v31, v9, v43
	v_cvt_pk_bf16_f32 v17, v17, v31
	ds_read2_b32 v[42:43], v36 offset0:24 offset1:57
	global_store_dwordx4 v[32:33], v[14:17], off sc1
	s_waitcnt lgkmcnt(0)
	v_mul_f32_e32 v10, v10, v42
	v_mul_f32_e32 v11, v11, v43
	v_cvt_pk_bf16_f32 v14, v10, v11
	ds_read2_b32 v[10:11], v36 offset0:90 offset1:123
	s_waitcnt lgkmcnt(0)
	v_mul_f32_e32 v10, v12, v10
	v_mul_f32_e32 v11, v13, v11
	v_cvt_pk_bf16_f32 v15, v10, v11
	ds_read2_b32 v[10:11], v36 offset0:156 offset1:189
	s_waitcnt lgkmcnt(0)
	v_mul_f32_e32 v6, v6, v10
	v_mul_f32_e32 v7, v7, v11
	v_cvt_pk_bf16_f32 v16, v6, v7
	ds_read2_b32 v[6:7], v36 offset0:222 offset1:255
	s_waitcnt lgkmcnt(0)
	v_mul_f32_e32 v6, v8, v6
	v_mul_f32_e32 v7, v9, v7
	v_cvt_pk_bf16_f32 v17, v6, v7
	s_branch .LBB0_286

; __device__ __forceinline__ unsigned pk2(float lo, float hi) { unsigned r; asm volatile("v_cvt_pk_bf16_f32 %0, %1, %2" : "=v"(r) : "v"(lo), "v"(hi)); return r; }
; __device__ __forceinline__ void p0_transpose_item(const float* W, int K, int N, bf16* WT, int kb, int src_col0, int dst_row0, float* scr, int lane, const float* kgain = nullptr) {
;     ...
;     for (int j = 0; j < 4; ++j) { const int n = (lane >> 3) + 8 * j; const float* s = scr + (8 * c) * 33 + n;
;         v4u o;
;         if (src_col0 >= 0) { o.x = pk2(s[0 * 33] * g0.x, s[1 * 33] * g0.y); o.y = pk2(s[2 * 33] * g0.z, s[3 * 33] * g0.w); o.z = pk2(s[4 * 33] * g1.x, s[5 * 33] * g1.y); o.w = pk2(s[6 * 33] * g1.z, s[7 * 33] * g1.w); }
;         else { o.x = 0u; o.y = 0u; o.z = 0u; o.w = 0u; }
;         *(v4u*)(WT + (size_t)(dst_row0 + n) * K + k0 + 8 * c) = o; }
.LBB0_307:
	v_add_u32_e32 v20, 24, v6
	v_ashrrev_i32_e32 v21, 31, v20
	v_lshlrev_b64 v[20:21], 13, v[20:21]
	v_lshl_add_u64 v[12:13], v[12:13], 0, v[20:21]
	global_store_dwordx4 v[12:13], v[2:5], off sc1
	s_waitcnt lgkmcnt(0)
	s_add_i32 s2, s13, 0x400
	s_add_i32 s12, s12, 0x8000
	s_cmpk_lt_i32 s13, 0x1c00
	s_mov_b32 s13, s2
	s_cbranch_scc0 .LBB0_318

; __device__ __forceinline__ unsigned pk2(float lo, float hi) { unsigned r; asm volatile("v_cvt_pk_bf16_f32 %0, %1, %2" : "=v"(r) : "v"(lo), "v"(hi)); return r; }
; __device__ __forceinline__ void p0_transpose_item(const float* W, int K, int N, bf16* WT, int kb, int src_col0, int dst_row0, float* scr, int lane, const float* kgain = nullptr) {
;     ...
;     for (int j = 0; j < 4; ++j) { const int n = (lane >> 3) + 8 * j; const float* s = scr + (8 * c) * 33 + n;
;         v4u o;
;         if (src_col0 >= 0) { o.x = pk2(s[0 * 33] * g0.x, s[1 * 33] * g0.y); o.y = pk2(s[2 * 33] * g0.z, s[3 * 33] * g0.w); o.z = pk2(s[4 * 33] * g1.x, s[5 * 33] * g1.y); o.w = pk2(s[6 * 33] * g1.z, s[7 * 33] * g1.w); }
;         else { o.x = 0u; o.y = 0u; o.z = 0u; o.w = 0u; }
;         *(v4u*)(WT + (size_t)(dst_row0 + n) * K + k0 + 8 * c) = o; }
;     __builtin_amdgcn_s_waitcnt(0xC07F); asm volatile("" ::: "memory");
.LBB0_310:
	s_waitcnt lgkmcnt(0)
	s_ashr_i32 s9, s8, 31
	v_lshl_add_u64 v[12:13], s[8:9], 1, v[10:11]
	s_mov_b64 s[8:9], -1
	s_and_b64 vcc, exec, s[4:5]
	s_cbranch_vccz .LBB0_312
	s_add_i32 s2, s14, s12
	v_add_u32_e32 v2, s2, v35
	v_ashrrev_i32_e32 v3, 31, v2
	v_lshlrev_b64 v[4:5], 13, v[2:3]
	v_lshl_add_u64 v[4:5], v[12:13], 0, v[4:5]
	global_store_dwordx4 v[4:5], v[26:29], off sc1
	s_mov_b64 s[8:9], 0
	v_mov_b32_e32 v6, v2
.LBB0_312:
	v_mov_b32_e32 v2, 0
	s_andn2_b64 vcc, exec, s[8:9]
	v_mov_b32_e32 v3, 0
	v_mov_b32_e32 v4, 0
	v_mov_b32_e32 v5, 0
	s_cbranch_vccnz .LBB0_314
	ds_read2_b32 v[2:3], v36 offset1:33
	s_add_i32 s14, s14, s12
	s_waitcnt lgkmcnt(0)
	v_cvt_pk_bf16_f32 v2, v2, v3
	ds_read2_b32 v[4:5], v36 offset0:66 offset1:99
	v_add_u32_e32 v6, s14, v35
	s_waitcnt lgkmcnt(0)
	v_cvt_pk_bf16_f32 v3, v4, v5
	ds_read2_b32 v[4:5], v36 offset0:132 offset1:165
	v_lshlrev_b64 v[30:31], 13, v[6:7]
	s_waitcnt lgkmcnt(0)
	v_cvt_pk_bf16_f32 v4, v4, v5
	ds_read2_b32 v[20:21], v36 offset0:198 offset1:231
	s_waitcnt lgkmcnt(0)
	v_cvt_pk_bf16_f32 v5, v20, v21
	v_lshl_add_u64 v[30:31], v[12:13], 0, v[30:31]
	ds_read2_b32 v[20:21], v36 offset0:8 offset1:41
	global_store_dwordx4 v[30:31], v[2:5], off sc1
	s_waitcnt lgkmcnt(0)
	s_nop 0
	v_cvt_pk_bf16_f32 v2, v20, v21
	ds_read2_b32 v[4:5], v36 offset0:74 offset1:107
	s_waitcnt lgkmcnt(0)
	v_cvt_pk_bf16_f32 v3, v4, v5
	ds_read2_b32 v[4:5], v36 offset0:140 offset1:173
	s_waitcnt lgkmcnt(0)
	v_cvt_pk_bf16_f32 v4, v4, v5
	ds_read2_b32 v[20:21], v36 offset0:206 offset1:239
	s_waitcnt lgkmcnt(0)
	v_cvt_pk_bf16_f32 v5, v20, v21
.LBB0_314:
	v_add_u32_e32 v20, 8, v6
	v_ashrrev_i32_e32 v21, 31, v20
	v_lshlrev_b64 v[20:21], 13, v[20:21]
	v_lshl_add_u64 v[20:21], v[12:13], 0, v[20:21]
	global_store_dwordx4 v[20:21], v[2:5], off sc1
	s_mov_b64 s[8:9], -1
	s_and_b64 vcc, exec, s[4:5]
	v_add_u32_e32 v20, 16, v6
	s_cbranch_vccz .LBB0_316
	v_ashrrev_i32_e32 v21, 31, v20
	v_lshlrev_b64 v[2:3], 13, v[20:21]
	v_lshl_add_u64 v[2:3], v[12:13], 0, v[2:3]
	global_store_dwordx4 v[2:3], v[26:29], off sc1
	s_mov_b64 s[8:9], 0
.LBB0_316:
	v_mov_b32_e32 v2, 0
	s_andn2_b64 vcc, exec, s[8:9]
	v_mov_b32_e32 v3, 0
	v_mov_b32_e32 v4, 0
	v_mov_b32_e32 v5, 0
	s_cbranch_vccnz .LBB0_307
	ds_read2_b32 v[2:3], v36 offset0:16 offset1:49
	s_waitcnt lgkmcnt(0)
	v_cvt_pk_bf16_f32 v2, v2, v3
	ds_read2_b32 v[4:5], v36 offset0:82 offset1:115
	v_mov_b32_e32 v21, v7
	s_waitcnt lgkmcnt(0)
	v_cvt_pk_bf16_f32 v3, v4, v5
	ds_read2_b32 v[4:5], v36 offset0:148 offset1:181
	v_lshlrev_b64 v[20:21], 13, v[20:21]
	s_waitcnt lgkmcnt(0)
	v_cvt_pk_bf16_f32 v4, v4, v5
	ds_read2_b32 v[30:31], v36 offset0:214 offset1:247
	s_waitcnt lgkmcnt(0)
	v_cvt_pk_bf16_f32 v5, v30, v31
	v_lshl_add_u64 v[20:21], v[12:13], 0, v[20:21]
	ds_read2_b32 v[30:31], v36 offset0:24 offset1:57
	global_store_dwordx4 v[20:21], v[2:5], off sc1
	s_waitcnt lgkmcnt(0)
	s_nop 0
	v_cvt_pk_bf16_f32 v2, v30, v31
	ds_read2_b32 v[4:5], v36 offset0:90 offset1:123
	s_waitcnt lgkmcnt(0)
	v_cvt_pk_bf16_f32 v3, v4, v5
	ds_read2_b32 v[4:5], v36 offset0:156 offset1:189
	s_waitcnt lgkmcnt(0)
	v_cvt_pk_bf16_f32 v4, v4, v5
	ds_read2_b32 v[20:21], v36 offset0:222 offset1:255
	s_waitcnt lgkmcnt(0)
	v_cvt_pk_bf16_f32 v5, v20, v21
	s_branch .LBB0_307

; __device__ __forceinline__ unsigned pk2(float lo, float hi) { unsigned r; asm volatile("v_cvt_pk_bf16_f32 %0, %1, %2" : "=v"(r) : "v"(lo), "v"(hi)); return r; }
; __device__ __forceinline__ void p0_transpose_item(const float* W, int K, int N, bf16* WT, int kb, int src_col0, int dst_row0, float* scr, int lane, const float* kgain = nullptr) {
;     ...
;     for (int j = 0; j < 4; ++j) { const int n = (lane >> 3) + 8 * j; const float* s = scr + (8 * c) * 33 + n;
;         v4u o;
;         if (src_col0 >= 0) { o.x = pk2(s[0 * 33] * g0.x, s[1 * 33] * g0.y); o.y = pk2(s[2 * 33] * g0.z, s[3 * 33] * g0.w); o.z = pk2(s[4 * 33] * g1.x, s[5 * 33] * g1.y); o.w = pk2(s[6 * 33] * g1.z, s[7 * 33] * g1.w); }
;         else { o.x = 0u; o.y = 0u; o.z = 0u; o.w = 0u; }
;         *(v4u*)(WT + (size_t)(dst_row0 + n) * K + k0 + 8 * c) = o; }
.LBB0_331:
	v_add_u32_e32 v2, 24, v18
	v_ashrrev_i32_e32 v3, 31, v2
	v_lshlrev_b64 v[2:3], 13, v[2:3]
	v_lshl_add_u64 v[2:3], v[26:27], 0, v[2:3]
	global_store_dwordx4 v[2:3], v[10:13], off sc1
	s_waitcnt lgkmcnt(0)
	s_add_i32 s0, s10, 0x400
	s_add_i32 s11, s11, 0x8000
	s_cmpk_lt_i32 s10, 0x3c00
	s_mov_b32 s10, s0
	s_cbranch_scc0 .LBB0_343

; __device__ __forceinline__ unsigned pk2(float lo, float hi) { unsigned r; asm volatile("v_cvt_pk_bf16_f32 %0, %1, %2" : "=v"(r) : "v"(lo), "v"(hi)); return r; }
; __device__ __forceinline__ void p0_transpose_item(const float* W, int K, int N, bf16* WT, int kb, int src_col0, int dst_row0, float* scr, int lane, const float* kgain = nullptr) {
;     ...
;     for (int j = 0; j < 4; ++j) { const int n = (lane >> 3) + 8 * j; const float* s = scr + (8 * c) * 33 + n;
;         v4u o;
;         if (src_col0 >= 0) { o.x = pk2(s[0 * 33] * g0.x, s[1 * 33] * g0.y); o.y = pk2(s[2 * 33] * g0.z, s[3 * 33] * g0.w); o.z = pk2(s[4 * 33] * g1.x, s[5 * 33] * g1.y); o.w = pk2(s[6 * 33] * g1.z, s[7 * 33] * g1.w); }
;         else { o.x = 0u; o.y = 0u; o.z = 0u; o.w = 0u; }
;         *(v4u*)(WT + (size_t)(dst_row0 + n) * K + k0 + 8 * c) = o; }
;     __builtin_amdgcn_s_waitcnt(0xC07F); asm volatile("" ::: "memory");
.LBB0_335:
	s_waitcnt lgkmcnt(0)
	v_lshl_add_u64 v[26:27], s[4:5], 1, v[24:25]
	s_mov_b64 s[4:5], -1
	s_and_b64 vcc, exec, s[2:3]
	s_cbranch_vccz .LBB0_337
	s_add_i32 s0, s8, s11
	v_add_u32_e32 v10, s0, v35
	v_ashrrev_i32_e32 v11, 31, v10
	v_lshlrev_b64 v[12:13], 13, v[10:11]
	v_lshl_add_u64 v[12:13], v[26:27], 0, v[12:13]
	global_store_dwordx4 v[12:13], v[38:41], off sc1
	s_mov_b64 s[4:5], 0
	v_mov_b32_e32 v18, v10
.LBB0_337:
	v_mov_b32_e32 v10, 0
	s_andn2_b64 vcc, exec, s[4:5]
	v_mov_b32_e32 v11, 0
	v_mov_b32_e32 v12, 0
	v_mov_b32_e32 v13, 0
	s_cbranch_vccnz .LBB0_339
	ds_read2_b32 v[10:11], v36 offset1:33
	s_add_i32 s8, s8, s11
	s_waitcnt lgkmcnt(0)
	v_mul_f32_e32 v10, v6, v10
	v_mul_f32_e32 v11, v7, v11
	v_cvt_pk_bf16_f32 v10, v10, v11
	ds_read2_b32 v[12:13], v36 offset0:66 offset1:99
	s_waitcnt lgkmcnt(0)
	v_mul_f32_e32 v11, v8, v12
	v_mul_f32_e32 v12, v9, v13
	v_cvt_pk_bf16_f32 v11, v11, v12
	ds_read2_b32 v[12:13], v36 offset0:132 offset1:165
	s_waitcnt lgkmcnt(0)
	v_mul_f32_e32 v12, v2, v12
	v_mul_f32_e32 v13, v3, v13
	v_cvt_pk_bf16_f32 v12, v12, v13
	ds_read2_b32 v[28:29], v36 offset0:198 offset1:231
	s_waitcnt lgkmcnt(0)
	v_mul_f32_e32 v13, v4, v28
	v_mul_f32_e32 v18, v5, v29
	v_cvt_pk_bf16_f32 v13, v13, v18
	ds_read2_b32 v[28:29], v36 offset0:8 offset1:41
	v_add_u32_e32 v18, s8, v35
	v_lshlrev_b64 v[42:43], 13, v[18:19]
	v_lshl_add_u64 v[42:43], v[26:27], 0, v[42:43]
	global_store_dwordx4 v[42:43], v[10:13], off sc1
	s_waitcnt lgkmcnt(0)
	s_nop 0
	v_mul_f32_e32 v10, v6, v28
	v_mul_f32_e32 v11, v7, v29
	v_cvt_pk_bf16_f32 v10, v10, v11
	ds_read2_b32 v[12:13], v36 offset0:74 offset1:107
	s_waitcnt lgkmcnt(0)
	v_mul_f32_e32 v11, v8, v12
	v_mul_f32_e32 v12, v9, v13
	v_cvt_pk_bf16_f32 v11, v11, v12
	ds_read2_b32 v[12:13], v36 offset0:140 offset1:173
	s_waitcnt lgkmcnt(0)
	v_mul_f32_e32 v12, v2, v12
	v_mul_f32_e32 v13, v3, v13
	v_cvt_pk_bf16_f32 v12, v12, v13
	ds_read2_b32 v[28:29], v36 offset0:206 offset1:239
	s_waitcnt lgkmcnt(0)
	v_mul_f32_e32 v13, v4, v28
	v_mul_f32_e32 v28, v5, v29
	v_cvt_pk_bf16_f32 v13, v13, v28
.LBB0_339:
	v_add_u32_e32 v28, 8, v18
	v_ashrrev_i32_e32 v29, 31, v28
	v_lshlrev_b64 v[28:29], 13, v[28:29]
	v_lshl_add_u64 v[28:29], v[26:27], 0, v[28:29]
	global_store_dwordx4 v[28:29], v[10:13], off sc1
	s_mov_b64 s[4:5], -1
	s_and_b64 vcc, exec, s[2:3]
	v_add_u32_e32 v28, 16, v18
	s_cbranch_vccz .LBB0_341
	v_ashrrev_i32_e32 v29, 31, v28
	v_lshlrev_b64 v[10:11], 13, v[28:29]
	v_lshl_add_u64 v[10:11], v[26:27], 0, v[10:11]
	global_store_dwordx4 v[10:11], v[38:41], off sc1
	s_mov_b64 s[4:5], 0
.LBB0_341:
	v_mov_b32_e32 v10, 0
	s_andn2_b64 vcc, exec, s[4:5]
	v_mov_b32_e32 v11, 0
	v_mov_b32_e32 v12, 0
	v_mov_b32_e32 v13, 0
	s_cbranch_vccnz .LBB0_331
	ds_read2_b32 v[10:11], v36 offset0:16 offset1:49
	s_waitcnt lgkmcnt(0)
	v_mul_f32_e32 v10, v6, v10
	v_mul_f32_e32 v11, v7, v11
	v_cvt_pk_bf16_f32 v10, v10, v11
	ds_read2_b32 v[12:13], v36 offset0:82 offset1:115
	s_waitcnt lgkmcnt(0)
	v_mul_f32_e32 v11, v8, v12
	v_mul_f32_e32 v12, v9, v13
	v_cvt_pk_bf16_f32 v11, v11, v12
	ds_read2_b32 v[12:13], v36 offset0:148 offset1:181
	s_waitcnt lgkmcnt(0)
	v_mul_f32_e32 v12, v2, v12
	v_mul_f32_e32 v13, v3, v13
	v_cvt_pk_bf16_f32 v12, v12, v13
	ds_read2_b32 v[42:43], v36 offset0:214 offset1:247
	s_waitcnt lgkmcnt(0)
	v_mul_f32_e32 v13, v4, v42
	v_mul_f32_e32 v29, v5, v43
	v_cvt_pk_bf16_f32 v13, v13, v29
	ds_read2_b32 v[42:43], v36 offset0:24 offset1:57
	v_mov_b32_e32 v29, v19
	v_lshlrev_b64 v[28:29], 13, v[28:29]
	v_lshl_add_u64 v[28:29], v[26:27], 0, v[28:29]
	global_store_dwordx4 v[28:29], v[10:13], off sc1
	s_waitcnt lgkmcnt(0)
	v_mul_f32_e32 v6, v6, v42
	v_mul_f32_e32 v7, v7, v43
	v_cvt_pk_bf16_f32 v10, v6, v7
	ds_read2_b32 v[6:7], v36 offset0:90 offset1:123
	s_waitcnt lgkmcnt(0)
	v_mul_f32_e32 v6, v8, v6
	v_mul_f32_e32 v7, v9, v7
	v_cvt_pk_bf16_f32 v11, v6, v7
	ds_read2_b32 v[6:7], v36 offset0:156 offset1:189
	s_waitcnt lgkmcnt(0)
	v_mul_f32_e32 v2, v2, v6
	v_mul_f32_e32 v3, v3, v7
	v_cvt_pk_bf16_f32 v12, v2, v3
	ds_read2_b32 v[2:3], v36 offset0:222 offset1:255
	s_waitcnt lgkmcnt(0)
	v_mul_f32_e32 v2, v4, v2
	v_mul_f32_e32 v3, v5, v3
	v_cvt_pk_bf16_f32 v13, v2, v3
	s_branch .LBB0_331

; __device__ __forceinline__ unsigned pk2(float lo, float hi) { unsigned r; asm volatile("v_cvt_pk_bf16_f32 %0, %1, %2" : "=v"(r) : "v"(lo), "v"(hi)); return r; }
; __device__ __forceinline__ void p0_transpose_item(const float* W, int K, int N, bf16* WT, int kb, int src_col0, int dst_row0, float* scr, int lane, const float* kgain = nullptr) {
;     ...
;     for (int j = 0; j < 4; ++j) { const int n = (lane >> 3) + 8 * j; const float* s = scr + (8 * c) * 33 + n;
;         v4u o;
;         if (src_col0 >= 0) { o.x = pk2(s[0 * 33] * g0.x, s[1 * 33] * g0.y); o.y = pk2(s[2 * 33] * g0.z, s[3 * 33] * g0.w); o.z = pk2(s[4 * 33] * g1.x, s[5 * 33] * g1.y); o.w = pk2(s[6 * 33] * g1.z, s[7 * 33] * g1.w); }
;         else { o.x = 0u; o.y = 0u; o.z = 0u; o.w = 0u; }
;         *(v4u*)(WT + (size_t)(dst_row0 + n) * K + k0 + 8 * c) = o; }
.LBB0_347:
	v_or_b32_e32 v32, s0, v22
	v_ashrrev_i32_e32 v33, 31, v32
	v_lshlrev_b64 v[32:33], 9, v[32:33]
	v_lshl_add_u64 v[18:19], v[18:19], 0, v[32:33]
	global_store_dwordx4 v[18:19], v[2:5], off sc1
	s_waitcnt lgkmcnt(0)
	s_add_i32 s0, s10, 0x400
	s_add_i32 s12, s12, 0x8000
	s_add_i32 s13, s13, 0x10000
	s_cmpk_lt_i32 s10, 0xfc20
	s_mov_b32 s10, s0
	s_cbranch_scc0 .LBB0_344

; __device__ __forceinline__ unsigned pk2(float lo, float hi) { unsigned r; asm volatile("v_cvt_pk_bf16_f32 %0, %1, %2" : "=v"(r) : "v"(lo), "v"(hi)); return r; }
; __device__ __forceinline__ void p0_transpose_item(const float* W, int K, int N, bf16* WT, int kb, int src_col0, int dst_row0, float* scr, int lane, const float* kgain = nullptr) {
;     ...
;     for (int j = 0; j < 4; ++j) { const int n = (lane >> 3) + 8 * j; const float* s = scr + (8 * c) * 33 + n;
;         v4u o;
;         if (src_col0 >= 0) { o.x = pk2(s[0 * 33] * g0.x, s[1 * 33] * g0.y); o.y = pk2(s[2 * 33] * g0.z, s[3 * 33] * g0.w); o.z = pk2(s[4 * 33] * g1.x, s[5 * 33] * g1.y); o.w = pk2(s[6 * 33] * g1.z, s[7 * 33] * g1.w); }
;         else { o.x = 0u; o.y = 0u; o.z = 0u; o.w = 0u; }
;         *(v4u*)(WT + (size_t)(dst_row0 + n) * K + k0 + 8 * c) = o; }
; __device__ __forceinline__ void p0_prologue(Frame& F, bool split = false) {
;     ...
;         p0_transpose_matrix2(F, FIN(F, 11) + (size_t)kn * 256 * 256, 256, 256, (bf16*)FW(F, WS_MISC + MISC_GATE), 8, [](int nb) { return nb * 32; },
;             [=](int nb) { const int e0 = nb * 32; return (2 * n + (e0 >> 7)) * 256 + (e0 & 127) + 128 * k; }, it0); }
.LBB0_350:
	s_lshl_b32 s5, s5, 9
	s_sub_i32 s5, s13, s5
	s_and_b32 s5, s5, 0xffffff00
	s_and_b32 s0, s0, 0x60
	s_add_i32 s5, s11, s5
	s_waitcnt lgkmcnt(0)
	s_or_b32 s0, s5, s0
	s_ashr_i32 s5, s4, 31
	v_lshl_add_u64 v[18:19], s[4:5], 1, v[10:11]
	s_mov_b64 s[4:5], -1
	s_and_b64 vcc, exec, s[2:3]
	v_or_b32_e32 v6, s0, v35
	s_cbranch_vccz .LBB0_352
	v_ashrrev_i32_e32 v3, 31, v6
	v_mov_b32_e32 v2, v6
	v_lshlrev_b64 v[2:3], 9, v[2:3]
	v_lshl_add_u64 v[2:3], v[18:19], 0, v[2:3]
	global_store_dwordx4 v[2:3], v[28:31], off sc1
	s_mov_b64 s[4:5], 0
.LBB0_352:
	v_mov_b32_e32 v2, 0
	s_andn2_b64 vcc, exec, s[4:5]
	v_mov_b32_e32 v3, 0
	v_mov_b32_e32 v4, 0
	v_mov_b32_e32 v5, 0
	s_cbranch_vccnz .LBB0_354
	ds_read2_b32 v[2:3], v36 offset1:33
	s_waitcnt lgkmcnt(0)
	v_cvt_pk_bf16_f32 v2, v2, v3
	ds_read2_b32 v[4:5], v36 offset0:66 offset1:99
	s_waitcnt lgkmcnt(0)
	v_cvt_pk_bf16_f32 v3, v4, v5
	ds_read2_b32 v[4:5], v36 offset0:132 offset1:165
	v_lshlrev_b64 v[38:39], 9, v[6:7]
	s_waitcnt lgkmcnt(0)
	v_cvt_pk_bf16_f32 v4, v4, v5
	ds_read2_b32 v[32:33], v36 offset0:198 offset1:231
	s_waitcnt lgkmcnt(0)
	v_cvt_pk_bf16_f32 v5, v32, v33
	v_lshl_add_u64 v[38:39], v[18:19], 0, v[38:39]
	ds_read2_b32 v[32:33], v36 offset0:8 offset1:41
	global_store_dwordx4 v[38:39], v[2:5], off sc1
	s_waitcnt lgkmcnt(0)
	s_nop 0
	v_cvt_pk_bf16_f32 v2, v32, v33
	ds_read2_b32 v[4:5], v36 offset0:74 offset1:107
	s_waitcnt lgkmcnt(0)
	v_cvt_pk_bf16_f32 v3, v4, v5
	ds_read2_b32 v[4:5], v36 offset0:140 offset1:173
	s_waitcnt lgkmcnt(0)
	v_cvt_pk_bf16_f32 v4, v4, v5
	ds_read2_b32 v[32:33], v36 offset0:206 offset1:239
	s_waitcnt lgkmcnt(0)
	v_cvt_pk_bf16_f32 v5, v32, v33
.LBB0_354:
	v_or_b32_e32 v32, s0, v20
	v_ashrrev_i32_e32 v33, 31, v32
	v_lshlrev_b64 v[32:33], 9, v[32:33]
	v_lshl_add_u64 v[32:33], v[18:19], 0, v[32:33]
	s_mov_b64 s[4:5], -1
	s_and_b64 vcc, exec, s[2:3]
	v_or_b32_e32 v6, s0, v21
	global_store_dwordx4 v[32:33], v[2:5], off sc1
	s_cbranch_vccz .LBB0_356
	s_nop 0
	v_ashrrev_i32_e32 v3, 31, v6
	v_mov_b32_e32 v2, v6
	v_lshlrev_b64 v[2:3], 9, v[2:3]
	v_lshl_add_u64 v[2:3], v[18:19], 0, v[2:3]
	global_store_dwordx4 v[2:3], v[28:31], off sc1
	s_mov_b64 s[4:5], 0
.LBB0_356:
	s_nop 0
	v_mov_b32_e32 v2, 0
	s_andn2_b64 vcc, exec, s[4:5]
	v_mov_b32_e32 v3, 0
	v_mov_b32_e32 v4, 0
	v_mov_b32_e32 v5, 0
	s_cbranch_vccnz .LBB0_347
	ds_read2_b32 v[2:3], v36 offset0:16 offset1:49
	s_waitcnt lgkmcnt(0)
	v_cvt_pk_bf16_f32 v2, v2, v3
	ds_read2_b32 v[4:5], v36 offset0:82 offset1:115
	s_waitcnt lgkmcnt(0)
	v_cvt_pk_bf16_f32 v3, v4, v5
	ds_read2_b32 v[4:5], v36 offset0:148 offset1:181
	v_lshlrev_b64 v[38:39], 9, v[6:7]
	s_waitcnt lgkmcnt(0)
	v_cvt_pk_bf16_f32 v4, v4, v5
	ds_read2_b32 v[32:33], v36 offset0:214 offset1:247
	s_waitcnt lgkmcnt(0)
	v_cvt_pk_bf16_f32 v5, v32, v33
	v_lshl_add_u64 v[38:39], v[18:19], 0, v[38:39]
	ds_read2_b32 v[32:33], v36 offset0:24 offset1:57
	global_store_dwordx4 v[38:39], v[2:5], off sc1
	s_waitcnt lgkmcnt(0)
	s_nop 0
	v_cvt_pk_bf16_f32 v2, v32, v33
	ds_read2_b32 v[4:5], v36 offset0:90 offset1:123
	s_waitcnt lgkmcnt(0)
	v_cvt_pk_bf16_f32 v3, v4, v5
	ds_read2_b32 v[4:5], v36 offset0:156 offset1:189
	s_waitcnt lgkmcnt(0)
	v_cvt_pk_bf16_f32 v4, v4, v5
	ds_read2_b32 v[32:33], v36 offset0:222 offset1:255
	s_waitcnt lgkmcnt(0)
	v_cvt_pk_bf16_f32 v5, v32, v33
	s_branch .LBB0_347

; __device__ __forceinline__ unsigned pk2(float lo, float hi) { unsigned r; asm volatile("v_cvt_pk_bf16_f32 %0, %1, %2" : "=v"(r) : "v"(lo), "v"(hi)); return r; }
; __device__ __forceinline__ void p0_transpose_item(const float* W, int K, int N, bf16* WT, int kb, int src_col0, int dst_row0, float* scr, int lane, const float* kgain = nullptr) {
;     ...
;     for (int j = 0; j < 4; ++j) { const int n = (lane >> 3) + 8 * j; const float* s = scr + (8 * c) * 33 + n;
;         v4u o;
;         if (src_col0 >= 0) { o.x = pk2(s[0 * 33] * g0.x, s[1 * 33] * g0.y); o.y = pk2(s[2 * 33] * g0.z, s[3 * 33] * g0.w); o.z = pk2(s[4 * 33] * g1.x, s[5 * 33] * g1.y); o.w = pk2(s[6 * 33] * g1.z, s[7 * 33] * g1.w); }
;         else { o.x = 0u; o.y = 0u; o.z = 0u; o.w = 0u; }
;         *(v4u*)(WT + (size_t)(dst_row0 + n) * K + k0 + 8 * c) = o; }
.LBB0_362:
	v_add_u32_e32 v22, 24, v16
	v_ashrrev_i32_e32 v23, 31, v22
	v_lshlrev_b64 v[22:23], 13, v[22:23]
	v_lshl_add_u64 v[20:21], v[20:21], 0, v[22:23]
	global_store_dwordx4 v[20:21], v[2:5], off sc1
	s_waitcnt lgkmcnt(0)
	s_add_i32 s0, s11, 0x400
	s_add_i32 s12, s12, 0x8000
	s_cmpk_lt_i32 s11, 0xfd00
	s_mov_b32 s11, s0
	s_cbranch_scc0 .LBB0_373

; __device__ __forceinline__ unsigned pk2(float lo, float hi) { unsigned r; asm volatile("v_cvt_pk_bf16_f32 %0, %1, %2" : "=v"(r) : "v"(lo), "v"(hi)); return r; }
; __device__ __forceinline__ void p0_transpose_item(const float* W, int K, int N, bf16* WT, int kb, int src_col0, int dst_row0, float* scr, int lane, const float* kgain = nullptr) {
;     ...
;     for (int j = 0; j < 4; ++j) { const int n = (lane >> 3) + 8 * j; const float* s = scr + (8 * c) * 33 + n;
;         v4u o;
;         if (src_col0 >= 0) { o.x = pk2(s[0 * 33] * g0.x, s[1 * 33] * g0.y); o.y = pk2(s[2 * 33] * g0.z, s[3 * 33] * g0.w); o.z = pk2(s[4 * 33] * g1.x, s[5 * 33] * g1.y); o.w = pk2(s[6 * 33] * g1.z, s[7 * 33] * g1.w); }
;         else { o.x = 0u; o.y = 0u; o.z = 0u; o.w = 0u; }
;         *(v4u*)(WT + (size_t)(dst_row0 + n) * K + k0 + 8 * c) = o; }
;     __builtin_amdgcn_s_waitcnt(0xC07F); asm volatile("" ::: "memory");
.LBB0_365:
	s_waitcnt lgkmcnt(0)
	s_ashr_i32 s9, s8, 31
	v_lshl_add_u64 v[20:21], s[8:9], 1, v[18:19]
	s_mov_b64 s[8:9], -1
	s_and_b64 vcc, exec, s[4:5]
	s_cbranch_vccz .LBB0_367
	s_add_i32 s0, s13, s12
	v_add_u32_e32 v2, s0, v35
	v_ashrrev_i32_e32 v3, 31, v2
	v_lshlrev_b64 v[4:5], 13, v[2:3]
	v_lshl_add_u64 v[4:5], v[20:21], 0, v[4:5]
	global_store_dwordx4 v[4:5], v[38:41], off sc1
	s_mov_b64 s[8:9], 0
	v_mov_b32_e32 v16, v2
.LBB0_367:
	v_mov_b32_e32 v2, 0
	s_andn2_b64 vcc, exec, s[8:9]
	v_mov_b32_e32 v3, 0
	v_mov_b32_e32 v4, 0
	v_mov_b32_e32 v5, 0
	s_cbranch_vccnz .LBB0_369
	ds_read2_b32 v[2:3], v36 offset1:33
	s_add_i32 s13, s13, s12
	s_waitcnt lgkmcnt(0)
	v_cvt_pk_bf16_f32 v2, v2, v3
	ds_read2_b32 v[4:5], v36 offset0:66 offset1:99
	v_add_u32_e32 v16, s13, v35
	s_waitcnt lgkmcnt(0)
	v_cvt_pk_bf16_f32 v3, v4, v5
	ds_read2_b32 v[4:5], v36 offset0:132 offset1:165
	v_lshlrev_b64 v[32:33], 13, v[16:17]
	s_waitcnt lgkmcnt(0)
	v_cvt_pk_bf16_f32 v4, v4, v5
	ds_read2_b32 v[22:23], v36 offset0:198 offset1:231
	s_waitcnt lgkmcnt(0)
	v_cvt_pk_bf16_f32 v5, v22, v23
	v_lshl_add_u64 v[32:33], v[20:21], 0, v[32:33]
	ds_read2_b32 v[22:23], v36 offset0:8 offset1:41
	global_store_dwordx4 v[32:33], v[2:5], off sc1
	s_waitcnt lgkmcnt(0)
	s_nop 0
	v_cvt_pk_bf16_f32 v2, v22, v23
	ds_read2_b32 v[4:5], v36 offset0:74 offset1:107
	s_waitcnt lgkmcnt(0)
	v_cvt_pk_bf16_f32 v3, v4, v5
	ds_read2_b32 v[4:5], v36 offset0:140 offset1:173
	s_waitcnt lgkmcnt(0)
	v_cvt_pk_bf16_f32 v4, v4, v5
	ds_read2_b32 v[22:23], v36 offset0:206 offset1:239
	s_waitcnt lgkmcnt(0)
	v_cvt_pk_bf16_f32 v5, v22, v23
.LBB0_369:
	v_add_u32_e32 v22, 8, v16
	v_ashrrev_i32_e32 v23, 31, v22
	v_lshlrev_b64 v[22:23], 13, v[22:23]
	v_lshl_add_u64 v[22:23], v[20:21], 0, v[22:23]
	global_store_dwordx4 v[22:23], v[2:5], off sc1
	s_mov_b64 s[8:9], -1
	s_and_b64 vcc, exec, s[4:5]
	v_add_u32_e32 v22, 16, v16
	s_cbranch_vccz .LBB0_371
	v_ashrrev_i32_e32 v23, 31, v22
	v_lshlrev_b64 v[2:3], 13, v[22:23]
	v_lshl_add_u64 v[2:3], v[20:21], 0, v[2:3]
	global_store_dwordx4 v[2:3], v[38:41], off sc1
	s_mov_b64 s[8:9], 0
.LBB0_371:
	v_mov_b32_e32 v2, 0
	s_andn2_b64 vcc, exec, s[8:9]
	v_mov_b32_e32 v3, 0
	v_mov_b32_e32 v4, 0
	v_mov_b32_e32 v5, 0
	s_cbranch_vccnz .LBB0_362
	ds_read2_b32 v[2:3], v36 offset0:16 offset1:49
	s_waitcnt lgkmcnt(0)
	v_cvt_pk_bf16_f32 v2, v2, v3
	ds_read2_b32 v[4:5], v36 offset0:82 offset1:115
	v_mov_b32_e32 v23, v17
	s_waitcnt lgkmcnt(0)
	v_cvt_pk_bf16_f32 v3, v4, v5
	ds_read2_b32 v[4:5], v36 offset0:148 offset1:181
	v_lshlrev_b64 v[22:23], 13, v[22:23]
	s_waitcnt lgkmcnt(0)
	v_cvt_pk_bf16_f32 v4, v4, v5
	ds_read2_b32 v[32:33], v36 offset0:214 offset1:247
	s_waitcnt lgkmcnt(0)
	v_cvt_pk_bf16_f32 v5, v32, v33
	v_lshl_add_u64 v[22:23], v[20:21], 0, v[22:23]
	ds_read2_b32 v[32:33], v36 offset0:24 offset1:57
	global_store_dwordx4 v[22:23], v[2:5], off sc1
	s_waitcnt lgkmcnt(0)
	s_nop 0
	v_cvt_pk_bf16_f32 v2, v32, v33
	ds_read2_b32 v[4:5], v36 offset0:90 offset1:123
	s_waitcnt lgkmcnt(0)
	v_cvt_pk_bf16_f32 v3, v4, v5
	ds_read2_b32 v[4:5], v36 offset0:156 offset1:189
	s_waitcnt lgkmcnt(0)
	v_cvt_pk_bf16_f32 v4, v4, v5
	ds_read2_b32 v[22:23], v36 offset0:222 offset1:255
	s_waitcnt lgkmcnt(0)
	v_cvt_pk_bf16_f32 v5, v22, v23
	s_branch .LBB0_362

; __device__ __forceinline__ unsigned pk2(float lo, float hi) { unsigned r; asm volatile("v_cvt_pk_bf16_f32 %0, %1, %2" : "=v"(r) : "v"(lo), "v"(hi)); return r; }
; __device__ __forceinline__ void p0_transpose_item(const float* W, int K, int N, bf16* WT, int kb, int src_col0, int dst_row0, float* scr, int lane, const float* kgain = nullptr) {
;     ...
;     for (int j = 0; j < 4; ++j) { const int n = (lane >> 3) + 8 * j; const float* s = scr + (8 * c) * 33 + n;
;         v4u o;
;         if (src_col0 >= 0) { o.x = pk2(s[0 * 33] * g0.x, s[1 * 33] * g0.y); o.y = pk2(s[2 * 33] * g0.z, s[3 * 33] * g0.w); o.z = pk2(s[4 * 33] * g1.x, s[5 * 33] * g1.y); o.w = pk2(s[6 * 33] * g1.z, s[7 * 33] * g1.w); }
;         else { o.x = 0u; o.y = 0u; o.z = 0u; o.w = 0u; }
;         *(v4u*)(WT + (size_t)(dst_row0 + n) * K + k0 + 8 * c) = o; }
.LBB0_375:
	v_add_u32_e32 v22, 24, v16
	v_ashrrev_i32_e32 v23, 31, v22
	v_lshlrev_b64 v[22:23], 8, v[22:23]
	v_lshl_add_u64 v[20:21], v[20:21], 0, v[22:23]
	global_store_dwordx4 v[20:21], v[2:5], off sc1
	s_waitcnt lgkmcnt(0)
	s_add_i32 s0, s11, 0x400
	s_add_i32 s3, s3, 0x8000
	s_cmpk_lt_i32 s11, 0xfc08
	s_mov_b32 s11, s0
	s_cbranch_scc0 .LBB0_359

; __device__ __forceinline__ unsigned pk2(float lo, float hi) { unsigned r; asm volatile("v_cvt_pk_bf16_f32 %0, %1, %2" : "=v"(r) : "v"(lo), "v"(hi)); return r; }
; __device__ __forceinline__ void p0_transpose_item(const float* W, int K, int N, bf16* WT, int kb, int src_col0, int dst_row0, float* scr, int lane, const float* kgain = nullptr) {
;     ...
;     for (int j = 0; j < 4; ++j) { const int n = (lane >> 3) + 8 * j; const float* s = scr + (8 * c) * 33 + n;
;         v4u o;
;         if (src_col0 >= 0) { o.x = pk2(s[0 * 33] * g0.x, s[1 * 33] * g0.y); o.y = pk2(s[2 * 33] * g0.z, s[3 * 33] * g0.w); o.z = pk2(s[4 * 33] * g1.x, s[5 * 33] * g1.y); o.w = pk2(s[6 * 33] * g1.z, s[7 * 33] * g1.w); }
;         else { o.x = 0u; o.y = 0u; o.z = 0u; o.w = 0u; }
;         *(v4u*)(WT + (size_t)(dst_row0 + n) * K + k0 + 8 * c) = o; }
;     __builtin_amdgcn_s_waitcnt(0xC07F); asm volatile("" ::: "memory");
.LBB0_378:
	s_waitcnt lgkmcnt(0)
	s_ashr_i32 s9, s8, 31
	v_lshl_add_u64 v[20:21], s[8:9], 1, v[18:19]
	s_mov_b64 s[8:9], -1
	s_and_b64 vcc, exec, s[4:5]
	s_cbranch_vccz .LBB0_380
	s_add_i32 s0, s12, s3
	v_add_u32_e32 v2, s0, v35
	v_ashrrev_i32_e32 v3, 31, v2
	v_lshlrev_b64 v[4:5], 8, v[2:3]
	v_lshl_add_u64 v[4:5], v[20:21], 0, v[4:5]
	global_store_dwordx4 v[4:5], v[38:41], off sc1
	s_mov_b64 s[8:9], 0
	v_mov_b32_e32 v16, v2
.LBB0_380:
	v_mov_b32_e32 v2, 0
	s_andn2_b64 vcc, exec, s[8:9]
	v_mov_b32_e32 v3, 0
	v_mov_b32_e32 v4, 0
	v_mov_b32_e32 v5, 0
	s_cbranch_vccnz .LBB0_382
	ds_read2_b32 v[2:3], v36 offset1:33
	s_add_i32 s12, s12, s3
	s_waitcnt lgkmcnt(0)
	v_cvt_pk_bf16_f32 v2, v2, v3
	ds_read2_b32 v[4:5], v36 offset0:66 offset1:99
	v_add_u32_e32 v16, s12, v35
	s_waitcnt lgkmcnt(0)
	v_cvt_pk_bf16_f32 v3, v4, v5
	ds_read2_b32 v[4:5], v36 offset0:132 offset1:165
	v_lshlrev_b64 v[32:33], 8, v[16:17]
	s_waitcnt lgkmcnt(0)
	v_cvt_pk_bf16_f32 v4, v4, v5
	ds_read2_b32 v[22:23], v36 offset0:198 offset1:231
	s_waitcnt lgkmcnt(0)
	v_cvt_pk_bf16_f32 v5, v22, v23
	v_lshl_add_u64 v[32:33], v[20:21], 0, v[32:33]
	ds_read2_b32 v[22:23], v36 offset0:8 offset1:41
	global_store_dwordx4 v[32:33], v[2:5], off sc1
	s_waitcnt lgkmcnt(0)
	s_nop 0
	v_cvt_pk_bf16_f32 v2, v22, v23
	ds_read2_b32 v[4:5], v36 offset0:74 offset1:107
	s_waitcnt lgkmcnt(0)
	v_cvt_pk_bf16_f32 v3, v4, v5
	ds_read2_b32 v[4:5], v36 offset0:140 offset1:173
	s_waitcnt lgkmcnt(0)
	v_cvt_pk_bf16_f32 v4, v4, v5
	ds_read2_b32 v[22:23], v36 offset0:206 offset1:239
	s_waitcnt lgkmcnt(0)
	v_cvt_pk_bf16_f32 v5, v22, v23
.LBB0_382:
	v_add_u32_e32 v22, 8, v16
	v_ashrrev_i32_e32 v23, 31, v22
	v_lshlrev_b64 v[22:23], 8, v[22:23]
	v_lshl_add_u64 v[22:23], v[20:21], 0, v[22:23]
	global_store_dwordx4 v[22:23], v[2:5], off sc1
	s_mov_b64 s[8:9], -1
	s_and_b64 vcc, exec, s[4:5]
	v_add_u32_e32 v22, 16, v16
	s_cbranch_vccz .LBB0_384
	v_ashrrev_i32_e32 v23, 31, v22
	v_lshlrev_b64 v[2:3], 8, v[22:23]
	v_lshl_add_u64 v[2:3], v[20:21], 0, v[2:3]
	global_store_dwordx4 v[2:3], v[38:41], off sc1
	s_mov_b64 s[8:9], 0
.LBB0_384:
	v_mov_b32_e32 v2, 0
	s_andn2_b64 vcc, exec, s[8:9]
	v_mov_b32_e32 v3, 0
	v_mov_b32_e32 v4, 0
	v_mov_b32_e32 v5, 0
	s_cbranch_vccnz .LBB0_375
	ds_read2_b32 v[2:3], v36 offset0:16 offset1:49
	s_waitcnt lgkmcnt(0)
	v_cvt_pk_bf16_f32 v2, v2, v3
	ds_read2_b32 v[4:5], v36 offset0:82 offset1:115
	v_mov_b32_e32 v23, v17
	s_waitcnt lgkmcnt(0)
	v_cvt_pk_bf16_f32 v3, v4, v5
	ds_read2_b32 v[4:5], v36 offset0:148 offset1:181
	v_lshlrev_b64 v[22:23], 8, v[22:23]
	s_waitcnt lgkmcnt(0)
	v_cvt_pk_bf16_f32 v4, v4, v5
	ds_read2_b32 v[32:33], v36 offset0:214 offset1:247
	s_waitcnt lgkmcnt(0)
	v_cvt_pk_bf16_f32 v5, v32, v33
	v_lshl_add_u64 v[22:23], v[20:21], 0, v[22:23]
	ds_read2_b32 v[32:33], v36 offset0:24 offset1:57
	global_store_dwordx4 v[22:23], v[2:5], off sc1
	s_waitcnt lgkmcnt(0)
	s_nop 0
	v_cvt_pk_bf16_f32 v2, v32, v33
	ds_read2_b32 v[4:5], v36 offset0:90 offset1:123
	s_waitcnt lgkmcnt(0)
	v_cvt_pk_bf16_f32 v3, v4, v5
	ds_read2_b32 v[4:5], v36 offset0:156 offset1:189
	s_waitcnt lgkmcnt(0)
	v_cvt_pk_bf16_f32 v4, v4, v5
	ds_read2_b32 v[22:23], v36 offset0:222 offset1:255
	s_waitcnt lgkmcnt(0)
	v_cvt_pk_bf16_f32 v5, v22, v23
	s_branch .LBB0_375

; __device__ __forceinline__ unsigned cvt_pk_bf16(float lo, float hi) { unsigned r; asm volatile("v_cvt_pk_bf16_f32 %0, %1, %2" : "=v"(r) : "v"(lo), "v"(hi)); return r; }
;     __device__ __forceinline__ void operator()(const f32x4 (&acc)[2][2][4][2], const Unit& u, int wr, int wc, int fr, int fq) const {
;         const int row0 = u.pm * BM + wr * 64 + fr, col0 = u.pn * BM + wc * 32 + 8 * fq;
;         float scv[2][4];
; #pragma unroll
;         for (int ai = 0; ai < 2; ++ai)
; #pragma unroll
;             for (int m = 0; m < 4; ++m) scv[ai][m] = rs[row0 + ai * HALF + m * 16];
; #pragma unroll
;         for (int ai = 0; ai < 2; ++ai)
; #pragma unroll
;             for (int m = 0; m < 4; ++m) { const int row = row0 + ai * HALF + m * 16; const float sc = scv[ai][m]; bf16_t* rowp = O + (size_t)row * ldc + col0;
; #pragma unroll
;                 for (int bj = 0; bj < 2; ++bj) { const f32x4 v0 = acc[ai][bj][m][0] * sc, v1 = acc[ai][bj][m][1] * sc;
;                     u32x4 w; w.x = cvt_pk_bf16(v0[0], v0[1]); w.y = cvt_pk_bf16(v0[2], v0[3]); w.z = cvt_pk_bf16(v1[0], v1[1]); w.w = cvt_pk_bf16(v1[2], v1[3]);
;                     *(u32x4*)(rowp + bj * HALF) = w; } }
.LBB0_446:
	v_lshl_add_u32 v148, s24, 8, v1
	v_or_b32_e32 v162, 16, v148
	v_ashrrev_i32_e32 v149, 31, v148
	v_ashrrev_i32_e32 v163, 31, v162
	v_or_b32_e32 v166, 32, v148
	v_lshl_add_u64 v[158:159], v[148:149], 2, s[10:11]
	v_lshl_add_u64 v[146:147], v[162:163], 2, s[10:11]
	v_ashrrev_i32_e32 v167, 31, v166
	global_load_dword v160, v[158:159], off
	global_load_dword v164, v[146:147], off
	v_lshl_add_u64 v[146:147], v[166:167], 2, s[10:11]
	global_load_dword v168, v[146:147], off
	v_or_b32_e32 v170, 48, v148
	v_ashrrev_i32_e32 v171, 31, v170
	v_lshl_add_u64 v[146:147], v[170:171], 2, s[10:11]
	global_load_dword v154, v[146:147], off
	v_lshl_or_b32 v174, s48, 8, v153
	v_mov_b64_e32 v[146:147], s[8:9]
	v_ashrrev_i32_e32 v175, 31, v174
	v_add_u32_e32 v165, 0x80, v148
	v_add_u32_e32 v169, 0x90, v148
	v_add_u32_e32 v171, 0xa0, v148
	v_add_u32_e32 v178, 0xb0, v148
	v_mad_i64_i32 v[176:177], s[26:27], v148, s47, v[146:147]
	v_lshlrev_b64 v[148:149], 1, v[174:175]
	v_lshl_add_u64 v[174:175], v[176:177], 0, v[148:149]
	global_load_dword v172, v[158:159], off offset:512
	global_load_dword v176, v[158:159], off offset:576
	global_load_dword v152, v[158:159], off offset:640
	global_load_dword v150, v[158:159], off offset:704
	v_mad_i64_i32 v[162:163], s[26:27], v162, s47, v[146:147]
	v_lshl_add_u64 v[162:163], v[162:163], 0, v[148:149]
	v_mad_i64_i32 v[166:167], s[26:27], v166, s47, v[146:147]
	v_lshl_add_u64 v[166:167], v[166:167], 0, v[148:149]
	s_andn2_b64 vcc, exec, s[2:3]
	s_mov_b64 s[2:3], -1
	s_waitcnt vmcnt(0)
	v_pk_mul_f32 v[124:125], v[124:125], v[160:161] op_sel_hi:[1,0]
	v_pk_mul_f32 v[128:129], v[128:129], v[160:161] op_sel_hi:[1,0]
	v_pk_mul_f32 v[126:127], v[126:127], v[160:161] op_sel_hi:[1,0]
	v_pk_mul_f32 v[122:123], v[122:123], v[160:161] op_sel_hi:[1,0]
	v_pk_mul_f32 v[112:113], v[112:113], v[160:161] op_sel_hi:[1,0]
	v_pk_mul_f32 v[110:111], v[110:111], v[160:161] op_sel_hi:[1,0]
	v_pk_mul_f32 v[158:159], v[104:105], v[160:161] op_sel_hi:[1,0]
	v_pk_mul_f32 v[160:161], v[102:103], v[160:161] op_sel_hi:[1,0]
	v_cvt_pk_bf16_f32 v102, v126, v127
	v_cvt_pk_bf16_f32 v103, v128, v129
	v_cvt_pk_bf16_f32 v104, v122, v123
	v_cvt_pk_bf16_f32 v105, v124, v125
	v_pk_mul_f32 v[124:125], v[82:83], v[168:169] op_sel_hi:[1,0]
	global_store_dwordx4 v[174:175], v[102:105], off sc1
	v_cvt_pk_bf16_f32 v82, v110, v111
	v_cvt_pk_bf16_f32 v83, v112, v113
	v_pk_mul_f32 v[120:121], v[120:121], v[164:165] op_sel_hi:[1,0]
	v_pk_mul_f32 v[118:119], v[118:119], v[164:165] op_sel_hi:[1,0]
	v_pk_mul_f32 v[122:123], v[84:85], v[168:169] op_sel_hi:[1,0]
	v_cvt_pk_bf16_f32 v84, v160, v161
	v_cvt_pk_bf16_f32 v85, v158, v159
	global_store_dwordx4 v[174:175], v[82:85], off offset:256 sc1
	v_pk_mul_f32 v[116:117], v[116:117], v[164:165] op_sel_hi:[1,0]
	v_pk_mul_f32 v[114:115], v[114:115], v[164:165] op_sel_hi:[1,0]
	v_cvt_pk_bf16_f32 v82, v118, v119
	v_cvt_pk_bf16_f32 v83, v120, v121
	v_pk_mul_f32 v[96:97], v[96:97], v[164:165] op_sel_hi:[1,0]
	v_pk_mul_f32 v[94:95], v[94:95], v[164:165] op_sel_hi:[1,0]
	v_cvt_pk_bf16_f32 v84, v114, v115
	v_cvt_pk_bf16_f32 v85, v116, v117
	global_store_dwordx4 v[162:163], v[82:85], off sc1
	v_pk_mul_f32 v[92:93], v[92:93], v[164:165] op_sel_hi:[1,0]
	v_pk_mul_f32 v[90:91], v[90:91], v[164:165] op_sel_hi:[1,0]
	v_cvt_pk_bf16_f32 v82, v94, v95
	v_cvt_pk_bf16_f32 v83, v96, v97
	v_pk_mul_f32 v[108:109], v[108:109], v[168:169] op_sel_hi:[1,0]
	v_pk_mul_f32 v[106:107], v[106:107], v[168:169] op_sel_hi:[1,0]
	v_cvt_pk_bf16_f32 v84, v90, v91
	v_cvt_pk_bf16_f32 v85, v92, v93
	global_store_dwordx4 v[162:163], v[82:85], off offset:256 sc1
	v_pk_mul_f32 v[100:101], v[100:101], v[168:169] op_sel_hi:[1,0]
	v_pk_mul_f32 v[98:99], v[98:99], v[168:169] op_sel_hi:[1,0]
	v_cvt_pk_bf16_f32 v82, v106, v107
	v_cvt_pk_bf16_f32 v83, v108, v109
	v_pk_mul_f32 v[88:89], v[88:89], v[168:169] op_sel_hi:[1,0]
	v_pk_mul_f32 v[86:87], v[86:87], v[168:169] op_sel_hi:[1,0]
	v_cvt_pk_bf16_f32 v84, v98, v99
	v_cvt_pk_bf16_f32 v85, v100, v101
	global_store_dwordx4 v[166:167], v[82:85], off sc1
	v_pk_mul_f32 v[80:81], v[80:81], v[154:155] op_sel_hi:[1,0]
	v_pk_mul_f32 v[78:79], v[78:79], v[154:155] op_sel_hi:[1,0]
	v_cvt_pk_bf16_f32 v82, v86, v87
	v_cvt_pk_bf16_f32 v83, v88, v89
	v_cvt_pk_bf16_f32 v84, v124, v125
	v_cvt_pk_bf16_f32 v85, v122, v123
	global_store_dwordx4 v[166:167], v[82:85], off offset:256 sc1
	v_pk_mul_f32 v[72:73], v[72:73], v[154:155] op_sel_hi:[1,0]
	v_pk_mul_f32 v[70:71], v[70:71], v[154:155] op_sel_hi:[1,0]
	v_mad_i64_i32 v[82:83], s[26:27], v170, s47, v[146:147]
	v_lshl_add_u64 v[82:83], v[82:83], 0, v[148:149]
	v_pk_mul_f32 v[84:85], v[76:77], v[154:155] op_sel_hi:[1,0]
; __device__ __forceinline__ unsigned cvt_pk_bf16(float lo, float hi) { unsigned r; asm volatile("v_cvt_pk_bf16_f32 %0, %1, %2" : "=v"(r) : "v"(lo), "v"(hi)); return r; }
;     __device__ __forceinline__ void operator()(const f32x4 (&acc)[2][2][4][2], const Unit& u, int wr, int wc, int fr, int fq) const {
;     ...
; #pragma unroll
;         for (int ai = 0; ai < 2; ++ai)
; #pragma unroll
;             for (int m = 0; m < 4; ++m) { const int row = row0 + ai * HALF + m * 16; const float sc = scv[ai][m]; bf16_t* rowp = O + (size_t)row * ldc + col0;
; #pragma unroll
;                 for (int bj = 0; bj < 2; ++bj) { const f32x4 v0 = acc[ai][bj][m][0] * sc, v1 = acc[ai][bj][m][1] * sc;
;                     u32x4 w; w.x = cvt_pk_bf16(v0[0], v0[1]); w.y = cvt_pk_bf16(v0[2], v0[3]); w.z = cvt_pk_bf16(v1[0], v1[1]); w.w = cvt_pk_bf16(v1[2], v1[3]);
;                     *(u32x4*)(rowp + bj * HALF) = w; } }
	v_pk_mul_f32 v[76:77], v[74:75], v[154:155] op_sel_hi:[1,0]
	v_cvt_pk_bf16_f32 v74, v78, v79
	v_cvt_pk_bf16_f32 v75, v80, v81
	v_pk_mul_f32 v[64:65], v[64:65], v[172:173] op_sel_hi:[1,0]
	v_cvt_pk_bf16_f32 v76, v76, v77
	v_cvt_pk_bf16_f32 v77, v84, v85
	global_store_dwordx4 v[82:83], v[74:77], off sc1
	v_pk_mul_f32 v[62:63], v[62:63], v[172:173] op_sel_hi:[1,0]
	v_pk_mul_f32 v[56:57], v[56:57], v[172:173] op_sel_hi:[1,0]
	v_pk_mul_f32 v[74:75], v[68:69], v[154:155] op_sel_hi:[1,0]
	v_pk_mul_f32 v[68:69], v[66:67], v[154:155] op_sel_hi:[1,0]
	v_cvt_pk_bf16_f32 v66, v70, v71
	v_cvt_pk_bf16_f32 v67, v72, v73
	v_pk_mul_f32 v[54:55], v[54:55], v[172:173] op_sel_hi:[1,0]
	v_cvt_pk_bf16_f32 v68, v68, v69
	v_cvt_pk_bf16_f32 v69, v74, v75
	global_store_dwordx4 v[82:83], v[66:69], off offset:256 sc1
	v_pk_mul_f32 v[50:51], v[50:51], v[176:177] op_sel_hi:[1,0]
	v_pk_mul_f32 v[40:41], v[40:41], v[176:177] op_sel_hi:[1,0]
	v_mad_i64_i32 v[66:67], s[26:27], v165, s47, v[146:147]
	v_lshl_add_u64 v[66:67], v[66:67], 0, v[148:149]
	v_pk_mul_f32 v[68:69], v[60:61], v[172:173] op_sel_hi:[1,0]
	v_pk_mul_f32 v[60:61], v[58:59], v[172:173] op_sel_hi:[1,0]
	v_cvt_pk_bf16_f32 v58, v62, v63
	v_cvt_pk_bf16_f32 v59, v64, v65
	v_pk_mul_f32 v[38:39], v[38:39], v[176:177] op_sel_hi:[1,0]
	v_cvt_pk_bf16_f32 v60, v60, v61
	v_cvt_pk_bf16_f32 v61, v68, v69
	global_store_dwordx4 v[66:67], v[58:61], off sc1
	v_pk_mul_f32 v[34:35], v[34:35], v[152:153] op_sel_hi:[1,0]
	v_pk_mul_f32 v[24:25], v[24:25], v[152:153] op_sel_hi:[1,0]
	v_pk_mul_f32 v[58:59], v[48:49], v[172:173] op_sel_hi:[1,0]
	v_pk_mul_f32 v[48:49], v[46:47], v[172:173] op_sel_hi:[1,0]
	v_cvt_pk_bf16_f32 v46, v54, v55
	v_cvt_pk_bf16_f32 v47, v56, v57
	v_pk_mul_f32 v[22:23], v[22:23], v[152:153] op_sel_hi:[1,0]
	v_cvt_pk_bf16_f32 v48, v48, v49
	v_cvt_pk_bf16_f32 v49, v58, v59
	global_store_dwordx4 v[66:67], v[46:49], off offset:256 sc1
	v_pk_mul_f32 v[18:19], v[18:19], v[150:151] op_sel_hi:[1,0]
	v_pk_mul_f32 v[8:9], v[8:9], v[150:151] op_sel_hi:[1,0]
	v_mad_i64_i32 v[46:47], s[26:27], v169, s47, v[146:147]
	v_lshl_add_u64 v[46:47], v[46:47], 0, v[148:149]
	v_pk_mul_f32 v[48:49], v[52:53], v[176:177] op_sel_hi:[1,0]
	v_pk_mul_f32 v[52:53], v[44:45], v[176:177] op_sel_hi:[1,0]
	v_pk_mul_f32 v[44:45], v[42:43], v[176:177] op_sel_hi:[1,0]
	v_cvt_pk_bf16_f32 v42, v50, v51
	v_cvt_pk_bf16_f32 v43, v48, v49
	v_pk_mul_f32 v[6:7], v[6:7], v[150:151] op_sel_hi:[1,0]
	v_cvt_pk_bf16_f32 v44, v44, v45
	v_cvt_pk_bf16_f32 v45, v52, v53
	global_store_dwordx4 v[46:47], v[42:45], off sc1
	s_nop 1
	v_pk_mul_f32 v[42:43], v[32:33], v[176:177] op_sel_hi:[1,0]
	v_pk_mul_f32 v[32:33], v[30:31], v[176:177] op_sel_hi:[1,0]
	v_cvt_pk_bf16_f32 v30, v38, v39
	v_cvt_pk_bf16_f32 v31, v40, v41
	s_nop 0
	v_cvt_pk_bf16_f32 v32, v32, v33
	v_cvt_pk_bf16_f32 v33, v42, v43
	global_store_dwordx4 v[46:47], v[30:33], off offset:256 sc1
	s_nop 1
	v_mad_i64_i32 v[30:31], s[26:27], v171, s47, v[146:147]
	v_lshl_add_u64 v[30:31], v[30:31], 0, v[148:149]
	v_pk_mul_f32 v[32:33], v[36:37], v[152:153] op_sel_hi:[1,0]
	v_pk_mul_f32 v[36:37], v[28:29], v[152:153] op_sel_hi:[1,0]
	v_pk_mul_f32 v[28:29], v[26:27], v[152:153] op_sel_hi:[1,0]
	v_cvt_pk_bf16_f32 v26, v34, v35
	v_cvt_pk_bf16_f32 v27, v32, v33
	s_nop 0
	v_cvt_pk_bf16_f32 v28, v28, v29
	v_cvt_pk_bf16_f32 v29, v36, v37
	global_store_dwordx4 v[30:31], v[26:29], off sc1
	s_nop 1
	v_pk_mul_f32 v[26:27], v[16:17], v[152:153] op_sel_hi:[1,0]
	v_pk_mul_f32 v[16:17], v[14:15], v[152:153] op_sel_hi:[1,0]
	v_cvt_pk_bf16_f32 v14, v22, v23
	v_cvt_pk_bf16_f32 v15, v24, v25
	s_nop 0
	v_cvt_pk_bf16_f32 v16, v16, v17
	v_cvt_pk_bf16_f32 v17, v26, v27
	global_store_dwordx4 v[30:31], v[14:17], off offset:256 sc1
	s_nop 1
	v_mad_i64_i32 v[14:15], s[26:27], v178, s47, v[146:147]
	v_lshl_add_u64 v[14:15], v[14:15], 0, v[148:149]
	v_pk_mul_f32 v[16:17], v[20:21], v[150:151] op_sel_hi:[1,0]
	v_pk_mul_f32 v[20:21], v[12:13], v[150:151] op_sel_hi:[1,0]
	v_pk_mul_f32 v[12:13], v[10:11], v[150:151] op_sel_hi:[1,0]
	v_cvt_pk_bf16_f32 v10, v18, v19
	v_cvt_pk_bf16_f32 v11, v16, v17
	s_nop 0
	v_cvt_pk_bf16_f32 v12, v12, v13
	v_cvt_pk_bf16_f32 v13, v20, v21
	global_store_dwordx4 v[14:15], v[10:13], off sc1
	s_nop 1
	v_pk_mul_f32 v[10:11], v[4:5], v[150:151] op_sel_hi:[1,0]
	v_pk_mul_f32 v[4:5], v[2:3], v[150:151] op_sel_hi:[1,0]
	v_cvt_pk_bf16_f32 v2, v6, v7
	v_cvt_pk_bf16_f32 v3, v8, v9
	s_nop 0
	v_cvt_pk_bf16_f32 v4, v4, v5
	v_cvt_pk_bf16_f32 v5, v10, v11
	global_store_dwordx4 v[14:15], v[2:5], off offset:256 sc1
	s_cbranch_vccnz .LBB0_439
	s_andn2_b64 vcc, exec, s[4:5]
	s_cbranch_vccnz .LBB0_438
	s_barrier
	s_branch .LBB0_438

; __device__ __forceinline__ unsigned pk2(float lo, float hi) { unsigned r; asm volatile("v_cvt_pk_bf16_f32 %0, %1, %2" : "=v"(r) : "v"(lo), "v"(hi)); return r; }
; __device__ __forceinline__ void p0_transpose_item(const float* W, int K, int N, bf16* WT, int kb, int src_col0, int dst_row0, float* scr, int lane, const float* kgain = nullptr) {
;     ...
;     for (int j = 0; j < 4; ++j) { const int n = (lane >> 3) + 8 * j; const float* s = scr + (8 * c) * 33 + n;
;         v4u o;
;         if (src_col0 >= 0) { o.x = pk2(s[0 * 33] * g0.x, s[1 * 33] * g0.y); o.y = pk2(s[2 * 33] * g0.z, s[3 * 33] * g0.w); o.z = pk2(s[4 * 33] * g1.x, s[5 * 33] * g1.y); o.w = pk2(s[6 * 33] * g1.z, s[7 * 33] * g1.w); }
;         else { o.x = 0u; o.y = 0u; o.z = 0u; o.w = 0u; }
;         *(v4u*)(WT + (size_t)(dst_row0 + n) * K + k0 + 8 * c) = o; }
.LBB0_452:
	v_add_u32_e32 v2, 24, v14
	v_ashrrev_i32_e32 v3, 31, v2
	v_lshlrev_b64 v[2:3], 13, v[2:3]
	v_lshl_add_u64 v[2:3], v[22:23], 0, v[2:3]
	global_store_dwordx4 v[2:3], v[10:13], off sc1
	s_waitcnt lgkmcnt(0)
	s_add_i32 s0, s8, 0x300
	s_addk_i32 s9, 0x6000
	s_cmpk_lt_i32 s8, 0x3d00
	s_mov_b32 s8, s0
	s_cbranch_scc0 .LBB0_464

; __device__ __forceinline__ unsigned pk2(float lo, float hi) { unsigned r; asm volatile("v_cvt_pk_bf16_f32 %0, %1, %2" : "=v"(r) : "v"(lo), "v"(hi)); return r; }
; __device__ __forceinline__ void p0_transpose_item(const float* W, int K, int N, bf16* WT, int kb, int src_col0, int dst_row0, float* scr, int lane, const float* kgain = nullptr) {
;     ...
;     for (int j = 0; j < 4; ++j) { const int n = (lane >> 3) + 8 * j; const float* s = scr + (8 * c) * 33 + n;
;         v4u o;
;         if (src_col0 >= 0) { o.x = pk2(s[0 * 33] * g0.x, s[1 * 33] * g0.y); o.y = pk2(s[2 * 33] * g0.z, s[3 * 33] * g0.w); o.z = pk2(s[4 * 33] * g1.x, s[5 * 33] * g1.y); o.w = pk2(s[6 * 33] * g1.z, s[7 * 33] * g1.w); }
;         else { o.x = 0u; o.y = 0u; o.z = 0u; o.w = 0u; }
;         *(v4u*)(WT + (size_t)(dst_row0 + n) * K + k0 + 8 * c) = o; }
;     __builtin_amdgcn_s_waitcnt(0xC07F); asm volatile("" ::: "memory");
.LBB0_456:
	s_waitcnt lgkmcnt(0)
	v_lshl_add_u64 v[22:23], s[4:5], 1, v[20:21]
	s_mov_b64 s[4:5], -1
	s_and_b64 vcc, exec, s[2:3]
	s_cbranch_vccz .LBB0_458
	s_add_i32 s0, s10, s9
	v_add_u32_e32 v10, s0, v27
	v_ashrrev_i32_e32 v11, 31, v10
	v_lshlrev_b64 v[12:13], 13, v[10:11]
	v_lshl_add_u64 v[12:13], v[22:23], 0, v[12:13]
	global_store_dwordx4 v[12:13], v[36:39], off sc1
	s_mov_b64 s[4:5], 0
	v_mov_b32_e32 v14, v10
.LBB0_458:
	v_mov_b32_e32 v10, 0
	s_andn2_b64 vcc, exec, s[4:5]
	v_mov_b32_e32 v11, 0
	v_mov_b32_e32 v12, 0
	v_mov_b32_e32 v13, 0
	s_cbranch_vccnz .LBB0_460
	ds_read2_b32 v[10:11], v28 offset1:33
	s_add_i32 s10, s10, s9
	s_waitcnt lgkmcnt(0)
	v_mul_f32_e32 v10, v6, v10
	v_mul_f32_e32 v11, v7, v11
	v_cvt_pk_bf16_f32 v10, v10, v11
	ds_read2_b32 v[12:13], v28 offset0:66 offset1:99
	s_waitcnt lgkmcnt(0)
	v_mul_f32_e32 v11, v8, v12
	v_mul_f32_e32 v12, v9, v13
	v_cvt_pk_bf16_f32 v11, v11, v12
	ds_read2_b32 v[12:13], v28 offset0:132 offset1:165
	s_waitcnt lgkmcnt(0)
	v_mul_f32_e32 v12, v2, v12
	v_mul_f32_e32 v13, v3, v13
	v_cvt_pk_bf16_f32 v12, v12, v13
	ds_read2_b32 v[24:25], v28 offset0:198 offset1:231
	s_waitcnt lgkmcnt(0)
	v_mul_f32_e32 v13, v4, v24
	v_mul_f32_e32 v14, v5, v25
	v_cvt_pk_bf16_f32 v13, v13, v14
	ds_read2_b32 v[24:25], v28 offset0:8 offset1:41
	v_add_u32_e32 v14, s10, v27
	v_lshlrev_b64 v[40:41], 13, v[14:15]
	v_lshl_add_u64 v[40:41], v[22:23], 0, v[40:41]
	global_store_dwordx4 v[40:41], v[10:13], off sc1
	s_waitcnt lgkmcnt(0)
	s_nop 0
	v_mul_f32_e32 v10, v6, v24
	v_mul_f32_e32 v11, v7, v25
	v_cvt_pk_bf16_f32 v10, v10, v11
	ds_read2_b32 v[12:13], v28 offset0:74 offset1:107
	s_waitcnt lgkmcnt(0)
	v_mul_f32_e32 v11, v8, v12
	v_mul_f32_e32 v12, v9, v13
	v_cvt_pk_bf16_f32 v11, v11, v12
	ds_read2_b32 v[12:13], v28 offset0:140 offset1:173
	s_waitcnt lgkmcnt(0)
	v_mul_f32_e32 v12, v2, v12
	v_mul_f32_e32 v13, v3, v13
	v_cvt_pk_bf16_f32 v12, v12, v13
	ds_read2_b32 v[24:25], v28 offset0:206 offset1:239
	s_waitcnt lgkmcnt(0)
	v_mul_f32_e32 v13, v4, v24
	v_mul_f32_e32 v24, v5, v25
	v_cvt_pk_bf16_f32 v13, v13, v24
.LBB0_460:
	v_add_u32_e32 v24, 8, v14
	v_ashrrev_i32_e32 v25, 31, v24
	v_lshlrev_b64 v[24:25], 13, v[24:25]
	v_lshl_add_u64 v[24:25], v[22:23], 0, v[24:25]
	global_store_dwordx4 v[24:25], v[10:13], off sc1
	s_mov_b64 s[4:5], -1
	s_and_b64 vcc, exec, s[2:3]
	v_add_u32_e32 v24, 16, v14
	s_cbranch_vccz .LBB0_462
	v_ashrrev_i32_e32 v25, 31, v24
	v_lshlrev_b64 v[10:11], 13, v[24:25]
	v_lshl_add_u64 v[10:11], v[22:23], 0, v[10:11]
	global_store_dwordx4 v[10:11], v[36:39], off sc1
	s_mov_b64 s[4:5], 0
.LBB0_462:
	v_mov_b32_e32 v10, 0
	s_andn2_b64 vcc, exec, s[4:5]
	v_mov_b32_e32 v11, 0
	v_mov_b32_e32 v12, 0
	v_mov_b32_e32 v13, 0
	s_cbranch_vccnz .LBB0_452
	ds_read2_b32 v[10:11], v28 offset0:16 offset1:49
	s_waitcnt lgkmcnt(0)
	v_mul_f32_e32 v10, v6, v10
	v_mul_f32_e32 v11, v7, v11
	v_cvt_pk_bf16_f32 v10, v10, v11
	ds_read2_b32 v[12:13], v28 offset0:82 offset1:115
	s_waitcnt lgkmcnt(0)
	v_mul_f32_e32 v11, v8, v12
	v_mul_f32_e32 v12, v9, v13
	v_cvt_pk_bf16_f32 v11, v11, v12
	ds_read2_b32 v[12:13], v28 offset0:148 offset1:181
	s_waitcnt lgkmcnt(0)
	v_mul_f32_e32 v12, v2, v12
	v_mul_f32_e32 v13, v3, v13
	v_cvt_pk_bf16_f32 v12, v12, v13
	ds_read2_b32 v[40:41], v28 offset0:214 offset1:247
	s_waitcnt lgkmcnt(0)
	v_mul_f32_e32 v13, v4, v40
	v_mul_f32_e32 v25, v5, v41
	v_cvt_pk_bf16_f32 v13, v13, v25
	ds_read2_b32 v[40:41], v28 offset0:24 offset1:57
	v_mov_b32_e32 v25, v15
	v_lshlrev_b64 v[24:25], 13, v[24:25]
	v_lshl_add_u64 v[24:25], v[22:23], 0, v[24:25]
	global_store_dwordx4 v[24:25], v[10:13], off sc1
	s_waitcnt lgkmcnt(0)
	v_mul_f32_e32 v6, v6, v40
	v_mul_f32_e32 v7, v7, v41
	v_cvt_pk_bf16_f32 v10, v6, v7
	ds_read2_b32 v[6:7], v28 offset0:90 offset1:123
	s_waitcnt lgkmcnt(0)
	v_mul_f32_e32 v6, v8, v6
	v_mul_f32_e32 v7, v9, v7
	v_cvt_pk_bf16_f32 v11, v6, v7
	ds_read2_b32 v[6:7], v28 offset0:156 offset1:189
	s_waitcnt lgkmcnt(0)
	v_mul_f32_e32 v2, v2, v6
	v_mul_f32_e32 v3, v3, v7
	v_cvt_pk_bf16_f32 v12, v2, v3
	ds_read2_b32 v[2:3], v28 offset0:222 offset1:255
	s_waitcnt lgkmcnt(0)
	v_mul_f32_e32 v2, v4, v2
	v_mul_f32_e32 v3, v5, v3
	v_cvt_pk_bf16_f32 v13, v2, v3
	s_branch .LBB0_452

.LBB0_596:
	s_or_b64 exec, exec, s[0:1]
	s_waitcnt lgkmcnt(0)
	ds_read_b64 v[72:73], v139
	ds_read_b128 v[68:71], v191
	v_add_u32_e32 v2, s82, v189
	v_mul_lo_u32 v2, v2, s73
	v_lshlrev_b32_e32 v74, 1, v180
	v_add3_u32 v2, 0, v2, v74
	s_waitcnt lgkmcnt(0)
	v_lshlrev_b32_e32 v74, 16, v68
	v_fmac_f32_e32 v74, v52, v72
	v_and_b32_e32 v52, 0xffff0000, v68
	v_fmac_f32_e32 v52, v53, v73
	v_lshlrev_b32_e32 v53, 16, v69
	v_fmac_f32_e32 v53, v36, v72
	v_and_b32_e32 v36, 0xffff0000, v69
	v_fmac_f32_e32 v36, v37, v73
	v_lshlrev_b32_e32 v37, 16, v70
	v_fmac_f32_e32 v37, v20, v72
	v_and_b32_e32 v20, 0xffff0000, v70
	v_fmac_f32_e32 v20, v21, v73
	v_lshlrev_b32_e32 v21, 16, v71
	v_fmac_f32_e32 v21, v4, v72
	v_and_b32_e32 v4, 0xffff0000, v71
	v_cvt_pk_bf16_f32 v52, v74, v52
	v_fmac_f32_e32 v4, v5, v73
	v_cvt_pk_bf16_f32 v36, v53, v36
	v_cvt_pk_bf16_f32 v20, v37, v20
	v_cvt_pk_bf16_f32 v4, v21, v4
	ds_write_b16 v2, v52
	ds_write_b16_d16_hi v2, v52 offset:272
	ds_write_b16 v2, v36 offset:64
	ds_write_b16_d16_hi v2, v36 offset:336
	ds_write_b16 v2, v20 offset:128
	ds_write_b16_d16_hi v2, v20 offset:400
	ds_write_b16 v2, v4 offset:192
	ds_write_b16_d16_hi v2, v4 offset:464
	ds_read_b128 v[68:71], v191 offset:8192
	ds_read_b64 v[4:5], v139 offset:8
	v_readlane_b32 s0, v254, 62
	v_readlane_b32 s8, v254, 59
	s_add_i32 s2, s0, s84
	s_waitcnt lgkmcnt(1)
	v_lshlrev_b32_e32 v20, 16, v68
	v_and_b32_e32 v21, 0xffff0000, v68
	s_waitcnt lgkmcnt(0)
	v_fmac_f32_e32 v20, v54, v4
	v_fmac_f32_e32 v21, v55, v5
	v_cvt_pk_bf16_f32 v20, v20, v21
	v_lshlrev_b32_e32 v21, 16, v69
	v_and_b32_e32 v36, 0xffff0000, v69
	v_fmac_f32_e32 v21, v38, v4
	v_fmac_f32_e32 v36, v39, v5
	v_cvt_pk_bf16_f32 v21, v21, v36
	v_lshlrev_b32_e32 v36, 16, v70
	v_fmac_f32_e32 v36, v22, v4
	v_and_b32_e32 v22, 0xffff0000, v70
	v_fmac_f32_e32 v22, v23, v5
	v_lshlrev_b32_e32 v23, 16, v71
	v_fmac_f32_e32 v23, v6, v4
	v_and_b32_e32 v4, 0xffff0000, v71
	v_fmac_f32_e32 v4, v7, v5
	v_cvt_pk_bf16_f32 v22, v36, v22
	v_cvt_pk_bf16_f32 v4, v23, v4
	ds_write_b16 v2, v20 offset:544
	ds_write_b16_d16_hi v2, v20 offset:816
	ds_write_b16 v2, v21 offset:608
	ds_write_b16_d16_hi v2, v21 offset:880
	ds_write_b16 v2, v22 offset:672
	ds_write_b16_d16_hi v2, v22 offset:944
	ds_write_b16 v2, v4 offset:736
	ds_write_b16_d16_hi v2, v4 offset:1008
	ds_read_b128 v[4:7], v191 offset:16384
	ds_read_b64 v[20:21], v139 offset:32
	v_ashrrev_i32_e32 v69, 4, v178
	v_readlane_b32 s9, v254, 60
	v_add_u32_e32 v74, 4, v69
	s_waitcnt lgkmcnt(1)
	v_lshlrev_b32_e32 v22, 16, v4
	v_and_b32_e32 v4, 0xffff0000, v4
	s_waitcnt lgkmcnt(0)
	v_fmac_f32_e32 v22, v56, v20
	v_fmac_f32_e32 v4, v57, v21
	v_cvt_pk_bf16_f32 v4, v22, v4
	v_lshlrev_b32_e32 v22, 16, v5
	v_and_b32_e32 v5, 0xffff0000, v5
	v_fmac_f32_e32 v22, v40, v20
	v_fmac_f32_e32 v5, v41, v21
	v_cvt_pk_bf16_f32 v5, v22, v5
	v_lshlrev_b32_e32 v22, 16, v6
	v_and_b32_e32 v6, 0xffff0000, v6
	v_fmac_f32_e32 v22, v24, v20
	v_fmac_f32_e32 v6, v25, v21
	v_cvt_pk_bf16_f32 v6, v22, v6
	v_lshlrev_b32_e32 v22, 16, v7
	v_and_b32_e32 v7, 0xffff0000, v7
	v_fmac_f32_e32 v7, v9, v21
	v_fmac_f32_e32 v22, v8, v20
	v_cvt_pk_bf16_f32 v7, v22, v7
	ds_write_b16 v2, v4 offset:2176
	ds_write_b16_d16_hi v2, v4 offset:2448
	ds_write_b16 v2, v5 offset:2240
	ds_write_b16_d16_hi v2, v5 offset:2512
	ds_write_b16 v2, v6 offset:2304
	ds_write_b16_d16_hi v2, v6 offset:2576
	ds_write_b16 v2, v7 offset:2368
	ds_write_b16_d16_hi v2, v7 offset:2640
	ds_read_b128 v[4:7], v191 offset:24576
	ds_read_b64 v[8:9], v139 offset:40
	v_lshlrev_b32_e32 v36, 4, v179
	v_mov_b32_e32 v37, v3
	v_add_u32_e32 v68, 8, v69
	s_waitcnt lgkmcnt(1)
	v_lshlrev_b32_e32 v20, 16, v4
	v_and_b32_e32 v4, 0xffff0000, v4
	s_waitcnt lgkmcnt(0)
	v_fmac_f32_e32 v20, v58, v8
	v_fmac_f32_e32 v4, v59, v9
	v_cvt_pk_bf16_f32 v4, v20, v4
	v_lshlrev_b32_e32 v20, 16, v5
	v_and_b32_e32 v5, 0xffff0000, v5
	v_fmac_f32_e32 v20, v42, v8
	v_fmac_f32_e32 v5, v43, v9
	v_cvt_pk_bf16_f32 v5, v20, v5
	v_lshlrev_b32_e32 v20, 16, v6
	v_and_b32_e32 v6, 0xffff0000, v6
	v_fmac_f32_e32 v20, v26, v8
	v_fmac_f32_e32 v6, v27, v9
	v_cvt_pk_bf16_f32 v6, v20, v6
	v_lshlrev_b32_e32 v20, 16, v7
	v_and_b32_e32 v7, 0xffff0000, v7
	v_fmac_f32_e32 v7, v11, v9
	v_fmac_f32_e32 v20, v10, v8
	v_cvt_pk_bf16_f32 v7, v20, v7
	ds_write_b16 v2, v4 offset:2720
	ds_write_b16_d16_hi v2, v4 offset:2992
	ds_write_b16 v2, v5 offset:2784
	ds_write_b16_d16_hi v2, v5 offset:3056
	ds_write_b16 v2, v6 offset:2848
	ds_write_b16_d16_hi v2, v6 offset:3120
	ds_write_b16 v2, v7 offset:2912
	ds_write_b16_d16_hi v2, v7 offset:3184
	ds_read_b128 v[4:7], v191 offset:32768
	ds_read_b64 v[8:9], v139 offset:64
	v_mov_b32_e32 v55, v3
	v_mov_b32_e32 v41, v3
	v_readlane_b32 s84, v254, 17
	s_waitcnt lgkmcnt(1)
	v_lshlrev_b32_e32 v10, 16, v4
	v_and_b32_e32 v4, 0xffff0000, v4
	s_waitcnt lgkmcnt(0)
	v_fmac_f32_e32 v10, v60, v8
	v_fmac_f32_e32 v4, v61, v9
	v_cvt_pk_bf16_f32 v4, v10, v4
	v_lshlrev_b32_e32 v10, 16, v5
	v_and_b32_e32 v5, 0xffff0000, v5
	v_fmac_f32_e32 v10, v44, v8
	v_fmac_f32_e32 v5, v45, v9
	v_cvt_pk_bf16_f32 v5, v10, v5
	v_lshlrev_b32_e32 v10, 16, v6
	v_and_b32_e32 v6, 0xffff0000, v6
	v_fmac_f32_e32 v10, v28, v8
	v_fmac_f32_e32 v6, v29, v9
	v_cvt_pk_bf16_f32 v6, v10, v6
	v_lshlrev_b32_e32 v10, 16, v7
	v_and_b32_e32 v7, 0xffff0000, v7
	v_fmac_f32_e32 v7, v13, v9
	v_fmac_f32_e32 v10, v12, v8
	v_cvt_pk_bf16_f32 v7, v10, v7
	ds_write_b16 v2, v4 offset:4352
	ds_write_b16_d16_hi v2, v4 offset:4624
	ds_write_b16 v2, v5 offset:4416
	ds_write_b16_d16_hi v2, v5 offset:4688
	ds_write_b16 v2, v6 offset:4480
	ds_write_b16_d16_hi v2, v6 offset:4752
	ds_write_b16 v2, v7 offset:4544
	ds_write_b16_d16_hi v2, v7 offset:4816
	ds_read_b128 v[4:7], v191 offset:40960
	ds_read_b64 v[8:9], v139 offset:72
	v_mov_b32_e32 v61, v3
	v_add_u32_e32 v45, 28, v69
	v_add_u32_e32 v44, 0, v36
	s_waitcnt lgkmcnt(1)
; template <int VAR>
; __device__ __forceinline__ void nsa_attn_mfma(Frame& F, bf16* Y) {
;     ...
;       v4u zv[8];
; #pragma unroll
;       for (int j = 0; j < 8; ++j) { const int row = 4 * j + (lane >> 4), tt = t0 + 4 * wid + (row >> 3), hh = g * 8 + (row & 7);
;         zv[j] = *(const v4u*)(proj + (size_t)(b * SEQ + tt) * NSA_NP + NSA_Z + hh * 128 + (lane & 15) * 8); }
	v_lshlrev_b32_e32 v10, 16, v4
	v_and_b32_e32 v4, 0xffff0000, v4
	s_waitcnt lgkmcnt(0)
	v_fmac_f32_e32 v10, v62, v8
	v_fmac_f32_e32 v4, v63, v9
	v_cvt_pk_bf16_f32 v4, v10, v4
	v_lshlrev_b32_e32 v10, 16, v5
	v_and_b32_e32 v5, 0xffff0000, v5
	v_fmac_f32_e32 v10, v46, v8
	v_fmac_f32_e32 v5, v47, v9
	v_cvt_pk_bf16_f32 v5, v10, v5
	v_lshlrev_b32_e32 v10, 16, v6
	v_and_b32_e32 v6, 0xffff0000, v6
	v_fmac_f32_e32 v10, v30, v8
	v_fmac_f32_e32 v6, v31, v9
	v_cvt_pk_bf16_f32 v6, v10, v6
	v_lshlrev_b32_e32 v10, 16, v7
	v_and_b32_e32 v7, 0xffff0000, v7
	v_fmac_f32_e32 v7, v15, v9
	v_fmac_f32_e32 v10, v14, v8
	v_cvt_pk_bf16_f32 v7, v10, v7
	ds_write_b16 v2, v4 offset:4896
	ds_write_b16_d16_hi v2, v4 offset:5168
	ds_write_b16 v2, v5 offset:4960
	ds_write_b16_d16_hi v2, v5 offset:5232
	ds_write_b16 v2, v6 offset:5024
	ds_write_b16_d16_hi v2, v6 offset:5296
	ds_write_b16 v2, v7 offset:5088
	ds_write_b16_d16_hi v2, v7 offset:5360
	ds_read_b128 v[4:7], v191 offset:49152
	ds_read_b64 v[8:9], v139 offset:96
	v_readlane_b32 s85, v254, 18
	v_readlane_b32 s10, v254, 61
	s_waitcnt lgkmcnt(1)
	v_lshlrev_b32_e32 v10, 16, v4
	v_and_b32_e32 v4, 0xffff0000, v4
	s_waitcnt lgkmcnt(0)
	v_fmac_f32_e32 v10, v64, v8
	v_fmac_f32_e32 v4, v65, v9
	v_cvt_pk_bf16_f32 v4, v10, v4
	v_lshlrev_b32_e32 v10, 16, v5
	v_and_b32_e32 v5, 0xffff0000, v5
	v_fmac_f32_e32 v10, v48, v8
	v_fmac_f32_e32 v5, v49, v9
	v_cvt_pk_bf16_f32 v5, v10, v5
	v_lshlrev_b32_e32 v10, 16, v6
	v_and_b32_e32 v6, 0xffff0000, v6
	v_fmac_f32_e32 v10, v32, v8
	v_fmac_f32_e32 v6, v33, v9
	v_cvt_pk_bf16_f32 v6, v10, v6
	v_lshlrev_b32_e32 v10, 16, v7
	v_and_b32_e32 v7, 0xffff0000, v7
	v_fmac_f32_e32 v7, v17, v9
	v_fmac_f32_e32 v10, v16, v8
	v_cvt_pk_bf16_f32 v7, v10, v7
	ds_write_b16 v2, v4 offset:6528
	ds_write_b16_d16_hi v2, v4 offset:6800
	ds_write_b16 v2, v5 offset:6592
	ds_write_b16_d16_hi v2, v5 offset:6864
	ds_write_b16 v2, v6 offset:6656
	ds_write_b16_d16_hi v2, v6 offset:6928
	ds_write_b16 v2, v7 offset:6720
	ds_write_b16_d16_hi v2, v7 offset:6992
	ds_read_b128 v[4:7], v191 offset:57344
	ds_read_b64 v[8:9], v139 offset:104
	v_add_u32_e32 v65, 20, v69
	v_mov_b32_e32 v49, v3
	v_add_u32_e32 v64, 24, v69
	s_waitcnt lgkmcnt(1)
	v_lshlrev_b32_e32 v10, 16, v4
	v_and_b32_e32 v4, 0xffff0000, v4
	s_waitcnt lgkmcnt(0)
	v_fmac_f32_e32 v10, v66, v8
	v_fmac_f32_e32 v4, v67, v9
	v_cvt_pk_bf16_f32 v4, v10, v4
	v_lshlrev_b32_e32 v10, 16, v5
	v_and_b32_e32 v5, 0xffff0000, v5
	v_fmac_f32_e32 v10, v50, v8
	v_fmac_f32_e32 v5, v51, v9
	v_cvt_pk_bf16_f32 v5, v10, v5
	v_lshlrev_b32_e32 v10, 16, v6
	v_and_b32_e32 v6, 0xffff0000, v6
	v_fmac_f32_e32 v10, v34, v8
	v_fmac_f32_e32 v6, v35, v9
	v_cvt_pk_bf16_f32 v6, v10, v6
	v_lshlrev_b32_e32 v10, 16, v7
	v_and_b32_e32 v7, 0xffff0000, v7
	v_fmac_f32_e32 v7, v19, v9
	v_fmac_f32_e32 v10, v18, v8
	v_cvt_pk_bf16_f32 v7, v10, v7
	ds_write_b16 v2, v4 offset:7072
	ds_write_b16_d16_hi v2, v4 offset:7344
	ds_write_b16 v2, v5 offset:7136
	ds_write_b16_d16_hi v2, v5 offset:7408
	ds_write_b16 v2, v6 offset:7200
	ds_write_b16_d16_hi v2, v6 offset:7472
	ds_write_b16 v2, v7 offset:7264
	ds_write_b16_d16_hi v2, v7 offset:7536
	v_ashrrev_i32_e32 v2, 7, v178
	v_and_or_b32 v8, v69, 7, s75
	v_add_u32_e32 v62, s2, v2
	v_mov_b64_e32 v[4:5], s[8:9]
	v_mad_i64_i32 v[6:7], s[0:1], v62, s89, v[4:5]
	v_lshlrev_b32_e32 v2, 8, v8
	v_ashrrev_i32_e32 v8, 3, v74
	v_lshl_add_u64 v[6:7], v[6:7], 0, v[2:3]
	v_and_or_b32 v10, v74, 7, s75
	v_add_u32_e32 v58, s2, v8
	v_lshl_add_u64 v[6:7], v[6:7], 0, v[36:37]
	v_mad_i64_i32 v[8:9], s[0:1], v58, s89, v[4:5]
	v_lshlrev_b32_e32 v60, 8, v10
	v_add_co_u32_e32 v6, vcc, s74, v6
	v_lshl_add_u64 v[8:9], v[8:9], 0, v[60:61]
	s_nop 0
	v_addc_co_u32_e32 v7, vcc, 0, v7, vcc
	v_lshl_add_u64 v[8:9], v[8:9], 0, v[36:37]
	s_waitcnt lgkmcnt(0)
	v_add_co_u32_e32 v8, vcc, s74, v8
	v_add_u32_e32 v67, 12, v69
	s_nop 0
	v_addc_co_u32_e32 v9, vcc, 0, v9, vcc
	global_load_dwordx4 v[32:35], v[6:7], off offset:2048
	global_load_dwordx4 v[28:31], v[8:9], off offset:2048
	v_ashrrev_i32_e32 v6, 3, v68
	v_add_u32_e32 v56, s2, v6
	v_mad_i64_i32 v[6:7], s[0:1], v56, s89, v[4:5]
	v_ashrrev_i32_e32 v8, 3, v67
	v_lshl_add_u64 v[6:7], v[6:7], 0, v[2:3]
	v_and_or_b32 v10, v67, 7, s75
	v_add_u32_e32 v52, s2, v8
	v_lshl_add_u64 v[6:7], v[6:7], 0, v[36:37]
	v_mad_i64_i32 v[8:9], s[0:1], v52, s89, v[4:5]
	v_lshlrev_b32_e32 v54, 8, v10
	v_add_co_u32_e32 v6, vcc, s74, v6
	v_lshl_add_u64 v[8:9], v[8:9], 0, v[54:55]
	s_nop 0
	v_addc_co_u32_e32 v7, vcc, 0, v7, vcc
	v_lshl_add_u64 v[8:9], v[8:9], 0, v[36:37]
	v_add_co_u32_e32 v8, vcc, s74, v8
	v_add_u32_e32 v66, 16, v69
	s_nop 0
	v_addc_co_u32_e32 v9, vcc, 0, v9, vcc
	global_load_dwordx4 v[24:27], v[6:7], off offset:2048
	global_load_dwordx4 v[20:23], v[8:9], off offset:2048
	v_ashrrev_i32_e32 v6, 3, v66
	v_add_u32_e32 v50, s2, v6
	v_mad_i64_i32 v[6:7], s[0:1], v50, s89, v[4:5]
	v_ashrrev_i32_e32 v8, 3, v65
	v_lshl_add_u64 v[6:7], v[6:7], 0, v[2:3]
	v_and_or_b32 v10, v65, 7, s75
	v_add_u32_e32 v46, s2, v8
	v_lshl_add_u64 v[6:7], v[6:7], 0, v[36:37]
	v_mad_i64_i32 v[8:9], s[0:1], v46, s89, v[4:5]
	v_lshlrev_b32_e32 v48, 8, v10
	v_add_co_u32_e32 v6, vcc, s74, v6
	v_lshl_add_u64 v[8:9], v[8:9], 0, v[48:49]
	s_nop 0
	v_addc_co_u32_e32 v7, vcc, 0, v7, vcc
	v_lshl_add_u64 v[8:9], v[8:9], 0, v[36:37]
	v_add_co_u32_e32 v8, vcc, s74, v8
	v_add_u32_e32 v69, s82, v69
	s_nop 0
	v_addc_co_u32_e32 v9, vcc, 0, v9, vcc
	global_load_dwordx4 v[16:19], v[6:7], off offset:2048
	global_load_dwordx4 v[12:15], v[8:9], off offset:2048
	v_ashrrev_i32_e32 v6, 3, v64
	v_add_u32_e32 v42, s2, v6
	v_mad_i64_i32 v[6:7], s[0:1], v42, s89, v[4:5]
	v_ashrrev_i32_e32 v8, 3, v45
	v_lshl_add_u64 v[6:7], v[6:7], 0, v[2:3]
	v_and_or_b32 v9, v45, 7, s75
	v_add_u32_e32 v38, s2, v8
	v_mad_u64_u32 v[70:71], s[0:1], v69, s73, v[44:45]
	v_lshl_add_u64 v[6:7], v[6:7], 0, v[36:37]
	v_mad_i64_i32 v[4:5], s[0:1], v38, s89, v[4:5]
	v_lshlrev_b32_e32 v40, 8, v9
	v_add_co_u32_e32 v6, vcc, s74, v6
	v_lshl_add_u64 v[4:5], v[4:5], 0, v[40:41]
	s_nop 0
	v_addc_co_u32_e32 v7, vcc, 0, v7, vcc
	v_lshl_add_u64 v[4:5], v[4:5], 0, v[36:37]
	v_add_co_u32_e32 v4, vcc, s74, v4
	v_ashrrev_i32_e32 v63, 31, v62
	s_nop 0
	v_addc_co_u32_e32 v5, vcc, 0, v5, vcc
	global_load_dwordx4 v[8:11], v[6:7], off offset:2048
	s_nop 0
	global_load_dwordx4 v[4:7], v[4:5], off offset:2048
	ds_read_b128 v[70:73], v70
	v_lshlrev_b64 v[62:63], 13, v[62:63]
	v_lshl_add_u64 v[62:63], s[92:93], 0, v[62:63]
	v_lshl_add_u64 v[62:63], v[62:63], 0, v[2:3]
	s_waitcnt vmcnt(7)
; __device__ __forceinline__ float bflo(unsigned w) { return __uint_as_float(w << 16); }
; __device__ __forceinline__ float bfhi(unsigned w) { return __uint_as_float(w & 0xffff0000u); }
; __device__ __forceinline__ float siluf_(float x) { return x * __builtin_amdgcn_rcpf(1.0f + __expf(-x)); }
; __device__ __forceinline__ unsigned cvtpk(float lo, float hi) { unsigned r; asm volatile("v_cvt_pk_bf16_f32 %0, %1, %2" : "=v"(r) : "v"(lo), "v"(hi)); return r; }
; template <int VAR>
; __device__ __forceinline__ void nsa_attn_mfma(Frame& F, bf16* Y) {
;     ...
; #pragma unroll
;       for (int j = 0; j < 8; ++j) { const int row = 4 * j + (lane >> 4), tt = t0 + 4 * wid + (row >> 3), hh = g * 8 + (row & 7);
;         const v4u tv = *(const v4u*)((const unsigned short*)(lds + AT_K) + (wid * 32 + row) * ROWP + (lane & 15) * 8); const v4u z = zv[j]; v4u y;
;         y.x = cvtpk(bflo(tv.x) * siluf_(bflo(z.x)), bfhi(tv.x) * siluf_(bfhi(z.x))); y.y = cvtpk(bflo(tv.y) * siluf_(bflo(z.y)), bfhi(tv.y) * siluf_(bfhi(z.y)));
;         y.z = cvtpk(bflo(tv.z) * siluf_(bflo(z.z)), bfhi(tv.z) * siluf_(bfhi(z.z))); y.w = cvtpk(bflo(tv.w) * siluf_(bflo(z.w)), bfhi(tv.w) * siluf_(bfhi(z.w)));
;         *(v4u*)(Y + (size_t)(b * SEQ + tt) * DM + hh * 128 + (lane & 15) * 8) = y; }
	v_lshlrev_b32_e32 v69, 16, v32
	v_and_b32_e32 v32, 0xffff0000, v32
	v_mul_f32_e32 v75, 0xbfb8aa3b, v69
	v_mul_f32_e32 v76, 0xbfb8aa3b, v32
	v_exp_f32_e32 v75, v75
	v_exp_f32_e32 v76, v76
	s_waitcnt lgkmcnt(0)
	v_lshlrev_b32_e32 v77, 16, v70
	v_and_b32_e32 v70, 0xffff0000, v70
	v_add_f32_e32 v75, 1.0, v75
	v_add_f32_e32 v76, 1.0, v76
	v_rcp_f32_e32 v75, v75
	v_rcp_f32_e32 v76, v76
	v_lshl_add_u64 v[62:63], v[62:63], 0, v[36:37]
	v_ashrrev_i32_e32 v59, 31, v58
	v_mul_f32_e32 v69, v75, v69
	v_mul_f32_e32 v32, v76, v32
	v_mul_f32_e32 v69, v69, v77
	v_mul_f32_e32 v32, v32, v70
	v_cvt_pk_bf16_f32 v32, v69, v32
	v_lshlrev_b32_e32 v69, 16, v33
	v_and_b32_e32 v33, 0xffff0000, v33
	v_mul_f32_e32 v70, 0xbfb8aa3b, v69
	v_mul_f32_e32 v75, 0xbfb8aa3b, v33
	v_exp_f32_e32 v70, v70
	v_exp_f32_e32 v75, v75
	v_lshlrev_b32_e32 v76, 16, v71
	v_ashrrev_i32_e32 v57, 31, v56
	v_add_f32_e32 v70, 1.0, v70
	v_add_f32_e32 v75, 1.0, v75
	v_rcp_f32_e32 v70, v70
	v_rcp_f32_e32 v75, v75
	v_ashrrev_i32_e32 v53, 31, v52
	v_ashrrev_i32_e32 v51, 31, v50
	v_mul_f32_e32 v69, v70, v69
	v_and_b32_e32 v70, 0xffff0000, v71
	v_mul_f32_e32 v33, v75, v33
	v_mul_f32_e32 v69, v69, v76
	v_mul_f32_e32 v33, v33, v70
	v_cvt_pk_bf16_f32 v33, v69, v33
	v_lshlrev_b32_e32 v69, 16, v34
	v_and_b32_e32 v34, 0xffff0000, v34
	v_mul_f32_e32 v70, 0xbfb8aa3b, v69
	v_mul_f32_e32 v71, 0xbfb8aa3b, v34
	v_exp_f32_e32 v70, v70
	v_exp_f32_e32 v71, v71
	v_lshlrev_b32_e32 v75, 16, v72
	v_ashrrev_i32_e32 v47, 31, v46
	v_add_f32_e32 v70, 1.0, v70
	v_add_f32_e32 v71, 1.0, v71
	v_rcp_f32_e32 v70, v70
	v_rcp_f32_e32 v71, v71
	v_ashrrev_i32_e32 v43, 31, v42
	v_ashrrev_i32_e32 v39, 31, v38
	v_mul_f32_e32 v69, v70, v69
	v_and_b32_e32 v70, 0xffff0000, v72
	v_mul_f32_e32 v34, v71, v34
	v_mul_f32_e32 v69, v69, v75
	v_mul_f32_e32 v34, v34, v70
	v_cvt_pk_bf16_f32 v34, v69, v34
	v_lshlrev_b32_e32 v69, 16, v35
	v_and_b32_e32 v35, 0xffff0000, v35
	v_mul_f32_e32 v70, 0xbfb8aa3b, v69
	v_mul_f32_e32 v71, 0xbfb8aa3b, v35
	v_exp_f32_e32 v70, v70
	v_exp_f32_e32 v71, v71
	v_lshlrev_b32_e32 v72, 16, v73
	v_add_f32_e32 v70, 1.0, v70
	v_add_f32_e32 v71, 1.0, v71
	v_rcp_f32_e32 v70, v70
	v_rcp_f32_e32 v71, v71
	v_mul_f32_e32 v69, v70, v69
	v_and_b32_e32 v70, 0xffff0000, v73
	v_mul_f32_e32 v35, v71, v35
	v_mul_f32_e32 v35, v35, v70
	v_mul_f32_e32 v69, v69, v72
	v_cvt_pk_bf16_f32 v35, v69, v35
	global_store_dwordx4 v[62:63], v[32:35], off sc1
	s_waitcnt vmcnt(7)
	v_lshlrev_b32_e32 v62, 16, v28
	v_and_b32_e32 v28, 0xffff0000, v28
	v_mul_f32_e32 v63, 0xbfb8aa3b, v62
	v_mul_f32_e32 v69, 0xbfb8aa3b, v28
	v_exp_f32_e32 v63, v63
	v_exp_f32_e32 v69, v69
	v_add_u32_e32 v32, s82, v74
	v_mad_u64_u32 v[32:33], s[0:1], v32, s73, v[44:45]
	ds_read_b128 v[32:35], v32
	v_add_f32_e32 v63, 1.0, v63
	v_add_f32_e32 v69, 1.0, v69
	v_rcp_f32_e32 v63, v63
	v_rcp_f32_e32 v69, v69
	s_waitcnt lgkmcnt(0)
	v_lshlrev_b32_e32 v70, 16, v32
	v_and_b32_e32 v32, 0xffff0000, v32
	v_mul_f32_e32 v62, v63, v62
	v_mul_f32_e32 v28, v69, v28
	v_mul_f32_e32 v62, v62, v70
	v_mul_f32_e32 v28, v28, v32
	v_lshlrev_b32_e32 v32, 16, v29
	v_and_b32_e32 v29, 0xffff0000, v29
	v_cvt_pk_bf16_f32 v28, v62, v28
	v_mul_f32_e32 v62, 0xbfb8aa3b, v32
	v_mul_f32_e32 v63, 0xbfb8aa3b, v29
	v_exp_f32_e32 v62, v62
	v_exp_f32_e32 v63, v63
	v_lshlrev_b32_e32 v69, 16, v33
	v_and_b32_e32 v33, 0xffff0000, v33
	v_add_f32_e32 v62, 1.0, v62
	v_add_f32_e32 v63, 1.0, v63
	v_rcp_f32_e32 v62, v62
	v_rcp_f32_e32 v63, v63
	v_mul_f32_e32 v32, v62, v32
	v_mul_f32_e32 v29, v63, v29
	v_mul_f32_e32 v32, v32, v69
	v_mul_f32_e32 v29, v29, v33
	v_cvt_pk_bf16_f32 v29, v32, v29
	v_lshlrev_b32_e32 v32, 16, v30
	v_and_b32_e32 v30, 0xffff0000, v30
	v_mul_f32_e32 v33, 0xbfb8aa3b, v32
	v_mul_f32_e32 v62, 0xbfb8aa3b, v30
	v_exp_f32_e32 v33, v33
	v_exp_f32_e32 v62, v62
	v_lshlrev_b32_e32 v63, 16, v34
	v_add_f32_e32 v33, 1.0, v33
	v_add_f32_e32 v62, 1.0, v62
	v_rcp_f32_e32 v33, v33
	v_rcp_f32_e32 v62, v62
	v_mul_f32_e32 v32, v33, v32
	v_and_b32_e32 v33, 0xffff0000, v34
	v_mul_f32_e32 v30, v62, v30
	v_mul_f32_e32 v32, v32, v63
	v_mul_f32_e32 v30, v30, v33
	v_cvt_pk_bf16_f32 v30, v32, v30
	v_lshlrev_b32_e32 v32, 16, v31
	v_and_b32_e32 v31, 0xffff0000, v31
	v_mul_f32_e32 v33, 0xbfb8aa3b, v32
	v_mul_f32_e32 v34, 0xbfb8aa3b, v31
	v_exp_f32_e32 v33, v33
	v_exp_f32_e32 v34, v34
	v_lshlrev_b32_e32 v62, 16, v35
	v_add_f32_e32 v33, 1.0, v33
	v_add_f32_e32 v34, 1.0, v34
	v_rcp_f32_e32 v33, v33
	v_rcp_f32_e32 v34, v34
	v_mul_f32_e32 v32, v33, v32
	v_and_b32_e32 v33, 0xffff0000, v35
	v_mul_f32_e32 v31, v34, v31
	v_mul_f32_e32 v32, v32, v62
	v_mul_f32_e32 v31, v31, v33
	v_cvt_pk_bf16_f32 v31, v32, v31
	v_lshlrev_b64 v[32:33], 13, v[58:59]
	v_lshl_add_u64 v[32:33], s[92:93], 0, v[32:33]
	v_lshl_add_u64 v[32:33], v[32:33], 0, v[60:61]
	v_lshl_add_u64 v[32:33], v[32:33], 0, v[36:37]
	global_store_dwordx4 v[32:33], v[28:31], off sc1
	s_waitcnt vmcnt(7)
	v_lshlrev_b32_e32 v32, 16, v24
	v_and_b32_e32 v24, 0xffff0000, v24
	v_mul_f32_e32 v33, 0xbfb8aa3b, v32
	v_mul_f32_e32 v34, 0xbfb8aa3b, v24
	v_exp_f32_e32 v33, v33
	v_exp_f32_e32 v34, v34
	v_add_u32_e32 v28, s82, v68
	v_mad_u64_u32 v[28:29], s[0:1], v28, s73, v[44:45]
	ds_read_b128 v[28:31], v28
	v_add_f32_e32 v33, 1.0, v33
	v_add_f32_e32 v34, 1.0, v34
	v_rcp_f32_e32 v33, v33
	v_rcp_f32_e32 v34, v34
	s_waitcnt lgkmcnt(0)
; __device__ __forceinline__ float bflo(unsigned w) { return __uint_as_float(w << 16); }
; __device__ __forceinline__ float bfhi(unsigned w) { return __uint_as_float(w & 0xffff0000u); }
; __device__ __forceinline__ float siluf_(float x) { return x * __builtin_amdgcn_rcpf(1.0f + __expf(-x)); }
; __device__ __forceinline__ unsigned cvtpk(float lo, float hi) { unsigned r; asm volatile("v_cvt_pk_bf16_f32 %0, %1, %2" : "=v"(r) : "v"(lo), "v"(hi)); return r; }
; template <int VAR>
; __device__ __forceinline__ void nsa_attn_mfma(Frame& F, bf16* Y) {
;     ...
; #pragma unroll
;       for (int j = 0; j < 8; ++j) { const int row = 4 * j + (lane >> 4), tt = t0 + 4 * wid + (row >> 3), hh = g * 8 + (row & 7);
;         const v4u tv = *(const v4u*)((const unsigned short*)(lds + AT_K) + (wid * 32 + row) * ROWP + (lane & 15) * 8); const v4u z = zv[j]; v4u y;
;         y.x = cvtpk(bflo(tv.x) * siluf_(bflo(z.x)), bfhi(tv.x) * siluf_(bfhi(z.x))); y.y = cvtpk(bflo(tv.y) * siluf_(bflo(z.y)), bfhi(tv.y) * siluf_(bfhi(z.y)));
;         y.z = cvtpk(bflo(tv.z) * siluf_(bflo(z.z)), bfhi(tv.z) * siluf_(bfhi(z.z))); y.w = cvtpk(bflo(tv.w) * siluf_(bflo(z.w)), bfhi(tv.w) * siluf_(bfhi(z.w)));
;         *(v4u*)(Y + (size_t)(b * SEQ + tt) * DM + hh * 128 + (lane & 15) * 8) = y; }
	v_lshlrev_b32_e32 v35, 16, v28
	v_and_b32_e32 v28, 0xffff0000, v28
	v_mul_f32_e32 v32, v33, v32
	v_mul_f32_e32 v24, v34, v24
	v_mul_f32_e32 v32, v32, v35
	v_mul_f32_e32 v24, v24, v28
	v_lshlrev_b32_e32 v28, 16, v25
	v_and_b32_e32 v25, 0xffff0000, v25
	v_cvt_pk_bf16_f32 v24, v32, v24
	v_mul_f32_e32 v32, 0xbfb8aa3b, v28
	v_mul_f32_e32 v33, 0xbfb8aa3b, v25
	v_exp_f32_e32 v32, v32
	v_exp_f32_e32 v33, v33
	v_lshlrev_b32_e32 v34, 16, v29
	v_and_b32_e32 v29, 0xffff0000, v29
	v_add_f32_e32 v32, 1.0, v32
	v_add_f32_e32 v33, 1.0, v33
	v_rcp_f32_e32 v32, v32
	v_rcp_f32_e32 v33, v33
	v_mul_f32_e32 v28, v32, v28
	v_mul_f32_e32 v25, v33, v25
	v_mul_f32_e32 v28, v28, v34
	v_mul_f32_e32 v25, v25, v29
	v_cvt_pk_bf16_f32 v25, v28, v25
	v_lshlrev_b32_e32 v28, 16, v26
	v_and_b32_e32 v26, 0xffff0000, v26
	v_mul_f32_e32 v29, 0xbfb8aa3b, v28
	v_mul_f32_e32 v32, 0xbfb8aa3b, v26
	v_exp_f32_e32 v29, v29
	v_exp_f32_e32 v32, v32
	v_lshlrev_b32_e32 v33, 16, v30
	v_add_f32_e32 v29, 1.0, v29
	v_add_f32_e32 v32, 1.0, v32
	v_rcp_f32_e32 v29, v29
	v_rcp_f32_e32 v32, v32
	v_mul_f32_e32 v28, v29, v28
	v_and_b32_e32 v29, 0xffff0000, v30
	v_mul_f32_e32 v26, v32, v26
	v_mul_f32_e32 v28, v28, v33
	v_mul_f32_e32 v26, v26, v29
	v_cvt_pk_bf16_f32 v26, v28, v26
	v_lshlrev_b32_e32 v28, 16, v27
	v_and_b32_e32 v27, 0xffff0000, v27
	v_mul_f32_e32 v29, 0xbfb8aa3b, v28
	v_mul_f32_e32 v30, 0xbfb8aa3b, v27
	v_exp_f32_e32 v29, v29
	v_exp_f32_e32 v30, v30
	v_lshlrev_b32_e32 v32, 16, v31
	v_add_f32_e32 v29, 1.0, v29
	v_add_f32_e32 v30, 1.0, v30
	v_rcp_f32_e32 v29, v29
	v_rcp_f32_e32 v30, v30
	v_mul_f32_e32 v28, v29, v28
	v_and_b32_e32 v29, 0xffff0000, v31
	v_mul_f32_e32 v27, v30, v27
	v_mul_f32_e32 v28, v28, v32
	v_mul_f32_e32 v27, v27, v29
	v_cvt_pk_bf16_f32 v27, v28, v27
	v_lshlrev_b64 v[28:29], 13, v[56:57]
	v_lshl_add_u64 v[28:29], s[92:93], 0, v[28:29]
	v_lshl_add_u64 v[28:29], v[28:29], 0, v[2:3]
	v_lshl_add_u64 v[28:29], v[28:29], 0, v[36:37]
	global_store_dwordx4 v[28:29], v[24:27], off sc1
	s_waitcnt vmcnt(7)
	v_lshlrev_b32_e32 v28, 16, v20
	v_and_b32_e32 v20, 0xffff0000, v20
	v_mul_f32_e32 v29, 0xbfb8aa3b, v28
	v_mul_f32_e32 v30, 0xbfb8aa3b, v20
	v_exp_f32_e32 v29, v29
	v_exp_f32_e32 v30, v30
	v_add_u32_e32 v24, s82, v67
	v_mad_u64_u32 v[24:25], s[0:1], v24, s73, v[44:45]
	ds_read_b128 v[24:27], v24
	v_add_f32_e32 v29, 1.0, v29
	v_add_f32_e32 v30, 1.0, v30
	v_rcp_f32_e32 v29, v29
	v_rcp_f32_e32 v30, v30
	s_waitcnt lgkmcnt(0)
	v_lshlrev_b32_e32 v31, 16, v24
	v_and_b32_e32 v24, 0xffff0000, v24
	v_mul_f32_e32 v28, v29, v28
	v_mul_f32_e32 v20, v30, v20
	v_mul_f32_e32 v28, v28, v31
	v_mul_f32_e32 v20, v20, v24
	v_lshlrev_b32_e32 v24, 16, v21
	v_and_b32_e32 v21, 0xffff0000, v21
	v_cvt_pk_bf16_f32 v20, v28, v20
	v_mul_f32_e32 v28, 0xbfb8aa3b, v24
	v_mul_f32_e32 v29, 0xbfb8aa3b, v21
	v_exp_f32_e32 v28, v28
	v_exp_f32_e32 v29, v29
	v_lshlrev_b32_e32 v30, 16, v25
	v_and_b32_e32 v25, 0xffff0000, v25
	v_add_f32_e32 v28, 1.0, v28
	v_add_f32_e32 v29, 1.0, v29
	v_rcp_f32_e32 v28, v28
	v_rcp_f32_e32 v29, v29
	v_mul_f32_e32 v24, v28, v24
	v_mul_f32_e32 v21, v29, v21
	v_mul_f32_e32 v24, v24, v30
	v_mul_f32_e32 v21, v21, v25
	v_cvt_pk_bf16_f32 v21, v24, v21
	v_lshlrev_b32_e32 v24, 16, v22
	v_and_b32_e32 v22, 0xffff0000, v22
	v_mul_f32_e32 v25, 0xbfb8aa3b, v24
	v_mul_f32_e32 v28, 0xbfb8aa3b, v22
	v_exp_f32_e32 v25, v25
	v_exp_f32_e32 v28, v28
	v_lshlrev_b32_e32 v29, 16, v26
	v_add_f32_e32 v25, 1.0, v25
	v_add_f32_e32 v28, 1.0, v28
	v_rcp_f32_e32 v25, v25
	v_rcp_f32_e32 v28, v28
	v_mul_f32_e32 v24, v25, v24
	v_and_b32_e32 v25, 0xffff0000, v26
	v_mul_f32_e32 v22, v28, v22
	v_mul_f32_e32 v24, v24, v29
	v_mul_f32_e32 v22, v22, v25
	v_cvt_pk_bf16_f32 v22, v24, v22
	v_lshlrev_b32_e32 v24, 16, v23
	v_and_b32_e32 v23, 0xffff0000, v23
	v_mul_f32_e32 v25, 0xbfb8aa3b, v24
	v_mul_f32_e32 v26, 0xbfb8aa3b, v23
	v_exp_f32_e32 v25, v25
	v_exp_f32_e32 v26, v26
	v_lshlrev_b32_e32 v28, 16, v27
	v_add_f32_e32 v25, 1.0, v25
	v_add_f32_e32 v26, 1.0, v26
	v_rcp_f32_e32 v25, v25
	v_rcp_f32_e32 v26, v26
	v_mul_f32_e32 v24, v25, v24
	v_and_b32_e32 v25, 0xffff0000, v27
	v_mul_f32_e32 v23, v26, v23
	v_mul_f32_e32 v24, v24, v28
	v_mul_f32_e32 v23, v23, v25
	v_cvt_pk_bf16_f32 v23, v24, v23
	v_lshlrev_b64 v[24:25], 13, v[52:53]
	v_lshl_add_u64 v[24:25], s[92:93], 0, v[24:25]
	v_lshl_add_u64 v[24:25], v[24:25], 0, v[54:55]
	v_lshl_add_u64 v[24:25], v[24:25], 0, v[36:37]
	global_store_dwordx4 v[24:25], v[20:23], off sc1
	s_waitcnt vmcnt(7)
	v_lshlrev_b32_e32 v24, 16, v16
	v_and_b32_e32 v16, 0xffff0000, v16
	v_mul_f32_e32 v25, 0xbfb8aa3b, v24
	v_mul_f32_e32 v26, 0xbfb8aa3b, v16
	v_exp_f32_e32 v25, v25
	v_exp_f32_e32 v26, v26
	v_add_u32_e32 v20, s82, v66
	v_mad_u64_u32 v[20:21], s[0:1], v20, s73, v[44:45]
	ds_read_b128 v[20:23], v20
	v_add_f32_e32 v25, 1.0, v25
	v_add_f32_e32 v26, 1.0, v26
	v_rcp_f32_e32 v25, v25
	v_rcp_f32_e32 v26, v26
	s_waitcnt lgkmcnt(0)
; __device__ __forceinline__ float bflo(unsigned w) { return __uint_as_float(w << 16); }
; __device__ __forceinline__ float bfhi(unsigned w) { return __uint_as_float(w & 0xffff0000u); }
; __device__ __forceinline__ float siluf_(float x) { return x * __builtin_amdgcn_rcpf(1.0f + __expf(-x)); }
; __device__ __forceinline__ unsigned cvtpk(float lo, float hi) { unsigned r; asm volatile("v_cvt_pk_bf16_f32 %0, %1, %2" : "=v"(r) : "v"(lo), "v"(hi)); return r; }
; template <int VAR>
; __device__ __forceinline__ void nsa_attn_mfma(Frame& F, bf16* Y) {
;     ...
; #pragma unroll
;       for (int j = 0; j < 8; ++j) { const int row = 4 * j + (lane >> 4), tt = t0 + 4 * wid + (row >> 3), hh = g * 8 + (row & 7);
;         const v4u tv = *(const v4u*)((const unsigned short*)(lds + AT_K) + (wid * 32 + row) * ROWP + (lane & 15) * 8); const v4u z = zv[j]; v4u y;
;         y.x = cvtpk(bflo(tv.x) * siluf_(bflo(z.x)), bfhi(tv.x) * siluf_(bfhi(z.x))); y.y = cvtpk(bflo(tv.y) * siluf_(bflo(z.y)), bfhi(tv.y) * siluf_(bfhi(z.y)));
;         y.z = cvtpk(bflo(tv.z) * siluf_(bflo(z.z)), bfhi(tv.z) * siluf_(bfhi(z.z))); y.w = cvtpk(bflo(tv.w) * siluf_(bflo(z.w)), bfhi(tv.w) * siluf_(bfhi(z.w)));
;         *(v4u*)(Y + (size_t)(b * SEQ + tt) * DM + hh * 128 + (lane & 15) * 8) = y; }
	v_lshlrev_b32_e32 v27, 16, v20
	v_and_b32_e32 v20, 0xffff0000, v20
	v_mul_f32_e32 v24, v25, v24
	v_mul_f32_e32 v16, v26, v16
	v_mul_f32_e32 v24, v24, v27
	v_mul_f32_e32 v16, v16, v20
	v_lshlrev_b32_e32 v20, 16, v17
	v_and_b32_e32 v17, 0xffff0000, v17
	v_cvt_pk_bf16_f32 v16, v24, v16
	v_mul_f32_e32 v24, 0xbfb8aa3b, v20
	v_mul_f32_e32 v25, 0xbfb8aa3b, v17
	v_exp_f32_e32 v24, v24
	v_exp_f32_e32 v25, v25
	v_lshlrev_b32_e32 v26, 16, v21
	v_and_b32_e32 v21, 0xffff0000, v21
	v_add_f32_e32 v24, 1.0, v24
	v_add_f32_e32 v25, 1.0, v25
	v_rcp_f32_e32 v24, v24
	v_rcp_f32_e32 v25, v25
	v_mul_f32_e32 v20, v24, v20
	v_mul_f32_e32 v17, v25, v17
	v_mul_f32_e32 v20, v20, v26
	v_mul_f32_e32 v17, v17, v21
	v_cvt_pk_bf16_f32 v17, v20, v17
	v_lshlrev_b32_e32 v20, 16, v18
	v_and_b32_e32 v18, 0xffff0000, v18
	v_mul_f32_e32 v21, 0xbfb8aa3b, v20
	v_mul_f32_e32 v24, 0xbfb8aa3b, v18
	v_exp_f32_e32 v21, v21
	v_exp_f32_e32 v24, v24
	v_lshlrev_b32_e32 v25, 16, v22
	v_add_f32_e32 v21, 1.0, v21
	v_add_f32_e32 v24, 1.0, v24
	v_rcp_f32_e32 v21, v21
	v_rcp_f32_e32 v24, v24
	v_mul_f32_e32 v20, v21, v20
	v_and_b32_e32 v21, 0xffff0000, v22
	v_mul_f32_e32 v18, v24, v18
	v_mul_f32_e32 v20, v20, v25
	v_mul_f32_e32 v18, v18, v21
	v_cvt_pk_bf16_f32 v18, v20, v18
	v_lshlrev_b32_e32 v20, 16, v19
	v_and_b32_e32 v19, 0xffff0000, v19
	v_mul_f32_e32 v21, 0xbfb8aa3b, v20
	v_mul_f32_e32 v22, 0xbfb8aa3b, v19
	v_exp_f32_e32 v21, v21
	v_exp_f32_e32 v22, v22
	v_lshlrev_b32_e32 v24, 16, v23
	v_add_f32_e32 v21, 1.0, v21
	v_add_f32_e32 v22, 1.0, v22
	v_rcp_f32_e32 v21, v21
	v_rcp_f32_e32 v22, v22
	v_mul_f32_e32 v20, v21, v20
	v_and_b32_e32 v21, 0xffff0000, v23
	v_mul_f32_e32 v19, v22, v19
	v_mul_f32_e32 v20, v20, v24
	v_mul_f32_e32 v19, v19, v21
	v_cvt_pk_bf16_f32 v19, v20, v19
	v_lshlrev_b64 v[20:21], 13, v[50:51]
	v_lshl_add_u64 v[20:21], s[92:93], 0, v[20:21]
	v_lshl_add_u64 v[20:21], v[20:21], 0, v[2:3]
	v_lshl_add_u64 v[20:21], v[20:21], 0, v[36:37]
	global_store_dwordx4 v[20:21], v[16:19], off sc1
	s_waitcnt vmcnt(7)
	v_lshlrev_b32_e32 v20, 16, v12
	v_and_b32_e32 v12, 0xffff0000, v12
	v_mul_f32_e32 v21, 0xbfb8aa3b, v20
	v_mul_f32_e32 v22, 0xbfb8aa3b, v12
	v_exp_f32_e32 v21, v21
	v_exp_f32_e32 v22, v22
	v_add_u32_e32 v16, s82, v65
	v_mad_u64_u32 v[16:17], s[0:1], v16, s73, v[44:45]
	ds_read_b128 v[16:19], v16
	v_add_f32_e32 v21, 1.0, v21
	v_add_f32_e32 v22, 1.0, v22
	v_rcp_f32_e32 v21, v21
	v_rcp_f32_e32 v22, v22
	s_waitcnt lgkmcnt(0)
	v_lshlrev_b32_e32 v23, 16, v16
	v_and_b32_e32 v16, 0xffff0000, v16
	v_mul_f32_e32 v20, v21, v20
	v_mul_f32_e32 v12, v22, v12
	v_mul_f32_e32 v20, v20, v23
	v_mul_f32_e32 v12, v12, v16
	v_lshlrev_b32_e32 v16, 16, v13
	v_and_b32_e32 v13, 0xffff0000, v13
	v_cvt_pk_bf16_f32 v12, v20, v12
	v_mul_f32_e32 v20, 0xbfb8aa3b, v16
	v_mul_f32_e32 v21, 0xbfb8aa3b, v13
	v_exp_f32_e32 v20, v20
	v_exp_f32_e32 v21, v21
	v_lshlrev_b32_e32 v22, 16, v17
	v_and_b32_e32 v17, 0xffff0000, v17
	v_add_f32_e32 v20, 1.0, v20
	v_add_f32_e32 v21, 1.0, v21
	v_rcp_f32_e32 v20, v20
	v_rcp_f32_e32 v21, v21
	v_mul_f32_e32 v16, v20, v16
	v_mul_f32_e32 v13, v21, v13
	v_mul_f32_e32 v16, v16, v22
	v_mul_f32_e32 v13, v13, v17
	v_cvt_pk_bf16_f32 v13, v16, v13
	v_lshlrev_b32_e32 v16, 16, v14
	v_and_b32_e32 v14, 0xffff0000, v14
	v_mul_f32_e32 v17, 0xbfb8aa3b, v16
	v_mul_f32_e32 v20, 0xbfb8aa3b, v14
	v_exp_f32_e32 v17, v17
	v_exp_f32_e32 v20, v20
	v_lshlrev_b32_e32 v21, 16, v18
	v_add_f32_e32 v17, 1.0, v17
	v_add_f32_e32 v20, 1.0, v20
	v_rcp_f32_e32 v17, v17
	v_rcp_f32_e32 v20, v20
	v_mul_f32_e32 v16, v17, v16
	v_and_b32_e32 v17, 0xffff0000, v18
	v_mul_f32_e32 v14, v20, v14
	v_mul_f32_e32 v16, v16, v21
	v_mul_f32_e32 v14, v14, v17
	v_cvt_pk_bf16_f32 v14, v16, v14
	v_lshlrev_b32_e32 v16, 16, v15
	v_and_b32_e32 v15, 0xffff0000, v15
	v_mul_f32_e32 v17, 0xbfb8aa3b, v16
	v_mul_f32_e32 v18, 0xbfb8aa3b, v15
	v_exp_f32_e32 v17, v17
	v_exp_f32_e32 v18, v18
	v_lshlrev_b32_e32 v20, 16, v19
	v_add_f32_e32 v17, 1.0, v17
	v_add_f32_e32 v18, 1.0, v18
	v_rcp_f32_e32 v17, v17
	v_rcp_f32_e32 v18, v18
	v_mul_f32_e32 v16, v17, v16
	v_and_b32_e32 v17, 0xffff0000, v19
	v_mul_f32_e32 v15, v18, v15
	v_mul_f32_e32 v16, v16, v20
	v_mul_f32_e32 v15, v15, v17
	v_cvt_pk_bf16_f32 v15, v16, v15
	v_lshlrev_b64 v[16:17], 13, v[46:47]
	v_lshl_add_u64 v[16:17], s[92:93], 0, v[16:17]
	v_lshl_add_u64 v[16:17], v[16:17], 0, v[48:49]
	v_lshl_add_u64 v[16:17], v[16:17], 0, v[36:37]
	global_store_dwordx4 v[16:17], v[12:15], off sc1
	s_waitcnt vmcnt(7)
	v_lshlrev_b32_e32 v16, 16, v8
	v_and_b32_e32 v8, 0xffff0000, v8
	v_mul_f32_e32 v17, 0xbfb8aa3b, v16
	v_mul_f32_e32 v18, 0xbfb8aa3b, v8
	v_exp_f32_e32 v17, v17
	v_exp_f32_e32 v18, v18
	v_add_u32_e32 v12, s82, v64
	v_mad_u64_u32 v[12:13], s[0:1], v12, s73, v[44:45]
	ds_read_b128 v[12:15], v12
	v_add_f32_e32 v17, 1.0, v17
	v_add_f32_e32 v18, 1.0, v18
	v_rcp_f32_e32 v17, v17
	v_rcp_f32_e32 v18, v18
	s_waitcnt lgkmcnt(0)
; __device__ __forceinline__ float bflo(unsigned w) { return __uint_as_float(w << 16); }
; __device__ __forceinline__ float bfhi(unsigned w) { return __uint_as_float(w & 0xffff0000u); }
; __device__ __forceinline__ float siluf_(float x) { return x * __builtin_amdgcn_rcpf(1.0f + __expf(-x)); }
; __device__ __forceinline__ unsigned cvtpk(float lo, float hi) { unsigned r; asm volatile("v_cvt_pk_bf16_f32 %0, %1, %2" : "=v"(r) : "v"(lo), "v"(hi)); return r; }
; template <int VAR>
; __device__ __forceinline__ void nsa_attn_mfma(Frame& F, bf16* Y) {
;     ...
; #pragma unroll
;       for (int j = 0; j < 8; ++j) { const int row = 4 * j + (lane >> 4), tt = t0 + 4 * wid + (row >> 3), hh = g * 8 + (row & 7);
;         const v4u tv = *(const v4u*)((const unsigned short*)(lds + AT_K) + (wid * 32 + row) * ROWP + (lane & 15) * 8); const v4u z = zv[j]; v4u y;
;         y.x = cvtpk(bflo(tv.x) * siluf_(bflo(z.x)), bfhi(tv.x) * siluf_(bfhi(z.x))); y.y = cvtpk(bflo(tv.y) * siluf_(bflo(z.y)), bfhi(tv.y) * siluf_(bfhi(z.y)));
;         y.z = cvtpk(bflo(tv.z) * siluf_(bflo(z.z)), bfhi(tv.z) * siluf_(bfhi(z.z))); y.w = cvtpk(bflo(tv.w) * siluf_(bflo(z.w)), bfhi(tv.w) * siluf_(bfhi(z.w)));
;         *(v4u*)(Y + (size_t)(b * SEQ + tt) * DM + hh * 128 + (lane & 15) * 8) = y; }
	v_lshlrev_b32_e32 v19, 16, v12
	v_and_b32_e32 v12, 0xffff0000, v12
	v_mul_f32_e32 v16, v17, v16
	v_mul_f32_e32 v8, v18, v8
	v_mul_f32_e32 v16, v16, v19
	v_mul_f32_e32 v8, v8, v12
	v_lshlrev_b32_e32 v12, 16, v9
	v_and_b32_e32 v9, 0xffff0000, v9
	v_cvt_pk_bf16_f32 v8, v16, v8
	v_mul_f32_e32 v16, 0xbfb8aa3b, v12
	v_mul_f32_e32 v17, 0xbfb8aa3b, v9
	v_exp_f32_e32 v16, v16
	v_exp_f32_e32 v17, v17
	v_lshlrev_b32_e32 v18, 16, v13
	v_and_b32_e32 v13, 0xffff0000, v13
	v_add_f32_e32 v16, 1.0, v16
	v_add_f32_e32 v17, 1.0, v17
	v_rcp_f32_e32 v16, v16
	v_rcp_f32_e32 v17, v17
	v_mul_f32_e32 v12, v16, v12
	v_mul_f32_e32 v9, v17, v9
	v_mul_f32_e32 v12, v12, v18
	v_mul_f32_e32 v9, v9, v13
	v_cvt_pk_bf16_f32 v9, v12, v9
	v_lshlrev_b32_e32 v12, 16, v10
	v_and_b32_e32 v10, 0xffff0000, v10
	v_mul_f32_e32 v13, 0xbfb8aa3b, v12
	v_mul_f32_e32 v16, 0xbfb8aa3b, v10
	v_exp_f32_e32 v13, v13
	v_exp_f32_e32 v16, v16
	v_lshlrev_b32_e32 v17, 16, v14
	v_add_f32_e32 v13, 1.0, v13
	v_add_f32_e32 v16, 1.0, v16
	v_rcp_f32_e32 v13, v13
	v_rcp_f32_e32 v16, v16
	v_mul_f32_e32 v12, v13, v12
	v_and_b32_e32 v13, 0xffff0000, v14
	v_mul_f32_e32 v10, v16, v10
	v_mul_f32_e32 v12, v12, v17
	v_mul_f32_e32 v10, v10, v13
	v_cvt_pk_bf16_f32 v10, v12, v10
	v_lshlrev_b32_e32 v12, 16, v11
	v_and_b32_e32 v11, 0xffff0000, v11
	v_mul_f32_e32 v13, 0xbfb8aa3b, v12
	v_mul_f32_e32 v14, 0xbfb8aa3b, v11
	v_exp_f32_e32 v13, v13
	v_exp_f32_e32 v14, v14
	v_lshlrev_b32_e32 v16, 16, v15
	v_add_f32_e32 v13, 1.0, v13
	v_add_f32_e32 v14, 1.0, v14
	v_rcp_f32_e32 v13, v13
	v_rcp_f32_e32 v14, v14
	v_mul_f32_e32 v12, v13, v12
	v_and_b32_e32 v13, 0xffff0000, v15
	v_mul_f32_e32 v11, v14, v11
	v_mul_f32_e32 v12, v12, v16
	v_mul_f32_e32 v11, v11, v13
	v_cvt_pk_bf16_f32 v11, v12, v11
	v_lshlrev_b64 v[12:13], 13, v[42:43]
	v_lshl_add_u64 v[12:13], s[92:93], 0, v[12:13]
	v_lshl_add_u64 v[12:13], v[12:13], 0, v[2:3]
	v_lshl_add_u64 v[12:13], v[12:13], 0, v[36:37]
	v_add_u32_e32 v2, s82, v45
	global_store_dwordx4 v[12:13], v[8:11], off sc1
	s_nop 1
	v_mad_u64_u32 v[8:9], s[0:1], v2, s73, v[44:45]
	s_waitcnt vmcnt(7)
	v_lshlrev_b32_e32 v2, 16, v4
	v_and_b32_e32 v4, 0xffff0000, v4
	v_mul_f32_e32 v12, 0xbfb8aa3b, v2
	v_mul_f32_e32 v13, 0xbfb8aa3b, v4
	v_exp_f32_e32 v12, v12
	v_exp_f32_e32 v13, v13
	ds_read_b128 v[8:11], v8
	s_and_b32 s0, s80, 0x80000003
	v_add_f32_e32 v12, 1.0, v12
	v_add_f32_e32 v13, 1.0, v13
	v_rcp_f32_e32 v12, v12
	v_rcp_f32_e32 v13, v13
	s_waitcnt lgkmcnt(0)
	v_lshlrev_b32_e32 v14, 16, v8
	v_and_b32_e32 v8, 0xffff0000, v8
	v_mul_f32_e32 v2, v12, v2
	v_mul_f32_e32 v4, v13, v4
	v_mul_f32_e32 v2, v2, v14
	v_mul_f32_e32 v4, v4, v8
	v_cvt_pk_bf16_f32 v4, v2, v4
	v_lshlrev_b32_e32 v2, 16, v5
	v_and_b32_e32 v5, 0xffff0000, v5
	v_mul_f32_e32 v8, 0xbfb8aa3b, v2
	v_mul_f32_e32 v12, 0xbfb8aa3b, v5
	v_exp_f32_e32 v8, v8
	v_exp_f32_e32 v12, v12
	v_lshlrev_b32_e32 v13, 16, v9
	s_cmp_eq_u32 s0, 3
	v_add_f32_e32 v8, 1.0, v8
	v_add_f32_e32 v12, 1.0, v12
	v_rcp_f32_e32 v8, v8
	v_rcp_f32_e32 v12, v12
	v_readlane_b32 s0, v254, 40
	s_cselect_b32 s0, s0, 1
	v_mul_f32_e32 v2, v8, v2
	v_and_b32_e32 v8, 0xffff0000, v9
	v_mul_f32_e32 v5, v12, v5
	v_mul_f32_e32 v2, v2, v13
	v_mul_f32_e32 v5, v5, v8
	v_cvt_pk_bf16_f32 v5, v2, v5
	v_lshlrev_b32_e32 v2, 16, v6
	v_and_b32_e32 v6, 0xffff0000, v6
	v_mul_f32_e32 v8, 0xbfb8aa3b, v2
	v_mul_f32_e32 v9, 0xbfb8aa3b, v6
	v_exp_f32_e32 v8, v8
	v_exp_f32_e32 v9, v9
	v_lshlrev_b32_e32 v12, 16, v10
	s_add_i32 s80, s0, s80
	v_add_f32_e32 v8, 1.0, v8
	v_add_f32_e32 v9, 1.0, v9
	v_rcp_f32_e32 v8, v8
	v_rcp_f32_e32 v9, v9
	s_cmpk_lt_i32 s80, 0x400
	v_mul_f32_e32 v2, v8, v2
	v_and_b32_e32 v8, 0xffff0000, v10
	v_mul_f32_e32 v6, v9, v6
	v_mul_f32_e32 v2, v2, v12
	v_mul_f32_e32 v6, v6, v8
	v_cvt_pk_bf16_f32 v6, v2, v6
	v_lshlrev_b32_e32 v2, 16, v7
	v_and_b32_e32 v7, 0xffff0000, v7
	v_mul_f32_e32 v8, 0xbfb8aa3b, v2
	v_mul_f32_e32 v9, 0xbfb8aa3b, v7
	v_exp_f32_e32 v8, v8
	v_exp_f32_e32 v9, v9
	v_lshlrev_b32_e32 v10, 16, v11
	v_add_f32_e32 v8, 1.0, v8
	v_add_f32_e32 v9, 1.0, v9
	v_rcp_f32_e32 v8, v8
	v_rcp_f32_e32 v9, v9
	v_mul_f32_e32 v2, v8, v2
	v_and_b32_e32 v8, 0xffff0000, v11
	v_mul_f32_e32 v7, v9, v7
	v_mul_f32_e32 v7, v7, v8
	v_lshlrev_b64 v[8:9], 13, v[38:39]
	v_lshl_add_u64 v[8:9], s[92:93], 0, v[8:9]
	v_lshl_add_u64 v[8:9], v[8:9], 0, v[40:41]
	v_lshl_add_u64 v[8:9], v[8:9], 0, v[36:37]
	v_mul_f32_e32 v2, v2, v10
	v_cvt_pk_bf16_f32 v7, v2, v7
	global_store_dwordx4 v[8:9], v[4:7], off sc1
	s_cbranch_scc0 .LBB0_897

; __device__ __forceinline__ unsigned cvt_pk_bf16(float lo, float hi) { unsigned r; asm volatile("v_cvt_pk_bf16_f32 %0, %1, %2" : "=v"(r) : "v"(lo), "v"(hi)); return r; }
;     __device__ __forceinline__ void operator()(const f32x4 (&acc)[2][2][4][2], const Unit& u, int wr, int wc, int fr, int fq) const {
;     ...
;             for (int m = 0; m < 4; ++m) { bf16_t* rowp = base + (size_t)(row0 + ai * HALF + m * 16) * ldc + col0;
; #pragma unroll
;                 for (int bj = 0; bj < 2; ++bj) { f32x4 v0 = acc[ai][bj][m][0] + bv[bj][0], v1 = acc[ai][bj][m][1] + bv[bj][1];
;                     if (ACT == 1) { f32x2 a = gelu_pk((f32x2){v0[0], v0[1]}), b = gelu_pk((f32x2){v0[2], v0[3]}), c = gelu_pk((f32x2){v1[0], v1[1]}), d = gelu_pk((f32x2){v1[2], v1[3]});
;                         v0 = (f32x4){a.x, a.y, b.x, b.y}; v1 = (f32x4){c.x, c.y, d.x, d.y}; }
;                     v0 = v0 * sc; v1 = v1 * sc; u32x4 w; w.x = cvt_pk_bf16(v0[0], v0[1]); w.y = cvt_pk_bf16(v0[2], v0[3]); w.z = cvt_pk_bf16(v1[0], v1[1]); w.w = cvt_pk_bf16(v1[2], v1[3]);
;                     *(u32x4*)(rowp + bj * HALF) = w; } }
.LBB0_969:
	v_lshl_add_u32 v154, s28, 8, v1
	v_lshl_or_b32 v146, s56, 8, v149
	v_ashrrev_i32_e32 v147, 31, v146
	v_ashrrev_i32_e32 v155, 31, v154
	v_lshl_add_u64 v[156:157], v[146:147], 1, s[8:9]
	v_lshlrev_b64 v[146:147], 13, v[154:155]
	v_lshl_add_u64 v[146:147], v[156:157], 0, v[146:147]
	v_pk_add_f32 v[128:129], v[128:129], 0 op_sel_hi:[1,0]
	v_pk_add_f32 v[126:127], v[126:127], 0 op_sel_hi:[1,0]
	v_pk_add_f32 v[158:159], v[124:125], 0 op_sel_hi:[1,0]
	v_pk_add_f32 v[124:125], v[122:123], 0 op_sel_hi:[1,0]
	v_cvt_pk_bf16_f32 v122, v126, v127
	v_cvt_pk_bf16_f32 v123, v128, v129
	v_pk_add_f32 v[118:119], v[118:119], 0 op_sel_hi:[1,0]
	v_cvt_pk_bf16_f32 v124, v124, v125
	v_cvt_pk_bf16_f32 v125, v158, v159
	global_store_dwordx4 v[146:147], v[122:125], off sc1
	v_pk_add_f32 v[120:121], v[120:121], 0 op_sel_hi:[1,0]
	v_pk_add_f32 v[114:115], v[114:115], 0 op_sel_hi:[1,0]
	v_pk_add_f32 v[122:123], v[112:113], 0 op_sel_hi:[1,0]
	v_pk_add_f32 v[112:113], v[110:111], 0 op_sel_hi:[1,0]
	v_cvt_pk_bf16_f32 v110, v118, v119
	v_cvt_pk_bf16_f32 v111, v120, v121
	v_pk_add_f32 v[102:103], v[102:103], 0 op_sel_hi:[1,0]
	v_cvt_pk_bf16_f32 v112, v112, v113
	v_cvt_pk_bf16_f32 v113, v122, v123
	global_store_dwordx4 v[146:147], v[110:113], off offset:256 sc1
	v_pk_add_f32 v[104:105], v[104:105], 0 op_sel_hi:[1,0]
	v_pk_add_f32 v[98:99], v[98:99], 0 op_sel_hi:[1,0]
	v_or_b32_e32 v110, 16, v154
	v_ashrrev_i32_e32 v111, 31, v110
	v_lshlrev_b64 v[110:111], 13, v[110:111]
	v_lshl_add_u64 v[110:111], v[156:157], 0, v[110:111]
	v_pk_add_f32 v[112:113], v[116:117], 0 op_sel_hi:[1,0]
	v_pk_add_f32 v[116:117], v[108:109], 0 op_sel_hi:[1,0]
	v_pk_add_f32 v[108:109], v[106:107], 0 op_sel_hi:[1,0]
	v_cvt_pk_bf16_f32 v106, v114, v115
	v_cvt_pk_bf16_f32 v107, v112, v113
	v_pk_add_f32 v[86:87], v[86:87], 0 op_sel_hi:[1,0]
	v_cvt_pk_bf16_f32 v108, v108, v109
	v_cvt_pk_bf16_f32 v109, v116, v117
	global_store_dwordx4 v[110:111], v[106:109], off sc1
	v_pk_add_f32 v[88:89], v[88:89], 0 op_sel_hi:[1,0]
	v_pk_add_f32 v[82:83], v[82:83], 0 op_sel_hi:[1,0]
	v_pk_add_f32 v[106:107], v[96:97], 0 op_sel_hi:[1,0]
	v_pk_add_f32 v[96:97], v[94:95], 0 op_sel_hi:[1,0]
	v_cvt_pk_bf16_f32 v94, v102, v103
	v_cvt_pk_bf16_f32 v95, v104, v105
	v_pk_add_f32 v[72:73], v[72:73], 0 op_sel_hi:[1,0]
	v_cvt_pk_bf16_f32 v96, v96, v97
	v_cvt_pk_bf16_f32 v97, v106, v107
	global_store_dwordx4 v[110:111], v[94:97], off offset:256 sc1
	v_pk_add_f32 v[70:71], v[70:71], 0 op_sel_hi:[1,0]
	v_pk_add_f32 v[62:63], v[62:63], 0 op_sel_hi:[1,0]
	v_or_b32_e32 v94, 32, v154
	v_ashrrev_i32_e32 v95, 31, v94
	v_lshlrev_b64 v[94:95], 13, v[94:95]
	v_lshl_add_u64 v[94:95], v[156:157], 0, v[94:95]
	v_pk_add_f32 v[96:97], v[100:101], 0 op_sel_hi:[1,0]
	v_pk_add_f32 v[100:101], v[92:93], 0 op_sel_hi:[1,0]
	v_pk_add_f32 v[92:93], v[90:91], 0 op_sel_hi:[1,0]
	v_cvt_pk_bf16_f32 v90, v98, v99
	v_cvt_pk_bf16_f32 v91, v96, v97
	v_pk_add_f32 v[64:65], v[64:65], 0 op_sel_hi:[1,0]
	v_cvt_pk_bf16_f32 v92, v92, v93
	v_cvt_pk_bf16_f32 v93, v100, v101
	global_store_dwordx4 v[94:95], v[90:93], off sc1
	v_pk_add_f32 v[56:57], v[56:57], 0 op_sel_hi:[1,0]
	v_pk_add_f32 v[54:55], v[54:55], 0 op_sel_hi:[1,0]
	v_pk_add_f32 v[90:91], v[80:81], 0 op_sel_hi:[1,0]
	v_pk_add_f32 v[80:81], v[78:79], 0 op_sel_hi:[1,0]
	v_cvt_pk_bf16_f32 v78, v86, v87
	v_cvt_pk_bf16_f32 v79, v88, v89
	v_pk_add_f32 v[50:51], v[50:51], 0 op_sel_hi:[1,0]
	v_cvt_pk_bf16_f32 v80, v80, v81
	v_cvt_pk_bf16_f32 v81, v90, v91
	global_store_dwordx4 v[94:95], v[78:81], off offset:256 sc1
	v_pk_add_f32 v[40:41], v[40:41], 0 op_sel_hi:[1,0]
	v_pk_add_f32 v[38:39], v[38:39], 0 op_sel_hi:[1,0]
	v_or_b32_e32 v78, 48, v154
	v_ashrrev_i32_e32 v79, 31, v78
	v_lshlrev_b64 v[78:79], 13, v[78:79]
	v_lshl_add_u64 v[78:79], v[156:157], 0, v[78:79]
	v_pk_add_f32 v[80:81], v[84:85], 0 op_sel_hi:[1,0]
	v_pk_add_f32 v[84:85], v[76:77], 0 op_sel_hi:[1,0]
	v_pk_add_f32 v[76:77], v[74:75], 0 op_sel_hi:[1,0]
	v_cvt_pk_bf16_f32 v74, v82, v83
	v_cvt_pk_bf16_f32 v75, v80, v81
; __device__ __forceinline__ unsigned cvt_pk_bf16(float lo, float hi) { unsigned r; asm volatile("v_cvt_pk_bf16_f32 %0, %1, %2" : "=v"(r) : "v"(lo), "v"(hi)); return r; }
;     __device__ __forceinline__ void operator()(const f32x4 (&acc)[2][2][4][2], const Unit& u, int wr, int wc, int fr, int fq) const {
;     ...
;             for (int m = 0; m < 4; ++m) { bf16_t* rowp = base + (size_t)(row0 + ai * HALF + m * 16) * ldc + col0;
; #pragma unroll
;                 for (int bj = 0; bj < 2; ++bj) { f32x4 v0 = acc[ai][bj][m][0] + bv[bj][0], v1 = acc[ai][bj][m][1] + bv[bj][1];
;                     if (ACT == 1) { f32x2 a = gelu_pk((f32x2){v0[0], v0[1]}), b = gelu_pk((f32x2){v0[2], v0[3]}), c = gelu_pk((f32x2){v1[0], v1[1]}), d = gelu_pk((f32x2){v1[2], v1[3]});
;                         v0 = (f32x4){a.x, a.y, b.x, b.y}; v1 = (f32x4){c.x, c.y, d.x, d.y}; }
;                     v0 = v0 * sc; v1 = v1 * sc; u32x4 w; w.x = cvt_pk_bf16(v0[0], v0[1]); w.y = cvt_pk_bf16(v0[2], v0[3]); w.z = cvt_pk_bf16(v1[0], v1[1]); w.w = cvt_pk_bf16(v1[2], v1[3]);
;                     *(u32x4*)(rowp + bj * HALF) = w; } }
	v_pk_add_f32 v[34:35], v[34:35], 0 op_sel_hi:[1,0]
	v_cvt_pk_bf16_f32 v76, v76, v77
	v_cvt_pk_bf16_f32 v77, v84, v85
	global_store_dwordx4 v[78:79], v[74:77], off sc1
	v_pk_add_f32 v[24:25], v[24:25], 0 op_sel_hi:[1,0]
	v_pk_add_f32 v[22:23], v[22:23], 0 op_sel_hi:[1,0]
	v_pk_add_f32 v[74:75], v[68:69], 0 op_sel_hi:[1,0]
	v_pk_add_f32 v[68:69], v[66:67], 0 op_sel_hi:[1,0]
	v_cvt_pk_bf16_f32 v66, v70, v71
	v_cvt_pk_bf16_f32 v67, v72, v73
	v_pk_add_f32 v[18:19], v[18:19], 0 op_sel_hi:[1,0]
	v_cvt_pk_bf16_f32 v68, v68, v69
	v_cvt_pk_bf16_f32 v69, v74, v75
	global_store_dwordx4 v[78:79], v[66:69], off offset:256 sc1
	v_pk_add_f32 v[8:9], v[8:9], 0 op_sel_hi:[1,0]
	v_pk_add_f32 v[6:7], v[6:7], 0 op_sel_hi:[1,0]
	v_pk_add_f32 v[68:69], v[60:61], 0 op_sel_hi:[1,0]
	v_pk_add_f32 v[60:61], v[58:59], 0 op_sel_hi:[1,0]
	v_cvt_pk_bf16_f32 v58, v62, v63
	v_add_co_u32_e32 v62, vcc, s52, v146
	v_cvt_pk_bf16_f32 v59, v64, v65
	v_cvt_pk_bf16_f32 v60, v60, v61
	v_cvt_pk_bf16_f32 v61, v68, v69
	v_lshl_add_u64 v[66:67], v[146:147], 0, s[4:5]
	s_nop 0
	v_addc_co_u32_e32 v63, vcc, 0, v147, vcc
	global_store_dwordx4 v[62:63], v[58:61], off sc1
	s_nop 1
	v_pk_add_f32 v[58:59], v[48:49], 0 op_sel_hi:[1,0]
	v_pk_add_f32 v[48:49], v[46:47], 0 op_sel_hi:[1,0]
	v_cvt_pk_bf16_f32 v46, v54, v55
	v_cvt_pk_bf16_f32 v47, v56, v57
	s_nop 0
	v_cvt_pk_bf16_f32 v48, v48, v49
	v_cvt_pk_bf16_f32 v49, v58, v59
	global_store_dwordx4 v[66:67], v[46:49], off offset:256 sc1
	s_nop 1
	v_pk_add_f32 v[48:49], v[52:53], 0 op_sel_hi:[1,0]
	v_pk_add_f32 v[52:53], v[44:45], 0 op_sel_hi:[1,0]
	v_pk_add_f32 v[44:45], v[42:43], 0 op_sel_hi:[1,0]
	v_cvt_pk_bf16_f32 v42, v50, v51
	v_cvt_pk_bf16_f32 v43, v48, v49
	v_add_co_u32_e32 v48, vcc, s53, v146
	v_cvt_pk_bf16_f32 v44, v44, v45
	v_cvt_pk_bf16_f32 v45, v52, v53
	v_lshl_add_u64 v[46:47], v[146:147], 0, s[14:15]
	s_nop 0
	v_addc_co_u32_e32 v49, vcc, 0, v147, vcc
	global_store_dwordx4 v[48:49], v[42:45], off sc1
	s_nop 1
	v_pk_add_f32 v[42:43], v[32:33], 0 op_sel_hi:[1,0]
	v_pk_add_f32 v[32:33], v[30:31], 0 op_sel_hi:[1,0]
	v_cvt_pk_bf16_f32 v30, v38, v39
	v_cvt_pk_bf16_f32 v31, v40, v41
	s_nop 0
	v_cvt_pk_bf16_f32 v32, v32, v33
	v_cvt_pk_bf16_f32 v33, v42, v43
	global_store_dwordx4 v[46:47], v[30:33], off offset:256 sc1
	s_nop 1
	v_pk_add_f32 v[32:33], v[36:37], 0 op_sel_hi:[1,0]
	v_pk_add_f32 v[36:37], v[28:29], 0 op_sel_hi:[1,0]
	v_pk_add_f32 v[28:29], v[26:27], 0 op_sel_hi:[1,0]
	v_cvt_pk_bf16_f32 v26, v34, v35
	v_cvt_pk_bf16_f32 v27, v32, v33
	v_add_co_u32_e32 v32, vcc, s54, v146
	v_cvt_pk_bf16_f32 v28, v28, v29
	v_cvt_pk_bf16_f32 v29, v36, v37
	v_lshl_add_u64 v[30:31], v[146:147], 0, s[16:17]
	s_nop 0
	v_addc_co_u32_e32 v33, vcc, 0, v147, vcc
	global_store_dwordx4 v[32:33], v[26:29], off sc1
	s_nop 1
	v_pk_add_f32 v[26:27], v[16:17], 0 op_sel_hi:[1,0]
	v_pk_add_f32 v[16:17], v[14:15], 0 op_sel_hi:[1,0]
	v_cvt_pk_bf16_f32 v14, v22, v23
	v_cvt_pk_bf16_f32 v15, v24, v25
	s_nop 0
	v_cvt_pk_bf16_f32 v16, v16, v17
	v_cvt_pk_bf16_f32 v17, v26, v27
	global_store_dwordx4 v[30:31], v[14:17], off offset:256 sc1
	s_nop 1
	v_pk_add_f32 v[16:17], v[20:21], 0 op_sel_hi:[1,0]
	v_pk_add_f32 v[20:21], v[12:13], 0 op_sel_hi:[1,0]
	v_pk_add_f32 v[12:13], v[10:11], 0 op_sel_hi:[1,0]
	v_cvt_pk_bf16_f32 v10, v18, v19
	v_cvt_pk_bf16_f32 v11, v16, v17
	v_add_co_u32_e32 v16, vcc, s55, v146
	v_lshl_add_u64 v[14:15], v[146:147], 0, s[18:19]
	s_nop 0
	v_addc_co_u32_e32 v17, vcc, 0, v147, vcc
	v_cvt_pk_bf16_f32 v12, v12, v13
	v_cvt_pk_bf16_f32 v13, v20, v21
	global_store_dwordx4 v[16:17], v[10:13], off sc1
	s_andn2_b64 vcc, exec, s[2:3]
	s_mov_b64 s[2:3], -1
	v_pk_add_f32 v[10:11], v[4:5], 0 op_sel_hi:[1,0]
	v_pk_add_f32 v[4:5], v[2:3], 0 op_sel_hi:[1,0]
	v_cvt_pk_bf16_f32 v2, v6, v7
	v_cvt_pk_bf16_f32 v3, v8, v9
	s_nop 0
	v_cvt_pk_bf16_f32 v4, v4, v5
	v_cvt_pk_bf16_f32 v5, v10, v11
	global_store_dwordx4 v[14:15], v[2:5], off offset:256 sc1
	s_cbranch_vccnz .LBB0_958
	s_andn2_b64 vcc, exec, s[6:7]
	s_cbranch_vccnz .LBB0_957
	s_barrier
	s_branch .LBB0_957

; __device__ __forceinline__ unsigned cvt_pk_bf16(float lo, float hi) { unsigned r; asm volatile("v_cvt_pk_bf16_f32 %0, %1, %2" : "=v"(r) : "v"(lo), "v"(hi)); return r; }
;     __device__ __forceinline__ void operator()(const f32x4 (&acc)[2][2][4][2], const Unit& u, int wr, int wc, int fr, int fq) const {
;         const int row0 = u.pm * BM + wr * 64 + fr, col0 = u.pn * BM + wc * 32 + 8 * fq;
;         float scv[2][4];
; #pragma unroll
;         for (int ai = 0; ai < 2; ++ai)
; #pragma unroll
;             for (int m = 0; m < 4; ++m) scv[ai][m] = rs[row0 + ai * HALF + m * 16];
; #pragma unroll
;         for (int ai = 0; ai < 2; ++ai)
; #pragma unroll
;             for (int m = 0; m < 4; ++m) { const int row = row0 + ai * HALF + m * 16; const float sc = scv[ai][m]; bf16_t* rowp = O + (size_t)row * ldc + col0;
; #pragma unroll
;                 for (int bj = 0; bj < 2; ++bj) { const f32x4 v0 = acc[ai][bj][m][0] * sc, v1 = acc[ai][bj][m][1] * sc;
;                     u32x4 w; w.x = cvt_pk_bf16(v0[0], v0[1]); w.y = cvt_pk_bf16(v0[2], v0[3]); w.z = cvt_pk_bf16(v1[0], v1[1]); w.w = cvt_pk_bf16(v1[2], v1[3]);
;                     *(u32x4*)(rowp + bj * HALF) = w; } }
.LBB0_1100:
	v_lshl_add_u32 v148, s30, 8, v1
	v_ashrrev_i32_e32 v149, 31, v148
	v_or_b32_e32 v160, 16, v148
	v_or_b32_e32 v164, 32, v148
	v_lshl_add_u64 v[156:157], v[148:149], 2, s[8:9]
	v_ashrrev_i32_e32 v161, 31, v160
	v_ashrrev_i32_e32 v165, 31, v164
	global_load_dword v158, v[156:157], off
	v_lshl_add_u64 v[162:163], v[160:161], 2, s[8:9]
	v_lshl_add_u64 v[166:167], v[164:165], 2, s[8:9]
	global_load_dword v162, v[162:163], off
	v_or_b32_e32 v168, 48, v148
	global_load_dword v166, v[166:167], off
	v_ashrrev_i32_e32 v169, 31, v168
	v_lshl_add_u64 v[170:171], v[168:169], 2, s[8:9]
	global_load_dword v150, v[170:171], off
	global_load_dword v172, v[156:157], off offset:512
	global_load_dword v174, v[156:157], off offset:576
	global_load_dword v152, v[156:157], off offset:640
	global_load_dword v146, v[156:157], off offset:704
	v_lshl_or_b32 v170, s58, 8, v151
	v_ashrrev_i32_e32 v171, 31, v170
	v_lshlrev_b64 v[148:149], 14, v[148:149]
	v_lshlrev_b64 v[170:171], 1, v[170:171]
	v_lshl_add_u64 v[148:149], s[6:7], 0, v[148:149]
	v_lshlrev_b64 v[160:161], 14, v[160:161]
	v_lshlrev_b64 v[164:165], 14, v[164:165]
	v_lshlrev_b64 v[168:169], 14, v[168:169]
	v_lshl_add_u64 v[148:149], v[148:149], 0, v[170:171]
	v_lshl_add_u64 v[156:157], s[6:7], 0, v[160:161]
	v_lshl_add_u64 v[160:161], s[6:7], 0, v[164:165]
	v_lshl_add_u64 v[164:165], s[6:7], 0, v[168:169]
	v_lshl_add_u64 v[156:157], v[156:157], 0, v[170:171]
	v_lshl_add_u64 v[160:161], v[160:161], 0, v[170:171]
	v_lshl_add_u64 v[164:165], v[164:165], 0, v[170:171]
	s_waitcnt vmcnt(0)
	v_pk_mul_f32 v[124:125], v[124:125], v[158:159] op_sel_hi:[1,0]
	v_pk_mul_f32 v[128:129], v[128:129], v[158:159] op_sel_hi:[1,0]
	v_pk_mul_f32 v[126:127], v[126:127], v[158:159] op_sel_hi:[1,0]
	v_pk_mul_f32 v[122:123], v[122:123], v[158:159] op_sel_hi:[1,0]
	v_pk_mul_f32 v[108:109], v[108:109], v[158:159] op_sel_hi:[1,0]
	v_pk_mul_f32 v[106:107], v[106:107], v[158:159] op_sel_hi:[1,0]
	v_pk_mul_f32 v[168:169], v[100:101], v[158:159] op_sel_hi:[1,0]
	v_pk_mul_f32 v[158:159], v[98:99], v[158:159] op_sel_hi:[1,0]
	v_cvt_pk_bf16_f32 v98, v126, v127
	v_cvt_pk_bf16_f32 v99, v128, v129
	v_cvt_pk_bf16_f32 v100, v122, v123
	v_cvt_pk_bf16_f32 v101, v124, v125
	v_pk_mul_f32 v[124:125], v[78:79], v[166:167] op_sel_hi:[1,0]
	global_store_dwordx4 v[148:149], v[98:101], off sc1
	v_cvt_pk_bf16_f32 v78, v106, v107
	v_cvt_pk_bf16_f32 v79, v108, v109
	v_pk_mul_f32 v[120:121], v[120:121], v[162:163] op_sel_hi:[1,0]
	v_pk_mul_f32 v[118:119], v[118:119], v[162:163] op_sel_hi:[1,0]
	v_pk_mul_f32 v[122:123], v[80:81], v[166:167] op_sel_hi:[1,0]
	v_cvt_pk_bf16_f32 v80, v158, v159
	v_cvt_pk_bf16_f32 v81, v168, v169
	global_store_dwordx4 v[148:149], v[78:81], off offset:256 sc1
	v_pk_mul_f32 v[116:117], v[116:117], v[162:163] op_sel_hi:[1,0]
	v_pk_mul_f32 v[114:115], v[114:115], v[162:163] op_sel_hi:[1,0]
	v_cvt_pk_bf16_f32 v78, v118, v119
	v_cvt_pk_bf16_f32 v79, v120, v121
	v_pk_mul_f32 v[92:93], v[92:93], v[162:163] op_sel_hi:[1,0]
	v_pk_mul_f32 v[90:91], v[90:91], v[162:163] op_sel_hi:[1,0]
	v_cvt_pk_bf16_f32 v80, v114, v115
	v_cvt_pk_bf16_f32 v81, v116, v117
	global_store_dwordx4 v[156:157], v[78:81], off sc1
	v_pk_mul_f32 v[88:89], v[88:89], v[162:163] op_sel_hi:[1,0]
	v_pk_mul_f32 v[86:87], v[86:87], v[162:163] op_sel_hi:[1,0]
	v_cvt_pk_bf16_f32 v78, v90, v91
	v_cvt_pk_bf16_f32 v79, v92, v93
	v_pk_mul_f32 v[112:113], v[112:113], v[166:167] op_sel_hi:[1,0]
	v_pk_mul_f32 v[110:111], v[110:111], v[166:167] op_sel_hi:[1,0]
	v_cvt_pk_bf16_f32 v80, v86, v87
	v_cvt_pk_bf16_f32 v81, v88, v89
	global_store_dwordx4 v[156:157], v[78:81], off offset:256 sc1
	v_pk_mul_f32 v[104:105], v[104:105], v[166:167] op_sel_hi:[1,0]
	v_pk_mul_f32 v[102:103], v[102:103], v[166:167] op_sel_hi:[1,0]
	v_cvt_pk_bf16_f32 v78, v110, v111
	v_cvt_pk_bf16_f32 v79, v112, v113
	v_pk_mul_f32 v[84:85], v[84:85], v[166:167] op_sel_hi:[1,0]
	v_pk_mul_f32 v[82:83], v[82:83], v[166:167] op_sel_hi:[1,0]
	v_cvt_pk_bf16_f32 v80, v102, v103
	v_cvt_pk_bf16_f32 v81, v104, v105
	global_store_dwordx4 v[160:161], v[78:81], off sc1
	v_pk_mul_f32 v[96:97], v[96:97], v[150:151] op_sel_hi:[1,0]
	v_pk_mul_f32 v[94:95], v[94:95], v[150:151] op_sel_hi:[1,0]
	v_cvt_pk_bf16_f32 v78, v82, v83
	v_cvt_pk_bf16_f32 v79, v84, v85
	v_cvt_pk_bf16_f32 v80, v124, v125
	v_cvt_pk_bf16_f32 v81, v122, v123
	global_store_dwordx4 v[160:161], v[78:81], off offset:256 sc1
	v_pk_mul_f32 v[72:73], v[72:73], v[150:151] op_sel_hi:[1,0]
	v_pk_mul_f32 v[70:71], v[70:71], v[150:151] op_sel_hi:[1,0]
	v_pk_mul_f32 v[78:79], v[76:77], v[150:151] op_sel_hi:[1,0]
	v_pk_mul_f32 v[76:77], v[74:75], v[150:151] op_sel_hi:[1,0]
	v_cvt_pk_bf16_f32 v74, v94, v95
; __device__ __forceinline__ unsigned cvt_pk_bf16(float lo, float hi) { unsigned r; asm volatile("v_cvt_pk_bf16_f32 %0, %1, %2" : "=v"(r) : "v"(lo), "v"(hi)); return r; }
;     __device__ __forceinline__ void operator()(const f32x4 (&acc)[2][2][4][2], const Unit& u, int wr, int wc, int fr, int fq) const {
;     ...
;             for (int m = 0; m < 4; ++m) { const int row = row0 + ai * HALF + m * 16; const float sc = scv[ai][m]; bf16_t* rowp = O + (size_t)row * ldc + col0;
; #pragma unroll
;                 for (int bj = 0; bj < 2; ++bj) { const f32x4 v0 = acc[ai][bj][m][0] * sc, v1 = acc[ai][bj][m][1] * sc;
;                     u32x4 w; w.x = cvt_pk_bf16(v0[0], v0[1]); w.y = cvt_pk_bf16(v0[2], v0[3]); w.z = cvt_pk_bf16(v1[0], v1[1]); w.w = cvt_pk_bf16(v1[2], v1[3]);
;                     *(u32x4*)(rowp + bj * HALF) = w; } }
	v_cvt_pk_bf16_f32 v75, v96, v97
	v_pk_mul_f32 v[62:63], v[62:63], v[172:173] op_sel_hi:[1,0]
	v_cvt_pk_bf16_f32 v76, v76, v77
	v_cvt_pk_bf16_f32 v77, v78, v79
	global_store_dwordx4 v[164:165], v[74:77], off sc1
	v_pk_mul_f32 v[64:65], v[64:65], v[172:173] op_sel_hi:[1,0]
	v_pk_mul_f32 v[56:57], v[56:57], v[172:173] op_sel_hi:[1,0]
	v_pk_mul_f32 v[74:75], v[68:69], v[150:151] op_sel_hi:[1,0]
	v_pk_mul_f32 v[68:69], v[66:67], v[150:151] op_sel_hi:[1,0]
	v_cvt_pk_bf16_f32 v66, v70, v71
	v_cvt_pk_bf16_f32 v67, v72, v73
	v_pk_mul_f32 v[54:55], v[54:55], v[172:173] op_sel_hi:[1,0]
	v_cvt_pk_bf16_f32 v68, v68, v69
	v_cvt_pk_bf16_f32 v69, v74, v75
	global_store_dwordx4 v[164:165], v[66:69], off offset:256 sc1
	v_pk_mul_f32 v[50:51], v[50:51], v[174:175] op_sel_hi:[1,0]
	v_pk_mul_f32 v[40:41], v[40:41], v[174:175] op_sel_hi:[1,0]
	v_pk_mul_f32 v[68:69], v[60:61], v[172:173] op_sel_hi:[1,0]
	v_pk_mul_f32 v[60:61], v[58:59], v[172:173] op_sel_hi:[1,0]
	v_cvt_pk_bf16_f32 v58, v62, v63
	v_add_co_u32_e32 v62, vcc, s54, v148
	v_cvt_pk_bf16_f32 v59, v64, v65
	v_cvt_pk_bf16_f32 v60, v60, v61
	v_cvt_pk_bf16_f32 v61, v68, v69
	v_lshl_add_u64 v[66:67], v[148:149], 0, s[14:15]
	s_nop 0
	v_addc_co_u32_e32 v63, vcc, 0, v149, vcc
	global_store_dwordx4 v[62:63], v[58:61], off sc1
	v_pk_mul_f32 v[38:39], v[38:39], v[174:175] op_sel_hi:[1,0]
	v_pk_mul_f32 v[34:35], v[34:35], v[152:153] op_sel_hi:[1,0]
	v_pk_mul_f32 v[58:59], v[48:49], v[172:173] op_sel_hi:[1,0]
	v_pk_mul_f32 v[48:49], v[46:47], v[172:173] op_sel_hi:[1,0]
	v_cvt_pk_bf16_f32 v46, v54, v55
	v_cvt_pk_bf16_f32 v47, v56, v57
	v_pk_mul_f32 v[24:25], v[24:25], v[152:153] op_sel_hi:[1,0]
	v_cvt_pk_bf16_f32 v48, v48, v49
	v_cvt_pk_bf16_f32 v49, v58, v59
	global_store_dwordx4 v[66:67], v[46:49], off offset:256 sc1
	v_pk_mul_f32 v[22:23], v[22:23], v[152:153] op_sel_hi:[1,0]
	v_pk_mul_f32 v[18:19], v[18:19], v[146:147] op_sel_hi:[1,0]
	v_pk_mul_f32 v[48:49], v[52:53], v[174:175] op_sel_hi:[1,0]
	v_pk_mul_f32 v[52:53], v[44:45], v[174:175] op_sel_hi:[1,0]
	v_pk_mul_f32 v[44:45], v[42:43], v[174:175] op_sel_hi:[1,0]
	v_cvt_pk_bf16_f32 v42, v50, v51
	v_cvt_pk_bf16_f32 v43, v48, v49
	v_add_co_u32_e32 v48, vcc, s55, v148
	v_cvt_pk_bf16_f32 v44, v44, v45
	v_cvt_pk_bf16_f32 v45, v52, v53
	v_lshl_add_u64 v[46:47], v[148:149], 0, s[16:17]
	s_nop 0
	v_addc_co_u32_e32 v49, vcc, 0, v149, vcc
	global_store_dwordx4 v[48:49], v[42:45], off sc1
	v_pk_mul_f32 v[8:9], v[8:9], v[146:147] op_sel_hi:[1,0]
	v_pk_mul_f32 v[6:7], v[6:7], v[146:147] op_sel_hi:[1,0]
	v_pk_mul_f32 v[42:43], v[32:33], v[174:175] op_sel_hi:[1,0]
	v_pk_mul_f32 v[32:33], v[30:31], v[174:175] op_sel_hi:[1,0]
	v_cvt_pk_bf16_f32 v30, v38, v39
	v_cvt_pk_bf16_f32 v31, v40, v41
	s_nop 0
	v_cvt_pk_bf16_f32 v32, v32, v33
	v_cvt_pk_bf16_f32 v33, v42, v43
	global_store_dwordx4 v[46:47], v[30:33], off offset:256 sc1
	s_nop 1
	v_pk_mul_f32 v[32:33], v[36:37], v[152:153] op_sel_hi:[1,0]
	v_pk_mul_f32 v[36:37], v[28:29], v[152:153] op_sel_hi:[1,0]
	v_pk_mul_f32 v[28:29], v[26:27], v[152:153] op_sel_hi:[1,0]
	v_cvt_pk_bf16_f32 v26, v34, v35
	v_cvt_pk_bf16_f32 v27, v32, v33
	v_add_co_u32_e32 v32, vcc, s56, v148
	v_cvt_pk_bf16_f32 v28, v28, v29
	v_cvt_pk_bf16_f32 v29, v36, v37
	v_lshl_add_u64 v[30:31], v[148:149], 0, s[18:19]
	s_nop 0
	v_addc_co_u32_e32 v33, vcc, 0, v149, vcc
	global_store_dwordx4 v[32:33], v[26:29], off sc1
	s_nop 1
	v_pk_mul_f32 v[26:27], v[16:17], v[152:153] op_sel_hi:[1,0]
	v_pk_mul_f32 v[16:17], v[14:15], v[152:153] op_sel_hi:[1,0]
	v_cvt_pk_bf16_f32 v14, v22, v23
	v_cvt_pk_bf16_f32 v15, v24, v25
	s_nop 0
	v_cvt_pk_bf16_f32 v16, v16, v17
	v_cvt_pk_bf16_f32 v17, v26, v27
	global_store_dwordx4 v[30:31], v[14:17], off offset:256 sc1
	s_nop 1
	v_pk_mul_f32 v[16:17], v[20:21], v[146:147] op_sel_hi:[1,0]
	v_pk_mul_f32 v[20:21], v[12:13], v[146:147] op_sel_hi:[1,0]
	v_pk_mul_f32 v[12:13], v[10:11], v[146:147] op_sel_hi:[1,0]
	v_cvt_pk_bf16_f32 v10, v18, v19
	v_cvt_pk_bf16_f32 v11, v16, v17
	v_add_co_u32_e32 v16, vcc, s57, v148
	v_lshl_add_u64 v[14:15], v[148:149], 0, s[20:21]
	s_nop 0
	v_addc_co_u32_e32 v17, vcc, 0, v149, vcc
	v_cvt_pk_bf16_f32 v12, v12, v13
	v_cvt_pk_bf16_f32 v13, v20, v21
	global_store_dwordx4 v[16:17], v[10:13], off sc1
	s_andn2_b64 vcc, exec, s[2:3]
	s_mov_b64 s[2:3], -1
	v_pk_mul_f32 v[10:11], v[4:5], v[146:147] op_sel_hi:[1,0]
	v_pk_mul_f32 v[4:5], v[2:3], v[146:147] op_sel_hi:[1,0]
	v_cvt_pk_bf16_f32 v2, v6, v7
	v_cvt_pk_bf16_f32 v3, v8, v9
	s_nop 0
	v_cvt_pk_bf16_f32 v4, v4, v5
	v_cvt_pk_bf16_f32 v5, v10, v11
	global_store_dwordx4 v[14:15], v[2:5], off offset:256 sc1
	s_cbranch_vccnz .LBB0_1089
	s_andn2_b64 vcc, exec, s[4:5]
	s_cbranch_vccnz .LBB0_1088
	s_barrier
	s_branch .LBB0_1088

; __device__ __forceinline__ void rg_conv(Frame& F) {
;     ...
;     for (int it = F.vcu * NTHREADS + F.tid; it < (MTOK / CR) * 512; it += F.G * NTHREADS) {
;         const int row0 = (it >> 9) * CR, ch = (it & 511) * 8; const bool head = (row0 & (SEQ - 1)) == 0;
;         v4u x[CR + 3];
; #pragma unroll
;         for (int i = 0; i < CR + 3; ++i) x[i] = *(const v4u*)(proj + (size_t)((i < 3 && head) ? row0 : row0 - 3 + i) * RG_NP + ch);
;         v4f w0[4], w1[4];
; #pragma unroll
;         for (int k4 = 0; k4 < 4; ++k4) { w0[k4] = *(const v4f*)(conv_w + k4 * DM + ch); w1[k4] = *(const v4f*)(conv_w + k4 * DM + ch + 4); }
;         const v4f b0 = *(const v4f*)(conv_b + ch), b1 = *(const v4f*)(conv_b + ch + 4);
.LBB0_1157:
	v_ashrrev_i32_e32 v6, 5, v1
	v_and_b32_e32 v142, -16, v6
	v_and_b32_e32 v2, 0xfe00, v1
	v_cmp_ne_u32_e32 vcc, 0, v2
	v_add_u32_e32 v4, -3, v142
	v_and_b32_e32 v7, 0xff8, v174
	v_cndmask_b32_e32 v4, v142, v4, vcc
	v_lshlrev_b32_e32 v110, 1, v7
	v_ashrrev_i32_e32 v5, 31, v4
	v_lshl_add_u64 v[2:3], s[10:11], 0, v[110:111]
	v_lshlrev_b64 v[4:5], 14, v[4:5]
	v_lshl_add_u64 v[4:5], v[2:3], 0, v[4:5]
	global_load_dwordx4 v[98:101], v[4:5], off
	v_add_u32_e32 v4, -2, v142
	v_cndmask_b32_e32 v4, v142, v4, vcc
	v_ashrrev_i32_e32 v5, 31, v4
	v_lshlrev_b64 v[4:5], 14, v[4:5]
	v_lshl_add_u64 v[4:5], v[2:3], 0, v[4:5]
	global_load_dwordx4 v[102:105], v[4:5], off
	v_subbrev_co_u32_e64 v4, s[2:3], 0, v142, vcc
	v_ashrrev_i32_e32 v5, 31, v4
	v_lshlrev_b64 v[4:5], 14, v[4:5]
	v_lshl_add_u64 v[4:5], v[2:3], 0, v[4:5]
	v_ashrrev_i32_e32 v143, 31, v142
	global_load_dwordx4 v[106:109], v[4:5], off
	v_lshlrev_b64 v[4:5], 14, v[142:143]
	v_or_b32_e32 v140, 1, v142
	v_lshl_add_u64 v[4:5], v[2:3], 0, v[4:5]
	v_ashrrev_i32_e32 v141, 31, v140
	global_load_dwordx4 v[94:97], v[4:5], off
	v_lshlrev_b64 v[4:5], 14, v[140:141]
	v_or_b32_e32 v138, 2, v142
	v_lshl_add_u64 v[4:5], v[2:3], 0, v[4:5]
	v_ashrrev_i32_e32 v139, 31, v138
	global_load_dwordx4 v[78:81], v[4:5], off
	v_lshlrev_b64 v[4:5], 14, v[138:139]
	v_or_b32_e32 v136, 3, v142
	v_lshl_add_u64 v[4:5], v[2:3], 0, v[4:5]
	v_ashrrev_i32_e32 v137, 31, v136
	global_load_dwordx4 v[82:85], v[4:5], off
	v_lshlrev_b64 v[4:5], 14, v[136:137]
	v_or_b32_e32 v134, 4, v142
	v_lshl_add_u64 v[4:5], v[2:3], 0, v[4:5]
	v_ashrrev_i32_e32 v135, 31, v134
	global_load_dwordx4 v[70:73], v[4:5], off
	v_lshlrev_b64 v[4:5], 14, v[134:135]
	v_or_b32_e32 v132, 5, v142
	v_lshl_add_u64 v[4:5], v[2:3], 0, v[4:5]
	v_ashrrev_i32_e32 v133, 31, v132
	global_load_dwordx4 v[74:77], v[4:5], off
	v_lshlrev_b64 v[4:5], 14, v[132:133]
	v_or_b32_e32 v130, 6, v142
	v_lshl_add_u64 v[4:5], v[2:3], 0, v[4:5]
	v_ashrrev_i32_e32 v131, 31, v130
	global_load_dwordx4 v[62:65], v[4:5], off
	v_lshlrev_b64 v[4:5], 14, v[130:131]
	v_or_b32_e32 v128, 7, v142
	v_lshl_add_u64 v[4:5], v[2:3], 0, v[4:5]
	v_ashrrev_i32_e32 v129, 31, v128
	global_load_dwordx4 v[66:69], v[4:5], off
	v_lshlrev_b64 v[4:5], 14, v[128:129]
	v_or_b32_e32 v126, 8, v142
	v_lshl_add_u64 v[4:5], v[2:3], 0, v[4:5]
	v_ashrrev_i32_e32 v127, 31, v126
	global_load_dwordx4 v[38:41], v[4:5], off
	v_lshlrev_b64 v[4:5], 14, v[126:127]
	v_or_b32_e32 v124, 9, v142
	v_lshl_add_u64 v[4:5], v[2:3], 0, v[4:5]
	v_ashrrev_i32_e32 v125, 31, v124
	global_load_dwordx4 v[42:45], v[4:5], off
	v_lshlrev_b64 v[4:5], 14, v[124:125]
	v_or_b32_e32 v122, 10, v142
	v_lshl_add_u64 v[4:5], v[2:3], 0, v[4:5]
	v_ashrrev_i32_e32 v123, 31, v122
	global_load_dwordx4 v[30:33], v[4:5], off
	v_lshlrev_b64 v[4:5], 14, v[122:123]
	v_or_b32_e32 v120, 11, v142
	v_lshl_add_u64 v[4:5], v[2:3], 0, v[4:5]
	v_ashrrev_i32_e32 v121, 31, v120
	global_load_dwordx4 v[34:37], v[4:5], off
	v_lshlrev_b64 v[4:5], 14, v[120:121]
	v_or_b32_e32 v118, 12, v142
	v_lshl_add_u64 v[4:5], v[2:3], 0, v[4:5]
	v_ashrrev_i32_e32 v119, 31, v118
	global_load_dwordx4 v[22:25], v[4:5], off
	v_lshlrev_b64 v[4:5], 14, v[118:119]
	v_or_b32_e32 v116, 13, v142
	v_lshl_add_u64 v[4:5], v[2:3], 0, v[4:5]
	v_ashrrev_i32_e32 v117, 31, v116
	global_load_dwordx4 v[26:29], v[4:5], off
	v_lshlrev_b64 v[4:5], 14, v[116:117]
	v_or_b32_e32 v114, 14, v142
	v_lshl_add_u64 v[4:5], v[2:3], 0, v[4:5]
	v_ashrrev_i32_e32 v115, 31, v114
	global_load_dwordx4 v[14:17], v[4:5], off
	v_lshlrev_b64 v[4:5], 14, v[114:115]
	v_or_b32_e32 v112, 15, v6
	v_lshlrev_b32_e32 v58, 2, v7
	v_mov_b32_e32 v59, v111
	v_lshl_add_u64 v[4:5], v[2:3], 0, v[4:5]
	v_ashrrev_i32_e32 v113, 31, v112
	s_waitcnt lgkmcnt(0)
	v_lshl_add_u64 v[54:55], s[4:5], 0, v[58:59]
	global_load_dwordx4 v[18:21], v[4:5], off
	v_lshlrev_b64 v[4:5], 14, v[112:113]
	v_add_co_u32_e64 v8, s[2:3], s24, v54
	v_lshl_add_u64 v[2:3], v[2:3], 0, v[4:5]
	s_nop 0
	v_addc_co_u32_e64 v9, s[2:3], 0, v55, s[2:3]
	global_load_dwordx4 v[2:5], v[2:3], off
	s_nop 0
	global_load_dwordx4 v[46:49], v58, s[4:5] offset:16
	global_load_dwordx4 v[50:53], v58, s[4:5]
	v_lshl_add_u64 v[6:7], v[54:55], 0, s[16:17]
	global_load_dwordx4 v[90:93], v[8:9], off
	global_load_dwordx4 v[86:89], v[6:7], off offset:16
	v_add_co_u32_e64 v8, s[2:3], s25, v54
	v_lshl_add_u64 v[6:7], v[54:55], 0, s[18:19]
	s_nop 0
	v_addc_co_u32_e64 v9, s[2:3], 0, v55, s[2:3]
	v_lshl_add_u64 v[56:57], v[54:55], 0, s[20:21]
	v_add_co_u32_e64 v54, s[2:3], s26, v54
	global_load_dwordx4 v[10:13], v[8:9], off
	s_nop 0
	global_load_dwordx4 v[6:9], v[6:7], off offset:16
	v_addc_co_u32_e64 v55, s[2:3], 0, v55, s[2:3]
	global_load_dwordx4 v[144:147], v[54:55], off
	global_load_dwordx4 v[176:179], v[56:57], off offset:16
	s_nop 0
	global_load_dwordx4 v[54:57], v58, s[6:7] offset:16
	s_nop 0
	global_load_dwordx4 v[58:61], v58, s[6:7]
	s_waitcnt vmcnt(0)
; __device__ __forceinline__ float bflo(unsigned w) { return __uint_as_float(w << 16); }
; __device__ __forceinline__ float bfhi(unsigned w) { return __uint_as_float(w & 0xffff0000u); }
; __device__ __forceinline__ unsigned pk2(float lo, float hi) { unsigned r; asm volatile("v_cvt_pk_bf16_f32 %0, %1, %2" : "=v"(r) : "v"(lo), "v"(hi)); return r; }
; __device__ __forceinline__ void rg_conv(Frame& F) {
;     ...
; #pragma unroll
;         for (int i = 0; i < 3; ++i) { x[i].x = head ? 0u : x[i].x; x[i].y = head ? 0u : x[i].y; x[i].z = head ? 0u : x[i].z; x[i].w = head ? 0u : x[i].w; }
; #pragma unroll
;         for (int j = 0; j < CR; ++j) { v4f a0 = b0, a1 = b1;
; #pragma unroll
;             for (int k4 = 0; k4 < 4; ++k4) { const v4u xx = x[j + k4];
;                 a0.x += w0[k4].x * bflo(xx.x); a0.y += w0[k4].y * bfhi(xx.x); a0.z += w0[k4].z * bflo(xx.y); a0.w += w0[k4].w * bfhi(xx.y);
;                 a1.x += w1[k4].x * bflo(xx.z); a1.y += w1[k4].y * bfhi(xx.z); a1.z += w1[k4].z * bflo(xx.w); a1.w += w1[k4].w * bfhi(xx.w); }
;             v4u o; o.x = pk2(a0.x, a0.y); o.y = pk2(a0.z, a0.w); o.z = pk2(a1.x, a1.y); o.w = pk2(a1.z, a1.w);
;             *(v4u*)(XC + (size_t)(row0 + j) * DM + ch) = o; }
	v_cndmask_b32_e32 v148, 0, v98, vcc
	v_cndmask_b32_e32 v150, 0, v106, vcc
	v_lshlrev_b32_e32 v106, 16, v148
	v_cndmask_b32_e32 v149, 0, v99, vcc
	v_lshl_add_u64 v[98:99], s[12:13], 0, v[110:111]
	v_cndmask_b32_e32 v100, 0, v100, vcc
	v_cndmask_b32_e32 v101, 0, v101, vcc
	v_cndmask_b32_e32 v102, 0, v102, vcc
	v_cndmask_b32_e32 v151, 0, v107, vcc
	v_lshlrev_b32_e32 v173, 16, v102
	v_lshlrev_b32_e32 v157, 16, v150
	v_lshlrev_b32_e32 v156, 16, v94
	v_and_b32_e32 v171, 0xffff0000, v102
	v_and_b32_e32 v155, 0xffff0000, v150
	v_and_b32_e32 v154, 0xffff0000, v94
	v_cndmask_b32_e32 v103, 0, v103, vcc
	v_cndmask_b32_e32 v104, 0, v104, vcc
	v_cndmask_b32_e32 v105, 0, v105, vcc
	v_lshlrev_b32_e32 v169, 16, v103
	v_lshlrev_b32_e32 v165, 16, v104
	v_and_b32_e32 v163, 0xffff0000, v104
	v_lshlrev_b32_e32 v161, 16, v105
	v_and_b32_e32 v159, 0xffff0000, v105
	v_lshlrev_b32_e32 v153, 16, v151
	v_lshlrev_b32_e32 v152, 16, v95
	v_and_b32_e32 v167, 0xffff0000, v103
	v_and_b32_e32 v151, 0xffff0000, v151
	v_and_b32_e32 v150, 0xffff0000, v95
	v_cndmask_b32_e32 v108, 0, v108, vcc
	v_cndmask_b32_e32 v109, 0, v109, vcc
	v_lshlrev_b64 v[142:143], 13, v[142:143]
	v_lshl_add_u64 v[142:143], v[98:99], 0, v[142:143]
	v_mov_b32_e32 v172, v157
	v_add_u32_e32 v1, s22, v1
	v_cmp_lt_i32_e32 vcc, s27, v1
	v_add_u32_e32 v174, s23, v174
	s_or_b64 s[14:15], vcc, s[14:15]
	v_mov_b32_e32 v107, v10
	v_mov_b32_e32 v104, v146
	v_mov_b32_e32 v105, v12
	v_mov_b32_e32 v102, v176
	v_fma_f32 v110, v50, v106, v58
	v_and_b32_e32 v106, 0xffff0000, v148
	v_fma_f32 v148, v51, v106, v59
	v_lshlrev_b32_e32 v106, 16, v149
	v_fma_f32 v158, v52, v106, v60
	v_and_b32_e32 v106, 0xffff0000, v149
	v_fma_f32 v149, v53, v106, v61
	v_lshlrev_b32_e32 v106, 16, v100
	v_and_b32_e32 v100, 0xffff0000, v100
	v_fma_f32 v162, v47, v100, v55
	v_lshlrev_b32_e32 v100, 16, v101
	v_fma_f32 v160, v46, v106, v54
	v_fma_f32 v164, v48, v100, v56
	v_and_b32_e32 v100, 0xffff0000, v101
	v_mov_b32_e32 v106, v144
	v_fma_f32 v166, v49, v100, v57
	v_fmac_f32_e32 v110, v90, v173
	v_pk_mul_f32 v[100:101], v[106:107], v[156:157]
	v_fmac_f32_e32 v148, v91, v171
	v_add_f32_e32 v10, v101, v110
	v_add_f32_e32 v110, v100, v10
	v_mov_b32_e32 v10, v145
	v_pk_mul_f32 v[100:101], v[10:11], v[154:155]
	v_fmac_f32_e32 v158, v92, v169
	v_add_f32_e32 v94, v101, v148
	v_add_f32_e32 v168, v100, v94
	v_pk_mul_f32 v[100:101], v[104:105], v[152:153]
	v_fmac_f32_e32 v149, v93, v167
	v_add_f32_e32 v12, v101, v158
	v_add_f32_e32 v158, v100, v12
	v_mov_b32_e32 v12, v147
	v_pk_mul_f32 v[94:95], v[12:13], v[150:151]
	v_lshlrev_b32_e32 v148, 16, v96
	v_add_f32_e32 v95, v95, v149
	v_lshlrev_b32_e32 v149, 16, v108
	v_mov_b32_e32 v103, v6
	v_fmac_f32_e32 v160, v86, v165
	v_add_f32_e32 v170, v94, v95
	v_pk_mul_f32 v[94:95], v[102:103], v[148:149]
	v_and_b32_e32 v147, 0xffff0000, v108
	v_add_f32_e32 v6, v95, v160
	v_add_f32_e32 v160, v94, v6
	v_and_b32_e32 v146, 0xffff0000, v96
	v_mov_b32_e32 v6, v177
	v_fmac_f32_e32 v162, v87, v163
	v_pk_mul_f32 v[94:95], v[6:7], v[146:147]
	v_lshlrev_b32_e32 v145, 16, v109
	v_add_f32_e32 v95, v95, v162
	v_lshlrev_b32_e32 v144, 16, v97
	v_mov_b32_e32 v100, v178
	v_mov_b32_e32 v101, v8
	v_fmac_f32_e32 v164, v88, v161
	v_add_f32_e32 v96, v94, v95
	v_pk_mul_f32 v[94:95], v[100:101], v[144:145]
	v_and_b32_e32 v109, 0xffff0000, v109
	v_add_f32_e32 v8, v95, v164
	v_add_f32_e32 v162, v94, v8
	v_and_b32_e32 v108, 0xffff0000, v97
	v_mov_b32_e32 v8, v179
	v_fmac_f32_e32 v166, v89, v159
	v_pk_mul_f32 v[94:95], v[8:9], v[108:109]
	v_mov_b32_e32 v164, v149
	v_add_f32_e32 v95, v95, v166
	v_add_f32_e32 v97, v94, v95
	v_cvt_pk_bf16_f32 v94, v110, v168
	v_cvt_pk_bf16_f32 v95, v158, v170
	v_cvt_pk_bf16_f32 v96, v160, v96
	v_cvt_pk_bf16_f32 v97, v162, v97
	global_store_dwordx4 v[142:143], v[94:97], off sc1
	v_mov_b32_e32 v170, v155
	v_mov_b32_e32 v168, v153
	v_mov_b32_e32 v94, v90
	v_mov_b32_e32 v95, v50
	v_pk_mul_f32 v[96:97], v[94:95], v[172:173]
	v_mov_b32_e32 v166, v151
	v_add_f32_e32 v50, v97, v58
	v_add_f32_e32 v110, v96, v50
	v_mov_b32_e32 v50, v91
	v_pk_mul_f32 v[90:91], v[50:51], v[170:171]
	v_mov_b32_e32 v162, v147
	v_add_f32_e32 v91, v91, v59
	v_add_f32_e32 v170, v90, v91
	v_mov_b32_e32 v90, v92
	v_mov_b32_e32 v91, v52
	v_pk_mul_f32 v[96:97], v[90:91], v[168:169]
	v_mov_b32_e32 v160, v145
	v_add_f32_e32 v52, v97, v60
	v_add_f32_e32 v168, v96, v52
	v_mov_b32_e32 v52, v93
	v_pk_mul_f32 v[92:93], v[52:53], v[166:167]
	v_mov_b32_e32 v158, v109
	v_add_f32_e32 v93, v93, v61
	v_add_f32_e32 v166, v92, v93
	v_mov_b32_e32 v92, v86
	v_mov_b32_e32 v93, v46
	v_pk_mul_f32 v[96:97], v[92:93], v[164:165]
	s_nop 0
	v_add_f32_e32 v46, v97, v54
	v_add_f32_e32 v164, v96, v46
	v_mov_b32_e32 v46, v87
	v_pk_mul_f32 v[86:87], v[46:47], v[162:163]
	s_nop 0
	v_add_f32_e32 v87, v87, v55
	v_add_f32_e32 v165, v86, v87
	v_mov_b32_e32 v86, v88
	v_mov_b32_e32 v87, v48
	v_pk_mul_f32 v[96:97], v[86:87], v[160:161]
	s_nop 0
	v_add_f32_e32 v48, v97, v56
	v_add_f32_e32 v167, v96, v48
	v_pk_mul_f32 v[96:97], v[94:95], v[156:157]
	v_mov_b32_e32 v48, v89
	v_add_f32_e32 v97, v97, v58
	v_add_f32_e32 v157, v96, v97
	v_pk_mul_f32 v[96:97], v[50:51], v[154:155]
	v_pk_mul_f32 v[88:89], v[48:49], v[158:159]
	v_add_f32_e32 v97, v97, v59
	v_add_f32_e32 v158, v96, v97
	v_pk_mul_f32 v[96:97], v[90:91], v[152:153]
	v_add_f32_e32 v89, v89, v57
	v_add_f32_e32 v97, v97, v60
	v_add_f32_e32 v160, v96, v97
	v_pk_mul_f32 v[96:97], v[52:53], v[150:151]
	v_add_f32_e32 v169, v88, v89
	v_add_f32_e32 v97, v97, v61
	v_add_f32_e32 v161, v96, v97
	v_pk_mul_f32 v[96:97], v[92:93], v[148:149]
	v_lshlrev_b64 v[88:89], 13, v[140:141]
	v_add_f32_e32 v97, v97, v54
	v_add_f32_e32 v162, v96, v97
; __device__ __forceinline__ float bflo(unsigned w) { return __uint_as_float(w << 16); }
; __device__ __forceinline__ float bfhi(unsigned w) { return __uint_as_float(w & 0xffff0000u); }
; __device__ __forceinline__ unsigned pk2(float lo, float hi) { unsigned r; asm volatile("v_cvt_pk_bf16_f32 %0, %1, %2" : "=v"(r) : "v"(lo), "v"(hi)); return r; }
; __device__ __forceinline__ void rg_conv(Frame& F) {
;     ...
;         for (int j = 0; j < CR; ++j) { v4f a0 = b0, a1 = b1;
; #pragma unroll
;             for (int k4 = 0; k4 < 4; ++k4) { const v4u xx = x[j + k4];
;                 a0.x += w0[k4].x * bflo(xx.x); a0.y += w0[k4].y * bfhi(xx.x); a0.z += w0[k4].z * bflo(xx.y); a0.w += w0[k4].w * bfhi(xx.y);
;                 a1.x += w1[k4].x * bflo(xx.z); a1.y += w1[k4].y * bfhi(xx.z); a1.z += w1[k4].z * bflo(xx.w); a1.w += w1[k4].w * bfhi(xx.w); }
;             v4u o; o.x = pk2(a0.x, a0.y); o.y = pk2(a0.z, a0.w); o.z = pk2(a1.x, a1.y); o.w = pk2(a1.z, a1.w);
;             *(v4u*)(XC + (size_t)(row0 + j) * DM + ch) = o; }
	v_pk_mul_f32 v[96:97], v[46:47], v[146:147]
	v_lshl_add_u64 v[88:89], v[98:99], 0, v[88:89]
	v_add_f32_e32 v97, v97, v55
	v_add_f32_e32 v171, v96, v97
	v_pk_mul_f32 v[96:97], v[86:87], v[144:145]
	s_nop 0
	v_add_f32_e32 v97, v97, v56
	v_add_f32_e32 v172, v96, v97
	v_pk_mul_f32 v[96:97], v[48:49], v[108:109]
	s_nop 0
	v_add_f32_e32 v97, v97, v57
	v_add_f32_e32 v173, v96, v97
	v_lshlrev_b32_e32 v97, 16, v78
	v_lshlrev_b32_e32 v96, 16, v82
	v_pk_mov_b32 v[140:141], v[96:97], v[156:157] op_sel:[1,0]
	s_nop 0
	v_pk_mul_f32 v[142:143], v[106:107], v[140:141]
	s_nop 0
	v_add_f32_e32 v110, v143, v110
	v_add_f32_e32 v110, v142, v110
	v_pk_mul_f32 v[142:143], v[106:107], v[96:97]
	s_nop 0
	v_add_f32_e32 v143, v143, v157
	v_add_f32_e32 v175, v142, v143
	v_and_b32_e32 v143, 0xffff0000, v78
	v_and_b32_e32 v142, 0xffff0000, v82
	v_pk_mov_b32 v[154:155], v[142:143], v[154:155] op_sel:[1,0]
	s_nop 0
	v_pk_mul_f32 v[156:157], v[10:11], v[154:155]
	s_nop 0
	v_add_f32_e32 v78, v157, v170
	v_add_f32_e32 v78, v156, v78
	v_pk_mul_f32 v[156:157], v[10:11], v[142:143]
	v_cvt_pk_bf16_f32 v78, v110, v78
	s_nop 0
	v_add_f32_e32 v82, v157, v158
	v_add_f32_e32 v110, v156, v82
	v_lshlrev_b32_e32 v157, 16, v79
	v_lshlrev_b32_e32 v156, 16, v83
	v_pk_mov_b32 v[152:153], v[156:157], v[152:153] op_sel:[1,0]
	s_nop 0
	v_pk_mul_f32 v[158:159], v[104:105], v[152:153]
	s_nop 0
	v_add_f32_e32 v82, v159, v168
	v_add_f32_e32 v145, v158, v82
	v_pk_mul_f32 v[158:159], v[104:105], v[156:157]
	s_nop 0
	v_add_f32_e32 v82, v159, v160
	v_add_f32_e32 v168, v158, v82
	v_and_b32_e32 v159, 0xffff0000, v79
	v_and_b32_e32 v158, 0xffff0000, v83
	v_pk_mov_b32 v[82:83], v[158:159], v[150:151] op_sel:[1,0]
	s_nop 0
	v_pk_mul_f32 v[150:151], v[12:13], v[82:83]
	s_nop 0
	v_add_f32_e32 v79, v151, v166
	v_add_f32_e32 v79, v150, v79
	v_pk_mul_f32 v[150:151], v[12:13], v[158:159]
	v_cvt_pk_bf16_f32 v79, v145, v79
	s_nop 0
	v_add_f32_e32 v149, v151, v161
	v_add_f32_e32 v166, v150, v149
	v_lshlrev_b32_e32 v151, 16, v80
	v_lshlrev_b32_e32 v150, 16, v84
	v_pk_mov_b32 v[148:149], v[150:151], v[148:149] op_sel:[1,0]
	s_nop 0
	v_pk_mul_f32 v[160:161], v[102:103], v[148:149]
	s_nop 0
	v_add_f32_e32 v145, v161, v164
	v_add_f32_e32 v145, v160, v145
	v_pk_mul_f32 v[160:161], v[102:103], v[150:151]
	s_nop 0
	v_add_f32_e32 v161, v161, v162
	v_add_f32_e32 v170, v160, v161
	v_and_b32_e32 v161, 0xffff0000, v80
	v_and_b32_e32 v160, 0xffff0000, v84
	v_pk_mov_b32 v[146:147], v[160:161], v[146:147] op_sel:[1,0]
	s_nop 0
	v_pk_mul_f32 v[162:163], v[6:7], v[146:147]
	s_nop 0
	v_add_f32_e32 v80, v163, v165
	v_add_f32_e32 v80, v162, v80
	v_pk_mul_f32 v[162:163], v[6:7], v[160:161]
	v_cvt_pk_bf16_f32 v80, v145, v80
	s_nop 0
	v_add_f32_e32 v84, v163, v171
	v_add_f32_e32 v171, v162, v84
	v_lshlrev_b32_e32 v163, 16, v81
	v_lshlrev_b32_e32 v162, 16, v85
	v_pk_mov_b32 v[144:145], v[162:163], v[144:145] op_sel:[1,0]
	s_nop 0
	v_pk_mul_f32 v[164:165], v[100:101], v[144:145]
	s_nop 0
	v_add_f32_e32 v84, v165, v167
	v_add_f32_e32 v167, v164, v84
	v_pk_mul_f32 v[164:165], v[100:101], v[162:163]
	s_nop 0
	v_add_f32_e32 v84, v165, v172
	v_add_f32_e32 v172, v164, v84
	v_and_b32_e32 v165, 0xffff0000, v81
	v_and_b32_e32 v164, 0xffff0000, v85
	v_pk_mov_b32 v[84:85], v[164:165], v[108:109] op_sel:[1,0]
	s_nop 0
	v_pk_mul_f32 v[108:109], v[8:9], v[84:85]
	s_nop 0
	v_add_f32_e32 v81, v109, v169
	v_add_f32_e32 v81, v108, v81
	v_pk_mul_f32 v[108:109], v[8:9], v[164:165]
	v_cvt_pk_bf16_f32 v81, v167, v81
	global_store_dwordx4 v[88:89], v[78:81], off sc1
	v_add_f32_e32 v109, v109, v173
	v_lshlrev_b64 v[88:89], 13, v[138:139]
	v_add_f32_e32 v81, v108, v109
	v_cvt_pk_bf16_f32 v78, v175, v110
	v_cvt_pk_bf16_f32 v79, v168, v166
	v_lshl_add_u64 v[88:89], v[98:99], 0, v[88:89]
	v_cvt_pk_bf16_f32 v80, v170, v171
	v_cvt_pk_bf16_f32 v81, v172, v81
	global_store_dwordx4 v[88:89], v[78:81], off sc1
	s_nop 1
	v_pk_mul_f32 v[78:79], v[94:95], v[140:141]
	v_pk_mul_f32 v[80:81], v[94:95], v[96:97]
	v_add_f32_e32 v79, v79, v58
	v_add_f32_e32 v88, v78, v79
	v_pk_mul_f32 v[78:79], v[50:51], v[154:155]
	v_add_f32_e32 v81, v81, v58
	v_add_f32_e32 v79, v79, v59
	v_add_f32_e32 v108, v78, v79
	v_pk_mul_f32 v[78:79], v[90:91], v[152:153]
	v_add_f32_e32 v89, v80, v81
	v_pk_mul_f32 v[80:81], v[50:51], v[142:143]
	v_add_f32_e32 v79, v79, v60
	v_add_f32_e32 v81, v81, v59
	v_add_f32_e32 v110, v78, v79
	v_pk_mul_f32 v[78:79], v[52:53], v[82:83]
	v_add_f32_e32 v109, v80, v81
	v_pk_mul_f32 v[80:81], v[90:91], v[156:157]
	v_add_f32_e32 v79, v79, v61
	v_add_f32_e32 v81, v81, v60
	v_add_f32_e32 v140, v78, v79
	v_pk_mul_f32 v[78:79], v[92:93], v[148:149]
	v_add_f32_e32 v138, v80, v81
	v_pk_mul_f32 v[80:81], v[52:53], v[158:159]
	v_add_f32_e32 v79, v79, v54
	v_add_f32_e32 v81, v81, v61
	v_add_f32_e32 v148, v78, v79
	v_pk_mul_f32 v[78:79], v[46:47], v[146:147]
	v_add_f32_e32 v141, v80, v81
	v_pk_mul_f32 v[80:81], v[92:93], v[150:151]
	v_add_f32_e32 v79, v79, v55
	v_add_f32_e32 v81, v81, v54
	v_add_f32_e32 v149, v78, v79
	v_pk_mul_f32 v[78:79], v[86:87], v[144:145]
	v_add_f32_e32 v144, v80, v81
	v_pk_mul_f32 v[80:81], v[46:47], v[160:161]
	v_add_f32_e32 v79, v79, v56
	v_add_f32_e32 v81, v81, v55
	v_add_f32_e32 v153, v80, v81
	v_pk_mul_f32 v[80:81], v[86:87], v[162:163]
	v_add_f32_e32 v152, v78, v79
	v_add_f32_e32 v81, v81, v56
	v_add_f32_e32 v155, v80, v81
	v_pk_mul_f32 v[80:81], v[48:49], v[164:165]
	v_pk_mul_f32 v[78:79], v[48:49], v[84:85]
	v_add_f32_e32 v81, v81, v57
	v_add_f32_e32 v166, v80, v81
	v_lshlrev_b32_e32 v81, 16, v70
	v_lshlrev_b32_e32 v80, 16, v74
	v_pk_mov_b32 v[82:83], v[80:81], v[96:97] op_sel:[1,0]
	v_add_f32_e32 v79, v79, v57
	v_pk_mul_f32 v[84:85], v[106:107], v[82:83]
; __device__ __forceinline__ float bflo(unsigned w) { return __uint_as_float(w << 16); }
; __device__ __forceinline__ float bfhi(unsigned w) { return __uint_as_float(w & 0xffff0000u); }
; __device__ __forceinline__ unsigned pk2(float lo, float hi) { unsigned r; asm volatile("v_cvt_pk_bf16_f32 %0, %1, %2" : "=v"(r) : "v"(lo), "v"(hi)); return r; }
; __device__ __forceinline__ void rg_conv(Frame& F) {
;     ...
;         for (int j = 0; j < CR; ++j) { v4f a0 = b0, a1 = b1;
; #pragma unroll
;             for (int k4 = 0; k4 < 4; ++k4) { const v4u xx = x[j + k4];
;                 a0.x += w0[k4].x * bflo(xx.x); a0.y += w0[k4].y * bfhi(xx.x); a0.z += w0[k4].z * bflo(xx.y); a0.w += w0[k4].w * bfhi(xx.y);
;                 a1.x += w1[k4].x * bflo(xx.z); a1.y += w1[k4].y * bfhi(xx.z); a1.z += w1[k4].z * bflo(xx.w); a1.w += w1[k4].w * bfhi(xx.w); }
;             v4u o; o.x = pk2(a0.x, a0.y); o.y = pk2(a0.z, a0.w); o.z = pk2(a1.x, a1.y); o.w = pk2(a1.z, a1.w);
;             *(v4u*)(XC + (size_t)(row0 + j) * DM + ch) = o; }
	v_add_f32_e32 v154, v78, v79
	v_add_f32_e32 v85, v85, v88
	v_lshlrev_b64 v[78:79], 13, v[136:137]
	v_add_f32_e32 v136, v84, v85
	v_pk_mul_f32 v[84:85], v[106:107], v[80:81]
	v_lshl_add_u64 v[78:79], v[98:99], 0, v[78:79]
	v_add_f32_e32 v85, v85, v89
	v_add_f32_e32 v167, v84, v85
	v_and_b32_e32 v85, 0xffff0000, v70
	v_and_b32_e32 v84, 0xffff0000, v74
	v_pk_mov_b32 v[88:89], v[84:85], v[142:143] op_sel:[1,0]
	s_nop 0
	v_pk_mul_f32 v[96:97], v[10:11], v[88:89]
	s_nop 0
	v_add_f32_e32 v70, v97, v108
	v_add_f32_e32 v70, v96, v70
	v_pk_mul_f32 v[96:97], v[10:11], v[84:85]
	v_cvt_pk_bf16_f32 v70, v136, v70
	s_nop 0
	v_add_f32_e32 v74, v97, v109
	v_add_f32_e32 v168, v96, v74
	v_lshlrev_b32_e32 v97, 16, v71
	v_lshlrev_b32_e32 v96, 16, v75
	v_pk_mov_b32 v[108:109], v[96:97], v[156:157] op_sel:[1,0]
	s_nop 0
	v_pk_mul_f32 v[136:137], v[104:105], v[108:109]
	s_nop 0
	v_add_f32_e32 v74, v137, v110
	v_add_f32_e32 v110, v136, v74
	v_pk_mul_f32 v[136:137], v[104:105], v[96:97]
	s_nop 0
	v_add_f32_e32 v74, v137, v138
	v_add_f32_e32 v156, v136, v74
	v_and_b32_e32 v137, 0xffff0000, v71
	v_and_b32_e32 v136, 0xffff0000, v75
	v_pk_mov_b32 v[74:75], v[136:137], v[158:159] op_sel:[1,0]
	s_nop 0
	v_pk_mul_f32 v[138:139], v[12:13], v[74:75]
	s_nop 0
	v_add_f32_e32 v71, v139, v140
	v_add_f32_e32 v71, v138, v71
	v_pk_mul_f32 v[138:139], v[12:13], v[136:137]
	v_cvt_pk_bf16_f32 v71, v110, v71
	s_nop 0
	v_add_f32_e32 v139, v139, v141
	v_add_f32_e32 v110, v138, v139
	v_lshlrev_b32_e32 v139, 16, v72
	v_lshlrev_b32_e32 v138, 16, v76
	v_pk_mov_b32 v[140:141], v[138:139], v[150:151] op_sel:[1,0]
	s_nop 0
	v_pk_mul_f32 v[142:143], v[102:103], v[140:141]
	s_nop 0
	v_add_f32_e32 v143, v143, v148
	v_add_f32_e32 v148, v142, v143
	v_pk_mul_f32 v[142:143], v[102:103], v[138:139]
	s_nop 0
	v_add_f32_e32 v143, v143, v144
	v_add_f32_e32 v157, v142, v143
	v_and_b32_e32 v143, 0xffff0000, v72
	v_and_b32_e32 v142, 0xffff0000, v76
	v_pk_mov_b32 v[144:145], v[142:143], v[160:161] op_sel:[1,0]
	s_nop 0
	v_pk_mul_f32 v[146:147], v[6:7], v[144:145]
	s_nop 0
	v_add_f32_e32 v72, v147, v149
	v_add_f32_e32 v72, v146, v72
	v_pk_mul_f32 v[146:147], v[6:7], v[142:143]
	v_cvt_pk_bf16_f32 v72, v148, v72
	s_nop 0
	v_add_f32_e32 v76, v147, v153
	v_add_f32_e32 v158, v146, v76
	v_lshlrev_b32_e32 v147, 16, v73
	v_lshlrev_b32_e32 v146, 16, v77
	v_pk_mov_b32 v[148:149], v[146:147], v[162:163] op_sel:[1,0]
	s_nop 0
	v_pk_mul_f32 v[150:151], v[100:101], v[148:149]
	s_nop 0
	v_add_f32_e32 v76, v151, v152
	v_add_f32_e32 v159, v150, v76
	v_pk_mul_f32 v[150:151], v[100:101], v[146:147]
	s_nop 0
	v_add_f32_e32 v76, v151, v155
	v_add_f32_e32 v155, v150, v76
	v_and_b32_e32 v151, 0xffff0000, v73
	v_and_b32_e32 v150, 0xffff0000, v77
	v_pk_mov_b32 v[76:77], v[150:151], v[164:165] op_sel:[1,0]
	s_nop 0
	v_pk_mul_f32 v[152:153], v[8:9], v[76:77]
	s_nop 0
	v_add_f32_e32 v73, v153, v154
	v_add_f32_e32 v73, v152, v73
	v_pk_mul_f32 v[152:153], v[8:9], v[150:151]
	v_cvt_pk_bf16_f32 v73, v159, v73
	global_store_dwordx4 v[78:79], v[70:73], off sc1
	v_add_f32_e32 v153, v153, v166
	v_lshlrev_b64 v[78:79], 13, v[134:135]
	v_add_f32_e32 v73, v152, v153
	v_cvt_pk_bf16_f32 v70, v167, v168
	v_cvt_pk_bf16_f32 v71, v156, v110
	v_lshl_add_u64 v[78:79], v[98:99], 0, v[78:79]
	v_cvt_pk_bf16_f32 v72, v157, v158
	v_cvt_pk_bf16_f32 v73, v155, v73
	global_store_dwordx4 v[78:79], v[70:73], off sc1
	s_nop 1
	v_pk_mul_f32 v[70:71], v[94:95], v[82:83]
	v_pk_mul_f32 v[72:73], v[94:95], v[80:81]
	v_add_f32_e32 v71, v71, v58
	v_add_f32_e32 v78, v70, v71
	v_pk_mul_f32 v[70:71], v[50:51], v[88:89]
	v_add_f32_e32 v73, v73, v58
	v_add_f32_e32 v71, v71, v59
	v_add_f32_e32 v82, v70, v71
	v_pk_mul_f32 v[70:71], v[90:91], v[108:109]
	v_add_f32_e32 v79, v72, v73
	v_add_f32_e32 v71, v71, v60
	v_add_f32_e32 v88, v70, v71
	v_pk_mul_f32 v[70:71], v[52:53], v[74:75]
	v_pk_mul_f32 v[72:73], v[50:51], v[84:85]
	v_add_f32_e32 v71, v71, v61
	v_add_f32_e32 v108, v70, v71
	v_pk_mul_f32 v[70:71], v[92:93], v[140:141]
	v_add_f32_e32 v73, v73, v59
	v_add_f32_e32 v71, v71, v54
	v_add_f32_e32 v110, v70, v71
	v_pk_mul_f32 v[70:71], v[46:47], v[144:145]
	v_add_f32_e32 v83, v72, v73
	v_pk_mul_f32 v[72:73], v[90:91], v[96:97]
	v_add_f32_e32 v71, v71, v55
	v_add_f32_e32 v73, v73, v60
	v_add_f32_e32 v140, v70, v71
	v_pk_mul_f32 v[70:71], v[86:87], v[148:149]
	v_add_f32_e32 v89, v72, v73
	v_pk_mul_f32 v[72:73], v[52:53], v[136:137]
	v_add_f32_e32 v71, v71, v56
	v_add_f32_e32 v73, v73, v61
	v_add_f32_e32 v141, v70, v71
	v_pk_mul_f32 v[70:71], v[48:49], v[76:77]
	v_add_f32_e32 v109, v72, v73
	v_pk_mul_f32 v[72:73], v[92:93], v[138:139]
	v_add_f32_e32 v71, v71, v57
	v_add_f32_e32 v73, v73, v54
	v_add_f32_e32 v144, v70, v71
	v_lshlrev_b64 v[70:71], 13, v[132:133]
	v_add_f32_e32 v132, v72, v73
	v_pk_mul_f32 v[72:73], v[46:47], v[142:143]
	v_lshl_add_u64 v[70:71], v[98:99], 0, v[70:71]
	v_add_f32_e32 v73, v73, v55
	v_add_f32_e32 v145, v72, v73
	v_pk_mul_f32 v[72:73], v[86:87], v[146:147]
	s_nop 0
	v_add_f32_e32 v73, v73, v56
	v_add_f32_e32 v148, v72, v73
	v_pk_mul_f32 v[72:73], v[48:49], v[150:151]
	s_nop 0
	v_add_f32_e32 v73, v73, v57
	v_add_f32_e32 v149, v72, v73
	v_lshlrev_b32_e32 v73, 16, v62
	v_lshlrev_b32_e32 v72, 16, v66
	v_pk_mov_b32 v[74:75], v[72:73], v[80:81] op_sel:[1,0]
	s_nop 0
	v_pk_mul_f32 v[76:77], v[106:107], v[74:75]
	s_nop 0
	v_add_f32_e32 v77, v77, v78
	v_add_f32_e32 v133, v76, v77
	v_pk_mul_f32 v[76:77], v[106:107], v[72:73]
	s_nop 0
	v_add_f32_e32 v77, v77, v79
	v_add_f32_e32 v152, v76, v77
	v_and_b32_e32 v77, 0xffff0000, v62
	v_and_b32_e32 v76, 0xffff0000, v66
	v_pk_mov_b32 v[78:79], v[76:77], v[84:85] op_sel:[1,0]
	s_nop 0
	v_pk_mul_f32 v[80:81], v[10:11], v[78:79]
; __device__ __forceinline__ float bflo(unsigned w) { return __uint_as_float(w << 16); }
; __device__ __forceinline__ float bfhi(unsigned w) { return __uint_as_float(w & 0xffff0000u); }
; __device__ __forceinline__ unsigned pk2(float lo, float hi) { unsigned r; asm volatile("v_cvt_pk_bf16_f32 %0, %1, %2" : "=v"(r) : "v"(lo), "v"(hi)); return r; }
; __device__ __forceinline__ void rg_conv(Frame& F) {
;     ...
;         for (int j = 0; j < CR; ++j) { v4f a0 = b0, a1 = b1;
; #pragma unroll
;             for (int k4 = 0; k4 < 4; ++k4) { const v4u xx = x[j + k4];
;                 a0.x += w0[k4].x * bflo(xx.x); a0.y += w0[k4].y * bfhi(xx.x); a0.z += w0[k4].z * bflo(xx.y); a0.w += w0[k4].w * bfhi(xx.y);
;                 a1.x += w1[k4].x * bflo(xx.z); a1.y += w1[k4].y * bfhi(xx.z); a1.z += w1[k4].z * bflo(xx.w); a1.w += w1[k4].w * bfhi(xx.w); }
;             v4u o; o.x = pk2(a0.x, a0.y); o.y = pk2(a0.z, a0.w); o.z = pk2(a1.x, a1.y); o.w = pk2(a1.z, a1.w);
;             *(v4u*)(XC + (size_t)(row0 + j) * DM + ch) = o; }
	s_nop 0
	v_add_f32_e32 v62, v81, v82
	v_add_f32_e32 v62, v80, v62
	v_pk_mul_f32 v[80:81], v[10:11], v[76:77]
	v_cvt_pk_bf16_f32 v62, v133, v62
	s_nop 0
	v_add_f32_e32 v66, v81, v83
	v_add_f32_e32 v153, v80, v66
	v_lshlrev_b32_e32 v81, 16, v63
	v_lshlrev_b32_e32 v80, 16, v67
	v_pk_mov_b32 v[82:83], v[80:81], v[96:97] op_sel:[1,0]
	s_nop 0
	v_pk_mul_f32 v[84:85], v[104:105], v[82:83]
	s_nop 0
	v_add_f32_e32 v66, v85, v88
	v_add_f32_e32 v96, v84, v66
	v_pk_mul_f32 v[84:85], v[104:105], v[80:81]
	s_nop 0
	v_add_f32_e32 v66, v85, v89
	v_add_f32_e32 v154, v84, v66
	v_and_b32_e32 v85, 0xffff0000, v63
	v_and_b32_e32 v84, 0xffff0000, v67
	v_pk_mov_b32 v[66:67], v[84:85], v[136:137] op_sel:[1,0]
	s_nop 0
	v_pk_mul_f32 v[88:89], v[12:13], v[66:67]
	s_nop 0
	v_add_f32_e32 v63, v89, v108
	v_add_f32_e32 v63, v88, v63
	v_pk_mul_f32 v[88:89], v[12:13], v[84:85]
	v_cvt_pk_bf16_f32 v63, v96, v63
	s_nop 0
	v_add_f32_e32 v89, v89, v109
	v_add_f32_e32 v155, v88, v89
	v_lshlrev_b32_e32 v89, 16, v64
	v_lshlrev_b32_e32 v88, 16, v68
	v_pk_mov_b32 v[96:97], v[88:89], v[138:139] op_sel:[1,0]
	s_nop 0
	v_pk_mul_f32 v[108:109], v[102:103], v[96:97]
	s_nop 0
	v_add_f32_e32 v109, v109, v110
	v_add_f32_e32 v110, v108, v109
	v_pk_mul_f32 v[108:109], v[102:103], v[88:89]
	s_nop 0
	v_add_f32_e32 v109, v109, v132
	v_add_f32_e32 v156, v108, v109
	v_and_b32_e32 v109, 0xffff0000, v64
	v_and_b32_e32 v108, 0xffff0000, v68
	v_pk_mov_b32 v[132:133], v[108:109], v[142:143] op_sel:[1,0]
	s_nop 0
	v_pk_mul_f32 v[134:135], v[6:7], v[132:133]
	s_nop 0
	v_add_f32_e32 v64, v135, v140
	v_add_f32_e32 v64, v134, v64
	v_pk_mul_f32 v[134:135], v[6:7], v[108:109]
	v_cvt_pk_bf16_f32 v64, v110, v64
	s_nop 0
	v_add_f32_e32 v68, v135, v145
	v_add_f32_e32 v110, v134, v68
	v_lshlrev_b32_e32 v135, 16, v65
	v_lshlrev_b32_e32 v134, 16, v69
	v_pk_mov_b32 v[136:137], v[134:135], v[146:147] op_sel:[1,0]
	s_nop 0
	v_pk_mul_f32 v[138:139], v[100:101], v[136:137]
	s_nop 0
	v_add_f32_e32 v68, v139, v141
	v_add_f32_e32 v142, v138, v68
	v_pk_mul_f32 v[138:139], v[100:101], v[134:135]
	s_nop 0
	v_add_f32_e32 v68, v139, v148
	v_add_f32_e32 v143, v138, v68
	v_and_b32_e32 v139, 0xffff0000, v65
	v_and_b32_e32 v138, 0xffff0000, v69
	v_pk_mov_b32 v[68:69], v[138:139], v[150:151] op_sel:[1,0]
	s_nop 0
	v_pk_mul_f32 v[140:141], v[8:9], v[68:69]
	s_nop 0
	v_add_f32_e32 v65, v141, v144
	v_add_f32_e32 v65, v140, v65
	v_pk_mul_f32 v[140:141], v[8:9], v[138:139]
	v_cvt_pk_bf16_f32 v65, v142, v65
	global_store_dwordx4 v[70:71], v[62:65], off sc1
	v_add_f32_e32 v141, v141, v149
	v_lshlrev_b64 v[70:71], 13, v[130:131]
	v_add_f32_e32 v65, v140, v141
	v_cvt_pk_bf16_f32 v62, v152, v153
	v_cvt_pk_bf16_f32 v63, v154, v155
	v_lshl_add_u64 v[70:71], v[98:99], 0, v[70:71]
	v_cvt_pk_bf16_f32 v64, v156, v110
	v_cvt_pk_bf16_f32 v65, v143, v65
	global_store_dwordx4 v[70:71], v[62:65], off sc1
	s_nop 1
	v_pk_mul_f32 v[62:63], v[94:95], v[74:75]
	v_pk_mul_f32 v[64:65], v[94:95], v[72:73]
	v_add_f32_e32 v63, v63, v58
	v_add_f32_e32 v70, v62, v63
	v_pk_mul_f32 v[62:63], v[50:51], v[78:79]
	v_add_f32_e32 v65, v65, v58
	v_add_f32_e32 v63, v63, v59
	v_add_f32_e32 v74, v62, v63
	v_pk_mul_f32 v[62:63], v[90:91], v[82:83]
	v_add_f32_e32 v71, v64, v65
	v_add_f32_e32 v63, v63, v60
	v_add_f32_e32 v78, v62, v63
	v_pk_mul_f32 v[62:63], v[52:53], v[66:67]
	v_pk_mul_f32 v[64:65], v[50:51], v[76:77]
	v_add_f32_e32 v63, v63, v61
	v_add_f32_e32 v82, v62, v63
	v_pk_mul_f32 v[62:63], v[92:93], v[96:97]
	v_add_f32_e32 v65, v65, v59
	v_add_f32_e32 v63, v63, v54
	v_add_f32_e32 v96, v62, v63
	v_pk_mul_f32 v[62:63], v[46:47], v[132:133]
	v_add_f32_e32 v75, v64, v65
	v_pk_mul_f32 v[64:65], v[90:91], v[80:81]
	v_add_f32_e32 v63, v63, v55
	v_add_f32_e32 v65, v65, v60
	v_add_f32_e32 v97, v62, v63
	v_pk_mul_f32 v[62:63], v[86:87], v[136:137]
	v_add_f32_e32 v79, v64, v65
	v_pk_mul_f32 v[64:65], v[52:53], v[84:85]
	v_add_f32_e32 v63, v63, v56
	v_add_f32_e32 v65, v65, v61
	v_add_f32_e32 v110, v62, v63
	v_pk_mul_f32 v[62:63], v[48:49], v[68:69]
	v_add_f32_e32 v83, v64, v65
	v_pk_mul_f32 v[64:65], v[92:93], v[88:89]
	v_add_f32_e32 v63, v63, v57
	v_add_f32_e32 v65, v65, v54
	v_add_f32_e32 v130, v62, v63
	v_lshlrev_b64 v[62:63], 13, v[128:129]
	v_add_f32_e32 v128, v64, v65
	v_pk_mul_f32 v[64:65], v[46:47], v[108:109]
	v_lshl_add_u64 v[62:63], v[98:99], 0, v[62:63]
	v_add_f32_e32 v65, v65, v55
	v_add_f32_e32 v129, v64, v65
	v_pk_mul_f32 v[64:65], v[86:87], v[134:135]
	s_nop 0
	v_add_f32_e32 v65, v65, v56
	v_add_f32_e32 v131, v64, v65
	v_pk_mul_f32 v[64:65], v[48:49], v[138:139]
	s_nop 0
	v_add_f32_e32 v65, v65, v57
	v_add_f32_e32 v132, v64, v65
	v_lshlrev_b32_e32 v65, 16, v38
	v_lshlrev_b32_e32 v64, 16, v42
	v_pk_mov_b32 v[66:67], v[64:65], v[72:73] op_sel:[1,0]
	s_nop 0
	v_pk_mul_f32 v[68:69], v[106:107], v[66:67]
	s_nop 0
	v_add_f32_e32 v69, v69, v70
	v_add_f32_e32 v133, v68, v69
	v_pk_mul_f32 v[68:69], v[106:107], v[64:65]
	s_nop 0
	v_add_f32_e32 v69, v69, v71
	v_add_f32_e32 v136, v68, v69
	v_and_b32_e32 v69, 0xffff0000, v38
	v_and_b32_e32 v68, 0xffff0000, v42
	v_pk_mov_b32 v[70:71], v[68:69], v[76:77] op_sel:[1,0]
	s_nop 0
	v_pk_mul_f32 v[72:73], v[10:11], v[70:71]
	s_nop 0
	v_add_f32_e32 v38, v73, v74
	v_add_f32_e32 v38, v72, v38
	v_pk_mul_f32 v[72:73], v[10:11], v[68:69]
	v_cvt_pk_bf16_f32 v38, v133, v38
	s_nop 0
	v_add_f32_e32 v42, v73, v75
	v_add_f32_e32 v133, v72, v42
	v_lshlrev_b32_e32 v73, 16, v39
	v_lshlrev_b32_e32 v72, 16, v43
	v_pk_mov_b32 v[74:75], v[72:73], v[80:81] op_sel:[1,0]
	s_nop 0
	v_pk_mul_f32 v[76:77], v[104:105], v[74:75]
	s_nop 0
	v_add_f32_e32 v42, v77, v78
	v_add_f32_e32 v80, v76, v42
	v_pk_mul_f32 v[76:77], v[104:105], v[72:73]
	s_nop 0
; __device__ __forceinline__ float bflo(unsigned w) { return __uint_as_float(w << 16); }
; __device__ __forceinline__ float bfhi(unsigned w) { return __uint_as_float(w & 0xffff0000u); }
; __device__ __forceinline__ unsigned pk2(float lo, float hi) { unsigned r; asm volatile("v_cvt_pk_bf16_f32 %0, %1, %2" : "=v"(r) : "v"(lo), "v"(hi)); return r; }
; __device__ __forceinline__ void rg_conv(Frame& F) {
;     ...
;         for (int j = 0; j < CR; ++j) { v4f a0 = b0, a1 = b1;
; #pragma unroll
;             for (int k4 = 0; k4 < 4; ++k4) { const v4u xx = x[j + k4];
;                 a0.x += w0[k4].x * bflo(xx.x); a0.y += w0[k4].y * bfhi(xx.x); a0.z += w0[k4].z * bflo(xx.y); a0.w += w0[k4].w * bfhi(xx.y);
;                 a1.x += w1[k4].x * bflo(xx.z); a1.y += w1[k4].y * bfhi(xx.z); a1.z += w1[k4].z * bflo(xx.w); a1.w += w1[k4].w * bfhi(xx.w); }
;             v4u o; o.x = pk2(a0.x, a0.y); o.y = pk2(a0.z, a0.w); o.z = pk2(a1.x, a1.y); o.w = pk2(a1.z, a1.w);
;             *(v4u*)(XC + (size_t)(row0 + j) * DM + ch) = o; }
	v_add_f32_e32 v42, v77, v79
	v_add_f32_e32 v137, v76, v42
	v_and_b32_e32 v77, 0xffff0000, v39
	v_and_b32_e32 v76, 0xffff0000, v43
	v_pk_mov_b32 v[42:43], v[76:77], v[84:85] op_sel:[1,0]
	s_nop 0
	v_pk_mul_f32 v[78:79], v[12:13], v[42:43]
	s_nop 0
	v_add_f32_e32 v39, v79, v82
	v_add_f32_e32 v39, v78, v39
	v_pk_mul_f32 v[78:79], v[12:13], v[76:77]
	v_cvt_pk_bf16_f32 v39, v80, v39
	s_nop 0
	v_add_f32_e32 v79, v79, v83
	v_add_f32_e32 v140, v78, v79
	v_lshlrev_b32_e32 v79, 16, v40
	v_lshlrev_b32_e32 v78, 16, v44
	v_pk_mov_b32 v[80:81], v[78:79], v[88:89] op_sel:[1,0]
	s_nop 0
	v_pk_mul_f32 v[82:83], v[102:103], v[80:81]
	s_nop 0
	v_add_f32_e32 v83, v83, v96
	v_add_f32_e32 v96, v82, v83
	v_pk_mul_f32 v[82:83], v[102:103], v[78:79]
	s_nop 0
	v_add_f32_e32 v83, v83, v128
	v_add_f32_e32 v141, v82, v83
	v_and_b32_e32 v83, 0xffff0000, v40
	v_and_b32_e32 v82, 0xffff0000, v44
	v_pk_mov_b32 v[84:85], v[82:83], v[108:109] op_sel:[1,0]
	s_nop 0
	v_pk_mul_f32 v[88:89], v[6:7], v[84:85]
	s_nop 0
	v_add_f32_e32 v40, v89, v97
	v_add_f32_e32 v40, v88, v40
	v_pk_mul_f32 v[88:89], v[6:7], v[82:83]
	v_cvt_pk_bf16_f32 v40, v96, v40
	s_nop 0
	v_add_f32_e32 v44, v89, v129
	v_add_f32_e32 v142, v88, v44
	v_lshlrev_b32_e32 v89, 16, v41
	v_lshlrev_b32_e32 v88, 16, v45
	v_pk_mov_b32 v[96:97], v[88:89], v[134:135] op_sel:[1,0]
	s_nop 0
	v_pk_mul_f32 v[108:109], v[100:101], v[96:97]
	s_nop 0
	v_add_f32_e32 v44, v109, v110
	v_add_f32_e32 v110, v108, v44
	v_pk_mul_f32 v[108:109], v[100:101], v[88:89]
	s_nop 0
	v_add_f32_e32 v44, v109, v131
	v_add_f32_e32 v131, v108, v44
	v_and_b32_e32 v109, 0xffff0000, v41
	v_and_b32_e32 v108, 0xffff0000, v45
	v_pk_mov_b32 v[44:45], v[108:109], v[138:139] op_sel:[1,0]
	s_nop 0
	v_pk_mul_f32 v[128:129], v[8:9], v[44:45]
	s_nop 0
	v_add_f32_e32 v41, v129, v130
	v_add_f32_e32 v41, v128, v41
	v_pk_mul_f32 v[128:129], v[8:9], v[108:109]
	v_cvt_pk_bf16_f32 v41, v110, v41
	global_store_dwordx4 v[62:63], v[38:41], off sc1
	v_add_f32_e32 v129, v129, v132
	v_lshlrev_b64 v[62:63], 13, v[126:127]
	v_add_f32_e32 v41, v128, v129
	v_cvt_pk_bf16_f32 v38, v136, v133
	v_cvt_pk_bf16_f32 v39, v137, v140
	v_cvt_pk_bf16_f32 v40, v141, v142
	v_cvt_pk_bf16_f32 v41, v131, v41
	v_lshl_add_u64 v[62:63], v[98:99], 0, v[62:63]
	global_store_dwordx4 v[62:63], v[38:41], off sc1
	s_nop 1
	v_pk_mul_f32 v[38:39], v[94:95], v[66:67]
	v_pk_mul_f32 v[40:41], v[94:95], v[64:65]
	v_add_f32_e32 v39, v39, v58
	v_add_f32_e32 v41, v41, v58
	v_add_f32_e32 v62, v38, v39
	v_pk_mul_f32 v[38:39], v[50:51], v[70:71]
	v_add_f32_e32 v63, v40, v41
	v_pk_mul_f32 v[40:41], v[50:51], v[68:69]
	v_add_f32_e32 v39, v39, v59
	v_add_f32_e32 v41, v41, v59
	v_add_f32_e32 v66, v38, v39
	v_pk_mul_f32 v[38:39], v[90:91], v[74:75]
	v_add_f32_e32 v67, v40, v41
	v_pk_mul_f32 v[40:41], v[90:91], v[72:73]
	v_add_f32_e32 v39, v39, v60
	v_add_f32_e32 v41, v41, v60
	v_add_f32_e32 v70, v38, v39
	v_pk_mul_f32 v[38:39], v[52:53], v[42:43]
	v_add_f32_e32 v71, v40, v41
	v_pk_mul_f32 v[40:41], v[52:53], v[76:77]
	v_add_f32_e32 v39, v39, v61
	v_add_f32_e32 v41, v41, v61
	v_add_f32_e32 v74, v38, v39
	v_pk_mul_f32 v[38:39], v[92:93], v[80:81]
	v_add_f32_e32 v75, v40, v41
	v_pk_mul_f32 v[40:41], v[92:93], v[78:79]
	v_add_f32_e32 v39, v39, v54
	v_add_f32_e32 v41, v41, v54
	v_add_f32_e32 v80, v38, v39
	v_pk_mul_f32 v[38:39], v[46:47], v[84:85]
	v_add_f32_e32 v85, v40, v41
	v_pk_mul_f32 v[40:41], v[46:47], v[82:83]
	v_add_f32_e32 v39, v39, v55
	v_add_f32_e32 v41, v41, v55
	v_add_f32_e32 v81, v38, v39
	v_pk_mul_f32 v[38:39], v[86:87], v[96:97]
	v_add_f32_e32 v97, v40, v41
	v_pk_mul_f32 v[40:41], v[86:87], v[88:89]
	v_add_f32_e32 v39, v39, v56
	v_add_f32_e32 v41, v41, v56
	v_add_f32_e32 v84, v38, v39
	v_pk_mul_f32 v[38:39], v[48:49], v[44:45]
	v_add_f32_e32 v110, v40, v41
	v_pk_mul_f32 v[40:41], v[48:49], v[108:109]
	v_add_f32_e32 v39, v39, v57
	v_add_f32_e32 v41, v41, v57
	v_add_f32_e32 v96, v38, v39
	v_lshlrev_b64 v[38:39], 13, v[124:125]
	v_add_f32_e32 v124, v40, v41
	v_lshlrev_b32_e32 v41, 16, v30
	v_lshlrev_b32_e32 v40, 16, v34
	v_pk_mov_b32 v[42:43], v[40:41], v[64:65] op_sel:[1,0]
	v_lshl_add_u64 v[38:39], v[98:99], 0, v[38:39]
	v_pk_mul_f32 v[44:45], v[106:107], v[42:43]
	s_nop 0
	v_add_f32_e32 v45, v45, v62
	v_add_f32_e32 v125, v44, v45
	v_pk_mul_f32 v[44:45], v[106:107], v[40:41]
	s_nop 0
	v_add_f32_e32 v45, v45, v63
	v_add_f32_e32 v126, v44, v45
	v_and_b32_e32 v45, 0xffff0000, v30
	v_and_b32_e32 v44, 0xffff0000, v34
	v_pk_mov_b32 v[62:63], v[44:45], v[68:69] op_sel:[1,0]
	s_nop 0
	v_pk_mul_f32 v[64:65], v[10:11], v[62:63]
	s_nop 0
	v_add_f32_e32 v30, v65, v66
	v_add_f32_e32 v30, v64, v30
	v_pk_mul_f32 v[64:65], v[10:11], v[44:45]
	v_cvt_pk_bf16_f32 v30, v125, v30
	s_nop 0
	v_add_f32_e32 v34, v65, v67
	v_add_f32_e32 v125, v64, v34
	v_lshlrev_b32_e32 v65, 16, v31
	v_lshlrev_b32_e32 v64, 16, v35
	v_pk_mov_b32 v[66:67], v[64:65], v[72:73] op_sel:[1,0]
	s_nop 0
	v_pk_mul_f32 v[68:69], v[104:105], v[66:67]
	s_nop 0
	v_add_f32_e32 v34, v69, v70
	v_add_f32_e32 v72, v68, v34
	v_pk_mul_f32 v[68:69], v[104:105], v[64:65]
	s_nop 0
	v_add_f32_e32 v34, v69, v71
	v_add_f32_e32 v127, v68, v34
	v_and_b32_e32 v69, 0xffff0000, v31
	v_and_b32_e32 v68, 0xffff0000, v35
	v_pk_mov_b32 v[34:35], v[68:69], v[76:77] op_sel:[1,0]
	s_nop 0
	v_pk_mul_f32 v[70:71], v[12:13], v[34:35]
	s_nop 0
	v_add_f32_e32 v31, v71, v74
	v_add_f32_e32 v31, v70, v31
	v_pk_mul_f32 v[70:71], v[12:13], v[68:69]
	v_cvt_pk_bf16_f32 v31, v72, v31
	s_nop 0
	v_add_f32_e32 v71, v71, v75
	v_add_f32_e32 v128, v70, v71
	v_lshlrev_b32_e32 v71, 16, v32
	v_lshlrev_b32_e32 v70, 16, v36
	v_pk_mov_b32 v[72:73], v[70:71], v[78:79] op_sel:[1,0]
	s_nop 0
	v_pk_mul_f32 v[74:75], v[102:103], v[72:73]
; __device__ __forceinline__ float bflo(unsigned w) { return __uint_as_float(w << 16); }
; __device__ __forceinline__ float bfhi(unsigned w) { return __uint_as_float(w & 0xffff0000u); }
; __device__ __forceinline__ unsigned pk2(float lo, float hi) { unsigned r; asm volatile("v_cvt_pk_bf16_f32 %0, %1, %2" : "=v"(r) : "v"(lo), "v"(hi)); return r; }
; __device__ __forceinline__ void rg_conv(Frame& F) {
;     ...
;         for (int j = 0; j < CR; ++j) { v4f a0 = b0, a1 = b1;
; #pragma unroll
;             for (int k4 = 0; k4 < 4; ++k4) { const v4u xx = x[j + k4];
;                 a0.x += w0[k4].x * bflo(xx.x); a0.y += w0[k4].y * bfhi(xx.x); a0.z += w0[k4].z * bflo(xx.y); a0.w += w0[k4].w * bfhi(xx.y);
;                 a1.x += w1[k4].x * bflo(xx.z); a1.y += w1[k4].y * bfhi(xx.z); a1.z += w1[k4].z * bflo(xx.w); a1.w += w1[k4].w * bfhi(xx.w); }
;             v4u o; o.x = pk2(a0.x, a0.y); o.y = pk2(a0.z, a0.w); o.z = pk2(a1.x, a1.y); o.w = pk2(a1.z, a1.w);
;             *(v4u*)(XC + (size_t)(row0 + j) * DM + ch) = o; }
	s_nop 0
	v_add_f32_e32 v75, v75, v80
	v_add_f32_e32 v80, v74, v75
	v_pk_mul_f32 v[74:75], v[102:103], v[70:71]
	s_nop 0
	v_add_f32_e32 v75, v75, v85
	v_add_f32_e32 v129, v74, v75
	v_and_b32_e32 v75, 0xffff0000, v32
	v_and_b32_e32 v74, 0xffff0000, v36
	v_pk_mov_b32 v[76:77], v[74:75], v[82:83] op_sel:[1,0]
	s_nop 0
	v_pk_mul_f32 v[78:79], v[6:7], v[76:77]
	s_nop 0
	v_add_f32_e32 v32, v79, v81
	v_add_f32_e32 v32, v78, v32
	v_pk_mul_f32 v[78:79], v[6:7], v[74:75]
	v_cvt_pk_bf16_f32 v32, v80, v32
	s_nop 0
	v_add_f32_e32 v36, v79, v97
	v_add_f32_e32 v97, v78, v36
	v_lshlrev_b32_e32 v79, 16, v33
	v_lshlrev_b32_e32 v78, 16, v37
	v_pk_mov_b32 v[80:81], v[78:79], v[88:89] op_sel:[1,0]
	s_nop 0
	v_pk_mul_f32 v[82:83], v[100:101], v[80:81]
	s_nop 0
	v_add_f32_e32 v36, v83, v84
	v_add_f32_e32 v88, v82, v36
	v_pk_mul_f32 v[82:83], v[100:101], v[78:79]
	s_nop 0
	v_add_f32_e32 v36, v83, v110
	v_add_f32_e32 v89, v82, v36
	v_and_b32_e32 v83, 0xffff0000, v33
	v_and_b32_e32 v82, 0xffff0000, v37
	v_pk_mov_b32 v[36:37], v[82:83], v[108:109] op_sel:[1,0]
	s_nop 0
	v_pk_mul_f32 v[84:85], v[8:9], v[36:37]
	s_nop 0
	v_add_f32_e32 v33, v85, v96
	v_add_f32_e32 v33, v84, v33
	v_pk_mul_f32 v[84:85], v[8:9], v[82:83]
	v_cvt_pk_bf16_f32 v33, v88, v33
	global_store_dwordx4 v[38:39], v[30:33], off sc1
	v_add_f32_e32 v85, v85, v124
	v_lshlrev_b64 v[38:39], 13, v[122:123]
	v_add_f32_e32 v33, v84, v85
	v_cvt_pk_bf16_f32 v30, v126, v125
	v_cvt_pk_bf16_f32 v31, v127, v128
	v_cvt_pk_bf16_f32 v32, v129, v97
	v_cvt_pk_bf16_f32 v33, v89, v33
	v_lshl_add_u64 v[38:39], v[98:99], 0, v[38:39]
	global_store_dwordx4 v[38:39], v[30:33], off sc1
	s_nop 1
	v_pk_mul_f32 v[30:31], v[94:95], v[42:43]
	v_pk_mul_f32 v[32:33], v[94:95], v[40:41]
	v_add_f32_e32 v31, v31, v58
	v_add_f32_e32 v33, v33, v58
	v_add_f32_e32 v38, v30, v31
	v_pk_mul_f32 v[30:31], v[50:51], v[62:63]
	v_add_f32_e32 v39, v32, v33
	v_pk_mul_f32 v[32:33], v[50:51], v[44:45]
	v_add_f32_e32 v31, v31, v59
	v_add_f32_e32 v33, v33, v59
	v_add_f32_e32 v42, v30, v31
	v_pk_mul_f32 v[30:31], v[90:91], v[66:67]
	v_add_f32_e32 v43, v32, v33
	v_pk_mul_f32 v[32:33], v[90:91], v[64:65]
	v_add_f32_e32 v31, v31, v60
	v_add_f32_e32 v33, v33, v60
	v_add_f32_e32 v62, v30, v31
	v_pk_mul_f32 v[30:31], v[52:53], v[34:35]
	v_add_f32_e32 v63, v32, v33
	v_pk_mul_f32 v[32:33], v[52:53], v[68:69]
	v_add_f32_e32 v31, v31, v61
	v_add_f32_e32 v33, v33, v61
	v_add_f32_e32 v66, v30, v31
	v_pk_mul_f32 v[30:31], v[92:93], v[72:73]
	v_add_f32_e32 v67, v32, v33
	v_pk_mul_f32 v[32:33], v[92:93], v[70:71]
	v_add_f32_e32 v31, v31, v54
	v_add_f32_e32 v33, v33, v54
	v_add_f32_e32 v72, v30, v31
	v_pk_mul_f32 v[30:31], v[46:47], v[76:77]
	v_add_f32_e32 v77, v32, v33
	v_pk_mul_f32 v[32:33], v[46:47], v[74:75]
	v_add_f32_e32 v31, v31, v55
	v_add_f32_e32 v33, v33, v55
	v_add_f32_e32 v73, v30, v31
	v_pk_mul_f32 v[30:31], v[86:87], v[80:81]
	v_add_f32_e32 v81, v32, v33
	v_pk_mul_f32 v[32:33], v[86:87], v[78:79]
	v_add_f32_e32 v31, v31, v56
	v_add_f32_e32 v33, v33, v56
	v_add_f32_e32 v84, v32, v33
	v_pk_mul_f32 v[32:33], v[48:49], v[82:83]
	v_add_f32_e32 v76, v30, v31
	v_add_f32_e32 v33, v33, v57
	v_add_f32_e32 v85, v32, v33
	v_lshlrev_b32_e32 v33, 16, v22
	v_lshlrev_b32_e32 v32, 16, v26
	v_pk_mov_b32 v[34:35], v[32:33], v[40:41] op_sel:[1,0]
	v_pk_mul_f32 v[30:31], v[48:49], v[36:37]
	v_pk_mul_f32 v[36:37], v[106:107], v[34:35]
	v_add_f32_e32 v31, v31, v57
	v_add_f32_e32 v37, v37, v38
	v_add_f32_e32 v88, v36, v37
	v_pk_mul_f32 v[36:37], v[106:107], v[32:33]
	v_add_f32_e32 v80, v30, v31
	v_add_f32_e32 v37, v37, v39
	v_add_f32_e32 v89, v36, v37
	v_and_b32_e32 v37, 0xffff0000, v22
	v_and_b32_e32 v36, 0xffff0000, v26
	v_pk_mov_b32 v[38:39], v[36:37], v[44:45] op_sel:[1,0]
	v_lshlrev_b64 v[30:31], 13, v[120:121]
	v_pk_mul_f32 v[40:41], v[10:11], v[38:39]
	v_lshl_add_u64 v[30:31], v[98:99], 0, v[30:31]
	v_add_f32_e32 v22, v41, v42
	v_add_f32_e32 v22, v40, v22
	v_pk_mul_f32 v[40:41], v[10:11], v[36:37]
	v_cvt_pk_bf16_f32 v22, v88, v22
	s_nop 0
	v_add_f32_e32 v26, v41, v43
	v_add_f32_e32 v88, v40, v26
	v_lshlrev_b32_e32 v41, 16, v23
	v_lshlrev_b32_e32 v40, 16, v27
	v_pk_mov_b32 v[42:43], v[40:41], v[64:65] op_sel:[1,0]
	s_nop 0
	v_pk_mul_f32 v[44:45], v[104:105], v[42:43]
	s_nop 0
	v_add_f32_e32 v26, v45, v62
	v_add_f32_e32 v64, v44, v26
	v_pk_mul_f32 v[44:45], v[104:105], v[40:41]
	s_nop 0
	v_add_f32_e32 v26, v45, v63
	v_add_f32_e32 v96, v44, v26
	v_and_b32_e32 v45, 0xffff0000, v23
	v_and_b32_e32 v44, 0xffff0000, v27
	v_pk_mov_b32 v[26:27], v[44:45], v[68:69] op_sel:[1,0]
	s_nop 0
	v_pk_mul_f32 v[62:63], v[12:13], v[26:27]
	s_nop 0
	v_add_f32_e32 v23, v63, v66
	v_add_f32_e32 v23, v62, v23
	v_pk_mul_f32 v[62:63], v[12:13], v[44:45]
	v_cvt_pk_bf16_f32 v23, v64, v23
	s_nop 0
	v_add_f32_e32 v63, v63, v67
	v_add_f32_e32 v97, v62, v63
	v_lshlrev_b32_e32 v63, 16, v24
	v_lshlrev_b32_e32 v62, 16, v28
	v_pk_mov_b32 v[64:65], v[62:63], v[70:71] op_sel:[1,0]
	s_nop 0
	v_pk_mul_f32 v[66:67], v[102:103], v[64:65]
	s_nop 0
	v_add_f32_e32 v67, v67, v72
	v_add_f32_e32 v72, v66, v67
	v_pk_mul_f32 v[66:67], v[102:103], v[62:63]
	s_nop 0
	v_add_f32_e32 v67, v67, v77
	v_add_f32_e32 v108, v66, v67
	v_and_b32_e32 v67, 0xffff0000, v24
	v_and_b32_e32 v66, 0xffff0000, v28
	v_pk_mov_b32 v[68:69], v[66:67], v[74:75] op_sel:[1,0]
	s_nop 0
	v_pk_mul_f32 v[70:71], v[6:7], v[68:69]
	s_nop 0
	v_add_f32_e32 v24, v71, v73
	v_add_f32_e32 v24, v70, v24
	v_pk_mul_f32 v[70:71], v[6:7], v[66:67]
	v_cvt_pk_bf16_f32 v24, v72, v24
	s_nop 0
	v_add_f32_e32 v28, v71, v81
	v_add_f32_e32 v81, v70, v28
	v_lshlrev_b32_e32 v71, 16, v25
	v_lshlrev_b32_e32 v70, 16, v29
	v_pk_mov_b32 v[72:73], v[70:71], v[78:79] op_sel:[1,0]
; __device__ __forceinline__ float bflo(unsigned w) { return __uint_as_float(w << 16); }
; __device__ __forceinline__ float bfhi(unsigned w) { return __uint_as_float(w & 0xffff0000u); }
; __device__ __forceinline__ unsigned pk2(float lo, float hi) { unsigned r; asm volatile("v_cvt_pk_bf16_f32 %0, %1, %2" : "=v"(r) : "v"(lo), "v"(hi)); return r; }
; __device__ __forceinline__ void rg_conv(Frame& F) {
;     ...
;         for (int j = 0; j < CR; ++j) { v4f a0 = b0, a1 = b1;
; #pragma unroll
;             for (int k4 = 0; k4 < 4; ++k4) { const v4u xx = x[j + k4];
;                 a0.x += w0[k4].x * bflo(xx.x); a0.y += w0[k4].y * bfhi(xx.x); a0.z += w0[k4].z * bflo(xx.y); a0.w += w0[k4].w * bfhi(xx.y);
;                 a1.x += w1[k4].x * bflo(xx.z); a1.y += w1[k4].y * bfhi(xx.z); a1.z += w1[k4].z * bflo(xx.w); a1.w += w1[k4].w * bfhi(xx.w); }
;             v4u o; o.x = pk2(a0.x, a0.y); o.y = pk2(a0.z, a0.w); o.z = pk2(a1.x, a1.y); o.w = pk2(a1.z, a1.w);
;             *(v4u*)(XC + (size_t)(row0 + j) * DM + ch) = o; }
	s_nop 0
	v_pk_mul_f32 v[74:75], v[100:101], v[72:73]
	s_nop 0
	v_add_f32_e32 v28, v75, v76
	v_add_f32_e32 v78, v74, v28
	v_pk_mul_f32 v[74:75], v[100:101], v[70:71]
	s_nop 0
	v_add_f32_e32 v28, v75, v84
	v_add_f32_e32 v79, v74, v28
	v_and_b32_e32 v75, 0xffff0000, v25
	v_and_b32_e32 v74, 0xffff0000, v29
	v_pk_mov_b32 v[28:29], v[74:75], v[82:83] op_sel:[1,0]
	s_nop 0
	v_pk_mul_f32 v[76:77], v[8:9], v[28:29]
	s_nop 0
	v_add_f32_e32 v25, v77, v80
	v_add_f32_e32 v25, v76, v25
	v_pk_mul_f32 v[76:77], v[8:9], v[74:75]
	v_cvt_pk_bf16_f32 v25, v78, v25
	global_store_dwordx4 v[30:31], v[22:25], off sc1
	v_add_f32_e32 v77, v77, v85
	v_lshlrev_b64 v[30:31], 13, v[118:119]
	v_add_f32_e32 v25, v76, v77
	v_cvt_pk_bf16_f32 v22, v89, v88
	v_cvt_pk_bf16_f32 v23, v96, v97
	v_lshl_add_u64 v[30:31], v[98:99], 0, v[30:31]
	v_cvt_pk_bf16_f32 v24, v108, v81
	v_cvt_pk_bf16_f32 v25, v79, v25
	global_store_dwordx4 v[30:31], v[22:25], off sc1
	v_lshlrev_b32_e32 v31, 16, v15
	v_lshlrev_b32_e32 v30, 16, v19
	v_pk_mul_f32 v[22:23], v[94:95], v[34:35]
	s_nop 0
	v_add_f32_e32 v23, v23, v58
	v_add_f32_e32 v24, v22, v23
	v_pk_mul_f32 v[22:23], v[50:51], v[38:39]
	s_nop 0
	v_add_f32_e32 v23, v23, v59
	v_add_f32_e32 v25, v22, v23
	v_pk_mul_f32 v[22:23], v[90:91], v[42:43]
	v_lshlrev_b32_e32 v43, 16, v14
	v_add_f32_e32 v23, v23, v60
	v_add_f32_e32 v34, v22, v23
	v_pk_mul_f32 v[22:23], v[52:53], v[26:27]
	v_lshlrev_b32_e32 v42, 16, v18
	v_add_f32_e32 v23, v23, v61
	v_add_f32_e32 v35, v22, v23
	v_pk_mul_f32 v[22:23], v[92:93], v[64:65]
	v_pk_mov_b32 v[64:65], v[42:43], v[32:33] op_sel:[1,0]
	v_add_f32_e32 v23, v23, v54
	v_add_f32_e32 v76, v22, v23
	v_pk_mul_f32 v[22:23], v[46:47], v[68:69]
	s_nop 0
	v_add_f32_e32 v23, v23, v55
	v_add_f32_e32 v68, v22, v23
	v_pk_mul_f32 v[22:23], v[86:87], v[72:73]
	s_nop 0
	v_add_f32_e32 v23, v23, v56
	v_add_f32_e32 v72, v22, v23
	v_pk_mul_f32 v[22:23], v[48:49], v[28:29]
	v_and_b32_e32 v29, 0xffff0000, v14
	v_add_f32_e32 v23, v23, v57
	v_add_f32_e32 v73, v22, v23
	v_lshlrev_b64 v[22:23], 13, v[116:117]
	v_lshl_add_u64 v[38:39], v[98:99], 0, v[22:23]
	v_pk_mul_f32 v[22:23], v[94:95], v[32:33]
	v_and_b32_e32 v28, 0xffff0000, v18
	v_add_f32_e32 v23, v23, v58
	v_add_f32_e32 v26, v22, v23
	v_pk_mul_f32 v[22:23], v[50:51], v[36:37]
	v_pk_mov_b32 v[36:37], v[28:29], v[36:37] op_sel:[1,0]
	v_add_f32_e32 v23, v23, v59
	v_add_f32_e32 v27, v22, v23
	v_pk_mul_f32 v[22:23], v[90:91], v[40:41]
	v_pk_mov_b32 v[40:41], v[30:31], v[40:41] op_sel:[1,0]
	v_add_f32_e32 v23, v23, v60
	v_add_f32_e32 v69, v22, v23
	v_pk_mul_f32 v[22:23], v[52:53], v[44:45]
	s_nop 0
	v_add_f32_e32 v23, v23, v61
	v_add_f32_e32 v77, v22, v23
	v_pk_mul_f32 v[22:23], v[92:93], v[62:63]
	s_nop 0
	v_add_f32_e32 v23, v23, v54
	v_add_f32_e32 v78, v22, v23
	v_pk_mul_f32 v[22:23], v[46:47], v[66:67]
	s_nop 0
	v_add_f32_e32 v23, v23, v55
	v_add_f32_e32 v79, v22, v23
	v_pk_mul_f32 v[22:23], v[86:87], v[70:71]
	s_nop 0
	v_add_f32_e32 v23, v23, v56
	v_add_f32_e32 v80, v22, v23
	v_pk_mul_f32 v[22:23], v[48:49], v[74:75]
	s_nop 0
	v_add_f32_e32 v23, v23, v57
	v_add_f32_e32 v81, v22, v23
	v_pk_mul_f32 v[22:23], v[106:107], v[64:65]
	s_nop 0
	v_add_f32_e32 v23, v23, v24
	v_add_f32_e32 v24, v22, v23
	v_pk_mul_f32 v[22:23], v[106:107], v[42:43]
	s_nop 0
	v_add_f32_e32 v23, v23, v26
	v_add_f32_e32 v43, v22, v23
	v_pk_mul_f32 v[22:23], v[10:11], v[36:37]
	v_and_b32_e32 v26, 0xffff0000, v19
	v_add_f32_e32 v14, v23, v25
	v_add_f32_e32 v14, v22, v14
	v_pk_mul_f32 v[22:23], v[10:11], v[28:29]
	v_cvt_pk_bf16_f32 v32, v24, v14
	v_lshlrev_b32_e32 v25, 16, v16
	v_add_f32_e32 v18, v23, v27
	v_add_f32_e32 v29, v22, v18
	v_pk_mul_f32 v[22:23], v[104:105], v[40:41]
	v_and_b32_e32 v27, 0xffff0000, v15
	v_add_f32_e32 v14, v23, v34
	v_add_f32_e32 v18, v22, v14
	v_pk_mul_f32 v[22:23], v[104:105], v[30:31]
	v_pk_mov_b32 v[44:45], v[26:27], v[44:45] op_sel:[1,0]
	v_add_f32_e32 v14, v23, v69
	v_add_f32_e32 v31, v22, v14
	v_pk_mul_f32 v[14:15], v[12:13], v[44:45]
	v_lshlrev_b32_e32 v24, 16, v20
	v_add_f32_e32 v15, v15, v35
	v_add_f32_e32 v19, v14, v15
	v_pk_mul_f32 v[14:15], v[12:13], v[26:27]
	v_pk_mov_b32 v[62:63], v[24:25], v[62:63] op_sel:[1,0]
; __device__ __forceinline__ float bflo(unsigned w) { return __uint_as_float(w << 16); }
; __device__ __forceinline__ float bfhi(unsigned w) { return __uint_as_float(w & 0xffff0000u); }
; __device__ __forceinline__ unsigned pk2(float lo, float hi) { unsigned r; asm volatile("v_cvt_pk_bf16_f32 %0, %1, %2" : "=v"(r) : "v"(lo), "v"(hi)); return r; }
; __device__ __forceinline__ void rg_conv(Frame& F) {
;     ...
;         for (int j = 0; j < CR; ++j) { v4f a0 = b0, a1 = b1;
; #pragma unroll
;             for (int k4 = 0; k4 < 4; ++k4) { const v4u xx = x[j + k4];
;                 a0.x += w0[k4].x * bflo(xx.x); a0.y += w0[k4].y * bfhi(xx.x); a0.z += w0[k4].z * bflo(xx.y); a0.w += w0[k4].w * bfhi(xx.y);
;                 a1.x += w1[k4].x * bflo(xx.z); a1.y += w1[k4].y * bfhi(xx.z); a1.z += w1[k4].z * bflo(xx.w); a1.w += w1[k4].w * bfhi(xx.w); }
;             v4u o; o.x = pk2(a0.x, a0.y); o.y = pk2(a0.z, a0.w); o.z = pk2(a1.x, a1.y); o.w = pk2(a1.z, a1.w);
;             *(v4u*)(XC + (size_t)(row0 + j) * DM + ch) = o; }
	v_add_f32_e32 v15, v15, v77
	v_add_f32_e32 v27, v14, v15
	v_pk_mul_f32 v[14:15], v[102:103], v[62:63]
	v_cvt_pk_bf16_f32 v33, v18, v19
	v_and_b32_e32 v19, 0xffff0000, v16
	v_add_f32_e32 v15, v15, v76
	v_add_f32_e32 v22, v14, v15
	v_pk_mul_f32 v[14:15], v[102:103], v[24:25]
	v_and_b32_e32 v18, 0xffff0000, v20
	v_add_f32_e32 v15, v15, v78
	v_pk_mov_b32 v[66:67], v[18:19], v[66:67] op_sel:[1,0]
	v_add_f32_e32 v25, v14, v15
	v_pk_mul_f32 v[14:15], v[6:7], v[66:67]
	v_lshlrev_b32_e32 v23, 16, v17
	v_add_f32_e32 v15, v15, v68
	v_add_f32_e32 v16, v14, v15
	v_pk_mul_f32 v[14:15], v[6:7], v[18:19]
	v_cvt_pk_bf16_f32 v34, v22, v16
	v_lshlrev_b32_e32 v22, 16, v21
	v_add_f32_e32 v15, v15, v79
	v_pk_mov_b32 v[68:69], v[22:23], v[70:71] op_sel:[1,0]
	v_add_f32_e32 v19, v14, v15
	v_pk_mul_f32 v[14:15], v[100:101], v[68:69]
	s_nop 0
	v_add_f32_e32 v15, v15, v72
	v_add_f32_e32 v20, v14, v15
	v_pk_mul_f32 v[14:15], v[100:101], v[22:23]
	s_nop 0
	v_add_f32_e32 v15, v15, v80
	v_add_f32_e32 v23, v14, v15
	v_and_b32_e32 v15, 0xffff0000, v17
	v_and_b32_e32 v14, 0xffff0000, v21
	v_pk_mov_b32 v[70:71], v[14:15], v[74:75] op_sel:[1,0]
	s_nop 0
	v_pk_mul_f32 v[16:17], v[8:9], v[70:71]
	s_nop 0
	v_add_f32_e32 v17, v17, v73
	v_add_f32_e32 v21, v16, v17
	v_pk_mul_f32 v[16:17], v[8:9], v[14:15]
	v_cvt_pk_bf16_f32 v35, v20, v21
	global_store_dwordx4 v[38:39], v[32:35], off sc1
	v_add_f32_e32 v15, v17, v81
	v_add_f32_e32 v15, v16, v15
	v_lshlrev_b64 v[16:17], 13, v[114:115]
	v_lshl_add_u64 v[16:17], v[98:99], 0, v[16:17]
	v_cvt_pk_bf16_f32 v32, v43, v29
	v_cvt_pk_bf16_f32 v33, v31, v27
	v_cvt_pk_bf16_f32 v34, v25, v19
	v_cvt_pk_bf16_f32 v35, v23, v15
	global_store_dwordx4 v[16:17], v[32:35], off sc1
	v_pk_mul_f32 v[16:17], v[94:95], v[64:65]
	v_mov_b32_e32 v29, v30
	v_add_f32_e32 v15, v17, v58
	v_add_f32_e32 v27, v16, v15
	v_pk_mul_f32 v[16:17], v[50:51], v[36:37]
	v_pk_mul_f32 v[32:33], v[48:49], v[70:71]
	v_add_f32_e32 v15, v17, v59
	v_add_f32_e32 v25, v16, v15
	v_pk_mul_f32 v[16:17], v[90:91], v[40:41]
	s_nop 0
	v_add_f32_e32 v15, v17, v60
	v_add_f32_e32 v23, v16, v15
	v_pk_mul_f32 v[16:17], v[52:53], v[44:45]
	s_nop 0
	v_add_f32_e32 v15, v17, v61
	v_add_f32_e32 v21, v16, v15
	v_pk_mul_f32 v[16:17], v[92:93], v[62:63]
	s_nop 0
	v_add_f32_e32 v15, v17, v54
	v_add_f32_e32 v20, v16, v15
	v_pk_mul_f32 v[16:17], v[46:47], v[66:67]
	s_nop 0
	v_add_f32_e32 v15, v17, v55
	v_add_f32_e32 v19, v16, v15
	v_pk_mul_f32 v[16:17], v[86:87], v[68:69]
	s_nop 0
	v_add_f32_e32 v15, v17, v56
	v_add_f32_e32 v17, v16, v15
	v_add_f32_e32 v15, v33, v57
	v_add_f32_e32 v15, v32, v15
	v_lshlrev_b32_e32 v32, 16, v2
	v_mov_b32_e32 v33, v42
	v_pk_mul_f32 v[32:33], v[106:107], v[32:33]
	s_nop 0
	v_add_f32_e32 v16, v33, v27
	v_add_f32_e32 v16, v32, v16
	v_and_b32_e32 v32, 0xffff0000, v2
	v_mov_b32_e32 v33, v28
	v_pk_mul_f32 v[10:11], v[10:11], v[32:33]
	v_lshlrev_b32_e32 v28, 16, v3
	v_add_f32_e32 v2, v11, v25
	v_pk_mul_f32 v[28:29], v[104:105], v[28:29]
	v_add_f32_e32 v10, v10, v2
	v_add_f32_e32 v2, v29, v23
	v_add_f32_e32 v11, v28, v2
	v_and_b32_e32 v2, 0xffff0000, v3
	v_mov_b32_e32 v3, v26
	v_pk_mul_f32 v[2:3], v[12:13], v[2:3]
	s_nop 0
	v_add_f32_e32 v3, v3, v21
	v_add_f32_e32 v12, v2, v3
	v_lshlrev_b32_e32 v2, 16, v4
	v_mov_b32_e32 v3, v24
	v_pk_mul_f32 v[2:3], v[102:103], v[2:3]
	s_nop 0
	v_add_f32_e32 v3, v3, v20
	v_add_f32_e32 v13, v2, v3
	v_and_b32_e32 v2, 0xffff0000, v4
	v_mov_b32_e32 v3, v18
	v_pk_mul_f32 v[2:3], v[6:7], v[2:3]
	s_nop 0
	v_add_f32_e32 v3, v3, v19
	v_add_f32_e32 v4, v2, v3
	v_lshlrev_b32_e32 v2, 16, v5
	v_mov_b32_e32 v3, v22
	v_pk_mul_f32 v[2:3], v[100:101], v[2:3]
	s_nop 0
	v_add_f32_e32 v3, v3, v17
	v_add_f32_e32 v6, v2, v3
	v_and_b32_e32 v2, 0xffff0000, v5
	v_mov_b32_e32 v3, v14
	v_pk_mul_f32 v[2:3], v[8:9], v[2:3]
	s_nop 0
	v_add_f32_e32 v3, v3, v15
	v_add_f32_e32 v5, v2, v3
	v_cvt_pk_bf16_f32 v2, v16, v10
	v_cvt_pk_bf16_f32 v3, v11, v12
	v_cvt_pk_bf16_f32 v4, v13, v4
	v_cvt_pk_bf16_f32 v5, v6, v5
	v_lshlrev_b64 v[6:7], 13, v[112:113]
	v_lshl_add_u64 v[6:7], v[98:99], 0, v[6:7]
	global_store_dwordx4 v[6:7], v[2:5], off sc1
	s_andn2_b64 exec, exec, s[14:15]
	s_cbranch_execnz .LBB0_1157

; __device__ __forceinline__ unsigned cvt_pk_bf16(float lo, float hi) { unsigned r; asm volatile("v_cvt_pk_bf16_f32 %0, %1, %2" : "=v"(r) : "v"(lo), "v"(hi)); return r; }
; __device__ __forceinline__ float bflo(unsigned w) { return __uint_as_float(w << 16); }
; __device__ __forceinline__ float bfhi(unsigned w) { return __uint_as_float(w & 0xffff0000u); }
; __device__ __forceinline__ float sigmoidf_(float x) { return __builtin_amdgcn_rcpf(1.0f + __expf(-x)); }
;     __device__ __forceinline__ void operator()(const pg8::f32x4 (&acc)[2][2][4][2], const pg8::Unit& u, int wr, int wc, int fr, int fq) const {
;     ...
;         const int row0 = u.pm * 256 + wr * 64 + fr, ch0 = u.pn * 128 + wc * 32 + 4 * fq;
;         v4f biv[2], brv[2], spv[2];
;         v2u xv[2][2][4];
; #pragma unroll
;         for (int n = 0; n < 2; ++n)
; #pragma unroll
;             for (int ai = 0; ai < 2; ++ai)
; #pragma unroll
;                 for (int m = 0; m < 4; ++m) xv[n][ai][m] = *(const v2u*)(XC + (size_t)(row0 + ai * 128 + m * 16) * DM + ch0 + 16 * n);
; #pragma unroll
;         for (int n = 0; n < 2; ++n) { biv[n] = *(const v4f*)(gate_b + ch0 + 16 * n); brv[n] = *(const v4f*)(gate_b + DM + ch0 + 16 * n); spv[n] = *(const v4f*)(SP + ch0 + 16 * n); }
; #pragma unroll
;         for (int n = 0; n < 2; ++n) { const int ch = ch0 + 16 * n; const v4f bi = biv[n], br = brv[n], sp = spv[n];
; #pragma unroll
;             for (int ai = 0; ai < 2; ++ai)
; #pragma unroll
;                 for (int m = 0; m < 4; ++m) { const int row = row0 + ai * 128 + m * 16; const bool first = (row & (SEQ - 1)) == 0; const size_t off = (size_t)row * DM + ch;
;                     const v2u xw = xv[n][ai][m]; const float x[4] = {bflo(xw.x), bfhi(xw.x), bflo(xw.y), bfhi(xw.y)};
;                     const pg8::f32x4 vi = acc[ai][0][m][n], vr = acc[ai][1][m][n]; v4u av;
; #pragma unroll
;                     for (int j = 0; j < 4; ++j) { const float ig = sigmoidf_(vi[j] + bi[j]), rg = sigmoidf_(vr[j] + br[j]);
;                         const float la = -8.0f * rg * sp[j];
;                         const float oma = 1.0f - __expf(la);
;                         const float mult = first ? 1.0f : __builtin_amdgcn_sqrtf(oma * (2.0f - oma));
;                         av[j] = pg8::cvt_pk_bf16(oma, mult * ig * x[j]); }
.LBB0_1234:
	s_lshl_b32 s4, s6, 8
	v_mov_b32_e32 v74, v1
	v_mov_b32_e32 v75, v217
	s_add_i32 s4, s4, s59
	s_nop 0
	v_add_u32_e32 v214, s4, v75
	s_lshl_b32 s4, s12, 7
	s_or_b32 s4, s4, s60
	v_lshl_add_u32 v74, v74, 2, s4
	v_ashrrev_i32_e32 v75, 31, v74
	v_ashrrev_i32_e32 v215, 31, v214
	v_lshl_add_u64 v[76:77], v[74:75], 1, s[20:21]
	v_lshlrev_b64 v[78:79], 13, v[214:215]
	v_lshlrev_b64 v[184:185], 2, v[74:75]
	v_lshl_add_u64 v[170:171], v[76:77], 0, v[78:79]
	v_lshl_add_u64 v[74:75], s[18:19], 0, v[184:185]
	global_load_dwordx2 v[222:223], v[170:171], off
	v_lshl_add_u64 v[82:83], s[40:41], 0, v[184:185]
	global_load_dwordx4 v[146:149], v[74:75], off
	global_load_dwordx4 v[150:153], v[82:83], off
	v_lshl_add_u64 v[172:173], s[28:29], 0, v[184:185]
	global_load_dwordx4 v[142:145], v[172:173], off
	v_add_u32_e32 v198, 0x80, v214
	v_add_u32_e32 v210, 16, v214
	v_add_u32_e32 v206, 32, v214
	v_add_u32_e32 v202, 48, v214
	v_add_u32_e32 v194, 0x90, v214
	v_add_u32_e32 v190, 0xa0, v214
	v_add_u32_e32 v186, 0xb0, v214
	v_ashrrev_i32_e32 v199, 31, v198
	v_ashrrev_i32_e32 v211, 31, v210
	v_ashrrev_i32_e32 v207, 31, v206
	v_ashrrev_i32_e32 v203, 31, v202
	v_ashrrev_i32_e32 v195, 31, v194
	v_ashrrev_i32_e32 v191, 31, v190
	v_ashrrev_i32_e32 v187, 31, v186
	v_lshlrev_b64 v[78:79], 13, v[198:199]
	v_lshlrev_b64 v[80:81], 13, v[210:211]
	v_lshlrev_b64 v[84:85], 13, v[206:207]
	v_lshlrev_b64 v[174:175], 13, v[202:203]
	v_lshlrev_b64 v[176:177], 13, v[194:195]
	v_lshlrev_b64 v[178:179], 13, v[190:191]
	v_lshlrev_b64 v[180:181], 13, v[186:187]
	v_lshl_add_u64 v[182:183], v[76:77], 0, v[80:81]
	v_lshl_add_u64 v[192:193], v[76:77], 0, v[84:85]
	v_lshl_add_u64 v[174:175], v[76:77], 0, v[174:175]
	v_lshl_add_u64 v[196:197], v[76:77], 0, v[78:79]
	v_lshl_add_u64 v[176:177], v[76:77], 0, v[176:177]
	v_lshl_add_u64 v[224:225], v[76:77], 0, v[178:179]
	v_lshl_add_u64 v[226:227], v[76:77], 0, v[180:181]
	global_load_dwordx4 v[78:81], v[74:75], off offset:64
	s_nop 0
	global_load_dwordx4 v[82:85], v[82:83], off offset:64
	s_nop 0
	global_load_dwordx4 v[74:77], v[172:173], off offset:64
	global_load_dwordx2 v[228:229], v[182:183], off
	s_nop 0
	global_load_dwordx2 v[182:183], v[182:183], off offset:32
	s_nop 0
	global_load_dwordx2 v[188:189], v[170:171], off offset:32
	global_load_dwordx2 v[212:213], v[192:193], off
	global_load_dwordx2 v[208:209], v[174:175], off
	global_load_dwordx2 v[178:179], v[174:175], off offset:32
	global_load_dwordx2 v[180:181], v[192:193], off offset:32
	global_load_dwordx2 v[204:205], v[196:197], off
	global_load_dwordx2 v[200:201], v[176:177], off
	s_nop 0
	global_load_dwordx2 v[174:175], v[176:177], off offset:32
	s_nop 0
	global_load_dwordx2 v[176:177], v[196:197], off offset:32
	s_nop 0
	global_load_dwordx2 v[196:197], v[224:225], off
	global_load_dwordx2 v[192:193], v[226:227], off
	global_load_dwordx2 v[170:171], v[226:227], off offset:32
	global_load_dwordx2 v[172:173], v[224:225], off offset:32
	v_and_b32_e32 v230, 0x7ff, v214
	v_cmp_eq_u32_e64 s[10:11], 0, v230
	s_waitcnt vmcnt(0)
	v_lshlrev_b32_e32 v224, 16, v222
	v_add_f32_e32 v134, v134, v146
	v_add_f32_e32 v138, v138, v150
	v_mul_f32_e32 v138, 0xbfb8aa3b, v138
	v_exp_f32_e32 v138, v138
	v_add_f32_e32 v139, v139, v151
	v_mul_f32_e32 v139, 0xbfb8aa3b, v139
	v_exp_f32_e32 v139, v139
	v_add_f32_e32 v138, 1.0, v138
	v_rcp_f32_e32 v138, v138
	v_mul_f32_e32 v134, 0xbfb8aa3b, v134
	v_add_f32_e32 v139, 1.0, v139
	v_rcp_f32_e32 v139, v139
	v_mul_f32_e32 v138, 0xc1000000, v138
	v_mul_f32_e32 v138, v142, v138
	v_mul_f32_e32 v138, 0x3fb8aa3b, v138
	v_exp_f32_e32 v138, v138
	v_exp_f32_e32 v134, v134
	v_mul_f32_e32 v139, 0xc1000000, v139
	v_mul_f32_e32 v139, v143, v139
	v_sub_f32_e32 v138, 1.0, v138
	v_mul_f32_e32 v139, 0x3fb8aa3b, v139
	v_sub_f32_e32 v226, 2.0, v138
	v_exp_f32_e32 v139, v139
	v_mul_f32_e32 v226, v138, v226
	v_add_f32_e32 v135, v135, v147
	v_add_f32_e32 v134, 1.0, v134
	v_sqrt_f32_e32 v226, v226
	v_mul_f32_e32 v135, 0xbfb8aa3b, v135
	v_rcp_f32_e32 v134, v134
	v_exp_f32_e32 v135, v135
	v_sub_f32_e32 v139, 1.0, v139
	v_sub_f32_e32 v227, 2.0, v139
	v_cndmask_b32_e64 v226, v226, 1.0, s[10:11]
	v_mul_f32_e32 v227, v139, v227
	v_mul_f32_e32 v134, v134, v226
	v_add_f32_e32 v140, v140, v152
	v_add_f32_e32 v135, 1.0, v135
	v_sqrt_f32_e32 v227, v227
	v_mul_f32_e32 v134, v134, v224
	v_rcp_f32_e32 v135, v135
	v_cvt_pk_bf16_f32 v138, v138, v134
	v_mul_f32_e32 v134, 0xbfb8aa3b, v140
	v_add_f32_e32 v136, v136, v148
	v_exp_f32_e32 v134, v134
	v_mul_f32_e32 v136, 0xbfb8aa3b, v136
	v_exp_f32_e32 v136, v136
	v_cndmask_b32_e64 v140, v227, 1.0, s[10:11]
	v_and_b32_e32 v222, 0xffff0000, v222
	v_mul_f32_e32 v135, v135, v140
	v_mul_f32_e32 v135, v135, v222
	v_add_f32_e32 v134, 1.0, v134
	v_rcp_f32_e32 v134, v134
	v_cvt_pk_bf16_f32 v139, v139, v135
	v_add_f32_e32 v135, 1.0, v136
	v_add_f32_e32 v136, v141, v153
	v_mul_f32_e32 v136, 0xbfb8aa3b, v136
	v_exp_f32_e32 v136, v136
	v_mul_f32_e32 v134, 0xc1000000, v134
	v_mul_f32_e32 v134, v144, v134
	v_mul_f32_e32 v134, 0x3fb8aa3b, v134
	v_add_f32_e32 v136, 1.0, v136
	v_exp_f32_e32 v134, v134
	v_rcp_f32_e32 v136, v136
	v_add_f32_e32 v130, v130, v150
	v_mul_f32_e32 v130, 0xbfb8aa3b, v130
	v_sub_f32_e32 v134, 1.0, v134
	v_mul_f32_e32 v136, 0xc1000000, v136
	v_sub_f32_e32 v140, 2.0, v134
	v_mul_f32_e32 v136, v145, v136
	v_mul_f32_e32 v140, v134, v140
	v_mul_f32_e32 v136, 0x3fb8aa3b, v136
	v_sqrt_f32_e32 v140, v140
	v_exp_f32_e32 v136, v136
	v_exp_f32_e32 v130, v130
	v_rcp_f32_e32 v135, v135
	v_add_f32_e32 v137, v137, v149
	v_mul_f32_e32 v137, 0xbfb8aa3b, v137
	v_exp_f32_e32 v137, v137
	v_cndmask_b32_e64 v140, v140, 1.0, s[10:11]
	v_sub_f32_e32 v136, 1.0, v136
; __device__ __forceinline__ unsigned cvt_pk_bf16(float lo, float hi) { unsigned r; asm volatile("v_cvt_pk_bf16_f32 %0, %1, %2" : "=v"(r) : "v"(lo), "v"(hi)); return r; }
; __device__ __forceinline__ float bflo(unsigned w) { return __uint_as_float(w << 16); }
; __device__ __forceinline__ float bfhi(unsigned w) { return __uint_as_float(w & 0xffff0000u); }
; __device__ __forceinline__ float sigmoidf_(float x) { return __builtin_amdgcn_rcpf(1.0f + __expf(-x)); }
;     __device__ __forceinline__ void operator()(const pg8::f32x4 (&acc)[2][2][4][2], const pg8::Unit& u, int wr, int wc, int fr, int fq) const {
;     ...
;         for (int n = 0; n < 2; ++n) { const int ch = ch0 + 16 * n; const v4f bi = biv[n], br = brv[n], sp = spv[n];
; #pragma unroll
;             for (int ai = 0; ai < 2; ++ai)
; #pragma unroll
;                 for (int m = 0; m < 4; ++m) { const int row = row0 + ai * 128 + m * 16; const bool first = (row & (SEQ - 1)) == 0; const size_t off = (size_t)row * DM + ch;
;                     const v2u xw = xv[n][ai][m]; const float x[4] = {bflo(xw.x), bfhi(xw.x), bflo(xw.y), bfhi(xw.y)};
;                     const pg8::f32x4 vi = acc[ai][0][m][n], vr = acc[ai][1][m][n]; v4u av;
; #pragma unroll
;                     for (int j = 0; j < 4; ++j) { const float ig = sigmoidf_(vi[j] + bi[j]), rg = sigmoidf_(vr[j] + br[j]);
;                         const float la = -8.0f * rg * sp[j];
;                         const float oma = 1.0f - __expf(la);
;                         const float mult = first ? 1.0f : __builtin_amdgcn_sqrtf(oma * (2.0f - oma));
;                         av[j] = pg8::cvt_pk_bf16(oma, mult * ig * x[j]); }
;                     *(v4u*)(AU + off) = av;
;                     if (m & 1) asm volatile("" ::: "memory"); } }
	v_add_f32_e32 v130, 1.0, v130
	v_mul_f32_e32 v135, v135, v140
	v_sub_f32_e32 v140, 2.0, v136
	v_rcp_f32_e32 v130, v130
	v_mul_f32_e32 v140, v136, v140
	v_add_f32_e32 v137, 1.0, v137
	v_sqrt_f32_e32 v141, v140
	v_rcp_f32_e32 v137, v137
	v_add_f32_e32 v131, v131, v151
	v_mul_f32_e32 v130, 0xc1000000, v130
	v_mul_f32_e32 v131, 0xbfb8aa3b, v131
	v_lshlrev_b32_e32 v225, 16, v223
	v_mul_f32_e32 v130, v142, v130
	v_exp_f32_e32 v131, v131
	v_mul_f32_e32 v135, v135, v225
	v_cvt_pk_bf16_f32 v140, v134, v135
	v_cndmask_b32_e64 v134, v141, 1.0, s[10:11]
	v_mul_f32_e32 v130, 0x3fb8aa3b, v130
	v_and_b32_e32 v223, 0xffff0000, v223
	v_mul_f32_e32 v134, v137, v134
	v_exp_f32_e32 v130, v130
	v_mul_f32_e32 v134, v134, v223
	v_add_f32_e32 v126, v126, v146
	v_cvt_pk_bf16_f32 v141, v136, v134
	v_lshlrev_b64 v[134:135], 14, v[214:215]
	v_mul_f32_e32 v126, 0xbfb8aa3b, v126
	v_add_f32_e32 v131, 1.0, v131
	v_lshl_add_u64 v[134:135], s[30:31], 0, v[134:135]
	v_exp_f32_e32 v126, v126
	v_rcp_f32_e32 v131, v131
	v_lshl_add_u64 v[134:135], v[134:135], 0, v[184:185]
	v_sub_f32_e32 v130, 1.0, v130
	global_store_dwordx4 v[134:135], v[138:141], off sc1
	v_add_f32_e32 v126, 1.0, v126
	v_mul_f32_e32 v131, 0xc1000000, v131
	v_sub_f32_e32 v141, 2.0, v130
	v_mul_f32_e32 v141, v130, v141
	v_sqrt_f32_e32 v141, v141
	v_rcp_f32_e32 v126, v126
	v_add_f32_e32 v127, v127, v147
	v_mul_f32_e32 v131, v143, v131
	v_and_b32_e32 v136, 0x7ff, v210
	v_mul_f32_e32 v127, 0xbfb8aa3b, v127
	v_mul_f32_e32 v131, 0x3fb8aa3b, v131
	v_cmp_eq_u32_e32 vcc, 0, v136
	v_exp_f32_e32 v127, v127
	v_exp_f32_e32 v131, v131
	v_cndmask_b32_e64 v136, v141, 1.0, vcc
	v_lshlrev_b32_e32 v137, 16, v228
	v_mul_f32_e32 v126, v126, v136
	v_mul_f32_e32 v126, v126, v137
	v_cvt_pk_bf16_f32 v130, v130, v126
	v_add_f32_e32 v126, 1.0, v127
	v_sub_f32_e32 v127, 1.0, v131
	v_sub_f32_e32 v131, 2.0, v127
	v_mul_f32_e32 v131, v127, v131
	v_add_f32_e32 v132, v132, v152
	v_sqrt_f32_e32 v131, v131
	v_mul_f32_e32 v132, 0xbfb8aa3b, v132
	v_rcp_f32_e32 v126, v126
	v_exp_f32_e32 v132, v132
	v_cndmask_b32_e64 v131, v131, 1.0, vcc
	v_add_f32_e32 v128, v128, v148
	v_mul_f32_e32 v126, v126, v131
	v_add_f32_e32 v131, 1.0, v132
	v_rcp_f32_e32 v131, v131
	v_mul_f32_e32 v128, 0xbfb8aa3b, v128
	v_exp_f32_e32 v128, v128
	v_and_b32_e32 v138, 0xffff0000, v228
	v_mul_f32_e32 v131, 0xc1000000, v131
	v_mul_f32_e32 v131, v144, v131
	v_mul_f32_e32 v126, v126, v138
	v_mul_f32_e32 v131, 0x3fb8aa3b, v131
	v_exp_f32_e32 v132, v131
	v_cvt_pk_bf16_f32 v131, v127, v126
	v_add_f32_e32 v126, 1.0, v128
	v_add_f32_e32 v128, v133, v153
	v_mul_f32_e32 v128, 0xbfb8aa3b, v128
	v_exp_f32_e32 v128, v128
	v_sub_f32_e32 v127, 1.0, v132
	v_sub_f32_e32 v132, 2.0, v127
	v_add_f32_e32 v122, v122, v150
	v_add_f32_e32 v128, 1.0, v128
	v_rcp_f32_e32 v128, v128
	v_mul_f32_e32 v132, v127, v132
	v_mul_f32_e32 v122, 0xbfb8aa3b, v122
	v_sqrt_f32_e32 v132, v132
	v_mul_f32_e32 v128, 0xc1000000, v128
	v_mul_f32_e32 v128, v145, v128
	v_mul_f32_e32 v128, 0x3fb8aa3b, v128
	v_exp_f32_e32 v128, v128
	v_exp_f32_e32 v122, v122
	v_rcp_f32_e32 v126, v126
	v_add_f32_e32 v129, v129, v149
	v_mul_f32_e32 v129, 0xbfb8aa3b, v129
	v_exp_f32_e32 v129, v129
	v_cndmask_b32_e64 v132, v132, 1.0, vcc
	v_sub_f32_e32 v128, 1.0, v128
	v_add_f32_e32 v122, 1.0, v122
	v_mul_f32_e32 v126, v126, v132
	v_sub_f32_e32 v132, 2.0, v128
	v_rcp_f32_e32 v122, v122
	v_mul_f32_e32 v132, v128, v132
	v_add_f32_e32 v129, 1.0, v129
	v_sqrt_f32_e32 v133, v132
	v_rcp_f32_e32 v129, v129
	v_add_f32_e32 v123, v123, v151
	v_lshlrev_b32_e32 v139, 16, v229
	v_mul_f32_e32 v122, 0xc1000000, v122
	v_mul_f32_e32 v123, 0xbfb8aa3b, v123
	v_mul_f32_e32 v126, v126, v139
	v_mul_f32_e32 v122, v142, v122
	v_exp_f32_e32 v123, v123
	v_cvt_pk_bf16_f32 v132, v127, v126
	v_cndmask_b32_e64 v126, v133, 1.0, vcc
	v_mul_f32_e32 v122, 0x3fb8aa3b, v122
	v_and_b32_e32 v140, 0xffff0000, v229
	v_mul_f32_e32 v126, v129, v126
	v_exp_f32_e32 v122, v122
	v_mul_f32_e32 v126, v126, v140
	v_add_f32_e32 v118, v118, v146
	v_cvt_pk_bf16_f32 v133, v128, v126
	v_lshlrev_b64 v[126:127], 14, v[210:211]
	v_mul_f32_e32 v118, 0xbfb8aa3b, v118
	v_add_f32_e32 v123, 1.0, v123
	v_lshl_add_u64 v[126:127], s[30:31], 0, v[126:127]
	v_exp_f32_e32 v118, v118
	v_rcp_f32_e32 v123, v123
	v_lshl_add_u64 v[126:127], v[126:127], 0, v[184:185]
	v_sub_f32_e32 v122, 1.0, v122
	global_store_dwordx4 v[126:127], v[130:133], off sc1
	v_add_f32_e32 v118, 1.0, v118
	v_mul_f32_e32 v123, 0xc1000000, v123
	v_sub_f32_e32 v133, 2.0, v122
	v_mul_f32_e32 v133, v122, v133
	v_sqrt_f32_e32 v133, v133
	v_rcp_f32_e32 v118, v118
	v_add_f32_e32 v119, v119, v147
	v_mul_f32_e32 v123, v143, v123
	v_and_b32_e32 v128, 0x7ff, v206
	v_mul_f32_e32 v119, 0xbfb8aa3b, v119
	v_mul_f32_e32 v123, 0x3fb8aa3b, v123
	v_cmp_eq_u32_e64 s[4:5], 0, v128
	v_exp_f32_e32 v119, v119
	v_exp_f32_e32 v123, v123
	v_cndmask_b32_e64 v128, v133, 1.0, s[4:5]
	v_lshlrev_b32_e32 v129, 16, v212
	v_mul_f32_e32 v118, v118, v128
	v_mul_f32_e32 v118, v118, v129
	v_cvt_pk_bf16_f32 v122, v122, v118
	v_add_f32_e32 v118, 1.0, v119
	v_sub_f32_e32 v119, 1.0, v123
	v_sub_f32_e32 v123, 2.0, v119
	v_mul_f32_e32 v123, v119, v123
	v_add_f32_e32 v124, v124, v152
	v_sqrt_f32_e32 v123, v123
	v_mul_f32_e32 v124, 0xbfb8aa3b, v124
	v_rcp_f32_e32 v118, v118
	v_exp_f32_e32 v124, v124
	v_cndmask_b32_e64 v123, v123, 1.0, s[4:5]
	v_add_f32_e32 v120, v120, v148
	v_mul_f32_e32 v118, v118, v123
	v_add_f32_e32 v123, 1.0, v124
	v_rcp_f32_e32 v123, v123
	v_mul_f32_e32 v120, 0xbfb8aa3b, v120
	v_exp_f32_e32 v120, v120
	v_and_b32_e32 v130, 0xffff0000, v212
	v_mul_f32_e32 v123, 0xc1000000, v123
	v_mul_f32_e32 v123, v144, v123
	v_mul_f32_e32 v118, v118, v130
	v_mul_f32_e32 v123, 0x3fb8aa3b, v123
; __device__ __forceinline__ unsigned cvt_pk_bf16(float lo, float hi) { unsigned r; asm volatile("v_cvt_pk_bf16_f32 %0, %1, %2" : "=v"(r) : "v"(lo), "v"(hi)); return r; }
; __device__ __forceinline__ float bflo(unsigned w) { return __uint_as_float(w << 16); }
; __device__ __forceinline__ float bfhi(unsigned w) { return __uint_as_float(w & 0xffff0000u); }
; __device__ __forceinline__ float sigmoidf_(float x) { return __builtin_amdgcn_rcpf(1.0f + __expf(-x)); }
;     __device__ __forceinline__ void operator()(const pg8::f32x4 (&acc)[2][2][4][2], const pg8::Unit& u, int wr, int wc, int fr, int fq) const {
;     ...
;         for (int n = 0; n < 2; ++n) { const int ch = ch0 + 16 * n; const v4f bi = biv[n], br = brv[n], sp = spv[n];
; #pragma unroll
;             for (int ai = 0; ai < 2; ++ai)
; #pragma unroll
;                 for (int m = 0; m < 4; ++m) { const int row = row0 + ai * 128 + m * 16; const bool first = (row & (SEQ - 1)) == 0; const size_t off = (size_t)row * DM + ch;
;                     const v2u xw = xv[n][ai][m]; const float x[4] = {bflo(xw.x), bfhi(xw.x), bflo(xw.y), bfhi(xw.y)};
;                     const pg8::f32x4 vi = acc[ai][0][m][n], vr = acc[ai][1][m][n]; v4u av;
; #pragma unroll
;                     for (int j = 0; j < 4; ++j) { const float ig = sigmoidf_(vi[j] + bi[j]), rg = sigmoidf_(vr[j] + br[j]);
;                         const float la = -8.0f * rg * sp[j];
;                         const float oma = 1.0f - __expf(la);
;                         const float mult = first ? 1.0f : __builtin_amdgcn_sqrtf(oma * (2.0f - oma));
;                         av[j] = pg8::cvt_pk_bf16(oma, mult * ig * x[j]); }
;                     *(v4u*)(AU + off) = av;
;                     if (m & 1) asm volatile("" ::: "memory"); } }
	v_exp_f32_e32 v124, v123
	v_cvt_pk_bf16_f32 v123, v119, v118
	v_add_f32_e32 v118, 1.0, v120
	v_add_f32_e32 v120, v125, v153
	v_mul_f32_e32 v120, 0xbfb8aa3b, v120
	v_exp_f32_e32 v120, v120
	v_sub_f32_e32 v119, 1.0, v124
	v_sub_f32_e32 v124, 2.0, v119
	v_add_f32_e32 v114, v114, v150
	v_add_f32_e32 v120, 1.0, v120
	v_rcp_f32_e32 v120, v120
	v_mul_f32_e32 v124, v119, v124
	v_mul_f32_e32 v114, 0xbfb8aa3b, v114
	v_sqrt_f32_e32 v124, v124
	v_mul_f32_e32 v120, 0xc1000000, v120
	v_mul_f32_e32 v120, v145, v120
	v_mul_f32_e32 v120, 0x3fb8aa3b, v120
	v_exp_f32_e32 v120, v120
	v_exp_f32_e32 v114, v114
	v_rcp_f32_e32 v118, v118
	v_add_f32_e32 v121, v121, v149
	v_mul_f32_e32 v121, 0xbfb8aa3b, v121
	v_exp_f32_e32 v121, v121
	v_cndmask_b32_e64 v124, v124, 1.0, s[4:5]
	v_sub_f32_e32 v120, 1.0, v120
	v_add_f32_e32 v114, 1.0, v114
	v_mul_f32_e32 v118, v118, v124
	v_sub_f32_e32 v124, 2.0, v120
	v_rcp_f32_e32 v114, v114
	v_mul_f32_e32 v124, v120, v124
	v_add_f32_e32 v121, 1.0, v121
	v_sqrt_f32_e32 v125, v124
	v_rcp_f32_e32 v121, v121
	v_add_f32_e32 v115, v115, v151
	v_lshlrev_b32_e32 v131, 16, v213
	v_mul_f32_e32 v114, 0xc1000000, v114
	v_mul_f32_e32 v115, 0xbfb8aa3b, v115
	v_mul_f32_e32 v118, v118, v131
	v_mul_f32_e32 v114, v142, v114
	v_exp_f32_e32 v115, v115
	v_cvt_pk_bf16_f32 v124, v119, v118
	v_cndmask_b32_e64 v118, v125, 1.0, s[4:5]
	v_mul_f32_e32 v114, 0x3fb8aa3b, v114
	v_and_b32_e32 v132, 0xffff0000, v213
	v_mul_f32_e32 v118, v121, v118
	v_exp_f32_e32 v114, v114
	v_mul_f32_e32 v118, v118, v132
	v_add_f32_e32 v110, v110, v146
	v_cvt_pk_bf16_f32 v125, v120, v118
	v_lshlrev_b64 v[118:119], 14, v[206:207]
	v_mul_f32_e32 v110, 0xbfb8aa3b, v110
	v_add_f32_e32 v115, 1.0, v115
	v_lshl_add_u64 v[118:119], s[30:31], 0, v[118:119]
	v_exp_f32_e32 v110, v110
	v_rcp_f32_e32 v115, v115
	v_lshl_add_u64 v[118:119], v[118:119], 0, v[184:185]
	v_sub_f32_e32 v114, 1.0, v114
	global_store_dwordx4 v[118:119], v[122:125], off sc1
	v_add_f32_e32 v110, 1.0, v110
	v_mul_f32_e32 v115, 0xc1000000, v115
	v_sub_f32_e32 v125, 2.0, v114
	v_mul_f32_e32 v125, v114, v125
	v_sqrt_f32_e32 v125, v125
	v_rcp_f32_e32 v110, v110
	v_add_f32_e32 v111, v111, v147
	v_mul_f32_e32 v115, v143, v115
	v_and_b32_e32 v120, 0x7ff, v202
	v_mul_f32_e32 v111, 0xbfb8aa3b, v111
	v_mul_f32_e32 v115, 0x3fb8aa3b, v115
	v_cmp_eq_u32_e64 s[6:7], 0, v120
	v_exp_f32_e32 v111, v111
	v_exp_f32_e32 v115, v115
	v_cndmask_b32_e64 v120, v125, 1.0, s[6:7]
	v_lshlrev_b32_e32 v121, 16, v208
	v_mul_f32_e32 v110, v110, v120
	v_mul_f32_e32 v110, v110, v121
	v_cvt_pk_bf16_f32 v114, v114, v110
	v_add_f32_e32 v110, 1.0, v111
	v_sub_f32_e32 v111, 1.0, v115
	v_sub_f32_e32 v115, 2.0, v111
	v_mul_f32_e32 v115, v111, v115
	v_add_f32_e32 v116, v116, v152
	v_sqrt_f32_e32 v115, v115
	v_mul_f32_e32 v116, 0xbfb8aa3b, v116
	v_rcp_f32_e32 v110, v110
	v_exp_f32_e32 v116, v116
	v_cndmask_b32_e64 v115, v115, 1.0, s[6:7]
	v_add_f32_e32 v112, v112, v148
	v_mul_f32_e32 v110, v110, v115
	v_add_f32_e32 v115, 1.0, v116
	v_rcp_f32_e32 v115, v115
	v_mul_f32_e32 v112, 0xbfb8aa3b, v112
	v_exp_f32_e32 v112, v112
	v_and_b32_e32 v122, 0xffff0000, v208
	v_mul_f32_e32 v115, 0xc1000000, v115
	v_mul_f32_e32 v115, v144, v115
	v_mul_f32_e32 v110, v110, v122
	v_mul_f32_e32 v115, 0x3fb8aa3b, v115
	v_exp_f32_e32 v116, v115
	v_cvt_pk_bf16_f32 v115, v111, v110
	v_add_f32_e32 v110, 1.0, v112
	v_add_f32_e32 v112, v117, v153
	v_mul_f32_e32 v112, 0xbfb8aa3b, v112
	v_exp_f32_e32 v112, v112
	v_sub_f32_e32 v111, 1.0, v116
	v_sub_f32_e32 v116, 2.0, v111
	v_add_f32_e32 v106, v106, v150
	v_add_f32_e32 v112, 1.0, v112
	v_rcp_f32_e32 v112, v112
	v_mul_f32_e32 v116, v111, v116
	v_mul_f32_e32 v106, 0xbfb8aa3b, v106
	v_sqrt_f32_e32 v116, v116
	v_mul_f32_e32 v112, 0xc1000000, v112
	v_mul_f32_e32 v112, v145, v112
	v_mul_f32_e32 v112, 0x3fb8aa3b, v112
	v_exp_f32_e32 v112, v112
	v_exp_f32_e32 v106, v106
	v_rcp_f32_e32 v110, v110
	v_add_f32_e32 v113, v113, v149
	v_mul_f32_e32 v113, 0xbfb8aa3b, v113
	v_exp_f32_e32 v113, v113
	v_cndmask_b32_e64 v116, v116, 1.0, s[6:7]
	v_sub_f32_e32 v112, 1.0, v112
	v_add_f32_e32 v106, 1.0, v106
	v_mul_f32_e32 v110, v110, v116
	v_sub_f32_e32 v116, 2.0, v112
	v_rcp_f32_e32 v106, v106
	v_mul_f32_e32 v116, v112, v116
	v_add_f32_e32 v113, 1.0, v113
	v_sqrt_f32_e32 v117, v116
	v_rcp_f32_e32 v113, v113
	v_add_f32_e32 v107, v107, v151
	v_lshlrev_b32_e32 v123, 16, v209
	v_mul_f32_e32 v106, 0xc1000000, v106
	v_mul_f32_e32 v107, 0xbfb8aa3b, v107
	v_mul_f32_e32 v110, v110, v123
	v_mul_f32_e32 v106, v142, v106
	v_exp_f32_e32 v107, v107
	v_cvt_pk_bf16_f32 v116, v111, v110
	v_cndmask_b32_e64 v110, v117, 1.0, s[6:7]
	v_mul_f32_e32 v106, 0x3fb8aa3b, v106
	v_and_b32_e32 v124, 0xffff0000, v209
	v_mul_f32_e32 v110, v113, v110
	v_exp_f32_e32 v106, v106
	v_mul_f32_e32 v110, v110, v124
	v_add_f32_e32 v102, v102, v146
	v_cvt_pk_bf16_f32 v117, v112, v110
	v_lshlrev_b64 v[110:111], 14, v[202:203]
	v_mul_f32_e32 v102, 0xbfb8aa3b, v102
	v_add_f32_e32 v107, 1.0, v107
	v_lshl_add_u64 v[110:111], s[30:31], 0, v[110:111]
	v_exp_f32_e32 v102, v102
	v_rcp_f32_e32 v107, v107
	v_lshl_add_u64 v[110:111], v[110:111], 0, v[184:185]
	v_sub_f32_e32 v106, 1.0, v106
	global_store_dwordx4 v[110:111], v[114:117], off sc1
	v_add_f32_e32 v102, 1.0, v102
	v_mul_f32_e32 v107, 0xc1000000, v107
	v_sub_f32_e32 v117, 2.0, v106
	v_mul_f32_e32 v117, v106, v117
	v_sqrt_f32_e32 v117, v117
	v_rcp_f32_e32 v102, v102
	v_add_f32_e32 v103, v103, v147
	v_mul_f32_e32 v107, v143, v107
	v_and_b32_e32 v112, 0x7ff, v198
	v_mul_f32_e32 v103, 0xbfb8aa3b, v103
	v_mul_f32_e32 v107, 0x3fb8aa3b, v107
	v_cmp_eq_u32_e64 s[8:9], 0, v112
	v_exp_f32_e32 v103, v103
	v_exp_f32_e32 v107, v107
	v_cndmask_b32_e64 v112, v117, 1.0, s[8:9]
; __device__ __forceinline__ unsigned cvt_pk_bf16(float lo, float hi) { unsigned r; asm volatile("v_cvt_pk_bf16_f32 %0, %1, %2" : "=v"(r) : "v"(lo), "v"(hi)); return r; }
; __device__ __forceinline__ float bflo(unsigned w) { return __uint_as_float(w << 16); }
; __device__ __forceinline__ float bfhi(unsigned w) { return __uint_as_float(w & 0xffff0000u); }
; __device__ __forceinline__ float sigmoidf_(float x) { return __builtin_amdgcn_rcpf(1.0f + __expf(-x)); }
;     __device__ __forceinline__ void operator()(const pg8::f32x4 (&acc)[2][2][4][2], const pg8::Unit& u, int wr, int wc, int fr, int fq) const {
;     ...
;         for (int n = 0; n < 2; ++n) { const int ch = ch0 + 16 * n; const v4f bi = biv[n], br = brv[n], sp = spv[n];
; #pragma unroll
;             for (int ai = 0; ai < 2; ++ai)
; #pragma unroll
;                 for (int m = 0; m < 4; ++m) { const int row = row0 + ai * 128 + m * 16; const bool first = (row & (SEQ - 1)) == 0; const size_t off = (size_t)row * DM + ch;
;                     const v2u xw = xv[n][ai][m]; const float x[4] = {bflo(xw.x), bfhi(xw.x), bflo(xw.y), bfhi(xw.y)};
;                     const pg8::f32x4 vi = acc[ai][0][m][n], vr = acc[ai][1][m][n]; v4u av;
; #pragma unroll
;                     for (int j = 0; j < 4; ++j) { const float ig = sigmoidf_(vi[j] + bi[j]), rg = sigmoidf_(vr[j] + br[j]);
;                         const float la = -8.0f * rg * sp[j];
;                         const float oma = 1.0f - __expf(la);
;                         const float mult = first ? 1.0f : __builtin_amdgcn_sqrtf(oma * (2.0f - oma));
;                         av[j] = pg8::cvt_pk_bf16(oma, mult * ig * x[j]); }
;                     *(v4u*)(AU + off) = av;
;                     if (m & 1) asm volatile("" ::: "memory"); } }
	v_lshlrev_b32_e32 v113, 16, v204
	v_mul_f32_e32 v102, v102, v112
	v_mul_f32_e32 v102, v102, v113
	v_cvt_pk_bf16_f32 v106, v106, v102
	v_add_f32_e32 v102, 1.0, v103
	v_sub_f32_e32 v103, 1.0, v107
	v_sub_f32_e32 v107, 2.0, v103
	v_mul_f32_e32 v107, v103, v107
	v_add_f32_e32 v108, v108, v152
	v_sqrt_f32_e32 v107, v107
	v_mul_f32_e32 v108, 0xbfb8aa3b, v108
	v_rcp_f32_e32 v102, v102
	v_exp_f32_e32 v108, v108
	v_cndmask_b32_e64 v107, v107, 1.0, s[8:9]
	v_add_f32_e32 v104, v104, v148
	v_mul_f32_e32 v102, v102, v107
	v_add_f32_e32 v107, 1.0, v108
	v_rcp_f32_e32 v107, v107
	v_mul_f32_e32 v104, 0xbfb8aa3b, v104
	v_exp_f32_e32 v104, v104
	v_and_b32_e32 v114, 0xffff0000, v204
	v_mul_f32_e32 v107, 0xc1000000, v107
	v_mul_f32_e32 v107, v144, v107
	v_mul_f32_e32 v102, v102, v114
	v_mul_f32_e32 v107, 0x3fb8aa3b, v107
	v_exp_f32_e32 v108, v107
	v_cvt_pk_bf16_f32 v107, v103, v102
	v_add_f32_e32 v102, 1.0, v104
	v_add_f32_e32 v104, v109, v153
	v_mul_f32_e32 v104, 0xbfb8aa3b, v104
	v_exp_f32_e32 v104, v104
	v_sub_f32_e32 v103, 1.0, v108
	v_sub_f32_e32 v108, 2.0, v103
	v_add_f32_e32 v98, v98, v150
	v_add_f32_e32 v104, 1.0, v104
	v_rcp_f32_e32 v104, v104
	v_mul_f32_e32 v108, v103, v108
	v_mul_f32_e32 v98, 0xbfb8aa3b, v98
	v_sqrt_f32_e32 v108, v108
	v_mul_f32_e32 v104, 0xc1000000, v104
	v_mul_f32_e32 v104, v145, v104
	v_mul_f32_e32 v104, 0x3fb8aa3b, v104
	v_exp_f32_e32 v104, v104
	v_exp_f32_e32 v98, v98
	v_rcp_f32_e32 v102, v102
	v_add_f32_e32 v105, v105, v149
	v_mul_f32_e32 v105, 0xbfb8aa3b, v105
	v_exp_f32_e32 v105, v105
	v_cndmask_b32_e64 v108, v108, 1.0, s[8:9]
	v_sub_f32_e32 v104, 1.0, v104
	v_add_f32_e32 v98, 1.0, v98
	v_mul_f32_e32 v102, v102, v108
	v_sub_f32_e32 v108, 2.0, v104
	v_rcp_f32_e32 v98, v98
	v_mul_f32_e32 v108, v104, v108
	v_add_f32_e32 v105, 1.0, v105
	v_sqrt_f32_e32 v109, v108
	v_rcp_f32_e32 v105, v105
	v_add_f32_e32 v99, v99, v151
	v_lshlrev_b32_e32 v115, 16, v205
	v_mul_f32_e32 v98, 0xc1000000, v98
	v_mul_f32_e32 v99, 0xbfb8aa3b, v99
	v_mul_f32_e32 v102, v102, v115
	v_mul_f32_e32 v98, v142, v98
	v_exp_f32_e32 v99, v99
	v_cvt_pk_bf16_f32 v108, v103, v102
	v_cndmask_b32_e64 v102, v109, 1.0, s[8:9]
	v_mul_f32_e32 v98, 0x3fb8aa3b, v98
	v_and_b32_e32 v116, 0xffff0000, v205
	v_mul_f32_e32 v102, v105, v102
	v_exp_f32_e32 v98, v98
	v_mul_f32_e32 v102, v102, v116
	v_add_f32_e32 v94, v94, v146
	v_cvt_pk_bf16_f32 v109, v104, v102
	v_lshlrev_b64 v[102:103], 14, v[198:199]
	v_mul_f32_e32 v94, 0xbfb8aa3b, v94
	v_add_f32_e32 v99, 1.0, v99
	v_lshl_add_u64 v[102:103], s[30:31], 0, v[102:103]
	v_exp_f32_e32 v94, v94
	v_rcp_f32_e32 v99, v99
	v_lshl_add_u64 v[102:103], v[102:103], 0, v[184:185]
	v_sub_f32_e32 v98, 1.0, v98
	global_store_dwordx4 v[102:103], v[106:109], off sc1
	v_add_f32_e32 v94, 1.0, v94
	v_mul_f32_e32 v99, 0xc1000000, v99
	v_sub_f32_e32 v109, 2.0, v98
	v_mul_f32_e32 v109, v98, v109
	v_sqrt_f32_e32 v109, v109
	v_rcp_f32_e32 v94, v94
	v_add_f32_e32 v95, v95, v147
	v_mul_f32_e32 v99, v143, v99
	v_and_b32_e32 v104, 0x7ff, v194
	v_mul_f32_e32 v95, 0xbfb8aa3b, v95
	v_mul_f32_e32 v99, 0x3fb8aa3b, v99
	v_cmp_eq_u32_e64 s[12:13], 0, v104
	v_exp_f32_e32 v95, v95
	v_exp_f32_e32 v99, v99
	v_cndmask_b32_e64 v104, v109, 1.0, s[12:13]
	v_lshlrev_b32_e32 v105, 16, v200
	v_mul_f32_e32 v94, v94, v104
	v_mul_f32_e32 v94, v94, v105
	v_cvt_pk_bf16_f32 v98, v98, v94
	v_add_f32_e32 v94, 1.0, v95
	v_sub_f32_e32 v95, 1.0, v99
	v_sub_f32_e32 v99, 2.0, v95
	v_mul_f32_e32 v99, v95, v99
	v_add_f32_e32 v100, v100, v152
	v_sqrt_f32_e32 v99, v99
	v_mul_f32_e32 v100, 0xbfb8aa3b, v100
	v_rcp_f32_e32 v94, v94
	v_exp_f32_e32 v100, v100
	v_cndmask_b32_e64 v99, v99, 1.0, s[12:13]
	v_add_f32_e32 v96, v96, v148
	v_mul_f32_e32 v94, v94, v99
	v_add_f32_e32 v99, 1.0, v100
	v_rcp_f32_e32 v99, v99
	v_mul_f32_e32 v96, 0xbfb8aa3b, v96
	v_exp_f32_e32 v96, v96
	v_and_b32_e32 v106, 0xffff0000, v200
	v_mul_f32_e32 v99, 0xc1000000, v99
	v_mul_f32_e32 v99, v144, v99
	v_mul_f32_e32 v94, v94, v106
	v_mul_f32_e32 v99, 0x3fb8aa3b, v99
	v_exp_f32_e32 v100, v99
	v_cvt_pk_bf16_f32 v99, v95, v94
	v_add_f32_e32 v94, 1.0, v96
	v_add_f32_e32 v96, v101, v153
	v_mul_f32_e32 v96, 0xbfb8aa3b, v96
	v_exp_f32_e32 v96, v96
	v_sub_f32_e32 v95, 1.0, v100
	v_sub_f32_e32 v100, 2.0, v95
	v_add_f32_e32 v90, v90, v150
	v_add_f32_e32 v96, 1.0, v96
	v_rcp_f32_e32 v96, v96
	v_mul_f32_e32 v100, v95, v100
	v_mul_f32_e32 v90, 0xbfb8aa3b, v90
	v_sqrt_f32_e32 v100, v100
	v_mul_f32_e32 v96, 0xc1000000, v96
	v_mul_f32_e32 v96, v145, v96
	v_mul_f32_e32 v96, 0x3fb8aa3b, v96
	v_exp_f32_e32 v96, v96
	v_exp_f32_e32 v90, v90
	v_rcp_f32_e32 v94, v94
	v_add_f32_e32 v97, v97, v149
	v_mul_f32_e32 v97, 0xbfb8aa3b, v97
	v_exp_f32_e32 v97, v97
	v_cndmask_b32_e64 v100, v100, 1.0, s[12:13]
	v_sub_f32_e32 v96, 1.0, v96
	v_add_f32_e32 v90, 1.0, v90
	v_mul_f32_e32 v94, v94, v100
	v_sub_f32_e32 v100, 2.0, v96
	v_rcp_f32_e32 v90, v90
	v_mul_f32_e32 v100, v96, v100
	v_add_f32_e32 v97, 1.0, v97
	v_sqrt_f32_e32 v101, v100
	v_rcp_f32_e32 v97, v97
	v_add_f32_e32 v91, v91, v151
	v_lshlrev_b32_e32 v107, 16, v201
	v_mul_f32_e32 v90, 0xc1000000, v90
	v_mul_f32_e32 v91, 0xbfb8aa3b, v91
	v_mul_f32_e32 v94, v94, v107
	v_mul_f32_e32 v90, v142, v90
	v_exp_f32_e32 v91, v91
	v_cvt_pk_bf16_f32 v100, v95, v94
	v_cndmask_b32_e64 v94, v101, 1.0, s[12:13]
	v_mul_f32_e32 v90, 0x3fb8aa3b, v90
	v_and_b32_e32 v108, 0xffff0000, v201
	v_mul_f32_e32 v94, v97, v94
	v_exp_f32_e32 v90, v90
	v_mul_f32_e32 v94, v94, v108
	v_add_f32_e32 v86, v86, v146
	v_cvt_pk_bf16_f32 v101, v96, v94
	v_lshlrev_b64 v[94:95], 14, v[194:195]
	v_mul_f32_e32 v86, 0xbfb8aa3b, v86
	v_add_f32_e32 v91, 1.0, v91
	v_lshl_add_u64 v[94:95], s[30:31], 0, v[94:95]
	v_exp_f32_e32 v86, v86
	v_rcp_f32_e32 v91, v91
; __device__ __forceinline__ unsigned cvt_pk_bf16(float lo, float hi) { unsigned r; asm volatile("v_cvt_pk_bf16_f32 %0, %1, %2" : "=v"(r) : "v"(lo), "v"(hi)); return r; }
; __device__ __forceinline__ float bflo(unsigned w) { return __uint_as_float(w << 16); }
; __device__ __forceinline__ float bfhi(unsigned w) { return __uint_as_float(w & 0xffff0000u); }
; __device__ __forceinline__ float sigmoidf_(float x) { return __builtin_amdgcn_rcpf(1.0f + __expf(-x)); }
;     __device__ __forceinline__ void operator()(const pg8::f32x4 (&acc)[2][2][4][2], const pg8::Unit& u, int wr, int wc, int fr, int fq) const {
;     ...
;         for (int n = 0; n < 2; ++n) { const int ch = ch0 + 16 * n; const v4f bi = biv[n], br = brv[n], sp = spv[n];
; #pragma unroll
;             for (int ai = 0; ai < 2; ++ai)
; #pragma unroll
;                 for (int m = 0; m < 4; ++m) { const int row = row0 + ai * 128 + m * 16; const bool first = (row & (SEQ - 1)) == 0; const size_t off = (size_t)row * DM + ch;
;                     const v2u xw = xv[n][ai][m]; const float x[4] = {bflo(xw.x), bfhi(xw.x), bflo(xw.y), bfhi(xw.y)};
;                     const pg8::f32x4 vi = acc[ai][0][m][n], vr = acc[ai][1][m][n]; v4u av;
; #pragma unroll
;                     for (int j = 0; j < 4; ++j) { const float ig = sigmoidf_(vi[j] + bi[j]), rg = sigmoidf_(vr[j] + br[j]);
;                         const float la = -8.0f * rg * sp[j];
;                         const float oma = 1.0f - __expf(la);
;                         const float mult = first ? 1.0f : __builtin_amdgcn_sqrtf(oma * (2.0f - oma));
;                         av[j] = pg8::cvt_pk_bf16(oma, mult * ig * x[j]); }
;                     *(v4u*)(AU + off) = av;
;                     if (m & 1) asm volatile("" ::: "memory"); } }
	v_lshl_add_u64 v[94:95], v[94:95], 0, v[184:185]
	v_sub_f32_e32 v90, 1.0, v90
	global_store_dwordx4 v[94:95], v[98:101], off sc1
	v_add_f32_e32 v86, 1.0, v86
	v_mul_f32_e32 v91, 0xc1000000, v91
	v_sub_f32_e32 v101, 2.0, v90
	v_mul_f32_e32 v101, v90, v101
	v_sqrt_f32_e32 v101, v101
	v_rcp_f32_e32 v86, v86
	v_add_f32_e32 v87, v87, v147
	v_mul_f32_e32 v91, v143, v91
	v_and_b32_e32 v96, 0x7ff, v190
	v_mul_f32_e32 v87, 0xbfb8aa3b, v87
	v_mul_f32_e32 v91, 0x3fb8aa3b, v91
	v_cmp_eq_u32_e64 s[14:15], 0, v96
	v_exp_f32_e32 v87, v87
	v_exp_f32_e32 v91, v91
	v_cndmask_b32_e64 v96, v101, 1.0, s[14:15]
	v_lshlrev_b32_e32 v97, 16, v196
	v_mul_f32_e32 v86, v86, v96
	v_mul_f32_e32 v86, v86, v97
	v_cvt_pk_bf16_f32 v90, v90, v86
	v_add_f32_e32 v86, 1.0, v87
	v_sub_f32_e32 v87, 1.0, v91
	v_sub_f32_e32 v91, 2.0, v87
	v_mul_f32_e32 v91, v87, v91
	v_add_f32_e32 v92, v92, v152
	v_sqrt_f32_e32 v91, v91
	v_mul_f32_e32 v92, 0xbfb8aa3b, v92
	v_rcp_f32_e32 v86, v86
	v_exp_f32_e32 v92, v92
	v_cndmask_b32_e64 v91, v91, 1.0, s[14:15]
	v_add_f32_e32 v88, v88, v148
	v_mul_f32_e32 v86, v86, v91
	v_add_f32_e32 v91, 1.0, v92
	v_rcp_f32_e32 v91, v91
	v_mul_f32_e32 v88, 0xbfb8aa3b, v88
	v_exp_f32_e32 v88, v88
	v_and_b32_e32 v98, 0xffff0000, v196
	v_mul_f32_e32 v91, 0xc1000000, v91
	v_mul_f32_e32 v91, v144, v91
	v_mul_f32_e32 v86, v86, v98
	v_mul_f32_e32 v91, 0x3fb8aa3b, v91
	v_exp_f32_e32 v92, v91
	v_cvt_pk_bf16_f32 v91, v87, v86
	v_add_f32_e32 v86, 1.0, v88
	v_add_f32_e32 v88, v93, v153
	v_mul_f32_e32 v88, 0xbfb8aa3b, v88
	v_exp_f32_e32 v88, v88
	v_sub_f32_e32 v87, 1.0, v92
	v_sub_f32_e32 v92, 2.0, v87
	v_add_f32_e32 v70, v70, v150
	v_add_f32_e32 v88, 1.0, v88
	v_rcp_f32_e32 v88, v88
	v_mul_f32_e32 v92, v87, v92
	v_mul_f32_e32 v70, 0xbfb8aa3b, v70
	v_sqrt_f32_e32 v92, v92
	v_mul_f32_e32 v88, 0xc1000000, v88
	v_mul_f32_e32 v88, v145, v88
	v_mul_f32_e32 v88, 0x3fb8aa3b, v88
	v_exp_f32_e32 v88, v88
	v_exp_f32_e32 v70, v70
	v_rcp_f32_e32 v86, v86
	v_add_f32_e32 v89, v89, v149
	v_mul_f32_e32 v89, 0xbfb8aa3b, v89
	v_exp_f32_e32 v89, v89
	v_cndmask_b32_e64 v92, v92, 1.0, s[14:15]
	v_sub_f32_e32 v88, 1.0, v88
	v_add_f32_e32 v70, 1.0, v70
	v_mul_f32_e32 v86, v86, v92
	v_sub_f32_e32 v92, 2.0, v88
	v_rcp_f32_e32 v70, v70
	v_mul_f32_e32 v92, v88, v92
	v_add_f32_e32 v89, 1.0, v89
	v_sqrt_f32_e32 v93, v92
	v_rcp_f32_e32 v89, v89
	v_add_f32_e32 v71, v71, v151
	v_lshlrev_b32_e32 v99, 16, v197
	v_mul_f32_e32 v70, 0xc1000000, v70
	v_mul_f32_e32 v71, 0xbfb8aa3b, v71
	v_mul_f32_e32 v86, v86, v99
	v_mul_f32_e32 v70, v142, v70
	v_exp_f32_e32 v71, v71
	v_cvt_pk_bf16_f32 v92, v87, v86
	v_cndmask_b32_e64 v86, v93, 1.0, s[14:15]
	v_mul_f32_e32 v70, 0x3fb8aa3b, v70
	v_and_b32_e32 v100, 0xffff0000, v197
	v_mul_f32_e32 v86, v89, v86
	v_exp_f32_e32 v70, v70
	v_mul_f32_e32 v86, v86, v100
	v_add_f32_e32 v66, v66, v146
	v_cvt_pk_bf16_f32 v93, v88, v86
	v_lshlrev_b64 v[86:87], 14, v[190:191]
	v_mul_f32_e32 v66, 0xbfb8aa3b, v66
	v_add_f32_e32 v71, 1.0, v71
	v_lshl_add_u64 v[86:87], s[30:31], 0, v[86:87]
	v_exp_f32_e32 v66, v66
	v_rcp_f32_e32 v71, v71
	v_lshl_add_u64 v[86:87], v[86:87], 0, v[184:185]
	v_sub_f32_e32 v70, 1.0, v70
	global_store_dwordx4 v[86:87], v[90:93], off sc1
	v_add_f32_e32 v66, 1.0, v66
	v_mul_f32_e32 v71, 0xc1000000, v71
	v_sub_f32_e32 v93, 2.0, v70
	v_mul_f32_e32 v93, v70, v93
	v_sqrt_f32_e32 v93, v93
	v_rcp_f32_e32 v66, v66
	v_add_f32_e32 v67, v67, v147
	v_mul_f32_e32 v71, v143, v71
	v_and_b32_e32 v88, 0x7ff, v186
	v_mul_f32_e32 v67, 0xbfb8aa3b, v67
	v_mul_f32_e32 v71, 0x3fb8aa3b, v71
	v_cmp_eq_u32_e64 s[16:17], 0, v88
	v_exp_f32_e32 v67, v67
	v_exp_f32_e32 v71, v71
	v_cndmask_b32_e64 v88, v93, 1.0, s[16:17]
	v_lshlrev_b32_e32 v89, 16, v192
	v_mul_f32_e32 v66, v66, v88
	v_mul_f32_e32 v66, v66, v89
	v_cvt_pk_bf16_f32 v70, v70, v66
	v_add_f32_e32 v66, 1.0, v67
	v_sub_f32_e32 v67, 1.0, v71
	v_sub_f32_e32 v71, 2.0, v67
	v_mul_f32_e32 v71, v67, v71
	v_add_f32_e32 v72, v72, v152
	v_sqrt_f32_e32 v71, v71
	v_mul_f32_e32 v72, 0xbfb8aa3b, v72
	v_rcp_f32_e32 v66, v66
	v_exp_f32_e32 v72, v72
	v_cndmask_b32_e64 v71, v71, 1.0, s[16:17]
	v_add_f32_e32 v68, v68, v148
	v_mul_f32_e32 v66, v66, v71
	v_add_f32_e32 v71, 1.0, v72
	v_rcp_f32_e32 v71, v71
	v_mul_f32_e32 v68, 0xbfb8aa3b, v68
	v_exp_f32_e32 v68, v68
	v_and_b32_e32 v90, 0xffff0000, v192
	v_mul_f32_e32 v71, 0xc1000000, v71
	v_mul_f32_e32 v71, v144, v71
	v_mul_f32_e32 v66, v66, v90
	v_mul_f32_e32 v71, 0x3fb8aa3b, v71
	v_exp_f32_e32 v72, v71
	v_cvt_pk_bf16_f32 v71, v67, v66
	v_add_f32_e32 v66, 1.0, v68
	v_add_f32_e32 v68, v73, v153
	v_mul_f32_e32 v68, 0xbfb8aa3b, v68
	v_exp_f32_e32 v68, v68
	v_sub_f32_e32 v67, 1.0, v72
	v_sub_f32_e32 v72, 2.0, v67
	v_add_f32_e32 v62, v62, v82
	v_add_f32_e32 v68, 1.0, v68
	v_rcp_f32_e32 v68, v68
	v_mul_f32_e32 v72, v67, v72
	v_mul_f32_e32 v62, 0xbfb8aa3b, v62
	v_sqrt_f32_e32 v72, v72
	v_mul_f32_e32 v68, 0xc1000000, v68
	v_mul_f32_e32 v68, v145, v68
	v_mul_f32_e32 v68, 0x3fb8aa3b, v68
	v_exp_f32_e32 v68, v68
	v_exp_f32_e32 v62, v62
	v_rcp_f32_e32 v66, v66
	v_add_f32_e32 v69, v69, v149
	v_mul_f32_e32 v69, 0xbfb8aa3b, v69
	v_exp_f32_e32 v69, v69
	v_cndmask_b32_e64 v72, v72, 1.0, s[16:17]
	v_sub_f32_e32 v68, 1.0, v68
	v_add_f32_e32 v62, 1.0, v62
	v_mul_f32_e32 v66, v66, v72
	v_sub_f32_e32 v72, 2.0, v68
	v_rcp_f32_e32 v62, v62
	v_mul_f32_e32 v72, v68, v72
	v_add_f32_e32 v69, 1.0, v69
	v_sqrt_f32_e32 v73, v72
	v_rcp_f32_e32 v69, v69
	v_add_f32_e32 v63, v63, v83
	v_lshlrev_b32_e32 v91, 16, v193
	v_mul_f32_e32 v62, 0xc1000000, v62
	v_mul_f32_e32 v63, 0xbfb8aa3b, v63
	v_mul_f32_e32 v66, v66, v91
	v_mul_f32_e32 v62, v74, v62
	v_exp_f32_e32 v63, v63
	v_cvt_pk_bf16_f32 v72, v67, v66
	v_cndmask_b32_e64 v66, v73, 1.0, s[16:17]
; __device__ __forceinline__ unsigned cvt_pk_bf16(float lo, float hi) { unsigned r; asm volatile("v_cvt_pk_bf16_f32 %0, %1, %2" : "=v"(r) : "v"(lo), "v"(hi)); return r; }
; __device__ __forceinline__ float bflo(unsigned w) { return __uint_as_float(w << 16); }
; __device__ __forceinline__ float bfhi(unsigned w) { return __uint_as_float(w & 0xffff0000u); }
; __device__ __forceinline__ float sigmoidf_(float x) { return __builtin_amdgcn_rcpf(1.0f + __expf(-x)); }
;     __device__ __forceinline__ void operator()(const pg8::f32x4 (&acc)[2][2][4][2], const pg8::Unit& u, int wr, int wc, int fr, int fq) const {
;     ...
;         for (int n = 0; n < 2; ++n) { const int ch = ch0 + 16 * n; const v4f bi = biv[n], br = brv[n], sp = spv[n];
; #pragma unroll
;             for (int ai = 0; ai < 2; ++ai)
; #pragma unroll
;                 for (int m = 0; m < 4; ++m) { const int row = row0 + ai * 128 + m * 16; const bool first = (row & (SEQ - 1)) == 0; const size_t off = (size_t)row * DM + ch;
;                     const v2u xw = xv[n][ai][m]; const float x[4] = {bflo(xw.x), bfhi(xw.x), bflo(xw.y), bfhi(xw.y)};
;                     const pg8::f32x4 vi = acc[ai][0][m][n], vr = acc[ai][1][m][n]; v4u av;
; #pragma unroll
;                     for (int j = 0; j < 4; ++j) { const float ig = sigmoidf_(vi[j] + bi[j]), rg = sigmoidf_(vr[j] + br[j]);
;                         const float la = -8.0f * rg * sp[j];
;                         const float oma = 1.0f - __expf(la);
;                         const float mult = first ? 1.0f : __builtin_amdgcn_sqrtf(oma * (2.0f - oma));
;                         av[j] = pg8::cvt_pk_bf16(oma, mult * ig * x[j]); }
;                     *(v4u*)(AU + off) = av;
;                     if (m & 1) asm volatile("" ::: "memory"); } }
	v_mul_f32_e32 v62, 0x3fb8aa3b, v62
	v_and_b32_e32 v92, 0xffff0000, v193
	v_mul_f32_e32 v66, v69, v66
	v_exp_f32_e32 v62, v62
	v_mul_f32_e32 v66, v66, v92
	v_add_f32_e32 v58, v58, v78
	v_cvt_pk_bf16_f32 v73, v68, v66
	v_lshlrev_b64 v[66:67], 14, v[186:187]
	v_mul_f32_e32 v58, 0xbfb8aa3b, v58
	v_add_f32_e32 v63, 1.0, v63
	v_lshl_add_u64 v[66:67], s[30:31], 0, v[66:67]
	v_exp_f32_e32 v58, v58
	v_rcp_f32_e32 v63, v63
	v_lshl_add_u64 v[66:67], v[66:67], 0, v[184:185]
	v_sub_f32_e32 v62, 1.0, v62
	global_store_dwordx4 v[66:67], v[70:73], off sc1
	v_add_f32_e32 v58, 1.0, v58
	v_mul_f32_e32 v63, 0xc1000000, v63
	v_sub_f32_e32 v72, 2.0, v62
	v_mul_f32_e32 v72, v62, v72
	v_sqrt_f32_e32 v72, v72
	v_rcp_f32_e32 v58, v58
	v_mul_f32_e32 v63, v75, v63
	v_mul_f32_e32 v63, 0x3fb8aa3b, v63
	v_exp_f32_e32 v63, v63
	v_cndmask_b32_e64 v72, v72, 1.0, s[10:11]
	v_add_f32_e32 v59, v59, v79
	v_lshlrev_b32_e32 v68, 16, v188
	v_mul_f32_e32 v58, v58, v72
	v_mul_f32_e32 v59, 0xbfb8aa3b, v59
	v_mul_f32_e32 v58, v58, v68
	v_exp_f32_e32 v59, v59
	v_cvt_pk_bf16_f32 v58, v62, v58
	v_sub_f32_e32 v62, 1.0, v63
	v_sub_f32_e32 v63, 2.0, v62
	v_mul_f32_e32 v63, v62, v63
	v_add_f32_e32 v64, v64, v84
	v_add_f32_e32 v59, 1.0, v59
	v_sqrt_f32_e32 v63, v63
	v_mul_f32_e32 v64, 0xbfb8aa3b, v64
	v_rcp_f32_e32 v59, v59
	v_exp_f32_e32 v64, v64
	v_cndmask_b32_e64 v63, v63, 1.0, s[10:11]
	v_and_b32_e32 v69, 0xffff0000, v188
	v_mul_f32_e32 v59, v59, v63
	v_add_f32_e32 v63, 1.0, v64
	v_rcp_f32_e32 v63, v63
	v_mul_f32_e32 v59, v59, v69
	v_cvt_pk_bf16_f32 v59, v62, v59
	v_add_f32_e32 v54, v54, v82
	v_mul_f32_e32 v63, 0xc1000000, v63
	v_mul_f32_e32 v63, v76, v63
	v_mul_f32_e32 v63, 0x3fb8aa3b, v63
	v_exp_f32_e32 v63, v63
	v_add_f32_e32 v60, v60, v80
	v_mul_f32_e32 v54, 0xbfb8aa3b, v54
	v_mul_f32_e32 v60, 0xbfb8aa3b, v60
	v_sub_f32_e32 v62, 1.0, v63
	v_add_f32_e32 v63, v65, v85
	v_mul_f32_e32 v63, 0xbfb8aa3b, v63
	v_exp_f32_e32 v63, v63
	v_exp_f32_e32 v54, v54
	v_exp_f32_e32 v60, v60
	v_sub_f32_e32 v64, 2.0, v62
	v_add_f32_e32 v63, 1.0, v63
	v_rcp_f32_e32 v63, v63
	v_mul_f32_e32 v64, v62, v64
	v_add_f32_e32 v54, 1.0, v54
	v_add_f32_e32 v60, 1.0, v60
	v_mul_f32_e32 v63, 0xc1000000, v63
	v_mul_f32_e32 v63, v77, v63
	v_mul_f32_e32 v63, 0x3fb8aa3b, v63
	v_sqrt_f32_e32 v64, v64
	v_exp_f32_e32 v63, v63
	v_rcp_f32_e32 v54, v54
	v_rcp_f32_e32 v60, v60
	v_add_f32_e32 v61, v61, v81
	v_mul_f32_e32 v61, 0xbfb8aa3b, v61
	v_exp_f32_e32 v61, v61
	v_add_f32_e32 v55, v55, v83
	v_cndmask_b32_e64 v64, v64, 1.0, s[10:11]
	v_sub_f32_e32 v63, 1.0, v63
	v_mul_f32_e32 v54, 0xc1000000, v54
	v_mul_f32_e32 v55, 0xbfb8aa3b, v55
	v_mul_f32_e32 v60, v60, v64
	v_sub_f32_e32 v64, 2.0, v63
	v_mul_f32_e32 v54, v74, v54
	v_exp_f32_e32 v55, v55
	v_mul_f32_e32 v64, v63, v64
	v_mul_f32_e32 v54, 0x3fb8aa3b, v54
	v_add_f32_e32 v61, 1.0, v61
	v_sqrt_f32_e32 v64, v64
	v_exp_f32_e32 v54, v54
	v_rcp_f32_e32 v61, v61
	v_add_f32_e32 v50, v50, v78
	v_lshlrev_b32_e32 v70, 16, v189
	v_mul_f32_e32 v50, 0xbfb8aa3b, v50
	v_add_f32_e32 v55, 1.0, v55
	v_mul_f32_e32 v60, v60, v70
	v_exp_f32_e32 v50, v50
	v_rcp_f32_e32 v55, v55
	v_cvt_pk_bf16_f32 v60, v62, v60
	v_cndmask_b32_e64 v62, v64, 1.0, s[10:11]
	v_sub_f32_e32 v54, 1.0, v54
	v_mul_f32_e32 v61, v61, v62
	v_sub_f32_e32 v62, 2.0, v54
	v_mul_f32_e32 v62, v54, v62
	v_add_f32_e32 v50, 1.0, v50
	v_sqrt_f32_e32 v62, v62
	v_mul_f32_e32 v55, 0xc1000000, v55
	v_rcp_f32_e32 v50, v50
	v_mul_f32_e32 v55, v75, v55
	v_mul_f32_e32 v55, 0x3fb8aa3b, v55
	v_and_b32_e32 v71, 0xffff0000, v189
	v_exp_f32_e32 v55, v55
	v_mul_f32_e32 v61, v61, v71
	v_cndmask_b32_e64 v62, v62, 1.0, vcc
	v_add_f32_e32 v51, v51, v79
	v_cvt_pk_bf16_f32 v61, v63, v61
	global_store_dwordx4 v[134:135], v[58:61], off offset:64 sc1
	v_mul_f32_e32 v50, v50, v62
	v_mul_f32_e32 v51, 0xbfb8aa3b, v51
	v_lshlrev_b32_e32 v58, 16, v182
	v_mul_f32_e32 v50, v50, v58
	v_exp_f32_e32 v51, v51
	v_cvt_pk_bf16_f32 v50, v54, v50
	v_sub_f32_e32 v54, 1.0, v55
	v_sub_f32_e32 v55, 2.0, v54
	v_mul_f32_e32 v55, v54, v55
	v_add_f32_e32 v56, v56, v84
	v_add_f32_e32 v51, 1.0, v51
	v_sqrt_f32_e32 v55, v55
	v_mul_f32_e32 v56, 0xbfb8aa3b, v56
	v_rcp_f32_e32 v51, v51
	v_exp_f32_e32 v56, v56
	v_cndmask_b32_e64 v55, v55, 1.0, vcc
	v_and_b32_e32 v59, 0xffff0000, v182
	v_mul_f32_e32 v51, v51, v55
	v_add_f32_e32 v55, 1.0, v56
	v_rcp_f32_e32 v55, v55
	v_mul_f32_e32 v51, v51, v59
	v_cvt_pk_bf16_f32 v51, v54, v51
	v_add_f32_e32 v46, v46, v82
	v_mul_f32_e32 v55, 0xc1000000, v55
	v_mul_f32_e32 v55, v76, v55
	v_mul_f32_e32 v55, 0x3fb8aa3b, v55
	v_exp_f32_e32 v55, v55
	v_add_f32_e32 v52, v52, v80
	v_mul_f32_e32 v46, 0xbfb8aa3b, v46
	v_mul_f32_e32 v52, 0xbfb8aa3b, v52
	v_sub_f32_e32 v54, 1.0, v55
	v_add_f32_e32 v55, v57, v85
	v_mul_f32_e32 v55, 0xbfb8aa3b, v55
	v_exp_f32_e32 v55, v55
	v_exp_f32_e32 v46, v46
	v_exp_f32_e32 v52, v52
	v_sub_f32_e32 v56, 2.0, v54
	v_add_f32_e32 v55, 1.0, v55
	v_rcp_f32_e32 v55, v55
	v_mul_f32_e32 v56, v54, v56
	v_add_f32_e32 v46, 1.0, v46
	v_add_f32_e32 v52, 1.0, v52
	v_mul_f32_e32 v55, 0xc1000000, v55
	v_mul_f32_e32 v55, v77, v55
	v_mul_f32_e32 v55, 0x3fb8aa3b, v55
	v_sqrt_f32_e32 v56, v56
	v_exp_f32_e32 v55, v55
	v_rcp_f32_e32 v46, v46
	v_rcp_f32_e32 v52, v52
	v_add_f32_e32 v53, v53, v81
	v_mul_f32_e32 v53, 0xbfb8aa3b, v53
	v_exp_f32_e32 v53, v53
	v_add_f32_e32 v47, v47, v83
	v_cndmask_b32_e64 v56, v56, 1.0, vcc
	v_sub_f32_e32 v55, 1.0, v55
	v_mul_f32_e32 v46, 0xc1000000, v46
	v_mul_f32_e32 v47, 0xbfb8aa3b, v47
	v_mul_f32_e32 v52, v52, v56
	v_sub_f32_e32 v56, 2.0, v55
	v_mul_f32_e32 v46, v74, v46
	v_exp_f32_e32 v47, v47
	v_mul_f32_e32 v56, v55, v56
	v_mul_f32_e32 v46, 0x3fb8aa3b, v46
	v_add_f32_e32 v53, 1.0, v53
	v_sqrt_f32_e32 v56, v56
; __device__ __forceinline__ unsigned cvt_pk_bf16(float lo, float hi) { unsigned r; asm volatile("v_cvt_pk_bf16_f32 %0, %1, %2" : "=v"(r) : "v"(lo), "v"(hi)); return r; }
; __device__ __forceinline__ float bflo(unsigned w) { return __uint_as_float(w << 16); }
; __device__ __forceinline__ float bfhi(unsigned w) { return __uint_as_float(w & 0xffff0000u); }
; __device__ __forceinline__ float sigmoidf_(float x) { return __builtin_amdgcn_rcpf(1.0f + __expf(-x)); }
;     __device__ __forceinline__ void operator()(const pg8::f32x4 (&acc)[2][2][4][2], const pg8::Unit& u, int wr, int wc, int fr, int fq) const {
;     ...
;         for (int n = 0; n < 2; ++n) { const int ch = ch0 + 16 * n; const v4f bi = biv[n], br = brv[n], sp = spv[n];
; #pragma unroll
;             for (int ai = 0; ai < 2; ++ai)
; #pragma unroll
;                 for (int m = 0; m < 4; ++m) { const int row = row0 + ai * 128 + m * 16; const bool first = (row & (SEQ - 1)) == 0; const size_t off = (size_t)row * DM + ch;
;                     const v2u xw = xv[n][ai][m]; const float x[4] = {bflo(xw.x), bfhi(xw.x), bflo(xw.y), bfhi(xw.y)};
;                     const pg8::f32x4 vi = acc[ai][0][m][n], vr = acc[ai][1][m][n]; v4u av;
; #pragma unroll
;                     for (int j = 0; j < 4; ++j) { const float ig = sigmoidf_(vi[j] + bi[j]), rg = sigmoidf_(vr[j] + br[j]);
;                         const float la = -8.0f * rg * sp[j];
;                         const float oma = 1.0f - __expf(la);
;                         const float mult = first ? 1.0f : __builtin_amdgcn_sqrtf(oma * (2.0f - oma));
;                         av[j] = pg8::cvt_pk_bf16(oma, mult * ig * x[j]); }
;                     *(v4u*)(AU + off) = av;
;                     if (m & 1) asm volatile("" ::: "memory"); } }
	v_exp_f32_e32 v46, v46
	v_rcp_f32_e32 v53, v53
	v_add_f32_e32 v42, v42, v78
	v_lshlrev_b32_e32 v60, 16, v183
	v_mul_f32_e32 v42, 0xbfb8aa3b, v42
	v_add_f32_e32 v47, 1.0, v47
	v_mul_f32_e32 v52, v52, v60
	v_exp_f32_e32 v42, v42
	v_rcp_f32_e32 v47, v47
	v_cvt_pk_bf16_f32 v52, v54, v52
	v_cndmask_b32_e64 v54, v56, 1.0, vcc
	v_sub_f32_e32 v46, 1.0, v46
	v_mul_f32_e32 v53, v53, v54
	v_sub_f32_e32 v54, 2.0, v46
	v_mul_f32_e32 v54, v46, v54
	v_add_f32_e32 v42, 1.0, v42
	v_sqrt_f32_e32 v54, v54
	v_mul_f32_e32 v47, 0xc1000000, v47
	v_rcp_f32_e32 v42, v42
	v_mul_f32_e32 v47, v75, v47
	v_mul_f32_e32 v47, 0x3fb8aa3b, v47
	v_and_b32_e32 v61, 0xffff0000, v183
	v_exp_f32_e32 v47, v47
	v_mul_f32_e32 v53, v53, v61
	v_cndmask_b32_e64 v54, v54, 1.0, s[4:5]
	v_add_f32_e32 v43, v43, v79
	v_cvt_pk_bf16_f32 v53, v55, v53
	global_store_dwordx4 v[126:127], v[50:53], off offset:64 sc1
	v_mul_f32_e32 v42, v42, v54
	v_mul_f32_e32 v43, 0xbfb8aa3b, v43
	v_lshlrev_b32_e32 v50, 16, v180
	v_mul_f32_e32 v42, v42, v50
	v_exp_f32_e32 v43, v43
	v_cvt_pk_bf16_f32 v42, v46, v42
	v_sub_f32_e32 v46, 1.0, v47
	v_sub_f32_e32 v47, 2.0, v46
	v_mul_f32_e32 v47, v46, v47
	v_add_f32_e32 v48, v48, v84
	v_add_f32_e32 v43, 1.0, v43
	v_sqrt_f32_e32 v47, v47
	v_mul_f32_e32 v48, 0xbfb8aa3b, v48
	v_rcp_f32_e32 v43, v43
	v_exp_f32_e32 v48, v48
	v_cndmask_b32_e64 v47, v47, 1.0, s[4:5]
	v_and_b32_e32 v51, 0xffff0000, v180
	v_mul_f32_e32 v43, v43, v47
	v_add_f32_e32 v47, 1.0, v48
	v_rcp_f32_e32 v47, v47
	v_mul_f32_e32 v43, v43, v51
	v_cvt_pk_bf16_f32 v43, v46, v43
	v_add_f32_e32 v38, v38, v82
	v_mul_f32_e32 v47, 0xc1000000, v47
	v_mul_f32_e32 v47, v76, v47
	v_mul_f32_e32 v47, 0x3fb8aa3b, v47
	v_exp_f32_e32 v47, v47
	v_add_f32_e32 v44, v44, v80
	v_mul_f32_e32 v38, 0xbfb8aa3b, v38
	v_mul_f32_e32 v44, 0xbfb8aa3b, v44
	v_sub_f32_e32 v46, 1.0, v47
	v_add_f32_e32 v47, v49, v85
	v_mul_f32_e32 v47, 0xbfb8aa3b, v47
	v_exp_f32_e32 v47, v47
	v_exp_f32_e32 v38, v38
	v_exp_f32_e32 v44, v44
	v_sub_f32_e32 v48, 2.0, v46
	v_add_f32_e32 v47, 1.0, v47
	v_rcp_f32_e32 v47, v47
	v_mul_f32_e32 v48, v46, v48
	v_add_f32_e32 v38, 1.0, v38
	v_add_f32_e32 v44, 1.0, v44
	v_mul_f32_e32 v47, 0xc1000000, v47
	v_mul_f32_e32 v47, v77, v47
	v_mul_f32_e32 v47, 0x3fb8aa3b, v47
	v_sqrt_f32_e32 v48, v48
	v_exp_f32_e32 v47, v47
	v_rcp_f32_e32 v38, v38
	v_rcp_f32_e32 v44, v44
	v_add_f32_e32 v45, v45, v81
	v_mul_f32_e32 v45, 0xbfb8aa3b, v45
	v_exp_f32_e32 v45, v45
	v_add_f32_e32 v39, v39, v83
	v_cndmask_b32_e64 v48, v48, 1.0, s[4:5]
	v_sub_f32_e32 v47, 1.0, v47
	v_mul_f32_e32 v38, 0xc1000000, v38
	v_mul_f32_e32 v39, 0xbfb8aa3b, v39
	v_mul_f32_e32 v44, v44, v48
	v_sub_f32_e32 v48, 2.0, v47
	v_mul_f32_e32 v38, v74, v38
	v_exp_f32_e32 v39, v39
	v_mul_f32_e32 v48, v47, v48
	v_mul_f32_e32 v38, 0x3fb8aa3b, v38
	v_add_f32_e32 v45, 1.0, v45
	v_sqrt_f32_e32 v48, v48
	v_exp_f32_e32 v38, v38
	v_rcp_f32_e32 v45, v45
	v_add_f32_e32 v34, v34, v78
	v_lshlrev_b32_e32 v52, 16, v181
	v_mul_f32_e32 v34, 0xbfb8aa3b, v34
	v_add_f32_e32 v39, 1.0, v39
	v_mul_f32_e32 v44, v44, v52
	v_exp_f32_e32 v34, v34
	v_rcp_f32_e32 v39, v39
	v_cvt_pk_bf16_f32 v44, v46, v44
	v_cndmask_b32_e64 v46, v48, 1.0, s[4:5]
	v_sub_f32_e32 v38, 1.0, v38
	v_mul_f32_e32 v45, v45, v46
	v_sub_f32_e32 v46, 2.0, v38
	v_mul_f32_e32 v46, v38, v46
	v_add_f32_e32 v34, 1.0, v34
	v_sqrt_f32_e32 v46, v46
	v_mul_f32_e32 v39, 0xc1000000, v39
	v_rcp_f32_e32 v34, v34
	v_mul_f32_e32 v39, v75, v39
	v_mul_f32_e32 v39, 0x3fb8aa3b, v39
	v_and_b32_e32 v53, 0xffff0000, v181
	v_exp_f32_e32 v39, v39
	v_mul_f32_e32 v45, v45, v53
	v_cndmask_b32_e64 v46, v46, 1.0, s[6:7]
	v_add_f32_e32 v35, v35, v79
	v_cvt_pk_bf16_f32 v45, v47, v45
	global_store_dwordx4 v[118:119], v[42:45], off offset:64 sc1
	v_mul_f32_e32 v34, v34, v46
	v_mul_f32_e32 v35, 0xbfb8aa3b, v35
	v_lshlrev_b32_e32 v42, 16, v178
	v_mul_f32_e32 v34, v34, v42
	v_exp_f32_e32 v35, v35
	v_cvt_pk_bf16_f32 v34, v38, v34
	v_sub_f32_e32 v38, 1.0, v39
	v_sub_f32_e32 v39, 2.0, v38
	v_mul_f32_e32 v39, v38, v39
	v_add_f32_e32 v40, v40, v84
	v_add_f32_e32 v35, 1.0, v35
	v_sqrt_f32_e32 v39, v39
	v_mul_f32_e32 v40, 0xbfb8aa3b, v40
	v_rcp_f32_e32 v35, v35
	v_exp_f32_e32 v40, v40
	v_cndmask_b32_e64 v39, v39, 1.0, s[6:7]
	v_and_b32_e32 v43, 0xffff0000, v178
	v_mul_f32_e32 v35, v35, v39
	v_add_f32_e32 v39, 1.0, v40
	v_rcp_f32_e32 v39, v39
	v_mul_f32_e32 v35, v35, v43
	v_cvt_pk_bf16_f32 v35, v38, v35
	v_add_f32_e32 v30, v30, v82
	v_mul_f32_e32 v39, 0xc1000000, v39
	v_mul_f32_e32 v39, v76, v39
	v_mul_f32_e32 v39, 0x3fb8aa3b, v39
	v_exp_f32_e32 v39, v39
	v_add_f32_e32 v36, v36, v80
	v_mul_f32_e32 v30, 0xbfb8aa3b, v30
	v_mul_f32_e32 v36, 0xbfb8aa3b, v36
	v_sub_f32_e32 v38, 1.0, v39
	v_add_f32_e32 v39, v41, v85
	v_mul_f32_e32 v39, 0xbfb8aa3b, v39
	v_exp_f32_e32 v39, v39
	v_exp_f32_e32 v30, v30
	v_exp_f32_e32 v36, v36
	v_sub_f32_e32 v40, 2.0, v38
	v_add_f32_e32 v39, 1.0, v39
	v_rcp_f32_e32 v39, v39
	v_mul_f32_e32 v40, v38, v40
	v_add_f32_e32 v30, 1.0, v30
	v_add_f32_e32 v36, 1.0, v36
	v_mul_f32_e32 v39, 0xc1000000, v39
	v_mul_f32_e32 v39, v77, v39
	v_mul_f32_e32 v39, 0x3fb8aa3b, v39
	v_sqrt_f32_e32 v40, v40
	v_exp_f32_e32 v39, v39
	v_rcp_f32_e32 v30, v30
	v_rcp_f32_e32 v36, v36
	v_add_f32_e32 v37, v37, v81
	v_mul_f32_e32 v37, 0xbfb8aa3b, v37
	v_exp_f32_e32 v37, v37
	v_add_f32_e32 v31, v31, v83
	v_cndmask_b32_e64 v40, v40, 1.0, s[6:7]
	v_sub_f32_e32 v39, 1.0, v39
	v_mul_f32_e32 v30, 0xc1000000, v30
	v_mul_f32_e32 v31, 0xbfb8aa3b, v31
	v_mul_f32_e32 v36, v36, v40
	v_sub_f32_e32 v40, 2.0, v39
	v_mul_f32_e32 v30, v74, v30
	v_exp_f32_e32 v31, v31
	v_mul_f32_e32 v40, v39, v40
	v_mul_f32_e32 v30, 0x3fb8aa3b, v30
	v_add_f32_e32 v37, 1.0, v37
	v_sqrt_f32_e32 v40, v40
	v_exp_f32_e32 v30, v30
; __device__ __forceinline__ unsigned cvt_pk_bf16(float lo, float hi) { unsigned r; asm volatile("v_cvt_pk_bf16_f32 %0, %1, %2" : "=v"(r) : "v"(lo), "v"(hi)); return r; }
; __device__ __forceinline__ float bflo(unsigned w) { return __uint_as_float(w << 16); }
; __device__ __forceinline__ float bfhi(unsigned w) { return __uint_as_float(w & 0xffff0000u); }
; __device__ __forceinline__ float sigmoidf_(float x) { return __builtin_amdgcn_rcpf(1.0f + __expf(-x)); }
;     __device__ __forceinline__ void operator()(const pg8::f32x4 (&acc)[2][2][4][2], const pg8::Unit& u, int wr, int wc, int fr, int fq) const {
;     ...
;         for (int n = 0; n < 2; ++n) { const int ch = ch0 + 16 * n; const v4f bi = biv[n], br = brv[n], sp = spv[n];
; #pragma unroll
;             for (int ai = 0; ai < 2; ++ai)
; #pragma unroll
;                 for (int m = 0; m < 4; ++m) { const int row = row0 + ai * 128 + m * 16; const bool first = (row & (SEQ - 1)) == 0; const size_t off = (size_t)row * DM + ch;
;                     const v2u xw = xv[n][ai][m]; const float x[4] = {bflo(xw.x), bfhi(xw.x), bflo(xw.y), bfhi(xw.y)};
;                     const pg8::f32x4 vi = acc[ai][0][m][n], vr = acc[ai][1][m][n]; v4u av;
; #pragma unroll
;                     for (int j = 0; j < 4; ++j) { const float ig = sigmoidf_(vi[j] + bi[j]), rg = sigmoidf_(vr[j] + br[j]);
;                         const float la = -8.0f * rg * sp[j];
;                         const float oma = 1.0f - __expf(la);
;                         const float mult = first ? 1.0f : __builtin_amdgcn_sqrtf(oma * (2.0f - oma));
;                         av[j] = pg8::cvt_pk_bf16(oma, mult * ig * x[j]); }
;                     *(v4u*)(AU + off) = av;
;                     if (m & 1) asm volatile("" ::: "memory"); } }
	v_rcp_f32_e32 v37, v37
	v_add_f32_e32 v26, v26, v78
	v_lshlrev_b32_e32 v44, 16, v179
	v_mul_f32_e32 v26, 0xbfb8aa3b, v26
	v_add_f32_e32 v31, 1.0, v31
	v_mul_f32_e32 v36, v36, v44
	v_exp_f32_e32 v26, v26
	v_rcp_f32_e32 v31, v31
	v_cvt_pk_bf16_f32 v36, v38, v36
	v_cndmask_b32_e64 v38, v40, 1.0, s[6:7]
	v_sub_f32_e32 v30, 1.0, v30
	v_mul_f32_e32 v37, v37, v38
	v_sub_f32_e32 v38, 2.0, v30
	v_mul_f32_e32 v38, v30, v38
	v_add_f32_e32 v26, 1.0, v26
	v_sqrt_f32_e32 v38, v38
	v_mul_f32_e32 v31, 0xc1000000, v31
	v_rcp_f32_e32 v26, v26
	v_mul_f32_e32 v31, v75, v31
	v_mul_f32_e32 v31, 0x3fb8aa3b, v31
	v_and_b32_e32 v45, 0xffff0000, v179
	v_exp_f32_e32 v31, v31
	v_mul_f32_e32 v37, v37, v45
	v_cndmask_b32_e64 v38, v38, 1.0, s[8:9]
	v_add_f32_e32 v27, v27, v79
	v_cvt_pk_bf16_f32 v37, v39, v37
	global_store_dwordx4 v[110:111], v[34:37], off offset:64 sc1
	v_mul_f32_e32 v26, v26, v38
	v_mul_f32_e32 v27, 0xbfb8aa3b, v27
	v_lshlrev_b32_e32 v34, 16, v176
	v_mul_f32_e32 v26, v26, v34
	v_exp_f32_e32 v27, v27
	v_cvt_pk_bf16_f32 v26, v30, v26
	v_sub_f32_e32 v30, 1.0, v31
	v_sub_f32_e32 v31, 2.0, v30
	v_mul_f32_e32 v31, v30, v31
	v_add_f32_e32 v32, v32, v84
	v_add_f32_e32 v27, 1.0, v27
	v_sqrt_f32_e32 v31, v31
	v_mul_f32_e32 v32, 0xbfb8aa3b, v32
	v_rcp_f32_e32 v27, v27
	v_exp_f32_e32 v32, v32
	v_cndmask_b32_e64 v31, v31, 1.0, s[8:9]
	v_and_b32_e32 v35, 0xffff0000, v176
	v_mul_f32_e32 v27, v27, v31
	v_add_f32_e32 v31, 1.0, v32
	v_rcp_f32_e32 v31, v31
	v_mul_f32_e32 v27, v27, v35
	v_cvt_pk_bf16_f32 v27, v30, v27
	v_add_f32_e32 v22, v22, v82
	v_mul_f32_e32 v31, 0xc1000000, v31
	v_mul_f32_e32 v31, v76, v31
	v_mul_f32_e32 v31, 0x3fb8aa3b, v31
	v_exp_f32_e32 v31, v31
	v_add_f32_e32 v28, v28, v80
	v_mul_f32_e32 v22, 0xbfb8aa3b, v22
	v_mul_f32_e32 v28, 0xbfb8aa3b, v28
	v_sub_f32_e32 v30, 1.0, v31
	v_add_f32_e32 v31, v33, v85
	v_mul_f32_e32 v31, 0xbfb8aa3b, v31
	v_exp_f32_e32 v31, v31
	v_exp_f32_e32 v22, v22
	v_exp_f32_e32 v28, v28
	v_sub_f32_e32 v32, 2.0, v30
	v_add_f32_e32 v31, 1.0, v31
	v_rcp_f32_e32 v31, v31
	v_mul_f32_e32 v32, v30, v32
	v_add_f32_e32 v22, 1.0, v22
	v_add_f32_e32 v28, 1.0, v28
	v_mul_f32_e32 v31, 0xc1000000, v31
	v_mul_f32_e32 v31, v77, v31
	v_mul_f32_e32 v31, 0x3fb8aa3b, v31
	v_sqrt_f32_e32 v32, v32
	v_exp_f32_e32 v31, v31
	v_rcp_f32_e32 v22, v22
	v_rcp_f32_e32 v28, v28
	v_add_f32_e32 v29, v29, v81
	v_mul_f32_e32 v29, 0xbfb8aa3b, v29
	v_exp_f32_e32 v29, v29
	v_add_f32_e32 v23, v23, v83
	v_cndmask_b32_e64 v32, v32, 1.0, s[8:9]
	v_sub_f32_e32 v31, 1.0, v31
	v_mul_f32_e32 v22, 0xc1000000, v22
	v_mul_f32_e32 v23, 0xbfb8aa3b, v23
	v_mul_f32_e32 v28, v28, v32
	v_sub_f32_e32 v32, 2.0, v31
	v_mul_f32_e32 v22, v74, v22
	v_exp_f32_e32 v23, v23
	v_mul_f32_e32 v32, v31, v32
	v_mul_f32_e32 v22, 0x3fb8aa3b, v22
	v_add_f32_e32 v29, 1.0, v29
	v_sqrt_f32_e32 v32, v32
	v_exp_f32_e32 v22, v22
	v_rcp_f32_e32 v29, v29
	v_add_f32_e32 v18, v18, v78
	v_lshlrev_b32_e32 v36, 16, v177
	v_mul_f32_e32 v18, 0xbfb8aa3b, v18
	v_add_f32_e32 v23, 1.0, v23
	v_mul_f32_e32 v28, v28, v36
	v_exp_f32_e32 v18, v18
	v_rcp_f32_e32 v23, v23
	v_cvt_pk_bf16_f32 v28, v30, v28
	v_cndmask_b32_e64 v30, v32, 1.0, s[8:9]
	v_sub_f32_e32 v22, 1.0, v22
	v_mul_f32_e32 v29, v29, v30
	v_sub_f32_e32 v30, 2.0, v22
	v_mul_f32_e32 v30, v22, v30
	v_add_f32_e32 v18, 1.0, v18
	v_sqrt_f32_e32 v30, v30
	v_mul_f32_e32 v23, 0xc1000000, v23
	v_rcp_f32_e32 v18, v18
	v_mul_f32_e32 v23, v75, v23
	v_mul_f32_e32 v23, 0x3fb8aa3b, v23
	v_and_b32_e32 v37, 0xffff0000, v177
	v_exp_f32_e32 v23, v23
	v_mul_f32_e32 v29, v29, v37
	v_cndmask_b32_e64 v30, v30, 1.0, s[12:13]
	v_add_f32_e32 v19, v19, v79
	v_cvt_pk_bf16_f32 v29, v31, v29
	global_store_dwordx4 v[102:103], v[26:29], off offset:64 sc1
	v_mul_f32_e32 v18, v18, v30
	v_mul_f32_e32 v19, 0xbfb8aa3b, v19
	v_lshlrev_b32_e32 v26, 16, v174
	v_mul_f32_e32 v18, v18, v26
	v_exp_f32_e32 v19, v19
	v_cvt_pk_bf16_f32 v18, v22, v18
	v_sub_f32_e32 v22, 1.0, v23
	v_sub_f32_e32 v23, 2.0, v22
	v_mul_f32_e32 v23, v22, v23
	v_add_f32_e32 v24, v24, v84
	v_add_f32_e32 v19, 1.0, v19
	v_sqrt_f32_e32 v23, v23
	v_mul_f32_e32 v24, 0xbfb8aa3b, v24
	v_rcp_f32_e32 v19, v19
	v_exp_f32_e32 v24, v24
	v_cndmask_b32_e64 v23, v23, 1.0, s[12:13]
	v_and_b32_e32 v27, 0xffff0000, v174
	v_mul_f32_e32 v19, v19, v23
	v_add_f32_e32 v23, 1.0, v24
	v_rcp_f32_e32 v23, v23
	v_mul_f32_e32 v19, v19, v27
	v_cvt_pk_bf16_f32 v19, v22, v19
	v_add_f32_e32 v14, v14, v82
	v_mul_f32_e32 v23, 0xc1000000, v23
	v_mul_f32_e32 v23, v76, v23
	v_mul_f32_e32 v23, 0x3fb8aa3b, v23
	v_exp_f32_e32 v23, v23
	v_add_f32_e32 v20, v20, v80
	v_mul_f32_e32 v14, 0xbfb8aa3b, v14
	v_mul_f32_e32 v20, 0xbfb8aa3b, v20
	v_sub_f32_e32 v22, 1.0, v23
	v_add_f32_e32 v23, v25, v85
	v_mul_f32_e32 v23, 0xbfb8aa3b, v23
	v_exp_f32_e32 v23, v23
	v_exp_f32_e32 v14, v14
	v_exp_f32_e32 v20, v20
	v_sub_f32_e32 v24, 2.0, v22
	v_add_f32_e32 v23, 1.0, v23
	v_rcp_f32_e32 v23, v23
	v_mul_f32_e32 v24, v22, v24
	v_add_f32_e32 v14, 1.0, v14
	v_add_f32_e32 v20, 1.0, v20
	v_mul_f32_e32 v23, 0xc1000000, v23
	v_mul_f32_e32 v23, v77, v23
	v_mul_f32_e32 v23, 0x3fb8aa3b, v23
	v_sqrt_f32_e32 v24, v24
	v_exp_f32_e32 v23, v23
	v_rcp_f32_e32 v14, v14
	v_rcp_f32_e32 v20, v20
	v_add_f32_e32 v21, v21, v81
	v_mul_f32_e32 v21, 0xbfb8aa3b, v21
	v_exp_f32_e32 v21, v21
	v_add_f32_e32 v15, v15, v83
	v_cndmask_b32_e64 v24, v24, 1.0, s[12:13]
	v_sub_f32_e32 v23, 1.0, v23
	v_mul_f32_e32 v14, 0xc1000000, v14
	v_mul_f32_e32 v15, 0xbfb8aa3b, v15
	v_mul_f32_e32 v20, v20, v24
	v_sub_f32_e32 v24, 2.0, v23
	v_mul_f32_e32 v14, v74, v14
	v_exp_f32_e32 v15, v15
	v_mul_f32_e32 v24, v23, v24
	v_mul_f32_e32 v14, 0x3fb8aa3b, v14
	v_add_f32_e32 v21, 1.0, v21
	v_sqrt_f32_e32 v24, v24
	v_exp_f32_e32 v14, v14
; __device__ __forceinline__ unsigned cvt_pk_bf16(float lo, float hi) { unsigned r; asm volatile("v_cvt_pk_bf16_f32 %0, %1, %2" : "=v"(r) : "v"(lo), "v"(hi)); return r; }
; __device__ __forceinline__ float bflo(unsigned w) { return __uint_as_float(w << 16); }
; __device__ __forceinline__ float bfhi(unsigned w) { return __uint_as_float(w & 0xffff0000u); }
; __device__ __forceinline__ float sigmoidf_(float x) { return __builtin_amdgcn_rcpf(1.0f + __expf(-x)); }
;     __device__ __forceinline__ void operator()(const pg8::f32x4 (&acc)[2][2][4][2], const pg8::Unit& u, int wr, int wc, int fr, int fq) const {
;     ...
;         for (int n = 0; n < 2; ++n) { const int ch = ch0 + 16 * n; const v4f bi = biv[n], br = brv[n], sp = spv[n];
; #pragma unroll
;             for (int ai = 0; ai < 2; ++ai)
; #pragma unroll
;                 for (int m = 0; m < 4; ++m) { const int row = row0 + ai * 128 + m * 16; const bool first = (row & (SEQ - 1)) == 0; const size_t off = (size_t)row * DM + ch;
;                     const v2u xw = xv[n][ai][m]; const float x[4] = {bflo(xw.x), bfhi(xw.x), bflo(xw.y), bfhi(xw.y)};
;                     const pg8::f32x4 vi = acc[ai][0][m][n], vr = acc[ai][1][m][n]; v4u av;
; #pragma unroll
;                     for (int j = 0; j < 4; ++j) { const float ig = sigmoidf_(vi[j] + bi[j]), rg = sigmoidf_(vr[j] + br[j]);
;                         const float la = -8.0f * rg * sp[j];
;                         const float oma = 1.0f - __expf(la);
;                         const float mult = first ? 1.0f : __builtin_amdgcn_sqrtf(oma * (2.0f - oma));
;                         av[j] = pg8::cvt_pk_bf16(oma, mult * ig * x[j]); }
;                     *(v4u*)(AU + off) = av;
;                     if (m & 1) asm volatile("" ::: "memory"); } }
	v_rcp_f32_e32 v21, v21
	v_add_f32_e32 v10, v10, v78
	v_lshlrev_b32_e32 v28, 16, v175
	v_mul_f32_e32 v10, 0xbfb8aa3b, v10
	v_add_f32_e32 v15, 1.0, v15
	v_mul_f32_e32 v20, v20, v28
	v_exp_f32_e32 v10, v10
	v_rcp_f32_e32 v15, v15
	v_cvt_pk_bf16_f32 v20, v22, v20
	v_cndmask_b32_e64 v22, v24, 1.0, s[12:13]
	v_sub_f32_e32 v14, 1.0, v14
	v_mul_f32_e32 v21, v21, v22
	v_sub_f32_e32 v22, 2.0, v14
	v_mul_f32_e32 v22, v14, v22
	v_add_f32_e32 v10, 1.0, v10
	v_sqrt_f32_e32 v22, v22
	v_mul_f32_e32 v15, 0xc1000000, v15
	v_rcp_f32_e32 v10, v10
	v_mul_f32_e32 v15, v75, v15
	v_mul_f32_e32 v15, 0x3fb8aa3b, v15
	v_and_b32_e32 v29, 0xffff0000, v175
	v_exp_f32_e32 v15, v15
	v_mul_f32_e32 v21, v21, v29
	v_cndmask_b32_e64 v22, v22, 1.0, s[14:15]
	v_add_f32_e32 v11, v11, v79
	v_cvt_pk_bf16_f32 v21, v23, v21
	global_store_dwordx4 v[94:95], v[18:21], off offset:64 sc1
	v_mul_f32_e32 v10, v10, v22
	v_mul_f32_e32 v11, 0xbfb8aa3b, v11
	v_lshlrev_b32_e32 v18, 16, v172
	v_mul_f32_e32 v10, v10, v18
	v_exp_f32_e32 v11, v11
	v_cvt_pk_bf16_f32 v10, v14, v10
	v_sub_f32_e32 v14, 1.0, v15
	v_sub_f32_e32 v15, 2.0, v14
	v_mul_f32_e32 v15, v14, v15
	v_add_f32_e32 v16, v16, v84
	v_add_f32_e32 v11, 1.0, v11
	v_sqrt_f32_e32 v15, v15
	v_mul_f32_e32 v16, 0xbfb8aa3b, v16
	v_rcp_f32_e32 v11, v11
	v_exp_f32_e32 v16, v16
	v_cndmask_b32_e64 v15, v15, 1.0, s[14:15]
	v_and_b32_e32 v19, 0xffff0000, v172
	v_mul_f32_e32 v11, v11, v15
	v_add_f32_e32 v15, 1.0, v16
	v_rcp_f32_e32 v15, v15
	v_mul_f32_e32 v11, v11, v19
	v_cvt_pk_bf16_f32 v11, v14, v11
	v_add_f32_e32 v6, v6, v82
	v_mul_f32_e32 v15, 0xc1000000, v15
	v_mul_f32_e32 v15, v76, v15
	v_mul_f32_e32 v15, 0x3fb8aa3b, v15
	v_exp_f32_e32 v15, v15
	v_add_f32_e32 v12, v12, v80
	v_mul_f32_e32 v6, 0xbfb8aa3b, v6
	v_mul_f32_e32 v12, 0xbfb8aa3b, v12
	v_sub_f32_e32 v14, 1.0, v15
	v_add_f32_e32 v15, v17, v85
	v_mul_f32_e32 v15, 0xbfb8aa3b, v15
	v_exp_f32_e32 v15, v15
	v_exp_f32_e32 v6, v6
	v_exp_f32_e32 v12, v12
	v_sub_f32_e32 v16, 2.0, v14
	v_add_f32_e32 v15, 1.0, v15
	v_rcp_f32_e32 v15, v15
	v_mul_f32_e32 v16, v14, v16
	v_add_f32_e32 v6, 1.0, v6
	v_add_f32_e32 v12, 1.0, v12
	v_mul_f32_e32 v15, 0xc1000000, v15
	v_mul_f32_e32 v15, v77, v15
	v_mul_f32_e32 v15, 0x3fb8aa3b, v15
	v_sqrt_f32_e32 v16, v16
	v_exp_f32_e32 v15, v15
	v_rcp_f32_e32 v6, v6
	v_rcp_f32_e32 v12, v12
	v_add_f32_e32 v13, v13, v81
	v_mul_f32_e32 v13, 0xbfb8aa3b, v13
	v_exp_f32_e32 v13, v13
	v_add_f32_e32 v7, v7, v83
	v_cndmask_b32_e64 v16, v16, 1.0, s[14:15]
	v_sub_f32_e32 v15, 1.0, v15
	v_mul_f32_e32 v6, 0xc1000000, v6
	v_mul_f32_e32 v7, 0xbfb8aa3b, v7
	v_mul_f32_e32 v12, v12, v16
	v_sub_f32_e32 v16, 2.0, v15
	v_mul_f32_e32 v6, v74, v6
	v_exp_f32_e32 v7, v7
	v_mul_f32_e32 v16, v15, v16
	v_mul_f32_e32 v6, 0x3fb8aa3b, v6
	v_add_f32_e32 v13, 1.0, v13
	v_sqrt_f32_e32 v16, v16
	v_exp_f32_e32 v6, v6
	v_rcp_f32_e32 v13, v13
	v_add_f32_e32 v2, v2, v78
	v_lshlrev_b32_e32 v20, 16, v173
	v_mul_f32_e32 v2, 0xbfb8aa3b, v2
	v_add_f32_e32 v7, 1.0, v7
	v_mul_f32_e32 v12, v12, v20
	v_exp_f32_e32 v2, v2
	v_rcp_f32_e32 v7, v7
	v_cvt_pk_bf16_f32 v12, v14, v12
	v_cndmask_b32_e64 v14, v16, 1.0, s[14:15]
	v_sub_f32_e32 v6, 1.0, v6
	v_mul_f32_e32 v13, v13, v14
	v_sub_f32_e32 v14, 2.0, v6
	v_mul_f32_e32 v14, v6, v14
	v_add_f32_e32 v2, 1.0, v2
	v_sqrt_f32_e32 v14, v14
	v_mul_f32_e32 v7, 0xc1000000, v7
	v_rcp_f32_e32 v2, v2
	v_mul_f32_e32 v7, v75, v7
	v_mul_f32_e32 v7, 0x3fb8aa3b, v7
	v_and_b32_e32 v21, 0xffff0000, v173
	v_exp_f32_e32 v7, v7
	v_mul_f32_e32 v13, v13, v21
	v_cndmask_b32_e64 v14, v14, 1.0, s[16:17]
	v_add_f32_e32 v3, v3, v79
	v_cvt_pk_bf16_f32 v13, v15, v13
	global_store_dwordx4 v[86:87], v[10:13], off offset:64 sc1
	v_mul_f32_e32 v2, v2, v14
	v_mul_f32_e32 v3, 0xbfb8aa3b, v3
	v_lshlrev_b32_e32 v10, 16, v170
	v_mul_f32_e32 v2, v2, v10
	v_exp_f32_e32 v3, v3
	v_cvt_pk_bf16_f32 v2, v6, v2
	v_sub_f32_e32 v6, 1.0, v7
	v_sub_f32_e32 v7, 2.0, v6
	v_mul_f32_e32 v7, v6, v7
	v_add_f32_e32 v8, v8, v84
	v_add_f32_e32 v3, 1.0, v3
	v_sqrt_f32_e32 v7, v7
	v_mul_f32_e32 v8, 0xbfb8aa3b, v8
	v_rcp_f32_e32 v3, v3
	v_exp_f32_e32 v8, v8
	v_cndmask_b32_e64 v7, v7, 1.0, s[16:17]
	v_and_b32_e32 v11, 0xffff0000, v170
	v_mul_f32_e32 v3, v3, v7
	v_add_f32_e32 v7, 1.0, v8
	v_rcp_f32_e32 v7, v7
	v_mul_f32_e32 v3, v3, v11
	v_cvt_pk_bf16_f32 v3, v6, v3
	v_add_f32_e32 v4, v4, v80
	v_mul_f32_e32 v7, 0xc1000000, v7
	v_mul_f32_e32 v7, v76, v7
	v_mul_f32_e32 v7, 0x3fb8aa3b, v7
	v_exp_f32_e32 v7, v7
	v_mul_f32_e32 v4, 0xbfb8aa3b, v4
	v_exp_f32_e32 v4, v4
	v_add_f32_e32 v5, v5, v81
	v_sub_f32_e32 v6, 1.0, v7
	v_add_f32_e32 v7, v9, v85
	v_mul_f32_e32 v7, 0xbfb8aa3b, v7
	v_exp_f32_e32 v7, v7
	v_sub_f32_e32 v8, 2.0, v6
	v_mul_f32_e32 v8, v6, v8
	v_add_f32_e32 v4, 1.0, v4
	v_add_f32_e32 v7, 1.0, v7
	v_rcp_f32_e32 v7, v7
	v_sqrt_f32_e32 v8, v8
	v_rcp_f32_e32 v4, v4
	v_mul_f32_e32 v5, 0xbfb8aa3b, v5
	v_mul_f32_e32 v7, 0xc1000000, v7
	v_mul_f32_e32 v7, v77, v7
	v_mul_f32_e32 v7, 0x3fb8aa3b, v7
	v_exp_f32_e32 v7, v7
	v_exp_f32_e32 v5, v5
	v_cndmask_b32_e64 v8, v8, 1.0, s[16:17]
	v_mul_f32_e32 v4, v4, v8
	v_sub_f32_e32 v7, 1.0, v7
	v_sub_f32_e32 v8, 2.0, v7
	v_mul_f32_e32 v8, v7, v8
	v_add_f32_e32 v5, 1.0, v5
	v_sqrt_f32_e32 v8, v8
	v_rcp_f32_e32 v5, v5
	v_lshlrev_b32_e32 v12, 16, v171
	v_mul_f32_e32 v4, v4, v12
	v_cvt_pk_bf16_f32 v4, v6, v4
	v_cndmask_b32_e64 v6, v8, 1.0, s[16:17]
	v_and_b32_e32 v13, 0xffff0000, v171
	v_mul_f32_e32 v5, v5, v6
	v_mul_f32_e32 v5, v5, v13
	v_cvt_pk_bf16_f32 v5, v7, v5
	global_store_dwordx4 v[66:67], v[2:5], off offset:64 sc1
	s_and_b64 vcc, exec, s[2:3]
	s_mov_b64 s[2:3], -1
	s_cbranch_vccnz .LBB0_1220
	s_andn2_b64 vcc, exec, s[26:27]
	s_cbranch_vccnz .LBB0_1219
	s_barrier
	s_branch .LBB0_1219

; __device__ __forceinline__ unsigned cvt_pk_bf16(float lo, float hi) { unsigned r; asm volatile("v_cvt_pk_bf16_f32 %0, %1, %2" : "=v"(r) : "v"(lo), "v"(hi)); return r; }
;     __device__ __forceinline__ void operator()(const f32x4 (&acc)[2][2][4][2], const Unit& u, int wr, int wc, int fr, int fq) const {
;         const int row0 = u.pm * BM + wr * 64 + fr, col0 = u.pn * BM + wc * 32 + 8 * fq;
;         float scv[2][4];
; #pragma unroll
;         for (int ai = 0; ai < 2; ++ai)
; #pragma unroll
;             for (int m = 0; m < 4; ++m) scv[ai][m] = rs[row0 + ai * HALF + m * 16];
; #pragma unroll
;         for (int ai = 0; ai < 2; ++ai)
; #pragma unroll
;             for (int m = 0; m < 4; ++m) { const int row = row0 + ai * HALF + m * 16; const float sc = scv[ai][m]; bf16_t* rowp = O + (size_t)row * ldc + col0;
; #pragma unroll
;                 for (int bj = 0; bj < 2; ++bj) { const f32x4 v0 = acc[ai][bj][m][0] * sc, v1 = acc[ai][bj][m][1] * sc;
;                     u32x4 w; w.x = cvt_pk_bf16(v0[0], v0[1]); w.y = cvt_pk_bf16(v0[2], v0[3]); w.z = cvt_pk_bf16(v1[0], v1[1]); w.w = cvt_pk_bf16(v1[2], v1[3]);
;                     *(u32x4*)(rowp + bj * HALF) = w; } }
.LBB0_1509:
	v_lshl_add_u32 v148, s30, 8, v1
	v_ashrrev_i32_e32 v149, 31, v148
	v_or_b32_e32 v160, 16, v148
	v_or_b32_e32 v164, 32, v148
	v_lshl_add_u64 v[156:157], v[148:149], 2, s[8:9]
	v_ashrrev_i32_e32 v161, 31, v160
	v_ashrrev_i32_e32 v165, 31, v164
	global_load_dword v158, v[156:157], off
	v_lshl_add_u64 v[162:163], v[160:161], 2, s[8:9]
	v_lshl_add_u64 v[166:167], v[164:165], 2, s[8:9]
	global_load_dword v162, v[162:163], off
	v_or_b32_e32 v168, 48, v148
	global_load_dword v166, v[166:167], off
	v_ashrrev_i32_e32 v169, 31, v168
	v_lshl_add_u64 v[170:171], v[168:169], 2, s[8:9]
	global_load_dword v150, v[170:171], off
	global_load_dword v172, v[156:157], off offset:512
	global_load_dword v174, v[156:157], off offset:576
	global_load_dword v152, v[156:157], off offset:640
	global_load_dword v146, v[156:157], off offset:704
	v_lshl_or_b32 v170, s58, 8, v151
	v_ashrrev_i32_e32 v171, 31, v170
	v_lshlrev_b64 v[148:149], 15, v[148:149]
	v_lshlrev_b64 v[170:171], 1, v[170:171]
	v_lshl_add_u64 v[148:149], s[6:7], 0, v[148:149]
	v_lshlrev_b64 v[160:161], 15, v[160:161]
	v_lshlrev_b64 v[164:165], 15, v[164:165]
	v_lshlrev_b64 v[168:169], 15, v[168:169]
	v_lshl_add_u64 v[148:149], v[148:149], 0, v[170:171]
	v_lshl_add_u64 v[156:157], s[6:7], 0, v[160:161]
	v_lshl_add_u64 v[160:161], s[6:7], 0, v[164:165]
	v_lshl_add_u64 v[164:165], s[6:7], 0, v[168:169]
	v_lshl_add_u64 v[156:157], v[156:157], 0, v[170:171]
	v_lshl_add_u64 v[160:161], v[160:161], 0, v[170:171]
	v_lshl_add_u64 v[164:165], v[164:165], 0, v[170:171]
	s_waitcnt vmcnt(0)
	v_pk_mul_f32 v[124:125], v[124:125], v[158:159] op_sel_hi:[1,0]
	v_pk_mul_f32 v[128:129], v[128:129], v[158:159] op_sel_hi:[1,0]
	v_pk_mul_f32 v[126:127], v[126:127], v[158:159] op_sel_hi:[1,0]
	v_pk_mul_f32 v[122:123], v[122:123], v[158:159] op_sel_hi:[1,0]
	v_pk_mul_f32 v[108:109], v[108:109], v[158:159] op_sel_hi:[1,0]
	v_pk_mul_f32 v[106:107], v[106:107], v[158:159] op_sel_hi:[1,0]
	v_pk_mul_f32 v[168:169], v[100:101], v[158:159] op_sel_hi:[1,0]
	v_pk_mul_f32 v[158:159], v[98:99], v[158:159] op_sel_hi:[1,0]
	v_cvt_pk_bf16_f32 v98, v126, v127
	v_cvt_pk_bf16_f32 v99, v128, v129
	v_cvt_pk_bf16_f32 v100, v122, v123
	v_cvt_pk_bf16_f32 v101, v124, v125
	v_pk_mul_f32 v[124:125], v[78:79], v[166:167] op_sel_hi:[1,0]
	global_store_dwordx4 v[148:149], v[98:101], off sc1
	v_cvt_pk_bf16_f32 v78, v106, v107
	v_cvt_pk_bf16_f32 v79, v108, v109
	v_pk_mul_f32 v[120:121], v[120:121], v[162:163] op_sel_hi:[1,0]
	v_pk_mul_f32 v[118:119], v[118:119], v[162:163] op_sel_hi:[1,0]
	v_pk_mul_f32 v[122:123], v[80:81], v[166:167] op_sel_hi:[1,0]
	v_cvt_pk_bf16_f32 v80, v158, v159
	v_cvt_pk_bf16_f32 v81, v168, v169
	global_store_dwordx4 v[148:149], v[78:81], off offset:256 sc1
	v_pk_mul_f32 v[116:117], v[116:117], v[162:163] op_sel_hi:[1,0]
	v_pk_mul_f32 v[114:115], v[114:115], v[162:163] op_sel_hi:[1,0]
	v_cvt_pk_bf16_f32 v78, v118, v119
	v_cvt_pk_bf16_f32 v79, v120, v121
	v_pk_mul_f32 v[92:93], v[92:93], v[162:163] op_sel_hi:[1,0]
	v_pk_mul_f32 v[90:91], v[90:91], v[162:163] op_sel_hi:[1,0]
	v_cvt_pk_bf16_f32 v80, v114, v115
	v_cvt_pk_bf16_f32 v81, v116, v117
	global_store_dwordx4 v[156:157], v[78:81], off sc1
	v_pk_mul_f32 v[88:89], v[88:89], v[162:163] op_sel_hi:[1,0]
	v_pk_mul_f32 v[86:87], v[86:87], v[162:163] op_sel_hi:[1,0]
	v_cvt_pk_bf16_f32 v78, v90, v91
	v_cvt_pk_bf16_f32 v79, v92, v93
	v_pk_mul_f32 v[112:113], v[112:113], v[166:167] op_sel_hi:[1,0]
	v_pk_mul_f32 v[110:111], v[110:111], v[166:167] op_sel_hi:[1,0]
	v_cvt_pk_bf16_f32 v80, v86, v87
	v_cvt_pk_bf16_f32 v81, v88, v89
	global_store_dwordx4 v[156:157], v[78:81], off offset:256 sc1
	v_pk_mul_f32 v[104:105], v[104:105], v[166:167] op_sel_hi:[1,0]
	v_pk_mul_f32 v[102:103], v[102:103], v[166:167] op_sel_hi:[1,0]
	v_cvt_pk_bf16_f32 v78, v110, v111
	v_cvt_pk_bf16_f32 v79, v112, v113
	v_pk_mul_f32 v[84:85], v[84:85], v[166:167] op_sel_hi:[1,0]
	v_pk_mul_f32 v[82:83], v[82:83], v[166:167] op_sel_hi:[1,0]
	v_cvt_pk_bf16_f32 v80, v102, v103
	v_cvt_pk_bf16_f32 v81, v104, v105
	global_store_dwordx4 v[160:161], v[78:81], off sc1
	v_pk_mul_f32 v[96:97], v[96:97], v[150:151] op_sel_hi:[1,0]
	v_pk_mul_f32 v[94:95], v[94:95], v[150:151] op_sel_hi:[1,0]
	v_cvt_pk_bf16_f32 v78, v82, v83
	v_cvt_pk_bf16_f32 v79, v84, v85
	v_cvt_pk_bf16_f32 v80, v124, v125
	v_cvt_pk_bf16_f32 v81, v122, v123
	global_store_dwordx4 v[160:161], v[78:81], off offset:256 sc1
	v_pk_mul_f32 v[72:73], v[72:73], v[150:151] op_sel_hi:[1,0]
	v_pk_mul_f32 v[70:71], v[70:71], v[150:151] op_sel_hi:[1,0]
	v_pk_mul_f32 v[78:79], v[76:77], v[150:151] op_sel_hi:[1,0]
	v_pk_mul_f32 v[76:77], v[74:75], v[150:151] op_sel_hi:[1,0]
	v_cvt_pk_bf16_f32 v74, v94, v95
; __device__ __forceinline__ unsigned cvt_pk_bf16(float lo, float hi) { unsigned r; asm volatile("v_cvt_pk_bf16_f32 %0, %1, %2" : "=v"(r) : "v"(lo), "v"(hi)); return r; }
;     __device__ __forceinline__ void operator()(const f32x4 (&acc)[2][2][4][2], const Unit& u, int wr, int wc, int fr, int fq) const {
;     ...
;             for (int m = 0; m < 4; ++m) { const int row = row0 + ai * HALF + m * 16; const float sc = scv[ai][m]; bf16_t* rowp = O + (size_t)row * ldc + col0;
; #pragma unroll
;                 for (int bj = 0; bj < 2; ++bj) { const f32x4 v0 = acc[ai][bj][m][0] * sc, v1 = acc[ai][bj][m][1] * sc;
;                     u32x4 w; w.x = cvt_pk_bf16(v0[0], v0[1]); w.y = cvt_pk_bf16(v0[2], v0[3]); w.z = cvt_pk_bf16(v1[0], v1[1]); w.w = cvt_pk_bf16(v1[2], v1[3]);
;                     *(u32x4*)(rowp + bj * HALF) = w; } }
	v_cvt_pk_bf16_f32 v75, v96, v97
	v_pk_mul_f32 v[62:63], v[62:63], v[172:173] op_sel_hi:[1,0]
	v_cvt_pk_bf16_f32 v76, v76, v77
	v_cvt_pk_bf16_f32 v77, v78, v79
	global_store_dwordx4 v[164:165], v[74:77], off sc1
	v_pk_mul_f32 v[64:65], v[64:65], v[172:173] op_sel_hi:[1,0]
	v_pk_mul_f32 v[56:57], v[56:57], v[172:173] op_sel_hi:[1,0]
	v_pk_mul_f32 v[74:75], v[68:69], v[150:151] op_sel_hi:[1,0]
	v_pk_mul_f32 v[68:69], v[66:67], v[150:151] op_sel_hi:[1,0]
	v_cvt_pk_bf16_f32 v66, v70, v71
	v_cvt_pk_bf16_f32 v67, v72, v73
	v_pk_mul_f32 v[54:55], v[54:55], v[172:173] op_sel_hi:[1,0]
	v_cvt_pk_bf16_f32 v68, v68, v69
	v_cvt_pk_bf16_f32 v69, v74, v75
	global_store_dwordx4 v[164:165], v[66:69], off offset:256 sc1
	v_pk_mul_f32 v[50:51], v[50:51], v[174:175] op_sel_hi:[1,0]
	v_pk_mul_f32 v[40:41], v[40:41], v[174:175] op_sel_hi:[1,0]
	v_pk_mul_f32 v[68:69], v[60:61], v[172:173] op_sel_hi:[1,0]
	v_pk_mul_f32 v[60:61], v[58:59], v[172:173] op_sel_hi:[1,0]
	v_cvt_pk_bf16_f32 v58, v62, v63
	v_add_co_u32_e32 v62, vcc, s54, v148
	v_cvt_pk_bf16_f32 v59, v64, v65
	v_cvt_pk_bf16_f32 v60, v60, v61
	v_cvt_pk_bf16_f32 v61, v68, v69
	v_lshl_add_u64 v[66:67], v[148:149], 0, s[14:15]
	s_nop 0
	v_addc_co_u32_e32 v63, vcc, 0, v149, vcc
	global_store_dwordx4 v[62:63], v[58:61], off sc1
	v_pk_mul_f32 v[38:39], v[38:39], v[174:175] op_sel_hi:[1,0]
	v_pk_mul_f32 v[34:35], v[34:35], v[152:153] op_sel_hi:[1,0]
	v_pk_mul_f32 v[58:59], v[48:49], v[172:173] op_sel_hi:[1,0]
	v_pk_mul_f32 v[48:49], v[46:47], v[172:173] op_sel_hi:[1,0]
	v_cvt_pk_bf16_f32 v46, v54, v55
	v_cvt_pk_bf16_f32 v47, v56, v57
	v_pk_mul_f32 v[24:25], v[24:25], v[152:153] op_sel_hi:[1,0]
	v_cvt_pk_bf16_f32 v48, v48, v49
	v_cvt_pk_bf16_f32 v49, v58, v59
	global_store_dwordx4 v[66:67], v[46:49], off offset:256 sc1
	v_pk_mul_f32 v[22:23], v[22:23], v[152:153] op_sel_hi:[1,0]
	v_pk_mul_f32 v[18:19], v[18:19], v[146:147] op_sel_hi:[1,0]
	v_pk_mul_f32 v[48:49], v[52:53], v[174:175] op_sel_hi:[1,0]
	v_pk_mul_f32 v[52:53], v[44:45], v[174:175] op_sel_hi:[1,0]
	v_pk_mul_f32 v[44:45], v[42:43], v[174:175] op_sel_hi:[1,0]
	v_cvt_pk_bf16_f32 v42, v50, v51
	v_cvt_pk_bf16_f32 v43, v48, v49
	v_add_co_u32_e32 v48, vcc, s55, v148
	v_cvt_pk_bf16_f32 v44, v44, v45
	v_cvt_pk_bf16_f32 v45, v52, v53
	v_lshl_add_u64 v[46:47], v[148:149], 0, s[16:17]
	s_nop 0
	v_addc_co_u32_e32 v49, vcc, 0, v149, vcc
	global_store_dwordx4 v[48:49], v[42:45], off sc1
	v_pk_mul_f32 v[8:9], v[8:9], v[146:147] op_sel_hi:[1,0]
	v_pk_mul_f32 v[6:7], v[6:7], v[146:147] op_sel_hi:[1,0]
	v_pk_mul_f32 v[42:43], v[32:33], v[174:175] op_sel_hi:[1,0]
	v_pk_mul_f32 v[32:33], v[30:31], v[174:175] op_sel_hi:[1,0]
	v_cvt_pk_bf16_f32 v30, v38, v39
	v_cvt_pk_bf16_f32 v31, v40, v41
	s_nop 0
	v_cvt_pk_bf16_f32 v32, v32, v33
	v_cvt_pk_bf16_f32 v33, v42, v43
	global_store_dwordx4 v[46:47], v[30:33], off offset:256 sc1
	s_nop 1
	v_pk_mul_f32 v[32:33], v[36:37], v[152:153] op_sel_hi:[1,0]
	v_pk_mul_f32 v[36:37], v[28:29], v[152:153] op_sel_hi:[1,0]
	v_pk_mul_f32 v[28:29], v[26:27], v[152:153] op_sel_hi:[1,0]
	v_cvt_pk_bf16_f32 v26, v34, v35
	v_cvt_pk_bf16_f32 v27, v32, v33
	v_add_co_u32_e32 v32, vcc, s56, v148
	v_cvt_pk_bf16_f32 v28, v28, v29
	v_cvt_pk_bf16_f32 v29, v36, v37
	v_lshl_add_u64 v[30:31], v[148:149], 0, s[18:19]
	s_nop 0
	v_addc_co_u32_e32 v33, vcc, 0, v149, vcc
	global_store_dwordx4 v[32:33], v[26:29], off sc1
	s_nop 1
	v_pk_mul_f32 v[26:27], v[16:17], v[152:153] op_sel_hi:[1,0]
	v_pk_mul_f32 v[16:17], v[14:15], v[152:153] op_sel_hi:[1,0]
	v_cvt_pk_bf16_f32 v14, v22, v23
	v_cvt_pk_bf16_f32 v15, v24, v25
	s_nop 0
	v_cvt_pk_bf16_f32 v16, v16, v17
	v_cvt_pk_bf16_f32 v17, v26, v27
	global_store_dwordx4 v[30:31], v[14:17], off offset:256 sc1
	s_nop 1
	v_pk_mul_f32 v[16:17], v[20:21], v[146:147] op_sel_hi:[1,0]
	v_pk_mul_f32 v[20:21], v[12:13], v[146:147] op_sel_hi:[1,0]
	v_pk_mul_f32 v[12:13], v[10:11], v[146:147] op_sel_hi:[1,0]
	v_cvt_pk_bf16_f32 v10, v18, v19
	v_cvt_pk_bf16_f32 v11, v16, v17
	v_add_co_u32_e32 v16, vcc, s57, v148
	v_lshl_add_u64 v[14:15], v[148:149], 0, s[20:21]
	s_nop 0
	v_addc_co_u32_e32 v17, vcc, 0, v149, vcc
	v_cvt_pk_bf16_f32 v12, v12, v13
	v_cvt_pk_bf16_f32 v13, v20, v21
	global_store_dwordx4 v[16:17], v[10:13], off sc1
	s_andn2_b64 vcc, exec, s[2:3]
	s_mov_b64 s[2:3], -1
	v_pk_mul_f32 v[10:11], v[4:5], v[146:147] op_sel_hi:[1,0]
	v_pk_mul_f32 v[4:5], v[2:3], v[146:147] op_sel_hi:[1,0]
	v_cvt_pk_bf16_f32 v2, v6, v7
	v_cvt_pk_bf16_f32 v3, v8, v9
	s_nop 0
	v_cvt_pk_bf16_f32 v4, v4, v5
	v_cvt_pk_bf16_f32 v5, v10, v11
	global_store_dwordx4 v[14:15], v[2:5], off offset:256 sc1
	s_cbranch_vccnz .LBB0_1498
	s_andn2_b64 vcc, exec, s[4:5]
	s_cbranch_vccnz .LBB0_1497
	s_barrier
	s_branch .LBB0_1497

; __device__ __forceinline__ unsigned f2bf(float f) { unsigned u = __float_as_uint(f); return (u + 0x7fffu + ((u >> 16) & 1u)) >> 16; }
; __device__ __forceinline__ int crow(int r, int hi) { return (r & 3) + 8 * (r >> 2) + 4 * hi; }
; __device__ __forceinline__ void hg_mfma(Frame& F, bf16* Y, int u, unsigned* prog = nullptr) {
;     ...
;         pv_one<0>(o, vbS + vb * 512, qr[0], qr[1], qr[2], qr[3]);
;         pv_one<0>(o, vbS + 16384 + vb * 512, qr[4], qr[5], qr[6], qr[7]);
; #pragma unroll
;         for (int r = 0; r < 16; ++r) { const int t = 32 * tb + crow(r, hi); *(bf16*)(lds + HG_O + t * 272 + (32 * vb + r32) * 2) = (bf16)f2bf(o[r]); }
;         { const float* dec = (const float*)(lds + HG_DEC);
; #pragma unroll
;           for (int r = 0; r < 16; ++r) { const float dv = dec[32 * dblk + crow(r, hi)]; Sa[r] *= dv; Sb[r] *= dv; }
;           bf16x8 kh[4];
; #pragma unroll
;           for (int ks = 0; ks < 4; ++ks) kh[ks] = *reinterpret_cast<const bf16x8*>((const char*)lds + HG_KH + (32 * dblk + r32) * 144 + (16 * ks + 8 * hi) * 2);
;           pv_one<0>(Sa, vbV + vblk0 * 512, kh[0], kh[1], kh[2], kh[3]);
;           pv_one<0>(Sb, vbV + (vblk0 + 1) * 512, kh[0], kh[1], kh[2], kh[3]); }
;       }
;       const bool post = prog && (c & 3) == 0 && c > 0 && c <= 16;
;       if (post) asm volatile("s_waitcnt vmcnt(0)" ::: "memory");
;       __syncthreads();
.LBB0_1574:
	ds_read_b64_tr_b16 v[206:207], v139 offset:0
	ds_read_b64_tr_b16 v[208:209], v139 offset:0x800
	ds_read_b64_tr_b16 v[210:211], v139 offset:0x1000
	ds_read_b64_tr_b16 v[212:213], v139 offset:0x1800
	ds_read_b64_tr_b16 v[218:219], v139 offset:0x2000
	ds_read_b64_tr_b16 v[220:221], v139 offset:0x2800
	ds_read_b64_tr_b16 v[228:229], v139 offset:0x3000
	ds_read_b64_tr_b16 v[230:231], v139 offset:0x3800
	s_waitcnt lgkmcnt(0)
	s_nop 0
	v_mfma_f32_32x32x16_bf16 v[34:49], v[66:69], v[206:209], v[34:49]
	ds_read_b64_tr_b16 v[66:67], v140 offset:0
	ds_read_b64_tr_b16 v[68:69], v140 offset:0x800
	v_mfma_f32_32x32x16_bf16 v[34:49], v[74:77], v[210:213], v[34:49]
	v_mfma_f32_32x32x16_bf16 v[34:49], v[70:73], v[218:221], v[34:49]
	ds_read_b64_tr_b16 v[70:71], v140 offset:0x1000
	ds_read_b64_tr_b16 v[72:73], v140 offset:0x1800
	ds_read_b64_tr_b16 v[74:75], v140 offset:0x2000
	ds_read_b64_tr_b16 v[76:77], v140 offset:0x2800
	ds_read_b64_tr_b16 v[206:207], v140 offset:0x3000
	ds_read_b64_tr_b16 v[208:209], v140 offset:0x3800
	s_waitcnt lgkmcnt(0)
	v_mfma_f32_32x32x16_bf16 v[34:49], v[78:81], v[228:231], v[34:49]
	v_mfma_f32_32x32x16_bf16 v[34:49], v[82:85], v[66:69], v[34:49]
	v_mfma_f32_32x32x16_bf16 v[34:49], v[86:89], v[70:73], v[34:49]
	v_mfma_f32_32x32x16_bf16 v[34:49], v[90:93], v[74:77], v[34:49]
	v_mfma_f32_32x32x16_bf16 v[34:49], v[94:97], v[206:209], v[34:49]
	s_nop 11
	v_bfe_u32 v66, v34, 16, 1
	v_bfe_u32 v67, v35, 16, 1
	v_bfe_u32 v68, v36, 16, 1
	v_bfe_u32 v69, v37, 16, 1
	v_bfe_u32 v70, v38, 16, 1
	v_bfe_u32 v71, v39, 16, 1
	v_bfe_u32 v72, v40, 16, 1
	v_bfe_u32 v73, v41, 16, 1
	v_bfe_u32 v74, v42, 16, 1
	v_bfe_u32 v75, v43, 16, 1
	v_bfe_u32 v76, v44, 16, 1
	v_add3_u32 v34, v34, v66, s61
	v_add3_u32 v35, v35, v67, s61
	v_add3_u32 v36, v36, v68, s61
	v_add3_u32 v37, v37, v69, s61
	v_add3_u32 v38, v38, v70, s61
	v_add3_u32 v39, v39, v71, s61
	v_add3_u32 v40, v40, v72, s61
	v_add3_u32 v41, v41, v73, s61
	v_add3_u32 v42, v42, v74, s61
	v_add3_u32 v43, v43, v75, s61
	ds_write_b16_d16_hi v173, v34
	ds_write_b16_d16_hi v173, v35 offset:272
	ds_write_b16_d16_hi v173, v36 offset:544
	ds_write_b16_d16_hi v173, v37 offset:816
	ds_write_b16_d16_hi v173, v38 offset:2176
	ds_write_b16_d16_hi v173, v39 offset:2448
	ds_write_b16_d16_hi v173, v40 offset:2720
	ds_write_b16_d16_hi v173, v41 offset:2992
	ds_write_b16_d16_hi v173, v42 offset:4352
	ds_write_b16_d16_hi v173, v43 offset:4624
	v_add3_u32 v34, v44, v76, s61
	ds_write_b16_d16_hi v173, v34 offset:4896
	v_bfe_u32 v34, v45, 16, 1
	v_add3_u32 v34, v45, v34, s61
	ds_write_b16_d16_hi v173, v34 offset:5168
	v_bfe_u32 v34, v46, 16, 1
	v_add3_u32 v34, v46, v34, s61
	ds_write_b16_d16_hi v173, v34 offset:6528
	v_bfe_u32 v34, v47, 16, 1
	v_add3_u32 v34, v47, v34, s61
	ds_write_b16_d16_hi v173, v34 offset:6800
	v_bfe_u32 v34, v48, 16, 1
	v_add3_u32 v34, v48, v34, s61
	ds_write_b16_d16_hi v173, v34 offset:7072
	v_bfe_u32 v34, v49, 16, 1
	v_add3_u32 v34, v49, v34, s61
	ds_write_b16_d16_hi v173, v34 offset:7344
	ds_read_b128 v[34:37], v149
	ds_read_b128 v[38:41], v149 offset:32
	ds_read_b128 v[42:45], v149 offset:64
	ds_read_b128 v[46:49], v149 offset:96
	ds_read_b128 v[66:69], v174 offset:49152
	ds_read_b128 v[70:73], v174 offset:49184
	ds_read_b128 v[74:77], v174 offset:49216
	ds_read_b128 v[78:81], v174 offset:49248
	s_waitcnt lgkmcnt(7)
	v_pk_mul_f32 v[18:19], v[18:19], v[34:35]
	v_pk_mul_f32 v[2:3], v[2:3], v[34:35]
	ds_read_b64_tr_b16 v[34:35], v142 offset:0
	v_pk_mul_f32 v[20:21], v[20:21], v[36:37]
	v_pk_mul_f32 v[4:5], v[4:5], v[36:37]
	ds_read_b64_tr_b16 v[36:37], v142 offset:0x800
	s_waitcnt lgkmcnt(6)
	v_pk_mul_f32 v[22:23], v[22:23], v[38:39]
	v_pk_mul_f32 v[6:7], v[6:7], v[38:39]
	ds_read_b64_tr_b16 v[38:39], v142 offset:0x1000
	v_pk_mul_f32 v[24:25], v[24:25], v[40:41]
	v_pk_mul_f32 v[8:9], v[8:9], v[40:41]
	ds_read_b64_tr_b16 v[40:41], v142 offset:0x1800
	s_waitcnt lgkmcnt(5)
	v_pk_mul_f32 v[26:27], v[26:27], v[42:43]
	v_pk_mul_f32 v[10:11], v[10:11], v[42:43]
	ds_read_b64_tr_b16 v[42:43], v142 offset:0x2000
	v_pk_mul_f32 v[28:29], v[28:29], v[44:45]
	v_pk_mul_f32 v[12:13], v[12:13], v[44:45]
	ds_read_b64_tr_b16 v[44:45], v142 offset:0x2800
	s_waitcnt lgkmcnt(4)
	v_pk_mul_f32 v[30:31], v[30:31], v[46:47]
	v_pk_mul_f32 v[14:15], v[14:15], v[46:47]
	ds_read_b64_tr_b16 v[46:47], v142 offset:0x3000
	v_pk_mul_f32 v[32:33], v[32:33], v[48:49]
	v_pk_mul_f32 v[16:17], v[16:17], v[48:49]
	ds_read_b64_tr_b16 v[48:49], v142 offset:0x3800
	s_waitcnt lgkmcnt(0)
	s_waitcnt lgkmcnt(3)
	v_mfma_f32_32x32x16_bf16 v[18:33], v[66:69], v[34:37], v[18:33]
	ds_read_b64_tr_b16 v[34:35], v143 offset:0
	ds_read_b64_tr_b16 v[36:37], v143 offset:0x800
	s_waitcnt lgkmcnt(2)
	v_mfma_f32_32x32x16_bf16 v[18:33], v[70:73], v[38:41], v[18:33]
	ds_read_b64_tr_b16 v[38:39], v143 offset:0x1000
	ds_read_b64_tr_b16 v[40:41], v143 offset:0x1800
	s_waitcnt lgkmcnt(1)
	v_mfma_f32_32x32x16_bf16 v[18:33], v[74:77], v[42:45], v[18:33]
	ds_read_b64_tr_b16 v[42:43], v143 offset:0x2000
	ds_read_b64_tr_b16 v[44:45], v143 offset:0x2800
	s_waitcnt lgkmcnt(0)
	v_mfma_f32_32x32x16_bf16 v[18:33], v[78:81], v[46:49], v[18:33]
	ds_read_b64_tr_b16 v[46:47], v143 offset:0x3000
	ds_read_b64_tr_b16 v[48:49], v143 offset:0x3800
	s_waitcnt lgkmcnt(0)
	v_mfma_f32_32x32x16_bf16 v[2:17], v[66:69], v[34:37], v[2:17]
	s_nop 10
	v_bfe_u32 v34, v18, 16, 1
	v_bfe_u32 v35, v19, 16, 1
	v_add3_u32 v34, v18, v34, s61
	v_add3_u32 v35, v19, v35, s61
	s_barrier
; __device__ __forceinline__ float bflo(unsigned w) { return __uint_as_float(w << 16); }
; __device__ __forceinline__ float bfhi(unsigned w) { return __uint_as_float(w & 0xffff0000u); }
; __device__ __forceinline__ unsigned f2bf(float f) { unsigned u = __float_as_uint(f); return (u + 0x7fffu + ((u >> 16) & 1u)) >> 16; }
; __device__ __forceinline__ unsigned xb_add(unsigned* p, unsigned v) { return __hip_atomic_fetch_add(p, v, __ATOMIC_RELAXED, __HIP_MEMORY_SCOPE_AGENT); }
; __device__ __forceinline__ int crow(int r, int hi) { return (r & 3) + 8 * (r >> 2) + 4 * hi; }
; __device__ __forceinline__ void hg_mfma(Frame& F, bf16* Y, int u, unsigned* prog = nullptr) {
;     ...
;           for (int ks = 0; ks < 4; ++ks) kh[ks] = *reinterpret_cast<const bf16x8*>((const char*)lds + HG_KH + (32 * dblk + r32) * 144 + (16 * ks + 8 * hi) * 2);
;           pv_one<0>(Sa, vbV + vblk0 * 512, kh[0], kh[1], kh[2], kh[3]);
;           pv_one<0>(Sb, vbV + (vblk0 + 1) * 512, kh[0], kh[1], kh[2], kh[3]); }
;       }
;       const bool post = prog && (c & 3) == 0 && c > 0 && c <= 16;
;       if (post) asm volatile("s_waitcnt vmcnt(0)" ::: "memory");
;       __syncthreads();
;       if (post && tid == 0) { __builtin_amdgcn_fence(__ATOMIC_RELEASE, "agent"); asm volatile("s_waitcnt vmcnt(0)" ::: "memory"); (void)xb_add(prog + b * 8 + (c >> 2) - 1, 1u); }
; #pragma unroll
;       for (int r = 0; r < 16; ++r) { const int d = 32 * dblk + crow(r, hi);
;         *(bf16*)(lds + HG_S + (d >> 6) * 16384 + v_st(d & 63, 32 * vblk0 + r32)) = (bf16)f2bf(Sa[r]);
;         *(bf16*)(lds + HG_S + (d >> 6) * 16384 + v_st(d & 63, 32 * (vblk0 + 1) + r32)) = (bf16)f2bf(Sb[r]); }
;       { const int t = tid >> 3, seg = tid & 7; const size_t row = row0 + (size_t)c * 64 + t;
;         const v4u oa = *(const v4u*)(lds + HG_O + t * 272 + seg * 32), ob = *(const v4u*)(lds + HG_O + t * 272 + seg * 32 + 16);
;         const unsigned ow[8] = {oa.x, oa.y, oa.z, oa.w, ob.x, ob.y, ob.z, ob.w}, gw[8] = {ga.x, ga.y, ga.z, ga.w, gb.x, gb.y, gb.z, gb.w};
;         float ss = 0.f;
; #pragma unroll
;         for (int i = 0; i < 8; ++i) { const float a = bflo(ow[i]), bq = bfhi(ow[i]); ss += a * a + bq * bq; }
;         ss += __shfl_xor(ss, 1); ss += __shfl_xor(ss, 2); ss += __shfl_xor(ss, 4);
	v_mfma_f32_32x32x16_bf16 v[2:17], v[70:73], v[38:41], v[2:17]
	ds_write_b16_d16_hi v175, v34
	v_bfe_u32 v34, v20, 16, 1
	ds_write_b16_d16_hi v175, v35 offset:64
	v_add3_u32 v34, v20, v34, s61
	v_bfe_u32 v36, v21, 16, 1
	v_bfe_u32 v37, v22, 16, 1
	v_add3_u32 v36, v21, v36, s61
	v_mfma_f32_32x32x16_bf16 v[2:17], v[74:77], v[42:45], v[2:17]
	v_add3_u32 v37, v22, v37, s61
	s_waitcnt vmcnt(1)
	v_lshlrev_b32_e32 v72, 16, v63
	v_mul_f32_e32 v73, 0xbfb8aa3b, v72
	v_exp_f32_e32 v74, v73
	v_lshlrev_b32_e32 v76, 16, v62
	s_waitcnt vmcnt(0)
	v_lshlrev_b32_e32 v82, 16, v61
	v_mul_f32_e32 v83, 0xbfb8aa3b, v82
	v_mfma_f32_32x32x16_bf16 v[2:17], v[78:81], v[46:49], v[2:17]
	v_exp_f32_e32 v84, v83
	v_and_b32_e32 v62, 0xffff0000, v62
	v_lshlrev_b32_e32 v86, 16, v60
	v_and_b32_e32 v60, 0xffff0000, v60
	v_and_b32_e32 v94, 0xffff0000, v58
	s_brev_b32 s50, 44
	s_add_i32 s93, s93, -1
	s_nop 4
	v_bfe_u32 v35, v2, 16, 1
	v_bfe_u32 v38, v3, 16, 1
	v_bfe_u32 v39, v4, 16, 1
	v_bfe_u32 v40, v5, 16, 1
	v_bfe_u32 v41, v6, 16, 1
	v_add3_u32 v35, v2, v35, s61
	v_add3_u32 v38, v3, v38, s61
	v_add3_u32 v39, v4, v39, s61
	v_add3_u32 v40, v5, v40, s61
	ds_write_b16_d16_hi v176, v35
	ds_write_b16_d16_hi v176, v38 offset:64
	ds_write_b16_d16_hi v177, v34 offset:128
	ds_write_b16_d16_hi v178, v39 offset:128
	ds_write_b16_d16_hi v179, v36 offset:192
	ds_write_b16_d16_hi v180, v40 offset:192
	ds_write_b16_d16_hi v181, v37
	v_add3_u32 v34, v6, v41, s61
	ds_write_b16_d16_hi v182, v34
	v_bfe_u32 v34, v23, 16, 1
	v_add3_u32 v34, v23, v34, s61
	ds_write_b16_d16_hi v183, v34 offset:64
	v_bfe_u32 v34, v7, 16, 1
	v_add3_u32 v34, v7, v34, s61
	ds_write_b16_d16_hi v184, v34 offset:64
	v_bfe_u32 v34, v24, 16, 1
	v_add3_u32 v34, v24, v34, s61
	ds_write_b16_d16_hi v185, v34 offset:128
	v_bfe_u32 v34, v8, 16, 1
	v_add3_u32 v34, v8, v34, s61
	ds_write_b16_d16_hi v186, v34 offset:128
	v_bfe_u32 v34, v25, 16, 1
	v_add3_u32 v34, v25, v34, s61
	ds_write_b16_d16_hi v187, v34 offset:192
	v_bfe_u32 v34, v9, 16, 1
	v_add3_u32 v34, v9, v34, s61
	ds_write_b16_d16_hi v188, v34 offset:192
	v_bfe_u32 v34, v26, 16, 1
	v_add3_u32 v34, v26, v34, s61
	ds_write_b16_d16_hi v189, v34
	v_bfe_u32 v34, v10, 16, 1
	v_add3_u32 v34, v10, v34, s61
	ds_write_b16_d16_hi v190, v34
	v_bfe_u32 v34, v27, 16, 1
	v_add3_u32 v34, v27, v34, s61
	ds_write_b16_d16_hi v191, v34 offset:64
	v_bfe_u32 v34, v11, 16, 1
	v_add3_u32 v34, v11, v34, s61
	ds_write_b16_d16_hi v192, v34 offset:64
	v_bfe_u32 v34, v28, 16, 1
	v_add3_u32 v34, v28, v34, s61
	ds_write_b16_d16_hi v193, v34 offset:128
	v_bfe_u32 v34, v12, 16, 1
	v_add3_u32 v34, v12, v34, s61
	ds_write_b16_d16_hi v194, v34 offset:128
	v_bfe_u32 v34, v29, 16, 1
	v_add3_u32 v34, v29, v34, s61
	ds_write_b16_d16_hi v195, v34 offset:192
	v_bfe_u32 v34, v13, 16, 1
	v_add3_u32 v34, v13, v34, s61
	ds_write_b16_d16_hi v196, v34 offset:192
	v_bfe_u32 v34, v30, 16, 1
	v_add3_u32 v34, v30, v34, s61
	ds_write_b16_d16_hi v197, v34
	v_bfe_u32 v34, v14, 16, 1
	v_add3_u32 v34, v14, v34, s61
	ds_write_b16_d16_hi v198, v34
	v_bfe_u32 v34, v31, 16, 1
	v_add3_u32 v34, v31, v34, s61
	ds_write_b16_d16_hi v199, v34 offset:64
	v_bfe_u32 v34, v15, 16, 1
	v_add3_u32 v34, v15, v34, s61
	ds_write_b16_d16_hi v200, v34 offset:64
	v_bfe_u32 v34, v32, 16, 1
	v_add3_u32 v34, v32, v34, s61
	ds_write_b16_d16_hi v201, v34 offset:128
	v_bfe_u32 v34, v16, 16, 1
	v_add3_u32 v34, v16, v34, s61
	ds_write_b16_d16_hi v202, v34 offset:128
	v_bfe_u32 v34, v33, 16, 1
	v_add3_u32 v34, v33, v34, s61
	ds_write_b16_d16_hi v203, v34 offset:192
	v_bfe_u32 v34, v17, 16, 1
	v_add3_u32 v34, v17, v34, s61
	v_and_b32_e32 v35, 64, v117
	ds_write_b16_d16_hi v204, v34 offset:192
	v_xor_b32_e32 v34, 1, v117
	v_add_u32_e32 v35, 64, v35
	v_cmp_lt_i32_e32 vcc, v34, v35
	v_lshlrev_b32_e32 v40, 16, v64
	v_mul_f32_e32 v38, 0xbfb8aa3b, v40
	v_cndmask_b32_e32 v34, v117, v34, vcc
	v_lshlrev_b32_e32 v37, 2, v34
	v_xor_b32_e32 v34, 2, v117
	v_cmp_lt_i32_e32 vcc, v34, v35
	ds_read_b128 v[46:49], v205 offset:16
	v_exp_f32_e32 v42, v38
	v_cndmask_b32_e32 v34, v117, v34, vcc
	v_lshlrev_b32_e32 v45, 2, v34
	v_xor_b32_e32 v34, 4, v117
	v_cmp_lt_i32_e32 vcc, v34, v35
	v_add_f32_e32 v42, 1.0, v42
	s_waitcnt lgkmcnt(0)
	v_and_b32_e32 v39, 0xffff0000, v49
	v_cndmask_b32_e32 v34, v117, v34, vcc
	v_lshlrev_b32_e32 v79, 2, v34
	v_lshlrev_b32_e32 v34, 16, v65
	v_mul_f32_e32 v35, 0xbfb8aa3b, v34
	v_rcp_f32_e32 v44, v42
	v_and_b32_e32 v43, 0xffff0000, v48
	v_and_b32_e32 v42, 0xffff0000, v64
	v_exp_f32_e32 v36, v35
	v_lshlrev_b32_e32 v35, 16, v49
	v_and_b32_e32 v38, 0xffff0000, v65
	v_lshlrev_b32_e32 v41, 16, v48
	v_mul_f32_e32 v48, 0xbfb8aa3b, v42
	v_mov_b32_e32 v64, v39
	v_mov_b32_e32 v65, v43
	v_lshlrev_b32_e32 v73, 16, v47
	v_and_b32_e32 v75, 0xffff0000, v47
	v_mul_f32_e32 v47, 0xbfb8aa3b, v76
	v_exp_f32_e32 v208, v48
	v_mov_b32_e32 v48, v35
	v_mov_b32_e32 v49, v41
	v_pk_mul_f32 v[64:65], v[64:65], v[64:65]
	v_exp_f32_e32 v47, v47
	v_pk_fma_f32 v[48:49], v[48:49], v[48:49], v[64:65]
	v_add_f32_e32 v64, 1.0, v74
	v_and_b32_e32 v74, 0xffff0000, v63
	v_mul_f32_e32 v63, 0xbfb8aa3b, v74
	v_exp_f32_e32 v65, v63
	v_and_b32_e32 v63, 0xffff0000, v46
	v_lshlrev_b32_e32 v77, 16, v46
	v_add_f32_e32 v47, 1.0, v47
	v_mul_f32_e32 v46, 0xbfb8aa3b, v62
	v_mov_b32_e32 v80, v75
	v_mov_b32_e32 v81, v63
	v_rcp_f32_e32 v78, v47
	v_exp_f32_e32 v209, v46
	v_mov_b32_e32 v46, v73
	v_mov_b32_e32 v47, v77
	v_pk_mul_f32 v[80:81], v[80:81], v[80:81]
	ds_read_b128 v[66:69], v205
	ds_read_b64 v[70:71], v144
	v_pk_fma_f32 v[46:47], v[46:47], v[46:47], v[80:81]
	v_add_f32_e32 v80, 1.0, v84
	v_and_b32_e32 v84, 0xffff0000, v61
	v_mul_f32_e32 v61, 0xbfb8aa3b, v86
	v_exp_f32_e32 v61, v61
	s_waitcnt lgkmcnt(1)
; __device__ __forceinline__ float bflo(unsigned w) { return __uint_as_float(w << 16); }
; __device__ __forceinline__ float bfhi(unsigned w) { return __uint_as_float(w & 0xffff0000u); }
; __device__ __forceinline__ float siluf_(float x) { return x * __builtin_amdgcn_rcpf(1.0f + __expf(-x)); }
; __device__ __forceinline__ unsigned cvtpk(float lo, float hi) { unsigned r; asm volatile("v_cvt_pk_bf16_f32 %0, %1, %2" : "=v"(r) : "v"(lo), "v"(hi)); return r; }
; __device__ __forceinline__ void hg_mfma(Frame& F, bf16* Y, int u, unsigned* prog = nullptr) {
;     ...
;       { const int t = tid >> 3, seg = tid & 7; const size_t row = row0 + (size_t)c * 64 + t;
;         const v4u oa = *(const v4u*)(lds + HG_O + t * 272 + seg * 32), ob = *(const v4u*)(lds + HG_O + t * 272 + seg * 32 + 16);
;         const unsigned ow[8] = {oa.x, oa.y, oa.z, oa.w, ob.x, ob.y, ob.z, ob.w}, gw[8] = {ga.x, ga.y, ga.z, ga.w, gb.x, gb.y, gb.z, gb.w};
;         float ss = 0.f;
; #pragma unroll
;         for (int i = 0; i < 8; ++i) { const float a = bflo(ow[i]), bq = bfhi(ow[i]); ss += a * a + bq * bq; }
;         ss += __shfl_xor(ss, 1); ss += __shfl_xor(ss, 2); ss += __shfl_xor(ss, 4);
;         const float rstd = rsqrtf(ss * (1.f / 128.f) + NORM_EPS);
;         unsigned yw[8]; const float* gnl = (const float*)(lds + HG_GN) + seg * 16;
; #pragma unroll
;         for (int i = 0; i < 8; ++i) { const v2f g2 = *(const v2f*)(gnl + 2 * i); const float gx = g2.x, gy = g2.y;
;           yw[i] = at::cvtpk(bflo(ow[i]) * rstd * gx * siluf_(bflo(gw[i])), bfhi(ow[i]) * rstd * gy * siluf_(bfhi(gw[i]))); }
;         v4u y0, y1; y0.x = yw[0]; y0.y = yw[1]; y0.z = yw[2]; y0.w = yw[3]; y1.x = yw[4]; y1.y = yw[5]; y1.z = yw[6]; y1.w = yw[7];
;         *(v4u*)(Y + row * DM + hd * 128 + seg * 16) = y0; *(v4u*)(Y + row * DM + hd * 128 + seg * 16 + 8) = y1; }
	v_and_b32_e32 v85, 0xffff0000, v69
	v_lshlrev_b32_e32 v83, 16, v69
	v_mul_f32_e32 v69, 0xbfb8aa3b, v84
	v_add_f32_e32 v61, 1.0, v61
	v_rcp_f32_e32 v88, v61
	v_and_b32_e32 v61, 0xffff0000, v68
	v_lshlrev_b32_e32 v87, 16, v68
	v_mul_f32_e32 v68, 0xbfb8aa3b, v60
	v_mov_b32_e32 v90, v85
	v_mov_b32_e32 v91, v61
	v_exp_f32_e32 v81, v69
	v_exp_f32_e32 v89, v68
	v_mov_b32_e32 v68, v83
	v_mov_b32_e32 v69, v87
	v_pk_mul_f32 v[90:91], v[90:91], v[90:91]
	v_and_b32_e32 v95, 0xffff0000, v66
	v_pk_fma_f32 v[68:69], v[68:69], v[68:69], v[90:91]
	v_lshlrev_b32_e32 v91, 16, v67
	v_and_b32_e32 v67, 0xffff0000, v67
	v_lshlrev_b32_e32 v93, 16, v66
	v_mov_b32_e32 v206, v95
	v_mov_b32_e32 v207, v67
	v_mov_b32_e32 v96, v93
	v_mov_b32_e32 v97, v91
	v_pk_mul_f32 v[206:207], v[206:207], v[206:207]
	v_lshlrev_b32_e32 v90, 16, v59
	v_pk_fma_f32 v[96:97], v[96:97], v[96:97], v[206:207]
	v_mul_f32_e32 v92, 0xbfb8aa3b, v90
	v_add_f32_e32 v66, v96, v97
	v_add_f32_e32 v66, v69, v66
	v_add_f32_e32 v66, v68, v66
	v_add_f32_e32 v47, v47, v66
	v_add_f32_e32 v46, v46, v47
	v_add_f32_e32 v46, v49, v46
	v_add_f32_e32 v46, v48, v46
	ds_bpermute_b32 v37, v37, v46
	v_exp_f32_e32 v92, v92
	v_and_b32_e32 v66, 0xffff0000, v59
	v_rcp_f32_e32 v80, v80
	v_rcp_f32_e32 v64, v64
	s_waitcnt lgkmcnt(0)
	v_add_f32_e32 v37, v46, v37
	ds_bpermute_b32 v45, v45, v37
	v_add_f32_e32 v47, 1.0, v92
	v_rcp_f32_e32 v48, v47
	v_mul_f32_e32 v47, 0xbfb8aa3b, v66
	v_lshlrev_b32_e32 v92, 16, v58
	s_waitcnt lgkmcnt(0)
	v_add_f32_e32 v37, v37, v45
	ds_bpermute_b32 v45, v79, v37
	v_mul_f32_e32 v46, 0xbfb8aa3b, v92
	v_exp_f32_e32 v49, v47
	v_mul_f32_e32 v47, 0xbfb8aa3b, v94
	v_exp_f32_e32 v46, v46
	s_waitcnt lgkmcnt(0)
	v_add_f32_e32 v37, v37, v45
	v_mov_b32_e32 v45, 0x358637bd
	v_fmamk_f32 v37, v37, 0x3c000000, v45
	v_exp_f32_e32 v47, v47
	v_mul_f32_e32 v45, 0x4b800000, v37
	v_cmp_gt_f32_e32 vcc, s58, v37
	v_add_f32_e32 v46, 1.0, v46
	v_rcp_f32_e32 v68, v46
	v_cndmask_b32_e32 v37, v37, v45, vcc
	v_rsq_f32_e32 v37, v37
	v_add_f32_e32 v45, 1.0, v47
	v_rcp_f32_e32 v46, v45
	v_add_f32_e32 v36, 1.0, v36
	v_mul_f32_e32 v45, 0x45800000, v37
	v_cndmask_b32_e32 v69, v37, v45, vcc
	v_mov_b32_e32 v47, v69
	v_pk_mul_f32 v[58:59], v[68:69], v[92:93]
	v_pk_mul_f32 v[46:47], v[46:47], v[94:95]
	v_mul_f32_e32 v37, v70, v59
	v_mul_f32_e32 v45, v71, v47
	v_mul_f32_e32 v37, v58, v37
	v_mul_f32_e32 v45, v46, v45
	v_cvt_pk_bf16_f32 v46, v37, v45
	ds_read_b64 v[58:59], v144 offset:8
	v_add_f32_e32 v37, 1.0, v49
	v_rcp_f32_e32 v70, v37
	v_mov_b32_e32 v49, v69
	v_pk_mul_f32 v[48:49], v[48:49], v[90:91]
	v_mov_b32_e32 v71, v69
	s_waitcnt lgkmcnt(0)
	v_mul_f32_e32 v37, v58, v49
	v_mul_f32_e32 v37, v48, v37
	v_pk_mul_f32 v[48:49], v[70:71], v[66:67]
	v_mov_b32_e32 v79, v69
	v_mul_f32_e32 v45, v59, v49
	v_mul_f32_e32 v45, v48, v45
	v_cvt_pk_bf16_f32 v47, v37, v45
	ds_read_b64 v[48:49], v144 offset:16
	v_add_f32_e32 v37, 1.0, v89
	v_rcp_f32_e32 v58, v37
	v_mov_b32_e32 v89, v69
	v_pk_mul_f32 v[66:67], v[88:89], v[86:87]
	v_mov_b32_e32 v59, v69
	s_waitcnt lgkmcnt(0)
	v_mul_f32_e32 v37, v48, v67
	v_pk_mul_f32 v[58:59], v[58:59], v[60:61]
	v_mul_f32_e32 v37, v66, v37
	v_mul_f32_e32 v45, v49, v59
	v_mul_f32_e32 v45, v58, v45
	v_cvt_pk_bf16_f32 v48, v37, v45
	ds_read_b64 v[58:59], v144 offset:24
	v_add_f32_e32 v37, 1.0, v81
	v_rcp_f32_e32 v60, v37
	v_mov_b32_e32 v81, v69
	v_pk_mul_f32 v[66:67], v[80:81], v[82:83]
	v_mov_b32_e32 v61, v69
	s_waitcnt lgkmcnt(0)
	v_mul_f32_e32 v37, v58, v67
	v_pk_mul_f32 v[60:61], v[60:61], v[84:85]
	v_mul_f32_e32 v37, v66, v37
	v_mul_f32_e32 v45, v59, v61
	v_mul_f32_e32 v45, v60, v45
	v_cvt_pk_bf16_f32 v49, v37, v45
	ds_read_b64 v[58:59], v144 offset:32
	v_add_f32_e32 v37, 1.0, v209
	v_rcp_f32_e32 v60, v37
	v_pk_mul_f32 v[66:67], v[78:79], v[76:77]
	v_mov_b32_e32 v61, v69
	s_waitcnt lgkmcnt(0)
	v_mul_f32_e32 v37, v58, v67
	v_pk_mul_f32 v[60:61], v[60:61], v[62:63]
	v_mul_f32_e32 v37, v66, v37
	v_mul_f32_e32 v45, v59, v61
	v_mul_f32_e32 v45, v60, v45
	v_cvt_pk_bf16_f32 v58, v37, v45
	v_add_f32_e32 v37, 1.0, v65
	ds_read_b64 v[60:61], v144 offset:40
	v_rcp_f32_e32 v62, v37
	v_mov_b32_e32 v65, v69
	v_mov_b32_e32 v63, v69
	v_pk_mul_f32 v[64:65], v[64:65], v[72:73]
	v_pk_mul_f32 v[62:63], v[62:63], v[74:75]
	s_waitcnt lgkmcnt(0)
	v_mul_f32_e32 v37, v60, v65
	v_mul_f32_e32 v45, v61, v63
	v_mul_f32_e32 v37, v64, v37
	v_mul_f32_e32 v45, v62, v45
	v_cvt_pk_bf16_f32 v59, v37, v45
	ds_read_b64 v[60:61], v144 offset:48
	v_add_f32_e32 v37, 1.0, v208
	v_rcp_f32_e32 v62, v37
	v_mov_b32_e32 v45, v69
	v_pk_mul_f32 v[40:41], v[44:45], v[40:41]
	v_mov_b32_e32 v63, v69
	s_waitcnt lgkmcnt(0)
	v_mul_f32_e32 v37, v60, v41
	v_mul_f32_e32 v37, v40, v37
	v_pk_mul_f32 v[40:41], v[62:63], v[42:43]
	v_rcp_f32_e32 v36, v36
	v_mul_f32_e32 v41, v61, v41
	v_mul_f32_e32 v40, v40, v41
	v_mul_f32_e32 v41, 0xbfb8aa3b, v38
	v_exp_f32_e32 v42, v41
	v_cvt_pk_bf16_f32 v60, v37, v40
	ds_read_b64 v[40:41], v144 offset:56
	v_mov_b32_e32 v37, v69
	v_add_f32_e32 v42, 1.0, v42
	v_rcp_f32_e32 v68, v42
	v_pk_mul_f32 v[34:35], v[36:37], v[34:35]
	v_lshl_add_u64 v[110:111], v[110:111], 0, s[72:73]
	s_waitcnt lgkmcnt(0)
	v_mul_f32_e32 v35, v40, v35
	v_mul_f32_e32 v36, v34, v35
	v_pk_mul_f32 v[34:35], v[68:69], v[38:39]
	v_lshl_add_u64 v[112:113], v[112:113], 0, s[72:73]
	v_mul_f32_e32 v35, v41, v35
	v_mul_f32_e32 v34, v34, v35
	v_cvt_pk_bf16_f32 v61, v36, v34
	v_lshl_add_u64 v[34:35], v[108:109], 0, s[62:63]
	v_add_co_u32_e32 v34, vcc, s50, v34
	s_mov_b64 s[50:51], 0x80000
	s_nop 0
	v_addc_co_u32_e32 v35, vcc, 0, v35, vcc
	v_lshl_add_u64 v[108:109], v[108:109], 0, s[50:51]
	s_cmp_lg_u32 s93, 0
	v_lshl_add_u64 v[114:115], v[114:115], 0, s[72:73]
	global_store_dwordx4 v[34:35], v[46:49], off sc1
	global_store_dwordx4 v[34:35], v[58:61], off offset:16 sc1
	s_cbranch_scc0 .LBB0_1567

; __device__ __forceinline__ unsigned pk2(float lo, float hi) { unsigned r; asm volatile("v_cvt_pk_bf16_f32 %0, %1, %2" : "=v"(r) : "v"(lo), "v"(hi)); return r; }
; __device__ __forceinline__ void p0_transpose_item(const float* W, int K, int N, bf16* WT, int kb, int src_col0, int dst_row0, float* scr, int lane, const float* kgain = nullptr) {
;     ...
;     for (int j = 0; j < 4; ++j) { const int n = (lane >> 3) + 8 * j; const float* s = scr + (8 * c) * 33 + n;
;         v4u o;
;         if (src_col0 >= 0) { o.x = pk2(s[0 * 33] * g0.x, s[1 * 33] * g0.y); o.y = pk2(s[2 * 33] * g0.z, s[3 * 33] * g0.w); o.z = pk2(s[4 * 33] * g1.x, s[5 * 33] * g1.y); o.w = pk2(s[6 * 33] * g1.z, s[7 * 33] * g1.w); }
;         else { o.x = 0u; o.y = 0u; o.z = 0u; o.w = 0u; }
;         *(v4u*)(WT + (size_t)(dst_row0 + n) * K + k0 + 8 * c) = o; }
.LBB0_1585:
	v_add_u32_e32 v14, 24, v6
	v_ashrrev_i32_e32 v15, 31, v14
	v_lshlrev_b64 v[14:15], 13, v[14:15]
	v_lshl_add_u64 v[12:13], v[12:13], 0, v[14:15]
	global_store_dwordx4 v[12:13], v[2:5], off sc1
	s_waitcnt lgkmcnt(0)
	s_add_i32 s10, s10, s76
	s_add_i32 s11, s11, s12
	s_cmpk_lt_i32 s10, 0x2000
	s_cbranch_scc0 .LBB0_1596

; __device__ __forceinline__ unsigned pk2(float lo, float hi) { unsigned r; asm volatile("v_cvt_pk_bf16_f32 %0, %1, %2" : "=v"(r) : "v"(lo), "v"(hi)); return r; }
; __device__ __forceinline__ void p0_transpose_item(const float* W, int K, int N, bf16* WT, int kb, int src_col0, int dst_row0, float* scr, int lane, const float* kgain = nullptr) {
;     ...
;     for (int j = 0; j < 4; ++j) { const int n = (lane >> 3) + 8 * j; const float* s = scr + (8 * c) * 33 + n;
;         v4u o;
;         if (src_col0 >= 0) { o.x = pk2(s[0 * 33] * g0.x, s[1 * 33] * g0.y); o.y = pk2(s[2 * 33] * g0.z, s[3 * 33] * g0.w); o.z = pk2(s[4 * 33] * g1.x, s[5 * 33] * g1.y); o.w = pk2(s[6 * 33] * g1.z, s[7 * 33] * g1.w); }
;         else { o.x = 0u; o.y = 0u; o.z = 0u; o.w = 0u; }
;         *(v4u*)(WT + (size_t)(dst_row0 + n) * K + k0 + 8 * c) = o; }
.LBB0_1588:
	s_waitcnt lgkmcnt(0)
	s_ashr_i32 s5, s4, 31
	v_lshl_add_u64 v[12:13], s[4:5], 1, v[10:11]
	s_mov_b64 s[4:5], -1
	s_and_b64 vcc, exec, s[2:3]
	s_cbranch_vccz .LBB0_1590
	s_add_i32 s0, s13, s11
	v_add_u32_e32 v2, s0, v18
	v_ashrrev_i32_e32 v3, 31, v2
	v_lshlrev_b64 v[4:5], 13, v[2:3]
	v_lshl_add_u64 v[4:5], v[12:13], 0, v[4:5]
	global_store_dwordx4 v[4:5], v[32:35], off sc1
	s_mov_b64 s[4:5], 0
	v_mov_b32_e32 v6, v2
.LBB0_1590:
	v_mov_b32_e32 v2, 0
	s_andn2_b64 vcc, exec, s[4:5]
	v_mov_b32_e32 v3, 0
	v_mov_b32_e32 v4, 0
	v_mov_b32_e32 v5, 0
	s_cbranch_vccnz .LBB0_1592
	ds_read2_b32 v[2:3], v19 offset1:33
	s_add_i32 s13, s13, s11
	s_waitcnt lgkmcnt(0)
	v_cvt_pk_bf16_f32 v2, v2, v3
	ds_read2_b32 v[4:5], v19 offset0:66 offset1:99
	v_add_u32_e32 v6, s13, v18
	s_waitcnt lgkmcnt(0)
	v_cvt_pk_bf16_f32 v3, v4, v5
	ds_read2_b32 v[4:5], v19 offset0:132 offset1:165
	v_lshlrev_b64 v[28:29], 13, v[6:7]
	s_waitcnt lgkmcnt(0)
	v_cvt_pk_bf16_f32 v4, v4, v5
	ds_read2_b32 v[14:15], v19 offset0:198 offset1:231
	s_waitcnt lgkmcnt(0)
	v_cvt_pk_bf16_f32 v5, v14, v15
	v_lshl_add_u64 v[28:29], v[12:13], 0, v[28:29]
	ds_read2_b32 v[14:15], v19 offset0:8 offset1:41
	global_store_dwordx4 v[28:29], v[2:5], off sc1
	s_waitcnt lgkmcnt(0)
	s_nop 0
	v_cvt_pk_bf16_f32 v2, v14, v15
	ds_read2_b32 v[4:5], v19 offset0:74 offset1:107
	s_waitcnt lgkmcnt(0)
	v_cvt_pk_bf16_f32 v3, v4, v5
	ds_read2_b32 v[4:5], v19 offset0:140 offset1:173
	s_waitcnt lgkmcnt(0)
	v_cvt_pk_bf16_f32 v4, v4, v5
	ds_read2_b32 v[14:15], v19 offset0:206 offset1:239
	s_waitcnt lgkmcnt(0)
	v_cvt_pk_bf16_f32 v5, v14, v15
.LBB0_1592:
	v_add_u32_e32 v14, 8, v6
	v_ashrrev_i32_e32 v15, 31, v14
	v_lshlrev_b64 v[14:15], 13, v[14:15]
	v_lshl_add_u64 v[14:15], v[12:13], 0, v[14:15]
	global_store_dwordx4 v[14:15], v[2:5], off sc1
	s_mov_b64 s[4:5], -1
	s_and_b64 vcc, exec, s[2:3]
	v_add_u32_e32 v14, 16, v6
	s_cbranch_vccz .LBB0_1594
	v_ashrrev_i32_e32 v15, 31, v14
	v_lshlrev_b64 v[2:3], 13, v[14:15]
	v_lshl_add_u64 v[2:3], v[12:13], 0, v[2:3]
	global_store_dwordx4 v[2:3], v[32:35], off sc1
	s_mov_b64 s[4:5], 0
.LBB0_1594:
	v_mov_b32_e32 v2, 0
	s_andn2_b64 vcc, exec, s[4:5]
	v_mov_b32_e32 v3, 0
	v_mov_b32_e32 v4, 0
	v_mov_b32_e32 v5, 0
	s_cbranch_vccnz .LBB0_1585
	ds_read2_b32 v[2:3], v19 offset0:16 offset1:49
	s_waitcnt lgkmcnt(0)
	v_cvt_pk_bf16_f32 v2, v2, v3
	ds_read2_b32 v[4:5], v19 offset0:82 offset1:115
	v_mov_b32_e32 v15, v7
	s_waitcnt lgkmcnt(0)
	v_cvt_pk_bf16_f32 v3, v4, v5
	ds_read2_b32 v[4:5], v19 offset0:148 offset1:181
	v_lshlrev_b64 v[14:15], 13, v[14:15]
	s_waitcnt lgkmcnt(0)
	v_cvt_pk_bf16_f32 v4, v4, v5
	ds_read2_b32 v[28:29], v19 offset0:214 offset1:247
	s_waitcnt lgkmcnt(0)
	v_cvt_pk_bf16_f32 v5, v28, v29
	v_lshl_add_u64 v[14:15], v[12:13], 0, v[14:15]
	ds_read2_b32 v[28:29], v19 offset0:24 offset1:57
	global_store_dwordx4 v[14:15], v[2:5], off sc1
	s_waitcnt lgkmcnt(0)
	s_nop 0
	v_cvt_pk_bf16_f32 v2, v28, v29
	ds_read2_b32 v[4:5], v19 offset0:90 offset1:123
	s_waitcnt lgkmcnt(0)
	v_cvt_pk_bf16_f32 v3, v4, v5
	ds_read2_b32 v[4:5], v19 offset0:156 offset1:189
	s_waitcnt lgkmcnt(0)
	v_cvt_pk_bf16_f32 v4, v4, v5
	ds_read2_b32 v[14:15], v19 offset0:222 offset1:255
	s_waitcnt lgkmcnt(0)
	v_cvt_pk_bf16_f32 v5, v14, v15
	s_branch .LBB0_1585

; __device__ __forceinline__ unsigned pk2(float lo, float hi) { unsigned r; asm volatile("v_cvt_pk_bf16_f32 %0, %1, %2" : "=v"(r) : "v"(lo), "v"(hi)); return r; }
; __device__ __forceinline__ void p0_transpose_item(const float* W, int K, int N, bf16* WT, int kb, int src_col0, int dst_row0, float* scr, int lane, const float* kgain = nullptr) {
;     ...
;     for (int j = 0; j < 4; ++j) { const int n = (lane >> 3) + 8 * j; const float* s = scr + (8 * c) * 33 + n;
;         v4u o;
;         if (src_col0 >= 0) { o.x = pk2(s[0 * 33] * g0.x, s[1 * 33] * g0.y); o.y = pk2(s[2 * 33] * g0.z, s[3 * 33] * g0.w); o.z = pk2(s[4 * 33] * g1.x, s[5 * 33] * g1.y); o.w = pk2(s[6 * 33] * g1.z, s[7 * 33] * g1.w); }
;         else { o.x = 0u; o.y = 0u; o.z = 0u; o.w = 0u; }
;         *(v4u*)(WT + (size_t)(dst_row0 + n) * K + k0 + 8 * c) = o; }
.LBB0_1598:
	v_add_u32_e32 v6, 24, v26
	v_ashrrev_i32_e32 v7, 31, v6
	v_lshlrev_b64 v[6:7], 13, v[6:7]
	v_lshl_add_u64 v[6:7], v[24:25], 0, v[6:7]
	global_store_dwordx4 v[6:7], v[14:17], off sc1
	s_waitcnt lgkmcnt(0)
	s_add_i32 s10, s10, s76
	s_add_i32 s11, s11, s12
	s_cmpk_lt_i32 s10, 0x5a00
	s_cbranch_scc0 .LBB0_1615

; __device__ __forceinline__ unsigned pk2(float lo, float hi) { unsigned r; asm volatile("v_cvt_pk_bf16_f32 %0, %1, %2" : "=v"(r) : "v"(lo), "v"(hi)); return r; }
; __device__ __forceinline__ void p0_transpose_item(const float* W, int K, int N, bf16* WT, int kb, int src_col0, int dst_row0, float* scr, int lane, const float* kgain = nullptr) {
;     ...
;     for (int j = 0; j < 4; ++j) { const int n = (lane >> 3) + 8 * j; const float* s = scr + (8 * c) * 33 + n;
;         v4u o;
;         if (src_col0 >= 0) { o.x = pk2(s[0 * 33] * g0.x, s[1 * 33] * g0.y); o.y = pk2(s[2 * 33] * g0.z, s[3 * 33] * g0.w); o.z = pk2(s[4 * 33] * g1.x, s[5 * 33] * g1.y); o.w = pk2(s[6 * 33] * g1.z, s[7 * 33] * g1.w); }
;         else { o.x = 0u; o.y = 0u; o.z = 0u; o.w = 0u; }
;         *(v4u*)(WT + (size_t)(dst_row0 + n) * K + k0 + 8 * c) = o; }
.LBB0_1607:
	s_waitcnt lgkmcnt(0)
	v_lshl_add_u64 v[24:25], s[4:5], 1, v[22:23]
	s_mov_b64 s[4:5], -1
	s_and_b64 vcc, exec, s[2:3]
	s_cbranch_vccz .LBB0_1609
	s_add_i32 s0, s11, s14
	v_add_u32_e32 v26, s0, v33
	v_ashrrev_i32_e32 v27, 31, v26
	v_lshlrev_b64 v[14:15], 13, v[26:27]
	v_lshl_add_u64 v[14:15], v[24:25], 0, v[14:15]
	global_store_dwordx4 v[14:15], v[2:5], off sc1
	s_mov_b64 s[4:5], 0
.LBB0_1609:
	v_mov_b32_e32 v14, 0
	s_andn2_b64 vcc, exec, s[4:5]
	v_mov_b32_e32 v15, 0
	v_mov_b32_e32 v16, 0
	v_mov_b32_e32 v17, 0
	s_cbranch_vccnz .LBB0_1611
	ds_read2_b32 v[14:15], v34 offset1:33
	s_add_i32 s0, s11, s14
	v_add_u32_e32 v26, s0, v33
	s_waitcnt lgkmcnt(0)
	v_mul_f32_e32 v14, v10, v14
	v_mul_f32_e32 v15, v11, v15
	v_cvt_pk_bf16_f32 v14, v14, v15
	ds_read2_b32 v[16:17], v34 offset0:66 offset1:99
	s_waitcnt lgkmcnt(0)
	v_mul_f32_e32 v15, v12, v16
	v_mul_f32_e32 v16, v13, v17
	v_cvt_pk_bf16_f32 v15, v15, v16
	ds_read2_b32 v[16:17], v34 offset0:132 offset1:165
	s_waitcnt lgkmcnt(0)
	v_mul_f32_e32 v16, v6, v16
	v_mul_f32_e32 v17, v7, v17
	v_cvt_pk_bf16_f32 v16, v16, v17
	ds_read2_b32 v[28:29], v34 offset0:198 offset1:231
	s_waitcnt lgkmcnt(0)
	v_mul_f32_e32 v17, v8, v28
	v_mul_f32_e32 v27, v9, v29
	v_cvt_pk_bf16_f32 v17, v17, v27
	ds_read2_b32 v[28:29], v34 offset0:8 offset1:41
	v_ashrrev_i32_e32 v27, 31, v26
	v_lshlrev_b64 v[42:43], 13, v[26:27]
	v_lshl_add_u64 v[42:43], v[24:25], 0, v[42:43]
	global_store_dwordx4 v[42:43], v[14:17], off sc1
	s_waitcnt lgkmcnt(0)
	s_nop 0
	v_mul_f32_e32 v14, v10, v28
	v_mul_f32_e32 v15, v11, v29
	v_cvt_pk_bf16_f32 v14, v14, v15
	ds_read2_b32 v[16:17], v34 offset0:74 offset1:107
	s_waitcnt lgkmcnt(0)
	v_mul_f32_e32 v15, v12, v16
	v_mul_f32_e32 v16, v13, v17
	v_cvt_pk_bf16_f32 v15, v15, v16
	ds_read2_b32 v[16:17], v34 offset0:140 offset1:173
	s_waitcnt lgkmcnt(0)
	v_mul_f32_e32 v16, v6, v16
	v_mul_f32_e32 v17, v7, v17
	v_cvt_pk_bf16_f32 v16, v16, v17
	ds_read2_b32 v[28:29], v34 offset0:206 offset1:239
	s_waitcnt lgkmcnt(0)
	v_mul_f32_e32 v17, v8, v28
	v_mul_f32_e32 v27, v9, v29
	v_cvt_pk_bf16_f32 v17, v17, v27
.LBB0_1611:
	v_add_u32_e32 v28, 8, v26
	v_ashrrev_i32_e32 v29, 31, v28
	v_lshlrev_b64 v[28:29], 13, v[28:29]
	v_lshl_add_u64 v[28:29], v[24:25], 0, v[28:29]
	global_store_dwordx4 v[28:29], v[14:17], off sc1
	v_add_u32_e32 v28, 16, v26
	s_mov_b64 s[4:5], -1
	s_and_b64 vcc, exec, s[2:3]
	v_ashrrev_i32_e32 v29, 31, v28
	s_cbranch_vccz .LBB0_1613
	v_lshlrev_b64 v[14:15], 13, v[28:29]
	v_lshl_add_u64 v[14:15], v[24:25], 0, v[14:15]
	global_store_dwordx4 v[14:15], v[2:5], off sc1
	s_mov_b64 s[4:5], 0
.LBB0_1613:
	v_mov_b32_e32 v14, 0
	s_andn2_b64 vcc, exec, s[4:5]
	v_mov_b32_e32 v15, 0
	v_mov_b32_e32 v16, 0
	v_mov_b32_e32 v17, 0
	s_cbranch_vccnz .LBB0_1598
	ds_read2_b32 v[14:15], v34 offset0:16 offset1:49
	v_lshlrev_b64 v[28:29], 13, v[28:29]
	v_lshl_add_u64 v[28:29], v[24:25], 0, v[28:29]
	s_waitcnt lgkmcnt(0)
	v_mul_f32_e32 v14, v10, v14
	v_mul_f32_e32 v15, v11, v15
	v_cvt_pk_bf16_f32 v14, v14, v15
	ds_read2_b32 v[16:17], v34 offset0:82 offset1:115
	s_waitcnt lgkmcnt(0)
	v_mul_f32_e32 v15, v12, v16
	v_mul_f32_e32 v16, v13, v17
	v_cvt_pk_bf16_f32 v15, v15, v16
	ds_read2_b32 v[16:17], v34 offset0:148 offset1:181
	s_waitcnt lgkmcnt(0)
	v_mul_f32_e32 v16, v6, v16
	v_mul_f32_e32 v17, v7, v17
	v_cvt_pk_bf16_f32 v16, v16, v17
	ds_read2_b32 v[42:43], v34 offset0:214 offset1:247
	s_waitcnt lgkmcnt(0)
	v_mul_f32_e32 v17, v8, v42
	v_mul_f32_e32 v27, v9, v43
	v_cvt_pk_bf16_f32 v17, v17, v27
	ds_read2_b32 v[42:43], v34 offset0:24 offset1:57
	global_store_dwordx4 v[28:29], v[14:17], off sc1
	s_waitcnt lgkmcnt(0)
	v_mul_f32_e32 v10, v10, v42
	v_mul_f32_e32 v11, v11, v43
	v_cvt_pk_bf16_f32 v14, v10, v11
	ds_read2_b32 v[10:11], v34 offset0:90 offset1:123
	s_waitcnt lgkmcnt(0)
	v_mul_f32_e32 v10, v12, v10
	v_mul_f32_e32 v11, v13, v11
	v_cvt_pk_bf16_f32 v15, v10, v11
	ds_read2_b32 v[10:11], v34 offset0:156 offset1:189
	s_waitcnt lgkmcnt(0)
	v_mul_f32_e32 v6, v6, v10
	v_mul_f32_e32 v7, v7, v11
	v_cvt_pk_bf16_f32 v16, v6, v7
	ds_read2_b32 v[6:7], v34 offset0:222 offset1:255
	s_waitcnt lgkmcnt(0)
	v_mul_f32_e32 v6, v8, v6
	v_mul_f32_e32 v7, v9, v7
	v_cvt_pk_bf16_f32 v17, v6, v7
	s_branch .LBB0_1598

; __device__ __forceinline__ unsigned pk2(float lo, float hi) { unsigned r; asm volatile("v_cvt_pk_bf16_f32 %0, %1, %2" : "=v"(r) : "v"(lo), "v"(hi)); return r; }
; __device__ __forceinline__ void p0_transpose_item(const float* W, int K, int N, bf16* WT, int kb, int src_col0, int dst_row0, float* scr, int lane, const float* kgain = nullptr) {
;     ...
;     for (int j = 0; j < 4; ++j) { const int n = (lane >> 3) + 8 * j; const float* s = scr + (8 * c) * 33 + n;
;         v4u o;
;         if (src_col0 >= 0) { o.x = pk2(s[0 * 33] * g0.x, s[1 * 33] * g0.y); o.y = pk2(s[2 * 33] * g0.z, s[3 * 33] * g0.w); o.z = pk2(s[4 * 33] * g1.x, s[5 * 33] * g1.y); o.w = pk2(s[6 * 33] * g1.z, s[7 * 33] * g1.w); }
;         else { o.x = 0u; o.y = 0u; o.z = 0u; o.w = 0u; }
;         *(v4u*)(WT + (size_t)(dst_row0 + n) * K + k0 + 8 * c) = o; }
.LBB0_1617:
	v_add_u32_e32 v14, 24, v6
	v_ashrrev_i32_e32 v15, 31, v14
	v_lshlrev_b64 v[14:15], 13, v[14:15]
	v_lshl_add_u64 v[12:13], v[12:13], 0, v[14:15]
	global_store_dwordx4 v[12:13], v[2:5], off sc1
	s_waitcnt lgkmcnt(0)
	s_add_i32 s7, s7, s76
	s_add_i32 s6, s6, s8
	s_cmpk_gt_i32 s7, 0x1fff
	s_cbranch_scc1 .LBB0_1628

; __device__ __forceinline__ unsigned pk2(float lo, float hi) { unsigned r; asm volatile("v_cvt_pk_bf16_f32 %0, %1, %2" : "=v"(r) : "v"(lo), "v"(hi)); return r; }
; __device__ __forceinline__ void p0_transpose_item(const float* W, int K, int N, bf16* WT, int kb, int src_col0, int dst_row0, float* scr, int lane, const float* kgain = nullptr) {
;     ...
;     for (int j = 0; j < 4; ++j) { const int n = (lane >> 3) + 8 * j; const float* s = scr + (8 * c) * 33 + n;
;         v4u o;
;         if (src_col0 >= 0) { o.x = pk2(s[0 * 33] * g0.x, s[1 * 33] * g0.y); o.y = pk2(s[2 * 33] * g0.z, s[3 * 33] * g0.w); o.z = pk2(s[4 * 33] * g1.x, s[5 * 33] * g1.y); o.w = pk2(s[6 * 33] * g1.z, s[7 * 33] * g1.w); }
;         else { o.x = 0u; o.y = 0u; o.z = 0u; o.w = 0u; }
;         *(v4u*)(WT + (size_t)(dst_row0 + n) * K + k0 + 8 * c) = o; }
.LBB0_1620:
	s_waitcnt lgkmcnt(0)
	s_ashr_i32 s5, s4, 31
	v_lshl_add_u64 v[12:13], s[4:5], 1, v[10:11]
	s_mov_b64 s[4:5], -1
	s_and_b64 vcc, exec, s[2:3]
	s_cbranch_vccz .LBB0_1622
	s_add_i32 s0, s9, s6
	v_add_u32_e32 v2, s0, v18
	v_ashrrev_i32_e32 v3, 31, v2
	v_lshlrev_b64 v[4:5], 13, v[2:3]
	v_lshl_add_u64 v[4:5], v[12:13], 0, v[4:5]
	global_store_dwordx4 v[4:5], v[28:31], off sc1
	s_mov_b64 s[4:5], 0
	v_mov_b32_e32 v6, v2
.LBB0_1622:
	v_mov_b32_e32 v2, 0
	s_andn2_b64 vcc, exec, s[4:5]
	v_mov_b32_e32 v3, 0
	v_mov_b32_e32 v4, 0
	v_mov_b32_e32 v5, 0
	s_cbranch_vccnz .LBB0_1624
	ds_read2_b32 v[2:3], v19 offset1:33
	s_add_i32 s9, s9, s6
	s_waitcnt lgkmcnt(0)
	v_cvt_pk_bf16_f32 v2, v2, v3
	ds_read2_b32 v[4:5], v19 offset0:66 offset1:99
	v_add_u32_e32 v6, s9, v18
	s_waitcnt lgkmcnt(0)
	v_cvt_pk_bf16_f32 v3, v4, v5
	ds_read2_b32 v[4:5], v19 offset0:132 offset1:165
	v_lshlrev_b64 v[32:33], 13, v[6:7]
	s_waitcnt lgkmcnt(0)
	v_cvt_pk_bf16_f32 v4, v4, v5
	ds_read2_b32 v[14:15], v19 offset0:198 offset1:231
	s_waitcnt lgkmcnt(0)
	v_cvt_pk_bf16_f32 v5, v14, v15
	v_lshl_add_u64 v[32:33], v[12:13], 0, v[32:33]
	ds_read2_b32 v[14:15], v19 offset0:8 offset1:41
	global_store_dwordx4 v[32:33], v[2:5], off sc1
	s_waitcnt lgkmcnt(0)
	s_nop 0
	v_cvt_pk_bf16_f32 v2, v14, v15
	ds_read2_b32 v[4:5], v19 offset0:74 offset1:107
	s_waitcnt lgkmcnt(0)
	v_cvt_pk_bf16_f32 v3, v4, v5
	ds_read2_b32 v[4:5], v19 offset0:140 offset1:173
	s_waitcnt lgkmcnt(0)
	v_cvt_pk_bf16_f32 v4, v4, v5
	ds_read2_b32 v[14:15], v19 offset0:206 offset1:239
	s_waitcnt lgkmcnt(0)
	v_cvt_pk_bf16_f32 v5, v14, v15
.LBB0_1624:
	v_add_u32_e32 v14, 8, v6
	v_ashrrev_i32_e32 v15, 31, v14
	v_lshlrev_b64 v[14:15], 13, v[14:15]
	v_lshl_add_u64 v[14:15], v[12:13], 0, v[14:15]
	global_store_dwordx4 v[14:15], v[2:5], off sc1
	s_mov_b64 s[4:5], -1
	s_and_b64 vcc, exec, s[2:3]
	v_add_u32_e32 v14, 16, v6
	s_cbranch_vccz .LBB0_1626
	v_ashrrev_i32_e32 v15, 31, v14
	v_lshlrev_b64 v[2:3], 13, v[14:15]
	v_lshl_add_u64 v[2:3], v[12:13], 0, v[2:3]
	global_store_dwordx4 v[2:3], v[28:31], off sc1
	s_mov_b64 s[4:5], 0
.LBB0_1626:
	v_mov_b32_e32 v2, 0
	s_andn2_b64 vcc, exec, s[4:5]
	v_mov_b32_e32 v3, 0
	v_mov_b32_e32 v4, 0
	v_mov_b32_e32 v5, 0
	s_cbranch_vccnz .LBB0_1617
	ds_read2_b32 v[2:3], v19 offset0:16 offset1:49
	s_waitcnt lgkmcnt(0)
	v_cvt_pk_bf16_f32 v2, v2, v3
	ds_read2_b32 v[4:5], v19 offset0:82 offset1:115
	v_mov_b32_e32 v15, v7
	s_waitcnt lgkmcnt(0)
	v_cvt_pk_bf16_f32 v3, v4, v5
	ds_read2_b32 v[4:5], v19 offset0:148 offset1:181
	v_lshlrev_b64 v[14:15], 13, v[14:15]
	s_waitcnt lgkmcnt(0)
	v_cvt_pk_bf16_f32 v4, v4, v5
	ds_read2_b32 v[32:33], v19 offset0:214 offset1:247
	s_waitcnt lgkmcnt(0)
	v_cvt_pk_bf16_f32 v5, v32, v33
	v_lshl_add_u64 v[14:15], v[12:13], 0, v[14:15]
	ds_read2_b32 v[32:33], v19 offset0:24 offset1:57
	global_store_dwordx4 v[14:15], v[2:5], off sc1
	s_waitcnt lgkmcnt(0)
	s_nop 0
	v_cvt_pk_bf16_f32 v2, v32, v33
	ds_read2_b32 v[4:5], v19 offset0:90 offset1:123
	s_waitcnt lgkmcnt(0)
	v_cvt_pk_bf16_f32 v3, v4, v5
	ds_read2_b32 v[4:5], v19 offset0:156 offset1:189
	s_waitcnt lgkmcnt(0)
	v_cvt_pk_bf16_f32 v4, v4, v5
	ds_read2_b32 v[14:15], v19 offset0:222 offset1:255
	s_waitcnt lgkmcnt(0)
	v_cvt_pk_bf16_f32 v5, v14, v15
	s_branch .LBB0_1617

; __device__ __forceinline__ unsigned pk2(float lo, float hi) { unsigned r; asm volatile("v_cvt_pk_bf16_f32 %0, %1, %2" : "=v"(r) : "v"(lo), "v"(hi)); return r; }
; __device__ __forceinline__ void p0_transpose_item(const float* W, int K, int N, bf16* WT, int kb, int src_col0, int dst_row0, float* scr, int lane, const float* kgain = nullptr) {
;     ...
;     for (int j = 0; j < 4; ++j) { const int n = (lane >> 3) + 8 * j; const float* s = scr + (8 * c) * 33 + n;
;         v4u o;
;         if (src_col0 >= 0) { o.x = pk2(s[0 * 33] * g0.x, s[1 * 33] * g0.y); o.y = pk2(s[2 * 33] * g0.z, s[3 * 33] * g0.w); o.z = pk2(s[4 * 33] * g1.x, s[5 * 33] * g1.y); o.w = pk2(s[6 * 33] * g1.z, s[7 * 33] * g1.w); }
;         else { o.x = 0u; o.y = 0u; o.z = 0u; o.w = 0u; }
;         *(v4u*)(WT + (size_t)(dst_row0 + n) * K + k0 + 8 * c) = o; }
.LBB0_1633:
	v_add_u32_e32 v20, 24, v6
	v_ashrrev_i32_e32 v21, 31, v20
	v_lshlrev_b64 v[20:21], 13, v[20:21]
	v_lshl_add_u64 v[12:13], v[12:13], 0, v[20:21]
	global_store_dwordx4 v[12:13], v[2:5], off sc1
	s_waitcnt lgkmcnt(0)
	s_add_i32 s0, s10, 0x400
	s_add_i32 s9, s9, 0x8000
	s_cmpk_lt_i32 s10, 0x1c00
	s_mov_b32 s10, s0
	s_cbranch_scc0 .LBB0_1644

; __device__ __forceinline__ unsigned pk2(float lo, float hi) { unsigned r; asm volatile("v_cvt_pk_bf16_f32 %0, %1, %2" : "=v"(r) : "v"(lo), "v"(hi)); return r; }
; __device__ __forceinline__ void p0_transpose_item(const float* W, int K, int N, bf16* WT, int kb, int src_col0, int dst_row0, float* scr, int lane, const float* kgain = nullptr) {
;     ...
;     for (int j = 0; j < 4; ++j) { const int n = (lane >> 3) + 8 * j; const float* s = scr + (8 * c) * 33 + n;
;         v4u o;
;         if (src_col0 >= 0) { o.x = pk2(s[0 * 33] * g0.x, s[1 * 33] * g0.y); o.y = pk2(s[2 * 33] * g0.z, s[3 * 33] * g0.w); o.z = pk2(s[4 * 33] * g1.x, s[5 * 33] * g1.y); o.w = pk2(s[6 * 33] * g1.z, s[7 * 33] * g1.w); }
;         else { o.x = 0u; o.y = 0u; o.z = 0u; o.w = 0u; }
;         *(v4u*)(WT + (size_t)(dst_row0 + n) * K + k0 + 8 * c) = o; }
.LBB0_1636:
	s_waitcnt lgkmcnt(0)
	s_ashr_i32 s5, s4, 31
	v_lshl_add_u64 v[12:13], s[4:5], 1, v[10:11]
	s_mov_b64 s[4:5], -1
	s_and_b64 vcc, exec, s[2:3]
	s_cbranch_vccz .LBB0_1638
	s_add_i32 s0, s11, s9
	v_add_u32_e32 v2, s0, v35
	v_ashrrev_i32_e32 v3, 31, v2
	v_lshlrev_b64 v[4:5], 13, v[2:3]
	v_lshl_add_u64 v[4:5], v[12:13], 0, v[4:5]
	global_store_dwordx4 v[4:5], v[28:31], off sc1
	s_mov_b64 s[4:5], 0
	v_mov_b32_e32 v6, v2
.LBB0_1638:
	v_mov_b32_e32 v2, 0
	s_andn2_b64 vcc, exec, s[4:5]
	v_mov_b32_e32 v3, 0
	v_mov_b32_e32 v4, 0
	v_mov_b32_e32 v5, 0
	s_cbranch_vccnz .LBB0_1640
	ds_read2_b32 v[2:3], v19 offset1:33
	s_add_i32 s11, s11, s9
	s_waitcnt lgkmcnt(0)
	v_cvt_pk_bf16_f32 v2, v2, v3
	ds_read2_b32 v[4:5], v19 offset0:66 offset1:99
	v_add_u32_e32 v6, s11, v35
	s_waitcnt lgkmcnt(0)
	v_cvt_pk_bf16_f32 v3, v4, v5
	ds_read2_b32 v[4:5], v19 offset0:132 offset1:165
	v_lshlrev_b64 v[32:33], 13, v[6:7]
	s_waitcnt lgkmcnt(0)
	v_cvt_pk_bf16_f32 v4, v4, v5
	ds_read2_b32 v[20:21], v19 offset0:198 offset1:231
	s_waitcnt lgkmcnt(0)
	v_cvt_pk_bf16_f32 v5, v20, v21
	v_lshl_add_u64 v[32:33], v[12:13], 0, v[32:33]
	ds_read2_b32 v[20:21], v19 offset0:8 offset1:41
	global_store_dwordx4 v[32:33], v[2:5], off sc1
	s_waitcnt lgkmcnt(0)
	s_nop 0
	v_cvt_pk_bf16_f32 v2, v20, v21
	ds_read2_b32 v[4:5], v19 offset0:74 offset1:107
	s_waitcnt lgkmcnt(0)
	v_cvt_pk_bf16_f32 v3, v4, v5
	ds_read2_b32 v[4:5], v19 offset0:140 offset1:173
	s_waitcnt lgkmcnt(0)
	v_cvt_pk_bf16_f32 v4, v4, v5
	ds_read2_b32 v[20:21], v19 offset0:206 offset1:239
	s_waitcnt lgkmcnt(0)
	v_cvt_pk_bf16_f32 v5, v20, v21
.LBB0_1640:
	v_add_u32_e32 v20, 8, v6
	v_ashrrev_i32_e32 v21, 31, v20
	v_lshlrev_b64 v[20:21], 13, v[20:21]
	v_lshl_add_u64 v[20:21], v[12:13], 0, v[20:21]
	global_store_dwordx4 v[20:21], v[2:5], off sc1
	s_mov_b64 s[4:5], -1
	s_and_b64 vcc, exec, s[2:3]
	v_add_u32_e32 v20, 16, v6
	s_cbranch_vccz .LBB0_1642
	v_ashrrev_i32_e32 v21, 31, v20
	v_lshlrev_b64 v[2:3], 13, v[20:21]
	v_lshl_add_u64 v[2:3], v[12:13], 0, v[2:3]
	global_store_dwordx4 v[2:3], v[28:31], off sc1
	s_mov_b64 s[4:5], 0
.LBB0_1642:
	v_mov_b32_e32 v2, 0
	s_andn2_b64 vcc, exec, s[4:5]
	v_mov_b32_e32 v3, 0
	v_mov_b32_e32 v4, 0
	v_mov_b32_e32 v5, 0
	s_cbranch_vccnz .LBB0_1633
	ds_read2_b32 v[2:3], v19 offset0:16 offset1:49
	s_waitcnt lgkmcnt(0)
	v_cvt_pk_bf16_f32 v2, v2, v3
	ds_read2_b32 v[4:5], v19 offset0:82 offset1:115
	v_mov_b32_e32 v21, v7
	s_waitcnt lgkmcnt(0)
	v_cvt_pk_bf16_f32 v3, v4, v5
	ds_read2_b32 v[4:5], v19 offset0:148 offset1:181
	v_lshlrev_b64 v[20:21], 13, v[20:21]
	s_waitcnt lgkmcnt(0)
	v_cvt_pk_bf16_f32 v4, v4, v5
	ds_read2_b32 v[32:33], v19 offset0:214 offset1:247
	s_waitcnt lgkmcnt(0)
	v_cvt_pk_bf16_f32 v5, v32, v33
	v_lshl_add_u64 v[20:21], v[12:13], 0, v[20:21]
	ds_read2_b32 v[32:33], v19 offset0:24 offset1:57
	global_store_dwordx4 v[20:21], v[2:5], off sc1
	s_waitcnt lgkmcnt(0)
	s_nop 0
	v_cvt_pk_bf16_f32 v2, v32, v33
	ds_read2_b32 v[4:5], v19 offset0:90 offset1:123
	s_waitcnt lgkmcnt(0)
	v_cvt_pk_bf16_f32 v3, v4, v5
	ds_read2_b32 v[4:5], v19 offset0:156 offset1:189
	s_waitcnt lgkmcnt(0)
	v_cvt_pk_bf16_f32 v4, v4, v5
	ds_read2_b32 v[20:21], v19 offset0:222 offset1:255
	s_waitcnt lgkmcnt(0)
	v_cvt_pk_bf16_f32 v5, v20, v21
	s_branch .LBB0_1633

; __device__ __forceinline__ unsigned pk2(float lo, float hi) { unsigned r; asm volatile("v_cvt_pk_bf16_f32 %0, %1, %2" : "=v"(r) : "v"(lo), "v"(hi)); return r; }
; __device__ __forceinline__ void p0_transpose_item(const float* W, int K, int N, bf16* WT, int kb, int src_col0, int dst_row0, float* scr, int lane, const float* kgain = nullptr) {
;     ...
;     for (int j = 0; j < 4; ++j) { const int n = (lane >> 3) + 8 * j; const float* s = scr + (8 * c) * 33 + n;
;         v4u o;
;         if (src_col0 >= 0) { o.x = pk2(s[0 * 33] * g0.x, s[1 * 33] * g0.y); o.y = pk2(s[2 * 33] * g0.z, s[3 * 33] * g0.w); o.z = pk2(s[4 * 33] * g1.x, s[5 * 33] * g1.y); o.w = pk2(s[6 * 33] * g1.z, s[7 * 33] * g1.w); }
;         else { o.x = 0u; o.y = 0u; o.z = 0u; o.w = 0u; }
;         *(v4u*)(WT + (size_t)(dst_row0 + n) * K + k0 + 8 * c) = o; }
.LBB0_1645:
	v_add_u32_e32 v2, 24, v30
	v_ashrrev_i32_e32 v3, 31, v2
	v_lshlrev_b64 v[2:3], 13, v[2:3]
	v_lshl_add_u64 v[2:3], v[28:29], 0, v[2:3]
	global_store_dwordx4 v[2:3], v[10:13], off sc1
	s_waitcnt lgkmcnt(0)
	s_add_i32 s0, s7, 0x400
	s_add_i32 s8, s8, 0x8000
	s_cmpk_lt_i32 s7, 0x5600
	s_mov_b32 s7, s0
	s_cbranch_scc0 .LBB0_1662

; __device__ __forceinline__ unsigned pk2(float lo, float hi) { unsigned r; asm volatile("v_cvt_pk_bf16_f32 %0, %1, %2" : "=v"(r) : "v"(lo), "v"(hi)); return r; }
; __device__ __forceinline__ void p0_transpose_item(const float* W, int K, int N, bf16* WT, int kb, int src_col0, int dst_row0, float* scr, int lane, const float* kgain = nullptr) {
;     ...
;     for (int j = 0; j < 4; ++j) { const int n = (lane >> 3) + 8 * j; const float* s = scr + (8 * c) * 33 + n;
;         v4u o;
;         if (src_col0 >= 0) { o.x = pk2(s[0 * 33] * g0.x, s[1 * 33] * g0.y); o.y = pk2(s[2 * 33] * g0.z, s[3 * 33] * g0.w); o.z = pk2(s[4 * 33] * g1.x, s[5 * 33] * g1.y); o.w = pk2(s[6 * 33] * g1.z, s[7 * 33] * g1.w); }
;         else { o.x = 0u; o.y = 0u; o.z = 0u; o.w = 0u; }
;         *(v4u*)(WT + (size_t)(dst_row0 + n) * K + k0 + 8 * c) = o; }
.LBB0_1654:
	s_waitcnt lgkmcnt(0)
	v_lshl_add_u64 v[28:29], s[4:5], 1, v[24:25]
	s_mov_b64 s[4:5], -1
	s_and_b64 vcc, exec, s[2:3]
	s_cbranch_vccz .LBB0_1656
	s_add_i32 s0, s8, s10
	v_add_u32_e32 v30, s0, v35
	v_ashrrev_i32_e32 v31, 31, v30
	v_lshlrev_b64 v[10:11], 13, v[30:31]
	v_lshl_add_u64 v[10:11], v[28:29], 0, v[10:11]
	global_store_dwordx4 v[10:11], v[44:47], off sc1
	s_mov_b64 s[4:5], 0
.LBB0_1656:
	v_mov_b32_e32 v10, 0
	s_andn2_b64 vcc, exec, s[4:5]
	v_mov_b32_e32 v11, 0
	v_mov_b32_e32 v12, 0
	v_mov_b32_e32 v13, 0
	s_cbranch_vccnz .LBB0_1658
	ds_read2_b32 v[10:11], v19 offset1:33
	s_add_i32 s0, s8, s10
	v_add_u32_e32 v30, s0, v35
	v_ashrrev_i32_e32 v31, 31, v30
	v_lshlrev_b64 v[48:49], 13, v[30:31]
	s_waitcnt lgkmcnt(0)
	v_mul_f32_e32 v10, v6, v10
	v_mul_f32_e32 v11, v7, v11
	v_cvt_pk_bf16_f32 v10, v10, v11
	ds_read2_b32 v[12:13], v19 offset0:66 offset1:99
	v_lshl_add_u64 v[48:49], v[28:29], 0, v[48:49]
	s_waitcnt lgkmcnt(0)
	v_mul_f32_e32 v11, v8, v12
	v_mul_f32_e32 v12, v9, v13
	v_cvt_pk_bf16_f32 v11, v11, v12
	ds_read2_b32 v[12:13], v19 offset0:132 offset1:165
	s_waitcnt lgkmcnt(0)
	v_mul_f32_e32 v12, v2, v12
	v_mul_f32_e32 v13, v3, v13
	v_cvt_pk_bf16_f32 v12, v12, v13
	ds_read2_b32 v[32:33], v19 offset0:198 offset1:231
	s_waitcnt lgkmcnt(0)
	v_mul_f32_e32 v13, v4, v32
	v_mul_f32_e32 v21, v5, v33
	v_cvt_pk_bf16_f32 v13, v13, v21
	ds_read2_b32 v[32:33], v19 offset0:8 offset1:41
	global_store_dwordx4 v[48:49], v[10:13], off sc1
	s_waitcnt lgkmcnt(0)
	s_nop 0
	v_mul_f32_e32 v10, v6, v32
	v_mul_f32_e32 v11, v7, v33
	v_cvt_pk_bf16_f32 v10, v10, v11
	ds_read2_b32 v[12:13], v19 offset0:74 offset1:107
	s_waitcnt lgkmcnt(0)
	v_mul_f32_e32 v11, v8, v12
	v_mul_f32_e32 v12, v9, v13
	v_cvt_pk_bf16_f32 v11, v11, v12
	ds_read2_b32 v[12:13], v19 offset0:140 offset1:173
	s_waitcnt lgkmcnt(0)
	v_mul_f32_e32 v12, v2, v12
	v_mul_f32_e32 v13, v3, v13
	v_cvt_pk_bf16_f32 v12, v12, v13
	ds_read2_b32 v[32:33], v19 offset0:206 offset1:239
	s_waitcnt lgkmcnt(0)
	v_mul_f32_e32 v13, v4, v32
	v_mul_f32_e32 v21, v5, v33
	v_cvt_pk_bf16_f32 v13, v13, v21
.LBB0_1658:
	v_add_u32_e32 v32, 8, v30
	v_ashrrev_i32_e32 v33, 31, v32
	v_lshlrev_b64 v[32:33], 13, v[32:33]
	v_lshl_add_u64 v[32:33], v[28:29], 0, v[32:33]
	global_store_dwordx4 v[32:33], v[10:13], off sc1
	v_add_u32_e32 v32, 16, v30
	s_mov_b64 s[4:5], -1
	s_and_b64 vcc, exec, s[2:3]
	v_ashrrev_i32_e32 v33, 31, v32
	s_cbranch_vccz .LBB0_1660
	v_lshlrev_b64 v[10:11], 13, v[32:33]
	v_lshl_add_u64 v[10:11], v[28:29], 0, v[10:11]
	global_store_dwordx4 v[10:11], v[44:47], off sc1
	s_mov_b64 s[4:5], 0
.LBB0_1660:
	v_mov_b32_e32 v10, 0
	s_andn2_b64 vcc, exec, s[4:5]
	v_mov_b32_e32 v11, 0
	v_mov_b32_e32 v12, 0
	v_mov_b32_e32 v13, 0
	s_cbranch_vccnz .LBB0_1645
	ds_read2_b32 v[10:11], v19 offset0:16 offset1:49
	v_lshlrev_b64 v[32:33], 13, v[32:33]
	v_lshl_add_u64 v[32:33], v[28:29], 0, v[32:33]
	s_waitcnt lgkmcnt(0)
	v_mul_f32_e32 v10, v6, v10
	v_mul_f32_e32 v11, v7, v11
	v_cvt_pk_bf16_f32 v10, v10, v11
	ds_read2_b32 v[12:13], v19 offset0:82 offset1:115
	s_waitcnt lgkmcnt(0)
	v_mul_f32_e32 v11, v8, v12
	v_mul_f32_e32 v12, v9, v13
	v_cvt_pk_bf16_f32 v11, v11, v12
	ds_read2_b32 v[12:13], v19 offset0:148 offset1:181
	s_waitcnt lgkmcnt(0)
	v_mul_f32_e32 v12, v2, v12
	v_mul_f32_e32 v13, v3, v13
	v_cvt_pk_bf16_f32 v12, v12, v13
	ds_read2_b32 v[48:49], v19 offset0:214 offset1:247
	s_waitcnt lgkmcnt(0)
	v_mul_f32_e32 v13, v4, v48
	v_mul_f32_e32 v21, v5, v49
	v_cvt_pk_bf16_f32 v13, v13, v21
	ds_read2_b32 v[48:49], v19 offset0:24 offset1:57
	global_store_dwordx4 v[32:33], v[10:13], off sc1
	s_waitcnt lgkmcnt(0)
	v_mul_f32_e32 v6, v6, v48
	v_mul_f32_e32 v7, v7, v49
	v_cvt_pk_bf16_f32 v10, v6, v7
	ds_read2_b32 v[6:7], v19 offset0:90 offset1:123
	s_waitcnt lgkmcnt(0)
	v_mul_f32_e32 v6, v8, v6
	v_mul_f32_e32 v7, v9, v7
	v_cvt_pk_bf16_f32 v11, v6, v7
	ds_read2_b32 v[6:7], v19 offset0:156 offset1:189
	s_waitcnt lgkmcnt(0)
	v_mul_f32_e32 v2, v2, v6
	v_mul_f32_e32 v3, v3, v7
	v_cvt_pk_bf16_f32 v12, v2, v3
	ds_read2_b32 v[2:3], v19 offset0:222 offset1:255
	s_waitcnt lgkmcnt(0)
	v_mul_f32_e32 v2, v4, v2
	v_mul_f32_e32 v3, v5, v3
	v_cvt_pk_bf16_f32 v13, v2, v3
	s_branch .LBB0_1645

; __device__ __forceinline__ unsigned pk2(float lo, float hi) { unsigned r; asm volatile("v_cvt_pk_bf16_f32 %0, %1, %2" : "=v"(r) : "v"(lo), "v"(hi)); return r; }
; __device__ __forceinline__ void p0_transpose_item(const float* W, int K, int N, bf16* WT, int kb, int src_col0, int dst_row0, float* scr, int lane, const float* kgain = nullptr) {
;     ...
;     for (int j = 0; j < 4; ++j) { const int n = (lane >> 3) + 8 * j; const float* s = scr + (8 * c) * 33 + n;
;         v4u o;
;         if (src_col0 >= 0) { o.x = pk2(s[0 * 33] * g0.x, s[1 * 33] * g0.y); o.y = pk2(s[2 * 33] * g0.z, s[3 * 33] * g0.w); o.z = pk2(s[4 * 33] * g1.x, s[5 * 33] * g1.y); o.w = pk2(s[6 * 33] * g1.z, s[7 * 33] * g1.w); }
;         else { o.x = 0u; o.y = 0u; o.z = 0u; o.w = 0u; }
;         *(v4u*)(WT + (size_t)(dst_row0 + n) * K + k0 + 8 * c) = o; }
.LBB0_1663:
	v_add_u32_e32 v12, 24, v20
	v_ashrrev_i32_e32 v13, 31, v12
	v_lshlrev_b64 v[12:13], 13, v[12:13]
	v_lshl_add_u64 v[10:11], v[10:11], 0, v[12:13]
	global_store_dwordx4 v[10:11], v[2:5], off sc1
	s_waitcnt lgkmcnt(0)
	s_add_i32 s0, s6, 0x400
	s_add_i32 s7, s7, 0x8000
	s_cmpk_gt_i32 s6, 0x1bff
	s_mov_b32 s6, s0
	s_cbranch_scc1 .LBB0_1674

; __device__ __forceinline__ unsigned pk2(float lo, float hi) { unsigned r; asm volatile("v_cvt_pk_bf16_f32 %0, %1, %2" : "=v"(r) : "v"(lo), "v"(hi)); return r; }
; __device__ __forceinline__ void p0_transpose_item(const float* W, int K, int N, bf16* WT, int kb, int src_col0, int dst_row0, float* scr, int lane, const float* kgain = nullptr) {
;     ...
;     for (int j = 0; j < 4; ++j) { const int n = (lane >> 3) + 8 * j; const float* s = scr + (8 * c) * 33 + n;
;         v4u o;
;         if (src_col0 >= 0) { o.x = pk2(s[0 * 33] * g0.x, s[1 * 33] * g0.y); o.y = pk2(s[2 * 33] * g0.z, s[3 * 33] * g0.w); o.z = pk2(s[4 * 33] * g1.x, s[5 * 33] * g1.y); o.w = pk2(s[6 * 33] * g1.z, s[7 * 33] * g1.w); }
;         else { o.x = 0u; o.y = 0u; o.z = 0u; o.w = 0u; }
;         *(v4u*)(WT + (size_t)(dst_row0 + n) * K + k0 + 8 * c) = o; }
.LBB0_1666:
	s_waitcnt lgkmcnt(0)
	s_ashr_i32 s5, s4, 31
	v_lshl_add_u64 v[10:11], s[4:5], 1, v[6:7]
	s_mov_b64 s[4:5], -1
	s_and_b64 vcc, exec, s[2:3]
	s_cbranch_vccz .LBB0_1668
	s_add_i32 s0, s8, s7
	v_add_u32_e32 v2, s0, v35
	v_ashrrev_i32_e32 v3, 31, v2
	v_lshlrev_b64 v[4:5], 13, v[2:3]
	v_lshl_add_u64 v[4:5], v[10:11], 0, v[4:5]
	global_store_dwordx4 v[4:5], v[28:31], off sc1
	s_mov_b64 s[4:5], 0
	v_mov_b32_e32 v20, v2
.LBB0_1668:
	v_mov_b32_e32 v2, 0
	s_andn2_b64 vcc, exec, s[4:5]
	v_mov_b32_e32 v3, 0
	v_mov_b32_e32 v4, 0
	v_mov_b32_e32 v5, 0
	s_cbranch_vccnz .LBB0_1670
	ds_read2_b32 v[2:3], v19 offset1:33
	s_add_i32 s8, s8, s7
	s_waitcnt lgkmcnt(0)
	v_cvt_pk_bf16_f32 v2, v2, v3
	ds_read2_b32 v[4:5], v19 offset0:66 offset1:99
	v_add_u32_e32 v20, s8, v35
	s_waitcnt lgkmcnt(0)
	v_cvt_pk_bf16_f32 v3, v4, v5
	ds_read2_b32 v[4:5], v19 offset0:132 offset1:165
	v_lshlrev_b64 v[32:33], 13, v[20:21]
	s_waitcnt lgkmcnt(0)
	v_cvt_pk_bf16_f32 v4, v4, v5
	ds_read2_b32 v[12:13], v19 offset0:198 offset1:231
	s_waitcnt lgkmcnt(0)
	v_cvt_pk_bf16_f32 v5, v12, v13
	v_lshl_add_u64 v[32:33], v[10:11], 0, v[32:33]
	ds_read2_b32 v[12:13], v19 offset0:8 offset1:41
	global_store_dwordx4 v[32:33], v[2:5], off sc1
	s_waitcnt lgkmcnt(0)
	s_nop 0
	v_cvt_pk_bf16_f32 v2, v12, v13
	ds_read2_b32 v[4:5], v19 offset0:74 offset1:107
	s_waitcnt lgkmcnt(0)
	v_cvt_pk_bf16_f32 v3, v4, v5
	ds_read2_b32 v[4:5], v19 offset0:140 offset1:173
	s_waitcnt lgkmcnt(0)
	v_cvt_pk_bf16_f32 v4, v4, v5
	ds_read2_b32 v[12:13], v19 offset0:206 offset1:239
	s_waitcnt lgkmcnt(0)
	v_cvt_pk_bf16_f32 v5, v12, v13
.LBB0_1670:
	v_add_u32_e32 v12, 8, v20
	v_ashrrev_i32_e32 v13, 31, v12
	v_lshlrev_b64 v[12:13], 13, v[12:13]
	v_lshl_add_u64 v[12:13], v[10:11], 0, v[12:13]
	global_store_dwordx4 v[12:13], v[2:5], off sc1
	s_mov_b64 s[4:5], -1
	s_and_b64 vcc, exec, s[2:3]
	v_add_u32_e32 v12, 16, v20
	s_cbranch_vccz .LBB0_1672
	v_ashrrev_i32_e32 v13, 31, v12
	v_lshlrev_b64 v[2:3], 13, v[12:13]
	v_lshl_add_u64 v[2:3], v[10:11], 0, v[2:3]
	global_store_dwordx4 v[2:3], v[28:31], off sc1
	s_mov_b64 s[4:5], 0
.LBB0_1672:
	v_mov_b32_e32 v2, 0
	s_andn2_b64 vcc, exec, s[4:5]
	v_mov_b32_e32 v3, 0
	v_mov_b32_e32 v4, 0
	v_mov_b32_e32 v5, 0
	s_cbranch_vccnz .LBB0_1663
	ds_read2_b32 v[2:3], v19 offset0:16 offset1:49
	s_waitcnt lgkmcnt(0)
	v_cvt_pk_bf16_f32 v2, v2, v3
	ds_read2_b32 v[4:5], v19 offset0:82 offset1:115
	v_mov_b32_e32 v13, v21
	s_waitcnt lgkmcnt(0)
	v_cvt_pk_bf16_f32 v3, v4, v5
	ds_read2_b32 v[4:5], v19 offset0:148 offset1:181
	v_lshlrev_b64 v[12:13], 13, v[12:13]
	s_waitcnt lgkmcnt(0)
	v_cvt_pk_bf16_f32 v4, v4, v5
	ds_read2_b32 v[32:33], v19 offset0:214 offset1:247
	s_waitcnt lgkmcnt(0)
	v_cvt_pk_bf16_f32 v5, v32, v33
	v_lshl_add_u64 v[12:13], v[10:11], 0, v[12:13]
	ds_read2_b32 v[32:33], v19 offset0:24 offset1:57
	global_store_dwordx4 v[12:13], v[2:5], off sc1
	s_waitcnt lgkmcnt(0)
	s_nop 0
	v_cvt_pk_bf16_f32 v2, v32, v33
	ds_read2_b32 v[4:5], v19 offset0:90 offset1:123
	s_waitcnt lgkmcnt(0)
	v_cvt_pk_bf16_f32 v3, v4, v5
	ds_read2_b32 v[4:5], v19 offset0:156 offset1:189
	s_waitcnt lgkmcnt(0)
	v_cvt_pk_bf16_f32 v4, v4, v5
	ds_read2_b32 v[12:13], v19 offset0:222 offset1:255
	s_waitcnt lgkmcnt(0)
	v_cvt_pk_bf16_f32 v5, v12, v13
	s_branch .LBB0_1663

; __device__ __forceinline__ unsigned pk2(float lo, float hi) { unsigned r; asm volatile("v_cvt_pk_bf16_f32 %0, %1, %2" : "=v"(r) : "v"(lo), "v"(hi)); return r; }
; __device__ __forceinline__ void p0_transpose_item(const float* W, int K, int N, bf16* WT, int kb, int src_col0, int dst_row0, float* scr, int lane, const float* kgain = nullptr) {
;     ...
;     for (int j = 0; j < 4; ++j) { const int n = (lane >> 3) + 8 * j; const float* s = scr + (8 * c) * 33 + n;
;         v4u o;
;         if (src_col0 >= 0) { o.x = pk2(s[0 * 33] * g0.x, s[1 * 33] * g0.y); o.y = pk2(s[2 * 33] * g0.z, s[3 * 33] * g0.w); o.z = pk2(s[4 * 33] * g1.x, s[5 * 33] * g1.y); o.w = pk2(s[6 * 33] * g1.z, s[7 * 33] * g1.w); }
;         else { o.x = 0u; o.y = 0u; o.z = 0u; o.w = 0u; }
;         *(v4u*)(WT + (size_t)(dst_row0 + n) * K + k0 + 8 * c) = o; }
.LBB0_1677:
	v_add_u32_e32 v12, 24, v18
	v_ashrrev_i32_e32 v13, 31, v12
	v_lshlrev_b64 v[12:13], 13, v[12:13]
	v_lshl_add_u64 v[10:11], v[10:11], 0, v[12:13]
	global_store_dwordx4 v[10:11], v[2:5], off sc1
	s_waitcnt lgkmcnt(0)
	s_add_i32 s2, s12, 0x400
	s_add_i32 s11, s11, 0x8000
	s_cmpk_lt_i32 s12, 0x1c00
	s_mov_b32 s12, s2
	s_cbranch_scc0 .LBB0_1688

; __device__ __forceinline__ unsigned pk2(float lo, float hi) { unsigned r; asm volatile("v_cvt_pk_bf16_f32 %0, %1, %2" : "=v"(r) : "v"(lo), "v"(hi)); return r; }
; __device__ __forceinline__ void p0_transpose_item(const float* W, int K, int N, bf16* WT, int kb, int src_col0, int dst_row0, float* scr, int lane, const float* kgain = nullptr) {
;     ...
;     for (int j = 0; j < 4; ++j) { const int n = (lane >> 3) + 8 * j; const float* s = scr + (8 * c) * 33 + n;
;         v4u o;
;         if (src_col0 >= 0) { o.x = pk2(s[0 * 33] * g0.x, s[1 * 33] * g0.y); o.y = pk2(s[2 * 33] * g0.z, s[3 * 33] * g0.w); o.z = pk2(s[4 * 33] * g1.x, s[5 * 33] * g1.y); o.w = pk2(s[6 * 33] * g1.z, s[7 * 33] * g1.w); }
;         else { o.x = 0u; o.y = 0u; o.z = 0u; o.w = 0u; }
;         *(v4u*)(WT + (size_t)(dst_row0 + n) * K + k0 + 8 * c) = o; }
.LBB0_1680:
	s_waitcnt lgkmcnt(0)
	s_ashr_i32 s7, s6, 31
	v_lshl_add_u64 v[10:11], s[6:7], 1, v[8:9]
	s_mov_b64 s[6:7], -1
	s_and_b64 vcc, exec, s[4:5]
	s_cbranch_vccz .LBB0_1682
	s_add_i32 s2, s13, s11
	v_add_u32_e32 v2, s2, v35
	v_ashrrev_i32_e32 v3, 31, v2
	v_lshlrev_b64 v[4:5], 13, v[2:3]
	v_lshl_add_u64 v[4:5], v[10:11], 0, v[4:5]
	s_mov_b64 s[6:7], 0
	v_mov_b32_e32 v18, v2
	global_store_dwordx4 v[4:5], v[26:29], off sc1
.LBB0_1682:
	v_mov_b32_e32 v2, 0
	s_andn2_b64 vcc, exec, s[6:7]
	v_mov_b32_e32 v3, 0
	v_mov_b32_e32 v4, 0
	v_mov_b32_e32 v5, 0
	s_cbranch_vccnz .LBB0_1684
	ds_read2_b32 v[2:3], v31 offset1:33
	s_add_i32 s13, s13, s11
	s_waitcnt lgkmcnt(0)
	v_cvt_pk_bf16_f32 v2, v2, v3
	ds_read2_b32 v[4:5], v31 offset0:66 offset1:99
	v_add_u32_e32 v18, s13, v35
	s_waitcnt lgkmcnt(0)
	v_cvt_pk_bf16_f32 v3, v4, v5
	ds_read2_b32 v[4:5], v31 offset0:132 offset1:165
	v_lshlrev_b64 v[32:33], 13, v[18:19]
	s_waitcnt lgkmcnt(0)
	v_cvt_pk_bf16_f32 v4, v4, v5
	ds_read2_b32 v[12:13], v31 offset0:198 offset1:231
	s_waitcnt lgkmcnt(0)
	v_cvt_pk_bf16_f32 v5, v12, v13
	v_lshl_add_u64 v[32:33], v[10:11], 0, v[32:33]
	ds_read2_b32 v[12:13], v31 offset0:8 offset1:41
	global_store_dwordx4 v[32:33], v[2:5], off sc1
	s_waitcnt lgkmcnt(0)
	s_nop 0
	v_cvt_pk_bf16_f32 v2, v12, v13
	ds_read2_b32 v[4:5], v31 offset0:74 offset1:107
	s_waitcnt lgkmcnt(0)
	v_cvt_pk_bf16_f32 v3, v4, v5
	ds_read2_b32 v[4:5], v31 offset0:140 offset1:173
	s_waitcnt lgkmcnt(0)
	v_cvt_pk_bf16_f32 v4, v4, v5
	ds_read2_b32 v[12:13], v31 offset0:206 offset1:239
	s_waitcnt lgkmcnt(0)
	v_cvt_pk_bf16_f32 v5, v12, v13
.LBB0_1684:
	v_add_u32_e32 v12, 8, v18
	v_ashrrev_i32_e32 v13, 31, v12
	v_lshlrev_b64 v[12:13], 13, v[12:13]
	v_lshl_add_u64 v[12:13], v[10:11], 0, v[12:13]
	global_store_dwordx4 v[12:13], v[2:5], off sc1
	s_mov_b64 s[6:7], -1
	s_and_b64 vcc, exec, s[4:5]
	v_add_u32_e32 v12, 16, v18
	s_cbranch_vccz .LBB0_1686
	v_ashrrev_i32_e32 v13, 31, v12
	v_lshlrev_b64 v[2:3], 13, v[12:13]
	v_lshl_add_u64 v[2:3], v[10:11], 0, v[2:3]
	s_mov_b64 s[6:7], 0
	global_store_dwordx4 v[2:3], v[26:29], off sc1
.LBB0_1686:
	v_mov_b32_e32 v2, 0
	s_andn2_b64 vcc, exec, s[6:7]
	v_mov_b32_e32 v3, 0
	v_mov_b32_e32 v4, 0
	v_mov_b32_e32 v5, 0
	s_cbranch_vccnz .LBB0_1677
	ds_read2_b32 v[2:3], v31 offset0:16 offset1:49
	s_waitcnt lgkmcnt(0)
	v_cvt_pk_bf16_f32 v2, v2, v3
	ds_read2_b32 v[4:5], v31 offset0:82 offset1:115
	v_mov_b32_e32 v13, v19
	s_waitcnt lgkmcnt(0)
	v_cvt_pk_bf16_f32 v3, v4, v5
	ds_read2_b32 v[4:5], v31 offset0:148 offset1:181
	v_lshlrev_b64 v[12:13], 13, v[12:13]
	s_waitcnt lgkmcnt(0)
	v_cvt_pk_bf16_f32 v4, v4, v5
	ds_read2_b32 v[32:33], v31 offset0:214 offset1:247
	s_waitcnt lgkmcnt(0)
	v_cvt_pk_bf16_f32 v5, v32, v33
	v_lshl_add_u64 v[12:13], v[10:11], 0, v[12:13]
	ds_read2_b32 v[32:33], v31 offset0:24 offset1:57
	global_store_dwordx4 v[12:13], v[2:5], off sc1
	s_waitcnt lgkmcnt(0)
	s_nop 0
	v_cvt_pk_bf16_f32 v2, v32, v33
	ds_read2_b32 v[4:5], v31 offset0:90 offset1:123
	s_waitcnt lgkmcnt(0)
	v_cvt_pk_bf16_f32 v3, v4, v5
	ds_read2_b32 v[4:5], v31 offset0:156 offset1:189
	s_waitcnt lgkmcnt(0)
	v_cvt_pk_bf16_f32 v4, v4, v5
	ds_read2_b32 v[12:13], v31 offset0:222 offset1:255
	s_waitcnt lgkmcnt(0)
	v_cvt_pk_bf16_f32 v5, v12, v13
	s_branch .LBB0_1677

; __device__ __forceinline__ unsigned pk2(float lo, float hi) { unsigned r; asm volatile("v_cvt_pk_bf16_f32 %0, %1, %2" : "=v"(r) : "v"(lo), "v"(hi)); return r; }
; __device__ __forceinline__ void p0_transpose_item(const float* W, int K, int N, bf16* WT, int kb, int src_col0, int dst_row0, float* scr, int lane, const float* kgain = nullptr) {
;     ...
;     for (int j = 0; j < 4; ++j) { const int n = (lane >> 3) + 8 * j; const float* s = scr + (8 * c) * 33 + n;
;         v4u o;
;         if (src_col0 >= 0) { o.x = pk2(s[0 * 33] * g0.x, s[1 * 33] * g0.y); o.y = pk2(s[2 * 33] * g0.z, s[3 * 33] * g0.w); o.z = pk2(s[4 * 33] * g1.x, s[5 * 33] * g1.y); o.w = pk2(s[6 * 33] * g1.z, s[7 * 33] * g1.w); }
;         else { o.x = 0u; o.y = 0u; o.z = 0u; o.w = 0u; }
;         *(v4u*)(WT + (size_t)(dst_row0 + n) * K + k0 + 8 * c) = o; }
.LBB0_1692:
	s_waitcnt vmcnt(2)
	v_add_u32_e32 v6, 24, v26
	v_ashrrev_i32_e32 v7, 31, v6
	v_lshlrev_b64 v[6:7], 13, v[6:7]
	v_lshl_add_u64 v[6:7], v[24:25], 0, v[6:7]
	global_store_dwordx4 v[6:7], v[14:17], off sc1
	s_waitcnt lgkmcnt(0)
	s_add_i32 s2, s9, 0x400
	s_add_i32 s10, s10, 0x8000
	s_cmpk_lt_i32 s9, 0x5600
	s_mov_b32 s9, s2
	s_cbranch_scc0 .LBB0_1709

; __device__ __forceinline__ unsigned pk2(float lo, float hi) { unsigned r; asm volatile("v_cvt_pk_bf16_f32 %0, %1, %2" : "=v"(r) : "v"(lo), "v"(hi)); return r; }
; __device__ __forceinline__ void p0_transpose_item(const float* W, int K, int N, bf16* WT, int kb, int src_col0, int dst_row0, float* scr, int lane, const float* kgain = nullptr) {
;     ...
;     for (int j = 0; j < 4; ++j) { const int n = (lane >> 3) + 8 * j; const float* s = scr + (8 * c) * 33 + n;
;         v4u o;
;         if (src_col0 >= 0) { o.x = pk2(s[0 * 33] * g0.x, s[1 * 33] * g0.y); o.y = pk2(s[2 * 33] * g0.z, s[3 * 33] * g0.w); o.z = pk2(s[4 * 33] * g1.x, s[5 * 33] * g1.y); o.w = pk2(s[6 * 33] * g1.z, s[7 * 33] * g1.w); }
;         else { o.x = 0u; o.y = 0u; o.z = 0u; o.w = 0u; }
;         *(v4u*)(WT + (size_t)(dst_row0 + n) * K + k0 + 8 * c) = o; }
.LBB0_1701:
	s_waitcnt lgkmcnt(0)
	v_lshl_add_u64 v[24:25], s[6:7], 1, v[20:21]
	s_mov_b64 s[6:7], -1
	s_and_b64 vcc, exec, s[4:5]
	s_cbranch_vccz .LBB0_1703
	s_add_i32 s2, s10, s12
	v_add_u32_e32 v26, s2, v35
	v_ashrrev_i32_e32 v27, 31, v26
	v_lshlrev_b64 v[14:15], 13, v[26:27]
	v_lshl_add_u64 v[14:15], v[24:25], 0, v[14:15]
	global_store_dwordx4 v[14:15], v[2:5], off sc1
	s_mov_b64 s[6:7], 0
.LBB0_1703:
	v_mov_b32_e32 v14, 0
	s_andn2_b64 vcc, exec, s[6:7]
	v_mov_b32_e32 v15, 0
	v_mov_b32_e32 v16, 0
	v_mov_b32_e32 v17, 0
	s_cbranch_vccnz .LBB0_1705
	ds_read2_b32 v[14:15], v31 offset1:33
	s_add_i32 s2, s10, s12
	v_add_u32_e32 v26, s2, v35
	s_waitcnt vmcnt(0) lgkmcnt(0)
	v_mul_f32_e32 v14, v10, v14
	v_mul_f32_e32 v15, v11, v15
	v_cvt_pk_bf16_f32 v14, v14, v15
	ds_read2_b32 v[16:17], v31 offset0:66 offset1:99
	s_waitcnt lgkmcnt(0)
	v_mul_f32_e32 v15, v12, v16
	v_mul_f32_e32 v16, v13, v17
	v_cvt_pk_bf16_f32 v15, v15, v16
	ds_read2_b32 v[16:17], v31 offset0:132 offset1:165
	s_waitcnt lgkmcnt(0)
	v_mul_f32_e32 v16, v6, v16
	v_mul_f32_e32 v17, v7, v17
	v_cvt_pk_bf16_f32 v16, v16, v17
	ds_read2_b32 v[28:29], v31 offset0:198 offset1:231
	s_waitcnt lgkmcnt(0)
	v_mul_f32_e32 v17, v8, v28
	v_mul_f32_e32 v27, v9, v29
	v_cvt_pk_bf16_f32 v17, v17, v27
	ds_read2_b32 v[28:29], v31 offset0:8 offset1:41
	v_ashrrev_i32_e32 v27, 31, v26
	v_lshlrev_b64 v[42:43], 13, v[26:27]
	v_lshl_add_u64 v[42:43], v[24:25], 0, v[42:43]
	global_store_dwordx4 v[42:43], v[14:17], off sc1
	s_waitcnt lgkmcnt(0)
	s_nop 0
	v_mul_f32_e32 v14, v10, v28
	v_mul_f32_e32 v15, v11, v29
	v_cvt_pk_bf16_f32 v14, v14, v15
	ds_read2_b32 v[16:17], v31 offset0:74 offset1:107
	s_waitcnt lgkmcnt(0)
	v_mul_f32_e32 v15, v12, v16
	v_mul_f32_e32 v16, v13, v17
	v_cvt_pk_bf16_f32 v15, v15, v16
	ds_read2_b32 v[16:17], v31 offset0:140 offset1:173
	s_waitcnt lgkmcnt(0)
	v_mul_f32_e32 v16, v6, v16
	v_mul_f32_e32 v17, v7, v17
	v_cvt_pk_bf16_f32 v16, v16, v17
	ds_read2_b32 v[28:29], v31 offset0:206 offset1:239
	s_waitcnt lgkmcnt(0)
	v_mul_f32_e32 v17, v8, v28
	v_mul_f32_e32 v27, v9, v29
	v_cvt_pk_bf16_f32 v17, v17, v27
.LBB0_1705:
	v_add_u32_e32 v28, 8, v26
	v_ashrrev_i32_e32 v29, 31, v28
	v_lshlrev_b64 v[28:29], 13, v[28:29]
	v_lshl_add_u64 v[28:29], v[24:25], 0, v[28:29]
	global_store_dwordx4 v[28:29], v[14:17], off sc1
	v_add_u32_e32 v28, 16, v26
	s_mov_b64 s[6:7], -1
	s_and_b64 vcc, exec, s[4:5]
	v_ashrrev_i32_e32 v29, 31, v28
	s_cbranch_vccz .LBB0_1707
	v_lshlrev_b64 v[14:15], 13, v[28:29]
	v_lshl_add_u64 v[14:15], v[24:25], 0, v[14:15]
	global_store_dwordx4 v[14:15], v[2:5], off sc1
	s_mov_b64 s[6:7], 0
.LBB0_1707:
	v_mov_b32_e32 v14, 0
	s_andn2_b64 vcc, exec, s[6:7]
	v_mov_b32_e32 v15, 0
	v_mov_b32_e32 v16, 0
	v_mov_b32_e32 v17, 0
	s_cbranch_vccnz .LBB0_1692
	ds_read2_b32 v[14:15], v31 offset0:16 offset1:49
	v_lshlrev_b64 v[28:29], 13, v[28:29]
	v_lshl_add_u64 v[28:29], v[24:25], 0, v[28:29]
	s_waitcnt vmcnt(1) lgkmcnt(0)
	v_mul_f32_e32 v14, v10, v14
	v_mul_f32_e32 v15, v11, v15
	v_cvt_pk_bf16_f32 v14, v14, v15
	ds_read2_b32 v[16:17], v31 offset0:82 offset1:115
	s_waitcnt lgkmcnt(0)
	v_mul_f32_e32 v15, v12, v16
	v_mul_f32_e32 v16, v13, v17
	v_cvt_pk_bf16_f32 v15, v15, v16
	ds_read2_b32 v[16:17], v31 offset0:148 offset1:181
	s_waitcnt lgkmcnt(0)
	v_mul_f32_e32 v16, v6, v16
	v_mul_f32_e32 v17, v7, v17
	v_cvt_pk_bf16_f32 v16, v16, v17
	ds_read2_b32 v[42:43], v31 offset0:214 offset1:247
	s_waitcnt lgkmcnt(0)
	v_mul_f32_e32 v17, v8, v42
	v_mul_f32_e32 v27, v9, v43
	v_cvt_pk_bf16_f32 v17, v17, v27
	ds_read2_b32 v[42:43], v31 offset0:24 offset1:57
	global_store_dwordx4 v[28:29], v[14:17], off sc1
	s_waitcnt lgkmcnt(0)
	v_mul_f32_e32 v10, v10, v42
	v_mul_f32_e32 v11, v11, v43
	v_cvt_pk_bf16_f32 v14, v10, v11
	ds_read2_b32 v[10:11], v31 offset0:90 offset1:123
	s_waitcnt lgkmcnt(0)
	v_mul_f32_e32 v10, v12, v10
	v_mul_f32_e32 v11, v13, v11
	v_cvt_pk_bf16_f32 v15, v10, v11
	ds_read2_b32 v[10:11], v31 offset0:156 offset1:189
	s_waitcnt lgkmcnt(0)
	v_mul_f32_e32 v6, v6, v10
	v_mul_f32_e32 v7, v7, v11
	v_cvt_pk_bf16_f32 v16, v6, v7
	ds_read2_b32 v[6:7], v31 offset0:222 offset1:255
	s_waitcnt lgkmcnt(0)
	v_mul_f32_e32 v6, v8, v6
	v_mul_f32_e32 v7, v9, v7
	v_cvt_pk_bf16_f32 v17, v6, v7
	s_branch .LBB0_1692

; __device__ __forceinline__ unsigned cvt_pk_bf16(float lo, float hi) { unsigned r; asm volatile("v_cvt_pk_bf16_f32 %0, %1, %2" : "=v"(r) : "v"(lo), "v"(hi)); return r; }
;     __device__ __forceinline__ void operator()(const f32x4 (&acc)[2][2][4][2], const Unit& u, int wr, int wc, int fr, int fq) const {
;         const int row0 = u.pm * BM + wr * 64 + fr; int colt = u.pn * BM; bf16_t* base = O;
;         float sc = 1.f; if (split_cols) { const int t = colt / split_cols; base += (size_t)t * split_stride; colt -= t * split_cols; if (t == 0) sc = scale0; }
;         const int col0 = colt + wc * 32 + 8 * fq, bcol0 = u.pn * BM + wc * 32 + 8 * fq;
;         f32x4 bv[2][2];
; #pragma unroll
;         for (int bj = 0; bj < 2; ++bj)
; #pragma unroll
;             for (int n = 0; n < 2; ++n) bv[bj][n] = bias ? *(const f32x4*)(bias + bcol0 + bj * HALF + 4 * n) : (f32x4){0.f, 0.f, 0.f, 0.f};
;     ...
;             for (int m = 0; m < 4; ++m) { bf16_t* rowp = base + (size_t)(row0 + ai * HALF + m * 16) * ldc + col0;
; #pragma unroll
;                 for (int bj = 0; bj < 2; ++bj) { f32x4 v0 = acc[ai][bj][m][0] + bv[bj][0], v1 = acc[ai][bj][m][1] + bv[bj][1];
;                     if (ACT == 1) { f32x2 a = gelu_pk((f32x2){v0[0], v0[1]}), b = gelu_pk((f32x2){v0[2], v0[3]}), c = gelu_pk((f32x2){v1[0], v1[1]}), d = gelu_pk((f32x2){v1[2], v1[3]});
;                         v0 = (f32x4){a.x, a.y, b.x, b.y}; v1 = (f32x4){c.x, c.y, d.x, d.y}; }
;                     v0 = v0 * sc; v1 = v1 * sc; u32x4 w; w.x = cvt_pk_bf16(v0[0], v0[1]); w.y = cvt_pk_bf16(v0[2], v0[3]); w.z = cvt_pk_bf16(v1[0], v1[1]); w.w = cvt_pk_bf16(v1[2], v1[3]);
;                     *(u32x4*)(rowp + bj * HALF) = w; } }
.LBB0_1772:
	v_lshl_add_u32 v146, s22, 8, v142
	v_ashrrev_i32_e32 v147, 31, v146
	v_lshlrev_b64 v[140:141], 13, v[146:147]
	v_lshl_add_u64 v[140:141], v[138:139], 0, v[140:141]
	v_pk_add_f32 v[128:129], v[128:129], 0 op_sel_hi:[1,0]
	v_pk_add_f32 v[126:127], v[126:127], 0 op_sel_hi:[1,0]
	v_pk_add_f32 v[148:149], v[124:125], 0 op_sel_hi:[1,0]
	v_pk_add_f32 v[124:125], v[122:123], 0 op_sel_hi:[1,0]
	v_cvt_pk_bf16_f32 v122, v126, v127
	v_cvt_pk_bf16_f32 v123, v128, v129
	v_pk_add_f32 v[118:119], v[118:119], 0 op_sel_hi:[1,0]
	v_cvt_pk_bf16_f32 v124, v124, v125
	v_cvt_pk_bf16_f32 v125, v148, v149
	global_store_dwordx4 v[140:141], v[122:125], off sc1
	v_pk_add_f32 v[120:121], v[120:121], 0 op_sel_hi:[1,0]
	v_pk_add_f32 v[114:115], v[114:115], 0 op_sel_hi:[1,0]
	v_pk_add_f32 v[122:123], v[112:113], 0 op_sel_hi:[1,0]
	v_pk_add_f32 v[112:113], v[110:111], 0 op_sel_hi:[1,0]
	v_cvt_pk_bf16_f32 v110, v118, v119
	v_cvt_pk_bf16_f32 v111, v120, v121
	v_pk_add_f32 v[102:103], v[102:103], 0 op_sel_hi:[1,0]
	v_cvt_pk_bf16_f32 v112, v112, v113
	v_cvt_pk_bf16_f32 v113, v122, v123
	global_store_dwordx4 v[140:141], v[110:113], off offset:256 sc1
	v_pk_add_f32 v[104:105], v[104:105], 0 op_sel_hi:[1,0]
	v_pk_add_f32 v[98:99], v[98:99], 0 op_sel_hi:[1,0]
	v_or_b32_e32 v110, 16, v146
	v_ashrrev_i32_e32 v111, 31, v110
	v_lshlrev_b64 v[110:111], 13, v[110:111]
	v_lshl_add_u64 v[110:111], v[138:139], 0, v[110:111]
	v_pk_add_f32 v[112:113], v[116:117], 0 op_sel_hi:[1,0]
	v_pk_add_f32 v[116:117], v[108:109], 0 op_sel_hi:[1,0]
	v_pk_add_f32 v[108:109], v[106:107], 0 op_sel_hi:[1,0]
	v_cvt_pk_bf16_f32 v106, v114, v115
	v_cvt_pk_bf16_f32 v107, v112, v113
	v_pk_add_f32 v[86:87], v[86:87], 0 op_sel_hi:[1,0]
	v_cvt_pk_bf16_f32 v108, v108, v109
	v_cvt_pk_bf16_f32 v109, v116, v117
	global_store_dwordx4 v[110:111], v[106:109], off sc1
	v_pk_add_f32 v[88:89], v[88:89], 0 op_sel_hi:[1,0]
	v_pk_add_f32 v[82:83], v[82:83], 0 op_sel_hi:[1,0]
	v_pk_add_f32 v[106:107], v[96:97], 0 op_sel_hi:[1,0]
	v_pk_add_f32 v[96:97], v[94:95], 0 op_sel_hi:[1,0]
	v_cvt_pk_bf16_f32 v94, v102, v103
	v_cvt_pk_bf16_f32 v95, v104, v105
	v_pk_add_f32 v[72:73], v[72:73], 0 op_sel_hi:[1,0]
	v_cvt_pk_bf16_f32 v96, v96, v97
	v_cvt_pk_bf16_f32 v97, v106, v107
	global_store_dwordx4 v[110:111], v[94:97], off offset:256 sc1
	v_pk_add_f32 v[70:71], v[70:71], 0 op_sel_hi:[1,0]
	v_pk_add_f32 v[62:63], v[62:63], 0 op_sel_hi:[1,0]
	v_or_b32_e32 v94, 32, v146
	v_ashrrev_i32_e32 v95, 31, v94
	v_lshlrev_b64 v[94:95], 13, v[94:95]
	v_lshl_add_u64 v[94:95], v[138:139], 0, v[94:95]
	v_pk_add_f32 v[96:97], v[100:101], 0 op_sel_hi:[1,0]
	v_pk_add_f32 v[100:101], v[92:93], 0 op_sel_hi:[1,0]
	v_pk_add_f32 v[92:93], v[90:91], 0 op_sel_hi:[1,0]
	v_cvt_pk_bf16_f32 v90, v98, v99
	v_cvt_pk_bf16_f32 v91, v96, v97
	v_pk_add_f32 v[64:65], v[64:65], 0 op_sel_hi:[1,0]
	v_cvt_pk_bf16_f32 v92, v92, v93
	v_cvt_pk_bf16_f32 v93, v100, v101
	global_store_dwordx4 v[94:95], v[90:93], off sc1
	v_pk_add_f32 v[56:57], v[56:57], 0 op_sel_hi:[1,0]
	v_pk_add_f32 v[54:55], v[54:55], 0 op_sel_hi:[1,0]
	v_pk_add_f32 v[90:91], v[80:81], 0 op_sel_hi:[1,0]
	v_pk_add_f32 v[80:81], v[78:79], 0 op_sel_hi:[1,0]
	v_cvt_pk_bf16_f32 v78, v86, v87
	v_cvt_pk_bf16_f32 v79, v88, v89
	v_pk_add_f32 v[50:51], v[50:51], 0 op_sel_hi:[1,0]
	v_cvt_pk_bf16_f32 v80, v80, v81
	v_cvt_pk_bf16_f32 v81, v90, v91
	global_store_dwordx4 v[94:95], v[78:81], off offset:256 sc1
	v_pk_add_f32 v[40:41], v[40:41], 0 op_sel_hi:[1,0]
	v_pk_add_f32 v[38:39], v[38:39], 0 op_sel_hi:[1,0]
	v_or_b32_e32 v78, 48, v146
	v_ashrrev_i32_e32 v79, 31, v78
	v_lshlrev_b64 v[78:79], 13, v[78:79]
	v_lshl_add_u64 v[78:79], v[138:139], 0, v[78:79]
	v_pk_add_f32 v[80:81], v[84:85], 0 op_sel_hi:[1,0]
	v_pk_add_f32 v[84:85], v[76:77], 0 op_sel_hi:[1,0]
	v_pk_add_f32 v[76:77], v[74:75], 0 op_sel_hi:[1,0]
	v_cvt_pk_bf16_f32 v74, v82, v83
	v_cvt_pk_bf16_f32 v75, v80, v81
	v_pk_add_f32 v[34:35], v[34:35], 0 op_sel_hi:[1,0]
	v_cvt_pk_bf16_f32 v76, v76, v77
; __device__ __forceinline__ unsigned cvt_pk_bf16(float lo, float hi) { unsigned r; asm volatile("v_cvt_pk_bf16_f32 %0, %1, %2" : "=v"(r) : "v"(lo), "v"(hi)); return r; }
;     __device__ __forceinline__ void operator()(const f32x4 (&acc)[2][2][4][2], const Unit& u, int wr, int wc, int fr, int fq) const {
;     ...
;             for (int m = 0; m < 4; ++m) { bf16_t* rowp = base + (size_t)(row0 + ai * HALF + m * 16) * ldc + col0;
; #pragma unroll
;                 for (int bj = 0; bj < 2; ++bj) { f32x4 v0 = acc[ai][bj][m][0] + bv[bj][0], v1 = acc[ai][bj][m][1] + bv[bj][1];
;                     if (ACT == 1) { f32x2 a = gelu_pk((f32x2){v0[0], v0[1]}), b = gelu_pk((f32x2){v0[2], v0[3]}), c = gelu_pk((f32x2){v1[0], v1[1]}), d = gelu_pk((f32x2){v1[2], v1[3]});
;                         v0 = (f32x4){a.x, a.y, b.x, b.y}; v1 = (f32x4){c.x, c.y, d.x, d.y}; }
;                     v0 = v0 * sc; v1 = v1 * sc; u32x4 w; w.x = cvt_pk_bf16(v0[0], v0[1]); w.y = cvt_pk_bf16(v0[2], v0[3]); w.z = cvt_pk_bf16(v1[0], v1[1]); w.w = cvt_pk_bf16(v1[2], v1[3]);
;                     *(u32x4*)(rowp + bj * HALF) = w; } }
	v_cvt_pk_bf16_f32 v77, v84, v85
	global_store_dwordx4 v[78:79], v[74:77], off sc1
	v_pk_add_f32 v[24:25], v[24:25], 0 op_sel_hi:[1,0]
	v_pk_add_f32 v[22:23], v[22:23], 0 op_sel_hi:[1,0]
	v_pk_add_f32 v[74:75], v[68:69], 0 op_sel_hi:[1,0]
	v_pk_add_f32 v[68:69], v[66:67], 0 op_sel_hi:[1,0]
	v_cvt_pk_bf16_f32 v66, v70, v71
	v_cvt_pk_bf16_f32 v67, v72, v73
	v_pk_add_f32 v[18:19], v[18:19], 0 op_sel_hi:[1,0]
	v_cvt_pk_bf16_f32 v68, v68, v69
	v_cvt_pk_bf16_f32 v69, v74, v75
	global_store_dwordx4 v[78:79], v[66:69], off offset:256 sc1
	s_mov_b64 s[22:23], -1
	v_pk_add_f32 v[8:9], v[8:9], 0 op_sel_hi:[1,0]
	v_pk_add_f32 v[68:69], v[60:61], 0 op_sel_hi:[1,0]
	v_pk_add_f32 v[60:61], v[58:59], 0 op_sel_hi:[1,0]
	v_cvt_pk_bf16_f32 v58, v62, v63
	v_add_co_u32_e32 v62, vcc, s55, v140
	v_cvt_pk_bf16_f32 v59, v64, v65
	v_cvt_pk_bf16_f32 v60, v60, v61
	v_cvt_pk_bf16_f32 v61, v68, v69
	v_lshl_add_u64 v[66:67], v[140:141], 0, s[6:7]
	s_nop 0
	v_addc_co_u32_e32 v63, vcc, 0, v141, vcc
	global_store_dwordx4 v[62:63], v[58:61], off sc1
	v_pk_add_f32 v[6:7], v[6:7], 0 op_sel_hi:[1,0]
	s_nop 0
	v_pk_add_f32 v[58:59], v[48:49], 0 op_sel_hi:[1,0]
	v_pk_add_f32 v[48:49], v[46:47], 0 op_sel_hi:[1,0]
	v_cvt_pk_bf16_f32 v46, v54, v55
	v_cvt_pk_bf16_f32 v47, v56, v57
	s_nop 0
	v_cvt_pk_bf16_f32 v48, v48, v49
	v_cvt_pk_bf16_f32 v49, v58, v59
	global_store_dwordx4 v[66:67], v[46:49], off offset:256 sc1
	s_nop 1
	v_pk_add_f32 v[48:49], v[52:53], 0 op_sel_hi:[1,0]
	v_pk_add_f32 v[52:53], v[44:45], 0 op_sel_hi:[1,0]
	v_pk_add_f32 v[44:45], v[42:43], 0 op_sel_hi:[1,0]
	v_cvt_pk_bf16_f32 v42, v50, v51
	v_cvt_pk_bf16_f32 v43, v48, v49
	v_add_co_u32_e32 v48, vcc, s56, v140
	v_cvt_pk_bf16_f32 v44, v44, v45
	v_cvt_pk_bf16_f32 v45, v52, v53
	v_lshl_add_u64 v[46:47], v[140:141], 0, s[14:15]
	s_nop 0
	v_addc_co_u32_e32 v49, vcc, 0, v141, vcc
	global_store_dwordx4 v[48:49], v[42:45], off sc1
	s_nop 1
	v_pk_add_f32 v[42:43], v[32:33], 0 op_sel_hi:[1,0]
	v_pk_add_f32 v[32:33], v[30:31], 0 op_sel_hi:[1,0]
	v_cvt_pk_bf16_f32 v30, v38, v39
	v_cvt_pk_bf16_f32 v31, v40, v41
	s_nop 0
	v_cvt_pk_bf16_f32 v32, v32, v33
	v_cvt_pk_bf16_f32 v33, v42, v43
	global_store_dwordx4 v[46:47], v[30:33], off offset:256 sc1
	s_nop 1
	v_pk_add_f32 v[32:33], v[36:37], 0 op_sel_hi:[1,0]
	v_pk_add_f32 v[36:37], v[28:29], 0 op_sel_hi:[1,0]
	v_pk_add_f32 v[28:29], v[26:27], 0 op_sel_hi:[1,0]
	v_cvt_pk_bf16_f32 v26, v34, v35
	v_cvt_pk_bf16_f32 v27, v32, v33
	v_add_co_u32_e32 v32, vcc, s57, v140
	v_cvt_pk_bf16_f32 v28, v28, v29
	v_cvt_pk_bf16_f32 v29, v36, v37
	v_lshl_add_u64 v[30:31], v[140:141], 0, s[16:17]
	s_nop 0
	v_addc_co_u32_e32 v33, vcc, 0, v141, vcc
	global_store_dwordx4 v[32:33], v[26:29], off sc1
	s_nop 1
	v_pk_add_f32 v[26:27], v[16:17], 0 op_sel_hi:[1,0]
	v_pk_add_f32 v[16:17], v[14:15], 0 op_sel_hi:[1,0]
	v_cvt_pk_bf16_f32 v14, v22, v23
	v_cvt_pk_bf16_f32 v15, v24, v25
	s_nop 0
	v_cvt_pk_bf16_f32 v16, v16, v17
	v_cvt_pk_bf16_f32 v17, v26, v27
	global_store_dwordx4 v[30:31], v[14:17], off offset:256 sc1
	s_nop 1
	v_pk_add_f32 v[16:17], v[20:21], 0 op_sel_hi:[1,0]
	v_pk_add_f32 v[20:21], v[12:13], 0 op_sel_hi:[1,0]
	v_pk_add_f32 v[12:13], v[10:11], 0 op_sel_hi:[1,0]
	v_cvt_pk_bf16_f32 v10, v18, v19
	v_cvt_pk_bf16_f32 v11, v16, v17
	v_add_co_u32_e32 v16, vcc, s58, v140
	v_lshl_add_u64 v[14:15], v[140:141], 0, s[18:19]
	s_nop 0
	v_addc_co_u32_e32 v17, vcc, 0, v141, vcc
	v_cvt_pk_bf16_f32 v12, v12, v13
	v_cvt_pk_bf16_f32 v13, v20, v21
	global_store_dwordx4 v[16:17], v[10:13], off sc1
	s_andn2_b64 vcc, exec, s[20:21]
	s_nop 0
	v_pk_add_f32 v[10:11], v[4:5], 0 op_sel_hi:[1,0]
	v_pk_add_f32 v[4:5], v[2:3], 0 op_sel_hi:[1,0]
	v_cvt_pk_bf16_f32 v2, v6, v7
	v_cvt_pk_bf16_f32 v3, v8, v9
	s_nop 0
	v_cvt_pk_bf16_f32 v4, v4, v5
	v_cvt_pk_bf16_f32 v5, v10, v11
	global_store_dwordx4 v[14:15], v[2:5], off offset:256 sc1
	s_cbranch_vccnz .LBB0_1739
	s_andn2_b64 vcc, exec, s[8:9]
	s_cbranch_vccnz .LBB0_1738
	s_barrier
	s_branch .LBB0_1738

; __device__ __forceinline__ float bflo(unsigned w) { return __uint_as_float(w << 16); }
; __device__ __forceinline__ float bfhi(unsigned w) { return __uint_as_float(w & 0xffff0000u); }
; __device__ __forceinline__ unsigned f2bf(float f) { unsigned u = __float_as_uint(f); return (u + 0x7fffu + ((u >> 16) & 1u)) >> 16; }
; __device__ __forceinline__ int crow(int r, int hi) { return (r & 3) + 8 * (r >> 2) + 4 * hi; }
; __device__ __forceinline__ int v_st(int k, int c) { const int kk = (k & ~0xC) | ((k & 4) << 1) | ((k & 8) >> 1); return ((kk >> 3) * 4 + (c >> 5)) * 512 + ((kk & 7) * 32 + (c & 31)) * 2; }
; __device__ __forceinline__ void hg_mfma(Frame& F, bf16* Y, int u, unsigned* prog = nullptr) {
;     ...
;       for (int r = 0; r < 16; ++r) { const int d = 32 * dblk + crow(r, hi);
;         *(bf16*)(lds + HG_S + (d >> 6) * 16384 + v_st(d & 63, 32 * vblk0 + r32)) = (bf16)f2bf(Sa[r]);
;         *(bf16*)(lds + HG_S + (d >> 6) * 16384 + v_st(d & 63, 32 * (vblk0 + 1) + r32)) = (bf16)f2bf(Sb[r]); }
;       { const int t = tid >> 3, seg = tid & 7; const size_t row = row0 + (size_t)c * 64 + t;
;         const v4u oa = *(const v4u*)(lds + HG_O + t * 272 + seg * 32), ob = *(const v4u*)(lds + HG_O + t * 272 + seg * 32 + 16);
;         const unsigned ow[8] = {oa.x, oa.y, oa.z, oa.w, ob.x, ob.y, ob.z, ob.w}, gw[8] = {ga.x, ga.y, ga.z, ga.w, gb.x, gb.y, gb.z, gb.w};
;         float ss = 0.f;
; #pragma unroll
;         for (int i = 0; i < 8; ++i) { const float a = bflo(ow[i]), bq = bfhi(ow[i]); ss += a * a + bq * bq; }
;         ss += __shfl_xor(ss, 1); ss += __shfl_xor(ss, 2); ss += __shfl_xor(ss, 4);
.LBB0_1784:
	s_or_b64 exec, exec, s[52:53]
	v_bfe_u32 v34, v18, 16, 1
	v_add3_u32 v34, v18, v34, s57
	ds_write_b16_d16_hi v170, v34
	s_nop 3
	v_bfe_u32 v34, v2, 16, 1
	v_add3_u32 v34, v2, v34, s57
	ds_write_b16_d16_hi v171, v34
	v_bfe_u32 v34, v19, 16, 1
	v_add3_u32 v34, v19, v34, s57
	ds_write_b16_d16_hi v170, v34 offset:64
	v_bfe_u32 v34, v3, 16, 1
	v_add3_u32 v34, v3, v34, s57
	ds_write_b16_d16_hi v171, v34 offset:64
	v_bfe_u32 v34, v20, 16, 1
	v_add3_u32 v34, v20, v34, s57
	ds_write_b16_d16_hi v172, v34 offset:128
	v_bfe_u32 v34, v4, 16, 1
	v_add3_u32 v34, v4, v34, s57
	ds_write_b16_d16_hi v173, v34 offset:128
	v_bfe_u32 v34, v21, 16, 1
	v_add3_u32 v34, v21, v34, s57
	ds_write_b16_d16_hi v174, v34 offset:192
	v_bfe_u32 v34, v5, 16, 1
	v_add3_u32 v34, v5, v34, s57
	ds_write_b16_d16_hi v175, v34 offset:192
	v_bfe_u32 v34, v22, 16, 1
	v_add3_u32 v34, v22, v34, s57
	ds_write_b16_d16_hi v176, v34
	v_bfe_u32 v34, v6, 16, 1
	v_add3_u32 v34, v6, v34, s57
	ds_write_b16_d16_hi v177, v34
	v_bfe_u32 v34, v23, 16, 1
	v_add3_u32 v34, v23, v34, s57
	ds_write_b16_d16_hi v178, v34 offset:64
	v_bfe_u32 v34, v7, 16, 1
	v_add3_u32 v34, v7, v34, s57
	ds_write_b16_d16_hi v179, v34 offset:64
	v_bfe_u32 v34, v24, 16, 1
	v_add3_u32 v34, v24, v34, s57
	ds_write_b16_d16_hi v180, v34 offset:128
	v_bfe_u32 v34, v8, 16, 1
	v_add3_u32 v34, v8, v34, s57
	ds_write_b16_d16_hi v181, v34 offset:128
	v_bfe_u32 v34, v25, 16, 1
	v_add3_u32 v34, v25, v34, s57
	ds_write_b16_d16_hi v182, v34 offset:192
	v_bfe_u32 v34, v9, 16, 1
	v_add3_u32 v34, v9, v34, s57
	ds_write_b16_d16_hi v183, v34 offset:192
	v_bfe_u32 v34, v26, 16, 1
	v_add3_u32 v34, v26, v34, s57
	ds_write_b16_d16_hi v184, v34
	v_bfe_u32 v34, v10, 16, 1
	v_add3_u32 v34, v10, v34, s57
	ds_write_b16_d16_hi v185, v34
	v_bfe_u32 v34, v27, 16, 1
	v_add3_u32 v34, v27, v34, s57
	ds_write_b16_d16_hi v186, v34 offset:64
	v_bfe_u32 v34, v11, 16, 1
	v_add3_u32 v34, v11, v34, s57
	ds_write_b16_d16_hi v187, v34 offset:64
	v_bfe_u32 v34, v28, 16, 1
	v_add3_u32 v34, v28, v34, s57
	ds_write_b16_d16_hi v188, v34 offset:128
	v_bfe_u32 v34, v12, 16, 1
	v_add3_u32 v34, v12, v34, s57
	ds_write_b16_d16_hi v189, v34 offset:128
	v_bfe_u32 v34, v29, 16, 1
	v_add3_u32 v34, v29, v34, s57
	ds_write_b16_d16_hi v190, v34 offset:192
	v_bfe_u32 v34, v13, 16, 1
	v_add3_u32 v34, v13, v34, s57
	ds_write_b16_d16_hi v191, v34 offset:192
	v_bfe_u32 v34, v30, 16, 1
	v_add3_u32 v34, v30, v34, s57
	ds_write_b16_d16_hi v192, v34
	v_bfe_u32 v34, v14, 16, 1
	v_add3_u32 v34, v14, v34, s57
	ds_write_b16_d16_hi v193, v34
	v_bfe_u32 v34, v31, 16, 1
	v_add3_u32 v34, v31, v34, s57
	ds_write_b16_d16_hi v194, v34 offset:64
	v_bfe_u32 v34, v15, 16, 1
	v_add3_u32 v34, v15, v34, s57
	ds_write_b16_d16_hi v195, v34 offset:64
	v_bfe_u32 v34, v32, 16, 1
	v_add3_u32 v34, v32, v34, s57
	ds_write_b16_d16_hi v196, v34 offset:128
	v_bfe_u32 v34, v16, 16, 1
	v_add3_u32 v34, v16, v34, s57
	ds_write_b16_d16_hi v197, v34 offset:128
	v_bfe_u32 v34, v33, 16, 1
	v_add3_u32 v34, v33, v34, s57
	ds_write_b16_d16_hi v198, v34 offset:192
	v_bfe_u32 v34, v17, 16, 1
	v_add3_u32 v34, v17, v34, s57
	v_and_b32_e32 v35, 64, v203
	ds_write_b16_d16_hi v199, v34 offset:192
	v_xor_b32_e32 v34, 1, v203
	v_add_u32_e32 v35, 64, v35
	v_cmp_lt_i32_e32 vcc, v34, v35
	s_waitcnt vmcnt(0)
	v_lshlrev_b32_e32 v40, 16, v64
	v_mul_f32_e32 v38, 0xbfb8aa3b, v40
	v_cndmask_b32_e32 v34, v203, v34, vcc
	v_lshlrev_b32_e32 v37, 2, v34
	v_xor_b32_e32 v34, 2, v203
	v_cmp_lt_i32_e32 vcc, v34, v35
	ds_read_b128 v[46:49], v200 offset:16
	v_exp_f32_e32 v42, v38
	v_cndmask_b32_e32 v34, v203, v34, vcc
	v_lshlrev_b32_e32 v45, 2, v34
	v_xor_b32_e32 v34, 4, v203
	v_cmp_lt_i32_e32 vcc, v34, v35
	v_lshlrev_b32_e32 v72, 16, v63
	v_mul_f32_e32 v73, 0xbfb8aa3b, v72
	v_cndmask_b32_e32 v34, v203, v34, vcc
	v_lshlrev_b32_e32 v79, 2, v34
	v_lshlrev_b32_e32 v34, 16, v65
	v_add_f32_e32 v42, 1.0, v42
	v_exp_f32_e32 v74, v73
	v_mul_f32_e32 v35, 0xbfb8aa3b, v34
	s_waitcnt lgkmcnt(0)
	v_and_b32_e32 v39, 0xffff0000, v49
	v_rcp_f32_e32 v44, v42
	v_and_b32_e32 v43, 0xffff0000, v48
	v_and_b32_e32 v42, 0xffff0000, v64
	v_lshlrev_b32_e32 v76, 16, v62
	v_exp_f32_e32 v36, v35
	v_lshlrev_b32_e32 v35, 16, v49
	v_and_b32_e32 v38, 0xffff0000, v65
	v_lshlrev_b32_e32 v41, 16, v48
	v_mul_f32_e32 v48, 0xbfb8aa3b, v42
	v_mov_b32_e32 v64, v39
	v_mov_b32_e32 v65, v43
	v_lshlrev_b32_e32 v73, 16, v47
	v_and_b32_e32 v75, 0xffff0000, v47
	v_mul_f32_e32 v47, 0xbfb8aa3b, v76
	v_exp_f32_e32 v206, v48
	v_mov_b32_e32 v48, v35
	v_mov_b32_e32 v49, v41
	v_pk_mul_f32 v[64:65], v[64:65], v[64:65]
	v_exp_f32_e32 v47, v47
	v_lshlrev_b32_e32 v82, 16, v61
	v_pk_fma_f32 v[48:49], v[48:49], v[48:49], v[64:65]
	v_add_f32_e32 v64, 1.0, v74
	v_and_b32_e32 v74, 0xffff0000, v63
	v_mul_f32_e32 v83, 0xbfb8aa3b, v82
	v_mul_f32_e32 v63, 0xbfb8aa3b, v74
	v_exp_f32_e32 v84, v83
	v_exp_f32_e32 v65, v63
	v_and_b32_e32 v63, 0xffff0000, v46
	v_and_b32_e32 v62, 0xffff0000, v62
	v_lshlrev_b32_e32 v77, 16, v46
	v_add_f32_e32 v47, 1.0, v47
	v_mul_f32_e32 v46, 0xbfb8aa3b, v62
	v_mov_b32_e32 v80, v75
	v_mov_b32_e32 v81, v63
	v_rcp_f32_e32 v78, v47
	v_exp_f32_e32 v207, v46
	v_mov_b32_e32 v46, v73
	v_mov_b32_e32 v47, v77
	v_pk_mul_f32 v[80:81], v[80:81], v[80:81]
	v_lshlrev_b32_e32 v86, 16, v60
	v_pk_fma_f32 v[46:47], v[46:47], v[46:47], v[80:81]
	v_add_f32_e32 v80, 1.0, v84
	v_and_b32_e32 v84, 0xffff0000, v61
	v_mul_f32_e32 v61, 0xbfb8aa3b, v86
	v_exp_f32_e32 v61, v61
	ds_read_b128 v[66:69], v200
	ds_read_b64 v[70:71], v147
	v_and_b32_e32 v60, 0xffff0000, v60
	v_and_b32_e32 v94, 0xffff0000, v58
	v_add_f32_e32 v61, 1.0, v61
	s_waitcnt lgkmcnt(1)
; __device__ __forceinline__ float bflo(unsigned w) { return __uint_as_float(w << 16); }
; __device__ __forceinline__ float bfhi(unsigned w) { return __uint_as_float(w & 0xffff0000u); }
; __device__ __forceinline__ float siluf_(float x) { return x * __builtin_amdgcn_rcpf(1.0f + __expf(-x)); }
; __device__ __forceinline__ unsigned cvtpk(float lo, float hi) { unsigned r; asm volatile("v_cvt_pk_bf16_f32 %0, %1, %2" : "=v"(r) : "v"(lo), "v"(hi)); return r; }
; __device__ __forceinline__ void hg_mfma(Frame& F, bf16* Y, int u, unsigned* prog = nullptr) {
;     ...
;       { const int t = tid >> 3, seg = tid & 7; const size_t row = row0 + (size_t)c * 64 + t;
;         const v4u oa = *(const v4u*)(lds + HG_O + t * 272 + seg * 32), ob = *(const v4u*)(lds + HG_O + t * 272 + seg * 32 + 16);
;         const unsigned ow[8] = {oa.x, oa.y, oa.z, oa.w, ob.x, ob.y, ob.z, ob.w}, gw[8] = {ga.x, ga.y, ga.z, ga.w, gb.x, gb.y, gb.z, gb.w};
;         float ss = 0.f;
; #pragma unroll
;         for (int i = 0; i < 8; ++i) { const float a = bflo(ow[i]), bq = bfhi(ow[i]); ss += a * a + bq * bq; }
;         ss += __shfl_xor(ss, 1); ss += __shfl_xor(ss, 2); ss += __shfl_xor(ss, 4);
;         const float rstd = rsqrtf(ss * (1.f / 128.f) + NORM_EPS);
;         unsigned yw[8]; const float* gnl = (const float*)(lds + HG_GN) + seg * 16;
; #pragma unroll
;         for (int i = 0; i < 8; ++i) { const v2f g2 = *(const v2f*)(gnl + 2 * i); const float gx = g2.x, gy = g2.y;
;           yw[i] = at::cvtpk(bflo(ow[i]) * rstd * gx * siluf_(bflo(gw[i])), bfhi(ow[i]) * rstd * gy * siluf_(bfhi(gw[i]))); }
;         v4u y0, y1; y0.x = yw[0]; y0.y = yw[1]; y0.z = yw[2]; y0.w = yw[3]; y1.x = yw[4]; y1.y = yw[5]; y1.z = yw[6]; y1.w = yw[7];
;         *(v4u*)(Y + row * DM + hd * 128 + seg * 16) = y0; *(v4u*)(Y + row * DM + hd * 128 + seg * 16 + 8) = y1; }
	v_and_b32_e32 v85, 0xffff0000, v69
	v_rcp_f32_e32 v88, v61
	v_and_b32_e32 v61, 0xffff0000, v68
	v_lshlrev_b32_e32 v83, 16, v69
	v_mul_f32_e32 v69, 0xbfb8aa3b, v84
	v_lshlrev_b32_e32 v87, 16, v68
	v_mul_f32_e32 v68, 0xbfb8aa3b, v60
	v_mov_b32_e32 v90, v85
	v_mov_b32_e32 v91, v61
	v_exp_f32_e32 v81, v69
	v_exp_f32_e32 v89, v68
	v_mov_b32_e32 v68, v83
	v_mov_b32_e32 v69, v87
	v_pk_mul_f32 v[90:91], v[90:91], v[90:91]
	v_and_b32_e32 v95, 0xffff0000, v66
	v_pk_fma_f32 v[68:69], v[68:69], v[68:69], v[90:91]
	v_lshlrev_b32_e32 v91, 16, v67
	v_and_b32_e32 v67, 0xffff0000, v67
	v_lshlrev_b32_e32 v93, 16, v66
	v_mov_b32_e32 v204, v95
	v_mov_b32_e32 v205, v67
	v_mov_b32_e32 v96, v93
	v_mov_b32_e32 v97, v91
	v_pk_mul_f32 v[204:205], v[204:205], v[204:205]
	v_lshlrev_b32_e32 v90, 16, v59
	v_pk_fma_f32 v[96:97], v[96:97], v[96:97], v[204:205]
	v_mul_f32_e32 v92, 0xbfb8aa3b, v90
	v_add_f32_e32 v66, v96, v97
	v_add_f32_e32 v66, v69, v66
	v_add_f32_e32 v66, v68, v66
	v_add_f32_e32 v47, v47, v66
	v_add_f32_e32 v46, v46, v47
	v_add_f32_e32 v46, v49, v46
	v_add_f32_e32 v46, v48, v46
	ds_bpermute_b32 v37, v37, v46
	v_exp_f32_e32 v92, v92
	v_and_b32_e32 v66, 0xffff0000, v59
	v_rcp_f32_e32 v80, v80
	v_rcp_f32_e32 v64, v64
	s_waitcnt lgkmcnt(0)
	v_add_f32_e32 v37, v46, v37
	ds_bpermute_b32 v45, v45, v37
	v_add_f32_e32 v47, 1.0, v92
	v_rcp_f32_e32 v48, v47
	v_mul_f32_e32 v47, 0xbfb8aa3b, v66
	v_lshlrev_b32_e32 v92, 16, v58
	s_waitcnt lgkmcnt(0)
	v_add_f32_e32 v37, v37, v45
	ds_bpermute_b32 v45, v79, v37
	v_mul_f32_e32 v46, 0xbfb8aa3b, v92
	v_exp_f32_e32 v49, v47
	v_mul_f32_e32 v47, 0xbfb8aa3b, v94
	v_exp_f32_e32 v46, v46
	s_waitcnt lgkmcnt(0)
	v_add_f32_e32 v37, v37, v45
	v_fmamk_f32 v37, v37, 0x3c000000, v201
	v_exp_f32_e32 v47, v47
	v_mul_f32_e32 v45, 0x4b800000, v37
	v_cmp_gt_f32_e32 vcc, s54, v37
	v_add_f32_e32 v46, 1.0, v46
	v_rcp_f32_e32 v68, v46
	v_cndmask_b32_e32 v37, v37, v45, vcc
	v_rsq_f32_e32 v37, v37
	v_add_f32_e32 v45, 1.0, v47
	v_rcp_f32_e32 v46, v45
	v_add_f32_e32 v36, 1.0, v36
	v_mul_f32_e32 v45, 0x45800000, v37
	v_cndmask_b32_e32 v69, v37, v45, vcc
	v_mov_b32_e32 v47, v69
	v_pk_mul_f32 v[58:59], v[68:69], v[92:93]
	v_pk_mul_f32 v[46:47], v[46:47], v[94:95]
	v_mul_f32_e32 v37, v70, v59
	v_mul_f32_e32 v45, v71, v47
	v_mul_f32_e32 v37, v58, v37
	v_mul_f32_e32 v45, v46, v45
	v_cvt_pk_bf16_f32 v46, v37, v45
	ds_read_b64 v[58:59], v147 offset:8
	v_add_f32_e32 v37, 1.0, v49
	v_rcp_f32_e32 v70, v37
	v_mov_b32_e32 v49, v69
	v_pk_mul_f32 v[48:49], v[48:49], v[90:91]
	v_mov_b32_e32 v71, v69
	s_waitcnt lgkmcnt(0)
	v_mul_f32_e32 v37, v58, v49
	v_mul_f32_e32 v37, v48, v37
	v_pk_mul_f32 v[48:49], v[70:71], v[66:67]
	v_mov_b32_e32 v79, v69
	v_mul_f32_e32 v45, v59, v49
	v_mul_f32_e32 v45, v48, v45
	v_cvt_pk_bf16_f32 v47, v37, v45
	ds_read_b64 v[48:49], v147 offset:16
	v_add_f32_e32 v37, 1.0, v89
	v_rcp_f32_e32 v58, v37
	v_mov_b32_e32 v89, v69
	v_pk_mul_f32 v[66:67], v[88:89], v[86:87]
	v_mov_b32_e32 v59, v69
	s_waitcnt lgkmcnt(0)
	v_mul_f32_e32 v37, v48, v67
	v_pk_mul_f32 v[58:59], v[58:59], v[60:61]
	v_mul_f32_e32 v37, v66, v37
	v_mul_f32_e32 v45, v49, v59
	v_mul_f32_e32 v45, v58, v45
	v_cvt_pk_bf16_f32 v48, v37, v45
	ds_read_b64 v[58:59], v147 offset:24
	v_add_f32_e32 v37, 1.0, v81
	v_rcp_f32_e32 v60, v37
	v_mov_b32_e32 v81, v69
	v_pk_mul_f32 v[66:67], v[80:81], v[82:83]
	v_mov_b32_e32 v61, v69
	s_waitcnt lgkmcnt(0)
	v_mul_f32_e32 v37, v58, v67
	v_pk_mul_f32 v[60:61], v[60:61], v[84:85]
	v_mul_f32_e32 v37, v66, v37
	v_mul_f32_e32 v45, v59, v61
	v_mul_f32_e32 v45, v60, v45
	v_cvt_pk_bf16_f32 v49, v37, v45
	ds_read_b64 v[58:59], v147 offset:32
	v_add_f32_e32 v37, 1.0, v207
	v_rcp_f32_e32 v60, v37
	v_pk_mul_f32 v[66:67], v[78:79], v[76:77]
	v_mov_b32_e32 v61, v69
	s_waitcnt lgkmcnt(0)
	v_mul_f32_e32 v37, v58, v67
	v_pk_mul_f32 v[60:61], v[60:61], v[62:63]
	v_mul_f32_e32 v37, v66, v37
	v_mul_f32_e32 v45, v59, v61
	v_mul_f32_e32 v45, v60, v45
	v_cvt_pk_bf16_f32 v58, v37, v45
	v_add_f32_e32 v37, 1.0, v65
	ds_read_b64 v[60:61], v147 offset:40
	v_rcp_f32_e32 v62, v37
	v_mov_b32_e32 v65, v69
	v_mov_b32_e32 v63, v69
	v_pk_mul_f32 v[64:65], v[64:65], v[72:73]
	v_pk_mul_f32 v[62:63], v[62:63], v[74:75]
	s_waitcnt lgkmcnt(0)
	v_mul_f32_e32 v37, v60, v65
	v_mul_f32_e32 v45, v61, v63
	v_mul_f32_e32 v37, v64, v37
	v_mul_f32_e32 v45, v62, v45
	v_cvt_pk_bf16_f32 v59, v37, v45
	ds_read_b64 v[60:61], v147 offset:48
	v_add_f32_e32 v37, 1.0, v206
	v_rcp_f32_e32 v62, v37
	v_mov_b32_e32 v45, v69
	v_pk_mul_f32 v[40:41], v[44:45], v[40:41]
	v_mov_b32_e32 v63, v69
	s_waitcnt lgkmcnt(0)
	v_mul_f32_e32 v37, v60, v41
	v_mul_f32_e32 v37, v40, v37
	v_pk_mul_f32 v[40:41], v[62:63], v[42:43]
	v_rcp_f32_e32 v36, v36
	v_mul_f32_e32 v41, v61, v41
	v_mul_f32_e32 v40, v40, v41
	v_mul_f32_e32 v41, 0xbfb8aa3b, v38
	v_exp_f32_e32 v42, v41
	v_cvt_pk_bf16_f32 v60, v37, v40
	ds_read_b64 v[40:41], v147 offset:56
	v_mov_b32_e32 v37, v69
	v_add_f32_e32 v42, 1.0, v42
	v_rcp_f32_e32 v68, v42
	v_pk_mul_f32 v[34:35], v[36:37], v[34:35]
	s_add_u32 s72, s72, 0x200000
	s_waitcnt lgkmcnt(0)
	v_mul_f32_e32 v35, v40, v35
	v_mul_f32_e32 v36, v34, v35
	v_pk_mul_f32 v[34:35], v[68:69], v[38:39]
	s_addc_u32 s73, s73, 0
	v_mul_f32_e32 v35, v41, v35
	s_add_i32 s1, s1, 1
	s_mov_b64 s[52:53], 0x80000
	v_mul_f32_e32 v34, v34, v35
	v_cvt_pk_bf16_f32 v61, v36, v34
	global_store_dwordx4 v[106:107], v[46:49], off sc1
	global_store_dwordx4 v[106:107], v[58:61], off offset:16 sc1
	s_cmp_lg_u32 s72, 0x4000000
	v_lshl_add_u64 v[106:107], v[106:107], 0, s[52:53]
	s_cbranch_scc0 .LBB0_1798

; __device__ __forceinline__ unsigned cvt_pk_bf16(float lo, float hi) { unsigned r; asm volatile("v_cvt_pk_bf16_f32 %0, %1, %2" : "=v"(r) : "v"(lo), "v"(hi)); return r; }
;     __device__ __forceinline__ void operator()(const f32x4 (&acc)[2][2][4][2], const Unit& u, int wr, int wc, int fr, int fq) const {
;         const int row0 = u.pm * BM + wr * 64 + fr; int colt = u.pn * BM; bf16_t* base = O;
;         float sc = 1.f; if (split_cols) { const int t = colt / split_cols; base += (size_t)t * split_stride; colt -= t * split_cols; if (t == 0) sc = scale0; }
;         const int col0 = colt + wc * 32 + 8 * fq, bcol0 = u.pn * BM + wc * 32 + 8 * fq;
;         f32x4 bv[2][2];
; #pragma unroll
;         for (int bj = 0; bj < 2; ++bj)
; #pragma unroll
;             for (int n = 0; n < 2; ++n) bv[bj][n] = bias ? *(const f32x4*)(bias + bcol0 + bj * HALF + 4 * n) : (f32x4){0.f, 0.f, 0.f, 0.f};
;     ...
;             for (int m = 0; m < 4; ++m) { bf16_t* rowp = base + (size_t)(row0 + ai * HALF + m * 16) * ldc + col0;
; #pragma unroll
;                 for (int bj = 0; bj < 2; ++bj) { f32x4 v0 = acc[ai][bj][m][0] + bv[bj][0], v1 = acc[ai][bj][m][1] + bv[bj][1];
;                     if (ACT == 1) { f32x2 a = gelu_pk((f32x2){v0[0], v0[1]}), b = gelu_pk((f32x2){v0[2], v0[3]}), c = gelu_pk((f32x2){v1[0], v1[1]}), d = gelu_pk((f32x2){v1[2], v1[3]});
;                         v0 = (f32x4){a.x, a.y, b.x, b.y}; v1 = (f32x4){c.x, c.y, d.x, d.y}; }
;                     v0 = v0 * sc; v1 = v1 * sc; u32x4 w; w.x = cvt_pk_bf16(v0[0], v0[1]); w.y = cvt_pk_bf16(v0[2], v0[3]); w.z = cvt_pk_bf16(v1[0], v1[1]); w.w = cvt_pk_bf16(v1[2], v1[3]);
;                     *(u32x4*)(rowp + bj * HALF) = w; } }
.LBB0_1871:
	v_lshl_add_u32 v160, s28, 8, v153
	v_lshl_or_b32 v146, s56, 8, v155
	v_ashrrev_i32_e32 v147, 31, v146
	v_ashrrev_i32_e32 v161, 31, v160
	v_lshl_add_u64 v[162:163], v[146:147], 1, s[4:5]
	v_lshlrev_b64 v[146:147], 13, v[160:161]
	v_lshl_add_u64 v[146:147], v[162:163], 0, v[146:147]
	v_pk_add_f32 v[128:129], v[128:129], 0 op_sel_hi:[1,0]
	v_pk_add_f32 v[126:127], v[126:127], 0 op_sel_hi:[1,0]
	v_pk_add_f32 v[164:165], v[124:125], 0 op_sel_hi:[1,0]
	v_pk_add_f32 v[124:125], v[122:123], 0 op_sel_hi:[1,0]
	v_cvt_pk_bf16_f32 v122, v126, v127
	v_cvt_pk_bf16_f32 v123, v128, v129
	v_pk_add_f32 v[118:119], v[118:119], 0 op_sel_hi:[1,0]
	v_cvt_pk_bf16_f32 v124, v124, v125
	v_cvt_pk_bf16_f32 v125, v164, v165
	global_store_dwordx4 v[146:147], v[122:125], off sc1
	v_pk_add_f32 v[120:121], v[120:121], 0 op_sel_hi:[1,0]
	v_pk_add_f32 v[114:115], v[114:115], 0 op_sel_hi:[1,0]
	v_pk_add_f32 v[122:123], v[112:113], 0 op_sel_hi:[1,0]
	v_pk_add_f32 v[112:113], v[110:111], 0 op_sel_hi:[1,0]
	v_cvt_pk_bf16_f32 v110, v118, v119
	v_cvt_pk_bf16_f32 v111, v120, v121
	v_pk_add_f32 v[102:103], v[102:103], 0 op_sel_hi:[1,0]
	v_cvt_pk_bf16_f32 v112, v112, v113
	v_cvt_pk_bf16_f32 v113, v122, v123
	global_store_dwordx4 v[146:147], v[110:113], off offset:256 sc1
	v_pk_add_f32 v[104:105], v[104:105], 0 op_sel_hi:[1,0]
	v_pk_add_f32 v[98:99], v[98:99], 0 op_sel_hi:[1,0]
	v_or_b32_e32 v110, 16, v160
	v_ashrrev_i32_e32 v111, 31, v110
	v_lshlrev_b64 v[110:111], 13, v[110:111]
	v_lshl_add_u64 v[110:111], v[162:163], 0, v[110:111]
	v_pk_add_f32 v[112:113], v[116:117], 0 op_sel_hi:[1,0]
	v_pk_add_f32 v[116:117], v[108:109], 0 op_sel_hi:[1,0]
	v_pk_add_f32 v[108:109], v[106:107], 0 op_sel_hi:[1,0]
	v_cvt_pk_bf16_f32 v106, v114, v115
	v_cvt_pk_bf16_f32 v107, v112, v113
	v_pk_add_f32 v[86:87], v[86:87], 0 op_sel_hi:[1,0]
	v_cvt_pk_bf16_f32 v108, v108, v109
	v_cvt_pk_bf16_f32 v109, v116, v117
	global_store_dwordx4 v[110:111], v[106:109], off sc1
	v_pk_add_f32 v[88:89], v[88:89], 0 op_sel_hi:[1,0]
	v_pk_add_f32 v[82:83], v[82:83], 0 op_sel_hi:[1,0]
	v_pk_add_f32 v[106:107], v[96:97], 0 op_sel_hi:[1,0]
	v_pk_add_f32 v[96:97], v[94:95], 0 op_sel_hi:[1,0]
	v_cvt_pk_bf16_f32 v94, v102, v103
	v_cvt_pk_bf16_f32 v95, v104, v105
	v_pk_add_f32 v[72:73], v[72:73], 0 op_sel_hi:[1,0]
	v_cvt_pk_bf16_f32 v96, v96, v97
	v_cvt_pk_bf16_f32 v97, v106, v107
	global_store_dwordx4 v[110:111], v[94:97], off offset:256 sc1
	v_pk_add_f32 v[70:71], v[70:71], 0 op_sel_hi:[1,0]
	v_pk_add_f32 v[62:63], v[62:63], 0 op_sel_hi:[1,0]
	v_or_b32_e32 v94, 32, v160
	v_ashrrev_i32_e32 v95, 31, v94
	v_lshlrev_b64 v[94:95], 13, v[94:95]
	v_lshl_add_u64 v[94:95], v[162:163], 0, v[94:95]
	v_pk_add_f32 v[96:97], v[100:101], 0 op_sel_hi:[1,0]
	v_pk_add_f32 v[100:101], v[92:93], 0 op_sel_hi:[1,0]
	v_pk_add_f32 v[92:93], v[90:91], 0 op_sel_hi:[1,0]
	v_cvt_pk_bf16_f32 v90, v98, v99
	v_cvt_pk_bf16_f32 v91, v96, v97
	v_pk_add_f32 v[64:65], v[64:65], 0 op_sel_hi:[1,0]
	v_cvt_pk_bf16_f32 v92, v92, v93
	v_cvt_pk_bf16_f32 v93, v100, v101
	global_store_dwordx4 v[94:95], v[90:93], off sc1
	v_pk_add_f32 v[56:57], v[56:57], 0 op_sel_hi:[1,0]
	v_pk_add_f32 v[54:55], v[54:55], 0 op_sel_hi:[1,0]
	v_pk_add_f32 v[90:91], v[80:81], 0 op_sel_hi:[1,0]
	v_pk_add_f32 v[80:81], v[78:79], 0 op_sel_hi:[1,0]
	v_cvt_pk_bf16_f32 v78, v86, v87
	v_cvt_pk_bf16_f32 v79, v88, v89
	v_pk_add_f32 v[50:51], v[50:51], 0 op_sel_hi:[1,0]
	v_cvt_pk_bf16_f32 v80, v80, v81
	v_cvt_pk_bf16_f32 v81, v90, v91
	global_store_dwordx4 v[94:95], v[78:81], off offset:256 sc1
	v_pk_add_f32 v[40:41], v[40:41], 0 op_sel_hi:[1,0]
	v_pk_add_f32 v[38:39], v[38:39], 0 op_sel_hi:[1,0]
	v_or_b32_e32 v78, 48, v160
	v_ashrrev_i32_e32 v79, 31, v78
	v_lshlrev_b64 v[78:79], 13, v[78:79]
	v_lshl_add_u64 v[78:79], v[162:163], 0, v[78:79]
	v_pk_add_f32 v[80:81], v[84:85], 0 op_sel_hi:[1,0]
	v_pk_add_f32 v[84:85], v[76:77], 0 op_sel_hi:[1,0]
	v_pk_add_f32 v[76:77], v[74:75], 0 op_sel_hi:[1,0]
	v_cvt_pk_bf16_f32 v74, v82, v83
	v_cvt_pk_bf16_f32 v75, v80, v81
; __device__ __forceinline__ unsigned cvt_pk_bf16(float lo, float hi) { unsigned r; asm volatile("v_cvt_pk_bf16_f32 %0, %1, %2" : "=v"(r) : "v"(lo), "v"(hi)); return r; }
;     __device__ __forceinline__ void operator()(const f32x4 (&acc)[2][2][4][2], const Unit& u, int wr, int wc, int fr, int fq) const {
;     ...
;             for (int m = 0; m < 4; ++m) { bf16_t* rowp = base + (size_t)(row0 + ai * HALF + m * 16) * ldc + col0;
; #pragma unroll
;                 for (int bj = 0; bj < 2; ++bj) { f32x4 v0 = acc[ai][bj][m][0] + bv[bj][0], v1 = acc[ai][bj][m][1] + bv[bj][1];
;                     if (ACT == 1) { f32x2 a = gelu_pk((f32x2){v0[0], v0[1]}), b = gelu_pk((f32x2){v0[2], v0[3]}), c = gelu_pk((f32x2){v1[0], v1[1]}), d = gelu_pk((f32x2){v1[2], v1[3]});
;                         v0 = (f32x4){a.x, a.y, b.x, b.y}; v1 = (f32x4){c.x, c.y, d.x, d.y}; }
;                     v0 = v0 * sc; v1 = v1 * sc; u32x4 w; w.x = cvt_pk_bf16(v0[0], v0[1]); w.y = cvt_pk_bf16(v0[2], v0[3]); w.z = cvt_pk_bf16(v1[0], v1[1]); w.w = cvt_pk_bf16(v1[2], v1[3]);
;                     *(u32x4*)(rowp + bj * HALF) = w; } }
	v_pk_add_f32 v[34:35], v[34:35], 0 op_sel_hi:[1,0]
	v_cvt_pk_bf16_f32 v76, v76, v77
	v_cvt_pk_bf16_f32 v77, v84, v85
	global_store_dwordx4 v[78:79], v[74:77], off sc1
	v_pk_add_f32 v[24:25], v[24:25], 0 op_sel_hi:[1,0]
	v_pk_add_f32 v[22:23], v[22:23], 0 op_sel_hi:[1,0]
	v_pk_add_f32 v[74:75], v[68:69], 0 op_sel_hi:[1,0]
	v_pk_add_f32 v[68:69], v[66:67], 0 op_sel_hi:[1,0]
	v_cvt_pk_bf16_f32 v66, v70, v71
	v_cvt_pk_bf16_f32 v67, v72, v73
	v_pk_add_f32 v[18:19], v[18:19], 0 op_sel_hi:[1,0]
	v_cvt_pk_bf16_f32 v68, v68, v69
	v_cvt_pk_bf16_f32 v69, v74, v75
	global_store_dwordx4 v[78:79], v[66:69], off offset:256 sc1
	v_pk_add_f32 v[8:9], v[8:9], 0 op_sel_hi:[1,0]
	v_pk_add_f32 v[6:7], v[6:7], 0 op_sel_hi:[1,0]
	v_pk_add_f32 v[68:69], v[60:61], 0 op_sel_hi:[1,0]
	v_pk_add_f32 v[60:61], v[58:59], 0 op_sel_hi:[1,0]
	v_cvt_pk_bf16_f32 v58, v62, v63
	v_add_co_u32_e32 v62, vcc, s52, v146
	v_cvt_pk_bf16_f32 v59, v64, v65
	v_cvt_pk_bf16_f32 v60, v60, v61
	v_cvt_pk_bf16_f32 v61, v68, v69
	v_lshl_add_u64 v[66:67], v[146:147], 0, s[6:7]
	s_nop 0
	v_addc_co_u32_e32 v63, vcc, 0, v147, vcc
	global_store_dwordx4 v[62:63], v[58:61], off sc1
	s_nop 1
	v_pk_add_f32 v[58:59], v[48:49], 0 op_sel_hi:[1,0]
	v_pk_add_f32 v[48:49], v[46:47], 0 op_sel_hi:[1,0]
	v_cvt_pk_bf16_f32 v46, v54, v55
	v_cvt_pk_bf16_f32 v47, v56, v57
	s_nop 0
	v_cvt_pk_bf16_f32 v48, v48, v49
	v_cvt_pk_bf16_f32 v49, v58, v59
	global_store_dwordx4 v[66:67], v[46:49], off offset:256 sc1
	s_nop 1
	v_pk_add_f32 v[48:49], v[52:53], 0 op_sel_hi:[1,0]
	v_pk_add_f32 v[52:53], v[44:45], 0 op_sel_hi:[1,0]
	v_pk_add_f32 v[44:45], v[42:43], 0 op_sel_hi:[1,0]
	v_cvt_pk_bf16_f32 v42, v50, v51
	v_cvt_pk_bf16_f32 v43, v48, v49
	v_add_co_u32_e32 v48, vcc, s53, v146
	v_cvt_pk_bf16_f32 v44, v44, v45
	v_cvt_pk_bf16_f32 v45, v52, v53
	v_lshl_add_u64 v[46:47], v[146:147], 0, s[14:15]
	s_nop 0
	v_addc_co_u32_e32 v49, vcc, 0, v147, vcc
	global_store_dwordx4 v[48:49], v[42:45], off sc1
	s_nop 1
	v_pk_add_f32 v[42:43], v[32:33], 0 op_sel_hi:[1,0]
	v_pk_add_f32 v[32:33], v[30:31], 0 op_sel_hi:[1,0]
	v_cvt_pk_bf16_f32 v30, v38, v39
	v_cvt_pk_bf16_f32 v31, v40, v41
	s_nop 0
	v_cvt_pk_bf16_f32 v32, v32, v33
	v_cvt_pk_bf16_f32 v33, v42, v43
	global_store_dwordx4 v[46:47], v[30:33], off offset:256 sc1
	s_nop 1
	v_pk_add_f32 v[32:33], v[36:37], 0 op_sel_hi:[1,0]
	v_pk_add_f32 v[36:37], v[28:29], 0 op_sel_hi:[1,0]
	v_pk_add_f32 v[28:29], v[26:27], 0 op_sel_hi:[1,0]
	v_cvt_pk_bf16_f32 v26, v34, v35
	v_cvt_pk_bf16_f32 v27, v32, v33
	v_add_co_u32_e32 v32, vcc, s54, v146
	v_cvt_pk_bf16_f32 v28, v28, v29
	v_cvt_pk_bf16_f32 v29, v36, v37
	v_lshl_add_u64 v[30:31], v[146:147], 0, s[16:17]
	s_nop 0
	v_addc_co_u32_e32 v33, vcc, 0, v147, vcc
	global_store_dwordx4 v[32:33], v[26:29], off sc1
	s_nop 1
	v_pk_add_f32 v[26:27], v[16:17], 0 op_sel_hi:[1,0]
	v_pk_add_f32 v[16:17], v[14:15], 0 op_sel_hi:[1,0]
	v_cvt_pk_bf16_f32 v14, v22, v23
	v_cvt_pk_bf16_f32 v15, v24, v25
	s_nop 0
	v_cvt_pk_bf16_f32 v16, v16, v17
	v_cvt_pk_bf16_f32 v17, v26, v27
	global_store_dwordx4 v[30:31], v[14:17], off offset:256 sc1
	s_nop 1
	v_pk_add_f32 v[16:17], v[20:21], 0 op_sel_hi:[1,0]
	v_pk_add_f32 v[20:21], v[12:13], 0 op_sel_hi:[1,0]
	v_pk_add_f32 v[12:13], v[10:11], 0 op_sel_hi:[1,0]
	v_cvt_pk_bf16_f32 v10, v18, v19
	v_cvt_pk_bf16_f32 v11, v16, v17
	v_add_co_u32_e32 v16, vcc, s55, v146
	v_lshl_add_u64 v[14:15], v[146:147], 0, s[18:19]
	s_nop 0
	v_addc_co_u32_e32 v17, vcc, 0, v147, vcc
	v_cvt_pk_bf16_f32 v12, v12, v13
	v_cvt_pk_bf16_f32 v13, v20, v21
	global_store_dwordx4 v[16:17], v[10:13], off sc1
	s_andn2_b64 vcc, exec, s[2:3]
	s_mov_b64 s[2:3], -1
	v_pk_add_f32 v[10:11], v[4:5], 0 op_sel_hi:[1,0]
	v_pk_add_f32 v[4:5], v[2:3], 0 op_sel_hi:[1,0]
	v_cvt_pk_bf16_f32 v2, v6, v7
	v_cvt_pk_bf16_f32 v3, v8, v9
	s_nop 0
	v_cvt_pk_bf16_f32 v4, v4, v5
	v_cvt_pk_bf16_f32 v5, v10, v11
	global_store_dwordx4 v[14:15], v[2:5], off offset:256 sc1
	s_cbranch_vccnz .LBB0_1860
	s_andn2_b64 vcc, exec, s[8:9]
	s_cbranch_vccnz .LBB0_1859
	s_barrier
	s_branch .LBB0_1859

; __device__ __forceinline__ unsigned cvt_pk_bf16(float lo, float hi) { unsigned r; asm volatile("v_cvt_pk_bf16_f32 %0, %1, %2" : "=v"(r) : "v"(lo), "v"(hi)); return r; }
;     __device__ __forceinline__ void operator()(const f32x4 (&acc)[2][2][4][2], const Unit& u, int wr, int wc, int fr, int fq) const {
;         const int row0 = u.pm * BM + wr * 64 + fr; int colt = u.pn * BM; bf16_t* base = O;
;         float sc = 1.f; if (split_cols) { const int t = colt / split_cols; base += (size_t)t * split_stride; colt -= t * split_cols; if (t == 0) sc = scale0; }
;         const int col0 = colt + wc * 32 + 8 * fq, bcol0 = u.pn * BM + wc * 32 + 8 * fq;
;         f32x4 bv[2][2];
; #pragma unroll
;         for (int bj = 0; bj < 2; ++bj)
; #pragma unroll
;             for (int n = 0; n < 2; ++n) bv[bj][n] = bias ? *(const f32x4*)(bias + bcol0 + bj * HALF + 4 * n) : (f32x4){0.f, 0.f, 0.f, 0.f};
;     ...
;             for (int m = 0; m < 4; ++m) { bf16_t* rowp = base + (size_t)(row0 + ai * HALF + m * 16) * ldc + col0;
; #pragma unroll
;                 for (int bj = 0; bj < 2; ++bj) { f32x4 v0 = acc[ai][bj][m][0] + bv[bj][0], v1 = acc[ai][bj][m][1] + bv[bj][1];
;                     if (ACT == 1) { f32x2 a = gelu_pk((f32x2){v0[0], v0[1]}), b = gelu_pk((f32x2){v0[2], v0[3]}), c = gelu_pk((f32x2){v1[0], v1[1]}), d = gelu_pk((f32x2){v1[2], v1[3]});
;                         v0 = (f32x4){a.x, a.y, b.x, b.y}; v1 = (f32x4){c.x, c.y, d.x, d.y}; }
;                     v0 = v0 * sc; v1 = v1 * sc; u32x4 w; w.x = cvt_pk_bf16(v0[0], v0[1]); w.y = cvt_pk_bf16(v0[2], v0[3]); w.z = cvt_pk_bf16(v1[0], v1[1]); w.w = cvt_pk_bf16(v1[2], v1[3]);
;                     *(u32x4*)(rowp + bj * HALF) = w; } }
.LBB0_1883:
	v_lshl_or_b32 v1, s2, 8, v1
	v_or_b32_e32 v132, s25, v1
	v_lshl_add_u32 v130, s21, 8, v142
	v_ashrrev_i32_e32 v133, 31, v132
	v_mov_b32_e32 v131, 0
	v_lshl_add_u64 v[132:133], v[132:133], 1, s[4:5]
	v_lshlrev_b64 v[134:135], 13, v[130:131]
	v_lshl_add_u64 v[134:135], v[132:133], 0, v[134:135]
	v_pk_add_f32 v[128:129], v[128:129], 0 op_sel_hi:[1,0]
	v_pk_add_f32 v[126:127], v[126:127], 0 op_sel_hi:[1,0]
	v_pk_add_f32 v[136:137], v[124:125], 0 op_sel_hi:[1,0]
	v_pk_add_f32 v[124:125], v[122:123], 0 op_sel_hi:[1,0]
	v_cvt_pk_bf16_f32 v122, v126, v127
	v_cvt_pk_bf16_f32 v123, v128, v129
	v_pk_add_f32 v[120:121], v[120:121], 0 op_sel_hi:[1,0]
	v_cvt_pk_bf16_f32 v124, v124, v125
	v_cvt_pk_bf16_f32 v125, v136, v137
	global_store_dwordx4 v[134:135], v[122:125], off sc1
	v_pk_add_f32 v[118:119], v[118:119], 0 op_sel_hi:[1,0]
	v_pk_add_f32 v[114:115], v[114:115], 0 op_sel_hi:[1,0]
	v_pk_add_f32 v[122:123], v[112:113], 0 op_sel_hi:[1,0]
	v_pk_add_f32 v[112:113], v[110:111], 0 op_sel_hi:[1,0]
	v_cvt_pk_bf16_f32 v110, v118, v119
	v_cvt_pk_bf16_f32 v111, v120, v121
	v_pk_add_f32 v[104:105], v[104:105], 0 op_sel_hi:[1,0]
	v_cvt_pk_bf16_f32 v112, v112, v113
	v_cvt_pk_bf16_f32 v113, v122, v123
	global_store_dwordx4 v[134:135], v[110:113], off offset:256 sc1
	v_pk_add_f32 v[102:103], v[102:103], 0 op_sel_hi:[1,0]
	v_pk_add_f32 v[98:99], v[98:99], 0 op_sel_hi:[1,0]
	v_or_b32_e32 v110, 16, v130
	v_mov_b32_e32 v111, v131
	v_lshlrev_b64 v[110:111], 13, v[110:111]
	v_lshl_add_u64 v[110:111], v[132:133], 0, v[110:111]
	v_pk_add_f32 v[112:113], v[116:117], 0 op_sel_hi:[1,0]
	v_pk_add_f32 v[116:117], v[108:109], 0 op_sel_hi:[1,0]
	v_pk_add_f32 v[108:109], v[106:107], 0 op_sel_hi:[1,0]
	v_cvt_pk_bf16_f32 v106, v114, v115
	v_cvt_pk_bf16_f32 v107, v112, v113
	v_pk_add_f32 v[88:89], v[88:89], 0 op_sel_hi:[1,0]
	v_cvt_pk_bf16_f32 v108, v108, v109
	v_cvt_pk_bf16_f32 v109, v116, v117
	global_store_dwordx4 v[110:111], v[106:109], off sc1
	v_pk_add_f32 v[86:87], v[86:87], 0 op_sel_hi:[1,0]
	v_pk_add_f32 v[82:83], v[82:83], 0 op_sel_hi:[1,0]
	v_pk_add_f32 v[106:107], v[96:97], 0 op_sel_hi:[1,0]
	v_pk_add_f32 v[96:97], v[94:95], 0 op_sel_hi:[1,0]
	v_cvt_pk_bf16_f32 v94, v102, v103
	v_cvt_pk_bf16_f32 v95, v104, v105
	v_pk_add_f32 v[72:73], v[72:73], 0 op_sel_hi:[1,0]
	v_cvt_pk_bf16_f32 v96, v96, v97
	v_cvt_pk_bf16_f32 v97, v106, v107
	global_store_dwordx4 v[110:111], v[94:97], off offset:256 sc1
	v_pk_add_f32 v[70:71], v[70:71], 0 op_sel_hi:[1,0]
	v_pk_add_f32 v[64:65], v[64:65], 0 op_sel_hi:[1,0]
	v_or_b32_e32 v94, 32, v130
	v_mov_b32_e32 v95, v131
	v_lshlrev_b64 v[94:95], 13, v[94:95]
	v_lshl_add_u64 v[94:95], v[132:133], 0, v[94:95]
	v_pk_add_f32 v[96:97], v[100:101], 0 op_sel_hi:[1,0]
	v_pk_add_f32 v[100:101], v[92:93], 0 op_sel_hi:[1,0]
	v_pk_add_f32 v[92:93], v[90:91], 0 op_sel_hi:[1,0]
	v_cvt_pk_bf16_f32 v90, v98, v99
	v_cvt_pk_bf16_f32 v91, v96, v97
	v_pk_add_f32 v[62:63], v[62:63], 0 op_sel_hi:[1,0]
	v_cvt_pk_bf16_f32 v92, v92, v93
	v_cvt_pk_bf16_f32 v93, v100, v101
	global_store_dwordx4 v[94:95], v[90:93], off sc1
	v_pk_add_f32 v[56:57], v[56:57], 0 op_sel_hi:[1,0]
	v_pk_add_f32 v[54:55], v[54:55], 0 op_sel_hi:[1,0]
	v_pk_add_f32 v[90:91], v[80:81], 0 op_sel_hi:[1,0]
	v_pk_add_f32 v[80:81], v[78:79], 0 op_sel_hi:[1,0]
	v_cvt_pk_bf16_f32 v78, v86, v87
	v_cvt_pk_bf16_f32 v79, v88, v89
	v_pk_add_f32 v[50:51], v[50:51], 0 op_sel_hi:[1,0]
	v_cvt_pk_bf16_f32 v80, v80, v81
	v_cvt_pk_bf16_f32 v81, v90, v91
	global_store_dwordx4 v[94:95], v[78:81], off offset:256 sc1
	v_pk_add_f32 v[40:41], v[40:41], 0 op_sel_hi:[1,0]
	v_pk_add_f32 v[38:39], v[38:39], 0 op_sel_hi:[1,0]
	v_or_b32_e32 v78, 48, v130
	v_mov_b32_e32 v79, v131
	v_lshlrev_b64 v[78:79], 13, v[78:79]
	v_lshl_add_u64 v[78:79], v[132:133], 0, v[78:79]
	v_pk_add_f32 v[80:81], v[84:85], 0 op_sel_hi:[1,0]
	v_pk_add_f32 v[84:85], v[76:77], 0 op_sel_hi:[1,0]
	v_pk_add_f32 v[76:77], v[74:75], 0 op_sel_hi:[1,0]
	v_cvt_pk_bf16_f32 v74, v82, v83
; __device__ __forceinline__ unsigned cvt_pk_bf16(float lo, float hi) { unsigned r; asm volatile("v_cvt_pk_bf16_f32 %0, %1, %2" : "=v"(r) : "v"(lo), "v"(hi)); return r; }
;     __device__ __forceinline__ void operator()(const f32x4 (&acc)[2][2][4][2], const Unit& u, int wr, int wc, int fr, int fq) const {
;     ...
;             for (int m = 0; m < 4; ++m) { bf16_t* rowp = base + (size_t)(row0 + ai * HALF + m * 16) * ldc + col0;
; #pragma unroll
;                 for (int bj = 0; bj < 2; ++bj) { f32x4 v0 = acc[ai][bj][m][0] + bv[bj][0], v1 = acc[ai][bj][m][1] + bv[bj][1];
;                     if (ACT == 1) { f32x2 a = gelu_pk((f32x2){v0[0], v0[1]}), b = gelu_pk((f32x2){v0[2], v0[3]}), c = gelu_pk((f32x2){v1[0], v1[1]}), d = gelu_pk((f32x2){v1[2], v1[3]});
;                         v0 = (f32x4){a.x, a.y, b.x, b.y}; v1 = (f32x4){c.x, c.y, d.x, d.y}; }
;                     v0 = v0 * sc; v1 = v1 * sc; u32x4 w; w.x = cvt_pk_bf16(v0[0], v0[1]); w.y = cvt_pk_bf16(v0[2], v0[3]); w.z = cvt_pk_bf16(v1[0], v1[1]); w.w = cvt_pk_bf16(v1[2], v1[3]);
;                     *(u32x4*)(rowp + bj * HALF) = w; } }
	v_cvt_pk_bf16_f32 v75, v80, v81
	v_pk_add_f32 v[34:35], v[34:35], 0 op_sel_hi:[1,0]
	v_cvt_pk_bf16_f32 v76, v76, v77
	v_cvt_pk_bf16_f32 v77, v84, v85
	global_store_dwordx4 v[78:79], v[74:77], off sc1
	v_pk_add_f32 v[24:25], v[24:25], 0 op_sel_hi:[1,0]
	v_pk_add_f32 v[22:23], v[22:23], 0 op_sel_hi:[1,0]
	v_pk_add_f32 v[74:75], v[68:69], 0 op_sel_hi:[1,0]
	v_pk_add_f32 v[68:69], v[66:67], 0 op_sel_hi:[1,0]
	v_cvt_pk_bf16_f32 v66, v70, v71
	v_cvt_pk_bf16_f32 v67, v72, v73
	v_pk_add_f32 v[18:19], v[18:19], 0 op_sel_hi:[1,0]
	v_cvt_pk_bf16_f32 v68, v68, v69
	v_cvt_pk_bf16_f32 v69, v74, v75
	global_store_dwordx4 v[78:79], v[66:69], off offset:256 sc1
	v_pk_add_f32 v[8:9], v[8:9], 0 op_sel_hi:[1,0]
	v_pk_add_f32 v[6:7], v[6:7], 0 op_sel_hi:[1,0]
	v_add_u32_e32 v66, 0x80, v130
	v_mov_b32_e32 v67, v131
	v_lshlrev_b64 v[66:67], 13, v[66:67]
	v_lshl_add_u64 v[66:67], v[132:133], 0, v[66:67]
	v_pk_add_f32 v[68:69], v[60:61], 0 op_sel_hi:[1,0]
	v_pk_add_f32 v[60:61], v[58:59], 0 op_sel_hi:[1,0]
	v_cvt_pk_bf16_f32 v58, v62, v63
	v_cvt_pk_bf16_f32 v59, v64, v65
	s_nop 0
	v_cvt_pk_bf16_f32 v60, v60, v61
	v_cvt_pk_bf16_f32 v61, v68, v69
	global_store_dwordx4 v[66:67], v[58:61], off sc1
	s_nop 1
	v_pk_add_f32 v[58:59], v[48:49], 0 op_sel_hi:[1,0]
	v_pk_add_f32 v[48:49], v[46:47], 0 op_sel_hi:[1,0]
	v_cvt_pk_bf16_f32 v46, v54, v55
	v_cvt_pk_bf16_f32 v47, v56, v57
	s_nop 0
	v_cvt_pk_bf16_f32 v48, v48, v49
	v_cvt_pk_bf16_f32 v49, v58, v59
	global_store_dwordx4 v[66:67], v[46:49], off offset:256 sc1
	s_nop 1
	v_add_u32_e32 v46, 0x90, v130
	v_mov_b32_e32 v47, v131
	v_lshlrev_b64 v[46:47], 13, v[46:47]
	v_lshl_add_u64 v[46:47], v[132:133], 0, v[46:47]
	v_pk_add_f32 v[48:49], v[52:53], 0 op_sel_hi:[1,0]
	v_pk_add_f32 v[52:53], v[44:45], 0 op_sel_hi:[1,0]
	v_pk_add_f32 v[44:45], v[42:43], 0 op_sel_hi:[1,0]
	v_cvt_pk_bf16_f32 v42, v50, v51
	v_cvt_pk_bf16_f32 v43, v48, v49
	s_nop 0
	v_cvt_pk_bf16_f32 v44, v44, v45
	v_cvt_pk_bf16_f32 v45, v52, v53
	global_store_dwordx4 v[46:47], v[42:45], off sc1
	s_nop 1
	v_pk_add_f32 v[42:43], v[32:33], 0 op_sel_hi:[1,0]
	v_pk_add_f32 v[32:33], v[30:31], 0 op_sel_hi:[1,0]
	v_cvt_pk_bf16_f32 v30, v38, v39
	v_cvt_pk_bf16_f32 v31, v40, v41
	s_nop 0
	v_cvt_pk_bf16_f32 v32, v32, v33
	v_cvt_pk_bf16_f32 v33, v42, v43
	global_store_dwordx4 v[46:47], v[30:33], off offset:256 sc1
	s_nop 1
	v_add_u32_e32 v30, 0xa0, v130
	v_mov_b32_e32 v31, v131
	v_lshlrev_b64 v[30:31], 13, v[30:31]
	v_lshl_add_u64 v[30:31], v[132:133], 0, v[30:31]
	v_pk_add_f32 v[32:33], v[36:37], 0 op_sel_hi:[1,0]
	v_pk_add_f32 v[36:37], v[28:29], 0 op_sel_hi:[1,0]
	v_pk_add_f32 v[28:29], v[26:27], 0 op_sel_hi:[1,0]
	v_cvt_pk_bf16_f32 v26, v34, v35
	v_cvt_pk_bf16_f32 v27, v32, v33
	v_add_u32_e32 v130, 0xb0, v130
	v_cvt_pk_bf16_f32 v28, v28, v29
	v_cvt_pk_bf16_f32 v29, v36, v37
	global_store_dwordx4 v[30:31], v[26:29], off sc1
	s_nop 1
	v_pk_add_f32 v[26:27], v[16:17], 0 op_sel_hi:[1,0]
	v_pk_add_f32 v[16:17], v[14:15], 0 op_sel_hi:[1,0]
	v_cvt_pk_bf16_f32 v14, v22, v23
	v_cvt_pk_bf16_f32 v15, v24, v25
	s_nop 0
	v_cvt_pk_bf16_f32 v16, v16, v17
	v_cvt_pk_bf16_f32 v17, v26, v27
	global_store_dwordx4 v[30:31], v[14:17], off offset:256 sc1
	s_nop 1
	v_lshlrev_b64 v[14:15], 13, v[130:131]
	v_lshl_add_u64 v[14:15], v[132:133], 0, v[14:15]
	v_pk_add_f32 v[16:17], v[20:21], 0 op_sel_hi:[1,0]
	v_pk_add_f32 v[20:21], v[12:13], 0 op_sel_hi:[1,0]
	v_pk_add_f32 v[12:13], v[10:11], 0 op_sel_hi:[1,0]
	v_cvt_pk_bf16_f32 v10, v18, v19
	v_cvt_pk_bf16_f32 v11, v16, v17
	s_nop 0
	v_cvt_pk_bf16_f32 v12, v12, v13
	v_cvt_pk_bf16_f32 v13, v20, v21
	global_store_dwordx4 v[14:15], v[10:13], off sc1
	s_nop 1
	v_pk_add_f32 v[10:11], v[4:5], 0 op_sel_hi:[1,0]
	v_pk_add_f32 v[4:5], v[2:3], 0 op_sel_hi:[1,0]
	v_cvt_pk_bf16_f32 v2, v6, v7
	v_cvt_pk_bf16_f32 v3, v8, v9
	s_nop 0
	v_cvt_pk_bf16_f32 v4, v4, v5
	v_cvt_pk_bf16_f32 v5, v10, v11
	global_store_dwordx4 v[14:15], v[2:5], off offset:256 sc1
	s_waitcnt vmcnt(0)
	s_barrier

; __device__ __forceinline__ unsigned cvt_pk_bf16(float lo, float hi) { unsigned r; asm volatile("v_cvt_pk_bf16_f32 %0, %1, %2" : "=v"(r) : "v"(lo), "v"(hi)); return r; }
;     __device__ __forceinline__ void operator()(const f32x4 (&acc)[2][2][4][2], const Unit& u, int wr, int wc, int fr, int fq) const {
;         const int row0 = u.pm * BM + wr * 64 + fr, col0 = u.pn * BM + wc * 32 + 8 * fq;
;         float scv[2][4];
; #pragma unroll
;         for (int ai = 0; ai < 2; ++ai)
; #pragma unroll
;             for (int m = 0; m < 4; ++m) scv[ai][m] = rs[row0 + ai * HALF + m * 16];
; #pragma unroll
;         for (int ai = 0; ai < 2; ++ai)
; #pragma unroll
;             for (int m = 0; m < 4; ++m) { const int row = row0 + ai * HALF + m * 16; const float sc = scv[ai][m]; bf16_t* rowp = O + (size_t)row * ldc + col0;
; #pragma unroll
;                 for (int bj = 0; bj < 2; ++bj) { const f32x4 v0 = acc[ai][bj][m][0] * sc, v1 = acc[ai][bj][m][1] * sc;
;                     u32x4 w; w.x = cvt_pk_bf16(v0[0], v0[1]); w.y = cvt_pk_bf16(v0[2], v0[3]); w.z = cvt_pk_bf16(v1[0], v1[1]); w.w = cvt_pk_bf16(v1[2], v1[3]);
;                     *(u32x4*)(rowp + bj * HALF) = w; } }
.LBB0_2003:
	v_lshl_add_u32 v148, s22, 8, v1
	v_or_b32_e32 v162, 16, v148
	v_ashrrev_i32_e32 v149, 31, v148
	v_ashrrev_i32_e32 v163, 31, v162
	v_or_b32_e32 v166, 32, v148
	v_lshl_add_u64 v[158:159], v[148:149], 2, s[8:9]
	v_lshl_add_u64 v[146:147], v[162:163], 2, s[8:9]
	v_ashrrev_i32_e32 v167, 31, v166
	global_load_dword v160, v[158:159], off
	global_load_dword v164, v[146:147], off
	v_lshl_add_u64 v[146:147], v[166:167], 2, s[8:9]
	global_load_dword v168, v[146:147], off
	v_or_b32_e32 v170, 48, v148
	v_ashrrev_i32_e32 v171, 31, v170
	v_lshl_add_u64 v[146:147], v[170:171], 2, s[8:9]
	global_load_dword v154, v[146:147], off
	v_lshl_or_b32 v172, s48, 8, v153
	v_mov_b64_e32 v[146:147], s[6:7]
	v_ashrrev_i32_e32 v173, 31, v172
	v_add_u32_e32 v165, 0x80, v148
	v_add_u32_e32 v169, 0x90, v148
	v_add_u32_e32 v171, 0xa0, v148
	v_add_u32_e32 v177, 0xb0, v148
	v_mad_i64_i32 v[174:175], s[24:25], v148, s47, v[146:147]
	v_lshlrev_b64 v[148:149], 1, v[172:173]
	v_lshl_add_u64 v[172:173], v[174:175], 0, v[148:149]
	global_load_dword v174, v[158:159], off offset:512
	global_load_dword v176, v[158:159], off offset:576
	global_load_dword v152, v[158:159], off offset:640
	global_load_dword v150, v[158:159], off offset:704
	v_mad_i64_i32 v[162:163], s[24:25], v162, s47, v[146:147]
	v_lshl_add_u64 v[162:163], v[162:163], 0, v[148:149]
	v_mad_i64_i32 v[166:167], s[24:25], v166, s47, v[146:147]
	v_lshl_add_u64 v[166:167], v[166:167], 0, v[148:149]
	s_andn2_b64 vcc, exec, s[2:3]
	s_mov_b64 s[2:3], -1
	s_waitcnt vmcnt(0)
	v_pk_mul_f32 v[124:125], v[124:125], v[160:161] op_sel_hi:[1,0]
	v_pk_mul_f32 v[128:129], v[128:129], v[160:161] op_sel_hi:[1,0]
	v_pk_mul_f32 v[126:127], v[126:127], v[160:161] op_sel_hi:[1,0]
	v_pk_mul_f32 v[122:123], v[122:123], v[160:161] op_sel_hi:[1,0]
	v_pk_mul_f32 v[112:113], v[112:113], v[160:161] op_sel_hi:[1,0]
	v_pk_mul_f32 v[110:111], v[110:111], v[160:161] op_sel_hi:[1,0]
	v_pk_mul_f32 v[158:159], v[104:105], v[160:161] op_sel_hi:[1,0]
	v_pk_mul_f32 v[160:161], v[102:103], v[160:161] op_sel_hi:[1,0]
	v_cvt_pk_bf16_f32 v102, v126, v127
	v_cvt_pk_bf16_f32 v103, v128, v129
	v_cvt_pk_bf16_f32 v104, v122, v123
	v_cvt_pk_bf16_f32 v105, v124, v125
	v_pk_mul_f32 v[124:125], v[82:83], v[168:169] op_sel_hi:[1,0]
	global_store_dwordx4 v[172:173], v[102:105], off sc1
	v_cvt_pk_bf16_f32 v82, v110, v111
	v_cvt_pk_bf16_f32 v83, v112, v113
	v_pk_mul_f32 v[120:121], v[120:121], v[164:165] op_sel_hi:[1,0]
	v_pk_mul_f32 v[118:119], v[118:119], v[164:165] op_sel_hi:[1,0]
	v_pk_mul_f32 v[122:123], v[84:85], v[168:169] op_sel_hi:[1,0]
	v_cvt_pk_bf16_f32 v84, v160, v161
	v_cvt_pk_bf16_f32 v85, v158, v159
	global_store_dwordx4 v[172:173], v[82:85], off offset:256 sc1
	v_pk_mul_f32 v[116:117], v[116:117], v[164:165] op_sel_hi:[1,0]
	v_pk_mul_f32 v[114:115], v[114:115], v[164:165] op_sel_hi:[1,0]
	v_cvt_pk_bf16_f32 v82, v118, v119
	v_cvt_pk_bf16_f32 v83, v120, v121
	v_pk_mul_f32 v[96:97], v[96:97], v[164:165] op_sel_hi:[1,0]
	v_pk_mul_f32 v[94:95], v[94:95], v[164:165] op_sel_hi:[1,0]
	v_cvt_pk_bf16_f32 v84, v114, v115
	v_cvt_pk_bf16_f32 v85, v116, v117
	global_store_dwordx4 v[162:163], v[82:85], off sc1
	v_pk_mul_f32 v[92:93], v[92:93], v[164:165] op_sel_hi:[1,0]
	v_pk_mul_f32 v[90:91], v[90:91], v[164:165] op_sel_hi:[1,0]
	v_cvt_pk_bf16_f32 v82, v94, v95
	v_cvt_pk_bf16_f32 v83, v96, v97
	v_pk_mul_f32 v[108:109], v[108:109], v[168:169] op_sel_hi:[1,0]
	v_pk_mul_f32 v[106:107], v[106:107], v[168:169] op_sel_hi:[1,0]
	v_cvt_pk_bf16_f32 v84, v90, v91
	v_cvt_pk_bf16_f32 v85, v92, v93
	global_store_dwordx4 v[162:163], v[82:85], off offset:256 sc1
	v_pk_mul_f32 v[100:101], v[100:101], v[168:169] op_sel_hi:[1,0]
	v_pk_mul_f32 v[98:99], v[98:99], v[168:169] op_sel_hi:[1,0]
	v_cvt_pk_bf16_f32 v82, v106, v107
	v_cvt_pk_bf16_f32 v83, v108, v109
	v_pk_mul_f32 v[88:89], v[88:89], v[168:169] op_sel_hi:[1,0]
	v_pk_mul_f32 v[86:87], v[86:87], v[168:169] op_sel_hi:[1,0]
	v_cvt_pk_bf16_f32 v84, v98, v99
	v_cvt_pk_bf16_f32 v85, v100, v101
	global_store_dwordx4 v[166:167], v[82:85], off sc1
	v_pk_mul_f32 v[80:81], v[80:81], v[154:155] op_sel_hi:[1,0]
	v_pk_mul_f32 v[78:79], v[78:79], v[154:155] op_sel_hi:[1,0]
	v_cvt_pk_bf16_f32 v82, v86, v87
	v_cvt_pk_bf16_f32 v83, v88, v89
	v_cvt_pk_bf16_f32 v84, v124, v125
	v_cvt_pk_bf16_f32 v85, v122, v123
	global_store_dwordx4 v[166:167], v[82:85], off offset:256 sc1
	v_pk_mul_f32 v[72:73], v[72:73], v[154:155] op_sel_hi:[1,0]
	v_pk_mul_f32 v[70:71], v[70:71], v[154:155] op_sel_hi:[1,0]
	v_mad_i64_i32 v[82:83], s[24:25], v170, s47, v[146:147]
	v_lshl_add_u64 v[82:83], v[82:83], 0, v[148:149]
	v_pk_mul_f32 v[84:85], v[76:77], v[154:155] op_sel_hi:[1,0]
; __device__ __forceinline__ unsigned cvt_pk_bf16(float lo, float hi) { unsigned r; asm volatile("v_cvt_pk_bf16_f32 %0, %1, %2" : "=v"(r) : "v"(lo), "v"(hi)); return r; }
;     __device__ __forceinline__ void operator()(const f32x4 (&acc)[2][2][4][2], const Unit& u, int wr, int wc, int fr, int fq) const {
;     ...
;             for (int m = 0; m < 4; ++m) { const int row = row0 + ai * HALF + m * 16; const float sc = scv[ai][m]; bf16_t* rowp = O + (size_t)row * ldc + col0;
; #pragma unroll
;                 for (int bj = 0; bj < 2; ++bj) { const f32x4 v0 = acc[ai][bj][m][0] * sc, v1 = acc[ai][bj][m][1] * sc;
;                     u32x4 w; w.x = cvt_pk_bf16(v0[0], v0[1]); w.y = cvt_pk_bf16(v0[2], v0[3]); w.z = cvt_pk_bf16(v1[0], v1[1]); w.w = cvt_pk_bf16(v1[2], v1[3]);
;                     *(u32x4*)(rowp + bj * HALF) = w; } }
	v_pk_mul_f32 v[76:77], v[74:75], v[154:155] op_sel_hi:[1,0]
	v_cvt_pk_bf16_f32 v74, v78, v79
	v_cvt_pk_bf16_f32 v75, v80, v81
	v_pk_mul_f32 v[64:65], v[64:65], v[174:175] op_sel_hi:[1,0]
	v_cvt_pk_bf16_f32 v76, v76, v77
	v_cvt_pk_bf16_f32 v77, v84, v85
	global_store_dwordx4 v[82:83], v[74:77], off sc1
	v_pk_mul_f32 v[62:63], v[62:63], v[174:175] op_sel_hi:[1,0]
	v_pk_mul_f32 v[56:57], v[56:57], v[174:175] op_sel_hi:[1,0]
	v_pk_mul_f32 v[74:75], v[68:69], v[154:155] op_sel_hi:[1,0]
	v_pk_mul_f32 v[68:69], v[66:67], v[154:155] op_sel_hi:[1,0]
	v_cvt_pk_bf16_f32 v66, v70, v71
	v_cvt_pk_bf16_f32 v67, v72, v73
	v_pk_mul_f32 v[54:55], v[54:55], v[174:175] op_sel_hi:[1,0]
	v_cvt_pk_bf16_f32 v68, v68, v69
	v_cvt_pk_bf16_f32 v69, v74, v75
	global_store_dwordx4 v[82:83], v[66:69], off offset:256 sc1
	v_pk_mul_f32 v[50:51], v[50:51], v[176:177] op_sel_hi:[1,0]
	v_pk_mul_f32 v[40:41], v[40:41], v[176:177] op_sel_hi:[1,0]
	v_mad_i64_i32 v[66:67], s[24:25], v165, s47, v[146:147]
	v_lshl_add_u64 v[66:67], v[66:67], 0, v[148:149]
	v_pk_mul_f32 v[68:69], v[60:61], v[174:175] op_sel_hi:[1,0]
	v_pk_mul_f32 v[60:61], v[58:59], v[174:175] op_sel_hi:[1,0]
	v_cvt_pk_bf16_f32 v58, v62, v63
	v_cvt_pk_bf16_f32 v59, v64, v65
	v_pk_mul_f32 v[38:39], v[38:39], v[176:177] op_sel_hi:[1,0]
	v_cvt_pk_bf16_f32 v60, v60, v61
	v_cvt_pk_bf16_f32 v61, v68, v69
	global_store_dwordx4 v[66:67], v[58:61], off sc1
	v_pk_mul_f32 v[34:35], v[34:35], v[152:153] op_sel_hi:[1,0]
	v_pk_mul_f32 v[24:25], v[24:25], v[152:153] op_sel_hi:[1,0]
	v_pk_mul_f32 v[58:59], v[48:49], v[174:175] op_sel_hi:[1,0]
	v_pk_mul_f32 v[48:49], v[46:47], v[174:175] op_sel_hi:[1,0]
	v_cvt_pk_bf16_f32 v46, v54, v55
	v_cvt_pk_bf16_f32 v47, v56, v57
	v_pk_mul_f32 v[22:23], v[22:23], v[152:153] op_sel_hi:[1,0]
	v_cvt_pk_bf16_f32 v48, v48, v49
	v_cvt_pk_bf16_f32 v49, v58, v59
	global_store_dwordx4 v[66:67], v[46:49], off offset:256 sc1
	v_pk_mul_f32 v[18:19], v[18:19], v[150:151] op_sel_hi:[1,0]
	v_pk_mul_f32 v[8:9], v[8:9], v[150:151] op_sel_hi:[1,0]
	v_mad_i64_i32 v[46:47], s[24:25], v169, s47, v[146:147]
	v_lshl_add_u64 v[46:47], v[46:47], 0, v[148:149]
	v_pk_mul_f32 v[48:49], v[52:53], v[176:177] op_sel_hi:[1,0]
	v_pk_mul_f32 v[52:53], v[44:45], v[176:177] op_sel_hi:[1,0]
	v_pk_mul_f32 v[44:45], v[42:43], v[176:177] op_sel_hi:[1,0]
	v_cvt_pk_bf16_f32 v42, v50, v51
	v_cvt_pk_bf16_f32 v43, v48, v49
	v_pk_mul_f32 v[6:7], v[6:7], v[150:151] op_sel_hi:[1,0]
	v_cvt_pk_bf16_f32 v44, v44, v45
	v_cvt_pk_bf16_f32 v45, v52, v53
	global_store_dwordx4 v[46:47], v[42:45], off sc1
	s_nop 1
	v_pk_mul_f32 v[42:43], v[32:33], v[176:177] op_sel_hi:[1,0]
	v_pk_mul_f32 v[32:33], v[30:31], v[176:177] op_sel_hi:[1,0]
	v_cvt_pk_bf16_f32 v30, v38, v39
	v_cvt_pk_bf16_f32 v31, v40, v41
	s_nop 0
	v_cvt_pk_bf16_f32 v32, v32, v33
	v_cvt_pk_bf16_f32 v33, v42, v43
	global_store_dwordx4 v[46:47], v[30:33], off offset:256 sc1
	s_nop 1
	v_mad_i64_i32 v[30:31], s[24:25], v171, s47, v[146:147]
	v_lshl_add_u64 v[30:31], v[30:31], 0, v[148:149]
	v_pk_mul_f32 v[32:33], v[36:37], v[152:153] op_sel_hi:[1,0]
	v_pk_mul_f32 v[36:37], v[28:29], v[152:153] op_sel_hi:[1,0]
	v_pk_mul_f32 v[28:29], v[26:27], v[152:153] op_sel_hi:[1,0]
	v_cvt_pk_bf16_f32 v26, v34, v35
	v_cvt_pk_bf16_f32 v27, v32, v33
	s_nop 0
	v_cvt_pk_bf16_f32 v28, v28, v29
	v_cvt_pk_bf16_f32 v29, v36, v37
	global_store_dwordx4 v[30:31], v[26:29], off sc1
	s_nop 1
	v_pk_mul_f32 v[26:27], v[16:17], v[152:153] op_sel_hi:[1,0]
	v_pk_mul_f32 v[16:17], v[14:15], v[152:153] op_sel_hi:[1,0]
	v_cvt_pk_bf16_f32 v14, v22, v23
	v_cvt_pk_bf16_f32 v15, v24, v25
	s_nop 0
	v_cvt_pk_bf16_f32 v16, v16, v17
	v_cvt_pk_bf16_f32 v17, v26, v27
	global_store_dwordx4 v[30:31], v[14:17], off offset:256 sc1
	s_nop 1
	v_mad_i64_i32 v[14:15], s[24:25], v177, s47, v[146:147]
	v_lshl_add_u64 v[14:15], v[14:15], 0, v[148:149]
	v_pk_mul_f32 v[16:17], v[20:21], v[150:151] op_sel_hi:[1,0]
	v_pk_mul_f32 v[20:21], v[12:13], v[150:151] op_sel_hi:[1,0]
	v_pk_mul_f32 v[12:13], v[10:11], v[150:151] op_sel_hi:[1,0]
	v_cvt_pk_bf16_f32 v10, v18, v19
	v_cvt_pk_bf16_f32 v11, v16, v17
	s_nop 0
	v_cvt_pk_bf16_f32 v12, v12, v13
	v_cvt_pk_bf16_f32 v13, v20, v21
	global_store_dwordx4 v[14:15], v[10:13], off sc1
	s_nop 1
	v_pk_mul_f32 v[10:11], v[4:5], v[150:151] op_sel_hi:[1,0]
	v_pk_mul_f32 v[4:5], v[2:3], v[150:151] op_sel_hi:[1,0]
	v_cvt_pk_bf16_f32 v2, v6, v7
	v_cvt_pk_bf16_f32 v3, v8, v9
	s_nop 0
	v_cvt_pk_bf16_f32 v4, v4, v5
	v_cvt_pk_bf16_f32 v5, v10, v11
	global_store_dwordx4 v[14:15], v[2:5], off offset:256 sc1
	s_cbranch_vccnz .LBB0_1996
	s_andn2_b64 vcc, exec, s[4:5]
	s_cbranch_vccnz .LBB0_1995
	s_barrier
	s_branch .LBB0_1995

; __device__ __forceinline__ unsigned pk2(float lo, float hi) { unsigned r; asm volatile("v_cvt_pk_bf16_f32 %0, %1, %2" : "=v"(r) : "v"(lo), "v"(hi)); return r; }
; __device__ __forceinline__ void p0_transpose_item(const float* W, int K, int N, bf16* WT, int kb, int src_col0, int dst_row0, float* scr, int lane, const float* kgain = nullptr) {
;     ...
;     for (int j = 0; j < 4; ++j) { const int n = (lane >> 3) + 8 * j; const float* s = scr + (8 * c) * 33 + n;
;         v4u o;
;         if (src_col0 >= 0) { o.x = pk2(s[0 * 33] * g0.x, s[1 * 33] * g0.y); o.y = pk2(s[2 * 33] * g0.z, s[3 * 33] * g0.w); o.z = pk2(s[4 * 33] * g1.x, s[5 * 33] * g1.y); o.w = pk2(s[6 * 33] * g1.z, s[7 * 33] * g1.w); }
;         else { o.x = 0u; o.y = 0u; o.z = 0u; o.w = 0u; }
;         *(v4u*)(WT + (size_t)(dst_row0 + n) * K + k0 + 8 * c) = o; }
.LBB0_2009:
	v_add_u32_e32 v14, 24, v6
	v_ashrrev_i32_e32 v15, 31, v14
	v_lshlrev_b64 v[14:15], 13, v[14:15]
	v_lshl_add_u64 v[12:13], v[12:13], 0, v[14:15]
	global_store_dwordx4 v[12:13], v[2:5], off sc1
	s_waitcnt lgkmcnt(0)
	s_add_i32 s2, s8, 0x300
	s_addk_i32 s9, 0x6000
	s_cmpk_lt_i32 s8, 0x1d00
	s_mov_b32 s8, s2
	s_cbranch_scc0 .LBB0_2020

; __device__ __forceinline__ unsigned pk2(float lo, float hi) { unsigned r; asm volatile("v_cvt_pk_bf16_f32 %0, %1, %2" : "=v"(r) : "v"(lo), "v"(hi)); return r; }
; __device__ __forceinline__ void p0_transpose_item(const float* W, int K, int N, bf16* WT, int kb, int src_col0, int dst_row0, float* scr, int lane, const float* kgain = nullptr) {
;     ...
;     for (int j = 0; j < 4; ++j) { const int n = (lane >> 3) + 8 * j; const float* s = scr + (8 * c) * 33 + n;
;         v4u o;
;         if (src_col0 >= 0) { o.x = pk2(s[0 * 33] * g0.x, s[1 * 33] * g0.y); o.y = pk2(s[2 * 33] * g0.z, s[3 * 33] * g0.w); o.z = pk2(s[4 * 33] * g1.x, s[5 * 33] * g1.y); o.w = pk2(s[6 * 33] * g1.z, s[7 * 33] * g1.w); }
;         else { o.x = 0u; o.y = 0u; o.z = 0u; o.w = 0u; }
;         *(v4u*)(WT + (size_t)(dst_row0 + n) * K + k0 + 8 * c) = o; }
.LBB0_2012:
	s_waitcnt lgkmcnt(0)
	s_ashr_i32 s7, s6, 31
	v_lshl_add_u64 v[12:13], s[6:7], 1, v[10:11]
	s_mov_b64 s[6:7], -1
	s_and_b64 vcc, exec, s[4:5]
	s_cbranch_vccz .LBB0_2014
	s_add_i32 s2, s10, s9
	v_add_u32_e32 v2, s2, v17
	v_ashrrev_i32_e32 v3, 31, v2
	v_lshlrev_b64 v[4:5], 13, v[2:3]
	v_lshl_add_u64 v[4:5], v[12:13], 0, v[4:5]
	global_store_dwordx4 v[4:5], v[26:29], off sc1
	s_mov_b64 s[6:7], 0
	v_mov_b32_e32 v6, v2
.LBB0_2014:
	v_mov_b32_e32 v2, 0
	s_andn2_b64 vcc, exec, s[6:7]
	v_mov_b32_e32 v3, 0
	v_mov_b32_e32 v4, 0
	v_mov_b32_e32 v5, 0
	s_cbranch_vccnz .LBB0_2016
	ds_read2_b32 v[2:3], v18 offset1:33
	s_add_i32 s10, s10, s9
	s_waitcnt lgkmcnt(0)
	v_cvt_pk_bf16_f32 v2, v2, v3
	ds_read2_b32 v[4:5], v18 offset0:66 offset1:99
	v_add_u32_e32 v6, s10, v17
	s_waitcnt lgkmcnt(0)
	v_cvt_pk_bf16_f32 v3, v4, v5
	ds_read2_b32 v[4:5], v18 offset0:132 offset1:165
	v_lshlrev_b64 v[30:31], 13, v[6:7]
	s_waitcnt lgkmcnt(0)
	v_cvt_pk_bf16_f32 v4, v4, v5
	ds_read2_b32 v[14:15], v18 offset0:198 offset1:231
	s_waitcnt lgkmcnt(0)
	v_cvt_pk_bf16_f32 v5, v14, v15
	v_lshl_add_u64 v[30:31], v[12:13], 0, v[30:31]
	ds_read2_b32 v[14:15], v18 offset0:8 offset1:41
	global_store_dwordx4 v[30:31], v[2:5], off sc1
	s_waitcnt lgkmcnt(0)
	s_nop 0
	v_cvt_pk_bf16_f32 v2, v14, v15
	ds_read2_b32 v[4:5], v18 offset0:74 offset1:107
	s_waitcnt lgkmcnt(0)
	v_cvt_pk_bf16_f32 v3, v4, v5
	ds_read2_b32 v[4:5], v18 offset0:140 offset1:173
	s_waitcnt lgkmcnt(0)
	v_cvt_pk_bf16_f32 v4, v4, v5
	ds_read2_b32 v[14:15], v18 offset0:206 offset1:239
	s_waitcnt lgkmcnt(0)
	v_cvt_pk_bf16_f32 v5, v14, v15
.LBB0_2016:
	v_add_u32_e32 v14, 8, v6
	v_ashrrev_i32_e32 v15, 31, v14
	v_lshlrev_b64 v[14:15], 13, v[14:15]
	v_lshl_add_u64 v[14:15], v[12:13], 0, v[14:15]
	global_store_dwordx4 v[14:15], v[2:5], off sc1
	s_mov_b64 s[6:7], -1
	s_and_b64 vcc, exec, s[4:5]
	v_add_u32_e32 v14, 16, v6
	s_cbranch_vccz .LBB0_2018
	v_ashrrev_i32_e32 v15, 31, v14
	v_lshlrev_b64 v[2:3], 13, v[14:15]
	v_lshl_add_u64 v[2:3], v[12:13], 0, v[2:3]
	global_store_dwordx4 v[2:3], v[26:29], off sc1
	s_mov_b64 s[6:7], 0
.LBB0_2018:
	v_mov_b32_e32 v2, 0
	s_andn2_b64 vcc, exec, s[6:7]
	v_mov_b32_e32 v3, 0
	v_mov_b32_e32 v4, 0
	v_mov_b32_e32 v5, 0
	s_cbranch_vccnz .LBB0_2009
	ds_read2_b32 v[2:3], v18 offset0:16 offset1:49
	s_waitcnt lgkmcnt(0)
	v_cvt_pk_bf16_f32 v2, v2, v3
	ds_read2_b32 v[4:5], v18 offset0:82 offset1:115
	v_mov_b32_e32 v15, v7
	s_waitcnt lgkmcnt(0)
	v_cvt_pk_bf16_f32 v3, v4, v5
	ds_read2_b32 v[4:5], v18 offset0:148 offset1:181
	v_lshlrev_b64 v[14:15], 13, v[14:15]
	s_waitcnt lgkmcnt(0)
	v_cvt_pk_bf16_f32 v4, v4, v5
	ds_read2_b32 v[30:31], v18 offset0:214 offset1:247
	s_waitcnt lgkmcnt(0)
	v_cvt_pk_bf16_f32 v5, v30, v31
	v_lshl_add_u64 v[14:15], v[12:13], 0, v[14:15]
	ds_read2_b32 v[30:31], v18 offset0:24 offset1:57
	global_store_dwordx4 v[14:15], v[2:5], off sc1
	s_waitcnt lgkmcnt(0)
	s_nop 0
	v_cvt_pk_bf16_f32 v2, v30, v31
	ds_read2_b32 v[4:5], v18 offset0:90 offset1:123
	s_waitcnt lgkmcnt(0)
	v_cvt_pk_bf16_f32 v3, v4, v5
	ds_read2_b32 v[4:5], v18 offset0:156 offset1:189
	s_waitcnt lgkmcnt(0)
	v_cvt_pk_bf16_f32 v4, v4, v5
	ds_read2_b32 v[14:15], v18 offset0:222 offset1:255
	s_waitcnt lgkmcnt(0)
	v_cvt_pk_bf16_f32 v5, v14, v15
	s_branch .LBB0_2009

.LBB0_2152:
	s_or_b64 exec, exec, s[4:5]
	s_waitcnt lgkmcnt(0)
	ds_read_b64 v[72:73], v139
	ds_read_b128 v[68:71], v191
	v_add_u32_e32 v2, s94, v188
	v_mul_lo_u32 v2, v2, s75
	v_lshlrev_b32_e32 v74, 1, v180
	v_add3_u32 v2, 0, v2, v74
	s_waitcnt lgkmcnt(0)
	v_lshlrev_b32_e32 v74, 16, v68
	v_fmac_f32_e32 v74, v52, v72
	v_and_b32_e32 v52, 0xffff0000, v68
	v_fmac_f32_e32 v52, v53, v73
	v_lshlrev_b32_e32 v53, 16, v69
	v_fmac_f32_e32 v53, v36, v72
	v_and_b32_e32 v36, 0xffff0000, v69
	v_fmac_f32_e32 v36, v37, v73
	v_lshlrev_b32_e32 v37, 16, v70
	v_fmac_f32_e32 v37, v20, v72
	v_and_b32_e32 v20, 0xffff0000, v70
	v_fmac_f32_e32 v20, v21, v73
	v_lshlrev_b32_e32 v21, 16, v71
	v_fmac_f32_e32 v21, v4, v72
	v_and_b32_e32 v4, 0xffff0000, v71
	v_cvt_pk_bf16_f32 v52, v74, v52
	v_fmac_f32_e32 v4, v5, v73
	v_cvt_pk_bf16_f32 v36, v53, v36
	v_cvt_pk_bf16_f32 v20, v37, v20
	v_cvt_pk_bf16_f32 v4, v21, v4
	ds_write_b16 v2, v52
	ds_write_b16_d16_hi v2, v52 offset:272
	ds_write_b16 v2, v36 offset:64
	ds_write_b16_d16_hi v2, v36 offset:336
	ds_write_b16 v2, v20 offset:128
	ds_write_b16_d16_hi v2, v20 offset:400
	ds_write_b16 v2, v4 offset:192
	ds_write_b16_d16_hi v2, v4 offset:464
	ds_read_b128 v[68:71], v191 offset:8192
	ds_read_b64 v[4:5], v139 offset:8
	v_readlane_b32 s2, v254, 62
	s_add_i32 s4, s2, s96
	v_mov_b32_e32 v37, v3
	s_waitcnt lgkmcnt(1)
	v_lshlrev_b32_e32 v20, 16, v68
	v_and_b32_e32 v21, 0xffff0000, v68
	s_waitcnt lgkmcnt(0)
	v_fmac_f32_e32 v20, v54, v4
	v_fmac_f32_e32 v21, v55, v5
	v_cvt_pk_bf16_f32 v20, v20, v21
	v_lshlrev_b32_e32 v21, 16, v69
	v_and_b32_e32 v36, 0xffff0000, v69
	v_fmac_f32_e32 v21, v38, v4
	v_fmac_f32_e32 v36, v39, v5
	v_cvt_pk_bf16_f32 v21, v21, v36
	v_lshlrev_b32_e32 v36, 16, v70
	v_fmac_f32_e32 v36, v22, v4
	v_and_b32_e32 v22, 0xffff0000, v70
	v_fmac_f32_e32 v22, v23, v5
	v_lshlrev_b32_e32 v23, 16, v71
	v_fmac_f32_e32 v23, v6, v4
	v_and_b32_e32 v4, 0xffff0000, v71
	v_fmac_f32_e32 v4, v7, v5
	v_cvt_pk_bf16_f32 v22, v36, v22
	v_cvt_pk_bf16_f32 v4, v23, v4
	ds_write_b16 v2, v20 offset:544
	ds_write_b16_d16_hi v2, v20 offset:816
	ds_write_b16 v2, v21 offset:608
	ds_write_b16_d16_hi v2, v21 offset:880
	ds_write_b16 v2, v22 offset:672
	ds_write_b16_d16_hi v2, v22 offset:944
	ds_write_b16 v2, v4 offset:736
	ds_write_b16_d16_hi v2, v4 offset:1008
	ds_read_b128 v[4:7], v191 offset:16384
	ds_read_b64 v[20:21], v139 offset:32
	v_ashrrev_i32_e32 v69, 4, v178
	v_add_u32_e32 v74, 4, v69
	v_lshlrev_b32_e32 v36, 4, v179
	s_waitcnt lgkmcnt(1)
	v_lshlrev_b32_e32 v22, 16, v4
	v_and_b32_e32 v4, 0xffff0000, v4
	s_waitcnt lgkmcnt(0)
	v_fmac_f32_e32 v22, v56, v20
	v_fmac_f32_e32 v4, v57, v21
	v_cvt_pk_bf16_f32 v4, v22, v4
	v_lshlrev_b32_e32 v22, 16, v5
	v_and_b32_e32 v5, 0xffff0000, v5
	v_fmac_f32_e32 v22, v40, v20
	v_fmac_f32_e32 v5, v41, v21
	v_cvt_pk_bf16_f32 v5, v22, v5
	v_lshlrev_b32_e32 v22, 16, v6
	v_and_b32_e32 v6, 0xffff0000, v6
	v_fmac_f32_e32 v22, v24, v20
	v_fmac_f32_e32 v6, v25, v21
	v_cvt_pk_bf16_f32 v6, v22, v6
	v_lshlrev_b32_e32 v22, 16, v7
	v_and_b32_e32 v7, 0xffff0000, v7
	v_fmac_f32_e32 v7, v9, v21
	v_fmac_f32_e32 v22, v8, v20
	v_cvt_pk_bf16_f32 v7, v22, v7
	ds_write_b16 v2, v4 offset:2176
	ds_write_b16_d16_hi v2, v4 offset:2448
	ds_write_b16 v2, v5 offset:2240
	ds_write_b16_d16_hi v2, v5 offset:2512
	ds_write_b16 v2, v6 offset:2304
	ds_write_b16_d16_hi v2, v6 offset:2576
	ds_write_b16 v2, v7 offset:2368
	ds_write_b16_d16_hi v2, v7 offset:2640
	ds_read_b128 v[4:7], v191 offset:24576
	ds_read_b64 v[8:9], v139 offset:40
	v_add_u32_e32 v68, 8, v69
	v_mov_b32_e32 v55, v3
	v_mov_b32_e32 v41, v3
	s_waitcnt lgkmcnt(1)
	v_lshlrev_b32_e32 v20, 16, v4
	v_and_b32_e32 v4, 0xffff0000, v4
	s_waitcnt lgkmcnt(0)
	v_fmac_f32_e32 v20, v58, v8
	v_fmac_f32_e32 v4, v59, v9
	v_cvt_pk_bf16_f32 v4, v20, v4
	v_lshlrev_b32_e32 v20, 16, v5
	v_and_b32_e32 v5, 0xffff0000, v5
	v_fmac_f32_e32 v20, v42, v8
	v_fmac_f32_e32 v5, v43, v9
	v_cvt_pk_bf16_f32 v5, v20, v5
	v_lshlrev_b32_e32 v20, 16, v6
	v_and_b32_e32 v6, 0xffff0000, v6
	v_fmac_f32_e32 v20, v26, v8
	v_fmac_f32_e32 v6, v27, v9
	v_cvt_pk_bf16_f32 v6, v20, v6
	v_lshlrev_b32_e32 v20, 16, v7
	v_and_b32_e32 v7, 0xffff0000, v7
	v_fmac_f32_e32 v7, v11, v9
	v_fmac_f32_e32 v20, v10, v8
	v_cvt_pk_bf16_f32 v7, v20, v7
	ds_write_b16 v2, v4 offset:2720
	ds_write_b16_d16_hi v2, v4 offset:2992
	ds_write_b16 v2, v5 offset:2784
	ds_write_b16_d16_hi v2, v5 offset:3056
	ds_write_b16 v2, v6 offset:2848
	ds_write_b16_d16_hi v2, v6 offset:3120
	ds_write_b16 v2, v7 offset:2912
	ds_write_b16_d16_hi v2, v7 offset:3184
	ds_read_b128 v[4:7], v191 offset:32768
	ds_read_b64 v[8:9], v139 offset:64
	v_readlane_b32 s12, v254, 61
	s_waitcnt lgkmcnt(1)
	v_lshlrev_b32_e32 v10, 16, v4
	v_and_b32_e32 v4, 0xffff0000, v4
	s_waitcnt lgkmcnt(0)
	v_fmac_f32_e32 v10, v60, v8
	v_fmac_f32_e32 v4, v61, v9
	v_cvt_pk_bf16_f32 v4, v10, v4
	v_lshlrev_b32_e32 v10, 16, v5
	v_and_b32_e32 v5, 0xffff0000, v5
	v_fmac_f32_e32 v10, v44, v8
	v_fmac_f32_e32 v5, v45, v9
	v_cvt_pk_bf16_f32 v5, v10, v5
	v_lshlrev_b32_e32 v10, 16, v6
	v_and_b32_e32 v6, 0xffff0000, v6
	v_fmac_f32_e32 v10, v28, v8
	v_fmac_f32_e32 v6, v29, v9
	v_cvt_pk_bf16_f32 v6, v10, v6
	v_lshlrev_b32_e32 v10, 16, v7
	v_and_b32_e32 v7, 0xffff0000, v7
	v_fmac_f32_e32 v7, v13, v9
	v_fmac_f32_e32 v10, v12, v8
	v_cvt_pk_bf16_f32 v7, v10, v7
	ds_write_b16 v2, v4 offset:4352
	ds_write_b16_d16_hi v2, v4 offset:4624
	ds_write_b16 v2, v5 offset:4416
	ds_write_b16_d16_hi v2, v5 offset:4688
	ds_write_b16 v2, v6 offset:4480
	ds_write_b16_d16_hi v2, v6 offset:4752
	ds_write_b16 v2, v7 offset:4544
	ds_write_b16_d16_hi v2, v7 offset:4816
	ds_read_b128 v[4:7], v191 offset:40960
	ds_read_b64 v[8:9], v139 offset:72
	v_mov_b32_e32 v61, v3
	v_add_u32_e32 v45, 28, v69
	v_add_u32_e32 v44, 0, v36
	s_waitcnt lgkmcnt(1)
; template <int VAR>
; __device__ __forceinline__ void nsa_attn_mfma(Frame& F, bf16* Y) {
;     ...
;       v4u zv[8];
; #pragma unroll
;       for (int j = 0; j < 8; ++j) { const int row = 4 * j + (lane >> 4), tt = t0 + 4 * wid + (row >> 3), hh = g * 8 + (row & 7);
;         zv[j] = *(const v4u*)(proj + (size_t)(b * SEQ + tt) * NSA_NP + NSA_Z + hh * 128 + (lane & 15) * 8); }
	v_lshlrev_b32_e32 v10, 16, v4
	v_and_b32_e32 v4, 0xffff0000, v4
	s_waitcnt lgkmcnt(0)
	v_fmac_f32_e32 v10, v62, v8
	v_fmac_f32_e32 v4, v63, v9
	v_cvt_pk_bf16_f32 v4, v10, v4
	v_lshlrev_b32_e32 v10, 16, v5
	v_and_b32_e32 v5, 0xffff0000, v5
	v_fmac_f32_e32 v10, v46, v8
	v_fmac_f32_e32 v5, v47, v9
	v_cvt_pk_bf16_f32 v5, v10, v5
	v_lshlrev_b32_e32 v10, 16, v6
	v_and_b32_e32 v6, 0xffff0000, v6
	v_fmac_f32_e32 v10, v30, v8
	v_fmac_f32_e32 v6, v31, v9
	v_cvt_pk_bf16_f32 v6, v10, v6
	v_lshlrev_b32_e32 v10, 16, v7
	v_and_b32_e32 v7, 0xffff0000, v7
	v_fmac_f32_e32 v7, v15, v9
	v_fmac_f32_e32 v10, v14, v8
	v_cvt_pk_bf16_f32 v7, v10, v7
	ds_write_b16 v2, v4 offset:4896
	ds_write_b16_d16_hi v2, v4 offset:5168
	ds_write_b16 v2, v5 offset:4960
	ds_write_b16_d16_hi v2, v5 offset:5232
	ds_write_b16 v2, v6 offset:5024
	ds_write_b16_d16_hi v2, v6 offset:5296
	ds_write_b16 v2, v7 offset:5088
	ds_write_b16_d16_hi v2, v7 offset:5360
	ds_read_b128 v[4:7], v191 offset:49152
	ds_read_b64 v[8:9], v139 offset:96
	s_waitcnt lgkmcnt(1)
	v_lshlrev_b32_e32 v10, 16, v4
	v_and_b32_e32 v4, 0xffff0000, v4
	s_waitcnt lgkmcnt(0)
	v_fmac_f32_e32 v10, v64, v8
	v_fmac_f32_e32 v4, v65, v9
	v_cvt_pk_bf16_f32 v4, v10, v4
	v_lshlrev_b32_e32 v10, 16, v5
	v_and_b32_e32 v5, 0xffff0000, v5
	v_fmac_f32_e32 v10, v48, v8
	v_fmac_f32_e32 v5, v49, v9
	v_cvt_pk_bf16_f32 v5, v10, v5
	v_lshlrev_b32_e32 v10, 16, v6
	v_and_b32_e32 v6, 0xffff0000, v6
	v_fmac_f32_e32 v10, v32, v8
	v_fmac_f32_e32 v6, v33, v9
	v_cvt_pk_bf16_f32 v6, v10, v6
	v_lshlrev_b32_e32 v10, 16, v7
	v_and_b32_e32 v7, 0xffff0000, v7
	v_fmac_f32_e32 v7, v17, v9
	v_fmac_f32_e32 v10, v16, v8
	v_cvt_pk_bf16_f32 v7, v10, v7
	ds_write_b16 v2, v4 offset:6528
	ds_write_b16_d16_hi v2, v4 offset:6800
	ds_write_b16 v2, v5 offset:6592
	ds_write_b16_d16_hi v2, v5 offset:6864
	ds_write_b16 v2, v6 offset:6656
	ds_write_b16_d16_hi v2, v6 offset:6928
	ds_write_b16 v2, v7 offset:6720
	ds_write_b16_d16_hi v2, v7 offset:6992
	ds_read_b128 v[4:7], v191 offset:57344
	ds_read_b64 v[8:9], v139 offset:104
	v_add_u32_e32 v65, 20, v69
	v_mov_b32_e32 v49, v3
	v_add_u32_e32 v64, 24, v69
	s_waitcnt lgkmcnt(1)
	v_lshlrev_b32_e32 v10, 16, v4
	v_and_b32_e32 v4, 0xffff0000, v4
	s_waitcnt lgkmcnt(0)
	v_fmac_f32_e32 v10, v66, v8
	v_fmac_f32_e32 v4, v67, v9
	v_cvt_pk_bf16_f32 v4, v10, v4
	v_lshlrev_b32_e32 v10, 16, v5
	v_and_b32_e32 v5, 0xffff0000, v5
	v_fmac_f32_e32 v10, v50, v8
	v_fmac_f32_e32 v5, v51, v9
	v_cvt_pk_bf16_f32 v5, v10, v5
	v_lshlrev_b32_e32 v10, 16, v6
	v_and_b32_e32 v6, 0xffff0000, v6
	v_fmac_f32_e32 v10, v34, v8
	v_fmac_f32_e32 v6, v35, v9
	v_cvt_pk_bf16_f32 v6, v10, v6
	v_lshlrev_b32_e32 v10, 16, v7
	v_and_b32_e32 v7, 0xffff0000, v7
	v_fmac_f32_e32 v7, v19, v9
	v_fmac_f32_e32 v10, v18, v8
	v_cvt_pk_bf16_f32 v7, v10, v7
	ds_write_b16 v2, v4 offset:7072
	ds_write_b16_d16_hi v2, v4 offset:7344
	ds_write_b16 v2, v5 offset:7136
	ds_write_b16_d16_hi v2, v5 offset:7408
	ds_write_b16 v2, v6 offset:7200
	ds_write_b16_d16_hi v2, v6 offset:7472
	ds_write_b16 v2, v7 offset:7264
	ds_write_b16_d16_hi v2, v7 offset:7536
	v_ashrrev_i32_e32 v2, 7, v178
	v_and_or_b32 v8, v69, 7, s93
	v_add_u32_e32 v62, s4, v2
	v_mov_b64_e32 v[4:5], s[10:11]
	v_mad_i64_i32 v[6:7], s[2:3], v62, s73, v[4:5]
	v_lshlrev_b32_e32 v2, 8, v8
	v_ashrrev_i32_e32 v8, 3, v74
	v_lshl_add_u64 v[6:7], v[6:7], 0, v[2:3]
	v_and_or_b32 v10, v74, 7, s93
	v_add_u32_e32 v58, s4, v8
	v_lshl_add_u64 v[6:7], v[6:7], 0, v[36:37]
	v_mad_i64_i32 v[8:9], s[2:3], v58, s73, v[4:5]
	v_lshlrev_b32_e32 v60, 8, v10
	v_add_co_u32_e32 v6, vcc, s92, v6
	v_lshl_add_u64 v[8:9], v[8:9], 0, v[60:61]
	s_nop 0
	v_addc_co_u32_e32 v7, vcc, 0, v7, vcc
	v_lshl_add_u64 v[8:9], v[8:9], 0, v[36:37]
	s_waitcnt lgkmcnt(0)
	v_add_co_u32_e32 v8, vcc, s92, v8
	v_add_u32_e32 v67, 12, v69
	s_nop 0
	v_addc_co_u32_e32 v9, vcc, 0, v9, vcc
	global_load_dwordx4 v[32:35], v[6:7], off offset:2048
	global_load_dwordx4 v[28:31], v[8:9], off offset:2048
	v_ashrrev_i32_e32 v6, 3, v68
	v_add_u32_e32 v56, s4, v6
	v_mad_i64_i32 v[6:7], s[2:3], v56, s73, v[4:5]
	v_ashrrev_i32_e32 v8, 3, v67
	v_lshl_add_u64 v[6:7], v[6:7], 0, v[2:3]
	v_and_or_b32 v10, v67, 7, s93
	v_add_u32_e32 v52, s4, v8
	v_lshl_add_u64 v[6:7], v[6:7], 0, v[36:37]
	v_mad_i64_i32 v[8:9], s[2:3], v52, s73, v[4:5]
	v_lshlrev_b32_e32 v54, 8, v10
	v_add_co_u32_e32 v6, vcc, s92, v6
	v_lshl_add_u64 v[8:9], v[8:9], 0, v[54:55]
	s_nop 0
	v_addc_co_u32_e32 v7, vcc, 0, v7, vcc
	v_lshl_add_u64 v[8:9], v[8:9], 0, v[36:37]
	v_add_co_u32_e32 v8, vcc, s92, v8
	v_add_u32_e32 v66, 16, v69
	s_nop 0
	v_addc_co_u32_e32 v9, vcc, 0, v9, vcc
	global_load_dwordx4 v[24:27], v[6:7], off offset:2048
	global_load_dwordx4 v[20:23], v[8:9], off offset:2048
	v_ashrrev_i32_e32 v6, 3, v66
	v_add_u32_e32 v50, s4, v6
	v_mad_i64_i32 v[6:7], s[2:3], v50, s73, v[4:5]
	v_ashrrev_i32_e32 v8, 3, v65
	v_lshl_add_u64 v[6:7], v[6:7], 0, v[2:3]
	v_and_or_b32 v10, v65, 7, s93
	v_add_u32_e32 v46, s4, v8
	v_lshl_add_u64 v[6:7], v[6:7], 0, v[36:37]
	v_mad_i64_i32 v[8:9], s[2:3], v46, s73, v[4:5]
	v_lshlrev_b32_e32 v48, 8, v10
	v_add_co_u32_e32 v6, vcc, s92, v6
	v_lshl_add_u64 v[8:9], v[8:9], 0, v[48:49]
	s_nop 0
	v_addc_co_u32_e32 v7, vcc, 0, v7, vcc
	v_lshl_add_u64 v[8:9], v[8:9], 0, v[36:37]
	v_add_co_u32_e32 v8, vcc, s92, v8
	v_add_u32_e32 v69, s94, v69
	s_nop 0
	v_addc_co_u32_e32 v9, vcc, 0, v9, vcc
	global_load_dwordx4 v[16:19], v[6:7], off offset:2048
	global_load_dwordx4 v[12:15], v[8:9], off offset:2048
	v_ashrrev_i32_e32 v6, 3, v64
	v_add_u32_e32 v42, s4, v6
	v_mad_i64_i32 v[6:7], s[2:3], v42, s73, v[4:5]
	v_ashrrev_i32_e32 v8, 3, v45
	v_lshl_add_u64 v[6:7], v[6:7], 0, v[2:3]
	v_and_or_b32 v9, v45, 7, s93
	v_add_u32_e32 v38, s4, v8
	v_mad_u64_u32 v[70:71], s[2:3], v69, s75, v[44:45]
	v_lshl_add_u64 v[6:7], v[6:7], 0, v[36:37]
	v_mad_i64_i32 v[4:5], s[2:3], v38, s73, v[4:5]
	v_lshlrev_b32_e32 v40, 8, v9
	v_add_co_u32_e32 v6, vcc, s92, v6
	v_lshl_add_u64 v[4:5], v[4:5], 0, v[40:41]
	s_nop 0
	v_addc_co_u32_e32 v7, vcc, 0, v7, vcc
	v_lshl_add_u64 v[4:5], v[4:5], 0, v[36:37]
	v_add_co_u32_e32 v4, vcc, s92, v4
	v_ashrrev_i32_e32 v63, 31, v62
	s_nop 0
	v_addc_co_u32_e32 v5, vcc, 0, v5, vcc
	global_load_dwordx4 v[8:11], v[6:7], off offset:2048
	s_nop 0
	global_load_dwordx4 v[4:7], v[4:5], off offset:2048
	ds_read_b128 v[70:73], v70
	v_lshlrev_b64 v[62:63], 13, v[62:63]
	v_lshl_add_u64 v[62:63], s[88:89], 0, v[62:63]
	v_lshl_add_u64 v[62:63], v[62:63], 0, v[2:3]
	s_waitcnt vmcnt(7)
; __device__ __forceinline__ float bflo(unsigned w) { return __uint_as_float(w << 16); }
; __device__ __forceinline__ float bfhi(unsigned w) { return __uint_as_float(w & 0xffff0000u); }
; __device__ __forceinline__ float siluf_(float x) { return x * __builtin_amdgcn_rcpf(1.0f + __expf(-x)); }
; __device__ __forceinline__ unsigned cvtpk(float lo, float hi) { unsigned r; asm volatile("v_cvt_pk_bf16_f32 %0, %1, %2" : "=v"(r) : "v"(lo), "v"(hi)); return r; }
; template <int VAR>
; __device__ __forceinline__ void nsa_attn_mfma(Frame& F, bf16* Y) {
;     ...
; #pragma unroll
;       for (int j = 0; j < 8; ++j) { const int row = 4 * j + (lane >> 4), tt = t0 + 4 * wid + (row >> 3), hh = g * 8 + (row & 7);
;         const v4u tv = *(const v4u*)((const unsigned short*)(lds + AT_K) + (wid * 32 + row) * ROWP + (lane & 15) * 8); const v4u z = zv[j]; v4u y;
;         y.x = cvtpk(bflo(tv.x) * siluf_(bflo(z.x)), bfhi(tv.x) * siluf_(bfhi(z.x))); y.y = cvtpk(bflo(tv.y) * siluf_(bflo(z.y)), bfhi(tv.y) * siluf_(bfhi(z.y)));
;         y.z = cvtpk(bflo(tv.z) * siluf_(bflo(z.z)), bfhi(tv.z) * siluf_(bfhi(z.z))); y.w = cvtpk(bflo(tv.w) * siluf_(bflo(z.w)), bfhi(tv.w) * siluf_(bfhi(z.w)));
;         *(v4u*)(Y + (size_t)(b * SEQ + tt) * DM + hh * 128 + (lane & 15) * 8) = y; }
	v_lshlrev_b32_e32 v69, 16, v32
	v_and_b32_e32 v32, 0xffff0000, v32
	v_mul_f32_e32 v75, 0xbfb8aa3b, v69
	v_mul_f32_e32 v76, 0xbfb8aa3b, v32
	v_exp_f32_e32 v75, v75
	v_exp_f32_e32 v76, v76
	s_waitcnt lgkmcnt(0)
	v_lshlrev_b32_e32 v77, 16, v70
	v_and_b32_e32 v70, 0xffff0000, v70
	v_add_f32_e32 v75, 1.0, v75
	v_add_f32_e32 v76, 1.0, v76
	v_rcp_f32_e32 v75, v75
	v_rcp_f32_e32 v76, v76
	v_lshl_add_u64 v[62:63], v[62:63], 0, v[36:37]
	v_ashrrev_i32_e32 v59, 31, v58
	v_mul_f32_e32 v69, v75, v69
	v_mul_f32_e32 v32, v76, v32
	v_mul_f32_e32 v69, v69, v77
	v_mul_f32_e32 v32, v32, v70
	v_cvt_pk_bf16_f32 v32, v69, v32
	v_lshlrev_b32_e32 v69, 16, v33
	v_and_b32_e32 v33, 0xffff0000, v33
	v_mul_f32_e32 v70, 0xbfb8aa3b, v69
	v_mul_f32_e32 v75, 0xbfb8aa3b, v33
	v_exp_f32_e32 v70, v70
	v_exp_f32_e32 v75, v75
	v_lshlrev_b32_e32 v76, 16, v71
	v_ashrrev_i32_e32 v57, 31, v56
	v_add_f32_e32 v70, 1.0, v70
	v_add_f32_e32 v75, 1.0, v75
	v_rcp_f32_e32 v70, v70
	v_rcp_f32_e32 v75, v75
	v_ashrrev_i32_e32 v53, 31, v52
	v_ashrrev_i32_e32 v51, 31, v50
	v_mul_f32_e32 v69, v70, v69
	v_and_b32_e32 v70, 0xffff0000, v71
	v_mul_f32_e32 v33, v75, v33
	v_mul_f32_e32 v69, v69, v76
	v_mul_f32_e32 v33, v33, v70
	v_cvt_pk_bf16_f32 v33, v69, v33
	v_lshlrev_b32_e32 v69, 16, v34
	v_and_b32_e32 v34, 0xffff0000, v34
	v_mul_f32_e32 v70, 0xbfb8aa3b, v69
	v_mul_f32_e32 v71, 0xbfb8aa3b, v34
	v_exp_f32_e32 v70, v70
	v_exp_f32_e32 v71, v71
	v_lshlrev_b32_e32 v75, 16, v72
	v_ashrrev_i32_e32 v47, 31, v46
	v_add_f32_e32 v70, 1.0, v70
	v_add_f32_e32 v71, 1.0, v71
	v_rcp_f32_e32 v70, v70
	v_rcp_f32_e32 v71, v71
	v_ashrrev_i32_e32 v43, 31, v42
	v_ashrrev_i32_e32 v39, 31, v38
	v_mul_f32_e32 v69, v70, v69
	v_and_b32_e32 v70, 0xffff0000, v72
	v_mul_f32_e32 v34, v71, v34
	v_mul_f32_e32 v69, v69, v75
	v_mul_f32_e32 v34, v34, v70
	v_cvt_pk_bf16_f32 v34, v69, v34
	v_lshlrev_b32_e32 v69, 16, v35
	v_and_b32_e32 v35, 0xffff0000, v35
	v_mul_f32_e32 v70, 0xbfb8aa3b, v69
	v_mul_f32_e32 v71, 0xbfb8aa3b, v35
	v_exp_f32_e32 v70, v70
	v_exp_f32_e32 v71, v71
	v_lshlrev_b32_e32 v72, 16, v73
	v_add_f32_e32 v70, 1.0, v70
	v_add_f32_e32 v71, 1.0, v71
	v_rcp_f32_e32 v70, v70
	v_rcp_f32_e32 v71, v71
	v_mul_f32_e32 v69, v70, v69
	v_and_b32_e32 v70, 0xffff0000, v73
	v_mul_f32_e32 v35, v71, v35
	v_mul_f32_e32 v35, v35, v70
	v_mul_f32_e32 v69, v69, v72
	v_cvt_pk_bf16_f32 v35, v69, v35
	global_store_dwordx4 v[62:63], v[32:35], off sc1
	s_waitcnt vmcnt(7)
	v_lshlrev_b32_e32 v62, 16, v28
	v_and_b32_e32 v28, 0xffff0000, v28
	v_mul_f32_e32 v63, 0xbfb8aa3b, v62
	v_mul_f32_e32 v69, 0xbfb8aa3b, v28
	v_exp_f32_e32 v63, v63
	v_exp_f32_e32 v69, v69
	v_add_u32_e32 v32, s94, v74
	v_mad_u64_u32 v[32:33], s[2:3], v32, s75, v[44:45]
	ds_read_b128 v[32:35], v32
	v_add_f32_e32 v63, 1.0, v63
	v_add_f32_e32 v69, 1.0, v69
	v_rcp_f32_e32 v63, v63
	v_rcp_f32_e32 v69, v69
	s_waitcnt lgkmcnt(0)
	v_lshlrev_b32_e32 v70, 16, v32
	v_and_b32_e32 v32, 0xffff0000, v32
	v_mul_f32_e32 v62, v63, v62
	v_mul_f32_e32 v28, v69, v28
	v_mul_f32_e32 v62, v62, v70
	v_mul_f32_e32 v28, v28, v32
	v_lshlrev_b32_e32 v32, 16, v29
	v_and_b32_e32 v29, 0xffff0000, v29
	v_cvt_pk_bf16_f32 v28, v62, v28
	v_mul_f32_e32 v62, 0xbfb8aa3b, v32
	v_mul_f32_e32 v63, 0xbfb8aa3b, v29
	v_exp_f32_e32 v62, v62
	v_exp_f32_e32 v63, v63
	v_lshlrev_b32_e32 v69, 16, v33
	v_and_b32_e32 v33, 0xffff0000, v33
	v_add_f32_e32 v62, 1.0, v62
	v_add_f32_e32 v63, 1.0, v63
	v_rcp_f32_e32 v62, v62
	v_rcp_f32_e32 v63, v63
	v_mul_f32_e32 v32, v62, v32
	v_mul_f32_e32 v29, v63, v29
	v_mul_f32_e32 v32, v32, v69
	v_mul_f32_e32 v29, v29, v33
	v_cvt_pk_bf16_f32 v29, v32, v29
	v_lshlrev_b32_e32 v32, 16, v30
	v_and_b32_e32 v30, 0xffff0000, v30
	v_mul_f32_e32 v33, 0xbfb8aa3b, v32
	v_mul_f32_e32 v62, 0xbfb8aa3b, v30
	v_exp_f32_e32 v33, v33
	v_exp_f32_e32 v62, v62
	v_lshlrev_b32_e32 v63, 16, v34
	v_add_f32_e32 v33, 1.0, v33
	v_add_f32_e32 v62, 1.0, v62
	v_rcp_f32_e32 v33, v33
	v_rcp_f32_e32 v62, v62
	v_mul_f32_e32 v32, v33, v32
	v_and_b32_e32 v33, 0xffff0000, v34
	v_mul_f32_e32 v30, v62, v30
	v_mul_f32_e32 v32, v32, v63
	v_mul_f32_e32 v30, v30, v33
	v_cvt_pk_bf16_f32 v30, v32, v30
	v_lshlrev_b32_e32 v32, 16, v31
	v_and_b32_e32 v31, 0xffff0000, v31
	v_mul_f32_e32 v33, 0xbfb8aa3b, v32
	v_mul_f32_e32 v34, 0xbfb8aa3b, v31
	v_exp_f32_e32 v33, v33
	v_exp_f32_e32 v34, v34
	v_lshlrev_b32_e32 v62, 16, v35
	v_add_f32_e32 v33, 1.0, v33
	v_add_f32_e32 v34, 1.0, v34
	v_rcp_f32_e32 v33, v33
	v_rcp_f32_e32 v34, v34
	v_mul_f32_e32 v32, v33, v32
	v_and_b32_e32 v33, 0xffff0000, v35
	v_mul_f32_e32 v31, v34, v31
	v_mul_f32_e32 v32, v32, v62
	v_mul_f32_e32 v31, v31, v33
	v_cvt_pk_bf16_f32 v31, v32, v31
	v_lshlrev_b64 v[32:33], 13, v[58:59]
	v_lshl_add_u64 v[32:33], s[88:89], 0, v[32:33]
	v_lshl_add_u64 v[32:33], v[32:33], 0, v[60:61]
	v_lshl_add_u64 v[32:33], v[32:33], 0, v[36:37]
	global_store_dwordx4 v[32:33], v[28:31], off sc1
	s_waitcnt vmcnt(7)
	v_lshlrev_b32_e32 v32, 16, v24
	v_and_b32_e32 v24, 0xffff0000, v24
	v_mul_f32_e32 v33, 0xbfb8aa3b, v32
	v_mul_f32_e32 v34, 0xbfb8aa3b, v24
	v_exp_f32_e32 v33, v33
	v_exp_f32_e32 v34, v34
	v_add_u32_e32 v28, s94, v68
	v_mad_u64_u32 v[28:29], s[2:3], v28, s75, v[44:45]
	ds_read_b128 v[28:31], v28
	v_add_f32_e32 v33, 1.0, v33
	v_add_f32_e32 v34, 1.0, v34
	v_rcp_f32_e32 v33, v33
	v_rcp_f32_e32 v34, v34
	s_waitcnt lgkmcnt(0)
; __device__ __forceinline__ float bflo(unsigned w) { return __uint_as_float(w << 16); }
; __device__ __forceinline__ float bfhi(unsigned w) { return __uint_as_float(w & 0xffff0000u); }
; __device__ __forceinline__ float siluf_(float x) { return x * __builtin_amdgcn_rcpf(1.0f + __expf(-x)); }
; __device__ __forceinline__ unsigned cvtpk(float lo, float hi) { unsigned r; asm volatile("v_cvt_pk_bf16_f32 %0, %1, %2" : "=v"(r) : "v"(lo), "v"(hi)); return r; }
; template <int VAR>
; __device__ __forceinline__ void nsa_attn_mfma(Frame& F, bf16* Y) {
;     ...
; #pragma unroll
;       for (int j = 0; j < 8; ++j) { const int row = 4 * j + (lane >> 4), tt = t0 + 4 * wid + (row >> 3), hh = g * 8 + (row & 7);
;         const v4u tv = *(const v4u*)((const unsigned short*)(lds + AT_K) + (wid * 32 + row) * ROWP + (lane & 15) * 8); const v4u z = zv[j]; v4u y;
;         y.x = cvtpk(bflo(tv.x) * siluf_(bflo(z.x)), bfhi(tv.x) * siluf_(bfhi(z.x))); y.y = cvtpk(bflo(tv.y) * siluf_(bflo(z.y)), bfhi(tv.y) * siluf_(bfhi(z.y)));
;         y.z = cvtpk(bflo(tv.z) * siluf_(bflo(z.z)), bfhi(tv.z) * siluf_(bfhi(z.z))); y.w = cvtpk(bflo(tv.w) * siluf_(bflo(z.w)), bfhi(tv.w) * siluf_(bfhi(z.w)));
;         *(v4u*)(Y + (size_t)(b * SEQ + tt) * DM + hh * 128 + (lane & 15) * 8) = y; }
	v_lshlrev_b32_e32 v35, 16, v28
	v_and_b32_e32 v28, 0xffff0000, v28
	v_mul_f32_e32 v32, v33, v32
	v_mul_f32_e32 v24, v34, v24
	v_mul_f32_e32 v32, v32, v35
	v_mul_f32_e32 v24, v24, v28
	v_lshlrev_b32_e32 v28, 16, v25
	v_and_b32_e32 v25, 0xffff0000, v25
	v_cvt_pk_bf16_f32 v24, v32, v24
	v_mul_f32_e32 v32, 0xbfb8aa3b, v28
	v_mul_f32_e32 v33, 0xbfb8aa3b, v25
	v_exp_f32_e32 v32, v32
	v_exp_f32_e32 v33, v33
	v_lshlrev_b32_e32 v34, 16, v29
	v_and_b32_e32 v29, 0xffff0000, v29
	v_add_f32_e32 v32, 1.0, v32
	v_add_f32_e32 v33, 1.0, v33
	v_rcp_f32_e32 v32, v32
	v_rcp_f32_e32 v33, v33
	v_mul_f32_e32 v28, v32, v28
	v_mul_f32_e32 v25, v33, v25
	v_mul_f32_e32 v28, v28, v34
	v_mul_f32_e32 v25, v25, v29
	v_cvt_pk_bf16_f32 v25, v28, v25
	v_lshlrev_b32_e32 v28, 16, v26
	v_and_b32_e32 v26, 0xffff0000, v26
	v_mul_f32_e32 v29, 0xbfb8aa3b, v28
	v_mul_f32_e32 v32, 0xbfb8aa3b, v26
	v_exp_f32_e32 v29, v29
	v_exp_f32_e32 v32, v32
	v_lshlrev_b32_e32 v33, 16, v30
	v_add_f32_e32 v29, 1.0, v29
	v_add_f32_e32 v32, 1.0, v32
	v_rcp_f32_e32 v29, v29
	v_rcp_f32_e32 v32, v32
	v_mul_f32_e32 v28, v29, v28
	v_and_b32_e32 v29, 0xffff0000, v30
	v_mul_f32_e32 v26, v32, v26
	v_mul_f32_e32 v28, v28, v33
	v_mul_f32_e32 v26, v26, v29
	v_cvt_pk_bf16_f32 v26, v28, v26
	v_lshlrev_b32_e32 v28, 16, v27
	v_and_b32_e32 v27, 0xffff0000, v27
	v_mul_f32_e32 v29, 0xbfb8aa3b, v28
	v_mul_f32_e32 v30, 0xbfb8aa3b, v27
	v_exp_f32_e32 v29, v29
	v_exp_f32_e32 v30, v30
	v_lshlrev_b32_e32 v32, 16, v31
	v_add_f32_e32 v29, 1.0, v29
	v_add_f32_e32 v30, 1.0, v30
	v_rcp_f32_e32 v29, v29
	v_rcp_f32_e32 v30, v30
	v_mul_f32_e32 v28, v29, v28
	v_and_b32_e32 v29, 0xffff0000, v31
	v_mul_f32_e32 v27, v30, v27
	v_mul_f32_e32 v28, v28, v32
	v_mul_f32_e32 v27, v27, v29
	v_cvt_pk_bf16_f32 v27, v28, v27
	v_lshlrev_b64 v[28:29], 13, v[56:57]
	v_lshl_add_u64 v[28:29], s[88:89], 0, v[28:29]
	v_lshl_add_u64 v[28:29], v[28:29], 0, v[2:3]
	v_lshl_add_u64 v[28:29], v[28:29], 0, v[36:37]
	global_store_dwordx4 v[28:29], v[24:27], off sc1
	s_waitcnt vmcnt(7)
	v_lshlrev_b32_e32 v28, 16, v20
	v_and_b32_e32 v20, 0xffff0000, v20
	v_mul_f32_e32 v29, 0xbfb8aa3b, v28
	v_mul_f32_e32 v30, 0xbfb8aa3b, v20
	v_exp_f32_e32 v29, v29
	v_exp_f32_e32 v30, v30
	v_add_u32_e32 v24, s94, v67
	v_mad_u64_u32 v[24:25], s[2:3], v24, s75, v[44:45]
	ds_read_b128 v[24:27], v24
	v_add_f32_e32 v29, 1.0, v29
	v_add_f32_e32 v30, 1.0, v30
	v_rcp_f32_e32 v29, v29
	v_rcp_f32_e32 v30, v30
	s_waitcnt lgkmcnt(0)
	v_lshlrev_b32_e32 v31, 16, v24
	v_and_b32_e32 v24, 0xffff0000, v24
	v_mul_f32_e32 v28, v29, v28
	v_mul_f32_e32 v20, v30, v20
	v_mul_f32_e32 v28, v28, v31
	v_mul_f32_e32 v20, v20, v24
	v_lshlrev_b32_e32 v24, 16, v21
	v_and_b32_e32 v21, 0xffff0000, v21
	v_cvt_pk_bf16_f32 v20, v28, v20
	v_mul_f32_e32 v28, 0xbfb8aa3b, v24
	v_mul_f32_e32 v29, 0xbfb8aa3b, v21
	v_exp_f32_e32 v28, v28
	v_exp_f32_e32 v29, v29
	v_lshlrev_b32_e32 v30, 16, v25
	v_and_b32_e32 v25, 0xffff0000, v25
	v_add_f32_e32 v28, 1.0, v28
	v_add_f32_e32 v29, 1.0, v29
	v_rcp_f32_e32 v28, v28
	v_rcp_f32_e32 v29, v29
	v_mul_f32_e32 v24, v28, v24
	v_mul_f32_e32 v21, v29, v21
	v_mul_f32_e32 v24, v24, v30
	v_mul_f32_e32 v21, v21, v25
	v_cvt_pk_bf16_f32 v21, v24, v21
	v_lshlrev_b32_e32 v24, 16, v22
	v_and_b32_e32 v22, 0xffff0000, v22
	v_mul_f32_e32 v25, 0xbfb8aa3b, v24
	v_mul_f32_e32 v28, 0xbfb8aa3b, v22
	v_exp_f32_e32 v25, v25
	v_exp_f32_e32 v28, v28
	v_lshlrev_b32_e32 v29, 16, v26
	v_add_f32_e32 v25, 1.0, v25
	v_add_f32_e32 v28, 1.0, v28
	v_rcp_f32_e32 v25, v25
	v_rcp_f32_e32 v28, v28
	v_mul_f32_e32 v24, v25, v24
	v_and_b32_e32 v25, 0xffff0000, v26
	v_mul_f32_e32 v22, v28, v22
	v_mul_f32_e32 v24, v24, v29
	v_mul_f32_e32 v22, v22, v25
	v_cvt_pk_bf16_f32 v22, v24, v22
	v_lshlrev_b32_e32 v24, 16, v23
	v_and_b32_e32 v23, 0xffff0000, v23
	v_mul_f32_e32 v25, 0xbfb8aa3b, v24
	v_mul_f32_e32 v26, 0xbfb8aa3b, v23
	v_exp_f32_e32 v25, v25
	v_exp_f32_e32 v26, v26
	v_lshlrev_b32_e32 v28, 16, v27
	v_add_f32_e32 v25, 1.0, v25
	v_add_f32_e32 v26, 1.0, v26
	v_rcp_f32_e32 v25, v25
	v_rcp_f32_e32 v26, v26
	v_mul_f32_e32 v24, v25, v24
	v_and_b32_e32 v25, 0xffff0000, v27
	v_mul_f32_e32 v23, v26, v23
	v_mul_f32_e32 v24, v24, v28
	v_mul_f32_e32 v23, v23, v25
	v_cvt_pk_bf16_f32 v23, v24, v23
	v_lshlrev_b64 v[24:25], 13, v[52:53]
	v_lshl_add_u64 v[24:25], s[88:89], 0, v[24:25]
	v_lshl_add_u64 v[24:25], v[24:25], 0, v[54:55]
	v_lshl_add_u64 v[24:25], v[24:25], 0, v[36:37]
	global_store_dwordx4 v[24:25], v[20:23], off sc1
	s_waitcnt vmcnt(7)
	v_lshlrev_b32_e32 v24, 16, v16
	v_and_b32_e32 v16, 0xffff0000, v16
	v_mul_f32_e32 v25, 0xbfb8aa3b, v24
	v_mul_f32_e32 v26, 0xbfb8aa3b, v16
	v_exp_f32_e32 v25, v25
	v_exp_f32_e32 v26, v26
	v_add_u32_e32 v20, s94, v66
	v_mad_u64_u32 v[20:21], s[2:3], v20, s75, v[44:45]
	ds_read_b128 v[20:23], v20
	v_add_f32_e32 v25, 1.0, v25
	v_add_f32_e32 v26, 1.0, v26
	v_rcp_f32_e32 v25, v25
	v_rcp_f32_e32 v26, v26
	s_waitcnt lgkmcnt(0)
; __device__ __forceinline__ float bflo(unsigned w) { return __uint_as_float(w << 16); }
; __device__ __forceinline__ float bfhi(unsigned w) { return __uint_as_float(w & 0xffff0000u); }
; __device__ __forceinline__ float siluf_(float x) { return x * __builtin_amdgcn_rcpf(1.0f + __expf(-x)); }
; __device__ __forceinline__ unsigned cvtpk(float lo, float hi) { unsigned r; asm volatile("v_cvt_pk_bf16_f32 %0, %1, %2" : "=v"(r) : "v"(lo), "v"(hi)); return r; }
; template <int VAR>
; __device__ __forceinline__ void nsa_attn_mfma(Frame& F, bf16* Y) {
;     ...
;       for (int j = 0; j < 8; ++j) { const int row = 4 * j + (lane >> 4), tt = t0 + 4 * wid + (row >> 3), hh = g * 8 + (row & 7);
;         const v4u tv = *(const v4u*)((const unsigned short*)(lds + AT_K) + (wid * 32 + row) * ROWP + (lane & 15) * 8); const v4u z = zv[j]; v4u y;
;         y.x = cvtpk(bflo(tv.x) * siluf_(bflo(z.x)), bfhi(tv.x) * siluf_(bfhi(z.x))); y.y = cvtpk(bflo(tv.y) * siluf_(bflo(z.y)), bfhi(tv.y) * siluf_(bfhi(z.y)));
;         y.z = cvtpk(bflo(tv.z) * siluf_(bflo(z.z)), bfhi(tv.z) * siluf_(bfhi(z.z))); y.w = cvtpk(bflo(tv.w) * siluf_(bflo(z.w)), bfhi(tv.w) * siluf_(bfhi(z.w)));
;         *(v4u*)(Y + (size_t)(b * SEQ + tt) * DM + hh * 128 + (lane & 15) * 8) = y; }
	v_lshlrev_b32_e32 v27, 16, v20
	v_and_b32_e32 v20, 0xffff0000, v20
	v_mul_f32_e32 v24, v25, v24
	v_mul_f32_e32 v16, v26, v16
	v_mul_f32_e32 v24, v24, v27
	v_mul_f32_e32 v16, v16, v20
	v_lshlrev_b32_e32 v20, 16, v17
	v_and_b32_e32 v17, 0xffff0000, v17
	v_cvt_pk_bf16_f32 v16, v24, v16
	v_mul_f32_e32 v24, 0xbfb8aa3b, v20
	v_mul_f32_e32 v25, 0xbfb8aa3b, v17
	v_exp_f32_e32 v24, v24
	v_exp_f32_e32 v25, v25
	v_lshlrev_b32_e32 v26, 16, v21
	v_and_b32_e32 v21, 0xffff0000, v21
	v_add_f32_e32 v24, 1.0, v24
	v_add_f32_e32 v25, 1.0, v25
	v_rcp_f32_e32 v24, v24
	v_rcp_f32_e32 v25, v25
	v_mul_f32_e32 v20, v24, v20
	v_mul_f32_e32 v17, v25, v17
	v_mul_f32_e32 v20, v20, v26
	v_mul_f32_e32 v17, v17, v21
	v_cvt_pk_bf16_f32 v17, v20, v17
	v_lshlrev_b32_e32 v20, 16, v18
	v_and_b32_e32 v18, 0xffff0000, v18
	v_mul_f32_e32 v21, 0xbfb8aa3b, v20
	v_mul_f32_e32 v24, 0xbfb8aa3b, v18
	v_exp_f32_e32 v21, v21
	v_exp_f32_e32 v24, v24
	v_lshlrev_b32_e32 v25, 16, v22
	v_add_f32_e32 v21, 1.0, v21
	v_add_f32_e32 v24, 1.0, v24
	v_rcp_f32_e32 v21, v21
	v_rcp_f32_e32 v24, v24
	v_mul_f32_e32 v20, v21, v20
	v_and_b32_e32 v21, 0xffff0000, v22
	v_mul_f32_e32 v18, v24, v18
	v_mul_f32_e32 v20, v20, v25
	v_mul_f32_e32 v18, v18, v21
	v_cvt_pk_bf16_f32 v18, v20, v18
	v_lshlrev_b32_e32 v20, 16, v19
	v_and_b32_e32 v19, 0xffff0000, v19
	v_mul_f32_e32 v21, 0xbfb8aa3b, v20
	v_mul_f32_e32 v22, 0xbfb8aa3b, v19
	v_exp_f32_e32 v21, v21
	v_exp_f32_e32 v22, v22
	v_lshlrev_b32_e32 v24, 16, v23
	v_add_f32_e32 v21, 1.0, v21
	v_add_f32_e32 v22, 1.0, v22
	v_rcp_f32_e32 v21, v21
	v_rcp_f32_e32 v22, v22
	v_mul_f32_e32 v20, v21, v20
	v_and_b32_e32 v21, 0xffff0000, v23
	v_mul_f32_e32 v19, v22, v19
	v_mul_f32_e32 v20, v20, v24
	v_mul_f32_e32 v19, v19, v21
	v_cvt_pk_bf16_f32 v19, v20, v19
	v_lshlrev_b64 v[20:21], 13, v[50:51]
	v_lshl_add_u64 v[20:21], s[88:89], 0, v[20:21]
	v_lshl_add_u64 v[20:21], v[20:21], 0, v[2:3]
	v_lshl_add_u64 v[20:21], v[20:21], 0, v[36:37]
	global_store_dwordx4 v[20:21], v[16:19], off sc1
	s_waitcnt vmcnt(7)
	v_lshlrev_b32_e32 v20, 16, v12
	v_and_b32_e32 v12, 0xffff0000, v12
	v_mul_f32_e32 v21, 0xbfb8aa3b, v20
	v_mul_f32_e32 v22, 0xbfb8aa3b, v12
	v_exp_f32_e32 v21, v21
	v_exp_f32_e32 v22, v22
	v_add_u32_e32 v16, s94, v65
	v_mad_u64_u32 v[16:17], s[2:3], v16, s75, v[44:45]
	ds_read_b128 v[16:19], v16
	v_add_f32_e32 v21, 1.0, v21
	v_add_f32_e32 v22, 1.0, v22
	v_rcp_f32_e32 v21, v21
	v_rcp_f32_e32 v22, v22
	s_waitcnt lgkmcnt(0)
	v_lshlrev_b32_e32 v23, 16, v16
	v_and_b32_e32 v16, 0xffff0000, v16
	v_mul_f32_e32 v20, v21, v20
	v_mul_f32_e32 v12, v22, v12
	v_mul_f32_e32 v20, v20, v23
	v_mul_f32_e32 v12, v12, v16
	v_lshlrev_b32_e32 v16, 16, v13
	v_and_b32_e32 v13, 0xffff0000, v13
	v_cvt_pk_bf16_f32 v12, v20, v12
	v_mul_f32_e32 v20, 0xbfb8aa3b, v16
	v_mul_f32_e32 v21, 0xbfb8aa3b, v13
	v_exp_f32_e32 v20, v20
	v_exp_f32_e32 v21, v21
	v_lshlrev_b32_e32 v22, 16, v17
	v_and_b32_e32 v17, 0xffff0000, v17
	v_add_f32_e32 v20, 1.0, v20
	v_add_f32_e32 v21, 1.0, v21
	v_rcp_f32_e32 v20, v20
	v_rcp_f32_e32 v21, v21
	v_mul_f32_e32 v16, v20, v16
	v_mul_f32_e32 v13, v21, v13
	v_mul_f32_e32 v16, v16, v22
	v_mul_f32_e32 v13, v13, v17
	v_cvt_pk_bf16_f32 v13, v16, v13
	v_lshlrev_b32_e32 v16, 16, v14
	v_and_b32_e32 v14, 0xffff0000, v14
	v_mul_f32_e32 v17, 0xbfb8aa3b, v16
	v_mul_f32_e32 v20, 0xbfb8aa3b, v14
	v_exp_f32_e32 v17, v17
	v_exp_f32_e32 v20, v20
	v_lshlrev_b32_e32 v21, 16, v18
	v_add_f32_e32 v17, 1.0, v17
	v_add_f32_e32 v20, 1.0, v20
	v_rcp_f32_e32 v17, v17
	v_rcp_f32_e32 v20, v20
	v_mul_f32_e32 v16, v17, v16
	v_and_b32_e32 v17, 0xffff0000, v18
	v_mul_f32_e32 v14, v20, v14
	v_mul_f32_e32 v16, v16, v21
	v_mul_f32_e32 v14, v14, v17
	v_cvt_pk_bf16_f32 v14, v16, v14
	v_lshlrev_b32_e32 v16, 16, v15
	v_and_b32_e32 v15, 0xffff0000, v15
	v_mul_f32_e32 v17, 0xbfb8aa3b, v16
	v_mul_f32_e32 v18, 0xbfb8aa3b, v15
	v_exp_f32_e32 v17, v17
	v_exp_f32_e32 v18, v18
	v_lshlrev_b32_e32 v20, 16, v19
	v_add_f32_e32 v17, 1.0, v17
	v_add_f32_e32 v18, 1.0, v18
	v_rcp_f32_e32 v17, v17
	v_rcp_f32_e32 v18, v18
	v_mul_f32_e32 v16, v17, v16
	v_and_b32_e32 v17, 0xffff0000, v19
	v_mul_f32_e32 v15, v18, v15
	v_mul_f32_e32 v16, v16, v20
	v_mul_f32_e32 v15, v15, v17
	v_cvt_pk_bf16_f32 v15, v16, v15
	v_lshlrev_b64 v[16:17], 13, v[46:47]
	v_lshl_add_u64 v[16:17], s[88:89], 0, v[16:17]
	v_lshl_add_u64 v[16:17], v[16:17], 0, v[48:49]
	v_lshl_add_u64 v[16:17], v[16:17], 0, v[36:37]
	global_store_dwordx4 v[16:17], v[12:15], off sc1
	s_waitcnt vmcnt(7)
	v_lshlrev_b32_e32 v16, 16, v8
	v_and_b32_e32 v8, 0xffff0000, v8
	v_mul_f32_e32 v17, 0xbfb8aa3b, v16
	v_mul_f32_e32 v18, 0xbfb8aa3b, v8
	v_exp_f32_e32 v17, v17
	v_exp_f32_e32 v18, v18
	v_add_u32_e32 v12, s94, v64
	v_mad_u64_u32 v[12:13], s[2:3], v12, s75, v[44:45]
	ds_read_b128 v[12:15], v12
	v_add_f32_e32 v17, 1.0, v17
	v_add_f32_e32 v18, 1.0, v18
	v_rcp_f32_e32 v17, v17
	v_rcp_f32_e32 v18, v18
	s_waitcnt lgkmcnt(0)
; __device__ __forceinline__ float bflo(unsigned w) { return __uint_as_float(w << 16); }
; __device__ __forceinline__ float bfhi(unsigned w) { return __uint_as_float(w & 0xffff0000u); }
; __device__ __forceinline__ float siluf_(float x) { return x * __builtin_amdgcn_rcpf(1.0f + __expf(-x)); }
; __device__ __forceinline__ unsigned cvtpk(float lo, float hi) { unsigned r; asm volatile("v_cvt_pk_bf16_f32 %0, %1, %2" : "=v"(r) : "v"(lo), "v"(hi)); return r; }
; template <int VAR>
; __device__ __forceinline__ void nsa_attn_mfma(Frame& F, bf16* Y) {
;     ...
;   for (int uu = F.vcu * 4; uu < 1024; uu += (uu % 4 == 3) ? (F.G - 1) * 4 + 1 : 1) {
;     ...
;       for (int j = 0; j < 8; ++j) { const int row = 4 * j + (lane >> 4), tt = t0 + 4 * wid + (row >> 3), hh = g * 8 + (row & 7);
;         const v4u tv = *(const v4u*)((const unsigned short*)(lds + AT_K) + (wid * 32 + row) * ROWP + (lane & 15) * 8); const v4u z = zv[j]; v4u y;
;         y.x = cvtpk(bflo(tv.x) * siluf_(bflo(z.x)), bfhi(tv.x) * siluf_(bfhi(z.x))); y.y = cvtpk(bflo(tv.y) * siluf_(bflo(z.y)), bfhi(tv.y) * siluf_(bfhi(z.y)));
;         y.z = cvtpk(bflo(tv.z) * siluf_(bflo(z.z)), bfhi(tv.z) * siluf_(bfhi(z.z))); y.w = cvtpk(bflo(tv.w) * siluf_(bflo(z.w)), bfhi(tv.w) * siluf_(bfhi(z.w)));
;         *(v4u*)(Y + (size_t)(b * SEQ + tt) * DM + hh * 128 + (lane & 15) * 8) = y; }
	v_lshlrev_b32_e32 v19, 16, v12
	v_and_b32_e32 v12, 0xffff0000, v12
	v_mul_f32_e32 v16, v17, v16
	v_mul_f32_e32 v8, v18, v8
	v_mul_f32_e32 v16, v16, v19
	v_mul_f32_e32 v8, v8, v12
	v_lshlrev_b32_e32 v12, 16, v9
	v_and_b32_e32 v9, 0xffff0000, v9
	v_cvt_pk_bf16_f32 v8, v16, v8
	v_mul_f32_e32 v16, 0xbfb8aa3b, v12
	v_mul_f32_e32 v17, 0xbfb8aa3b, v9
	v_exp_f32_e32 v16, v16
	v_exp_f32_e32 v17, v17
	v_lshlrev_b32_e32 v18, 16, v13
	v_and_b32_e32 v13, 0xffff0000, v13
	v_add_f32_e32 v16, 1.0, v16
	v_add_f32_e32 v17, 1.0, v17
	v_rcp_f32_e32 v16, v16
	v_rcp_f32_e32 v17, v17
	v_mul_f32_e32 v12, v16, v12
	v_mul_f32_e32 v9, v17, v9
	v_mul_f32_e32 v12, v12, v18
	v_mul_f32_e32 v9, v9, v13
	v_cvt_pk_bf16_f32 v9, v12, v9
	v_lshlrev_b32_e32 v12, 16, v10
	v_and_b32_e32 v10, 0xffff0000, v10
	v_mul_f32_e32 v13, 0xbfb8aa3b, v12
	v_mul_f32_e32 v16, 0xbfb8aa3b, v10
	v_exp_f32_e32 v13, v13
	v_exp_f32_e32 v16, v16
	v_lshlrev_b32_e32 v17, 16, v14
	v_add_f32_e32 v13, 1.0, v13
	v_add_f32_e32 v16, 1.0, v16
	v_rcp_f32_e32 v13, v13
	v_rcp_f32_e32 v16, v16
	v_mul_f32_e32 v12, v13, v12
	v_and_b32_e32 v13, 0xffff0000, v14
	v_mul_f32_e32 v10, v16, v10
	v_mul_f32_e32 v12, v12, v17
	v_mul_f32_e32 v10, v10, v13
	v_cvt_pk_bf16_f32 v10, v12, v10
	v_lshlrev_b32_e32 v12, 16, v11
	v_and_b32_e32 v11, 0xffff0000, v11
	v_mul_f32_e32 v13, 0xbfb8aa3b, v12
	v_mul_f32_e32 v14, 0xbfb8aa3b, v11
	v_exp_f32_e32 v13, v13
	v_exp_f32_e32 v14, v14
	v_lshlrev_b32_e32 v16, 16, v15
	v_add_f32_e32 v13, 1.0, v13
	v_add_f32_e32 v14, 1.0, v14
	v_rcp_f32_e32 v13, v13
	v_rcp_f32_e32 v14, v14
	v_mul_f32_e32 v12, v13, v12
	v_and_b32_e32 v13, 0xffff0000, v15
	v_mul_f32_e32 v11, v14, v11
	v_mul_f32_e32 v12, v12, v16
	v_mul_f32_e32 v11, v11, v13
	v_cvt_pk_bf16_f32 v11, v12, v11
	v_lshlrev_b64 v[12:13], 13, v[42:43]
	v_lshl_add_u64 v[12:13], s[88:89], 0, v[12:13]
	v_lshl_add_u64 v[12:13], v[12:13], 0, v[2:3]
	v_lshl_add_u64 v[12:13], v[12:13], 0, v[36:37]
	v_add_u32_e32 v2, s94, v45
	global_store_dwordx4 v[12:13], v[8:11], off sc1
	s_nop 1
	v_mad_u64_u32 v[8:9], s[2:3], v2, s75, v[44:45]
	s_waitcnt vmcnt(7)
	v_lshlrev_b32_e32 v2, 16, v4
	v_and_b32_e32 v4, 0xffff0000, v4
	v_mul_f32_e32 v12, 0xbfb8aa3b, v2
	v_mul_f32_e32 v13, 0xbfb8aa3b, v4
	v_exp_f32_e32 v12, v12
	v_exp_f32_e32 v13, v13
	ds_read_b128 v[8:11], v8
	s_and_b32 s2, s80, 0x80000003
	v_add_f32_e32 v12, 1.0, v12
	v_add_f32_e32 v13, 1.0, v13
	v_rcp_f32_e32 v12, v12
	v_rcp_f32_e32 v13, v13
	s_waitcnt lgkmcnt(0)
	v_lshlrev_b32_e32 v14, 16, v8
	v_and_b32_e32 v8, 0xffff0000, v8
	v_mul_f32_e32 v2, v12, v2
	v_mul_f32_e32 v4, v13, v4
	v_mul_f32_e32 v2, v2, v14
	v_mul_f32_e32 v4, v4, v8
	v_cvt_pk_bf16_f32 v4, v2, v4
	v_lshlrev_b32_e32 v2, 16, v5
	v_and_b32_e32 v5, 0xffff0000, v5
	v_mul_f32_e32 v8, 0xbfb8aa3b, v2
	v_mul_f32_e32 v12, 0xbfb8aa3b, v5
	v_exp_f32_e32 v8, v8
	v_exp_f32_e32 v12, v12
	v_lshlrev_b32_e32 v13, 16, v9
	s_cmp_eq_u32 s2, 3
	v_add_f32_e32 v8, 1.0, v8
	v_add_f32_e32 v12, 1.0, v12
	v_rcp_f32_e32 v8, v8
	v_rcp_f32_e32 v12, v12
	v_readlane_b32 s2, v254, 40
	s_cselect_b32 s2, s2, 1
	v_mul_f32_e32 v2, v8, v2
	v_and_b32_e32 v8, 0xffff0000, v9
	v_mul_f32_e32 v5, v12, v5
	v_mul_f32_e32 v2, v2, v13
	v_mul_f32_e32 v5, v5, v8
	v_cvt_pk_bf16_f32 v5, v2, v5
	v_lshlrev_b32_e32 v2, 16, v6
	v_and_b32_e32 v6, 0xffff0000, v6
	v_mul_f32_e32 v8, 0xbfb8aa3b, v2
	v_mul_f32_e32 v9, 0xbfb8aa3b, v6
	v_exp_f32_e32 v8, v8
	v_exp_f32_e32 v9, v9
	v_lshlrev_b32_e32 v12, 16, v10
	s_add_i32 s80, s2, s80
	v_add_f32_e32 v8, 1.0, v8
	v_add_f32_e32 v9, 1.0, v9
	v_rcp_f32_e32 v8, v8
	v_rcp_f32_e32 v9, v9
	s_cmpk_lt_i32 s80, 0x400
	v_mul_f32_e32 v2, v8, v2
	v_and_b32_e32 v8, 0xffff0000, v10
	v_mul_f32_e32 v6, v9, v6
	v_mul_f32_e32 v2, v2, v12
	v_mul_f32_e32 v6, v6, v8
	v_cvt_pk_bf16_f32 v6, v2, v6
	v_lshlrev_b32_e32 v2, 16, v7
	v_and_b32_e32 v7, 0xffff0000, v7
	v_mul_f32_e32 v8, 0xbfb8aa3b, v2
	v_mul_f32_e32 v9, 0xbfb8aa3b, v7
	v_exp_f32_e32 v8, v8
	v_exp_f32_e32 v9, v9
	v_lshlrev_b32_e32 v10, 16, v11
	v_add_f32_e32 v8, 1.0, v8
	v_add_f32_e32 v9, 1.0, v9
	v_rcp_f32_e32 v8, v8
	v_rcp_f32_e32 v9, v9
	v_mul_f32_e32 v2, v8, v2
	v_and_b32_e32 v8, 0xffff0000, v11
	v_mul_f32_e32 v7, v9, v7
	v_mul_f32_e32 v7, v7, v8
	v_lshlrev_b64 v[8:9], 13, v[38:39]
	v_lshl_add_u64 v[8:9], s[88:89], 0, v[8:9]
	v_lshl_add_u64 v[8:9], v[8:9], 0, v[40:41]
	v_lshl_add_u64 v[8:9], v[8:9], 0, v[36:37]
	v_mul_f32_e32 v2, v2, v10
	v_cvt_pk_bf16_f32 v7, v2, v7
	global_store_dwordx4 v[8:9], v[4:7], off sc1
	s_cbranch_scc0 .LBB0_2453
